# pipelined dil loop: previous group's PV MFMAs deferred into the next iteration's K write/readback wait window (V-fragment registers double-buffered)
# speedup vs baseline: 1.0032x; 1.0012x over previous
; #define LAS __attribute__((address_space(3)))
; #define GAS __attribute__((address_space(1)))
; __device__ __forceinline__ void dil_unit(LAS unsigned char* lds, bf16_t* proj, int seq, int hd, int T0, int rho) {
;     int tid_ = threadIdx.x; asm volatile("" : "+v"(tid_));
;     const int tid = tid_, lane = tid & 63, r32 = lane & 31, hi = lane >> 5, wid = __builtin_amdgcn_readfirstlane(tid >> 6);
;     bf16_t* base = proj + (size_t)seq * SEQ * NIN;
;     LAS unsigned char* wbuf = lds + wid * 4096;
;     const LAS unsigned char* vp = wbuf + ((lane >> 4) & 1) * 32 + (lane & 3) * 8 + (4 * hi + ((lane & 15) >> 2)) * 64;
;     const int P0 = T0 + rho;
;     bf16x8 qr[4];
; #pragma unroll
;     for (int ks = 0; ks < 4; ++ks) qr[ks] = *(const GAS bf16x8*)(base + (size_t)(P0 + 16 * r32) * NIN + PC_LQ + hd * 64 + 16 * ks + 8 * hi);
;     f32x16 o0 = {}, o1 = {}; float l = 0.f;
;     const bool bound = (T0 < 1024) || (T0 >= 15360);
.LBB0_554:
	s_lshr_b32 s82, s33, 8
	s_mul_i32 s82, s82, 13
	s_add_i32 s82, s82, s33
	s_ashr_i32 s2, s33, 6
	s_mul_hi_i32 s7, s2, 0x2aaaaaab
	s_lshl_b32 s3, s82, 8
	s_lshr_b32 s8, s7, 31
	s_and_b32 s6, s3, 0x3e00
	s_lshl_b32 s3, s82, 3
	s_add_i32 s7, s7, s8
	s_and_b32 s3, s3, 8
	s_mul_i32 s8, s7, 6
	s_add_i32 s3, s3, s64
	s_sub_i32 s8, s2, s8
	s_mul_hi_i32 s2, s7, 0x6000000
	s_mul_i32 s7, s7, 0x6000000
	v_mov_b32_e32 v2, v154
	s_add_u32 s56, s48, s7
	s_addc_u32 s57, s49, s2
	v_and_b32_e32 v105, 31, v2
	s_add_i32 s76, s3, s6
	v_lshl_add_u32 v3, v105, 4, s76
	v_mov_b64_e32 v[0:1], s[56:57]
	s_lshl_b32 s58, s8, 6
	v_bfe_u32 v106, v2, 5, 1
	v_mad_u64_u32 v[0:1], s[2:3], v3, s65, v[0:1]
	s_ashr_i32 s59, s58, 31
	v_lshl_add_u64 v[0:1], s[58:59], 1, v[0:1]
	v_lshlrev_b32_e32 v80, 4, v106
	v_lshl_add_u64 v[0:1], v[0:1], 0, v[80:81]
	global_load_dwordx4 v[48:51], v[0:1], off offset:1280
	global_load_dwordx4 v[52:55], v[0:1], off offset:1312
	global_load_dwordx4 v[56:59], v[0:1], off offset:1344
	global_load_dwordx4 v[60:63], v[0:1], off offset:1376
	v_readfirstlane_b32 s2, v2
	s_lshl_b32 s2, s2, 6
	s_and_b32 s2, s2, 0xfffff000
	v_lshlrev_b32_e32 v0, 1, v2
	v_lshlrev_b32_e32 v104, 3, v2
	v_lshlrev_b32_e32 v107, 2, v106
	v_lshrrev_b32_e32 v1, 2, v2
	v_and_b32_e32 v103, 63, v2
	v_and_b32_e32 v0, 32, v0
	v_and_b32_e32 v98, 24, v104
	v_and_or_b32 v1, v1, 3, v107
	s_add_i32 s77, s2, 0
	v_lshlrev_b32_e32 v108, 6, v1
	v_lshlrev_b32_e32 v1, 3, v106
	v_add3_u32 v109, s77, v0, v98
	s_addk_i32 s6, 0xc400
	v_lshrrev_b32_e32 v110, 2, v103
	v_lshlrev_b32_e32 v0, 4, v103
	s_mov_b64 s[2:3], -1
	s_cmp_gt_u32 s6, 0xffffc7ff
	v_lshlrev_b32_e32 v100, 1, v98
	s_mul_i32 s6, s8, 0x1c00
	v_lshlrev_b32_e32 v82, 1, v1
	v_or_b32_e32 v111, 16, v110
	v_add_u32_e32 v112, s77, v0
	s_cbranch_scc0 .LBB0_558
	s_movk_i32 s100, 0x1800
	s_add_i32 s101, s6, 0x15c00
	s_lshl_b32 s90, s58, 1
	s_add_u32 s82, s56, s90
	s_addc_u32 s83, s57, 0
	s_add_u32 s82, s82, 0x1200
	s_addc_u32 s83, s83, 0
	s_sub_i32 s90, s76, 64
	s_mul_i32 s90, s90, 0x1800
	s_add_u32 s84, s82, s90
	s_addc_u32 s85, s83, 0
	s_sub_i32 s90, s76, 256
	s_mul_i32 s90, s90, 0x1800
	s_add_u32 s86, s82, s90
	s_addc_u32 s87, s83, 0
	s_sub_i32 s90, s76, 1024
	s_mul_i32 s90, s90, 0x1800
	s_add_u32 s88, s82, s90
	s_addc_u32 s89, s83, 0
	v_lshlrev_b32_e32 v153, 1, v98
	v_mad_u32_u24 v80, v105, s100, v82
	v_mad_u32_u24 v100, v110, s100, v153
	v_add_u32_e32 v149, 0x18000, v100
	v_lshlrev_b32_e32 v83, 2, v105
	v_mad_u32_u24 v83, v83, s100, v82
	v_lshlrev_b32_e32 v101, 2, v110
	v_mad_u32_u24 v101, v101, s100, v153
	v_add_u32_e32 v150, 0x60000, v101
	v_lshlrev_b32_e32 v99, 4, v105
	v_mad_u32_u24 v99, v99, s100, v82
	v_lshlrev_b32_e32 v148, 4, v110
	v_mad_u32_u24 v148, v148, s100, v153
	v_add_u32_e32 v151, 0x180000, v148
	v_lshrrev_b32_e32 v249, 3, v103
	v_and_b32_e32 v250, 7, v103
	v_lshlrev_b32_e32 v250, 4, v250
	v_add_u32_e32 v235, 0, v249
	v_mad_u32_u24 v235, v235, s100, v250
	v_add_u32_e32 v236, 8, v249
	v_mad_u32_u24 v236, v236, s100, v250
	v_add_u32_e32 v237, 16, v249
	v_mad_u32_u24 v237, v237, s100, v250
	v_add_u32_e32 v238, 24, v249
	v_mad_u32_u24 v238, v238, s100, v250
	v_add_u32_e32 v239, 0, v249
	v_lshlrev_b32_e32 v239, 2, v239
	v_mad_u32_u24 v239, v239, s100, v250
	v_add_u32_e32 v240, 8, v249
	v_lshlrev_b32_e32 v240, 2, v240
	v_mad_u32_u24 v240, v240, s100, v250
	v_add_u32_e32 v241, 16, v249
	v_lshlrev_b32_e32 v241, 2, v241
	v_mad_u32_u24 v241, v241, s100, v250
	v_add_u32_e32 v242, 24, v249
	v_lshlrev_b32_e32 v242, 2, v242
	v_mad_u32_u24 v242, v242, s100, v250
	v_add_u32_e32 v243, 0, v249
	v_lshlrev_b32_e32 v243, 4, v243
	v_mad_u32_u24 v243, v243, s100, v250
	v_add_u32_e32 v244, 8, v249
	v_lshlrev_b32_e32 v244, 4, v244
	v_mad_u32_u24 v244, v244, s100, v250
	v_add_u32_e32 v245, 16, v249
	v_lshlrev_b32_e32 v245, 4, v245
	v_mad_u32_u24 v245, v245, s100, v250
	v_add_u32_e32 v246, 24, v249
	v_lshlrev_b32_e32 v246, 4, v246
	v_mad_u32_u24 v246, v246, s100, v250
	v_and_b32_e32 v247, 7, v249
	v_lshlrev_b32_e32 v247, 4, v247
	v_xor_b32_e32 v247, v247, v112
	v_and_b32_e32 v153, 7, v105
	v_or_b32_e32 v248, 0, v106
	v_xor_b32_e32 v248, v248, v153
	v_lshlrev_b32_e32 v248, 4, v248
	v_lshl_add_u32 v248, v105, 7, v248
	v_add_u32_e32 v248, s77, v248
	v_or_b32_e32 v249, 2, v106
	v_xor_b32_e32 v249, v249, v153
	v_lshlrev_b32_e32 v249, 4, v249
	v_lshl_add_u32 v249, v105, 7, v249
	v_add_u32_e32 v249, s77, v249
	v_or_b32_e32 v250, 4, v106
	v_xor_b32_e32 v250, v250, v153
	v_lshlrev_b32_e32 v250, 4, v250
	v_lshl_add_u32 v250, v105, 7, v250
	v_add_u32_e32 v250, s77, v250
	v_or_b32_e32 v251, 6, v106
	v_xor_b32_e32 v251, v251, v153
	v_lshlrev_b32_e32 v251, 4, v251
	v_lshl_add_u32 v251, v105, 7, v251
	v_add_u32_e32 v251, s77, v251
	v_lshlrev_b32_e32 v153, 1, v98
	v_mul_u32_u24_e32 v228, 17, v105
	v_sub_u32_e32 v228, v107, v228
	s_mul_i32 s90, s58, 153
	s_lshr_b32 s90, s90, 1
	s_add_i32 s90, s90, 34876
	v_lshl_add_u32 v228, v228, 2, s90
	v_lshlrev_b32_e32 v229, 2, v105
	v_sub_u32_e32 v229, v107, v229
	s_add_i32 s90, s101, 5104
	v_lshl_add_u32 v229, v229, 2, s90
	v_sub_u32_e32 v230, v107, v105
	s_add_i32 s90, s101, 6364
	v_lshl_add_u32 v230, v230, 2, s90
	v_add_u32_e32 v231, v109, v108
	v_mov_b64_e32 v[232:233], 0
	v_mov_b64_e32 v[0:1], 0
	v_mov_b64_e32 v[2:3], 0
	v_mov_b64_e32 v[4:5], 0
	v_mov_b64_e32 v[6:7], 0
	v_mov_b64_e32 v[8:9], 0
	v_mov_b64_e32 v[10:11], 0
	v_mov_b64_e32 v[12:13], 0
	v_mov_b64_e32 v[14:15], 0
	v_mov_b64_e32 v[16:17], 0
	v_mov_b64_e32 v[18:19], 0
	v_mov_b64_e32 v[20:21], 0
	v_mov_b64_e32 v[22:23], 0
	v_mov_b64_e32 v[24:25], 0
	v_mov_b64_e32 v[26:27], 0
	v_mov_b64_e32 v[28:29], 0
	v_mov_b64_e32 v[30:31], 0
	global_load_dwordx4 v[116:119], v235, s[84:85]
	global_load_dwordx4 v[120:123], v236, s[84:85]
	global_load_dwordx4 v[124:127], v237, s[84:85]
	global_load_dwordx4 v[128:131], v238, s[84:85]
	global_load_dwordx4 v[132:135], v100, s[84:85] offset:768
	global_load_dwordx4 v[136:139], v149, s[84:85] offset:768
	global_load_dwordx4 v[140:143], v100, s[84:85] offset:832
	global_load_dwordx4 v[144:147], v149, s[84:85] offset:832
	s_add_u32 s84, s84, 0x30000
	s_addc_u32 s85, s85, 0
	global_load_dwordx4 v[156:159], v235, s[84:85]
	global_load_dwordx4 v[160:163], v236, s[84:85]
	global_load_dwordx4 v[164:167], v237, s[84:85]
	global_load_dwordx4 v[168:171], v238, s[84:85]
	global_load_dwordx4 v[172:175], v100, s[84:85] offset:768
	global_load_dwordx4 v[176:179], v149, s[84:85] offset:768
	global_load_dwordx4 v[180:183], v100, s[84:85] offset:832
	global_load_dwordx4 v[184:187], v149, s[84:85] offset:832
	s_add_u32 s84, s84, 0x30000
	s_addc_u32 s85, s85, 0
	v_mov_b32_e32 v115, v228
	ds_read2_b32 v[32:33], v115 offset0:0 offset1:1
	ds_read2_b32 v[34:35], v115 offset0:2 offset1:3
	ds_read2_b32 v[36:37], v115 offset0:8 offset1:9
	ds_read2_b32 v[38:39], v115 offset0:10 offset1:11
	ds_read2_b32 v[40:41], v115 offset0:17 offset1:18
	ds_read2_b32 v[42:43], v115 offset0:19 offset1:20
	ds_read2_b32 v[44:45], v115 offset0:25 offset1:26
	ds_read2_b32 v[46:47], v115 offset0:27 offset1:28
	s_waitcnt vmcnt(8)
	ds_write_b128 v247, v[116:119]
	ds_write_b128 v247, v[120:123] offset:1024
	ds_write_b128 v247, v[124:127] offset:2048
	ds_write_b128 v247, v[128:131] offset:3072
	ds_read_b128 v[116:119], v248
	ds_read_b128 v[120:123], v249
	ds_read_b128 v[124:127], v250
	ds_read_b128 v[128:131], v251
	ds_write_b128 v112, v[132:135]
	ds_write_b128 v112, v[136:139] offset:1024
	ds_write_b128 v112, v[140:143] offset:2048
	ds_write_b128 v112, v[144:147] offset:3072
	s_waitcnt lgkmcnt(4)
	v_mfma_f32_32x32x16_bf16 v[32:47], v[116:119], v[48:51], v[32:47]
	v_mfma_f32_32x32x16_bf16 v[32:47], v[120:123], v[52:55], v[32:47]
	v_mfma_f32_32x32x16_bf16 v[32:47], v[124:127], v[56:59], v[32:47]
	v_mfma_f32_32x32x16_bf16 v[32:47], v[128:131], v[60:63], v[32:47]
	ds_read2_b32 v[188:189], v115 offset0:34 offset1:35
	ds_read2_b32 v[190:191], v115 offset0:36 offset1:37
	ds_read2_b32 v[192:193], v115 offset0:42 offset1:43
	ds_read2_b32 v[194:195], v115 offset0:44 offset1:45
	ds_read2_b32 v[196:197], v115 offset0:51 offset1:52
	ds_read2_b32 v[198:199], v115 offset0:53 offset1:54
	ds_read2_b32 v[200:201], v115 offset0:59 offset1:60
	ds_read2_b32 v[202:203], v115 offset0:61 offset1:62
	global_load_dwordx4 v[116:119], v235, s[84:85]
	global_load_dwordx4 v[120:123], v236, s[84:85]
	global_load_dwordx4 v[124:127], v237, s[84:85]
	global_load_dwordx4 v[128:131], v238, s[84:85]
	global_load_dwordx4 v[132:135], v100, s[84:85] offset:768
	global_load_dwordx4 v[136:139], v149, s[84:85] offset:768
	global_load_dwordx4 v[140:143], v100, s[84:85] offset:832
	global_load_dwordx4 v[144:147], v149, s[84:85] offset:832
	s_add_u32 s84, s84, 0x30000
	s_addc_u32 s85, s85, 0
	ds_read_b64_tr_b16 v[72:73], v231
	ds_read_b64_tr_b16 v[74:75], v231 offset:512
	ds_read_b64_tr_b16 v[76:77], v231 offset:2048
	ds_read_b64_tr_b16 v[78:79], v231 offset:2560
	ds_read_b64_tr_b16 v[220:221], v231 offset:1024
	ds_read_b64_tr_b16 v[222:223], v231 offset:1536
	ds_read_b64_tr_b16 v[224:225], v231 offset:3072
	ds_read_b64_tr_b16 v[226:227], v231 offset:3584
	v_exp_f32_e32 v32, v32
	v_exp_f32_e32 v33, v33
	v_exp_f32_e32 v34, v34
	v_exp_f32_e32 v35, v35
	s_waitcnt vmcnt(8)
	ds_write_b128 v247, v[156:159]
	ds_write_b128 v247, v[160:163] offset:1024
	ds_write_b128 v247, v[164:167] offset:2048
	ds_write_b128 v247, v[168:171] offset:3072
	ds_read_b128 v[156:159], v248
	ds_read_b128 v[160:163], v249
	ds_read_b128 v[164:167], v250
	ds_read_b128 v[168:171], v251
	ds_write_b128 v112, v[172:175]
	ds_write_b128 v112, v[176:179] offset:1024
	ds_write_b128 v112, v[180:183] offset:2048
	ds_write_b128 v112, v[184:187] offset:3072
	v_exp_f32_e32 v36, v36
	v_exp_f32_e32 v37, v37
	v_exp_f32_e32 v38, v38
	v_exp_f32_e32 v39, v39
	s_waitcnt lgkmcnt(4)
	v_mfma_f32_32x32x16_bf16 v[188:203], v[156:159], v[48:51], v[188:203]
	v_exp_f32_e32 v40, v40
	v_exp_f32_e32 v41, v41
	v_mfma_f32_32x32x16_bf16 v[188:203], v[160:163], v[52:55], v[188:203]
	v_exp_f32_e32 v42, v42
	v_exp_f32_e32 v43, v43
	v_mfma_f32_32x32x16_bf16 v[188:203], v[164:167], v[56:59], v[188:203]
	v_exp_f32_e32 v44, v44
	v_exp_f32_e32 v45, v45
	v_mfma_f32_32x32x16_bf16 v[188:203], v[168:171], v[60:63], v[188:203]
	v_exp_f32_e32 v46, v46
	v_exp_f32_e32 v47, v47
	v_cvt_pk_bf16_f32 v64, v32, v33
	v_cvt_pk_bf16_f32 v65, v34, v35
	v_cvt_pk_bf16_f32 v66, v36, v37
	v_cvt_pk_bf16_f32 v67, v38, v39
	v_cvt_pk_bf16_f32 v68, v40, v41
	v_cvt_pk_bf16_f32 v69, v42, v43
	v_cvt_pk_bf16_f32 v70, v44, v45
	v_cvt_pk_bf16_f32 v71, v46, v47
	v_pk_add_f32 v[232:233], v[232:233], v[32:33]
	v_pk_add_f32 v[232:233], v[232:233], v[34:35]
	v_pk_add_f32 v[232:233], v[232:233], v[36:37]
	v_pk_add_f32 v[232:233], v[232:233], v[38:39]
	v_pk_add_f32 v[232:233], v[232:233], v[40:41]
	v_pk_add_f32 v[232:233], v[232:233], v[42:43]
	v_pk_add_f32 v[232:233], v[232:233], v[44:45]
	v_pk_add_f32 v[232:233], v[232:233], v[46:47]
	ds_read2_b32 v[32:33], v115 offset0:68 offset1:69
	ds_read2_b32 v[34:35], v115 offset0:70 offset1:71
	ds_read2_b32 v[36:37], v115 offset0:76 offset1:77
	ds_read2_b32 v[38:39], v115 offset0:78 offset1:79
	ds_read2_b32 v[40:41], v115 offset0:85 offset1:86
	ds_read2_b32 v[42:43], v115 offset0:87 offset1:88
	ds_read2_b32 v[44:45], v115 offset0:93 offset1:94
	ds_read2_b32 v[46:47], v115 offset0:95 offset1:96
	global_load_dwordx4 v[156:159], v235, s[84:85]
	global_load_dwordx4 v[160:163], v236, s[84:85]
	global_load_dwordx4 v[164:167], v237, s[84:85]
	global_load_dwordx4 v[168:171], v238, s[84:85]
	global_load_dwordx4 v[172:175], v100, s[84:85] offset:768
	global_load_dwordx4 v[176:179], v149, s[84:85] offset:768
	global_load_dwordx4 v[180:183], v100, s[84:85] offset:832
	global_load_dwordx4 v[184:187], v149, s[84:85] offset:832
	s_add_u32 s84, s84, 0x30000
	s_addc_u32 s85, s85, 0
	ds_read_b64_tr_b16 v[204:205], v231
	ds_read_b64_tr_b16 v[206:207], v231 offset:512
	ds_read_b64_tr_b16 v[208:209], v231 offset:2048
	ds_read_b64_tr_b16 v[210:211], v231 offset:2560
	ds_read_b64_tr_b16 v[212:213], v231 offset:1024
	ds_read_b64_tr_b16 v[214:215], v231 offset:1536
	ds_read_b64_tr_b16 v[216:217], v231 offset:3072
	ds_read_b64_tr_b16 v[218:219], v231 offset:3584
	v_exp_f32_e32 v188, v188
	v_exp_f32_e32 v189, v189
	v_exp_f32_e32 v190, v190
	v_exp_f32_e32 v191, v191
	s_waitcnt vmcnt(8)
	ds_write_b128 v247, v[116:119]
	ds_write_b128 v247, v[120:123] offset:1024
	ds_write_b128 v247, v[124:127] offset:2048
	ds_write_b128 v247, v[128:131] offset:3072
	ds_read_b128 v[116:119], v248
	ds_read_b128 v[120:123], v249
	ds_read_b128 v[124:127], v250
	ds_read_b128 v[128:131], v251
	ds_write_b128 v112, v[132:135]
	ds_write_b128 v112, v[136:139] offset:1024
	ds_write_b128 v112, v[140:143] offset:2048
	ds_write_b128 v112, v[144:147] offset:3072
	v_mfma_f32_32x32x16_bf16 v[0:15], v[64:67], v[72:75], v[0:15]
	v_mfma_f32_32x32x16_bf16 v[16:31], v[64:67], v[76:79], v[16:31]
	v_mfma_f32_32x32x16_bf16 v[0:15], v[68:71], v[220:223], v[0:15]
	v_mfma_f32_32x32x16_bf16 v[16:31], v[68:71], v[224:227], v[16:31]
	v_exp_f32_e32 v192, v192
	v_exp_f32_e32 v193, v193
	v_exp_f32_e32 v194, v194
	v_exp_f32_e32 v195, v195
	s_waitcnt lgkmcnt(4)
	v_mfma_f32_32x32x16_bf16 v[32:47], v[116:119], v[48:51], v[32:47]
	v_exp_f32_e32 v196, v196
	v_exp_f32_e32 v197, v197
	v_mfma_f32_32x32x16_bf16 v[32:47], v[120:123], v[52:55], v[32:47]
	v_exp_f32_e32 v198, v198
	v_exp_f32_e32 v199, v199
	v_mfma_f32_32x32x16_bf16 v[32:47], v[124:127], v[56:59], v[32:47]
	v_exp_f32_e32 v200, v200
	v_exp_f32_e32 v201, v201
	v_mfma_f32_32x32x16_bf16 v[32:47], v[128:131], v[60:63], v[32:47]
	v_exp_f32_e32 v202, v202
	v_exp_f32_e32 v203, v203
	v_cvt_pk_bf16_f32 v64, v188, v189
	v_cvt_pk_bf16_f32 v65, v190, v191
	v_cvt_pk_bf16_f32 v66, v192, v193
	v_cvt_pk_bf16_f32 v67, v194, v195
	v_cvt_pk_bf16_f32 v68, v196, v197
	v_cvt_pk_bf16_f32 v69, v198, v199
	v_cvt_pk_bf16_f32 v70, v200, v201
	v_cvt_pk_bf16_f32 v71, v202, v203
	v_pk_add_f32 v[232:233], v[232:233], v[188:189]
	v_pk_add_f32 v[232:233], v[232:233], v[190:191]
	v_pk_add_f32 v[232:233], v[232:233], v[192:193]
	v_pk_add_f32 v[232:233], v[232:233], v[194:195]
	v_pk_add_f32 v[232:233], v[232:233], v[196:197]
	v_pk_add_f32 v[232:233], v[232:233], v[198:199]
	v_pk_add_f32 v[232:233], v[232:233], v[200:201]
	v_pk_add_f32 v[232:233], v[232:233], v[202:203]
	ds_read2_b32 v[188:189], v115 offset0:102 offset1:103
	ds_read2_b32 v[190:191], v115 offset0:104 offset1:105
	ds_read2_b32 v[192:193], v115 offset0:110 offset1:111
	ds_read2_b32 v[194:195], v115 offset0:112 offset1:113
	ds_read2_b32 v[196:197], v115 offset0:119 offset1:120
	ds_read2_b32 v[198:199], v115 offset0:121 offset1:122
	ds_read2_b32 v[200:201], v115 offset0:127 offset1:128
	ds_read2_b32 v[202:203], v115 offset0:129 offset1:130
	global_load_dwordx4 v[116:119], v235, s[84:85]
	global_load_dwordx4 v[120:123], v236, s[84:85]
	global_load_dwordx4 v[124:127], v237, s[84:85]
	global_load_dwordx4 v[128:131], v238, s[84:85]
	global_load_dwordx4 v[132:135], v100, s[84:85] offset:768
	global_load_dwordx4 v[136:139], v149, s[84:85] offset:768
	global_load_dwordx4 v[140:143], v100, s[84:85] offset:832
	global_load_dwordx4 v[144:147], v149, s[84:85] offset:832
	s_add_u32 s84, s84, 0x30000
	s_addc_u32 s85, s85, 0
	ds_read_b64_tr_b16 v[72:73], v231
	ds_read_b64_tr_b16 v[74:75], v231 offset:512
	ds_read_b64_tr_b16 v[76:77], v231 offset:2048
	ds_read_b64_tr_b16 v[78:79], v231 offset:2560
	ds_read_b64_tr_b16 v[220:221], v231 offset:1024
	ds_read_b64_tr_b16 v[222:223], v231 offset:1536
	ds_read_b64_tr_b16 v[224:225], v231 offset:3072
	ds_read_b64_tr_b16 v[226:227], v231 offset:3584
	v_exp_f32_e32 v32, v32
	v_exp_f32_e32 v33, v33
	v_exp_f32_e32 v34, v34
	v_exp_f32_e32 v35, v35
	s_waitcnt vmcnt(8)
	ds_write_b128 v247, v[156:159]
	ds_write_b128 v247, v[160:163] offset:1024
	ds_write_b128 v247, v[164:167] offset:2048
	ds_write_b128 v247, v[168:171] offset:3072
	ds_read_b128 v[156:159], v248
	ds_read_b128 v[160:163], v249
	ds_read_b128 v[164:167], v250
	ds_read_b128 v[168:171], v251
	ds_write_b128 v112, v[172:175]
	ds_write_b128 v112, v[176:179] offset:1024
	ds_write_b128 v112, v[180:183] offset:2048
	ds_write_b128 v112, v[184:187] offset:3072
	v_mfma_f32_32x32x16_bf16 v[0:15], v[64:67], v[204:207], v[0:15]
	v_mfma_f32_32x32x16_bf16 v[16:31], v[64:67], v[208:211], v[16:31]
	v_mfma_f32_32x32x16_bf16 v[0:15], v[68:71], v[212:215], v[0:15]
	v_mfma_f32_32x32x16_bf16 v[16:31], v[68:71], v[216:219], v[16:31]
	v_exp_f32_e32 v36, v36
	v_exp_f32_e32 v37, v37
	v_exp_f32_e32 v38, v38
	v_exp_f32_e32 v39, v39
	s_waitcnt lgkmcnt(4)
	v_mfma_f32_32x32x16_bf16 v[188:203], v[156:159], v[48:51], v[188:203]
	v_exp_f32_e32 v40, v40
	v_exp_f32_e32 v41, v41
	v_mfma_f32_32x32x16_bf16 v[188:203], v[160:163], v[52:55], v[188:203]
	v_exp_f32_e32 v42, v42
	v_exp_f32_e32 v43, v43
	v_mfma_f32_32x32x16_bf16 v[188:203], v[164:167], v[56:59], v[188:203]
	v_exp_f32_e32 v44, v44
	v_exp_f32_e32 v45, v45
	v_mfma_f32_32x32x16_bf16 v[188:203], v[168:171], v[60:63], v[188:203]
	v_exp_f32_e32 v46, v46
	v_exp_f32_e32 v47, v47
	v_cvt_pk_bf16_f32 v64, v32, v33
	v_cvt_pk_bf16_f32 v65, v34, v35
	v_cvt_pk_bf16_f32 v66, v36, v37
	v_cvt_pk_bf16_f32 v67, v38, v39
	v_cvt_pk_bf16_f32 v68, v40, v41
	v_cvt_pk_bf16_f32 v69, v42, v43
	v_cvt_pk_bf16_f32 v70, v44, v45
	v_cvt_pk_bf16_f32 v71, v46, v47
	v_pk_add_f32 v[232:233], v[232:233], v[32:33]
	v_pk_add_f32 v[232:233], v[232:233], v[34:35]
	v_pk_add_f32 v[232:233], v[232:233], v[36:37]
	v_pk_add_f32 v[232:233], v[232:233], v[38:39]
	v_pk_add_f32 v[232:233], v[232:233], v[40:41]
	v_pk_add_f32 v[232:233], v[232:233], v[42:43]
	v_pk_add_f32 v[232:233], v[232:233], v[44:45]
	v_pk_add_f32 v[232:233], v[232:233], v[46:47]
	ds_read2_b32 v[32:33], v115 offset0:136 offset1:137
	ds_read2_b32 v[34:35], v115 offset0:138 offset1:139
	ds_read2_b32 v[36:37], v115 offset0:144 offset1:145
	ds_read2_b32 v[38:39], v115 offset0:146 offset1:147
	ds_read2_b32 v[40:41], v115 offset0:153 offset1:154
	ds_read2_b32 v[42:43], v115 offset0:155 offset1:156
	ds_read2_b32 v[44:45], v115 offset0:161 offset1:162
	ds_read2_b32 v[46:47], v115 offset0:163 offset1:164
	global_load_dwordx4 v[156:159], v235, s[84:85]
	global_load_dwordx4 v[160:163], v236, s[84:85]
	global_load_dwordx4 v[164:167], v237, s[84:85]
	global_load_dwordx4 v[168:171], v238, s[84:85]
	global_load_dwordx4 v[172:175], v100, s[84:85] offset:768
	global_load_dwordx4 v[176:179], v149, s[84:85] offset:768
	global_load_dwordx4 v[180:183], v100, s[84:85] offset:832
	global_load_dwordx4 v[184:187], v149, s[84:85] offset:832
	s_add_u32 s84, s84, 0x30000
	s_addc_u32 s85, s85, 0
	ds_read_b64_tr_b16 v[204:205], v231
	ds_read_b64_tr_b16 v[206:207], v231 offset:512
	ds_read_b64_tr_b16 v[208:209], v231 offset:2048
	ds_read_b64_tr_b16 v[210:211], v231 offset:2560
	ds_read_b64_tr_b16 v[212:213], v231 offset:1024
	ds_read_b64_tr_b16 v[214:215], v231 offset:1536
	ds_read_b64_tr_b16 v[216:217], v231 offset:3072
	ds_read_b64_tr_b16 v[218:219], v231 offset:3584
	v_exp_f32_e32 v188, v188
	v_exp_f32_e32 v189, v189
	v_exp_f32_e32 v190, v190
	v_exp_f32_e32 v191, v191
	s_waitcnt vmcnt(8)
	ds_write_b128 v247, v[116:119]
	ds_write_b128 v247, v[120:123] offset:1024
	ds_write_b128 v247, v[124:127] offset:2048
	ds_write_b128 v247, v[128:131] offset:3072
	ds_read_b128 v[116:119], v248
	ds_read_b128 v[120:123], v249
	ds_read_b128 v[124:127], v250
	ds_read_b128 v[128:131], v251
	ds_write_b128 v112, v[132:135]
	ds_write_b128 v112, v[136:139] offset:1024
	ds_write_b128 v112, v[140:143] offset:2048
	ds_write_b128 v112, v[144:147] offset:3072
	v_mfma_f32_32x32x16_bf16 v[0:15], v[64:67], v[72:75], v[0:15]
	v_mfma_f32_32x32x16_bf16 v[16:31], v[64:67], v[76:79], v[16:31]
	v_mfma_f32_32x32x16_bf16 v[0:15], v[68:71], v[220:223], v[0:15]
	v_mfma_f32_32x32x16_bf16 v[16:31], v[68:71], v[224:227], v[16:31]
	v_exp_f32_e32 v192, v192
	v_exp_f32_e32 v193, v193
	v_exp_f32_e32 v194, v194
	v_exp_f32_e32 v195, v195
	s_waitcnt lgkmcnt(4)
	v_mfma_f32_32x32x16_bf16 v[32:47], v[116:119], v[48:51], v[32:47]
	v_exp_f32_e32 v196, v196
	v_exp_f32_e32 v197, v197
	v_mfma_f32_32x32x16_bf16 v[32:47], v[120:123], v[52:55], v[32:47]
	v_exp_f32_e32 v198, v198
	v_exp_f32_e32 v199, v199
	v_mfma_f32_32x32x16_bf16 v[32:47], v[124:127], v[56:59], v[32:47]
	v_exp_f32_e32 v200, v200
	v_exp_f32_e32 v201, v201
	v_mfma_f32_32x32x16_bf16 v[32:47], v[128:131], v[60:63], v[32:47]
	v_exp_f32_e32 v202, v202
	v_exp_f32_e32 v203, v203
	v_cvt_pk_bf16_f32 v64, v188, v189
	v_cvt_pk_bf16_f32 v65, v190, v191
	v_cvt_pk_bf16_f32 v66, v192, v193
	v_cvt_pk_bf16_f32 v67, v194, v195
	v_cvt_pk_bf16_f32 v68, v196, v197
	v_cvt_pk_bf16_f32 v69, v198, v199
	v_cvt_pk_bf16_f32 v70, v200, v201
	v_cvt_pk_bf16_f32 v71, v202, v203
	v_pk_add_f32 v[232:233], v[232:233], v[188:189]
	v_pk_add_f32 v[232:233], v[232:233], v[190:191]
	v_pk_add_f32 v[232:233], v[232:233], v[192:193]
	v_pk_add_f32 v[232:233], v[232:233], v[194:195]
	v_pk_add_f32 v[232:233], v[232:233], v[196:197]
	v_pk_add_f32 v[232:233], v[232:233], v[198:199]
	v_pk_add_f32 v[232:233], v[232:233], v[200:201]
	v_pk_add_f32 v[232:233], v[232:233], v[202:203]
	ds_read2_b32 v[188:189], v115 offset0:170 offset1:171
	ds_read2_b32 v[190:191], v115 offset0:172 offset1:173
	ds_read2_b32 v[192:193], v115 offset0:178 offset1:179
	ds_read2_b32 v[194:195], v115 offset0:180 offset1:181
	ds_read2_b32 v[196:197], v115 offset0:187 offset1:188
	ds_read2_b32 v[198:199], v115 offset0:189 offset1:190
	ds_read2_b32 v[200:201], v115 offset0:195 offset1:196
	ds_read2_b32 v[202:203], v115 offset0:197 offset1:198
	global_load_dwordx4 v[116:119], v235, s[84:85]
	global_load_dwordx4 v[120:123], v236, s[84:85]
	global_load_dwordx4 v[124:127], v237, s[84:85]
	global_load_dwordx4 v[128:131], v238, s[84:85]
	global_load_dwordx4 v[132:135], v100, s[84:85] offset:768
	global_load_dwordx4 v[136:139], v149, s[84:85] offset:768
	global_load_dwordx4 v[140:143], v100, s[84:85] offset:832
	global_load_dwordx4 v[144:147], v149, s[84:85] offset:832
	s_add_u32 s84, s84, 0x30000
	s_addc_u32 s85, s85, 0
	ds_read_b64_tr_b16 v[72:73], v231
	ds_read_b64_tr_b16 v[74:75], v231 offset:512
	ds_read_b64_tr_b16 v[76:77], v231 offset:2048
	ds_read_b64_tr_b16 v[78:79], v231 offset:2560
	ds_read_b64_tr_b16 v[220:221], v231 offset:1024
	ds_read_b64_tr_b16 v[222:223], v231 offset:1536
	ds_read_b64_tr_b16 v[224:225], v231 offset:3072
	ds_read_b64_tr_b16 v[226:227], v231 offset:3584
	v_exp_f32_e32 v32, v32
	v_exp_f32_e32 v33, v33
	v_exp_f32_e32 v34, v34
	v_exp_f32_e32 v35, v35
	s_waitcnt vmcnt(8)
	ds_write_b128 v247, v[156:159]
	ds_write_b128 v247, v[160:163] offset:1024
	ds_write_b128 v247, v[164:167] offset:2048
	ds_write_b128 v247, v[168:171] offset:3072
	ds_read_b128 v[156:159], v248
	ds_read_b128 v[160:163], v249
	ds_read_b128 v[164:167], v250
	ds_read_b128 v[168:171], v251
	ds_write_b128 v112, v[172:175]
	ds_write_b128 v112, v[176:179] offset:1024
	ds_write_b128 v112, v[180:183] offset:2048
	ds_write_b128 v112, v[184:187] offset:3072
	v_mfma_f32_32x32x16_bf16 v[0:15], v[64:67], v[204:207], v[0:15]
	v_mfma_f32_32x32x16_bf16 v[16:31], v[64:67], v[208:211], v[16:31]
	v_mfma_f32_32x32x16_bf16 v[0:15], v[68:71], v[212:215], v[0:15]
	v_mfma_f32_32x32x16_bf16 v[16:31], v[68:71], v[216:219], v[16:31]
	v_exp_f32_e32 v36, v36
	v_exp_f32_e32 v37, v37
	v_exp_f32_e32 v38, v38
	v_exp_f32_e32 v39, v39
	s_waitcnt lgkmcnt(4)
	v_mfma_f32_32x32x16_bf16 v[188:203], v[156:159], v[48:51], v[188:203]
	v_exp_f32_e32 v40, v40
	v_exp_f32_e32 v41, v41
	v_mfma_f32_32x32x16_bf16 v[188:203], v[160:163], v[52:55], v[188:203]
	v_exp_f32_e32 v42, v42
	v_exp_f32_e32 v43, v43
	v_mfma_f32_32x32x16_bf16 v[188:203], v[164:167], v[56:59], v[188:203]
	v_exp_f32_e32 v44, v44
	v_exp_f32_e32 v45, v45
	v_mfma_f32_32x32x16_bf16 v[188:203], v[168:171], v[60:63], v[188:203]
	v_exp_f32_e32 v46, v46
	v_exp_f32_e32 v47, v47
	v_cvt_pk_bf16_f32 v64, v32, v33
	v_cvt_pk_bf16_f32 v65, v34, v35
	v_cvt_pk_bf16_f32 v66, v36, v37
	v_cvt_pk_bf16_f32 v67, v38, v39
	v_cvt_pk_bf16_f32 v68, v40, v41
	v_cvt_pk_bf16_f32 v69, v42, v43
	v_cvt_pk_bf16_f32 v70, v44, v45
	v_cvt_pk_bf16_f32 v71, v46, v47
	v_pk_add_f32 v[232:233], v[232:233], v[32:33]
	v_pk_add_f32 v[232:233], v[232:233], v[34:35]
	v_pk_add_f32 v[232:233], v[232:233], v[36:37]
	v_pk_add_f32 v[232:233], v[232:233], v[38:39]
	v_pk_add_f32 v[232:233], v[232:233], v[40:41]
	v_pk_add_f32 v[232:233], v[232:233], v[42:43]
	v_pk_add_f32 v[232:233], v[232:233], v[44:45]
	v_pk_add_f32 v[232:233], v[232:233], v[46:47]
	ds_read2_b32 v[32:33], v115 offset0:204 offset1:205
	ds_read2_b32 v[34:35], v115 offset0:206 offset1:207
	ds_read2_b32 v[36:37], v115 offset0:212 offset1:213
	ds_read2_b32 v[38:39], v115 offset0:214 offset1:215
	ds_read2_b32 v[40:41], v115 offset0:221 offset1:222
	ds_read2_b32 v[42:43], v115 offset0:223 offset1:224
	ds_read2_b32 v[44:45], v115 offset0:229 offset1:230
	ds_read2_b32 v[46:47], v115 offset0:231 offset1:232
	global_load_dwordx4 v[156:159], v235, s[84:85]
	global_load_dwordx4 v[160:163], v236, s[84:85]
	global_load_dwordx4 v[164:167], v237, s[84:85]
	global_load_dwordx4 v[168:171], v238, s[84:85]
	global_load_dwordx4 v[172:175], v100, s[84:85] offset:768
	global_load_dwordx4 v[176:179], v149, s[84:85] offset:768
	global_load_dwordx4 v[180:183], v100, s[84:85] offset:832
	global_load_dwordx4 v[184:187], v149, s[84:85] offset:832
	s_add_u32 s84, s84, 0x30000
	s_addc_u32 s85, s85, 0
	ds_read_b64_tr_b16 v[204:205], v231
	ds_read_b64_tr_b16 v[206:207], v231 offset:512
	ds_read_b64_tr_b16 v[208:209], v231 offset:2048
	ds_read_b64_tr_b16 v[210:211], v231 offset:2560
	ds_read_b64_tr_b16 v[212:213], v231 offset:1024
	ds_read_b64_tr_b16 v[214:215], v231 offset:1536
	ds_read_b64_tr_b16 v[216:217], v231 offset:3072
	ds_read_b64_tr_b16 v[218:219], v231 offset:3584
	v_exp_f32_e32 v188, v188
	v_exp_f32_e32 v189, v189
	v_exp_f32_e32 v190, v190
	v_exp_f32_e32 v191, v191
	s_waitcnt vmcnt(8)
	ds_write_b128 v247, v[116:119]
	ds_write_b128 v247, v[120:123] offset:1024
	ds_write_b128 v247, v[124:127] offset:2048
	ds_write_b128 v247, v[128:131] offset:3072
	ds_read_b128 v[116:119], v248
	ds_read_b128 v[120:123], v249
	ds_read_b128 v[124:127], v250
	ds_read_b128 v[128:131], v251
	ds_write_b128 v112, v[132:135]
	ds_write_b128 v112, v[136:139] offset:1024
	ds_write_b128 v112, v[140:143] offset:2048
	ds_write_b128 v112, v[144:147] offset:3072
	v_mfma_f32_32x32x16_bf16 v[0:15], v[64:67], v[72:75], v[0:15]
	v_mfma_f32_32x32x16_bf16 v[16:31], v[64:67], v[76:79], v[16:31]
	v_mfma_f32_32x32x16_bf16 v[0:15], v[68:71], v[220:223], v[0:15]
	v_mfma_f32_32x32x16_bf16 v[16:31], v[68:71], v[224:227], v[16:31]
	v_exp_f32_e32 v192, v192
	v_exp_f32_e32 v193, v193
	v_exp_f32_e32 v194, v194
	v_exp_f32_e32 v195, v195
	s_waitcnt lgkmcnt(4)
	v_mfma_f32_32x32x16_bf16 v[32:47], v[116:119], v[48:51], v[32:47]
	v_exp_f32_e32 v196, v196
	v_exp_f32_e32 v197, v197
	v_mfma_f32_32x32x16_bf16 v[32:47], v[120:123], v[52:55], v[32:47]
	v_exp_f32_e32 v198, v198
	v_exp_f32_e32 v199, v199
	v_mfma_f32_32x32x16_bf16 v[32:47], v[124:127], v[56:59], v[32:47]
	v_exp_f32_e32 v200, v200
	v_exp_f32_e32 v201, v201
	v_mfma_f32_32x32x16_bf16 v[32:47], v[128:131], v[60:63], v[32:47]
	v_exp_f32_e32 v202, v202
	v_exp_f32_e32 v203, v203
	v_cvt_pk_bf16_f32 v64, v188, v189
	v_cvt_pk_bf16_f32 v65, v190, v191
	v_cvt_pk_bf16_f32 v66, v192, v193
	v_cvt_pk_bf16_f32 v67, v194, v195
	v_cvt_pk_bf16_f32 v68, v196, v197
	v_cvt_pk_bf16_f32 v69, v198, v199
	v_cvt_pk_bf16_f32 v70, v200, v201
	v_cvt_pk_bf16_f32 v71, v202, v203
	v_pk_add_f32 v[232:233], v[232:233], v[188:189]
	v_pk_add_f32 v[232:233], v[232:233], v[190:191]
	v_pk_add_f32 v[232:233], v[232:233], v[192:193]
	v_pk_add_f32 v[232:233], v[232:233], v[194:195]
	v_pk_add_f32 v[232:233], v[232:233], v[196:197]
	v_pk_add_f32 v[232:233], v[232:233], v[198:199]
	v_pk_add_f32 v[232:233], v[232:233], v[200:201]
	v_pk_add_f32 v[232:233], v[232:233], v[202:203]
	v_add_u32_e32 v115, 952, v115
	ds_read2_b32 v[188:189], v115 offset0:0 offset1:1
	ds_read2_b32 v[190:191], v115 offset0:2 offset1:3
	ds_read2_b32 v[192:193], v115 offset0:8 offset1:9
	ds_read2_b32 v[194:195], v115 offset0:10 offset1:11
	ds_read2_b32 v[196:197], v115 offset0:17 offset1:18
	ds_read2_b32 v[198:199], v115 offset0:19 offset1:20
	ds_read2_b32 v[200:201], v115 offset0:25 offset1:26
	ds_read2_b32 v[202:203], v115 offset0:27 offset1:28
	global_load_dwordx4 v[116:119], v235, s[84:85]
	global_load_dwordx4 v[120:123], v236, s[84:85]
	global_load_dwordx4 v[124:127], v237, s[84:85]
	global_load_dwordx4 v[128:131], v238, s[84:85]
	global_load_dwordx4 v[132:135], v100, s[84:85] offset:768
	global_load_dwordx4 v[136:139], v149, s[84:85] offset:768
	global_load_dwordx4 v[140:143], v100, s[84:85] offset:832
	global_load_dwordx4 v[144:147], v149, s[84:85] offset:832
	s_add_u32 s84, s84, 0x30000
	s_addc_u32 s85, s85, 0
	ds_read_b64_tr_b16 v[72:73], v231
	ds_read_b64_tr_b16 v[74:75], v231 offset:512
	ds_read_b64_tr_b16 v[76:77], v231 offset:2048
	ds_read_b64_tr_b16 v[78:79], v231 offset:2560
	ds_read_b64_tr_b16 v[220:221], v231 offset:1024
	ds_read_b64_tr_b16 v[222:223], v231 offset:1536
	ds_read_b64_tr_b16 v[224:225], v231 offset:3072
	ds_read_b64_tr_b16 v[226:227], v231 offset:3584
	v_exp_f32_e32 v32, v32
	v_exp_f32_e32 v33, v33
	v_exp_f32_e32 v34, v34
	v_exp_f32_e32 v35, v35
	s_waitcnt vmcnt(8)
	ds_write_b128 v247, v[156:159]
	ds_write_b128 v247, v[160:163] offset:1024
	ds_write_b128 v247, v[164:167] offset:2048
	ds_write_b128 v247, v[168:171] offset:3072
	ds_read_b128 v[156:159], v248
	ds_read_b128 v[160:163], v249
	ds_read_b128 v[164:167], v250
	ds_read_b128 v[168:171], v251
	ds_write_b128 v112, v[172:175]
	ds_write_b128 v112, v[176:179] offset:1024
	ds_write_b128 v112, v[180:183] offset:2048
	ds_write_b128 v112, v[184:187] offset:3072
	v_mfma_f32_32x32x16_bf16 v[0:15], v[64:67], v[204:207], v[0:15]
	v_mfma_f32_32x32x16_bf16 v[16:31], v[64:67], v[208:211], v[16:31]
	v_mfma_f32_32x32x16_bf16 v[0:15], v[68:71], v[212:215], v[0:15]
	v_mfma_f32_32x32x16_bf16 v[16:31], v[68:71], v[216:219], v[16:31]
	v_exp_f32_e32 v36, v36
	v_exp_f32_e32 v37, v37
	v_exp_f32_e32 v38, v38
	v_exp_f32_e32 v39, v39
	s_waitcnt lgkmcnt(4)
	v_mfma_f32_32x32x16_bf16 v[188:203], v[156:159], v[48:51], v[188:203]
	v_exp_f32_e32 v40, v40
	v_exp_f32_e32 v41, v41
	v_mfma_f32_32x32x16_bf16 v[188:203], v[160:163], v[52:55], v[188:203]
	v_exp_f32_e32 v42, v42
	v_exp_f32_e32 v43, v43
	v_mfma_f32_32x32x16_bf16 v[188:203], v[164:167], v[56:59], v[188:203]
	v_exp_f32_e32 v44, v44
	v_exp_f32_e32 v45, v45
	v_mfma_f32_32x32x16_bf16 v[188:203], v[168:171], v[60:63], v[188:203]
	v_exp_f32_e32 v46, v46
	v_exp_f32_e32 v47, v47
	v_cvt_pk_bf16_f32 v64, v32, v33
	v_cvt_pk_bf16_f32 v65, v34, v35
	v_cvt_pk_bf16_f32 v66, v36, v37
	v_cvt_pk_bf16_f32 v67, v38, v39
	v_cvt_pk_bf16_f32 v68, v40, v41
	v_cvt_pk_bf16_f32 v69, v42, v43
	v_cvt_pk_bf16_f32 v70, v44, v45
	v_cvt_pk_bf16_f32 v71, v46, v47
	v_pk_add_f32 v[232:233], v[232:233], v[32:33]
	v_pk_add_f32 v[232:233], v[232:233], v[34:35]
	v_pk_add_f32 v[232:233], v[232:233], v[36:37]
	v_pk_add_f32 v[232:233], v[232:233], v[38:39]
	v_pk_add_f32 v[232:233], v[232:233], v[40:41]
	v_pk_add_f32 v[232:233], v[232:233], v[42:43]
	v_pk_add_f32 v[232:233], v[232:233], v[44:45]
	v_pk_add_f32 v[232:233], v[232:233], v[46:47]
	ds_read2_b32 v[32:33], v115 offset0:34 offset1:35
	ds_read2_b32 v[34:35], v115 offset0:36 offset1:37
	ds_read2_b32 v[36:37], v115 offset0:42 offset1:43
	ds_read2_b32 v[38:39], v115 offset0:44 offset1:45
	ds_read2_b32 v[40:41], v115 offset0:51 offset1:52
	ds_read2_b32 v[42:43], v115 offset0:53 offset1:54
	ds_read2_b32 v[44:45], v115 offset0:59 offset1:60
	ds_read2_b32 v[46:47], v115 offset0:61 offset1:62
	global_load_dwordx4 v[156:159], v235, s[84:85]
	global_load_dwordx4 v[160:163], v236, s[84:85]
	global_load_dwordx4 v[164:167], v237, s[84:85]
	global_load_dwordx4 v[168:171], v238, s[84:85]
	global_load_dwordx4 v[172:175], v100, s[84:85] offset:768
	global_load_dwordx4 v[176:179], v149, s[84:85] offset:768
	global_load_dwordx4 v[180:183], v100, s[84:85] offset:832
	global_load_dwordx4 v[184:187], v149, s[84:85] offset:832
	s_add_u32 s84, s84, 0x30000
	s_addc_u32 s85, s85, 0
	ds_read_b64_tr_b16 v[204:205], v231
	ds_read_b64_tr_b16 v[206:207], v231 offset:512
	ds_read_b64_tr_b16 v[208:209], v231 offset:2048
	ds_read_b64_tr_b16 v[210:211], v231 offset:2560
	ds_read_b64_tr_b16 v[212:213], v231 offset:1024
	ds_read_b64_tr_b16 v[214:215], v231 offset:1536
	ds_read_b64_tr_b16 v[216:217], v231 offset:3072
	ds_read_b64_tr_b16 v[218:219], v231 offset:3584
	v_exp_f32_e32 v188, v188
	v_exp_f32_e32 v189, v189
	v_exp_f32_e32 v190, v190
	v_exp_f32_e32 v191, v191
	s_waitcnt vmcnt(8)
	ds_write_b128 v247, v[116:119]
	ds_write_b128 v247, v[120:123] offset:1024
	ds_write_b128 v247, v[124:127] offset:2048
	ds_write_b128 v247, v[128:131] offset:3072
	ds_read_b128 v[116:119], v248
	ds_read_b128 v[120:123], v249
	ds_read_b128 v[124:127], v250
	ds_read_b128 v[128:131], v251
	ds_write_b128 v112, v[132:135]
	ds_write_b128 v112, v[136:139] offset:1024
	ds_write_b128 v112, v[140:143] offset:2048
	ds_write_b128 v112, v[144:147] offset:3072
	v_mfma_f32_32x32x16_bf16 v[0:15], v[64:67], v[72:75], v[0:15]
	v_mfma_f32_32x32x16_bf16 v[16:31], v[64:67], v[76:79], v[16:31]
	v_mfma_f32_32x32x16_bf16 v[0:15], v[68:71], v[220:223], v[0:15]
	v_mfma_f32_32x32x16_bf16 v[16:31], v[68:71], v[224:227], v[16:31]
	v_exp_f32_e32 v192, v192
	v_exp_f32_e32 v193, v193
	v_exp_f32_e32 v194, v194
	v_exp_f32_e32 v195, v195
	s_waitcnt lgkmcnt(4)
	v_mfma_f32_32x32x16_bf16 v[32:47], v[116:119], v[48:51], v[32:47]
	v_exp_f32_e32 v196, v196
	v_exp_f32_e32 v197, v197
	v_mfma_f32_32x32x16_bf16 v[32:47], v[120:123], v[52:55], v[32:47]
	v_exp_f32_e32 v198, v198
	v_exp_f32_e32 v199, v199
	v_mfma_f32_32x32x16_bf16 v[32:47], v[124:127], v[56:59], v[32:47]
	v_exp_f32_e32 v200, v200
	v_exp_f32_e32 v201, v201
	v_mfma_f32_32x32x16_bf16 v[32:47], v[128:131], v[60:63], v[32:47]
	v_exp_f32_e32 v202, v202
	v_exp_f32_e32 v203, v203
	v_cvt_pk_bf16_f32 v64, v188, v189
	v_cvt_pk_bf16_f32 v65, v190, v191
	v_cvt_pk_bf16_f32 v66, v192, v193
	v_cvt_pk_bf16_f32 v67, v194, v195
	v_cvt_pk_bf16_f32 v68, v196, v197
	v_cvt_pk_bf16_f32 v69, v198, v199
	v_cvt_pk_bf16_f32 v70, v200, v201
	v_cvt_pk_bf16_f32 v71, v202, v203
	v_pk_add_f32 v[232:233], v[232:233], v[188:189]
	v_pk_add_f32 v[232:233], v[232:233], v[190:191]
	v_pk_add_f32 v[232:233], v[232:233], v[192:193]
	v_pk_add_f32 v[232:233], v[232:233], v[194:195]
	v_pk_add_f32 v[232:233], v[232:233], v[196:197]
	v_pk_add_f32 v[232:233], v[232:233], v[198:199]
	v_pk_add_f32 v[232:233], v[232:233], v[200:201]
	v_pk_add_f32 v[232:233], v[232:233], v[202:203]
	ds_read2_b32 v[188:189], v115 offset0:68 offset1:69
	ds_read2_b32 v[190:191], v115 offset0:70 offset1:71
	ds_read2_b32 v[192:193], v115 offset0:76 offset1:77
	ds_read2_b32 v[194:195], v115 offset0:78 offset1:79
	ds_read2_b32 v[196:197], v115 offset0:85 offset1:86
	ds_read2_b32 v[198:199], v115 offset0:87 offset1:88
	ds_read2_b32 v[200:201], v115 offset0:93 offset1:94
	ds_read2_b32 v[202:203], v115 offset0:95 offset1:96
	global_load_dwordx4 v[116:119], v235, s[84:85]
	global_load_dwordx4 v[120:123], v236, s[84:85]
	global_load_dwordx4 v[124:127], v237, s[84:85]
	global_load_dwordx4 v[128:131], v238, s[84:85]
	global_load_dwordx4 v[132:135], v100, s[84:85] offset:768
	global_load_dwordx4 v[136:139], v149, s[84:85] offset:768
	global_load_dwordx4 v[140:143], v100, s[84:85] offset:832
	global_load_dwordx4 v[144:147], v149, s[84:85] offset:832
	s_add_u32 s84, s84, 0x30000
	s_addc_u32 s85, s85, 0
	ds_read_b64_tr_b16 v[72:73], v231
	ds_read_b64_tr_b16 v[74:75], v231 offset:512
	ds_read_b64_tr_b16 v[76:77], v231 offset:2048
	ds_read_b64_tr_b16 v[78:79], v231 offset:2560
	ds_read_b64_tr_b16 v[220:221], v231 offset:1024
	ds_read_b64_tr_b16 v[222:223], v231 offset:1536
	ds_read_b64_tr_b16 v[224:225], v231 offset:3072
	ds_read_b64_tr_b16 v[226:227], v231 offset:3584
	v_exp_f32_e32 v32, v32
	v_exp_f32_e32 v33, v33
	v_exp_f32_e32 v34, v34
	v_exp_f32_e32 v35, v35
	s_waitcnt vmcnt(8)
	ds_write_b128 v247, v[156:159]
	ds_write_b128 v247, v[160:163] offset:1024
	ds_write_b128 v247, v[164:167] offset:2048
	ds_write_b128 v247, v[168:171] offset:3072
	ds_read_b128 v[156:159], v248
	ds_read_b128 v[160:163], v249
	ds_read_b128 v[164:167], v250
	ds_read_b128 v[168:171], v251
	ds_write_b128 v112, v[172:175]
	ds_write_b128 v112, v[176:179] offset:1024
	ds_write_b128 v112, v[180:183] offset:2048
	ds_write_b128 v112, v[184:187] offset:3072
	v_mfma_f32_32x32x16_bf16 v[0:15], v[64:67], v[204:207], v[0:15]
	v_mfma_f32_32x32x16_bf16 v[16:31], v[64:67], v[208:211], v[16:31]
	v_mfma_f32_32x32x16_bf16 v[0:15], v[68:71], v[212:215], v[0:15]
	v_mfma_f32_32x32x16_bf16 v[16:31], v[68:71], v[216:219], v[16:31]
	v_exp_f32_e32 v36, v36
	v_exp_f32_e32 v37, v37
	v_exp_f32_e32 v38, v38
	v_exp_f32_e32 v39, v39
	s_waitcnt lgkmcnt(4)
	v_mfma_f32_32x32x16_bf16 v[188:203], v[156:159], v[48:51], v[188:203]
	v_exp_f32_e32 v40, v40
	v_exp_f32_e32 v41, v41
	v_mfma_f32_32x32x16_bf16 v[188:203], v[160:163], v[52:55], v[188:203]
	v_exp_f32_e32 v42, v42
	v_exp_f32_e32 v43, v43
	v_mfma_f32_32x32x16_bf16 v[188:203], v[164:167], v[56:59], v[188:203]
	v_exp_f32_e32 v44, v44
	v_exp_f32_e32 v45, v45
	v_mfma_f32_32x32x16_bf16 v[188:203], v[168:171], v[60:63], v[188:203]
	v_exp_f32_e32 v46, v46
	v_exp_f32_e32 v47, v47
	v_cvt_pk_bf16_f32 v64, v32, v33
	v_cvt_pk_bf16_f32 v65, v34, v35
	v_cvt_pk_bf16_f32 v66, v36, v37
	v_cvt_pk_bf16_f32 v67, v38, v39
	v_cvt_pk_bf16_f32 v68, v40, v41
	v_cvt_pk_bf16_f32 v69, v42, v43
	v_cvt_pk_bf16_f32 v70, v44, v45
	v_cvt_pk_bf16_f32 v71, v46, v47
	v_pk_add_f32 v[232:233], v[232:233], v[32:33]
	v_pk_add_f32 v[232:233], v[232:233], v[34:35]
	v_pk_add_f32 v[232:233], v[232:233], v[36:37]
	v_pk_add_f32 v[232:233], v[232:233], v[38:39]
	v_pk_add_f32 v[232:233], v[232:233], v[40:41]
	v_pk_add_f32 v[232:233], v[232:233], v[42:43]
	v_pk_add_f32 v[232:233], v[232:233], v[44:45]
	v_pk_add_f32 v[232:233], v[232:233], v[46:47]
	ds_read2_b32 v[32:33], v115 offset0:102 offset1:103
	ds_read2_b32 v[34:35], v115 offset0:104 offset1:105
	ds_read2_b32 v[36:37], v115 offset0:110 offset1:111
	ds_read2_b32 v[38:39], v115 offset0:112 offset1:113
	ds_read2_b32 v[40:41], v115 offset0:119 offset1:120
	ds_read2_b32 v[42:43], v115 offset0:121 offset1:122
	ds_read2_b32 v[44:45], v115 offset0:127 offset1:128
	ds_read2_b32 v[46:47], v115 offset0:129 offset1:130
	global_load_dwordx4 v[156:159], v235, s[84:85]
	global_load_dwordx4 v[160:163], v236, s[84:85]
	global_load_dwordx4 v[164:167], v237, s[84:85]
	global_load_dwordx4 v[168:171], v238, s[84:85]
	global_load_dwordx4 v[172:175], v100, s[84:85] offset:768
	global_load_dwordx4 v[176:179], v149, s[84:85] offset:768
	global_load_dwordx4 v[180:183], v100, s[84:85] offset:832
	global_load_dwordx4 v[184:187], v149, s[84:85] offset:832
	s_add_u32 s84, s84, 0x30000
	s_addc_u32 s85, s85, 0
	ds_read_b64_tr_b16 v[204:205], v231
	ds_read_b64_tr_b16 v[206:207], v231 offset:512
	ds_read_b64_tr_b16 v[208:209], v231 offset:2048
	ds_read_b64_tr_b16 v[210:211], v231 offset:2560
	ds_read_b64_tr_b16 v[212:213], v231 offset:1024
	ds_read_b64_tr_b16 v[214:215], v231 offset:1536
	ds_read_b64_tr_b16 v[216:217], v231 offset:3072
	ds_read_b64_tr_b16 v[218:219], v231 offset:3584
	v_exp_f32_e32 v188, v188
	v_exp_f32_e32 v189, v189
	v_exp_f32_e32 v190, v190
	v_exp_f32_e32 v191, v191
	s_waitcnt vmcnt(8)
	ds_write_b128 v247, v[116:119]
	ds_write_b128 v247, v[120:123] offset:1024
	ds_write_b128 v247, v[124:127] offset:2048
	ds_write_b128 v247, v[128:131] offset:3072
	ds_read_b128 v[116:119], v248
	ds_read_b128 v[120:123], v249
	ds_read_b128 v[124:127], v250
	ds_read_b128 v[128:131], v251
	ds_write_b128 v112, v[132:135]
	ds_write_b128 v112, v[136:139] offset:1024
	ds_write_b128 v112, v[140:143] offset:2048
	ds_write_b128 v112, v[144:147] offset:3072
	v_mfma_f32_32x32x16_bf16 v[0:15], v[64:67], v[72:75], v[0:15]
	v_mfma_f32_32x32x16_bf16 v[16:31], v[64:67], v[76:79], v[16:31]
	v_mfma_f32_32x32x16_bf16 v[0:15], v[68:71], v[220:223], v[0:15]
	v_mfma_f32_32x32x16_bf16 v[16:31], v[68:71], v[224:227], v[16:31]
	v_exp_f32_e32 v192, v192
	v_exp_f32_e32 v193, v193
	v_exp_f32_e32 v194, v194
	v_exp_f32_e32 v195, v195
	s_waitcnt lgkmcnt(4)
	v_mfma_f32_32x32x16_bf16 v[32:47], v[116:119], v[48:51], v[32:47]
	v_exp_f32_e32 v196, v196
	v_exp_f32_e32 v197, v197
	v_mfma_f32_32x32x16_bf16 v[32:47], v[120:123], v[52:55], v[32:47]
	v_exp_f32_e32 v198, v198
	v_exp_f32_e32 v199, v199
	v_mfma_f32_32x32x16_bf16 v[32:47], v[124:127], v[56:59], v[32:47]
	v_exp_f32_e32 v200, v200
	v_exp_f32_e32 v201, v201
	v_mfma_f32_32x32x16_bf16 v[32:47], v[128:131], v[60:63], v[32:47]
	v_exp_f32_e32 v202, v202
	v_exp_f32_e32 v203, v203
	v_cvt_pk_bf16_f32 v64, v188, v189
	v_cvt_pk_bf16_f32 v65, v190, v191
	v_cvt_pk_bf16_f32 v66, v192, v193
	v_cvt_pk_bf16_f32 v67, v194, v195
	v_cvt_pk_bf16_f32 v68, v196, v197
	v_cvt_pk_bf16_f32 v69, v198, v199
	v_cvt_pk_bf16_f32 v70, v200, v201
	v_cvt_pk_bf16_f32 v71, v202, v203
	v_pk_add_f32 v[232:233], v[232:233], v[188:189]
	v_pk_add_f32 v[232:233], v[232:233], v[190:191]
	v_pk_add_f32 v[232:233], v[232:233], v[192:193]
	v_pk_add_f32 v[232:233], v[232:233], v[194:195]
	v_pk_add_f32 v[232:233], v[232:233], v[196:197]
	v_pk_add_f32 v[232:233], v[232:233], v[198:199]
	v_pk_add_f32 v[232:233], v[232:233], v[200:201]
	v_pk_add_f32 v[232:233], v[232:233], v[202:203]
	ds_read2_b32 v[188:189], v115 offset0:136 offset1:137
	ds_read2_b32 v[190:191], v115 offset0:138 offset1:139
	ds_read2_b32 v[192:193], v115 offset0:144 offset1:145
	ds_read2_b32 v[194:195], v115 offset0:146 offset1:147
	ds_read2_b32 v[196:197], v115 offset0:153 offset1:154
	ds_read2_b32 v[198:199], v115 offset0:155 offset1:156
	ds_read2_b32 v[200:201], v115 offset0:161 offset1:162
	ds_read2_b32 v[202:203], v115 offset0:163 offset1:164
	global_load_dwordx4 v[116:119], v235, s[84:85]
	global_load_dwordx4 v[120:123], v236, s[84:85]
	global_load_dwordx4 v[124:127], v237, s[84:85]
	global_load_dwordx4 v[128:131], v238, s[84:85]
	global_load_dwordx4 v[132:135], v100, s[84:85] offset:768
	global_load_dwordx4 v[136:139], v149, s[84:85] offset:768
	global_load_dwordx4 v[140:143], v100, s[84:85] offset:832
	global_load_dwordx4 v[144:147], v149, s[84:85] offset:832
	s_add_u32 s84, s84, 0x30000
	s_addc_u32 s85, s85, 0
	ds_read_b64_tr_b16 v[72:73], v231
	ds_read_b64_tr_b16 v[74:75], v231 offset:512
	ds_read_b64_tr_b16 v[76:77], v231 offset:2048
	ds_read_b64_tr_b16 v[78:79], v231 offset:2560
	ds_read_b64_tr_b16 v[220:221], v231 offset:1024
	ds_read_b64_tr_b16 v[222:223], v231 offset:1536
	ds_read_b64_tr_b16 v[224:225], v231 offset:3072
	ds_read_b64_tr_b16 v[226:227], v231 offset:3584
	v_exp_f32_e32 v32, v32
	v_exp_f32_e32 v33, v33
	v_exp_f32_e32 v34, v34
	v_exp_f32_e32 v35, v35
	s_waitcnt vmcnt(8)
	ds_write_b128 v247, v[156:159]
	ds_write_b128 v247, v[160:163] offset:1024
	ds_write_b128 v247, v[164:167] offset:2048
	ds_write_b128 v247, v[168:171] offset:3072
	ds_read_b128 v[156:159], v248
	ds_read_b128 v[160:163], v249
	ds_read_b128 v[164:167], v250
	ds_read_b128 v[168:171], v251
	ds_write_b128 v112, v[172:175]
	ds_write_b128 v112, v[176:179] offset:1024
	ds_write_b128 v112, v[180:183] offset:2048
	ds_write_b128 v112, v[184:187] offset:3072
	v_mfma_f32_32x32x16_bf16 v[0:15], v[64:67], v[204:207], v[0:15]
	v_mfma_f32_32x32x16_bf16 v[16:31], v[64:67], v[208:211], v[16:31]
	v_mfma_f32_32x32x16_bf16 v[0:15], v[68:71], v[212:215], v[0:15]
	v_mfma_f32_32x32x16_bf16 v[16:31], v[68:71], v[216:219], v[16:31]
	v_exp_f32_e32 v36, v36
	v_exp_f32_e32 v37, v37
	v_exp_f32_e32 v38, v38
	v_exp_f32_e32 v39, v39
	s_waitcnt lgkmcnt(4)
	v_mfma_f32_32x32x16_bf16 v[188:203], v[156:159], v[48:51], v[188:203]
	v_exp_f32_e32 v40, v40
	v_exp_f32_e32 v41, v41
	v_mfma_f32_32x32x16_bf16 v[188:203], v[160:163], v[52:55], v[188:203]
	v_exp_f32_e32 v42, v42
	v_exp_f32_e32 v43, v43
	v_mfma_f32_32x32x16_bf16 v[188:203], v[164:167], v[56:59], v[188:203]
	v_exp_f32_e32 v44, v44
	v_exp_f32_e32 v45, v45
	v_mfma_f32_32x32x16_bf16 v[188:203], v[168:171], v[60:63], v[188:203]
	v_exp_f32_e32 v46, v46
	v_exp_f32_e32 v47, v47
	v_cvt_pk_bf16_f32 v64, v32, v33
	v_cvt_pk_bf16_f32 v65, v34, v35
	v_cvt_pk_bf16_f32 v66, v36, v37
	v_cvt_pk_bf16_f32 v67, v38, v39
	v_cvt_pk_bf16_f32 v68, v40, v41
	v_cvt_pk_bf16_f32 v69, v42, v43
	v_cvt_pk_bf16_f32 v70, v44, v45
	v_cvt_pk_bf16_f32 v71, v46, v47
	v_pk_add_f32 v[232:233], v[232:233], v[32:33]
	v_pk_add_f32 v[232:233], v[232:233], v[34:35]
	v_pk_add_f32 v[232:233], v[232:233], v[36:37]
	v_pk_add_f32 v[232:233], v[232:233], v[38:39]
	v_pk_add_f32 v[232:233], v[232:233], v[40:41]
	v_pk_add_f32 v[232:233], v[232:233], v[42:43]
	v_pk_add_f32 v[232:233], v[232:233], v[44:45]
	v_pk_add_f32 v[232:233], v[232:233], v[46:47]
	ds_read2_b32 v[32:33], v115 offset0:170 offset1:171
	ds_read2_b32 v[34:35], v115 offset0:172 offset1:173
	ds_read2_b32 v[36:37], v115 offset0:178 offset1:179
	ds_read2_b32 v[38:39], v115 offset0:180 offset1:181
	ds_read2_b32 v[40:41], v115 offset0:187 offset1:188
	ds_read2_b32 v[42:43], v115 offset0:189 offset1:190
	ds_read2_b32 v[44:45], v115 offset0:195 offset1:196
	ds_read2_b32 v[46:47], v115 offset0:197 offset1:198
	global_load_dwordx4 v[156:159], v235, s[84:85]
	global_load_dwordx4 v[160:163], v236, s[84:85]
	global_load_dwordx4 v[164:167], v237, s[84:85]
	global_load_dwordx4 v[168:171], v238, s[84:85]
	global_load_dwordx4 v[172:175], v100, s[84:85] offset:768
	global_load_dwordx4 v[176:179], v149, s[84:85] offset:768
	global_load_dwordx4 v[180:183], v100, s[84:85] offset:832
	global_load_dwordx4 v[184:187], v149, s[84:85] offset:832
	s_add_u32 s84, s84, 0x30000
	s_addc_u32 s85, s85, 0
	ds_read_b64_tr_b16 v[204:205], v231
	ds_read_b64_tr_b16 v[206:207], v231 offset:512
	ds_read_b64_tr_b16 v[208:209], v231 offset:2048
	ds_read_b64_tr_b16 v[210:211], v231 offset:2560
	ds_read_b64_tr_b16 v[212:213], v231 offset:1024
	ds_read_b64_tr_b16 v[214:215], v231 offset:1536
	ds_read_b64_tr_b16 v[216:217], v231 offset:3072
	ds_read_b64_tr_b16 v[218:219], v231 offset:3584
	v_exp_f32_e32 v188, v188
	v_exp_f32_e32 v189, v189
	v_exp_f32_e32 v190, v190
	v_exp_f32_e32 v191, v191
	s_waitcnt vmcnt(8)
	ds_write_b128 v247, v[116:119]
	ds_write_b128 v247, v[120:123] offset:1024
	ds_write_b128 v247, v[124:127] offset:2048
	ds_write_b128 v247, v[128:131] offset:3072
	ds_read_b128 v[116:119], v248
	ds_read_b128 v[120:123], v249
	ds_read_b128 v[124:127], v250
	ds_read_b128 v[128:131], v251
	ds_write_b128 v112, v[132:135]
	ds_write_b128 v112, v[136:139] offset:1024
	ds_write_b128 v112, v[140:143] offset:2048
	ds_write_b128 v112, v[144:147] offset:3072
	v_mfma_f32_32x32x16_bf16 v[0:15], v[64:67], v[72:75], v[0:15]
	v_mfma_f32_32x32x16_bf16 v[16:31], v[64:67], v[76:79], v[16:31]
	v_mfma_f32_32x32x16_bf16 v[0:15], v[68:71], v[220:223], v[0:15]
	v_mfma_f32_32x32x16_bf16 v[16:31], v[68:71], v[224:227], v[16:31]
	v_exp_f32_e32 v192, v192
	v_exp_f32_e32 v193, v193
	v_exp_f32_e32 v194, v194
	v_exp_f32_e32 v195, v195
	s_waitcnt lgkmcnt(4)
	v_mfma_f32_32x32x16_bf16 v[32:47], v[116:119], v[48:51], v[32:47]
	v_exp_f32_e32 v196, v196
	v_exp_f32_e32 v197, v197
	v_mfma_f32_32x32x16_bf16 v[32:47], v[120:123], v[52:55], v[32:47]
	v_exp_f32_e32 v198, v198
	v_exp_f32_e32 v199, v199
	v_mfma_f32_32x32x16_bf16 v[32:47], v[124:127], v[56:59], v[32:47]
	v_exp_f32_e32 v200, v200
	v_exp_f32_e32 v201, v201
	v_mfma_f32_32x32x16_bf16 v[32:47], v[128:131], v[60:63], v[32:47]
	v_exp_f32_e32 v202, v202
	v_exp_f32_e32 v203, v203
	v_cvt_pk_bf16_f32 v64, v188, v189
	v_cvt_pk_bf16_f32 v65, v190, v191
	v_cvt_pk_bf16_f32 v66, v192, v193
	v_cvt_pk_bf16_f32 v67, v194, v195
	v_cvt_pk_bf16_f32 v68, v196, v197
	v_cvt_pk_bf16_f32 v69, v198, v199
	v_cvt_pk_bf16_f32 v70, v200, v201
	v_cvt_pk_bf16_f32 v71, v202, v203
	v_pk_add_f32 v[232:233], v[232:233], v[188:189]
	v_pk_add_f32 v[232:233], v[232:233], v[190:191]
	v_pk_add_f32 v[232:233], v[232:233], v[192:193]
	v_pk_add_f32 v[232:233], v[232:233], v[194:195]
	v_pk_add_f32 v[232:233], v[232:233], v[196:197]
	v_pk_add_f32 v[232:233], v[232:233], v[198:199]
	v_pk_add_f32 v[232:233], v[232:233], v[200:201]
	v_pk_add_f32 v[232:233], v[232:233], v[202:203]
	ds_read2_b32 v[188:189], v115 offset0:204 offset1:205
	ds_read2_b32 v[190:191], v115 offset0:206 offset1:207
	ds_read2_b32 v[192:193], v115 offset0:212 offset1:213
	ds_read2_b32 v[194:195], v115 offset0:214 offset1:215
	ds_read2_b32 v[196:197], v115 offset0:221 offset1:222
	ds_read2_b32 v[198:199], v115 offset0:223 offset1:224
	ds_read2_b32 v[200:201], v115 offset0:229 offset1:230
	ds_read2_b32 v[202:203], v115 offset0:231 offset1:232
	global_load_dwordx4 v[116:119], v235, s[84:85]
	global_load_dwordx4 v[120:123], v236, s[84:85]
	global_load_dwordx4 v[124:127], v237, s[84:85]
	global_load_dwordx4 v[128:131], v238, s[84:85]
	global_load_dwordx4 v[132:135], v100, s[84:85] offset:768
	global_load_dwordx4 v[136:139], v149, s[84:85] offset:768
	global_load_dwordx4 v[140:143], v100, s[84:85] offset:832
	global_load_dwordx4 v[144:147], v149, s[84:85] offset:832
	s_add_u32 s84, s84, 0x30000
	s_addc_u32 s85, s85, 0
	ds_read_b64_tr_b16 v[72:73], v231
	ds_read_b64_tr_b16 v[74:75], v231 offset:512
	ds_read_b64_tr_b16 v[76:77], v231 offset:2048
	ds_read_b64_tr_b16 v[78:79], v231 offset:2560
	ds_read_b64_tr_b16 v[220:221], v231 offset:1024
	ds_read_b64_tr_b16 v[222:223], v231 offset:1536
	ds_read_b64_tr_b16 v[224:225], v231 offset:3072
	ds_read_b64_tr_b16 v[226:227], v231 offset:3584
	v_exp_f32_e32 v32, v32
	v_exp_f32_e32 v33, v33
	v_exp_f32_e32 v34, v34
	v_exp_f32_e32 v35, v35
	s_waitcnt vmcnt(8)
	ds_write_b128 v247, v[156:159]
	ds_write_b128 v247, v[160:163] offset:1024
	ds_write_b128 v247, v[164:167] offset:2048
	ds_write_b128 v247, v[168:171] offset:3072
	ds_read_b128 v[156:159], v248
	ds_read_b128 v[160:163], v249
	ds_read_b128 v[164:167], v250
	ds_read_b128 v[168:171], v251
	ds_write_b128 v112, v[172:175]
	ds_write_b128 v112, v[176:179] offset:1024
	ds_write_b128 v112, v[180:183] offset:2048
	ds_write_b128 v112, v[184:187] offset:3072
	v_mfma_f32_32x32x16_bf16 v[0:15], v[64:67], v[204:207], v[0:15]
	v_mfma_f32_32x32x16_bf16 v[16:31], v[64:67], v[208:211], v[16:31]
	v_mfma_f32_32x32x16_bf16 v[0:15], v[68:71], v[212:215], v[0:15]
	v_mfma_f32_32x32x16_bf16 v[16:31], v[68:71], v[216:219], v[16:31]
	v_exp_f32_e32 v36, v36
	v_exp_f32_e32 v37, v37
	v_exp_f32_e32 v38, v38
	v_exp_f32_e32 v39, v39
	s_waitcnt lgkmcnt(4)
	v_mfma_f32_32x32x16_bf16 v[188:203], v[156:159], v[48:51], v[188:203]
	v_exp_f32_e32 v40, v40
	v_exp_f32_e32 v41, v41
	v_mfma_f32_32x32x16_bf16 v[188:203], v[160:163], v[52:55], v[188:203]
	v_exp_f32_e32 v42, v42
	v_exp_f32_e32 v43, v43
	v_mfma_f32_32x32x16_bf16 v[188:203], v[164:167], v[56:59], v[188:203]
	v_exp_f32_e32 v44, v44
	v_exp_f32_e32 v45, v45
	v_mfma_f32_32x32x16_bf16 v[188:203], v[168:171], v[60:63], v[188:203]
	v_exp_f32_e32 v46, v46
	v_exp_f32_e32 v47, v47
	v_cvt_pk_bf16_f32 v64, v32, v33
	v_cvt_pk_bf16_f32 v65, v34, v35
	v_cvt_pk_bf16_f32 v66, v36, v37
	v_cvt_pk_bf16_f32 v67, v38, v39
	v_cvt_pk_bf16_f32 v68, v40, v41
	v_cvt_pk_bf16_f32 v69, v42, v43
	v_cvt_pk_bf16_f32 v70, v44, v45
	v_cvt_pk_bf16_f32 v71, v46, v47
	v_pk_add_f32 v[232:233], v[232:233], v[32:33]
	v_pk_add_f32 v[232:233], v[232:233], v[34:35]
	v_pk_add_f32 v[232:233], v[232:233], v[36:37]
	v_pk_add_f32 v[232:233], v[232:233], v[38:39]
	v_pk_add_f32 v[232:233], v[232:233], v[40:41]
	v_pk_add_f32 v[232:233], v[232:233], v[42:43]
	v_pk_add_f32 v[232:233], v[232:233], v[44:45]
	v_pk_add_f32 v[232:233], v[232:233], v[46:47]
	v_add_u32_e32 v115, 952, v115
	ds_read2_b32 v[32:33], v115 offset0:0 offset1:1
	ds_read2_b32 v[34:35], v115 offset0:2 offset1:3
	ds_read2_b32 v[36:37], v115 offset0:8 offset1:9
	ds_read2_b32 v[38:39], v115 offset0:10 offset1:11
	ds_read2_b32 v[40:41], v115 offset0:17 offset1:18
	ds_read2_b32 v[42:43], v115 offset0:19 offset1:20
	ds_read2_b32 v[44:45], v115 offset0:25 offset1:26
	ds_read2_b32 v[46:47], v115 offset0:27 offset1:28
	global_load_dwordx4 v[156:159], v235, s[84:85]
	global_load_dwordx4 v[160:163], v236, s[84:85]
	global_load_dwordx4 v[164:167], v237, s[84:85]
	global_load_dwordx4 v[168:171], v238, s[84:85]
	global_load_dwordx4 v[172:175], v100, s[84:85] offset:768
	global_load_dwordx4 v[176:179], v149, s[84:85] offset:768
	global_load_dwordx4 v[180:183], v100, s[84:85] offset:832
	global_load_dwordx4 v[184:187], v149, s[84:85] offset:832
	s_add_u32 s84, s84, 0x30000
	s_addc_u32 s85, s85, 0
	ds_read_b64_tr_b16 v[204:205], v231
	ds_read_b64_tr_b16 v[206:207], v231 offset:512
	ds_read_b64_tr_b16 v[208:209], v231 offset:2048
	ds_read_b64_tr_b16 v[210:211], v231 offset:2560
	ds_read_b64_tr_b16 v[212:213], v231 offset:1024
	ds_read_b64_tr_b16 v[214:215], v231 offset:1536
	ds_read_b64_tr_b16 v[216:217], v231 offset:3072
	ds_read_b64_tr_b16 v[218:219], v231 offset:3584
	v_exp_f32_e32 v188, v188
	v_exp_f32_e32 v189, v189
	v_exp_f32_e32 v190, v190
	v_exp_f32_e32 v191, v191
	s_waitcnt vmcnt(8)
	ds_write_b128 v247, v[116:119]
	ds_write_b128 v247, v[120:123] offset:1024
	ds_write_b128 v247, v[124:127] offset:2048
	ds_write_b128 v247, v[128:131] offset:3072
	ds_read_b128 v[116:119], v248
	ds_read_b128 v[120:123], v249
	ds_read_b128 v[124:127], v250
	ds_read_b128 v[128:131], v251
	ds_write_b128 v112, v[132:135]
	ds_write_b128 v112, v[136:139] offset:1024
	ds_write_b128 v112, v[140:143] offset:2048
	ds_write_b128 v112, v[144:147] offset:3072
	v_mfma_f32_32x32x16_bf16 v[0:15], v[64:67], v[72:75], v[0:15]
	v_mfma_f32_32x32x16_bf16 v[16:31], v[64:67], v[76:79], v[16:31]
	v_mfma_f32_32x32x16_bf16 v[0:15], v[68:71], v[220:223], v[0:15]
	v_mfma_f32_32x32x16_bf16 v[16:31], v[68:71], v[224:227], v[16:31]
	v_exp_f32_e32 v192, v192
	v_exp_f32_e32 v193, v193
	v_exp_f32_e32 v194, v194
	v_exp_f32_e32 v195, v195
	s_waitcnt lgkmcnt(4)
	v_mfma_f32_32x32x16_bf16 v[32:47], v[116:119], v[48:51], v[32:47]
	v_exp_f32_e32 v196, v196
	v_exp_f32_e32 v197, v197
	v_mfma_f32_32x32x16_bf16 v[32:47], v[120:123], v[52:55], v[32:47]
	v_exp_f32_e32 v198, v198
	v_exp_f32_e32 v199, v199
	v_mfma_f32_32x32x16_bf16 v[32:47], v[124:127], v[56:59], v[32:47]
	v_exp_f32_e32 v200, v200
	v_exp_f32_e32 v201, v201
	v_mfma_f32_32x32x16_bf16 v[32:47], v[128:131], v[60:63], v[32:47]
	v_exp_f32_e32 v202, v202
	v_exp_f32_e32 v203, v203
	v_cvt_pk_bf16_f32 v64, v188, v189
	v_cvt_pk_bf16_f32 v65, v190, v191
	v_cvt_pk_bf16_f32 v66, v192, v193
	v_cvt_pk_bf16_f32 v67, v194, v195
	v_cvt_pk_bf16_f32 v68, v196, v197
	v_cvt_pk_bf16_f32 v69, v198, v199
	v_cvt_pk_bf16_f32 v70, v200, v201
	v_cvt_pk_bf16_f32 v71, v202, v203
	v_pk_add_f32 v[232:233], v[232:233], v[188:189]
	v_pk_add_f32 v[232:233], v[232:233], v[190:191]
	v_pk_add_f32 v[232:233], v[232:233], v[192:193]
	v_pk_add_f32 v[232:233], v[232:233], v[194:195]
	v_pk_add_f32 v[232:233], v[232:233], v[196:197]
	v_pk_add_f32 v[232:233], v[232:233], v[198:199]
	v_pk_add_f32 v[232:233], v[232:233], v[200:201]
	v_pk_add_f32 v[232:233], v[232:233], v[202:203]
	ds_read2_b32 v[188:189], v115 offset0:34 offset1:35
	ds_read2_b32 v[190:191], v115 offset0:36 offset1:37
	ds_read2_b32 v[192:193], v115 offset0:42 offset1:43
	ds_read2_b32 v[194:195], v115 offset0:44 offset1:45
	ds_read2_b32 v[196:197], v115 offset0:51 offset1:52
	ds_read2_b32 v[198:199], v115 offset0:53 offset1:54
	ds_read2_b32 v[200:201], v115 offset0:59 offset1:60
	ds_read2_b32 v[202:203], v115 offset0:61 offset1:62
	global_load_dwordx4 v[116:119], v235, s[84:85]
	global_load_dwordx4 v[120:123], v236, s[84:85]
	global_load_dwordx4 v[124:127], v237, s[84:85]
	global_load_dwordx4 v[128:131], v238, s[84:85]
	global_load_dwordx4 v[132:135], v100, s[84:85] offset:768
	global_load_dwordx4 v[136:139], v149, s[84:85] offset:768
	global_load_dwordx4 v[140:143], v100, s[84:85] offset:832
	global_load_dwordx4 v[144:147], v149, s[84:85] offset:832
	s_add_u32 s84, s84, 0x30000
	s_addc_u32 s85, s85, 0
	ds_read_b64_tr_b16 v[72:73], v231
	ds_read_b64_tr_b16 v[74:75], v231 offset:512
	ds_read_b64_tr_b16 v[76:77], v231 offset:2048
	ds_read_b64_tr_b16 v[78:79], v231 offset:2560
	ds_read_b64_tr_b16 v[220:221], v231 offset:1024
	ds_read_b64_tr_b16 v[222:223], v231 offset:1536
	ds_read_b64_tr_b16 v[224:225], v231 offset:3072
	ds_read_b64_tr_b16 v[226:227], v231 offset:3584
	v_exp_f32_e32 v32, v32
	v_exp_f32_e32 v33, v33
	v_exp_f32_e32 v34, v34
	v_exp_f32_e32 v35, v35
	s_waitcnt vmcnt(8)
	ds_write_b128 v247, v[156:159]
	ds_write_b128 v247, v[160:163] offset:1024
	ds_write_b128 v247, v[164:167] offset:2048
	ds_write_b128 v247, v[168:171] offset:3072
	ds_read_b128 v[156:159], v248
	ds_read_b128 v[160:163], v249
	ds_read_b128 v[164:167], v250
	ds_read_b128 v[168:171], v251
	ds_write_b128 v112, v[172:175]
	ds_write_b128 v112, v[176:179] offset:1024
	ds_write_b128 v112, v[180:183] offset:2048
	ds_write_b128 v112, v[184:187] offset:3072
	v_mfma_f32_32x32x16_bf16 v[0:15], v[64:67], v[204:207], v[0:15]
	v_mfma_f32_32x32x16_bf16 v[16:31], v[64:67], v[208:211], v[16:31]
	v_mfma_f32_32x32x16_bf16 v[0:15], v[68:71], v[212:215], v[0:15]
	v_mfma_f32_32x32x16_bf16 v[16:31], v[68:71], v[216:219], v[16:31]
	v_exp_f32_e32 v36, v36
	v_exp_f32_e32 v37, v37
	v_exp_f32_e32 v38, v38
	v_exp_f32_e32 v39, v39
	s_waitcnt lgkmcnt(4)
	v_mfma_f32_32x32x16_bf16 v[188:203], v[156:159], v[48:51], v[188:203]
	v_exp_f32_e32 v40, v40
	v_exp_f32_e32 v41, v41
	v_mfma_f32_32x32x16_bf16 v[188:203], v[160:163], v[52:55], v[188:203]
	v_exp_f32_e32 v42, v42
	v_exp_f32_e32 v43, v43
	v_mfma_f32_32x32x16_bf16 v[188:203], v[164:167], v[56:59], v[188:203]
	v_exp_f32_e32 v44, v44
	v_exp_f32_e32 v45, v45
	v_mfma_f32_32x32x16_bf16 v[188:203], v[168:171], v[60:63], v[188:203]
	v_exp_f32_e32 v46, v46
	v_exp_f32_e32 v47, v47
	v_cvt_pk_bf16_f32 v64, v32, v33
	v_cvt_pk_bf16_f32 v65, v34, v35
	v_cvt_pk_bf16_f32 v66, v36, v37
	v_cvt_pk_bf16_f32 v67, v38, v39
	v_cvt_pk_bf16_f32 v68, v40, v41
	v_cvt_pk_bf16_f32 v69, v42, v43
	v_cvt_pk_bf16_f32 v70, v44, v45
	v_cvt_pk_bf16_f32 v71, v46, v47
	v_pk_add_f32 v[232:233], v[232:233], v[32:33]
	v_pk_add_f32 v[232:233], v[232:233], v[34:35]
	v_pk_add_f32 v[232:233], v[232:233], v[36:37]
	v_pk_add_f32 v[232:233], v[232:233], v[38:39]
	v_pk_add_f32 v[232:233], v[232:233], v[40:41]
	v_pk_add_f32 v[232:233], v[232:233], v[42:43]
	v_pk_add_f32 v[232:233], v[232:233], v[44:45]
	v_pk_add_f32 v[232:233], v[232:233], v[46:47]
	ds_read2_b32 v[32:33], v115 offset0:68 offset1:69
	ds_read2_b32 v[34:35], v115 offset0:70 offset1:71
	ds_read2_b32 v[36:37], v115 offset0:76 offset1:77
	ds_read2_b32 v[38:39], v115 offset0:78 offset1:79
	ds_read2_b32 v[40:41], v115 offset0:85 offset1:86
	ds_read2_b32 v[42:43], v115 offset0:87 offset1:88
	ds_read2_b32 v[44:45], v115 offset0:93 offset1:94
	ds_read2_b32 v[46:47], v115 offset0:95 offset1:96
	global_load_dwordx4 v[156:159], v235, s[84:85]
	global_load_dwordx4 v[160:163], v236, s[84:85]
	global_load_dwordx4 v[164:167], v237, s[84:85]
	global_load_dwordx4 v[168:171], v238, s[84:85]
	global_load_dwordx4 v[172:175], v100, s[84:85] offset:768
	global_load_dwordx4 v[176:179], v149, s[84:85] offset:768
	global_load_dwordx4 v[180:183], v100, s[84:85] offset:832
	global_load_dwordx4 v[184:187], v149, s[84:85] offset:832
	s_add_u32 s84, s84, 0x30000
	s_addc_u32 s85, s85, 0
	ds_read_b64_tr_b16 v[204:205], v231
	ds_read_b64_tr_b16 v[206:207], v231 offset:512
	ds_read_b64_tr_b16 v[208:209], v231 offset:2048
	ds_read_b64_tr_b16 v[210:211], v231 offset:2560
	ds_read_b64_tr_b16 v[212:213], v231 offset:1024
	ds_read_b64_tr_b16 v[214:215], v231 offset:1536
	ds_read_b64_tr_b16 v[216:217], v231 offset:3072
	ds_read_b64_tr_b16 v[218:219], v231 offset:3584
	v_exp_f32_e32 v188, v188
	v_exp_f32_e32 v189, v189
	v_exp_f32_e32 v190, v190
	v_exp_f32_e32 v191, v191
	s_waitcnt vmcnt(8)
	ds_write_b128 v247, v[116:119]
	ds_write_b128 v247, v[120:123] offset:1024
	ds_write_b128 v247, v[124:127] offset:2048
	ds_write_b128 v247, v[128:131] offset:3072
	ds_read_b128 v[116:119], v248
	ds_read_b128 v[120:123], v249
	ds_read_b128 v[124:127], v250
	ds_read_b128 v[128:131], v251
	ds_write_b128 v112, v[132:135]
	ds_write_b128 v112, v[136:139] offset:1024
	ds_write_b128 v112, v[140:143] offset:2048
	ds_write_b128 v112, v[144:147] offset:3072
	v_mfma_f32_32x32x16_bf16 v[0:15], v[64:67], v[72:75], v[0:15]
	v_mfma_f32_32x32x16_bf16 v[16:31], v[64:67], v[76:79], v[16:31]
	v_mfma_f32_32x32x16_bf16 v[0:15], v[68:71], v[220:223], v[0:15]
	v_mfma_f32_32x32x16_bf16 v[16:31], v[68:71], v[224:227], v[16:31]
	v_exp_f32_e32 v192, v192
	v_exp_f32_e32 v193, v193
	v_exp_f32_e32 v194, v194
	v_exp_f32_e32 v195, v195
	s_waitcnt lgkmcnt(4)
	v_mfma_f32_32x32x16_bf16 v[32:47], v[116:119], v[48:51], v[32:47]
	v_exp_f32_e32 v196, v196
	v_exp_f32_e32 v197, v197
	v_mfma_f32_32x32x16_bf16 v[32:47], v[120:123], v[52:55], v[32:47]
	v_exp_f32_e32 v198, v198
	v_exp_f32_e32 v199, v199
	v_mfma_f32_32x32x16_bf16 v[32:47], v[124:127], v[56:59], v[32:47]
	v_exp_f32_e32 v200, v200
	v_exp_f32_e32 v201, v201
	v_mfma_f32_32x32x16_bf16 v[32:47], v[128:131], v[60:63], v[32:47]
	v_exp_f32_e32 v202, v202
	v_exp_f32_e32 v203, v203
	v_cvt_pk_bf16_f32 v64, v188, v189
	v_cvt_pk_bf16_f32 v65, v190, v191
	v_cvt_pk_bf16_f32 v66, v192, v193
	v_cvt_pk_bf16_f32 v67, v194, v195
	v_cvt_pk_bf16_f32 v68, v196, v197
	v_cvt_pk_bf16_f32 v69, v198, v199
	v_cvt_pk_bf16_f32 v70, v200, v201
	v_cvt_pk_bf16_f32 v71, v202, v203
	v_pk_add_f32 v[232:233], v[232:233], v[188:189]
	v_pk_add_f32 v[232:233], v[232:233], v[190:191]
	v_pk_add_f32 v[232:233], v[232:233], v[192:193]
	v_pk_add_f32 v[232:233], v[232:233], v[194:195]
	v_pk_add_f32 v[232:233], v[232:233], v[196:197]
	v_pk_add_f32 v[232:233], v[232:233], v[198:199]
	v_pk_add_f32 v[232:233], v[232:233], v[200:201]
	v_pk_add_f32 v[232:233], v[232:233], v[202:203]
	ds_read2_b32 v[188:189], v115 offset0:102 offset1:103
	ds_read2_b32 v[190:191], v115 offset0:104 offset1:105
	ds_read2_b32 v[192:193], v115 offset0:110 offset1:111
	ds_read2_b32 v[194:195], v115 offset0:112 offset1:113
	ds_read2_b32 v[196:197], v115 offset0:119 offset1:120
	ds_read2_b32 v[198:199], v115 offset0:121 offset1:122
	ds_read2_b32 v[200:201], v115 offset0:127 offset1:128
	ds_read2_b32 v[202:203], v115 offset0:129 offset1:130
	global_load_dwordx4 v[116:119], v235, s[84:85]
	global_load_dwordx4 v[120:123], v236, s[84:85]
	global_load_dwordx4 v[124:127], v237, s[84:85]
	global_load_dwordx4 v[128:131], v238, s[84:85]
	global_load_dwordx4 v[132:135], v100, s[84:85] offset:768
	global_load_dwordx4 v[136:139], v149, s[84:85] offset:768
	global_load_dwordx4 v[140:143], v100, s[84:85] offset:832
	global_load_dwordx4 v[144:147], v149, s[84:85] offset:832
	s_add_u32 s84, s84, 0x30000
	s_addc_u32 s85, s85, 0
	ds_read_b64_tr_b16 v[72:73], v231
	ds_read_b64_tr_b16 v[74:75], v231 offset:512
	ds_read_b64_tr_b16 v[76:77], v231 offset:2048
	ds_read_b64_tr_b16 v[78:79], v231 offset:2560
	ds_read_b64_tr_b16 v[220:221], v231 offset:1024
	ds_read_b64_tr_b16 v[222:223], v231 offset:1536
	ds_read_b64_tr_b16 v[224:225], v231 offset:3072
	ds_read_b64_tr_b16 v[226:227], v231 offset:3584
	v_exp_f32_e32 v32, v32
	v_exp_f32_e32 v33, v33
	v_exp_f32_e32 v34, v34
	v_exp_f32_e32 v35, v35
	s_waitcnt vmcnt(8)
	ds_write_b128 v247, v[156:159]
	ds_write_b128 v247, v[160:163] offset:1024
	ds_write_b128 v247, v[164:167] offset:2048
	ds_write_b128 v247, v[168:171] offset:3072
	ds_read_b128 v[156:159], v248
	ds_read_b128 v[160:163], v249
	ds_read_b128 v[164:167], v250
	ds_read_b128 v[168:171], v251
	ds_write_b128 v112, v[172:175]
	ds_write_b128 v112, v[176:179] offset:1024
	ds_write_b128 v112, v[180:183] offset:2048
	ds_write_b128 v112, v[184:187] offset:3072
	v_mfma_f32_32x32x16_bf16 v[0:15], v[64:67], v[204:207], v[0:15]
	v_mfma_f32_32x32x16_bf16 v[16:31], v[64:67], v[208:211], v[16:31]
	v_mfma_f32_32x32x16_bf16 v[0:15], v[68:71], v[212:215], v[0:15]
	v_mfma_f32_32x32x16_bf16 v[16:31], v[68:71], v[216:219], v[16:31]
	v_exp_f32_e32 v36, v36
	v_exp_f32_e32 v37, v37
	v_exp_f32_e32 v38, v38
	v_exp_f32_e32 v39, v39
	s_waitcnt lgkmcnt(4)
	v_mfma_f32_32x32x16_bf16 v[188:203], v[156:159], v[48:51], v[188:203]
	v_exp_f32_e32 v40, v40
	v_exp_f32_e32 v41, v41
	v_mfma_f32_32x32x16_bf16 v[188:203], v[160:163], v[52:55], v[188:203]
	v_exp_f32_e32 v42, v42
	v_exp_f32_e32 v43, v43
	v_mfma_f32_32x32x16_bf16 v[188:203], v[164:167], v[56:59], v[188:203]
	v_exp_f32_e32 v44, v44
	v_exp_f32_e32 v45, v45
	v_mfma_f32_32x32x16_bf16 v[188:203], v[168:171], v[60:63], v[188:203]
	v_exp_f32_e32 v46, v46
	v_exp_f32_e32 v47, v47
	v_cvt_pk_bf16_f32 v64, v32, v33
	v_cvt_pk_bf16_f32 v65, v34, v35
	v_cvt_pk_bf16_f32 v66, v36, v37
	v_cvt_pk_bf16_f32 v67, v38, v39
	v_cvt_pk_bf16_f32 v68, v40, v41
	v_cvt_pk_bf16_f32 v69, v42, v43
	v_cvt_pk_bf16_f32 v70, v44, v45
	v_cvt_pk_bf16_f32 v71, v46, v47
	v_pk_add_f32 v[232:233], v[232:233], v[32:33]
	v_pk_add_f32 v[232:233], v[232:233], v[34:35]
	v_pk_add_f32 v[232:233], v[232:233], v[36:37]
	v_pk_add_f32 v[232:233], v[232:233], v[38:39]
	v_pk_add_f32 v[232:233], v[232:233], v[40:41]
	v_pk_add_f32 v[232:233], v[232:233], v[42:43]
	v_pk_add_f32 v[232:233], v[232:233], v[44:45]
	v_pk_add_f32 v[232:233], v[232:233], v[46:47]
	ds_read2_b32 v[32:33], v115 offset0:136 offset1:137
	ds_read2_b32 v[34:35], v115 offset0:138 offset1:139
	ds_read2_b32 v[36:37], v115 offset0:144 offset1:145
	ds_read2_b32 v[38:39], v115 offset0:146 offset1:147
	ds_read2_b32 v[40:41], v115 offset0:153 offset1:154
	ds_read2_b32 v[42:43], v115 offset0:155 offset1:156
	ds_read2_b32 v[44:45], v115 offset0:161 offset1:162
	ds_read2_b32 v[46:47], v115 offset0:163 offset1:164
	global_load_dwordx4 v[156:159], v235, s[84:85]
	global_load_dwordx4 v[160:163], v236, s[84:85]
	global_load_dwordx4 v[164:167], v237, s[84:85]
	global_load_dwordx4 v[168:171], v238, s[84:85]
	global_load_dwordx4 v[172:175], v100, s[84:85] offset:768
	global_load_dwordx4 v[176:179], v149, s[84:85] offset:768
	global_load_dwordx4 v[180:183], v100, s[84:85] offset:832
	global_load_dwordx4 v[184:187], v149, s[84:85] offset:832
	ds_read_b64_tr_b16 v[204:205], v231
	ds_read_b64_tr_b16 v[206:207], v231 offset:512
	ds_read_b64_tr_b16 v[208:209], v231 offset:2048
	ds_read_b64_tr_b16 v[210:211], v231 offset:2560
	ds_read_b64_tr_b16 v[212:213], v231 offset:1024
	ds_read_b64_tr_b16 v[214:215], v231 offset:1536
	ds_read_b64_tr_b16 v[216:217], v231 offset:3072
	ds_read_b64_tr_b16 v[218:219], v231 offset:3584
	v_exp_f32_e32 v188, v188
	v_exp_f32_e32 v189, v189
	v_exp_f32_e32 v190, v190
	v_exp_f32_e32 v191, v191
	s_waitcnt vmcnt(8)
	ds_write_b128 v247, v[116:119]
	ds_write_b128 v247, v[120:123] offset:1024
	ds_write_b128 v247, v[124:127] offset:2048
	ds_write_b128 v247, v[128:131] offset:3072
	ds_read_b128 v[116:119], v248
	ds_read_b128 v[120:123], v249
	ds_read_b128 v[124:127], v250
	ds_read_b128 v[128:131], v251
	ds_write_b128 v112, v[132:135]
	ds_write_b128 v112, v[136:139] offset:1024
	ds_write_b128 v112, v[140:143] offset:2048
	ds_write_b128 v112, v[144:147] offset:3072
	v_mfma_f32_32x32x16_bf16 v[0:15], v[64:67], v[72:75], v[0:15]
	v_mfma_f32_32x32x16_bf16 v[16:31], v[64:67], v[76:79], v[16:31]
	v_mfma_f32_32x32x16_bf16 v[0:15], v[68:71], v[220:223], v[0:15]
	v_mfma_f32_32x32x16_bf16 v[16:31], v[68:71], v[224:227], v[16:31]
	v_exp_f32_e32 v192, v192
	v_exp_f32_e32 v193, v193
	v_exp_f32_e32 v194, v194
	v_exp_f32_e32 v195, v195
	s_waitcnt lgkmcnt(4)
	v_mfma_f32_32x32x16_bf16 v[32:47], v[116:119], v[48:51], v[32:47]
	v_exp_f32_e32 v196, v196
	v_exp_f32_e32 v197, v197
	v_mfma_f32_32x32x16_bf16 v[32:47], v[120:123], v[52:55], v[32:47]
	v_exp_f32_e32 v198, v198
	v_exp_f32_e32 v199, v199
	v_mfma_f32_32x32x16_bf16 v[32:47], v[124:127], v[56:59], v[32:47]
	v_exp_f32_e32 v200, v200
	v_exp_f32_e32 v201, v201
	v_mfma_f32_32x32x16_bf16 v[32:47], v[128:131], v[60:63], v[32:47]
	v_exp_f32_e32 v202, v202
	v_exp_f32_e32 v203, v203
	v_cvt_pk_bf16_f32 v64, v188, v189
	v_cvt_pk_bf16_f32 v65, v190, v191
	v_cvt_pk_bf16_f32 v66, v192, v193
	v_cvt_pk_bf16_f32 v67, v194, v195
	v_cvt_pk_bf16_f32 v68, v196, v197
	v_cvt_pk_bf16_f32 v69, v198, v199
	v_cvt_pk_bf16_f32 v70, v200, v201
	v_cvt_pk_bf16_f32 v71, v202, v203
	v_pk_add_f32 v[232:233], v[232:233], v[188:189]
	v_pk_add_f32 v[232:233], v[232:233], v[190:191]
	v_pk_add_f32 v[232:233], v[232:233], v[192:193]
	v_pk_add_f32 v[232:233], v[232:233], v[194:195]
	v_pk_add_f32 v[232:233], v[232:233], v[196:197]
	v_pk_add_f32 v[232:233], v[232:233], v[198:199]
	v_pk_add_f32 v[232:233], v[232:233], v[200:201]
	v_pk_add_f32 v[232:233], v[232:233], v[202:203]
	ds_read2_b32 v[188:189], v115 offset0:170 offset1:171
	ds_read2_b32 v[190:191], v115 offset0:172 offset1:173
	ds_read2_b32 v[192:193], v115 offset0:178 offset1:179
	ds_read2_b32 v[194:195], v115 offset0:180 offset1:181
	ds_read2_b32 v[196:197], v115 offset0:187 offset1:188
	ds_read2_b32 v[198:199], v115 offset0:189 offset1:190
	ds_read2_b32 v[200:201], v115 offset0:195 offset1:196
	ds_read2_b32 v[202:203], v115 offset0:197 offset1:198
	global_load_dwordx4 v[116:119], v239, s[86:87]
	global_load_dwordx4 v[120:123], v240, s[86:87]
	global_load_dwordx4 v[124:127], v241, s[86:87]
	global_load_dwordx4 v[128:131], v242, s[86:87]
	global_load_dwordx4 v[132:135], v101, s[86:87] offset:768
	global_load_dwordx4 v[136:139], v150, s[86:87] offset:768
	global_load_dwordx4 v[140:143], v101, s[86:87] offset:832
	global_load_dwordx4 v[144:147], v150, s[86:87] offset:832
	s_add_u32 s86, s86, 0xc0000
	s_addc_u32 s87, s87, 0
	ds_read_b64_tr_b16 v[72:73], v231
	ds_read_b64_tr_b16 v[74:75], v231 offset:512
	ds_read_b64_tr_b16 v[76:77], v231 offset:2048
	ds_read_b64_tr_b16 v[78:79], v231 offset:2560
	ds_read_b64_tr_b16 v[220:221], v231 offset:1024
	ds_read_b64_tr_b16 v[222:223], v231 offset:1536
	ds_read_b64_tr_b16 v[224:225], v231 offset:3072
	ds_read_b64_tr_b16 v[226:227], v231 offset:3584
	v_exp_f32_e32 v32, v32
	v_exp_f32_e32 v33, v33
	v_exp_f32_e32 v34, v34
	v_exp_f32_e32 v35, v35
	s_waitcnt vmcnt(8)
	ds_write_b128 v247, v[156:159]
	ds_write_b128 v247, v[160:163] offset:1024
	ds_write_b128 v247, v[164:167] offset:2048
	ds_write_b128 v247, v[168:171] offset:3072
	ds_read_b128 v[156:159], v248
	ds_read_b128 v[160:163], v249
	ds_read_b128 v[164:167], v250
	ds_read_b128 v[168:171], v251
	ds_write_b128 v112, v[172:175]
	ds_write_b128 v112, v[176:179] offset:1024
	ds_write_b128 v112, v[180:183] offset:2048
	ds_write_b128 v112, v[184:187] offset:3072
	v_mfma_f32_32x32x16_bf16 v[0:15], v[64:67], v[204:207], v[0:15]
	v_mfma_f32_32x32x16_bf16 v[16:31], v[64:67], v[208:211], v[16:31]
	v_mfma_f32_32x32x16_bf16 v[0:15], v[68:71], v[212:215], v[0:15]
	v_mfma_f32_32x32x16_bf16 v[16:31], v[68:71], v[216:219], v[16:31]
	v_exp_f32_e32 v36, v36
	v_exp_f32_e32 v37, v37
	v_exp_f32_e32 v38, v38
	v_exp_f32_e32 v39, v39
	s_waitcnt lgkmcnt(4)
	v_mfma_f32_32x32x16_bf16 v[188:203], v[156:159], v[48:51], v[188:203]
	v_exp_f32_e32 v40, v40
	v_exp_f32_e32 v41, v41
	v_mfma_f32_32x32x16_bf16 v[188:203], v[160:163], v[52:55], v[188:203]
	v_exp_f32_e32 v42, v42
	v_exp_f32_e32 v43, v43
	v_mfma_f32_32x32x16_bf16 v[188:203], v[164:167], v[56:59], v[188:203]
	v_exp_f32_e32 v44, v44
	v_exp_f32_e32 v45, v45
	v_mfma_f32_32x32x16_bf16 v[188:203], v[168:171], v[60:63], v[188:203]
	v_exp_f32_e32 v46, v46
	v_exp_f32_e32 v47, v47
	v_cvt_pk_bf16_f32 v64, v32, v33
	v_cvt_pk_bf16_f32 v65, v34, v35
	v_cvt_pk_bf16_f32 v66, v36, v37
	v_cvt_pk_bf16_f32 v67, v38, v39
	v_cvt_pk_bf16_f32 v68, v40, v41
	v_cvt_pk_bf16_f32 v69, v42, v43
	v_cvt_pk_bf16_f32 v70, v44, v45
	v_cvt_pk_bf16_f32 v71, v46, v47
	v_pk_add_f32 v[232:233], v[232:233], v[32:33]
	v_pk_add_f32 v[232:233], v[232:233], v[34:35]
	v_pk_add_f32 v[232:233], v[232:233], v[36:37]
	v_pk_add_f32 v[232:233], v[232:233], v[38:39]
	v_pk_add_f32 v[232:233], v[232:233], v[40:41]
	v_pk_add_f32 v[232:233], v[232:233], v[42:43]
	v_pk_add_f32 v[232:233], v[232:233], v[44:45]
	v_pk_add_f32 v[232:233], v[232:233], v[46:47]
	v_mov_b32_e32 v115, v229
	ds_read2_b32 v[32:33], v115 offset0:0 offset1:1
	ds_read2_b32 v[34:35], v115 offset0:2 offset1:3
	ds_read2_b32 v[36:37], v115 offset0:8 offset1:9
	ds_read2_b32 v[38:39], v115 offset0:10 offset1:11
	ds_read2_b32 v[40:41], v115 offset0:16 offset1:17
	ds_read2_b32 v[42:43], v115 offset0:18 offset1:19
	ds_read2_b32 v[44:45], v115 offset0:24 offset1:25
	ds_read2_b32 v[46:47], v115 offset0:26 offset1:27
	global_load_dwordx4 v[156:159], v239, s[86:87]
	global_load_dwordx4 v[160:163], v240, s[86:87]
	global_load_dwordx4 v[164:167], v241, s[86:87]
	global_load_dwordx4 v[168:171], v242, s[86:87]
	global_load_dwordx4 v[172:175], v101, s[86:87] offset:768
	global_load_dwordx4 v[176:179], v150, s[86:87] offset:768
	global_load_dwordx4 v[180:183], v101, s[86:87] offset:832
	global_load_dwordx4 v[184:187], v150, s[86:87] offset:832
	s_add_u32 s86, s86, 0xc0000
	s_addc_u32 s87, s87, 0
	ds_read_b64_tr_b16 v[204:205], v231
	ds_read_b64_tr_b16 v[206:207], v231 offset:512
	ds_read_b64_tr_b16 v[208:209], v231 offset:2048
	ds_read_b64_tr_b16 v[210:211], v231 offset:2560
	ds_read_b64_tr_b16 v[212:213], v231 offset:1024
	ds_read_b64_tr_b16 v[214:215], v231 offset:1536
	ds_read_b64_tr_b16 v[216:217], v231 offset:3072
	ds_read_b64_tr_b16 v[218:219], v231 offset:3584
	v_exp_f32_e32 v188, v188
	v_exp_f32_e32 v189, v189
	v_exp_f32_e32 v190, v190
	v_exp_f32_e32 v191, v191
	s_waitcnt vmcnt(8)
	ds_write_b128 v247, v[116:119]
	ds_write_b128 v247, v[120:123] offset:1024
	ds_write_b128 v247, v[124:127] offset:2048
	ds_write_b128 v247, v[128:131] offset:3072
	ds_read_b128 v[116:119], v248
	ds_read_b128 v[120:123], v249
	ds_read_b128 v[124:127], v250
	ds_read_b128 v[128:131], v251
	ds_write_b128 v112, v[132:135]
	ds_write_b128 v112, v[136:139] offset:1024
	ds_write_b128 v112, v[140:143] offset:2048
	ds_write_b128 v112, v[144:147] offset:3072
	v_mfma_f32_32x32x16_bf16 v[0:15], v[64:67], v[72:75], v[0:15]
	v_mfma_f32_32x32x16_bf16 v[16:31], v[64:67], v[76:79], v[16:31]
	v_mfma_f32_32x32x16_bf16 v[0:15], v[68:71], v[220:223], v[0:15]
	v_mfma_f32_32x32x16_bf16 v[16:31], v[68:71], v[224:227], v[16:31]
	v_exp_f32_e32 v192, v192
	v_exp_f32_e32 v193, v193
	v_exp_f32_e32 v194, v194
	v_exp_f32_e32 v195, v195
	s_waitcnt lgkmcnt(4)
	v_mfma_f32_32x32x16_bf16 v[32:47], v[116:119], v[48:51], v[32:47]
	v_exp_f32_e32 v196, v196
	v_exp_f32_e32 v197, v197
	v_mfma_f32_32x32x16_bf16 v[32:47], v[120:123], v[52:55], v[32:47]
	v_exp_f32_e32 v198, v198
	v_exp_f32_e32 v199, v199
	v_mfma_f32_32x32x16_bf16 v[32:47], v[124:127], v[56:59], v[32:47]
	v_exp_f32_e32 v200, v200
	v_exp_f32_e32 v201, v201
	v_mfma_f32_32x32x16_bf16 v[32:47], v[128:131], v[60:63], v[32:47]
	v_exp_f32_e32 v202, v202
	v_exp_f32_e32 v203, v203
	v_cvt_pk_bf16_f32 v64, v188, v189
	v_cvt_pk_bf16_f32 v65, v190, v191
	v_cvt_pk_bf16_f32 v66, v192, v193
	v_cvt_pk_bf16_f32 v67, v194, v195
	v_cvt_pk_bf16_f32 v68, v196, v197
	v_cvt_pk_bf16_f32 v69, v198, v199
	v_cvt_pk_bf16_f32 v70, v200, v201
	v_cvt_pk_bf16_f32 v71, v202, v203
	v_pk_add_f32 v[232:233], v[232:233], v[188:189]
	v_pk_add_f32 v[232:233], v[232:233], v[190:191]
	v_pk_add_f32 v[232:233], v[232:233], v[192:193]
	v_pk_add_f32 v[232:233], v[232:233], v[194:195]
	v_pk_add_f32 v[232:233], v[232:233], v[196:197]
	v_pk_add_f32 v[232:233], v[232:233], v[198:199]
	v_pk_add_f32 v[232:233], v[232:233], v[200:201]
	v_pk_add_f32 v[232:233], v[232:233], v[202:203]
	ds_read2_b32 v[188:189], v115 offset0:32 offset1:33
	ds_read2_b32 v[190:191], v115 offset0:34 offset1:35
	ds_read2_b32 v[192:193], v115 offset0:40 offset1:41
	ds_read2_b32 v[194:195], v115 offset0:42 offset1:43
	ds_read2_b32 v[196:197], v115 offset0:48 offset1:49
	ds_read2_b32 v[198:199], v115 offset0:50 offset1:51
	ds_read2_b32 v[200:201], v115 offset0:56 offset1:57
	ds_read2_b32 v[202:203], v115 offset0:58 offset1:59
	global_load_dwordx4 v[116:119], v239, s[86:87]
	global_load_dwordx4 v[120:123], v240, s[86:87]
	global_load_dwordx4 v[124:127], v241, s[86:87]
	global_load_dwordx4 v[128:131], v242, s[86:87]
	global_load_dwordx4 v[132:135], v101, s[86:87] offset:768
	global_load_dwordx4 v[136:139], v150, s[86:87] offset:768
	global_load_dwordx4 v[140:143], v101, s[86:87] offset:832
	global_load_dwordx4 v[144:147], v150, s[86:87] offset:832
	s_add_u32 s86, s86, 0xc0000
	s_addc_u32 s87, s87, 0
	ds_read_b64_tr_b16 v[72:73], v231
	ds_read_b64_tr_b16 v[74:75], v231 offset:512
	ds_read_b64_tr_b16 v[76:77], v231 offset:2048
	ds_read_b64_tr_b16 v[78:79], v231 offset:2560
	ds_read_b64_tr_b16 v[220:221], v231 offset:1024
	ds_read_b64_tr_b16 v[222:223], v231 offset:1536
	ds_read_b64_tr_b16 v[224:225], v231 offset:3072
	ds_read_b64_tr_b16 v[226:227], v231 offset:3584
	v_exp_f32_e32 v32, v32
	v_exp_f32_e32 v33, v33
	v_exp_f32_e32 v34, v34
	v_exp_f32_e32 v35, v35
	s_waitcnt vmcnt(8)
	ds_write_b128 v247, v[156:159]
	ds_write_b128 v247, v[160:163] offset:1024
	ds_write_b128 v247, v[164:167] offset:2048
	ds_write_b128 v247, v[168:171] offset:3072
	ds_read_b128 v[156:159], v248
	ds_read_b128 v[160:163], v249
	ds_read_b128 v[164:167], v250
	ds_read_b128 v[168:171], v251
	ds_write_b128 v112, v[172:175]
	ds_write_b128 v112, v[176:179] offset:1024
	ds_write_b128 v112, v[180:183] offset:2048
	ds_write_b128 v112, v[184:187] offset:3072
	v_mfma_f32_32x32x16_bf16 v[0:15], v[64:67], v[204:207], v[0:15]
	v_mfma_f32_32x32x16_bf16 v[16:31], v[64:67], v[208:211], v[16:31]
	v_mfma_f32_32x32x16_bf16 v[0:15], v[68:71], v[212:215], v[0:15]
	v_mfma_f32_32x32x16_bf16 v[16:31], v[68:71], v[216:219], v[16:31]
	v_exp_f32_e32 v36, v36
	v_exp_f32_e32 v37, v37
	v_exp_f32_e32 v38, v38
	v_exp_f32_e32 v39, v39
	s_waitcnt lgkmcnt(4)
	v_mfma_f32_32x32x16_bf16 v[188:203], v[156:159], v[48:51], v[188:203]
	v_exp_f32_e32 v40, v40
	v_exp_f32_e32 v41, v41
	v_mfma_f32_32x32x16_bf16 v[188:203], v[160:163], v[52:55], v[188:203]
	v_exp_f32_e32 v42, v42
	v_exp_f32_e32 v43, v43
	v_mfma_f32_32x32x16_bf16 v[188:203], v[164:167], v[56:59], v[188:203]
	v_exp_f32_e32 v44, v44
	v_exp_f32_e32 v45, v45
	v_mfma_f32_32x32x16_bf16 v[188:203], v[168:171], v[60:63], v[188:203]
	v_exp_f32_e32 v46, v46
	v_exp_f32_e32 v47, v47
	v_cvt_pk_bf16_f32 v64, v32, v33
	v_cvt_pk_bf16_f32 v65, v34, v35
	v_cvt_pk_bf16_f32 v66, v36, v37
	v_cvt_pk_bf16_f32 v67, v38, v39
	v_cvt_pk_bf16_f32 v68, v40, v41
	v_cvt_pk_bf16_f32 v69, v42, v43
	v_cvt_pk_bf16_f32 v70, v44, v45
	v_cvt_pk_bf16_f32 v71, v46, v47
	v_pk_add_f32 v[232:233], v[232:233], v[32:33]
	v_pk_add_f32 v[232:233], v[232:233], v[34:35]
	v_pk_add_f32 v[232:233], v[232:233], v[36:37]
	v_pk_add_f32 v[232:233], v[232:233], v[38:39]
	v_pk_add_f32 v[232:233], v[232:233], v[40:41]
	v_pk_add_f32 v[232:233], v[232:233], v[42:43]
	v_pk_add_f32 v[232:233], v[232:233], v[44:45]
	v_pk_add_f32 v[232:233], v[232:233], v[46:47]
	ds_read2_b32 v[32:33], v115 offset0:64 offset1:65
	ds_read2_b32 v[34:35], v115 offset0:66 offset1:67
	ds_read2_b32 v[36:37], v115 offset0:72 offset1:73
	ds_read2_b32 v[38:39], v115 offset0:74 offset1:75
	ds_read2_b32 v[40:41], v115 offset0:80 offset1:81
	ds_read2_b32 v[42:43], v115 offset0:82 offset1:83
	ds_read2_b32 v[44:45], v115 offset0:88 offset1:89
	ds_read2_b32 v[46:47], v115 offset0:90 offset1:91
	global_load_dwordx4 v[156:159], v239, s[86:87]
	global_load_dwordx4 v[160:163], v240, s[86:87]
	global_load_dwordx4 v[164:167], v241, s[86:87]
	global_load_dwordx4 v[168:171], v242, s[86:87]
	global_load_dwordx4 v[172:175], v101, s[86:87] offset:768
	global_load_dwordx4 v[176:179], v150, s[86:87] offset:768
	global_load_dwordx4 v[180:183], v101, s[86:87] offset:832
	global_load_dwordx4 v[184:187], v150, s[86:87] offset:832
	s_add_u32 s86, s86, 0xc0000
	s_addc_u32 s87, s87, 0
	ds_read_b64_tr_b16 v[204:205], v231
	ds_read_b64_tr_b16 v[206:207], v231 offset:512
	ds_read_b64_tr_b16 v[208:209], v231 offset:2048
	ds_read_b64_tr_b16 v[210:211], v231 offset:2560
	ds_read_b64_tr_b16 v[212:213], v231 offset:1024
	ds_read_b64_tr_b16 v[214:215], v231 offset:1536
	ds_read_b64_tr_b16 v[216:217], v231 offset:3072
	ds_read_b64_tr_b16 v[218:219], v231 offset:3584
	v_exp_f32_e32 v188, v188
	v_exp_f32_e32 v189, v189
	v_exp_f32_e32 v190, v190
	v_exp_f32_e32 v191, v191
	s_waitcnt vmcnt(8)
	ds_write_b128 v247, v[116:119]
	ds_write_b128 v247, v[120:123] offset:1024
	ds_write_b128 v247, v[124:127] offset:2048
	ds_write_b128 v247, v[128:131] offset:3072
	ds_read_b128 v[116:119], v248
	ds_read_b128 v[120:123], v249
	ds_read_b128 v[124:127], v250
	ds_read_b128 v[128:131], v251
	ds_write_b128 v112, v[132:135]
	ds_write_b128 v112, v[136:139] offset:1024
	ds_write_b128 v112, v[140:143] offset:2048
	ds_write_b128 v112, v[144:147] offset:3072
	v_mfma_f32_32x32x16_bf16 v[0:15], v[64:67], v[72:75], v[0:15]
	v_mfma_f32_32x32x16_bf16 v[16:31], v[64:67], v[76:79], v[16:31]
	v_mfma_f32_32x32x16_bf16 v[0:15], v[68:71], v[220:223], v[0:15]
	v_mfma_f32_32x32x16_bf16 v[16:31], v[68:71], v[224:227], v[16:31]
	v_exp_f32_e32 v192, v192
	v_exp_f32_e32 v193, v193
	v_exp_f32_e32 v194, v194
	v_exp_f32_e32 v195, v195
	s_waitcnt lgkmcnt(4)
	v_mfma_f32_32x32x16_bf16 v[32:47], v[116:119], v[48:51], v[32:47]
	v_exp_f32_e32 v196, v196
	v_exp_f32_e32 v197, v197
	v_mfma_f32_32x32x16_bf16 v[32:47], v[120:123], v[52:55], v[32:47]
	v_exp_f32_e32 v198, v198
	v_exp_f32_e32 v199, v199
	v_mfma_f32_32x32x16_bf16 v[32:47], v[124:127], v[56:59], v[32:47]
	v_exp_f32_e32 v200, v200
	v_exp_f32_e32 v201, v201
	v_mfma_f32_32x32x16_bf16 v[32:47], v[128:131], v[60:63], v[32:47]
	v_exp_f32_e32 v202, v202
	v_exp_f32_e32 v203, v203
	v_cvt_pk_bf16_f32 v64, v188, v189
	v_cvt_pk_bf16_f32 v65, v190, v191
	v_cvt_pk_bf16_f32 v66, v192, v193
	v_cvt_pk_bf16_f32 v67, v194, v195
	v_cvt_pk_bf16_f32 v68, v196, v197
	v_cvt_pk_bf16_f32 v69, v198, v199
	v_cvt_pk_bf16_f32 v70, v200, v201
	v_cvt_pk_bf16_f32 v71, v202, v203
	v_pk_add_f32 v[232:233], v[232:233], v[188:189]
	v_pk_add_f32 v[232:233], v[232:233], v[190:191]
	v_pk_add_f32 v[232:233], v[232:233], v[192:193]
	v_pk_add_f32 v[232:233], v[232:233], v[194:195]
	v_pk_add_f32 v[232:233], v[232:233], v[196:197]
	v_pk_add_f32 v[232:233], v[232:233], v[198:199]
	v_pk_add_f32 v[232:233], v[232:233], v[200:201]
	v_pk_add_f32 v[232:233], v[232:233], v[202:203]
	ds_read2_b32 v[188:189], v115 offset0:96 offset1:97
	ds_read2_b32 v[190:191], v115 offset0:98 offset1:99
	ds_read2_b32 v[192:193], v115 offset0:104 offset1:105
	ds_read2_b32 v[194:195], v115 offset0:106 offset1:107
	ds_read2_b32 v[196:197], v115 offset0:112 offset1:113
	ds_read2_b32 v[198:199], v115 offset0:114 offset1:115
	ds_read2_b32 v[200:201], v115 offset0:120 offset1:121
	ds_read2_b32 v[202:203], v115 offset0:122 offset1:123
	global_load_dwordx4 v[116:119], v239, s[86:87]
	global_load_dwordx4 v[120:123], v240, s[86:87]
	global_load_dwordx4 v[124:127], v241, s[86:87]
	global_load_dwordx4 v[128:131], v242, s[86:87]
	global_load_dwordx4 v[132:135], v101, s[86:87] offset:768
	global_load_dwordx4 v[136:139], v150, s[86:87] offset:768
	global_load_dwordx4 v[140:143], v101, s[86:87] offset:832
	global_load_dwordx4 v[144:147], v150, s[86:87] offset:832
	s_add_u32 s86, s86, 0xc0000
	s_addc_u32 s87, s87, 0
	ds_read_b64_tr_b16 v[72:73], v231
	ds_read_b64_tr_b16 v[74:75], v231 offset:512
	ds_read_b64_tr_b16 v[76:77], v231 offset:2048
	ds_read_b64_tr_b16 v[78:79], v231 offset:2560
	ds_read_b64_tr_b16 v[220:221], v231 offset:1024
	ds_read_b64_tr_b16 v[222:223], v231 offset:1536
	ds_read_b64_tr_b16 v[224:225], v231 offset:3072
	ds_read_b64_tr_b16 v[226:227], v231 offset:3584
	v_exp_f32_e32 v32, v32
	v_exp_f32_e32 v33, v33
	v_exp_f32_e32 v34, v34
	v_exp_f32_e32 v35, v35
	s_waitcnt vmcnt(8)
	ds_write_b128 v247, v[156:159]
	ds_write_b128 v247, v[160:163] offset:1024
	ds_write_b128 v247, v[164:167] offset:2048
	ds_write_b128 v247, v[168:171] offset:3072
	ds_read_b128 v[156:159], v248
	ds_read_b128 v[160:163], v249
	ds_read_b128 v[164:167], v250
	ds_read_b128 v[168:171], v251
	ds_write_b128 v112, v[172:175]
	ds_write_b128 v112, v[176:179] offset:1024
	ds_write_b128 v112, v[180:183] offset:2048
	ds_write_b128 v112, v[184:187] offset:3072
	v_mfma_f32_32x32x16_bf16 v[0:15], v[64:67], v[204:207], v[0:15]
	v_mfma_f32_32x32x16_bf16 v[16:31], v[64:67], v[208:211], v[16:31]
	v_mfma_f32_32x32x16_bf16 v[0:15], v[68:71], v[212:215], v[0:15]
	v_mfma_f32_32x32x16_bf16 v[16:31], v[68:71], v[216:219], v[16:31]
	v_exp_f32_e32 v36, v36
	v_exp_f32_e32 v37, v37
	v_exp_f32_e32 v38, v38
	v_exp_f32_e32 v39, v39
	s_waitcnt lgkmcnt(4)
	v_mfma_f32_32x32x16_bf16 v[188:203], v[156:159], v[48:51], v[188:203]
	v_exp_f32_e32 v40, v40
	v_exp_f32_e32 v41, v41
	v_mfma_f32_32x32x16_bf16 v[188:203], v[160:163], v[52:55], v[188:203]
	v_exp_f32_e32 v42, v42
	v_exp_f32_e32 v43, v43
	v_mfma_f32_32x32x16_bf16 v[188:203], v[164:167], v[56:59], v[188:203]
	v_exp_f32_e32 v44, v44
	v_exp_f32_e32 v45, v45
	v_mfma_f32_32x32x16_bf16 v[188:203], v[168:171], v[60:63], v[188:203]
	v_exp_f32_e32 v46, v46
	v_exp_f32_e32 v47, v47
	v_cvt_pk_bf16_f32 v64, v32, v33
	v_cvt_pk_bf16_f32 v65, v34, v35
	v_cvt_pk_bf16_f32 v66, v36, v37
	v_cvt_pk_bf16_f32 v67, v38, v39
	v_cvt_pk_bf16_f32 v68, v40, v41
	v_cvt_pk_bf16_f32 v69, v42, v43
	v_cvt_pk_bf16_f32 v70, v44, v45
	v_cvt_pk_bf16_f32 v71, v46, v47
	v_pk_add_f32 v[232:233], v[232:233], v[32:33]
	v_pk_add_f32 v[232:233], v[232:233], v[34:35]
	v_pk_add_f32 v[232:233], v[232:233], v[36:37]
	v_pk_add_f32 v[232:233], v[232:233], v[38:39]
	v_pk_add_f32 v[232:233], v[232:233], v[40:41]
	v_pk_add_f32 v[232:233], v[232:233], v[42:43]
	v_pk_add_f32 v[232:233], v[232:233], v[44:45]
	v_pk_add_f32 v[232:233], v[232:233], v[46:47]
	ds_read2_b32 v[32:33], v115 offset0:128 offset1:129
	ds_read2_b32 v[34:35], v115 offset0:130 offset1:131
	ds_read2_b32 v[36:37], v115 offset0:136 offset1:137
	ds_read2_b32 v[38:39], v115 offset0:138 offset1:139
	ds_read2_b32 v[40:41], v115 offset0:144 offset1:145
	ds_read2_b32 v[42:43], v115 offset0:146 offset1:147
	ds_read2_b32 v[44:45], v115 offset0:152 offset1:153
	ds_read2_b32 v[46:47], v115 offset0:154 offset1:155
	global_load_dwordx4 v[156:159], v239, s[86:87]
	global_load_dwordx4 v[160:163], v240, s[86:87]
	global_load_dwordx4 v[164:167], v241, s[86:87]
	global_load_dwordx4 v[168:171], v242, s[86:87]
	global_load_dwordx4 v[172:175], v101, s[86:87] offset:768
	global_load_dwordx4 v[176:179], v150, s[86:87] offset:768
	global_load_dwordx4 v[180:183], v101, s[86:87] offset:832
	global_load_dwordx4 v[184:187], v150, s[86:87] offset:832
	s_add_u32 s86, s86, 0xc0000
	s_addc_u32 s87, s87, 0
	ds_read_b64_tr_b16 v[204:205], v231
	ds_read_b64_tr_b16 v[206:207], v231 offset:512
	ds_read_b64_tr_b16 v[208:209], v231 offset:2048
	ds_read_b64_tr_b16 v[210:211], v231 offset:2560
	ds_read_b64_tr_b16 v[212:213], v231 offset:1024
	ds_read_b64_tr_b16 v[214:215], v231 offset:1536
	ds_read_b64_tr_b16 v[216:217], v231 offset:3072
	ds_read_b64_tr_b16 v[218:219], v231 offset:3584
	v_exp_f32_e32 v188, v188
	v_exp_f32_e32 v189, v189
	v_exp_f32_e32 v190, v190
	v_exp_f32_e32 v191, v191
	s_waitcnt vmcnt(8)
	ds_write_b128 v247, v[116:119]
	ds_write_b128 v247, v[120:123] offset:1024
	ds_write_b128 v247, v[124:127] offset:2048
	ds_write_b128 v247, v[128:131] offset:3072
	ds_read_b128 v[116:119], v248
	ds_read_b128 v[120:123], v249
	ds_read_b128 v[124:127], v250
	ds_read_b128 v[128:131], v251
	ds_write_b128 v112, v[132:135]
	ds_write_b128 v112, v[136:139] offset:1024
	ds_write_b128 v112, v[140:143] offset:2048
	ds_write_b128 v112, v[144:147] offset:3072
	v_mfma_f32_32x32x16_bf16 v[0:15], v[64:67], v[72:75], v[0:15]
	v_mfma_f32_32x32x16_bf16 v[16:31], v[64:67], v[76:79], v[16:31]
	v_mfma_f32_32x32x16_bf16 v[0:15], v[68:71], v[220:223], v[0:15]
	v_mfma_f32_32x32x16_bf16 v[16:31], v[68:71], v[224:227], v[16:31]
	v_exp_f32_e32 v192, v192
	v_exp_f32_e32 v193, v193
	v_exp_f32_e32 v194, v194
	v_exp_f32_e32 v195, v195
	s_waitcnt lgkmcnt(4)
	v_mfma_f32_32x32x16_bf16 v[32:47], v[116:119], v[48:51], v[32:47]
	v_exp_f32_e32 v196, v196
	v_exp_f32_e32 v197, v197
	v_mfma_f32_32x32x16_bf16 v[32:47], v[120:123], v[52:55], v[32:47]
	v_exp_f32_e32 v198, v198
	v_exp_f32_e32 v199, v199
	v_mfma_f32_32x32x16_bf16 v[32:47], v[124:127], v[56:59], v[32:47]
	v_exp_f32_e32 v200, v200
	v_exp_f32_e32 v201, v201
	v_mfma_f32_32x32x16_bf16 v[32:47], v[128:131], v[60:63], v[32:47]
	v_exp_f32_e32 v202, v202
	v_exp_f32_e32 v203, v203
	v_cvt_pk_bf16_f32 v64, v188, v189
	v_cvt_pk_bf16_f32 v65, v190, v191
	v_cvt_pk_bf16_f32 v66, v192, v193
	v_cvt_pk_bf16_f32 v67, v194, v195
	v_cvt_pk_bf16_f32 v68, v196, v197
	v_cvt_pk_bf16_f32 v69, v198, v199
	v_cvt_pk_bf16_f32 v70, v200, v201
	v_cvt_pk_bf16_f32 v71, v202, v203
	v_pk_add_f32 v[232:233], v[232:233], v[188:189]
	v_pk_add_f32 v[232:233], v[232:233], v[190:191]
	v_pk_add_f32 v[232:233], v[232:233], v[192:193]
	v_pk_add_f32 v[232:233], v[232:233], v[194:195]
	v_pk_add_f32 v[232:233], v[232:233], v[196:197]
	v_pk_add_f32 v[232:233], v[232:233], v[198:199]
	v_pk_add_f32 v[232:233], v[232:233], v[200:201]
	v_pk_add_f32 v[232:233], v[232:233], v[202:203]
	ds_read2_b32 v[188:189], v115 offset0:160 offset1:161
	ds_read2_b32 v[190:191], v115 offset0:162 offset1:163
	ds_read2_b32 v[192:193], v115 offset0:168 offset1:169
	ds_read2_b32 v[194:195], v115 offset0:170 offset1:171
	ds_read2_b32 v[196:197], v115 offset0:176 offset1:177
	ds_read2_b32 v[198:199], v115 offset0:178 offset1:179
	ds_read2_b32 v[200:201], v115 offset0:184 offset1:185
	ds_read2_b32 v[202:203], v115 offset0:186 offset1:187
	global_load_dwordx4 v[116:119], v239, s[86:87]
	global_load_dwordx4 v[120:123], v240, s[86:87]
	global_load_dwordx4 v[124:127], v241, s[86:87]
	global_load_dwordx4 v[128:131], v242, s[86:87]
	global_load_dwordx4 v[132:135], v101, s[86:87] offset:768
	global_load_dwordx4 v[136:139], v150, s[86:87] offset:768
	global_load_dwordx4 v[140:143], v101, s[86:87] offset:832
	global_load_dwordx4 v[144:147], v150, s[86:87] offset:832
	s_add_u32 s86, s86, 0xc0000
	s_addc_u32 s87, s87, 0
	ds_read_b64_tr_b16 v[72:73], v231
	ds_read_b64_tr_b16 v[74:75], v231 offset:512
	ds_read_b64_tr_b16 v[76:77], v231 offset:2048
	ds_read_b64_tr_b16 v[78:79], v231 offset:2560
	ds_read_b64_tr_b16 v[220:221], v231 offset:1024
	ds_read_b64_tr_b16 v[222:223], v231 offset:1536
	ds_read_b64_tr_b16 v[224:225], v231 offset:3072
	ds_read_b64_tr_b16 v[226:227], v231 offset:3584
	v_exp_f32_e32 v32, v32
	v_exp_f32_e32 v33, v33
	v_exp_f32_e32 v34, v34
	v_exp_f32_e32 v35, v35
	s_waitcnt vmcnt(8)
	ds_write_b128 v247, v[156:159]
	ds_write_b128 v247, v[160:163] offset:1024
	ds_write_b128 v247, v[164:167] offset:2048
	ds_write_b128 v247, v[168:171] offset:3072
	ds_read_b128 v[156:159], v248
	ds_read_b128 v[160:163], v249
	ds_read_b128 v[164:167], v250
	ds_read_b128 v[168:171], v251
	ds_write_b128 v112, v[172:175]
	ds_write_b128 v112, v[176:179] offset:1024
	ds_write_b128 v112, v[180:183] offset:2048
	ds_write_b128 v112, v[184:187] offset:3072
	v_mfma_f32_32x32x16_bf16 v[0:15], v[64:67], v[204:207], v[0:15]
	v_mfma_f32_32x32x16_bf16 v[16:31], v[64:67], v[208:211], v[16:31]
	v_mfma_f32_32x32x16_bf16 v[0:15], v[68:71], v[212:215], v[0:15]
	v_mfma_f32_32x32x16_bf16 v[16:31], v[68:71], v[216:219], v[16:31]
	v_exp_f32_e32 v36, v36
	v_exp_f32_e32 v37, v37
	v_exp_f32_e32 v38, v38
	v_exp_f32_e32 v39, v39
	s_waitcnt lgkmcnt(4)
	v_mfma_f32_32x32x16_bf16 v[188:203], v[156:159], v[48:51], v[188:203]
	v_exp_f32_e32 v40, v40
	v_exp_f32_e32 v41, v41
	v_mfma_f32_32x32x16_bf16 v[188:203], v[160:163], v[52:55], v[188:203]
	v_exp_f32_e32 v42, v42
	v_exp_f32_e32 v43, v43
	v_mfma_f32_32x32x16_bf16 v[188:203], v[164:167], v[56:59], v[188:203]
	v_exp_f32_e32 v44, v44
	v_exp_f32_e32 v45, v45
	v_mfma_f32_32x32x16_bf16 v[188:203], v[168:171], v[60:63], v[188:203]
	v_exp_f32_e32 v46, v46
	v_exp_f32_e32 v47, v47
	v_cvt_pk_bf16_f32 v64, v32, v33
	v_cvt_pk_bf16_f32 v65, v34, v35
	v_cvt_pk_bf16_f32 v66, v36, v37
	v_cvt_pk_bf16_f32 v67, v38, v39
	v_cvt_pk_bf16_f32 v68, v40, v41
	v_cvt_pk_bf16_f32 v69, v42, v43
	v_cvt_pk_bf16_f32 v70, v44, v45
	v_cvt_pk_bf16_f32 v71, v46, v47
	v_pk_add_f32 v[232:233], v[232:233], v[32:33]
	v_pk_add_f32 v[232:233], v[232:233], v[34:35]
	v_pk_add_f32 v[232:233], v[232:233], v[36:37]
	v_pk_add_f32 v[232:233], v[232:233], v[38:39]
	v_pk_add_f32 v[232:233], v[232:233], v[40:41]
	v_pk_add_f32 v[232:233], v[232:233], v[42:43]
	v_pk_add_f32 v[232:233], v[232:233], v[44:45]
	v_pk_add_f32 v[232:233], v[232:233], v[46:47]
	ds_read2_b32 v[32:33], v115 offset0:192 offset1:193
	ds_read2_b32 v[34:35], v115 offset0:194 offset1:195
	ds_read2_b32 v[36:37], v115 offset0:200 offset1:201
	ds_read2_b32 v[38:39], v115 offset0:202 offset1:203
	ds_read2_b32 v[40:41], v115 offset0:208 offset1:209
	ds_read2_b32 v[42:43], v115 offset0:210 offset1:211
	ds_read2_b32 v[44:45], v115 offset0:216 offset1:217
	ds_read2_b32 v[46:47], v115 offset0:218 offset1:219
	global_load_dwordx4 v[156:159], v239, s[86:87]
	global_load_dwordx4 v[160:163], v240, s[86:87]
	global_load_dwordx4 v[164:167], v241, s[86:87]
	global_load_dwordx4 v[168:171], v242, s[86:87]
	global_load_dwordx4 v[172:175], v101, s[86:87] offset:768
	global_load_dwordx4 v[176:179], v150, s[86:87] offset:768
	global_load_dwordx4 v[180:183], v101, s[86:87] offset:832
	global_load_dwordx4 v[184:187], v150, s[86:87] offset:832
	ds_read_b64_tr_b16 v[204:205], v231
	ds_read_b64_tr_b16 v[206:207], v231 offset:512
	ds_read_b64_tr_b16 v[208:209], v231 offset:2048
	ds_read_b64_tr_b16 v[210:211], v231 offset:2560
	ds_read_b64_tr_b16 v[212:213], v231 offset:1024
	ds_read_b64_tr_b16 v[214:215], v231 offset:1536
	ds_read_b64_tr_b16 v[216:217], v231 offset:3072
	ds_read_b64_tr_b16 v[218:219], v231 offset:3584
	v_exp_f32_e32 v188, v188
	v_exp_f32_e32 v189, v189
	v_exp_f32_e32 v190, v190
	v_exp_f32_e32 v191, v191
	s_waitcnt vmcnt(8)
	ds_write_b128 v247, v[116:119]
	ds_write_b128 v247, v[120:123] offset:1024
	ds_write_b128 v247, v[124:127] offset:2048
	ds_write_b128 v247, v[128:131] offset:3072
	ds_read_b128 v[116:119], v248
	ds_read_b128 v[120:123], v249
	ds_read_b128 v[124:127], v250
	ds_read_b128 v[128:131], v251
	ds_write_b128 v112, v[132:135]
	ds_write_b128 v112, v[136:139] offset:1024
	ds_write_b128 v112, v[140:143] offset:2048
	ds_write_b128 v112, v[144:147] offset:3072
	v_mfma_f32_32x32x16_bf16 v[0:15], v[64:67], v[72:75], v[0:15]
	v_mfma_f32_32x32x16_bf16 v[16:31], v[64:67], v[76:79], v[16:31]
	v_mfma_f32_32x32x16_bf16 v[0:15], v[68:71], v[220:223], v[0:15]
	v_mfma_f32_32x32x16_bf16 v[16:31], v[68:71], v[224:227], v[16:31]
	v_exp_f32_e32 v192, v192
	v_exp_f32_e32 v193, v193
	v_exp_f32_e32 v194, v194
	v_exp_f32_e32 v195, v195
	s_waitcnt lgkmcnt(4)
	v_mfma_f32_32x32x16_bf16 v[32:47], v[116:119], v[48:51], v[32:47]
	v_exp_f32_e32 v196, v196
	v_exp_f32_e32 v197, v197
	v_mfma_f32_32x32x16_bf16 v[32:47], v[120:123], v[52:55], v[32:47]
	v_exp_f32_e32 v198, v198
	v_exp_f32_e32 v199, v199
	v_mfma_f32_32x32x16_bf16 v[32:47], v[124:127], v[56:59], v[32:47]
	v_exp_f32_e32 v200, v200
	v_exp_f32_e32 v201, v201
	v_mfma_f32_32x32x16_bf16 v[32:47], v[128:131], v[60:63], v[32:47]
	v_exp_f32_e32 v202, v202
	v_exp_f32_e32 v203, v203
	v_cvt_pk_bf16_f32 v64, v188, v189
	v_cvt_pk_bf16_f32 v65, v190, v191
	v_cvt_pk_bf16_f32 v66, v192, v193
	v_cvt_pk_bf16_f32 v67, v194, v195
	v_cvt_pk_bf16_f32 v68, v196, v197
	v_cvt_pk_bf16_f32 v69, v198, v199
	v_cvt_pk_bf16_f32 v70, v200, v201
	v_cvt_pk_bf16_f32 v71, v202, v203
	v_pk_add_f32 v[232:233], v[232:233], v[188:189]
	v_pk_add_f32 v[232:233], v[232:233], v[190:191]
	v_pk_add_f32 v[232:233], v[232:233], v[192:193]
	v_pk_add_f32 v[232:233], v[232:233], v[194:195]
	v_pk_add_f32 v[232:233], v[232:233], v[196:197]
	v_pk_add_f32 v[232:233], v[232:233], v[198:199]
	v_pk_add_f32 v[232:233], v[232:233], v[200:201]
	v_pk_add_f32 v[232:233], v[232:233], v[202:203]
	ds_read2_b32 v[188:189], v115 offset0:224 offset1:225
	ds_read2_b32 v[190:191], v115 offset0:226 offset1:227
	ds_read2_b32 v[192:193], v115 offset0:232 offset1:233
	ds_read2_b32 v[194:195], v115 offset0:234 offset1:235
	ds_read2_b32 v[196:197], v115 offset0:240 offset1:241
	ds_read2_b32 v[198:199], v115 offset0:242 offset1:243
	ds_read2_b32 v[200:201], v115 offset0:248 offset1:249
	ds_read2_b32 v[202:203], v115 offset0:250 offset1:251
	global_load_dwordx4 v[116:119], v243, s[88:89]
	global_load_dwordx4 v[120:123], v244, s[88:89]
	global_load_dwordx4 v[124:127], v245, s[88:89]
	global_load_dwordx4 v[128:131], v246, s[88:89]
	global_load_dwordx4 v[132:135], v148, s[88:89] offset:768
	global_load_dwordx4 v[136:139], v151, s[88:89] offset:768
	global_load_dwordx4 v[140:143], v148, s[88:89] offset:832
	global_load_dwordx4 v[144:147], v151, s[88:89] offset:832
	s_add_u32 s88, s88, 0x300000
	s_addc_u32 s89, s89, 0
	ds_read_b64_tr_b16 v[72:73], v231
	ds_read_b64_tr_b16 v[74:75], v231 offset:512
	ds_read_b64_tr_b16 v[76:77], v231 offset:2048
	ds_read_b64_tr_b16 v[78:79], v231 offset:2560
	ds_read_b64_tr_b16 v[220:221], v231 offset:1024
	ds_read_b64_tr_b16 v[222:223], v231 offset:1536
	ds_read_b64_tr_b16 v[224:225], v231 offset:3072
	ds_read_b64_tr_b16 v[226:227], v231 offset:3584
	v_exp_f32_e32 v32, v32
	v_exp_f32_e32 v33, v33
	v_exp_f32_e32 v34, v34
	v_exp_f32_e32 v35, v35
	s_waitcnt vmcnt(8)
	ds_write_b128 v247, v[156:159]
	ds_write_b128 v247, v[160:163] offset:1024
	ds_write_b128 v247, v[164:167] offset:2048
	ds_write_b128 v247, v[168:171] offset:3072
	ds_read_b128 v[156:159], v248
	ds_read_b128 v[160:163], v249
	ds_read_b128 v[164:167], v250
	ds_read_b128 v[168:171], v251
	ds_write_b128 v112, v[172:175]
	ds_write_b128 v112, v[176:179] offset:1024
	ds_write_b128 v112, v[180:183] offset:2048
	ds_write_b128 v112, v[184:187] offset:3072
	v_mfma_f32_32x32x16_bf16 v[0:15], v[64:67], v[204:207], v[0:15]
	v_mfma_f32_32x32x16_bf16 v[16:31], v[64:67], v[208:211], v[16:31]
	v_mfma_f32_32x32x16_bf16 v[0:15], v[68:71], v[212:215], v[0:15]
	v_mfma_f32_32x32x16_bf16 v[16:31], v[68:71], v[216:219], v[16:31]
	v_exp_f32_e32 v36, v36
	v_exp_f32_e32 v37, v37
	v_exp_f32_e32 v38, v38
	v_exp_f32_e32 v39, v39
	s_waitcnt lgkmcnt(4)
	v_mfma_f32_32x32x16_bf16 v[188:203], v[156:159], v[48:51], v[188:203]
	v_exp_f32_e32 v40, v40
	v_exp_f32_e32 v41, v41
	v_mfma_f32_32x32x16_bf16 v[188:203], v[160:163], v[52:55], v[188:203]
	v_exp_f32_e32 v42, v42
	v_exp_f32_e32 v43, v43
	v_mfma_f32_32x32x16_bf16 v[188:203], v[164:167], v[56:59], v[188:203]
	v_exp_f32_e32 v44, v44
	v_exp_f32_e32 v45, v45
	v_mfma_f32_32x32x16_bf16 v[188:203], v[168:171], v[60:63], v[188:203]
	v_exp_f32_e32 v46, v46
	v_exp_f32_e32 v47, v47
	v_cvt_pk_bf16_f32 v64, v32, v33
	v_cvt_pk_bf16_f32 v65, v34, v35
	v_cvt_pk_bf16_f32 v66, v36, v37
	v_cvt_pk_bf16_f32 v67, v38, v39
	v_cvt_pk_bf16_f32 v68, v40, v41
	v_cvt_pk_bf16_f32 v69, v42, v43
	v_cvt_pk_bf16_f32 v70, v44, v45
	v_cvt_pk_bf16_f32 v71, v46, v47
	v_pk_add_f32 v[232:233], v[232:233], v[32:33]
	v_pk_add_f32 v[232:233], v[232:233], v[34:35]
	v_pk_add_f32 v[232:233], v[232:233], v[36:37]
	v_pk_add_f32 v[232:233], v[232:233], v[38:39]
	v_pk_add_f32 v[232:233], v[232:233], v[40:41]
	v_pk_add_f32 v[232:233], v[232:233], v[42:43]
	v_pk_add_f32 v[232:233], v[232:233], v[44:45]
	v_pk_add_f32 v[232:233], v[232:233], v[46:47]
	v_mov_b32_e32 v115, v230
	ds_read2_b32 v[32:33], v115 offset0:0 offset1:1
	ds_read2_b32 v[34:35], v115 offset0:2 offset1:3
	ds_read2_b32 v[36:37], v115 offset0:8 offset1:9
	ds_read2_b32 v[38:39], v115 offset0:10 offset1:11
	ds_read2_b32 v[40:41], v115 offset0:16 offset1:17
	ds_read2_b32 v[42:43], v115 offset0:18 offset1:19
	ds_read2_b32 v[44:45], v115 offset0:24 offset1:25
	ds_read2_b32 v[46:47], v115 offset0:26 offset1:27
	global_load_dwordx4 v[156:159], v243, s[88:89]
	global_load_dwordx4 v[160:163], v244, s[88:89]
	global_load_dwordx4 v[164:167], v245, s[88:89]
	global_load_dwordx4 v[168:171], v246, s[88:89]
	global_load_dwordx4 v[172:175], v148, s[88:89] offset:768
	global_load_dwordx4 v[176:179], v151, s[88:89] offset:768
	global_load_dwordx4 v[180:183], v148, s[88:89] offset:832
	global_load_dwordx4 v[184:187], v151, s[88:89] offset:832
	s_add_u32 s88, s88, 0x300000
	s_addc_u32 s89, s89, 0
	ds_read_b64_tr_b16 v[204:205], v231
	ds_read_b64_tr_b16 v[206:207], v231 offset:512
	ds_read_b64_tr_b16 v[208:209], v231 offset:2048
	ds_read_b64_tr_b16 v[210:211], v231 offset:2560
	ds_read_b64_tr_b16 v[212:213], v231 offset:1024
	ds_read_b64_tr_b16 v[214:215], v231 offset:1536
	ds_read_b64_tr_b16 v[216:217], v231 offset:3072
	ds_read_b64_tr_b16 v[218:219], v231 offset:3584
	v_exp_f32_e32 v188, v188
	v_exp_f32_e32 v189, v189
	v_exp_f32_e32 v190, v190
	v_exp_f32_e32 v191, v191
	s_waitcnt vmcnt(8)
	ds_write_b128 v247, v[116:119]
	ds_write_b128 v247, v[120:123] offset:1024
	ds_write_b128 v247, v[124:127] offset:2048
	ds_write_b128 v247, v[128:131] offset:3072
	ds_read_b128 v[116:119], v248
	ds_read_b128 v[120:123], v249
	ds_read_b128 v[124:127], v250
	ds_read_b128 v[128:131], v251
	ds_write_b128 v112, v[132:135]
	ds_write_b128 v112, v[136:139] offset:1024
	ds_write_b128 v112, v[140:143] offset:2048
	ds_write_b128 v112, v[144:147] offset:3072
	v_mfma_f32_32x32x16_bf16 v[0:15], v[64:67], v[72:75], v[0:15]
	v_mfma_f32_32x32x16_bf16 v[16:31], v[64:67], v[76:79], v[16:31]
	v_mfma_f32_32x32x16_bf16 v[0:15], v[68:71], v[220:223], v[0:15]
	v_mfma_f32_32x32x16_bf16 v[16:31], v[68:71], v[224:227], v[16:31]
	v_exp_f32_e32 v192, v192
	v_exp_f32_e32 v193, v193
	v_exp_f32_e32 v194, v194
	v_exp_f32_e32 v195, v195
	s_waitcnt lgkmcnt(4)
	v_mfma_f32_32x32x16_bf16 v[32:47], v[116:119], v[48:51], v[32:47]
	v_exp_f32_e32 v196, v196
	v_exp_f32_e32 v197, v197
	v_mfma_f32_32x32x16_bf16 v[32:47], v[120:123], v[52:55], v[32:47]
	v_exp_f32_e32 v198, v198
	v_exp_f32_e32 v199, v199
	v_mfma_f32_32x32x16_bf16 v[32:47], v[124:127], v[56:59], v[32:47]
	v_exp_f32_e32 v200, v200
	v_exp_f32_e32 v201, v201
	v_mfma_f32_32x32x16_bf16 v[32:47], v[128:131], v[60:63], v[32:47]
	v_exp_f32_e32 v202, v202
	v_exp_f32_e32 v203, v203
	v_cvt_pk_bf16_f32 v64, v188, v189
	v_cvt_pk_bf16_f32 v65, v190, v191
	v_cvt_pk_bf16_f32 v66, v192, v193
	v_cvt_pk_bf16_f32 v67, v194, v195
	v_cvt_pk_bf16_f32 v68, v196, v197
	v_cvt_pk_bf16_f32 v69, v198, v199
	v_cvt_pk_bf16_f32 v70, v200, v201
	v_cvt_pk_bf16_f32 v71, v202, v203
	v_pk_add_f32 v[232:233], v[232:233], v[188:189]
	v_pk_add_f32 v[232:233], v[232:233], v[190:191]
	v_pk_add_f32 v[232:233], v[232:233], v[192:193]
	v_pk_add_f32 v[232:233], v[232:233], v[194:195]
	v_pk_add_f32 v[232:233], v[232:233], v[196:197]
	v_pk_add_f32 v[232:233], v[232:233], v[198:199]
	v_pk_add_f32 v[232:233], v[232:233], v[200:201]
	v_pk_add_f32 v[232:233], v[232:233], v[202:203]
	ds_read2_b32 v[188:189], v115 offset0:32 offset1:33
	ds_read2_b32 v[190:191], v115 offset0:34 offset1:35
	ds_read2_b32 v[192:193], v115 offset0:40 offset1:41
	ds_read2_b32 v[194:195], v115 offset0:42 offset1:43
	ds_read2_b32 v[196:197], v115 offset0:48 offset1:49
	ds_read2_b32 v[198:199], v115 offset0:50 offset1:51
	ds_read2_b32 v[200:201], v115 offset0:56 offset1:57
	ds_read2_b32 v[202:203], v115 offset0:58 offset1:59
	global_load_dwordx4 v[116:119], v243, s[88:89]
	global_load_dwordx4 v[120:123], v244, s[88:89]
	global_load_dwordx4 v[124:127], v245, s[88:89]
	global_load_dwordx4 v[128:131], v246, s[88:89]
	global_load_dwordx4 v[132:135], v148, s[88:89] offset:768
	global_load_dwordx4 v[136:139], v151, s[88:89] offset:768
	global_load_dwordx4 v[140:143], v148, s[88:89] offset:832
	global_load_dwordx4 v[144:147], v151, s[88:89] offset:832
	s_add_u32 s88, s88, 0x300000
	s_addc_u32 s89, s89, 0
	ds_read_b64_tr_b16 v[72:73], v231
	ds_read_b64_tr_b16 v[74:75], v231 offset:512
	ds_read_b64_tr_b16 v[76:77], v231 offset:2048
	ds_read_b64_tr_b16 v[78:79], v231 offset:2560
	ds_read_b64_tr_b16 v[220:221], v231 offset:1024
	ds_read_b64_tr_b16 v[222:223], v231 offset:1536
	ds_read_b64_tr_b16 v[224:225], v231 offset:3072
	ds_read_b64_tr_b16 v[226:227], v231 offset:3584
	v_exp_f32_e32 v32, v32
	v_exp_f32_e32 v33, v33
	v_exp_f32_e32 v34, v34
	v_exp_f32_e32 v35, v35
	s_waitcnt vmcnt(8)
	ds_write_b128 v247, v[156:159]
	ds_write_b128 v247, v[160:163] offset:1024
	ds_write_b128 v247, v[164:167] offset:2048
	ds_write_b128 v247, v[168:171] offset:3072
	ds_read_b128 v[156:159], v248
	ds_read_b128 v[160:163], v249
	ds_read_b128 v[164:167], v250
	ds_read_b128 v[168:171], v251
	ds_write_b128 v112, v[172:175]
	ds_write_b128 v112, v[176:179] offset:1024
	ds_write_b128 v112, v[180:183] offset:2048
	ds_write_b128 v112, v[184:187] offset:3072
	v_mfma_f32_32x32x16_bf16 v[0:15], v[64:67], v[204:207], v[0:15]
	v_mfma_f32_32x32x16_bf16 v[16:31], v[64:67], v[208:211], v[16:31]
	v_mfma_f32_32x32x16_bf16 v[0:15], v[68:71], v[212:215], v[0:15]
	v_mfma_f32_32x32x16_bf16 v[16:31], v[68:71], v[216:219], v[16:31]
	v_exp_f32_e32 v36, v36
	v_exp_f32_e32 v37, v37
	v_exp_f32_e32 v38, v38
	v_exp_f32_e32 v39, v39
	s_waitcnt lgkmcnt(4)
	v_mfma_f32_32x32x16_bf16 v[188:203], v[156:159], v[48:51], v[188:203]
	v_exp_f32_e32 v40, v40
	v_exp_f32_e32 v41, v41
	v_mfma_f32_32x32x16_bf16 v[188:203], v[160:163], v[52:55], v[188:203]
	v_exp_f32_e32 v42, v42
	v_exp_f32_e32 v43, v43
	v_mfma_f32_32x32x16_bf16 v[188:203], v[164:167], v[56:59], v[188:203]
	v_exp_f32_e32 v44, v44
	v_exp_f32_e32 v45, v45
	v_mfma_f32_32x32x16_bf16 v[188:203], v[168:171], v[60:63], v[188:203]
	v_exp_f32_e32 v46, v46
	v_exp_f32_e32 v47, v47
	v_cvt_pk_bf16_f32 v64, v32, v33
	v_cvt_pk_bf16_f32 v65, v34, v35
	v_cvt_pk_bf16_f32 v66, v36, v37
	v_cvt_pk_bf16_f32 v67, v38, v39
	v_cvt_pk_bf16_f32 v68, v40, v41
	v_cvt_pk_bf16_f32 v69, v42, v43
	v_cvt_pk_bf16_f32 v70, v44, v45
	v_cvt_pk_bf16_f32 v71, v46, v47
	v_pk_add_f32 v[232:233], v[232:233], v[32:33]
	v_pk_add_f32 v[232:233], v[232:233], v[34:35]
	v_pk_add_f32 v[232:233], v[232:233], v[36:37]
	v_pk_add_f32 v[232:233], v[232:233], v[38:39]
	v_pk_add_f32 v[232:233], v[232:233], v[40:41]
	v_pk_add_f32 v[232:233], v[232:233], v[42:43]
	v_pk_add_f32 v[232:233], v[232:233], v[44:45]
	v_pk_add_f32 v[232:233], v[232:233], v[46:47]
	ds_read2_b32 v[32:33], v115 offset0:64 offset1:65
	ds_read2_b32 v[34:35], v115 offset0:66 offset1:67
	ds_read2_b32 v[36:37], v115 offset0:72 offset1:73
	ds_read2_b32 v[38:39], v115 offset0:74 offset1:75
	ds_read2_b32 v[40:41], v115 offset0:80 offset1:81
	ds_read2_b32 v[42:43], v115 offset0:82 offset1:83
	ds_read2_b32 v[44:45], v115 offset0:88 offset1:89
	ds_read2_b32 v[46:47], v115 offset0:90 offset1:91
	global_load_dwordx4 v[156:159], v243, s[88:89]
	global_load_dwordx4 v[160:163], v244, s[88:89]
	global_load_dwordx4 v[164:167], v245, s[88:89]
	global_load_dwordx4 v[168:171], v246, s[88:89]
	global_load_dwordx4 v[172:175], v148, s[88:89] offset:768
	global_load_dwordx4 v[176:179], v151, s[88:89] offset:768
	global_load_dwordx4 v[180:183], v148, s[88:89] offset:832
	global_load_dwordx4 v[184:187], v151, s[88:89] offset:832
	s_add_u32 s88, s88, 0x300000
	s_addc_u32 s89, s89, 0
	ds_read_b64_tr_b16 v[204:205], v231
	ds_read_b64_tr_b16 v[206:207], v231 offset:512
	ds_read_b64_tr_b16 v[208:209], v231 offset:2048
	ds_read_b64_tr_b16 v[210:211], v231 offset:2560
	ds_read_b64_tr_b16 v[212:213], v231 offset:1024
	ds_read_b64_tr_b16 v[214:215], v231 offset:1536
	ds_read_b64_tr_b16 v[216:217], v231 offset:3072
	ds_read_b64_tr_b16 v[218:219], v231 offset:3584
	v_exp_f32_e32 v188, v188
	v_exp_f32_e32 v189, v189
	v_exp_f32_e32 v190, v190
	v_exp_f32_e32 v191, v191
	s_waitcnt vmcnt(8)
	ds_write_b128 v247, v[116:119]
	ds_write_b128 v247, v[120:123] offset:1024
	ds_write_b128 v247, v[124:127] offset:2048
	ds_write_b128 v247, v[128:131] offset:3072
	ds_read_b128 v[116:119], v248
	ds_read_b128 v[120:123], v249
	ds_read_b128 v[124:127], v250
	ds_read_b128 v[128:131], v251
	ds_write_b128 v112, v[132:135]
	ds_write_b128 v112, v[136:139] offset:1024
	ds_write_b128 v112, v[140:143] offset:2048
	ds_write_b128 v112, v[144:147] offset:3072
	v_mfma_f32_32x32x16_bf16 v[0:15], v[64:67], v[72:75], v[0:15]
	v_mfma_f32_32x32x16_bf16 v[16:31], v[64:67], v[76:79], v[16:31]
	v_mfma_f32_32x32x16_bf16 v[0:15], v[68:71], v[220:223], v[0:15]
	v_mfma_f32_32x32x16_bf16 v[16:31], v[68:71], v[224:227], v[16:31]
	v_exp_f32_e32 v192, v192
	v_exp_f32_e32 v193, v193
	v_exp_f32_e32 v194, v194
	v_exp_f32_e32 v195, v195
	s_waitcnt lgkmcnt(4)
	v_mfma_f32_32x32x16_bf16 v[32:47], v[116:119], v[48:51], v[32:47]
	v_exp_f32_e32 v196, v196
	v_exp_f32_e32 v197, v197
	v_mfma_f32_32x32x16_bf16 v[32:47], v[120:123], v[52:55], v[32:47]
	v_exp_f32_e32 v198, v198
	v_exp_f32_e32 v199, v199
	v_mfma_f32_32x32x16_bf16 v[32:47], v[124:127], v[56:59], v[32:47]
	v_exp_f32_e32 v200, v200
	v_exp_f32_e32 v201, v201
	v_mfma_f32_32x32x16_bf16 v[32:47], v[128:131], v[60:63], v[32:47]
	v_exp_f32_e32 v202, v202
	v_exp_f32_e32 v203, v203
	v_cvt_pk_bf16_f32 v64, v188, v189
	v_cvt_pk_bf16_f32 v65, v190, v191
	v_cvt_pk_bf16_f32 v66, v192, v193
	v_cvt_pk_bf16_f32 v67, v194, v195
	v_cvt_pk_bf16_f32 v68, v196, v197
	v_cvt_pk_bf16_f32 v69, v198, v199
	v_cvt_pk_bf16_f32 v70, v200, v201
	v_cvt_pk_bf16_f32 v71, v202, v203
	v_pk_add_f32 v[232:233], v[232:233], v[188:189]
	v_pk_add_f32 v[232:233], v[232:233], v[190:191]
	v_pk_add_f32 v[232:233], v[232:233], v[192:193]
	v_pk_add_f32 v[232:233], v[232:233], v[194:195]
	v_pk_add_f32 v[232:233], v[232:233], v[196:197]
	v_pk_add_f32 v[232:233], v[232:233], v[198:199]
	v_pk_add_f32 v[232:233], v[232:233], v[200:201]
	v_pk_add_f32 v[232:233], v[232:233], v[202:203]
	ds_read2_b32 v[188:189], v115 offset0:96 offset1:97
	ds_read2_b32 v[190:191], v115 offset0:98 offset1:99
	ds_read2_b32 v[192:193], v115 offset0:104 offset1:105
	ds_read2_b32 v[194:195], v115 offset0:106 offset1:107
	ds_read2_b32 v[196:197], v115 offset0:112 offset1:113
	ds_read2_b32 v[198:199], v115 offset0:114 offset1:115
	ds_read2_b32 v[200:201], v115 offset0:120 offset1:121
	ds_read2_b32 v[202:203], v115 offset0:122 offset1:123
	global_load_dwordx4 v[116:119], v243, s[88:89]
	global_load_dwordx4 v[120:123], v244, s[88:89]
	global_load_dwordx4 v[124:127], v245, s[88:89]
	global_load_dwordx4 v[128:131], v246, s[88:89]
	global_load_dwordx4 v[132:135], v148, s[88:89] offset:768
	global_load_dwordx4 v[136:139], v151, s[88:89] offset:768
	global_load_dwordx4 v[140:143], v148, s[88:89] offset:832
	global_load_dwordx4 v[144:147], v151, s[88:89] offset:832
	ds_read_b64_tr_b16 v[72:73], v231
	ds_read_b64_tr_b16 v[74:75], v231 offset:512
	ds_read_b64_tr_b16 v[76:77], v231 offset:2048
	ds_read_b64_tr_b16 v[78:79], v231 offset:2560
	ds_read_b64_tr_b16 v[220:221], v231 offset:1024
	ds_read_b64_tr_b16 v[222:223], v231 offset:1536
	ds_read_b64_tr_b16 v[224:225], v231 offset:3072
	ds_read_b64_tr_b16 v[226:227], v231 offset:3584
	v_exp_f32_e32 v32, v32
	v_exp_f32_e32 v33, v33
	v_exp_f32_e32 v34, v34
	v_exp_f32_e32 v35, v35
	s_waitcnt vmcnt(8)
	ds_write_b128 v247, v[156:159]
	ds_write_b128 v247, v[160:163] offset:1024
	ds_write_b128 v247, v[164:167] offset:2048
	ds_write_b128 v247, v[168:171] offset:3072
	ds_read_b128 v[156:159], v248
	ds_read_b128 v[160:163], v249
	ds_read_b128 v[164:167], v250
	ds_read_b128 v[168:171], v251
	ds_write_b128 v112, v[172:175]
	ds_write_b128 v112, v[176:179] offset:1024
	ds_write_b128 v112, v[180:183] offset:2048
	ds_write_b128 v112, v[184:187] offset:3072
	v_mfma_f32_32x32x16_bf16 v[0:15], v[64:67], v[204:207], v[0:15]
	v_mfma_f32_32x32x16_bf16 v[16:31], v[64:67], v[208:211], v[16:31]
	v_mfma_f32_32x32x16_bf16 v[0:15], v[68:71], v[212:215], v[0:15]
	v_mfma_f32_32x32x16_bf16 v[16:31], v[68:71], v[216:219], v[16:31]
	v_exp_f32_e32 v36, v36
	v_exp_f32_e32 v37, v37
	v_exp_f32_e32 v38, v38
	v_exp_f32_e32 v39, v39
	s_waitcnt lgkmcnt(4)
	v_mfma_f32_32x32x16_bf16 v[188:203], v[156:159], v[48:51], v[188:203]
	v_exp_f32_e32 v40, v40
	v_exp_f32_e32 v41, v41
	v_mfma_f32_32x32x16_bf16 v[188:203], v[160:163], v[52:55], v[188:203]
	v_exp_f32_e32 v42, v42
	v_exp_f32_e32 v43, v43
	v_mfma_f32_32x32x16_bf16 v[188:203], v[164:167], v[56:59], v[188:203]
	v_exp_f32_e32 v44, v44
	v_exp_f32_e32 v45, v45
	v_mfma_f32_32x32x16_bf16 v[188:203], v[168:171], v[60:63], v[188:203]
	v_exp_f32_e32 v46, v46
	v_exp_f32_e32 v47, v47
	v_cvt_pk_bf16_f32 v64, v32, v33
	v_cvt_pk_bf16_f32 v65, v34, v35
	v_cvt_pk_bf16_f32 v66, v36, v37
	v_cvt_pk_bf16_f32 v67, v38, v39
	v_cvt_pk_bf16_f32 v68, v40, v41
	v_cvt_pk_bf16_f32 v69, v42, v43
	v_cvt_pk_bf16_f32 v70, v44, v45
	v_cvt_pk_bf16_f32 v71, v46, v47
	v_pk_add_f32 v[232:233], v[232:233], v[32:33]
	v_pk_add_f32 v[232:233], v[232:233], v[34:35]
	v_pk_add_f32 v[232:233], v[232:233], v[36:37]
	v_pk_add_f32 v[232:233], v[232:233], v[38:39]
	v_pk_add_f32 v[232:233], v[232:233], v[40:41]
	v_pk_add_f32 v[232:233], v[232:233], v[42:43]
	v_pk_add_f32 v[232:233], v[232:233], v[44:45]
	v_pk_add_f32 v[232:233], v[232:233], v[46:47]
	ds_read2_b32 v[32:33], v115 offset0:128 offset1:129
	ds_read2_b32 v[34:35], v115 offset0:130 offset1:131
	ds_read2_b32 v[36:37], v115 offset0:136 offset1:137
	ds_read2_b32 v[38:39], v115 offset0:138 offset1:139
	ds_read2_b32 v[40:41], v115 offset0:144 offset1:145
	ds_read2_b32 v[42:43], v115 offset0:146 offset1:147
	ds_read2_b32 v[44:45], v115 offset0:152 offset1:153
	ds_read2_b32 v[46:47], v115 offset0:154 offset1:155
	ds_read_b64_tr_b16 v[204:205], v231
	ds_read_b64_tr_b16 v[206:207], v231 offset:512
	ds_read_b64_tr_b16 v[208:209], v231 offset:2048
	ds_read_b64_tr_b16 v[210:211], v231 offset:2560
	ds_read_b64_tr_b16 v[212:213], v231 offset:1024
	ds_read_b64_tr_b16 v[214:215], v231 offset:1536
	ds_read_b64_tr_b16 v[216:217], v231 offset:3072
	ds_read_b64_tr_b16 v[218:219], v231 offset:3584
	v_exp_f32_e32 v188, v188
	v_exp_f32_e32 v189, v189
	v_exp_f32_e32 v190, v190
	v_exp_f32_e32 v191, v191
	s_waitcnt vmcnt(0)
; __device__ __forceinline__ int crow(int r, int hi) { return (r & 3) + 8 * (r >> 2) + 4 * hi; }
; __device__ __forceinline__ void dil_unit(LAS unsigned char* lds, bf16_t* proj, int seq, int hd, int T0, int rho) {
;     ...
;     l += __shfl_xor(l, 32);
; #pragma unroll
;     for (int rr = 0; rr < 16; ++rr) {
;         const int j = crow(rr, hi);
;         const float il = __builtin_amdgcn_rcpf(__shfl(l, j));
	ds_write_b128 v247, v[116:119]
	ds_write_b128 v247, v[120:123] offset:1024
	ds_write_b128 v247, v[124:127] offset:2048
	ds_write_b128 v247, v[128:131] offset:3072
	ds_read_b128 v[116:119], v248
	ds_read_b128 v[120:123], v249
	ds_read_b128 v[124:127], v250
	ds_read_b128 v[128:131], v251
	ds_write_b128 v112, v[132:135]
	ds_write_b128 v112, v[136:139] offset:1024
	ds_write_b128 v112, v[140:143] offset:2048
	ds_write_b128 v112, v[144:147] offset:3072
	v_mfma_f32_32x32x16_bf16 v[0:15], v[64:67], v[72:75], v[0:15]
	v_mfma_f32_32x32x16_bf16 v[16:31], v[64:67], v[76:79], v[16:31]
	v_mfma_f32_32x32x16_bf16 v[0:15], v[68:71], v[220:223], v[0:15]
	v_mfma_f32_32x32x16_bf16 v[16:31], v[68:71], v[224:227], v[16:31]
	v_exp_f32_e32 v192, v192
	v_exp_f32_e32 v193, v193
	v_exp_f32_e32 v194, v194
	v_exp_f32_e32 v195, v195
	s_waitcnt lgkmcnt(4)
	v_mfma_f32_32x32x16_bf16 v[32:47], v[116:119], v[48:51], v[32:47]
	v_exp_f32_e32 v196, v196
	v_exp_f32_e32 v197, v197
	v_mfma_f32_32x32x16_bf16 v[32:47], v[120:123], v[52:55], v[32:47]
	v_exp_f32_e32 v198, v198
	v_exp_f32_e32 v199, v199
	v_mfma_f32_32x32x16_bf16 v[32:47], v[124:127], v[56:59], v[32:47]
	v_exp_f32_e32 v200, v200
	v_exp_f32_e32 v201, v201
	v_mfma_f32_32x32x16_bf16 v[32:47], v[128:131], v[60:63], v[32:47]
	v_exp_f32_e32 v202, v202
	v_exp_f32_e32 v203, v203
	v_cvt_pk_bf16_f32 v64, v188, v189
	v_cvt_pk_bf16_f32 v65, v190, v191
	v_cvt_pk_bf16_f32 v66, v192, v193
	v_cvt_pk_bf16_f32 v67, v194, v195
	v_cvt_pk_bf16_f32 v68, v196, v197
	v_cvt_pk_bf16_f32 v69, v198, v199
	v_cvt_pk_bf16_f32 v70, v200, v201
	v_cvt_pk_bf16_f32 v71, v202, v203
	v_pk_add_f32 v[232:233], v[232:233], v[188:189]
	v_pk_add_f32 v[232:233], v[232:233], v[190:191]
	v_pk_add_f32 v[232:233], v[232:233], v[192:193]
	v_pk_add_f32 v[232:233], v[232:233], v[194:195]
	v_pk_add_f32 v[232:233], v[232:233], v[196:197]
	v_pk_add_f32 v[232:233], v[232:233], v[198:199]
	v_pk_add_f32 v[232:233], v[232:233], v[200:201]
	v_pk_add_f32 v[232:233], v[232:233], v[202:203]
	ds_read_b64_tr_b16 v[72:73], v231
	ds_read_b64_tr_b16 v[74:75], v231 offset:512
	ds_read_b64_tr_b16 v[76:77], v231 offset:2048
	ds_read_b64_tr_b16 v[78:79], v231 offset:2560
	ds_read_b64_tr_b16 v[220:221], v231 offset:1024
	ds_read_b64_tr_b16 v[222:223], v231 offset:1536
	ds_read_b64_tr_b16 v[224:225], v231 offset:3072
	ds_read_b64_tr_b16 v[226:227], v231 offset:3584
	s_waitcnt lgkmcnt(0)
	v_mfma_f32_32x32x16_bf16 v[0:15], v[64:67], v[204:207], v[0:15]
	v_mfma_f32_32x32x16_bf16 v[16:31], v[64:67], v[208:211], v[16:31]
	v_mfma_f32_32x32x16_bf16 v[0:15], v[68:71], v[212:215], v[0:15]
	v_mfma_f32_32x32x16_bf16 v[16:31], v[68:71], v[216:219], v[16:31]
	v_exp_f32_e32 v32, v32
	v_exp_f32_e32 v33, v33
	v_exp_f32_e32 v34, v34
	v_exp_f32_e32 v35, v35
	v_exp_f32_e32 v36, v36
	v_exp_f32_e32 v37, v37
	v_exp_f32_e32 v38, v38
	v_exp_f32_e32 v39, v39
	v_exp_f32_e32 v40, v40
	v_exp_f32_e32 v41, v41
	v_exp_f32_e32 v42, v42
	v_exp_f32_e32 v43, v43
	v_exp_f32_e32 v44, v44
	v_exp_f32_e32 v45, v45
	v_exp_f32_e32 v46, v46
	v_exp_f32_e32 v47, v47
	v_cvt_pk_bf16_f32 v64, v32, v33
	v_cvt_pk_bf16_f32 v65, v34, v35
	v_cvt_pk_bf16_f32 v66, v36, v37
	v_cvt_pk_bf16_f32 v67, v38, v39
	v_cvt_pk_bf16_f32 v68, v40, v41
	v_cvt_pk_bf16_f32 v69, v42, v43
	v_cvt_pk_bf16_f32 v70, v44, v45
	v_cvt_pk_bf16_f32 v71, v46, v47
	v_pk_add_f32 v[232:233], v[232:233], v[32:33]
	v_pk_add_f32 v[232:233], v[232:233], v[34:35]
	v_pk_add_f32 v[232:233], v[232:233], v[36:37]
	v_pk_add_f32 v[232:233], v[232:233], v[38:39]
	v_pk_add_f32 v[232:233], v[232:233], v[40:41]
	v_pk_add_f32 v[232:233], v[232:233], v[42:43]
	v_pk_add_f32 v[232:233], v[232:233], v[44:45]
	v_pk_add_f32 v[232:233], v[232:233], v[46:47]
	v_mfma_f32_32x32x16_bf16 v[0:15], v[64:67], v[72:75], v[0:15]
	v_mfma_f32_32x32x16_bf16 v[16:31], v[64:67], v[76:79], v[16:31]
	v_mfma_f32_32x32x16_bf16 v[0:15], v[68:71], v[220:223], v[0:15]
	v_mfma_f32_32x32x16_bf16 v[16:31], v[68:71], v[224:227], v[16:31]
	v_add_f32_e32 v113, v232, v233
	v_or_b32_e32 v114, 1, v107
	v_or_b32_e32 v97, 2, v107
	v_or_b32_e32 v96, 3, v107
	v_or_b32_e32 v95, 8, v107
	v_or_b32_e32 v94, 9, v107
	v_or_b32_e32 v93, 10, v107
	v_or_b32_e32 v92, 11, v107
	v_or_b32_e32 v91, 16, v107
	v_or_b32_e32 v90, 17, v107
	v_or_b32_e32 v89, 18, v107
	v_or_b32_e32 v88, 19, v107
	v_or_b32_e32 v87, 24, v107
	v_or_b32_e32 v86, 25, v107
	v_or_b32_e32 v85, 26, v107
	v_or_b32_e32 v84, 27, v107
	s_nop 11
	s_branch .LBB0_553
; #define LAS __attribute__((address_space(3)))
; #define GAS __attribute__((address_space(1)))
; __device__ __forceinline__ void dil_unit(LAS unsigned char* lds, bf16_t* proj, int seq, int hd, int T0, int rho) {
;     ...
;     bf16_t* base = proj + (size_t)seq * SEQ * NIN;
;     LAS unsigned char* wbuf = lds + wid * 4096;
;     const LAS unsigned char* vp = wbuf + ((lane >> 4) & 1) * 32 + (lane & 3) * 8 + (4 * hi + ((lane & 15) >> 2)) * 64;
;     const int P0 = T0 + rho;
;     bf16x8 qr[4];
; #pragma unroll
;     for (int ks = 0; ks < 4; ++ks) qr[ks] = *(const GAS bf16x8*)(base + (size_t)(P0 + 16 * r32) * NIN + PC_LQ + hd * 64 + 16 * ks + 8 * hi);
;     f32x16 o0 = {}, o1 = {}; float l = 0.f;
;     const bool bound = (T0 < 1024) || (T0 >= 15360);
.LBB0_558:
	s_movk_i32 s100, 0x1800
	s_add_i32 s101, s6, 0x15c00
	s_lshl_b32 s90, s58, 1
	s_add_u32 s82, s56, s90
	s_addc_u32 s83, s57, 0
	s_add_u32 s82, s82, 0x1200
	s_addc_u32 s83, s83, 0
	s_sub_i32 s90, s76, 64
	s_mul_i32 s90, s90, 0x1800
	s_add_u32 s84, s82, s90
	s_addc_u32 s85, s83, 0
	s_sub_i32 s90, s76, 256
	s_mul_i32 s90, s90, 0x1800
	s_add_u32 s86, s82, s90
	s_addc_u32 s87, s83, 0
	s_sub_i32 s90, s76, 1024
	s_mul_i32 s90, s90, 0x1800
	s_add_u32 s88, s82, s90
	s_addc_u32 s89, s83, 0
	v_lshlrev_b32_e32 v153, 1, v98
	v_mad_u32_u24 v80, v105, s100, v82
	v_mad_u32_u24 v100, v110, s100, v153
	v_add_u32_e32 v149, 0x18000, v100
	v_lshlrev_b32_e32 v83, 2, v105
	v_mad_u32_u24 v83, v83, s100, v82
	v_lshlrev_b32_e32 v101, 2, v110
	v_mad_u32_u24 v101, v101, s100, v153
	v_add_u32_e32 v150, 0x60000, v101
	v_lshlrev_b32_e32 v99, 4, v105
	v_mad_u32_u24 v99, v99, s100, v82
	v_lshlrev_b32_e32 v148, 4, v110
	v_mad_u32_u24 v148, v148, s100, v153
	v_add_u32_e32 v151, 0x180000, v148
	v_lshrrev_b32_e32 v249, 3, v103
	v_and_b32_e32 v250, 7, v103
	v_lshlrev_b32_e32 v250, 4, v250
	v_add_u32_e32 v235, 0, v249
	v_add_u32_e32 v236, 8, v249
	v_add_u32_e32 v237, 16, v249
	v_add_u32_e32 v238, 24, v249
	v_add_u32_e32 v239, 0, v249
	v_lshlrev_b32_e32 v239, 2, v239
	v_add_u32_e32 v240, 8, v249
	v_lshlrev_b32_e32 v240, 2, v240
	v_add_u32_e32 v241, 16, v249
	v_lshlrev_b32_e32 v241, 2, v241
	v_add_u32_e32 v242, 24, v249
	v_lshlrev_b32_e32 v242, 2, v242
	v_add_u32_e32 v243, 0, v249
	v_lshlrev_b32_e32 v243, 4, v243
	v_add_u32_e32 v244, 8, v249
	v_lshlrev_b32_e32 v244, 4, v244
	v_add_u32_e32 v245, 16, v249
	v_lshlrev_b32_e32 v245, 4, v245
	v_add_u32_e32 v246, 24, v249
	v_lshlrev_b32_e32 v246, 4, v246
	v_mov_b32_e32 v252, v250
	v_mov_b32_e32 v100, v110
	v_add_u32_e32 v149, 16, v100
	v_lshlrev_b32_e32 v101, 2, v110
	v_add_u32_e32 v150, 64, v101
	v_lshlrev_b32_e32 v148, 4, v110
	v_add_u32_e32 v151, 256, v148
	s_mov_b32 s98, 0x4000
	s_mov_b32 s99, 0x3fff
	v_and_b32_e32 v247, 7, v249
	v_lshlrev_b32_e32 v247, 4, v247
	v_xor_b32_e32 v247, v247, v112
	v_and_b32_e32 v153, 7, v105
	v_or_b32_e32 v248, 0, v106
	v_xor_b32_e32 v248, v248, v153
	v_lshlrev_b32_e32 v248, 4, v248
	v_lshl_add_u32 v248, v105, 7, v248
	v_add_u32_e32 v248, s77, v248
	v_or_b32_e32 v249, 2, v106
	v_xor_b32_e32 v249, v249, v153
	v_lshlrev_b32_e32 v249, 4, v249
	v_lshl_add_u32 v249, v105, 7, v249
	v_add_u32_e32 v249, s77, v249
	v_or_b32_e32 v250, 4, v106
	v_xor_b32_e32 v250, v250, v153
	v_lshlrev_b32_e32 v250, 4, v250
	v_lshl_add_u32 v250, v105, 7, v250
	v_add_u32_e32 v250, s77, v250
	v_or_b32_e32 v251, 6, v106
	v_xor_b32_e32 v251, v251, v153
	v_lshlrev_b32_e32 v251, 4, v251
	v_lshl_add_u32 v251, v105, 7, v251
	v_add_u32_e32 v251, s77, v251
	v_lshlrev_b32_e32 v153, 1, v98
	v_mul_u32_u24_e32 v228, 17, v105
	v_sub_u32_e32 v228, v107, v228
	s_mul_i32 s90, s58, 153
	s_lshr_b32 s90, s90, 1
	s_add_i32 s90, s90, 34876
	v_lshl_add_u32 v228, v228, 2, s90
	v_lshlrev_b32_e32 v229, 2, v105
	v_sub_u32_e32 v229, v107, v229
	s_add_i32 s90, s101, 5104
	v_lshl_add_u32 v229, v229, 2, s90
	v_sub_u32_e32 v230, v107, v105
	s_add_i32 s90, s101, 6364
	v_lshl_add_u32 v230, v230, 2, s90
	v_add_u32_e32 v231, v109, v108
	v_mov_b64_e32 v[232:233], 0
	v_mov_b64_e32 v[0:1], 0
	v_mov_b64_e32 v[2:3], 0
	v_mov_b64_e32 v[4:5], 0
	v_mov_b64_e32 v[6:7], 0
	v_mov_b64_e32 v[8:9], 0
	v_mov_b64_e32 v[10:11], 0
	v_mov_b64_e32 v[12:13], 0
	v_mov_b64_e32 v[14:15], 0
	v_mov_b64_e32 v[16:17], 0
	v_mov_b64_e32 v[18:19], 0
	v_mov_b64_e32 v[20:21], 0
	v_mov_b64_e32 v[22:23], 0
	v_mov_b64_e32 v[24:25], 0
	v_mov_b64_e32 v[26:27], 0
	v_mov_b64_e32 v[28:29], 0
	v_mov_b64_e32 v[30:31], 0
	s_add_i32 s90, s76, -64
	v_add_u32_e32 v80, s90, v235
	v_add_u32_e32 v83, s90, v236
	v_add_u32_e32 v99, s90, v237
	v_add_u32_e32 v253, s90, v238
	v_add_u32_e32 v254, s90, v100
	v_add_u32_e32 v255, s90, v149
	v_med3_i32 v80, v80, 0, s99
	v_med3_i32 v83, v83, 0, s99
	v_med3_i32 v99, v99, 0, s99
	v_med3_i32 v253, v253, 0, s99
	v_med3_i32 v254, v254, 0, s99
	v_med3_i32 v255, v255, 0, s99
	v_mad_u32_u24 v80, v80, s100, v252
	v_mad_u32_u24 v83, v83, s100, v252
	v_mad_u32_u24 v99, v99, s100, v252
	v_mad_u32_u24 v253, v253, s100, v252
	v_mad_u32_u24 v254, v254, s100, v153
	v_mad_u32_u24 v255, v255, s100, v153
	global_load_dwordx4 v[116:119], v80, s[82:83]
	global_load_dwordx4 v[120:123], v83, s[82:83]
	global_load_dwordx4 v[124:127], v99, s[82:83]
	global_load_dwordx4 v[128:131], v253, s[82:83]
	global_load_dwordx4 v[132:135], v254, s[82:83] offset:768
	global_load_dwordx4 v[136:139], v255, s[82:83] offset:768
	global_load_dwordx4 v[140:143], v254, s[82:83] offset:832
	global_load_dwordx4 v[144:147], v255, s[82:83] offset:832
	s_add_i32 s90, s76, -32
	v_add_u32_e32 v80, s90, v235
	v_add_u32_e32 v83, s90, v236
	v_add_u32_e32 v99, s90, v237
	v_add_u32_e32 v253, s90, v238
	v_add_u32_e32 v254, s90, v100
	v_add_u32_e32 v255, s90, v149
	v_med3_i32 v80, v80, 0, s99
	v_med3_i32 v83, v83, 0, s99
	v_med3_i32 v99, v99, 0, s99
	v_med3_i32 v253, v253, 0, s99
	v_med3_i32 v254, v254, 0, s99
	v_med3_i32 v255, v255, 0, s99
	v_mad_u32_u24 v80, v80, s100, v252
	v_mad_u32_u24 v83, v83, s100, v252
	v_mad_u32_u24 v99, v99, s100, v252
	v_mad_u32_u24 v253, v253, s100, v252
	v_mad_u32_u24 v254, v254, s100, v153
	v_mad_u32_u24 v255, v255, s100, v153
	global_load_dwordx4 v[156:159], v80, s[82:83]
	global_load_dwordx4 v[160:163], v83, s[82:83]
	global_load_dwordx4 v[164:167], v99, s[82:83]
	global_load_dwordx4 v[168:171], v253, s[82:83]
	global_load_dwordx4 v[172:175], v254, s[82:83] offset:768
	global_load_dwordx4 v[176:179], v255, s[82:83] offset:768
	global_load_dwordx4 v[180:183], v254, s[82:83] offset:832
	global_load_dwordx4 v[184:187], v255, s[82:83] offset:832
	v_mov_b32_e32 v115, v228
	ds_read2_b32 v[32:33], v115 offset0:0 offset1:1
	ds_read2_b32 v[34:35], v115 offset0:2 offset1:3
	ds_read2_b32 v[36:37], v115 offset0:8 offset1:9
	ds_read2_b32 v[38:39], v115 offset0:10 offset1:11
	ds_read2_b32 v[40:41], v115 offset0:17 offset1:18
	ds_read2_b32 v[42:43], v115 offset0:19 offset1:20
	ds_read2_b32 v[44:45], v115 offset0:25 offset1:26
	ds_read2_b32 v[46:47], v115 offset0:27 offset1:28
	s_waitcnt vmcnt(8)
	ds_write_b128 v247, v[116:119]
	ds_write_b128 v247, v[120:123] offset:1024
	ds_write_b128 v247, v[124:127] offset:2048
	ds_write_b128 v247, v[128:131] offset:3072
	ds_read_b128 v[116:119], v248
	ds_read_b128 v[120:123], v249
	ds_read_b128 v[124:127], v250
	ds_read_b128 v[128:131], v251
	ds_write_b128 v112, v[132:135]
	ds_write_b128 v112, v[136:139] offset:1024
	ds_write_b128 v112, v[140:143] offset:2048
	ds_write_b128 v112, v[144:147] offset:3072
	s_waitcnt lgkmcnt(4)
	v_mfma_f32_32x32x16_bf16 v[32:47], v[116:119], v[48:51], v[32:47]
	v_mfma_f32_32x32x16_bf16 v[32:47], v[120:123], v[52:55], v[32:47]
	v_mfma_f32_32x32x16_bf16 v[32:47], v[124:127], v[56:59], v[32:47]
	v_mfma_f32_32x32x16_bf16 v[32:47], v[128:131], v[60:63], v[32:47]
	ds_read2_b32 v[188:189], v115 offset0:34 offset1:35
	ds_read2_b32 v[190:191], v115 offset0:36 offset1:37
	ds_read2_b32 v[192:193], v115 offset0:42 offset1:43
	ds_read2_b32 v[194:195], v115 offset0:44 offset1:45
	ds_read2_b32 v[196:197], v115 offset0:51 offset1:52
	ds_read2_b32 v[198:199], v115 offset0:53 offset1:54
	ds_read2_b32 v[200:201], v115 offset0:59 offset1:60
	ds_read2_b32 v[202:203], v115 offset0:61 offset1:62
	s_add_i32 s90, s76, 0
	v_add_u32_e32 v80, s90, v235
	v_add_u32_e32 v83, s90, v236
	v_add_u32_e32 v99, s90, v237
	v_add_u32_e32 v253, s90, v238
	v_add_u32_e32 v254, s90, v100
	v_add_u32_e32 v255, s90, v149
	v_med3_i32 v80, v80, 0, s99
	v_med3_i32 v83, v83, 0, s99
	v_med3_i32 v99, v99, 0, s99
	v_med3_i32 v253, v253, 0, s99
	v_med3_i32 v254, v254, 0, s99
	v_med3_i32 v255, v255, 0, s99
	v_mad_u32_u24 v80, v80, s100, v252
	v_mad_u32_u24 v83, v83, s100, v252
	v_mad_u32_u24 v99, v99, s100, v252
	v_mad_u32_u24 v253, v253, s100, v252
	v_mad_u32_u24 v254, v254, s100, v153
	v_mad_u32_u24 v255, v255, s100, v153
	global_load_dwordx4 v[116:119], v80, s[82:83]
	global_load_dwordx4 v[120:123], v83, s[82:83]
	global_load_dwordx4 v[124:127], v99, s[82:83]
	global_load_dwordx4 v[128:131], v253, s[82:83]
	global_load_dwordx4 v[132:135], v254, s[82:83] offset:768
	global_load_dwordx4 v[136:139], v255, s[82:83] offset:768
	global_load_dwordx4 v[140:143], v254, s[82:83] offset:832
	global_load_dwordx4 v[144:147], v255, s[82:83] offset:832
	ds_read_b64_tr_b16 v[72:73], v231
	ds_read_b64_tr_b16 v[74:75], v231 offset:512
	ds_read_b64_tr_b16 v[76:77], v231 offset:2048
	ds_read_b64_tr_b16 v[78:79], v231 offset:2560
	ds_read_b64_tr_b16 v[220:221], v231 offset:1024
	ds_read_b64_tr_b16 v[222:223], v231 offset:1536
	ds_read_b64_tr_b16 v[224:225], v231 offset:3072
	ds_read_b64_tr_b16 v[226:227], v231 offset:3584
	v_exp_f32_e32 v32, v32
	v_exp_f32_e32 v33, v33
	v_exp_f32_e32 v34, v34
	v_exp_f32_e32 v35, v35
	s_waitcnt vmcnt(8)
	ds_write_b128 v247, v[156:159]
	ds_write_b128 v247, v[160:163] offset:1024
	ds_write_b128 v247, v[164:167] offset:2048
	ds_write_b128 v247, v[168:171] offset:3072
	ds_read_b128 v[156:159], v248
	ds_read_b128 v[160:163], v249
	ds_read_b128 v[164:167], v250
	ds_read_b128 v[168:171], v251
	ds_write_b128 v112, v[172:175]
	ds_write_b128 v112, v[176:179] offset:1024
	ds_write_b128 v112, v[180:183] offset:2048
	ds_write_b128 v112, v[184:187] offset:3072
	v_exp_f32_e32 v36, v36
	v_exp_f32_e32 v37, v37
	v_exp_f32_e32 v38, v38
	v_exp_f32_e32 v39, v39
	s_waitcnt lgkmcnt(4)
	v_mfma_f32_32x32x16_bf16 v[188:203], v[156:159], v[48:51], v[188:203]
	v_exp_f32_e32 v40, v40
	v_exp_f32_e32 v41, v41
	v_mfma_f32_32x32x16_bf16 v[188:203], v[160:163], v[52:55], v[188:203]
	v_exp_f32_e32 v42, v42
	v_exp_f32_e32 v43, v43
	v_mfma_f32_32x32x16_bf16 v[188:203], v[164:167], v[56:59], v[188:203]
	v_exp_f32_e32 v44, v44
	v_exp_f32_e32 v45, v45
	v_mfma_f32_32x32x16_bf16 v[188:203], v[168:171], v[60:63], v[188:203]
	v_exp_f32_e32 v46, v46
	v_exp_f32_e32 v47, v47
	s_add_i32 s90, s76, -64
	v_add_u32_e32 v84, s90, v107
	v_add_u32_e32 v85, 0, v84
	v_add_u32_e32 v86, 1, v84
	v_add_u32_e32 v87, 2, v84
	v_add_u32_e32 v88, 3, v84
	v_cmp_gt_u32_e64 s[30:31], s98, v85
	v_cmp_gt_u32_e64 s[36:37], s98, v86
	v_cmp_gt_u32_e64 s[78:79], s98, v87
	v_cmp_gt_u32_e64 s[50:51], s98, v88
	v_cndmask_b32_e64 v32, 0, v32, s[30:31]
	v_add_u32_e32 v85, 8, v84
	v_cmp_gt_u32_e64 s[30:31], s98, v85
	v_cndmask_b32_e64 v33, 0, v33, s[36:37]
	v_add_u32_e32 v86, 9, v84
	v_cmp_gt_u32_e64 s[36:37], s98, v86
	v_cndmask_b32_e64 v34, 0, v34, s[78:79]
	v_add_u32_e32 v87, 10, v84
	v_cmp_gt_u32_e64 s[78:79], s98, v87
	v_cndmask_b32_e64 v35, 0, v35, s[50:51]
	v_add_u32_e32 v88, 11, v84
	v_cmp_gt_u32_e64 s[50:51], s98, v88
	v_cndmask_b32_e64 v36, 0, v36, s[30:31]
	v_add_u32_e32 v85, 16, v84
	v_cmp_gt_u32_e64 s[30:31], s98, v85
	v_cndmask_b32_e64 v37, 0, v37, s[36:37]
	v_add_u32_e32 v86, 17, v84
	v_cmp_gt_u32_e64 s[36:37], s98, v86
	v_cndmask_b32_e64 v38, 0, v38, s[78:79]
	v_add_u32_e32 v87, 18, v84
	v_cmp_gt_u32_e64 s[78:79], s98, v87
	v_cndmask_b32_e64 v39, 0, v39, s[50:51]
	v_add_u32_e32 v88, 19, v84
	v_cmp_gt_u32_e64 s[50:51], s98, v88
	v_cndmask_b32_e64 v40, 0, v40, s[30:31]
	v_add_u32_e32 v85, 24, v84
	v_cmp_gt_u32_e64 s[30:31], s98, v85
	v_cndmask_b32_e64 v41, 0, v41, s[36:37]
	v_add_u32_e32 v86, 25, v84
	v_cmp_gt_u32_e64 s[36:37], s98, v86
	v_cndmask_b32_e64 v42, 0, v42, s[78:79]
	v_add_u32_e32 v87, 26, v84
	v_cmp_gt_u32_e64 s[78:79], s98, v87
	v_cndmask_b32_e64 v43, 0, v43, s[50:51]
	v_add_u32_e32 v88, 27, v84
	v_cmp_gt_u32_e64 s[50:51], s98, v88
	v_nop
	v_cndmask_b32_e64 v44, 0, v44, s[30:31]
	v_cndmask_b32_e64 v45, 0, v45, s[36:37]
	v_cndmask_b32_e64 v46, 0, v46, s[78:79]
	v_cndmask_b32_e64 v47, 0, v47, s[50:51]
	v_cvt_pk_bf16_f32 v64, v32, v33
	v_cvt_pk_bf16_f32 v65, v34, v35
	v_cvt_pk_bf16_f32 v66, v36, v37
	v_cvt_pk_bf16_f32 v67, v38, v39
	v_cvt_pk_bf16_f32 v68, v40, v41
	v_cvt_pk_bf16_f32 v69, v42, v43
	v_cvt_pk_bf16_f32 v70, v44, v45
	v_cvt_pk_bf16_f32 v71, v46, v47
	v_pk_add_f32 v[232:233], v[232:233], v[32:33]
	v_pk_add_f32 v[232:233], v[232:233], v[34:35]
	v_pk_add_f32 v[232:233], v[232:233], v[36:37]
	v_pk_add_f32 v[232:233], v[232:233], v[38:39]
	v_pk_add_f32 v[232:233], v[232:233], v[40:41]
	v_pk_add_f32 v[232:233], v[232:233], v[42:43]
	v_pk_add_f32 v[232:233], v[232:233], v[44:45]
	v_pk_add_f32 v[232:233], v[232:233], v[46:47]
	ds_read2_b32 v[32:33], v115 offset0:68 offset1:69
	ds_read2_b32 v[34:35], v115 offset0:70 offset1:71
	ds_read2_b32 v[36:37], v115 offset0:76 offset1:77
	ds_read2_b32 v[38:39], v115 offset0:78 offset1:79
	ds_read2_b32 v[40:41], v115 offset0:85 offset1:86
	ds_read2_b32 v[42:43], v115 offset0:87 offset1:88
	ds_read2_b32 v[44:45], v115 offset0:93 offset1:94
	ds_read2_b32 v[46:47], v115 offset0:95 offset1:96
	s_add_i32 s90, s76, 32
	v_add_u32_e32 v80, s90, v235
	v_add_u32_e32 v83, s90, v236
	v_add_u32_e32 v99, s90, v237
	v_add_u32_e32 v253, s90, v238
	v_add_u32_e32 v254, s90, v100
	v_add_u32_e32 v255, s90, v149
	v_med3_i32 v80, v80, 0, s99
	v_med3_i32 v83, v83, 0, s99
	v_med3_i32 v99, v99, 0, s99
	v_med3_i32 v253, v253, 0, s99
	v_med3_i32 v254, v254, 0, s99
	v_med3_i32 v255, v255, 0, s99
	v_mad_u32_u24 v80, v80, s100, v252
	v_mad_u32_u24 v83, v83, s100, v252
	v_mad_u32_u24 v99, v99, s100, v252
	v_mad_u32_u24 v253, v253, s100, v252
	v_mad_u32_u24 v254, v254, s100, v153
	v_mad_u32_u24 v255, v255, s100, v153
	global_load_dwordx4 v[156:159], v80, s[82:83]
	global_load_dwordx4 v[160:163], v83, s[82:83]
	global_load_dwordx4 v[164:167], v99, s[82:83]
	global_load_dwordx4 v[168:171], v253, s[82:83]
	global_load_dwordx4 v[172:175], v254, s[82:83] offset:768
	global_load_dwordx4 v[176:179], v255, s[82:83] offset:768
	global_load_dwordx4 v[180:183], v254, s[82:83] offset:832
	global_load_dwordx4 v[184:187], v255, s[82:83] offset:832
	ds_read_b64_tr_b16 v[204:205], v231
	ds_read_b64_tr_b16 v[206:207], v231 offset:512
	ds_read_b64_tr_b16 v[208:209], v231 offset:2048
	ds_read_b64_tr_b16 v[210:211], v231 offset:2560
	ds_read_b64_tr_b16 v[212:213], v231 offset:1024
	ds_read_b64_tr_b16 v[214:215], v231 offset:1536
	ds_read_b64_tr_b16 v[216:217], v231 offset:3072
	ds_read_b64_tr_b16 v[218:219], v231 offset:3584
	v_exp_f32_e32 v188, v188
	v_exp_f32_e32 v189, v189
	v_exp_f32_e32 v190, v190
	v_exp_f32_e32 v191, v191
	s_waitcnt vmcnt(8)
	ds_write_b128 v247, v[116:119]
	ds_write_b128 v247, v[120:123] offset:1024
	ds_write_b128 v247, v[124:127] offset:2048
	ds_write_b128 v247, v[128:131] offset:3072
	ds_read_b128 v[116:119], v248
	ds_read_b128 v[120:123], v249
	ds_read_b128 v[124:127], v250
	ds_read_b128 v[128:131], v251
	ds_write_b128 v112, v[132:135]
	ds_write_b128 v112, v[136:139] offset:1024
	ds_write_b128 v112, v[140:143] offset:2048
	ds_write_b128 v112, v[144:147] offset:3072
	v_mfma_f32_32x32x16_bf16 v[0:15], v[64:67], v[72:75], v[0:15]
	v_mfma_f32_32x32x16_bf16 v[16:31], v[64:67], v[76:79], v[16:31]
	v_mfma_f32_32x32x16_bf16 v[0:15], v[68:71], v[220:223], v[0:15]
	v_mfma_f32_32x32x16_bf16 v[16:31], v[68:71], v[224:227], v[16:31]
	v_exp_f32_e32 v192, v192
	v_exp_f32_e32 v193, v193
	v_exp_f32_e32 v194, v194
	v_exp_f32_e32 v195, v195
	s_waitcnt lgkmcnt(4)
	v_mfma_f32_32x32x16_bf16 v[32:47], v[116:119], v[48:51], v[32:47]
	v_exp_f32_e32 v196, v196
	v_exp_f32_e32 v197, v197
	v_mfma_f32_32x32x16_bf16 v[32:47], v[120:123], v[52:55], v[32:47]
	v_exp_f32_e32 v198, v198
	v_exp_f32_e32 v199, v199
	v_mfma_f32_32x32x16_bf16 v[32:47], v[124:127], v[56:59], v[32:47]
	v_exp_f32_e32 v200, v200
	v_exp_f32_e32 v201, v201
	v_mfma_f32_32x32x16_bf16 v[32:47], v[128:131], v[60:63], v[32:47]
	v_exp_f32_e32 v202, v202
	v_exp_f32_e32 v203, v203
	s_add_i32 s90, s76, -32
	v_add_u32_e32 v84, s90, v107
	v_add_u32_e32 v85, 0, v84
	v_add_u32_e32 v86, 1, v84
	v_add_u32_e32 v87, 2, v84
	v_add_u32_e32 v88, 3, v84
	v_cmp_gt_u32_e64 s[30:31], s98, v85
	v_cmp_gt_u32_e64 s[36:37], s98, v86
	v_cmp_gt_u32_e64 s[78:79], s98, v87
	v_cmp_gt_u32_e64 s[50:51], s98, v88
	v_cndmask_b32_e64 v188, 0, v188, s[30:31]
	v_add_u32_e32 v85, 8, v84
	v_cmp_gt_u32_e64 s[30:31], s98, v85
	v_cndmask_b32_e64 v189, 0, v189, s[36:37]
	v_add_u32_e32 v86, 9, v84
	v_cmp_gt_u32_e64 s[36:37], s98, v86
	v_cndmask_b32_e64 v190, 0, v190, s[78:79]
	v_add_u32_e32 v87, 10, v84
	v_cmp_gt_u32_e64 s[78:79], s98, v87
	v_cndmask_b32_e64 v191, 0, v191, s[50:51]
	v_add_u32_e32 v88, 11, v84
	v_cmp_gt_u32_e64 s[50:51], s98, v88
	v_cndmask_b32_e64 v192, 0, v192, s[30:31]
	v_add_u32_e32 v85, 16, v84
	v_cmp_gt_u32_e64 s[30:31], s98, v85
	v_cndmask_b32_e64 v193, 0, v193, s[36:37]
	v_add_u32_e32 v86, 17, v84
	v_cmp_gt_u32_e64 s[36:37], s98, v86
	v_cndmask_b32_e64 v194, 0, v194, s[78:79]
	v_add_u32_e32 v87, 18, v84
	v_cmp_gt_u32_e64 s[78:79], s98, v87
	v_cndmask_b32_e64 v195, 0, v195, s[50:51]
	v_add_u32_e32 v88, 19, v84
	v_cmp_gt_u32_e64 s[50:51], s98, v88
	v_cndmask_b32_e64 v196, 0, v196, s[30:31]
	v_add_u32_e32 v85, 24, v84
	v_cmp_gt_u32_e64 s[30:31], s98, v85
	v_cndmask_b32_e64 v197, 0, v197, s[36:37]
	v_add_u32_e32 v86, 25, v84
	v_cmp_gt_u32_e64 s[36:37], s98, v86
	v_cndmask_b32_e64 v198, 0, v198, s[78:79]
	v_add_u32_e32 v87, 26, v84
	v_cmp_gt_u32_e64 s[78:79], s98, v87
	v_cndmask_b32_e64 v199, 0, v199, s[50:51]
	v_add_u32_e32 v88, 27, v84
	v_cmp_gt_u32_e64 s[50:51], s98, v88
	v_nop
	v_cndmask_b32_e64 v200, 0, v200, s[30:31]
	v_cndmask_b32_e64 v201, 0, v201, s[36:37]
	v_cndmask_b32_e64 v202, 0, v202, s[78:79]
	v_cndmask_b32_e64 v203, 0, v203, s[50:51]
	v_cvt_pk_bf16_f32 v64, v188, v189
	v_cvt_pk_bf16_f32 v65, v190, v191
	v_cvt_pk_bf16_f32 v66, v192, v193
	v_cvt_pk_bf16_f32 v67, v194, v195
	v_cvt_pk_bf16_f32 v68, v196, v197
	v_cvt_pk_bf16_f32 v69, v198, v199
	v_cvt_pk_bf16_f32 v70, v200, v201
	v_cvt_pk_bf16_f32 v71, v202, v203
	v_pk_add_f32 v[232:233], v[232:233], v[188:189]
	v_pk_add_f32 v[232:233], v[232:233], v[190:191]
	v_pk_add_f32 v[232:233], v[232:233], v[192:193]
	v_pk_add_f32 v[232:233], v[232:233], v[194:195]
	v_pk_add_f32 v[232:233], v[232:233], v[196:197]
	v_pk_add_f32 v[232:233], v[232:233], v[198:199]
	v_pk_add_f32 v[232:233], v[232:233], v[200:201]
	v_pk_add_f32 v[232:233], v[232:233], v[202:203]
	ds_read2_b32 v[188:189], v115 offset0:102 offset1:103
	ds_read2_b32 v[190:191], v115 offset0:104 offset1:105
	ds_read2_b32 v[192:193], v115 offset0:110 offset1:111
	ds_read2_b32 v[194:195], v115 offset0:112 offset1:113
	ds_read2_b32 v[196:197], v115 offset0:119 offset1:120
	ds_read2_b32 v[198:199], v115 offset0:121 offset1:122
	ds_read2_b32 v[200:201], v115 offset0:127 offset1:128
	ds_read2_b32 v[202:203], v115 offset0:129 offset1:130
	s_add_i32 s90, s76, 64
	v_add_u32_e32 v80, s90, v235
	v_add_u32_e32 v83, s90, v236
	v_add_u32_e32 v99, s90, v237
	v_add_u32_e32 v253, s90, v238
	v_add_u32_e32 v254, s90, v100
	v_add_u32_e32 v255, s90, v149
	v_med3_i32 v80, v80, 0, s99
	v_med3_i32 v83, v83, 0, s99
	v_med3_i32 v99, v99, 0, s99
	v_med3_i32 v253, v253, 0, s99
	v_med3_i32 v254, v254, 0, s99
	v_med3_i32 v255, v255, 0, s99
	v_mad_u32_u24 v80, v80, s100, v252
	v_mad_u32_u24 v83, v83, s100, v252
	v_mad_u32_u24 v99, v99, s100, v252
	v_mad_u32_u24 v253, v253, s100, v252
	v_mad_u32_u24 v254, v254, s100, v153
	v_mad_u32_u24 v255, v255, s100, v153
	global_load_dwordx4 v[116:119], v80, s[82:83]
	global_load_dwordx4 v[120:123], v83, s[82:83]
	global_load_dwordx4 v[124:127], v99, s[82:83]
	global_load_dwordx4 v[128:131], v253, s[82:83]
	global_load_dwordx4 v[132:135], v254, s[82:83] offset:768
	global_load_dwordx4 v[136:139], v255, s[82:83] offset:768
	global_load_dwordx4 v[140:143], v254, s[82:83] offset:832
	global_load_dwordx4 v[144:147], v255, s[82:83] offset:832
	ds_read_b64_tr_b16 v[72:73], v231
	ds_read_b64_tr_b16 v[74:75], v231 offset:512
	ds_read_b64_tr_b16 v[76:77], v231 offset:2048
	ds_read_b64_tr_b16 v[78:79], v231 offset:2560
	ds_read_b64_tr_b16 v[220:221], v231 offset:1024
	ds_read_b64_tr_b16 v[222:223], v231 offset:1536
	ds_read_b64_tr_b16 v[224:225], v231 offset:3072
	ds_read_b64_tr_b16 v[226:227], v231 offset:3584
	v_exp_f32_e32 v32, v32
	v_exp_f32_e32 v33, v33
	v_exp_f32_e32 v34, v34
	v_exp_f32_e32 v35, v35
	s_waitcnt vmcnt(8)
	ds_write_b128 v247, v[156:159]
	ds_write_b128 v247, v[160:163] offset:1024
	ds_write_b128 v247, v[164:167] offset:2048
	ds_write_b128 v247, v[168:171] offset:3072
	ds_read_b128 v[156:159], v248
	ds_read_b128 v[160:163], v249
	ds_read_b128 v[164:167], v250
	ds_read_b128 v[168:171], v251
	ds_write_b128 v112, v[172:175]
	ds_write_b128 v112, v[176:179] offset:1024
	ds_write_b128 v112, v[180:183] offset:2048
	ds_write_b128 v112, v[184:187] offset:3072
	v_mfma_f32_32x32x16_bf16 v[0:15], v[64:67], v[204:207], v[0:15]
	v_mfma_f32_32x32x16_bf16 v[16:31], v[64:67], v[208:211], v[16:31]
	v_mfma_f32_32x32x16_bf16 v[0:15], v[68:71], v[212:215], v[0:15]
	v_mfma_f32_32x32x16_bf16 v[16:31], v[68:71], v[216:219], v[16:31]
	v_exp_f32_e32 v36, v36
	v_exp_f32_e32 v37, v37
	v_exp_f32_e32 v38, v38
	v_exp_f32_e32 v39, v39
	s_waitcnt lgkmcnt(4)
	v_mfma_f32_32x32x16_bf16 v[188:203], v[156:159], v[48:51], v[188:203]
	v_exp_f32_e32 v40, v40
	v_exp_f32_e32 v41, v41
	v_mfma_f32_32x32x16_bf16 v[188:203], v[160:163], v[52:55], v[188:203]
	v_exp_f32_e32 v42, v42
	v_exp_f32_e32 v43, v43
	v_mfma_f32_32x32x16_bf16 v[188:203], v[164:167], v[56:59], v[188:203]
	v_exp_f32_e32 v44, v44
	v_exp_f32_e32 v45, v45
	v_mfma_f32_32x32x16_bf16 v[188:203], v[168:171], v[60:63], v[188:203]
	v_exp_f32_e32 v46, v46
	v_exp_f32_e32 v47, v47
	s_add_i32 s90, s76, 0
	v_add_u32_e32 v84, s90, v107
	v_add_u32_e32 v85, 0, v84
	v_add_u32_e32 v86, 1, v84
	v_add_u32_e32 v87, 2, v84
	v_add_u32_e32 v88, 3, v84
	v_cmp_gt_u32_e64 s[30:31], s98, v85
	v_cmp_gt_u32_e64 s[36:37], s98, v86
	v_cmp_gt_u32_e64 s[78:79], s98, v87
	v_cmp_gt_u32_e64 s[50:51], s98, v88
	v_cndmask_b32_e64 v32, 0, v32, s[30:31]
	v_add_u32_e32 v85, 8, v84
	v_cmp_gt_u32_e64 s[30:31], s98, v85
	v_cndmask_b32_e64 v33, 0, v33, s[36:37]
	v_add_u32_e32 v86, 9, v84
	v_cmp_gt_u32_e64 s[36:37], s98, v86
	v_cndmask_b32_e64 v34, 0, v34, s[78:79]
	v_add_u32_e32 v87, 10, v84
	v_cmp_gt_u32_e64 s[78:79], s98, v87
	v_cndmask_b32_e64 v35, 0, v35, s[50:51]
	v_add_u32_e32 v88, 11, v84
	v_cmp_gt_u32_e64 s[50:51], s98, v88
	v_cndmask_b32_e64 v36, 0, v36, s[30:31]
	v_add_u32_e32 v85, 16, v84
	v_cmp_gt_u32_e64 s[30:31], s98, v85
	v_cndmask_b32_e64 v37, 0, v37, s[36:37]
	v_add_u32_e32 v86, 17, v84
	v_cmp_gt_u32_e64 s[36:37], s98, v86
	v_cndmask_b32_e64 v38, 0, v38, s[78:79]
	v_add_u32_e32 v87, 18, v84
	v_cmp_gt_u32_e64 s[78:79], s98, v87
	v_cndmask_b32_e64 v39, 0, v39, s[50:51]
	v_add_u32_e32 v88, 19, v84
	v_cmp_gt_u32_e64 s[50:51], s98, v88
	v_cndmask_b32_e64 v40, 0, v40, s[30:31]
	v_add_u32_e32 v85, 24, v84
	v_cmp_gt_u32_e64 s[30:31], s98, v85
	v_cndmask_b32_e64 v41, 0, v41, s[36:37]
	v_add_u32_e32 v86, 25, v84
	v_cmp_gt_u32_e64 s[36:37], s98, v86
	v_cndmask_b32_e64 v42, 0, v42, s[78:79]
	v_add_u32_e32 v87, 26, v84
	v_cmp_gt_u32_e64 s[78:79], s98, v87
	v_cndmask_b32_e64 v43, 0, v43, s[50:51]
	v_add_u32_e32 v88, 27, v84
	v_cmp_gt_u32_e64 s[50:51], s98, v88
	v_nop
	v_cndmask_b32_e64 v44, 0, v44, s[30:31]
	v_cndmask_b32_e64 v45, 0, v45, s[36:37]
	v_cndmask_b32_e64 v46, 0, v46, s[78:79]
	v_cndmask_b32_e64 v47, 0, v47, s[50:51]
	v_cvt_pk_bf16_f32 v64, v32, v33
	v_cvt_pk_bf16_f32 v65, v34, v35
	v_cvt_pk_bf16_f32 v66, v36, v37
	v_cvt_pk_bf16_f32 v67, v38, v39
	v_cvt_pk_bf16_f32 v68, v40, v41
	v_cvt_pk_bf16_f32 v69, v42, v43
	v_cvt_pk_bf16_f32 v70, v44, v45
	v_cvt_pk_bf16_f32 v71, v46, v47
	v_pk_add_f32 v[232:233], v[232:233], v[32:33]
	v_pk_add_f32 v[232:233], v[232:233], v[34:35]
	v_pk_add_f32 v[232:233], v[232:233], v[36:37]
	v_pk_add_f32 v[232:233], v[232:233], v[38:39]
	v_pk_add_f32 v[232:233], v[232:233], v[40:41]
	v_pk_add_f32 v[232:233], v[232:233], v[42:43]
	v_pk_add_f32 v[232:233], v[232:233], v[44:45]
	v_pk_add_f32 v[232:233], v[232:233], v[46:47]
	ds_read2_b32 v[32:33], v115 offset0:136 offset1:137
	ds_read2_b32 v[34:35], v115 offset0:138 offset1:139
	ds_read2_b32 v[36:37], v115 offset0:144 offset1:145
	ds_read2_b32 v[38:39], v115 offset0:146 offset1:147
	ds_read2_b32 v[40:41], v115 offset0:153 offset1:154
	ds_read2_b32 v[42:43], v115 offset0:155 offset1:156
	ds_read2_b32 v[44:45], v115 offset0:161 offset1:162
	ds_read2_b32 v[46:47], v115 offset0:163 offset1:164
	s_add_i32 s90, s76, 96
	v_add_u32_e32 v80, s90, v235
	v_add_u32_e32 v83, s90, v236
	v_add_u32_e32 v99, s90, v237
	v_add_u32_e32 v253, s90, v238
	v_add_u32_e32 v254, s90, v100
	v_add_u32_e32 v255, s90, v149
	v_med3_i32 v80, v80, 0, s99
	v_med3_i32 v83, v83, 0, s99
	v_med3_i32 v99, v99, 0, s99
	v_med3_i32 v253, v253, 0, s99
	v_med3_i32 v254, v254, 0, s99
	v_med3_i32 v255, v255, 0, s99
	v_mad_u32_u24 v80, v80, s100, v252
	v_mad_u32_u24 v83, v83, s100, v252
	v_mad_u32_u24 v99, v99, s100, v252
	v_mad_u32_u24 v253, v253, s100, v252
	v_mad_u32_u24 v254, v254, s100, v153
	v_mad_u32_u24 v255, v255, s100, v153
	global_load_dwordx4 v[156:159], v80, s[82:83]
	global_load_dwordx4 v[160:163], v83, s[82:83]
	global_load_dwordx4 v[164:167], v99, s[82:83]
	global_load_dwordx4 v[168:171], v253, s[82:83]
	global_load_dwordx4 v[172:175], v254, s[82:83] offset:768
	global_load_dwordx4 v[176:179], v255, s[82:83] offset:768
	global_load_dwordx4 v[180:183], v254, s[82:83] offset:832
	global_load_dwordx4 v[184:187], v255, s[82:83] offset:832
	ds_read_b64_tr_b16 v[204:205], v231
	ds_read_b64_tr_b16 v[206:207], v231 offset:512
	ds_read_b64_tr_b16 v[208:209], v231 offset:2048
	ds_read_b64_tr_b16 v[210:211], v231 offset:2560
	ds_read_b64_tr_b16 v[212:213], v231 offset:1024
	ds_read_b64_tr_b16 v[214:215], v231 offset:1536
	ds_read_b64_tr_b16 v[216:217], v231 offset:3072
	ds_read_b64_tr_b16 v[218:219], v231 offset:3584
	v_exp_f32_e32 v188, v188
	v_exp_f32_e32 v189, v189
	v_exp_f32_e32 v190, v190
	v_exp_f32_e32 v191, v191
	s_waitcnt vmcnt(8)
	ds_write_b128 v247, v[116:119]
	ds_write_b128 v247, v[120:123] offset:1024
	ds_write_b128 v247, v[124:127] offset:2048
	ds_write_b128 v247, v[128:131] offset:3072
	ds_read_b128 v[116:119], v248
	ds_read_b128 v[120:123], v249
	ds_read_b128 v[124:127], v250
	ds_read_b128 v[128:131], v251
	ds_write_b128 v112, v[132:135]
	ds_write_b128 v112, v[136:139] offset:1024
	ds_write_b128 v112, v[140:143] offset:2048
	ds_write_b128 v112, v[144:147] offset:3072
	v_mfma_f32_32x32x16_bf16 v[0:15], v[64:67], v[72:75], v[0:15]
	v_mfma_f32_32x32x16_bf16 v[16:31], v[64:67], v[76:79], v[16:31]
	v_mfma_f32_32x32x16_bf16 v[0:15], v[68:71], v[220:223], v[0:15]
	v_mfma_f32_32x32x16_bf16 v[16:31], v[68:71], v[224:227], v[16:31]
	v_exp_f32_e32 v192, v192
	v_exp_f32_e32 v193, v193
	v_exp_f32_e32 v194, v194
	v_exp_f32_e32 v195, v195
	s_waitcnt lgkmcnt(4)
	v_mfma_f32_32x32x16_bf16 v[32:47], v[116:119], v[48:51], v[32:47]
	v_exp_f32_e32 v196, v196
	v_exp_f32_e32 v197, v197
	v_mfma_f32_32x32x16_bf16 v[32:47], v[120:123], v[52:55], v[32:47]
	v_exp_f32_e32 v198, v198
	v_exp_f32_e32 v199, v199
	v_mfma_f32_32x32x16_bf16 v[32:47], v[124:127], v[56:59], v[32:47]
	v_exp_f32_e32 v200, v200
	v_exp_f32_e32 v201, v201
	v_mfma_f32_32x32x16_bf16 v[32:47], v[128:131], v[60:63], v[32:47]
	v_exp_f32_e32 v202, v202
	v_exp_f32_e32 v203, v203
	s_add_i32 s90, s76, 32
	v_add_u32_e32 v84, s90, v107
	v_add_u32_e32 v85, 0, v84
	v_add_u32_e32 v86, 1, v84
	v_add_u32_e32 v87, 2, v84
	v_add_u32_e32 v88, 3, v84
	v_cmp_gt_u32_e64 s[30:31], s98, v85
	v_cmp_gt_u32_e64 s[36:37], s98, v86
	v_cmp_gt_u32_e64 s[78:79], s98, v87
	v_cmp_gt_u32_e64 s[50:51], s98, v88
	v_cndmask_b32_e64 v188, 0, v188, s[30:31]
	v_add_u32_e32 v85, 8, v84
	v_cmp_gt_u32_e64 s[30:31], s98, v85
	v_cndmask_b32_e64 v189, 0, v189, s[36:37]
	v_add_u32_e32 v86, 9, v84
	v_cmp_gt_u32_e64 s[36:37], s98, v86
	v_cndmask_b32_e64 v190, 0, v190, s[78:79]
	v_add_u32_e32 v87, 10, v84
	v_cmp_gt_u32_e64 s[78:79], s98, v87
	v_cndmask_b32_e64 v191, 0, v191, s[50:51]
	v_add_u32_e32 v88, 11, v84
	v_cmp_gt_u32_e64 s[50:51], s98, v88
	v_cndmask_b32_e64 v192, 0, v192, s[30:31]
	v_add_u32_e32 v85, 16, v84
	v_cmp_gt_u32_e64 s[30:31], s98, v85
	v_cndmask_b32_e64 v193, 0, v193, s[36:37]
	v_add_u32_e32 v86, 17, v84
	v_cmp_gt_u32_e64 s[36:37], s98, v86
	v_cndmask_b32_e64 v194, 0, v194, s[78:79]
	v_add_u32_e32 v87, 18, v84
	v_cmp_gt_u32_e64 s[78:79], s98, v87
	v_cndmask_b32_e64 v195, 0, v195, s[50:51]
	v_add_u32_e32 v88, 19, v84
	v_cmp_gt_u32_e64 s[50:51], s98, v88
	v_cndmask_b32_e64 v196, 0, v196, s[30:31]
	v_add_u32_e32 v85, 24, v84
	v_cmp_gt_u32_e64 s[30:31], s98, v85
	v_cndmask_b32_e64 v197, 0, v197, s[36:37]
	v_add_u32_e32 v86, 25, v84
	v_cmp_gt_u32_e64 s[36:37], s98, v86
	v_cndmask_b32_e64 v198, 0, v198, s[78:79]
	v_add_u32_e32 v87, 26, v84
	v_cmp_gt_u32_e64 s[78:79], s98, v87
	v_cndmask_b32_e64 v199, 0, v199, s[50:51]
	v_add_u32_e32 v88, 27, v84
	v_cmp_gt_u32_e64 s[50:51], s98, v88
	v_nop
	v_cndmask_b32_e64 v200, 0, v200, s[30:31]
	v_cndmask_b32_e64 v201, 0, v201, s[36:37]
	v_cndmask_b32_e64 v202, 0, v202, s[78:79]
	v_cndmask_b32_e64 v203, 0, v203, s[50:51]
	v_cvt_pk_bf16_f32 v64, v188, v189
	v_cvt_pk_bf16_f32 v65, v190, v191
	v_cvt_pk_bf16_f32 v66, v192, v193
	v_cvt_pk_bf16_f32 v67, v194, v195
	v_cvt_pk_bf16_f32 v68, v196, v197
	v_cvt_pk_bf16_f32 v69, v198, v199
	v_cvt_pk_bf16_f32 v70, v200, v201
	v_cvt_pk_bf16_f32 v71, v202, v203
	v_pk_add_f32 v[232:233], v[232:233], v[188:189]
	v_pk_add_f32 v[232:233], v[232:233], v[190:191]
	v_pk_add_f32 v[232:233], v[232:233], v[192:193]
	v_pk_add_f32 v[232:233], v[232:233], v[194:195]
	v_pk_add_f32 v[232:233], v[232:233], v[196:197]
	v_pk_add_f32 v[232:233], v[232:233], v[198:199]
	v_pk_add_f32 v[232:233], v[232:233], v[200:201]
	v_pk_add_f32 v[232:233], v[232:233], v[202:203]
	ds_read2_b32 v[188:189], v115 offset0:170 offset1:171
	ds_read2_b32 v[190:191], v115 offset0:172 offset1:173
	ds_read2_b32 v[192:193], v115 offset0:178 offset1:179
	ds_read2_b32 v[194:195], v115 offset0:180 offset1:181
	ds_read2_b32 v[196:197], v115 offset0:187 offset1:188
	ds_read2_b32 v[198:199], v115 offset0:189 offset1:190
	ds_read2_b32 v[200:201], v115 offset0:195 offset1:196
	ds_read2_b32 v[202:203], v115 offset0:197 offset1:198
	s_add_i32 s90, s76, 128
	v_add_u32_e32 v80, s90, v235
	v_add_u32_e32 v83, s90, v236
	v_add_u32_e32 v99, s90, v237
	v_add_u32_e32 v253, s90, v238
	v_add_u32_e32 v254, s90, v100
	v_add_u32_e32 v255, s90, v149
	v_med3_i32 v80, v80, 0, s99
	v_med3_i32 v83, v83, 0, s99
	v_med3_i32 v99, v99, 0, s99
	v_med3_i32 v253, v253, 0, s99
	v_med3_i32 v254, v254, 0, s99
	v_med3_i32 v255, v255, 0, s99
	v_mad_u32_u24 v80, v80, s100, v252
	v_mad_u32_u24 v83, v83, s100, v252
	v_mad_u32_u24 v99, v99, s100, v252
	v_mad_u32_u24 v253, v253, s100, v252
	v_mad_u32_u24 v254, v254, s100, v153
	v_mad_u32_u24 v255, v255, s100, v153
	global_load_dwordx4 v[116:119], v80, s[82:83]
	global_load_dwordx4 v[120:123], v83, s[82:83]
	global_load_dwordx4 v[124:127], v99, s[82:83]
	global_load_dwordx4 v[128:131], v253, s[82:83]
	global_load_dwordx4 v[132:135], v254, s[82:83] offset:768
	global_load_dwordx4 v[136:139], v255, s[82:83] offset:768
	global_load_dwordx4 v[140:143], v254, s[82:83] offset:832
	global_load_dwordx4 v[144:147], v255, s[82:83] offset:832
	ds_read_b64_tr_b16 v[72:73], v231
	ds_read_b64_tr_b16 v[74:75], v231 offset:512
	ds_read_b64_tr_b16 v[76:77], v231 offset:2048
	ds_read_b64_tr_b16 v[78:79], v231 offset:2560
	ds_read_b64_tr_b16 v[220:221], v231 offset:1024
	ds_read_b64_tr_b16 v[222:223], v231 offset:1536
	ds_read_b64_tr_b16 v[224:225], v231 offset:3072
	ds_read_b64_tr_b16 v[226:227], v231 offset:3584
	v_exp_f32_e32 v32, v32
	v_exp_f32_e32 v33, v33
	v_exp_f32_e32 v34, v34
	v_exp_f32_e32 v35, v35
	s_waitcnt vmcnt(8)
	ds_write_b128 v247, v[156:159]
	ds_write_b128 v247, v[160:163] offset:1024
	ds_write_b128 v247, v[164:167] offset:2048
	ds_write_b128 v247, v[168:171] offset:3072
	ds_read_b128 v[156:159], v248
	ds_read_b128 v[160:163], v249
	ds_read_b128 v[164:167], v250
	ds_read_b128 v[168:171], v251
	ds_write_b128 v112, v[172:175]
	ds_write_b128 v112, v[176:179] offset:1024
	ds_write_b128 v112, v[180:183] offset:2048
	ds_write_b128 v112, v[184:187] offset:3072
	v_mfma_f32_32x32x16_bf16 v[0:15], v[64:67], v[204:207], v[0:15]
	v_mfma_f32_32x32x16_bf16 v[16:31], v[64:67], v[208:211], v[16:31]
	v_mfma_f32_32x32x16_bf16 v[0:15], v[68:71], v[212:215], v[0:15]
	v_mfma_f32_32x32x16_bf16 v[16:31], v[68:71], v[216:219], v[16:31]
	v_exp_f32_e32 v36, v36
	v_exp_f32_e32 v37, v37
	v_exp_f32_e32 v38, v38
	v_exp_f32_e32 v39, v39
	s_waitcnt lgkmcnt(4)
	v_mfma_f32_32x32x16_bf16 v[188:203], v[156:159], v[48:51], v[188:203]
	v_exp_f32_e32 v40, v40
	v_exp_f32_e32 v41, v41
	v_mfma_f32_32x32x16_bf16 v[188:203], v[160:163], v[52:55], v[188:203]
	v_exp_f32_e32 v42, v42
	v_exp_f32_e32 v43, v43
	v_mfma_f32_32x32x16_bf16 v[188:203], v[164:167], v[56:59], v[188:203]
	v_exp_f32_e32 v44, v44
	v_exp_f32_e32 v45, v45
	v_mfma_f32_32x32x16_bf16 v[188:203], v[168:171], v[60:63], v[188:203]
	v_exp_f32_e32 v46, v46
	v_exp_f32_e32 v47, v47
	s_add_i32 s90, s76, 64
	v_add_u32_e32 v84, s90, v107
	v_add_u32_e32 v85, 0, v84
	v_add_u32_e32 v86, 1, v84
	v_add_u32_e32 v87, 2, v84
	v_add_u32_e32 v88, 3, v84
	v_cmp_gt_u32_e64 s[30:31], s98, v85
	v_cmp_gt_u32_e64 s[36:37], s98, v86
	v_cmp_gt_u32_e64 s[78:79], s98, v87
	v_cmp_gt_u32_e64 s[50:51], s98, v88
	v_cndmask_b32_e64 v32, 0, v32, s[30:31]
	v_add_u32_e32 v85, 8, v84
	v_cmp_gt_u32_e64 s[30:31], s98, v85
	v_cndmask_b32_e64 v33, 0, v33, s[36:37]
	v_add_u32_e32 v86, 9, v84
	v_cmp_gt_u32_e64 s[36:37], s98, v86
	v_cndmask_b32_e64 v34, 0, v34, s[78:79]
	v_add_u32_e32 v87, 10, v84
	v_cmp_gt_u32_e64 s[78:79], s98, v87
	v_cndmask_b32_e64 v35, 0, v35, s[50:51]
	v_add_u32_e32 v88, 11, v84
	v_cmp_gt_u32_e64 s[50:51], s98, v88
	v_cndmask_b32_e64 v36, 0, v36, s[30:31]
	v_add_u32_e32 v85, 16, v84
	v_cmp_gt_u32_e64 s[30:31], s98, v85
	v_cndmask_b32_e64 v37, 0, v37, s[36:37]
	v_add_u32_e32 v86, 17, v84
	v_cmp_gt_u32_e64 s[36:37], s98, v86
	v_cndmask_b32_e64 v38, 0, v38, s[78:79]
	v_add_u32_e32 v87, 18, v84
	v_cmp_gt_u32_e64 s[78:79], s98, v87
	v_cndmask_b32_e64 v39, 0, v39, s[50:51]
	v_add_u32_e32 v88, 19, v84
	v_cmp_gt_u32_e64 s[50:51], s98, v88
	v_cndmask_b32_e64 v40, 0, v40, s[30:31]
	v_add_u32_e32 v85, 24, v84
	v_cmp_gt_u32_e64 s[30:31], s98, v85
	v_cndmask_b32_e64 v41, 0, v41, s[36:37]
	v_add_u32_e32 v86, 25, v84
	v_cmp_gt_u32_e64 s[36:37], s98, v86
	v_cndmask_b32_e64 v42, 0, v42, s[78:79]
	v_add_u32_e32 v87, 26, v84
	v_cmp_gt_u32_e64 s[78:79], s98, v87
	v_cndmask_b32_e64 v43, 0, v43, s[50:51]
	v_add_u32_e32 v88, 27, v84
	v_cmp_gt_u32_e64 s[50:51], s98, v88
	v_nop
	v_cndmask_b32_e64 v44, 0, v44, s[30:31]
	v_cndmask_b32_e64 v45, 0, v45, s[36:37]
	v_cndmask_b32_e64 v46, 0, v46, s[78:79]
	v_cndmask_b32_e64 v47, 0, v47, s[50:51]
	v_cvt_pk_bf16_f32 v64, v32, v33
	v_cvt_pk_bf16_f32 v65, v34, v35
	v_cvt_pk_bf16_f32 v66, v36, v37
	v_cvt_pk_bf16_f32 v67, v38, v39
	v_cvt_pk_bf16_f32 v68, v40, v41
	v_cvt_pk_bf16_f32 v69, v42, v43
	v_cvt_pk_bf16_f32 v70, v44, v45
	v_cvt_pk_bf16_f32 v71, v46, v47
	v_pk_add_f32 v[232:233], v[232:233], v[32:33]
	v_pk_add_f32 v[232:233], v[232:233], v[34:35]
	v_pk_add_f32 v[232:233], v[232:233], v[36:37]
	v_pk_add_f32 v[232:233], v[232:233], v[38:39]
	v_pk_add_f32 v[232:233], v[232:233], v[40:41]
	v_pk_add_f32 v[232:233], v[232:233], v[42:43]
	v_pk_add_f32 v[232:233], v[232:233], v[44:45]
	v_pk_add_f32 v[232:233], v[232:233], v[46:47]
	ds_read2_b32 v[32:33], v115 offset0:204 offset1:205
	ds_read2_b32 v[34:35], v115 offset0:206 offset1:207
	ds_read2_b32 v[36:37], v115 offset0:212 offset1:213
	ds_read2_b32 v[38:39], v115 offset0:214 offset1:215
	ds_read2_b32 v[40:41], v115 offset0:221 offset1:222
	ds_read2_b32 v[42:43], v115 offset0:223 offset1:224
	ds_read2_b32 v[44:45], v115 offset0:229 offset1:230
	ds_read2_b32 v[46:47], v115 offset0:231 offset1:232
	s_add_i32 s90, s76, 160
	v_add_u32_e32 v80, s90, v235
	v_add_u32_e32 v83, s90, v236
	v_add_u32_e32 v99, s90, v237
	v_add_u32_e32 v253, s90, v238
	v_add_u32_e32 v254, s90, v100
	v_add_u32_e32 v255, s90, v149
	v_med3_i32 v80, v80, 0, s99
	v_med3_i32 v83, v83, 0, s99
	v_med3_i32 v99, v99, 0, s99
	v_med3_i32 v253, v253, 0, s99
	v_med3_i32 v254, v254, 0, s99
	v_med3_i32 v255, v255, 0, s99
	v_mad_u32_u24 v80, v80, s100, v252
	v_mad_u32_u24 v83, v83, s100, v252
	v_mad_u32_u24 v99, v99, s100, v252
	v_mad_u32_u24 v253, v253, s100, v252
	v_mad_u32_u24 v254, v254, s100, v153
	v_mad_u32_u24 v255, v255, s100, v153
	global_load_dwordx4 v[156:159], v80, s[82:83]
	global_load_dwordx4 v[160:163], v83, s[82:83]
	global_load_dwordx4 v[164:167], v99, s[82:83]
	global_load_dwordx4 v[168:171], v253, s[82:83]
	global_load_dwordx4 v[172:175], v254, s[82:83] offset:768
	global_load_dwordx4 v[176:179], v255, s[82:83] offset:768
	global_load_dwordx4 v[180:183], v254, s[82:83] offset:832
	global_load_dwordx4 v[184:187], v255, s[82:83] offset:832
	ds_read_b64_tr_b16 v[204:205], v231
	ds_read_b64_tr_b16 v[206:207], v231 offset:512
	ds_read_b64_tr_b16 v[208:209], v231 offset:2048
	ds_read_b64_tr_b16 v[210:211], v231 offset:2560
	ds_read_b64_tr_b16 v[212:213], v231 offset:1024
	ds_read_b64_tr_b16 v[214:215], v231 offset:1536
	ds_read_b64_tr_b16 v[216:217], v231 offset:3072
	ds_read_b64_tr_b16 v[218:219], v231 offset:3584
	v_exp_f32_e32 v188, v188
	v_exp_f32_e32 v189, v189
	v_exp_f32_e32 v190, v190
	v_exp_f32_e32 v191, v191
	s_waitcnt vmcnt(8)
	ds_write_b128 v247, v[116:119]
	ds_write_b128 v247, v[120:123] offset:1024
	ds_write_b128 v247, v[124:127] offset:2048
	ds_write_b128 v247, v[128:131] offset:3072
	ds_read_b128 v[116:119], v248
	ds_read_b128 v[120:123], v249
	ds_read_b128 v[124:127], v250
	ds_read_b128 v[128:131], v251
	ds_write_b128 v112, v[132:135]
	ds_write_b128 v112, v[136:139] offset:1024
	ds_write_b128 v112, v[140:143] offset:2048
	ds_write_b128 v112, v[144:147] offset:3072
	v_mfma_f32_32x32x16_bf16 v[0:15], v[64:67], v[72:75], v[0:15]
	v_mfma_f32_32x32x16_bf16 v[16:31], v[64:67], v[76:79], v[16:31]
	v_mfma_f32_32x32x16_bf16 v[0:15], v[68:71], v[220:223], v[0:15]
	v_mfma_f32_32x32x16_bf16 v[16:31], v[68:71], v[224:227], v[16:31]
	v_exp_f32_e32 v192, v192
	v_exp_f32_e32 v193, v193
	v_exp_f32_e32 v194, v194
	v_exp_f32_e32 v195, v195
	s_waitcnt lgkmcnt(4)
	v_mfma_f32_32x32x16_bf16 v[32:47], v[116:119], v[48:51], v[32:47]
	v_exp_f32_e32 v196, v196
	v_exp_f32_e32 v197, v197
	v_mfma_f32_32x32x16_bf16 v[32:47], v[120:123], v[52:55], v[32:47]
	v_exp_f32_e32 v198, v198
	v_exp_f32_e32 v199, v199
	v_mfma_f32_32x32x16_bf16 v[32:47], v[124:127], v[56:59], v[32:47]
	v_exp_f32_e32 v200, v200
	v_exp_f32_e32 v201, v201
	v_mfma_f32_32x32x16_bf16 v[32:47], v[128:131], v[60:63], v[32:47]
	v_exp_f32_e32 v202, v202
	v_exp_f32_e32 v203, v203
	s_add_i32 s90, s76, 96
	v_add_u32_e32 v84, s90, v107
	v_add_u32_e32 v85, 0, v84
	v_add_u32_e32 v86, 1, v84
	v_add_u32_e32 v87, 2, v84
	v_add_u32_e32 v88, 3, v84
	v_cmp_gt_u32_e64 s[30:31], s98, v85
	v_cmp_gt_u32_e64 s[36:37], s98, v86
	v_cmp_gt_u32_e64 s[78:79], s98, v87
	v_cmp_gt_u32_e64 s[50:51], s98, v88
	v_cndmask_b32_e64 v188, 0, v188, s[30:31]
	v_add_u32_e32 v85, 8, v84
	v_cmp_gt_u32_e64 s[30:31], s98, v85
	v_cndmask_b32_e64 v189, 0, v189, s[36:37]
	v_add_u32_e32 v86, 9, v84
	v_cmp_gt_u32_e64 s[36:37], s98, v86
	v_cndmask_b32_e64 v190, 0, v190, s[78:79]
	v_add_u32_e32 v87, 10, v84
	v_cmp_gt_u32_e64 s[78:79], s98, v87
	v_cndmask_b32_e64 v191, 0, v191, s[50:51]
	v_add_u32_e32 v88, 11, v84
	v_cmp_gt_u32_e64 s[50:51], s98, v88
	v_cndmask_b32_e64 v192, 0, v192, s[30:31]
	v_add_u32_e32 v85, 16, v84
	v_cmp_gt_u32_e64 s[30:31], s98, v85
	v_cndmask_b32_e64 v193, 0, v193, s[36:37]
	v_add_u32_e32 v86, 17, v84
	v_cmp_gt_u32_e64 s[36:37], s98, v86
	v_cndmask_b32_e64 v194, 0, v194, s[78:79]
	v_add_u32_e32 v87, 18, v84
	v_cmp_gt_u32_e64 s[78:79], s98, v87
	v_cndmask_b32_e64 v195, 0, v195, s[50:51]
	v_add_u32_e32 v88, 19, v84
	v_cmp_gt_u32_e64 s[50:51], s98, v88
	v_cndmask_b32_e64 v196, 0, v196, s[30:31]
	v_add_u32_e32 v85, 24, v84
	v_cmp_gt_u32_e64 s[30:31], s98, v85
	v_cndmask_b32_e64 v197, 0, v197, s[36:37]
	v_add_u32_e32 v86, 25, v84
	v_cmp_gt_u32_e64 s[36:37], s98, v86
	v_cndmask_b32_e64 v198, 0, v198, s[78:79]
	v_add_u32_e32 v87, 26, v84
	v_cmp_gt_u32_e64 s[78:79], s98, v87
	v_cndmask_b32_e64 v199, 0, v199, s[50:51]
	v_add_u32_e32 v88, 27, v84
	v_cmp_gt_u32_e64 s[50:51], s98, v88
	v_nop
	v_cndmask_b32_e64 v200, 0, v200, s[30:31]
	v_cndmask_b32_e64 v201, 0, v201, s[36:37]
	v_cndmask_b32_e64 v202, 0, v202, s[78:79]
	v_cndmask_b32_e64 v203, 0, v203, s[50:51]
	v_cvt_pk_bf16_f32 v64, v188, v189
	v_cvt_pk_bf16_f32 v65, v190, v191
	v_cvt_pk_bf16_f32 v66, v192, v193
	v_cvt_pk_bf16_f32 v67, v194, v195
	v_cvt_pk_bf16_f32 v68, v196, v197
	v_cvt_pk_bf16_f32 v69, v198, v199
	v_cvt_pk_bf16_f32 v70, v200, v201
	v_cvt_pk_bf16_f32 v71, v202, v203
	v_pk_add_f32 v[232:233], v[232:233], v[188:189]
	v_pk_add_f32 v[232:233], v[232:233], v[190:191]
	v_pk_add_f32 v[232:233], v[232:233], v[192:193]
	v_pk_add_f32 v[232:233], v[232:233], v[194:195]
	v_pk_add_f32 v[232:233], v[232:233], v[196:197]
	v_pk_add_f32 v[232:233], v[232:233], v[198:199]
	v_pk_add_f32 v[232:233], v[232:233], v[200:201]
	v_pk_add_f32 v[232:233], v[232:233], v[202:203]
	v_add_u32_e32 v115, 952, v115
	ds_read2_b32 v[188:189], v115 offset0:0 offset1:1
	ds_read2_b32 v[190:191], v115 offset0:2 offset1:3
	ds_read2_b32 v[192:193], v115 offset0:8 offset1:9
	ds_read2_b32 v[194:195], v115 offset0:10 offset1:11
	ds_read2_b32 v[196:197], v115 offset0:17 offset1:18
	ds_read2_b32 v[198:199], v115 offset0:19 offset1:20
	ds_read2_b32 v[200:201], v115 offset0:25 offset1:26
	ds_read2_b32 v[202:203], v115 offset0:27 offset1:28
	s_add_i32 s90, s76, 192
	v_add_u32_e32 v80, s90, v235
	v_add_u32_e32 v83, s90, v236
	v_add_u32_e32 v99, s90, v237
	v_add_u32_e32 v253, s90, v238
	v_add_u32_e32 v254, s90, v100
	v_add_u32_e32 v255, s90, v149
	v_med3_i32 v80, v80, 0, s99
	v_med3_i32 v83, v83, 0, s99
	v_med3_i32 v99, v99, 0, s99
	v_med3_i32 v253, v253, 0, s99
	v_med3_i32 v254, v254, 0, s99
	v_med3_i32 v255, v255, 0, s99
	v_mad_u32_u24 v80, v80, s100, v252
	v_mad_u32_u24 v83, v83, s100, v252
	v_mad_u32_u24 v99, v99, s100, v252
	v_mad_u32_u24 v253, v253, s100, v252
	v_mad_u32_u24 v254, v254, s100, v153
	v_mad_u32_u24 v255, v255, s100, v153
	global_load_dwordx4 v[116:119], v80, s[82:83]
	global_load_dwordx4 v[120:123], v83, s[82:83]
	global_load_dwordx4 v[124:127], v99, s[82:83]
	global_load_dwordx4 v[128:131], v253, s[82:83]
	global_load_dwordx4 v[132:135], v254, s[82:83] offset:768
	global_load_dwordx4 v[136:139], v255, s[82:83] offset:768
	global_load_dwordx4 v[140:143], v254, s[82:83] offset:832
	global_load_dwordx4 v[144:147], v255, s[82:83] offset:832
	ds_read_b64_tr_b16 v[72:73], v231
	ds_read_b64_tr_b16 v[74:75], v231 offset:512
	ds_read_b64_tr_b16 v[76:77], v231 offset:2048
	ds_read_b64_tr_b16 v[78:79], v231 offset:2560
	ds_read_b64_tr_b16 v[220:221], v231 offset:1024
	ds_read_b64_tr_b16 v[222:223], v231 offset:1536
	ds_read_b64_tr_b16 v[224:225], v231 offset:3072
	ds_read_b64_tr_b16 v[226:227], v231 offset:3584
	v_exp_f32_e32 v32, v32
	v_exp_f32_e32 v33, v33
	v_exp_f32_e32 v34, v34
	v_exp_f32_e32 v35, v35
	s_waitcnt vmcnt(8)
	ds_write_b128 v247, v[156:159]
	ds_write_b128 v247, v[160:163] offset:1024
	ds_write_b128 v247, v[164:167] offset:2048
	ds_write_b128 v247, v[168:171] offset:3072
	ds_read_b128 v[156:159], v248
	ds_read_b128 v[160:163], v249
	ds_read_b128 v[164:167], v250
	ds_read_b128 v[168:171], v251
	ds_write_b128 v112, v[172:175]
	ds_write_b128 v112, v[176:179] offset:1024
	ds_write_b128 v112, v[180:183] offset:2048
	ds_write_b128 v112, v[184:187] offset:3072
	v_mfma_f32_32x32x16_bf16 v[0:15], v[64:67], v[204:207], v[0:15]
	v_mfma_f32_32x32x16_bf16 v[16:31], v[64:67], v[208:211], v[16:31]
	v_mfma_f32_32x32x16_bf16 v[0:15], v[68:71], v[212:215], v[0:15]
	v_mfma_f32_32x32x16_bf16 v[16:31], v[68:71], v[216:219], v[16:31]
	v_exp_f32_e32 v36, v36
	v_exp_f32_e32 v37, v37
	v_exp_f32_e32 v38, v38
	v_exp_f32_e32 v39, v39
	s_waitcnt lgkmcnt(4)
	v_mfma_f32_32x32x16_bf16 v[188:203], v[156:159], v[48:51], v[188:203]
	v_exp_f32_e32 v40, v40
	v_exp_f32_e32 v41, v41
	v_mfma_f32_32x32x16_bf16 v[188:203], v[160:163], v[52:55], v[188:203]
	v_exp_f32_e32 v42, v42
	v_exp_f32_e32 v43, v43
	v_mfma_f32_32x32x16_bf16 v[188:203], v[164:167], v[56:59], v[188:203]
	v_exp_f32_e32 v44, v44
	v_exp_f32_e32 v45, v45
	v_mfma_f32_32x32x16_bf16 v[188:203], v[168:171], v[60:63], v[188:203]
	v_exp_f32_e32 v46, v46
	v_exp_f32_e32 v47, v47
	s_add_i32 s90, s76, 128
	v_add_u32_e32 v84, s90, v107
	v_add_u32_e32 v85, 0, v84
	v_add_u32_e32 v86, 1, v84
	v_add_u32_e32 v87, 2, v84
	v_add_u32_e32 v88, 3, v84
	v_cmp_gt_u32_e64 s[30:31], s98, v85
	v_cmp_gt_u32_e64 s[36:37], s98, v86
	v_cmp_gt_u32_e64 s[78:79], s98, v87
	v_cmp_gt_u32_e64 s[50:51], s98, v88
	v_cndmask_b32_e64 v32, 0, v32, s[30:31]
	v_add_u32_e32 v85, 8, v84
	v_cmp_gt_u32_e64 s[30:31], s98, v85
	v_cndmask_b32_e64 v33, 0, v33, s[36:37]
	v_add_u32_e32 v86, 9, v84
	v_cmp_gt_u32_e64 s[36:37], s98, v86
	v_cndmask_b32_e64 v34, 0, v34, s[78:79]
	v_add_u32_e32 v87, 10, v84
	v_cmp_gt_u32_e64 s[78:79], s98, v87
	v_cndmask_b32_e64 v35, 0, v35, s[50:51]
	v_add_u32_e32 v88, 11, v84
	v_cmp_gt_u32_e64 s[50:51], s98, v88
	v_cndmask_b32_e64 v36, 0, v36, s[30:31]
	v_add_u32_e32 v85, 16, v84
	v_cmp_gt_u32_e64 s[30:31], s98, v85
	v_cndmask_b32_e64 v37, 0, v37, s[36:37]
	v_add_u32_e32 v86, 17, v84
	v_cmp_gt_u32_e64 s[36:37], s98, v86
	v_cndmask_b32_e64 v38, 0, v38, s[78:79]
	v_add_u32_e32 v87, 18, v84
	v_cmp_gt_u32_e64 s[78:79], s98, v87
	v_cndmask_b32_e64 v39, 0, v39, s[50:51]
	v_add_u32_e32 v88, 19, v84
	v_cmp_gt_u32_e64 s[50:51], s98, v88
	v_cndmask_b32_e64 v40, 0, v40, s[30:31]
	v_add_u32_e32 v85, 24, v84
	v_cmp_gt_u32_e64 s[30:31], s98, v85
	v_cndmask_b32_e64 v41, 0, v41, s[36:37]
	v_add_u32_e32 v86, 25, v84
	v_cmp_gt_u32_e64 s[36:37], s98, v86
	v_cndmask_b32_e64 v42, 0, v42, s[78:79]
	v_add_u32_e32 v87, 26, v84
	v_cmp_gt_u32_e64 s[78:79], s98, v87
	v_cndmask_b32_e64 v43, 0, v43, s[50:51]
	v_add_u32_e32 v88, 27, v84
	v_cmp_gt_u32_e64 s[50:51], s98, v88
	v_nop
	v_cndmask_b32_e64 v44, 0, v44, s[30:31]
	v_cndmask_b32_e64 v45, 0, v45, s[36:37]
	v_cndmask_b32_e64 v46, 0, v46, s[78:79]
	v_cndmask_b32_e64 v47, 0, v47, s[50:51]
	v_cvt_pk_bf16_f32 v64, v32, v33
	v_cvt_pk_bf16_f32 v65, v34, v35
	v_cvt_pk_bf16_f32 v66, v36, v37
	v_cvt_pk_bf16_f32 v67, v38, v39
	v_cvt_pk_bf16_f32 v68, v40, v41
	v_cvt_pk_bf16_f32 v69, v42, v43
	v_cvt_pk_bf16_f32 v70, v44, v45
	v_cvt_pk_bf16_f32 v71, v46, v47
	v_pk_add_f32 v[232:233], v[232:233], v[32:33]
	v_pk_add_f32 v[232:233], v[232:233], v[34:35]
	v_pk_add_f32 v[232:233], v[232:233], v[36:37]
	v_pk_add_f32 v[232:233], v[232:233], v[38:39]
	v_pk_add_f32 v[232:233], v[232:233], v[40:41]
	v_pk_add_f32 v[232:233], v[232:233], v[42:43]
	v_pk_add_f32 v[232:233], v[232:233], v[44:45]
	v_pk_add_f32 v[232:233], v[232:233], v[46:47]
	ds_read2_b32 v[32:33], v115 offset0:34 offset1:35
	ds_read2_b32 v[34:35], v115 offset0:36 offset1:37
	ds_read2_b32 v[36:37], v115 offset0:42 offset1:43
	ds_read2_b32 v[38:39], v115 offset0:44 offset1:45
	ds_read2_b32 v[40:41], v115 offset0:51 offset1:52
	ds_read2_b32 v[42:43], v115 offset0:53 offset1:54
	ds_read2_b32 v[44:45], v115 offset0:59 offset1:60
	ds_read2_b32 v[46:47], v115 offset0:61 offset1:62
	s_add_i32 s90, s76, 224
	v_add_u32_e32 v80, s90, v235
	v_add_u32_e32 v83, s90, v236
	v_add_u32_e32 v99, s90, v237
	v_add_u32_e32 v253, s90, v238
	v_add_u32_e32 v254, s90, v100
	v_add_u32_e32 v255, s90, v149
	v_med3_i32 v80, v80, 0, s99
	v_med3_i32 v83, v83, 0, s99
	v_med3_i32 v99, v99, 0, s99
	v_med3_i32 v253, v253, 0, s99
	v_med3_i32 v254, v254, 0, s99
	v_med3_i32 v255, v255, 0, s99
	v_mad_u32_u24 v80, v80, s100, v252
	v_mad_u32_u24 v83, v83, s100, v252
	v_mad_u32_u24 v99, v99, s100, v252
	v_mad_u32_u24 v253, v253, s100, v252
	v_mad_u32_u24 v254, v254, s100, v153
	v_mad_u32_u24 v255, v255, s100, v153
	global_load_dwordx4 v[156:159], v80, s[82:83]
	global_load_dwordx4 v[160:163], v83, s[82:83]
	global_load_dwordx4 v[164:167], v99, s[82:83]
	global_load_dwordx4 v[168:171], v253, s[82:83]
	global_load_dwordx4 v[172:175], v254, s[82:83] offset:768
	global_load_dwordx4 v[176:179], v255, s[82:83] offset:768
	global_load_dwordx4 v[180:183], v254, s[82:83] offset:832
	global_load_dwordx4 v[184:187], v255, s[82:83] offset:832
	ds_read_b64_tr_b16 v[204:205], v231
	ds_read_b64_tr_b16 v[206:207], v231 offset:512
	ds_read_b64_tr_b16 v[208:209], v231 offset:2048
	ds_read_b64_tr_b16 v[210:211], v231 offset:2560
	ds_read_b64_tr_b16 v[212:213], v231 offset:1024
	ds_read_b64_tr_b16 v[214:215], v231 offset:1536
	ds_read_b64_tr_b16 v[216:217], v231 offset:3072
	ds_read_b64_tr_b16 v[218:219], v231 offset:3584
	v_exp_f32_e32 v188, v188
	v_exp_f32_e32 v189, v189
	v_exp_f32_e32 v190, v190
	v_exp_f32_e32 v191, v191
	s_waitcnt vmcnt(8)
	ds_write_b128 v247, v[116:119]
	ds_write_b128 v247, v[120:123] offset:1024
	ds_write_b128 v247, v[124:127] offset:2048
	ds_write_b128 v247, v[128:131] offset:3072
	ds_read_b128 v[116:119], v248
	ds_read_b128 v[120:123], v249
	ds_read_b128 v[124:127], v250
	ds_read_b128 v[128:131], v251
	ds_write_b128 v112, v[132:135]
	ds_write_b128 v112, v[136:139] offset:1024
	ds_write_b128 v112, v[140:143] offset:2048
	ds_write_b128 v112, v[144:147] offset:3072
	v_mfma_f32_32x32x16_bf16 v[0:15], v[64:67], v[72:75], v[0:15]
	v_mfma_f32_32x32x16_bf16 v[16:31], v[64:67], v[76:79], v[16:31]
	v_mfma_f32_32x32x16_bf16 v[0:15], v[68:71], v[220:223], v[0:15]
	v_mfma_f32_32x32x16_bf16 v[16:31], v[68:71], v[224:227], v[16:31]
	v_exp_f32_e32 v192, v192
	v_exp_f32_e32 v193, v193
	v_exp_f32_e32 v194, v194
	v_exp_f32_e32 v195, v195
	s_waitcnt lgkmcnt(4)
	v_mfma_f32_32x32x16_bf16 v[32:47], v[116:119], v[48:51], v[32:47]
	v_exp_f32_e32 v196, v196
	v_exp_f32_e32 v197, v197
	v_mfma_f32_32x32x16_bf16 v[32:47], v[120:123], v[52:55], v[32:47]
	v_exp_f32_e32 v198, v198
	v_exp_f32_e32 v199, v199
	v_mfma_f32_32x32x16_bf16 v[32:47], v[124:127], v[56:59], v[32:47]
	v_exp_f32_e32 v200, v200
	v_exp_f32_e32 v201, v201
	v_mfma_f32_32x32x16_bf16 v[32:47], v[128:131], v[60:63], v[32:47]
	v_exp_f32_e32 v202, v202
	v_exp_f32_e32 v203, v203
	s_add_i32 s90, s76, 160
	v_add_u32_e32 v84, s90, v107
	v_add_u32_e32 v85, 0, v84
	v_add_u32_e32 v86, 1, v84
	v_add_u32_e32 v87, 2, v84
	v_add_u32_e32 v88, 3, v84
	v_cmp_gt_u32_e64 s[30:31], s98, v85
	v_cmp_gt_u32_e64 s[36:37], s98, v86
	v_cmp_gt_u32_e64 s[78:79], s98, v87
	v_cmp_gt_u32_e64 s[50:51], s98, v88
	v_cndmask_b32_e64 v188, 0, v188, s[30:31]
	v_add_u32_e32 v85, 8, v84
	v_cmp_gt_u32_e64 s[30:31], s98, v85
	v_cndmask_b32_e64 v189, 0, v189, s[36:37]
	v_add_u32_e32 v86, 9, v84
	v_cmp_gt_u32_e64 s[36:37], s98, v86
	v_cndmask_b32_e64 v190, 0, v190, s[78:79]
	v_add_u32_e32 v87, 10, v84
	v_cmp_gt_u32_e64 s[78:79], s98, v87
	v_cndmask_b32_e64 v191, 0, v191, s[50:51]
	v_add_u32_e32 v88, 11, v84
	v_cmp_gt_u32_e64 s[50:51], s98, v88
	v_cndmask_b32_e64 v192, 0, v192, s[30:31]
	v_add_u32_e32 v85, 16, v84
	v_cmp_gt_u32_e64 s[30:31], s98, v85
	v_cndmask_b32_e64 v193, 0, v193, s[36:37]
	v_add_u32_e32 v86, 17, v84
	v_cmp_gt_u32_e64 s[36:37], s98, v86
	v_cndmask_b32_e64 v194, 0, v194, s[78:79]
	v_add_u32_e32 v87, 18, v84
	v_cmp_gt_u32_e64 s[78:79], s98, v87
	v_cndmask_b32_e64 v195, 0, v195, s[50:51]
	v_add_u32_e32 v88, 19, v84
	v_cmp_gt_u32_e64 s[50:51], s98, v88
	v_cndmask_b32_e64 v196, 0, v196, s[30:31]
	v_add_u32_e32 v85, 24, v84
	v_cmp_gt_u32_e64 s[30:31], s98, v85
	v_cndmask_b32_e64 v197, 0, v197, s[36:37]
	v_add_u32_e32 v86, 25, v84
	v_cmp_gt_u32_e64 s[36:37], s98, v86
	v_cndmask_b32_e64 v198, 0, v198, s[78:79]
	v_add_u32_e32 v87, 26, v84
	v_cmp_gt_u32_e64 s[78:79], s98, v87
	v_cndmask_b32_e64 v199, 0, v199, s[50:51]
	v_add_u32_e32 v88, 27, v84
	v_cmp_gt_u32_e64 s[50:51], s98, v88
	v_nop
	v_cndmask_b32_e64 v200, 0, v200, s[30:31]
	v_cndmask_b32_e64 v201, 0, v201, s[36:37]
	v_cndmask_b32_e64 v202, 0, v202, s[78:79]
	v_cndmask_b32_e64 v203, 0, v203, s[50:51]
	v_cvt_pk_bf16_f32 v64, v188, v189
	v_cvt_pk_bf16_f32 v65, v190, v191
	v_cvt_pk_bf16_f32 v66, v192, v193
	v_cvt_pk_bf16_f32 v67, v194, v195
	v_cvt_pk_bf16_f32 v68, v196, v197
	v_cvt_pk_bf16_f32 v69, v198, v199
	v_cvt_pk_bf16_f32 v70, v200, v201
	v_cvt_pk_bf16_f32 v71, v202, v203
	v_pk_add_f32 v[232:233], v[232:233], v[188:189]
	v_pk_add_f32 v[232:233], v[232:233], v[190:191]
	v_pk_add_f32 v[232:233], v[232:233], v[192:193]
	v_pk_add_f32 v[232:233], v[232:233], v[194:195]
	v_pk_add_f32 v[232:233], v[232:233], v[196:197]
	v_pk_add_f32 v[232:233], v[232:233], v[198:199]
	v_pk_add_f32 v[232:233], v[232:233], v[200:201]
	v_pk_add_f32 v[232:233], v[232:233], v[202:203]
	ds_read2_b32 v[188:189], v115 offset0:68 offset1:69
	ds_read2_b32 v[190:191], v115 offset0:70 offset1:71
	ds_read2_b32 v[192:193], v115 offset0:76 offset1:77
	ds_read2_b32 v[194:195], v115 offset0:78 offset1:79
	ds_read2_b32 v[196:197], v115 offset0:85 offset1:86
	ds_read2_b32 v[198:199], v115 offset0:87 offset1:88
	ds_read2_b32 v[200:201], v115 offset0:93 offset1:94
	ds_read2_b32 v[202:203], v115 offset0:95 offset1:96
	s_add_i32 s90, s76, 256
	v_add_u32_e32 v80, s90, v235
	v_add_u32_e32 v83, s90, v236
	v_add_u32_e32 v99, s90, v237
	v_add_u32_e32 v253, s90, v238
	v_add_u32_e32 v254, s90, v100
	v_add_u32_e32 v255, s90, v149
	v_med3_i32 v80, v80, 0, s99
	v_med3_i32 v83, v83, 0, s99
	v_med3_i32 v99, v99, 0, s99
	v_med3_i32 v253, v253, 0, s99
	v_med3_i32 v254, v254, 0, s99
	v_med3_i32 v255, v255, 0, s99
	v_mad_u32_u24 v80, v80, s100, v252
	v_mad_u32_u24 v83, v83, s100, v252
	v_mad_u32_u24 v99, v99, s100, v252
	v_mad_u32_u24 v253, v253, s100, v252
	v_mad_u32_u24 v254, v254, s100, v153
	v_mad_u32_u24 v255, v255, s100, v153
	global_load_dwordx4 v[116:119], v80, s[82:83]
	global_load_dwordx4 v[120:123], v83, s[82:83]
	global_load_dwordx4 v[124:127], v99, s[82:83]
	global_load_dwordx4 v[128:131], v253, s[82:83]
	global_load_dwordx4 v[132:135], v254, s[82:83] offset:768
	global_load_dwordx4 v[136:139], v255, s[82:83] offset:768
	global_load_dwordx4 v[140:143], v254, s[82:83] offset:832
	global_load_dwordx4 v[144:147], v255, s[82:83] offset:832
	ds_read_b64_tr_b16 v[72:73], v231
	ds_read_b64_tr_b16 v[74:75], v231 offset:512
	ds_read_b64_tr_b16 v[76:77], v231 offset:2048
	ds_read_b64_tr_b16 v[78:79], v231 offset:2560
	ds_read_b64_tr_b16 v[220:221], v231 offset:1024
	ds_read_b64_tr_b16 v[222:223], v231 offset:1536
	ds_read_b64_tr_b16 v[224:225], v231 offset:3072
	ds_read_b64_tr_b16 v[226:227], v231 offset:3584
	v_exp_f32_e32 v32, v32
	v_exp_f32_e32 v33, v33
	v_exp_f32_e32 v34, v34
	v_exp_f32_e32 v35, v35
	s_waitcnt vmcnt(8)
	ds_write_b128 v247, v[156:159]
	ds_write_b128 v247, v[160:163] offset:1024
	ds_write_b128 v247, v[164:167] offset:2048
	ds_write_b128 v247, v[168:171] offset:3072
	ds_read_b128 v[156:159], v248
	ds_read_b128 v[160:163], v249
	ds_read_b128 v[164:167], v250
	ds_read_b128 v[168:171], v251
	ds_write_b128 v112, v[172:175]
	ds_write_b128 v112, v[176:179] offset:1024
	ds_write_b128 v112, v[180:183] offset:2048
	ds_write_b128 v112, v[184:187] offset:3072
	v_mfma_f32_32x32x16_bf16 v[0:15], v[64:67], v[204:207], v[0:15]
	v_mfma_f32_32x32x16_bf16 v[16:31], v[64:67], v[208:211], v[16:31]
	v_mfma_f32_32x32x16_bf16 v[0:15], v[68:71], v[212:215], v[0:15]
	v_mfma_f32_32x32x16_bf16 v[16:31], v[68:71], v[216:219], v[16:31]
	v_exp_f32_e32 v36, v36
	v_exp_f32_e32 v37, v37
	v_exp_f32_e32 v38, v38
	v_exp_f32_e32 v39, v39
	s_waitcnt lgkmcnt(4)
	v_mfma_f32_32x32x16_bf16 v[188:203], v[156:159], v[48:51], v[188:203]
	v_exp_f32_e32 v40, v40
	v_exp_f32_e32 v41, v41
	v_mfma_f32_32x32x16_bf16 v[188:203], v[160:163], v[52:55], v[188:203]
	v_exp_f32_e32 v42, v42
	v_exp_f32_e32 v43, v43
	v_mfma_f32_32x32x16_bf16 v[188:203], v[164:167], v[56:59], v[188:203]
	v_exp_f32_e32 v44, v44
	v_exp_f32_e32 v45, v45
	v_mfma_f32_32x32x16_bf16 v[188:203], v[168:171], v[60:63], v[188:203]
	v_exp_f32_e32 v46, v46
	v_exp_f32_e32 v47, v47
	s_add_i32 s90, s76, 192
	v_add_u32_e32 v84, s90, v107
	v_add_u32_e32 v85, 0, v84
	v_add_u32_e32 v86, 1, v84
	v_add_u32_e32 v87, 2, v84
	v_add_u32_e32 v88, 3, v84
	v_cmp_gt_u32_e64 s[30:31], s98, v85
	v_cmp_gt_u32_e64 s[36:37], s98, v86
	v_cmp_gt_u32_e64 s[78:79], s98, v87
	v_cmp_gt_u32_e64 s[50:51], s98, v88
	v_cndmask_b32_e64 v32, 0, v32, s[30:31]
	v_add_u32_e32 v85, 8, v84
	v_cmp_gt_u32_e64 s[30:31], s98, v85
	v_cndmask_b32_e64 v33, 0, v33, s[36:37]
	v_add_u32_e32 v86, 9, v84
	v_cmp_gt_u32_e64 s[36:37], s98, v86
	v_cndmask_b32_e64 v34, 0, v34, s[78:79]
	v_add_u32_e32 v87, 10, v84
	v_cmp_gt_u32_e64 s[78:79], s98, v87
	v_cndmask_b32_e64 v35, 0, v35, s[50:51]
	v_add_u32_e32 v88, 11, v84
	v_cmp_gt_u32_e64 s[50:51], s98, v88
	v_cndmask_b32_e64 v36, 0, v36, s[30:31]
	v_add_u32_e32 v85, 16, v84
	v_cmp_gt_u32_e64 s[30:31], s98, v85
	v_cndmask_b32_e64 v37, 0, v37, s[36:37]
	v_add_u32_e32 v86, 17, v84
	v_cmp_gt_u32_e64 s[36:37], s98, v86
	v_cndmask_b32_e64 v38, 0, v38, s[78:79]
	v_add_u32_e32 v87, 18, v84
	v_cmp_gt_u32_e64 s[78:79], s98, v87
	v_cndmask_b32_e64 v39, 0, v39, s[50:51]
	v_add_u32_e32 v88, 19, v84
	v_cmp_gt_u32_e64 s[50:51], s98, v88
	v_cndmask_b32_e64 v40, 0, v40, s[30:31]
	v_add_u32_e32 v85, 24, v84
	v_cmp_gt_u32_e64 s[30:31], s98, v85
	v_cndmask_b32_e64 v41, 0, v41, s[36:37]
	v_add_u32_e32 v86, 25, v84
	v_cmp_gt_u32_e64 s[36:37], s98, v86
	v_cndmask_b32_e64 v42, 0, v42, s[78:79]
	v_add_u32_e32 v87, 26, v84
	v_cmp_gt_u32_e64 s[78:79], s98, v87
	v_cndmask_b32_e64 v43, 0, v43, s[50:51]
	v_add_u32_e32 v88, 27, v84
	v_cmp_gt_u32_e64 s[50:51], s98, v88
	v_nop
	v_cndmask_b32_e64 v44, 0, v44, s[30:31]
	v_cndmask_b32_e64 v45, 0, v45, s[36:37]
	v_cndmask_b32_e64 v46, 0, v46, s[78:79]
	v_cndmask_b32_e64 v47, 0, v47, s[50:51]
	v_cvt_pk_bf16_f32 v64, v32, v33
	v_cvt_pk_bf16_f32 v65, v34, v35
	v_cvt_pk_bf16_f32 v66, v36, v37
	v_cvt_pk_bf16_f32 v67, v38, v39
	v_cvt_pk_bf16_f32 v68, v40, v41
	v_cvt_pk_bf16_f32 v69, v42, v43
	v_cvt_pk_bf16_f32 v70, v44, v45
	v_cvt_pk_bf16_f32 v71, v46, v47
	v_pk_add_f32 v[232:233], v[232:233], v[32:33]
	v_pk_add_f32 v[232:233], v[232:233], v[34:35]
	v_pk_add_f32 v[232:233], v[232:233], v[36:37]
	v_pk_add_f32 v[232:233], v[232:233], v[38:39]
	v_pk_add_f32 v[232:233], v[232:233], v[40:41]
	v_pk_add_f32 v[232:233], v[232:233], v[42:43]
	v_pk_add_f32 v[232:233], v[232:233], v[44:45]
	v_pk_add_f32 v[232:233], v[232:233], v[46:47]
	ds_read2_b32 v[32:33], v115 offset0:102 offset1:103
	ds_read2_b32 v[34:35], v115 offset0:104 offset1:105
	ds_read2_b32 v[36:37], v115 offset0:110 offset1:111
	ds_read2_b32 v[38:39], v115 offset0:112 offset1:113
	ds_read2_b32 v[40:41], v115 offset0:119 offset1:120
	ds_read2_b32 v[42:43], v115 offset0:121 offset1:122
	ds_read2_b32 v[44:45], v115 offset0:127 offset1:128
	ds_read2_b32 v[46:47], v115 offset0:129 offset1:130
	s_add_i32 s90, s76, 288
	v_add_u32_e32 v80, s90, v235
	v_add_u32_e32 v83, s90, v236
	v_add_u32_e32 v99, s90, v237
	v_add_u32_e32 v253, s90, v238
	v_add_u32_e32 v254, s90, v100
	v_add_u32_e32 v255, s90, v149
	v_med3_i32 v80, v80, 0, s99
	v_med3_i32 v83, v83, 0, s99
	v_med3_i32 v99, v99, 0, s99
	v_med3_i32 v253, v253, 0, s99
	v_med3_i32 v254, v254, 0, s99
	v_med3_i32 v255, v255, 0, s99
	v_mad_u32_u24 v80, v80, s100, v252
	v_mad_u32_u24 v83, v83, s100, v252
	v_mad_u32_u24 v99, v99, s100, v252
	v_mad_u32_u24 v253, v253, s100, v252
	v_mad_u32_u24 v254, v254, s100, v153
	v_mad_u32_u24 v255, v255, s100, v153
	global_load_dwordx4 v[156:159], v80, s[82:83]
	global_load_dwordx4 v[160:163], v83, s[82:83]
	global_load_dwordx4 v[164:167], v99, s[82:83]
	global_load_dwordx4 v[168:171], v253, s[82:83]
	global_load_dwordx4 v[172:175], v254, s[82:83] offset:768
	global_load_dwordx4 v[176:179], v255, s[82:83] offset:768
	global_load_dwordx4 v[180:183], v254, s[82:83] offset:832
	global_load_dwordx4 v[184:187], v255, s[82:83] offset:832
	ds_read_b64_tr_b16 v[204:205], v231
	ds_read_b64_tr_b16 v[206:207], v231 offset:512
	ds_read_b64_tr_b16 v[208:209], v231 offset:2048
	ds_read_b64_tr_b16 v[210:211], v231 offset:2560
	ds_read_b64_tr_b16 v[212:213], v231 offset:1024
	ds_read_b64_tr_b16 v[214:215], v231 offset:1536
	ds_read_b64_tr_b16 v[216:217], v231 offset:3072
	ds_read_b64_tr_b16 v[218:219], v231 offset:3584
	v_exp_f32_e32 v188, v188
	v_exp_f32_e32 v189, v189
	v_exp_f32_e32 v190, v190
	v_exp_f32_e32 v191, v191
	s_waitcnt vmcnt(8)
	ds_write_b128 v247, v[116:119]
	ds_write_b128 v247, v[120:123] offset:1024
	ds_write_b128 v247, v[124:127] offset:2048
	ds_write_b128 v247, v[128:131] offset:3072
	ds_read_b128 v[116:119], v248
	ds_read_b128 v[120:123], v249
	ds_read_b128 v[124:127], v250
	ds_read_b128 v[128:131], v251
	ds_write_b128 v112, v[132:135]
	ds_write_b128 v112, v[136:139] offset:1024
	ds_write_b128 v112, v[140:143] offset:2048
	ds_write_b128 v112, v[144:147] offset:3072
	v_mfma_f32_32x32x16_bf16 v[0:15], v[64:67], v[72:75], v[0:15]
	v_mfma_f32_32x32x16_bf16 v[16:31], v[64:67], v[76:79], v[16:31]
	v_mfma_f32_32x32x16_bf16 v[0:15], v[68:71], v[220:223], v[0:15]
	v_mfma_f32_32x32x16_bf16 v[16:31], v[68:71], v[224:227], v[16:31]
	v_exp_f32_e32 v192, v192
	v_exp_f32_e32 v193, v193
	v_exp_f32_e32 v194, v194
	v_exp_f32_e32 v195, v195
	s_waitcnt lgkmcnt(4)
	v_mfma_f32_32x32x16_bf16 v[32:47], v[116:119], v[48:51], v[32:47]
	v_exp_f32_e32 v196, v196
	v_exp_f32_e32 v197, v197
	v_mfma_f32_32x32x16_bf16 v[32:47], v[120:123], v[52:55], v[32:47]
	v_exp_f32_e32 v198, v198
	v_exp_f32_e32 v199, v199
	v_mfma_f32_32x32x16_bf16 v[32:47], v[124:127], v[56:59], v[32:47]
	v_exp_f32_e32 v200, v200
	v_exp_f32_e32 v201, v201
	v_mfma_f32_32x32x16_bf16 v[32:47], v[128:131], v[60:63], v[32:47]
	v_exp_f32_e32 v202, v202
	v_exp_f32_e32 v203, v203
	s_add_i32 s90, s76, 224
	v_add_u32_e32 v84, s90, v107
	v_add_u32_e32 v85, 0, v84
	v_add_u32_e32 v86, 1, v84
	v_add_u32_e32 v87, 2, v84
	v_add_u32_e32 v88, 3, v84
	v_cmp_gt_u32_e64 s[30:31], s98, v85
	v_cmp_gt_u32_e64 s[36:37], s98, v86
	v_cmp_gt_u32_e64 s[78:79], s98, v87
	v_cmp_gt_u32_e64 s[50:51], s98, v88
	v_cndmask_b32_e64 v188, 0, v188, s[30:31]
	v_add_u32_e32 v85, 8, v84
	v_cmp_gt_u32_e64 s[30:31], s98, v85
	v_cndmask_b32_e64 v189, 0, v189, s[36:37]
	v_add_u32_e32 v86, 9, v84
	v_cmp_gt_u32_e64 s[36:37], s98, v86
	v_cndmask_b32_e64 v190, 0, v190, s[78:79]
	v_add_u32_e32 v87, 10, v84
	v_cmp_gt_u32_e64 s[78:79], s98, v87
	v_cndmask_b32_e64 v191, 0, v191, s[50:51]
	v_add_u32_e32 v88, 11, v84
	v_cmp_gt_u32_e64 s[50:51], s98, v88
	v_cndmask_b32_e64 v192, 0, v192, s[30:31]
	v_add_u32_e32 v85, 16, v84
	v_cmp_gt_u32_e64 s[30:31], s98, v85
	v_cndmask_b32_e64 v193, 0, v193, s[36:37]
	v_add_u32_e32 v86, 17, v84
	v_cmp_gt_u32_e64 s[36:37], s98, v86
	v_cndmask_b32_e64 v194, 0, v194, s[78:79]
	v_add_u32_e32 v87, 18, v84
	v_cmp_gt_u32_e64 s[78:79], s98, v87
	v_cndmask_b32_e64 v195, 0, v195, s[50:51]
	v_add_u32_e32 v88, 19, v84
	v_cmp_gt_u32_e64 s[50:51], s98, v88
	v_cndmask_b32_e64 v196, 0, v196, s[30:31]
	v_add_u32_e32 v85, 24, v84
	v_cmp_gt_u32_e64 s[30:31], s98, v85
	v_cndmask_b32_e64 v197, 0, v197, s[36:37]
	v_add_u32_e32 v86, 25, v84
	v_cmp_gt_u32_e64 s[36:37], s98, v86
	v_cndmask_b32_e64 v198, 0, v198, s[78:79]
	v_add_u32_e32 v87, 26, v84
	v_cmp_gt_u32_e64 s[78:79], s98, v87
	v_cndmask_b32_e64 v199, 0, v199, s[50:51]
	v_add_u32_e32 v88, 27, v84
	v_cmp_gt_u32_e64 s[50:51], s98, v88
	v_nop
	v_cndmask_b32_e64 v200, 0, v200, s[30:31]
	v_cndmask_b32_e64 v201, 0, v201, s[36:37]
	v_cndmask_b32_e64 v202, 0, v202, s[78:79]
	v_cndmask_b32_e64 v203, 0, v203, s[50:51]
	v_cvt_pk_bf16_f32 v64, v188, v189
	v_cvt_pk_bf16_f32 v65, v190, v191
	v_cvt_pk_bf16_f32 v66, v192, v193
	v_cvt_pk_bf16_f32 v67, v194, v195
	v_cvt_pk_bf16_f32 v68, v196, v197
	v_cvt_pk_bf16_f32 v69, v198, v199
	v_cvt_pk_bf16_f32 v70, v200, v201
	v_cvt_pk_bf16_f32 v71, v202, v203
	v_pk_add_f32 v[232:233], v[232:233], v[188:189]
	v_pk_add_f32 v[232:233], v[232:233], v[190:191]
	v_pk_add_f32 v[232:233], v[232:233], v[192:193]
	v_pk_add_f32 v[232:233], v[232:233], v[194:195]
	v_pk_add_f32 v[232:233], v[232:233], v[196:197]
	v_pk_add_f32 v[232:233], v[232:233], v[198:199]
	v_pk_add_f32 v[232:233], v[232:233], v[200:201]
	v_pk_add_f32 v[232:233], v[232:233], v[202:203]
	ds_read2_b32 v[188:189], v115 offset0:136 offset1:137
	ds_read2_b32 v[190:191], v115 offset0:138 offset1:139
	ds_read2_b32 v[192:193], v115 offset0:144 offset1:145
	ds_read2_b32 v[194:195], v115 offset0:146 offset1:147
	ds_read2_b32 v[196:197], v115 offset0:153 offset1:154
	ds_read2_b32 v[198:199], v115 offset0:155 offset1:156
	ds_read2_b32 v[200:201], v115 offset0:161 offset1:162
	ds_read2_b32 v[202:203], v115 offset0:163 offset1:164
	s_add_i32 s90, s76, 320
	v_add_u32_e32 v80, s90, v235
	v_add_u32_e32 v83, s90, v236
	v_add_u32_e32 v99, s90, v237
	v_add_u32_e32 v253, s90, v238
	v_add_u32_e32 v254, s90, v100
	v_add_u32_e32 v255, s90, v149
	v_med3_i32 v80, v80, 0, s99
	v_med3_i32 v83, v83, 0, s99
	v_med3_i32 v99, v99, 0, s99
	v_med3_i32 v253, v253, 0, s99
	v_med3_i32 v254, v254, 0, s99
	v_med3_i32 v255, v255, 0, s99
	v_mad_u32_u24 v80, v80, s100, v252
	v_mad_u32_u24 v83, v83, s100, v252
	v_mad_u32_u24 v99, v99, s100, v252
	v_mad_u32_u24 v253, v253, s100, v252
	v_mad_u32_u24 v254, v254, s100, v153
	v_mad_u32_u24 v255, v255, s100, v153
	global_load_dwordx4 v[116:119], v80, s[82:83]
	global_load_dwordx4 v[120:123], v83, s[82:83]
	global_load_dwordx4 v[124:127], v99, s[82:83]
	global_load_dwordx4 v[128:131], v253, s[82:83]
	global_load_dwordx4 v[132:135], v254, s[82:83] offset:768
	global_load_dwordx4 v[136:139], v255, s[82:83] offset:768
	global_load_dwordx4 v[140:143], v254, s[82:83] offset:832
	global_load_dwordx4 v[144:147], v255, s[82:83] offset:832
	ds_read_b64_tr_b16 v[72:73], v231
	ds_read_b64_tr_b16 v[74:75], v231 offset:512
	ds_read_b64_tr_b16 v[76:77], v231 offset:2048
	ds_read_b64_tr_b16 v[78:79], v231 offset:2560
	ds_read_b64_tr_b16 v[220:221], v231 offset:1024
	ds_read_b64_tr_b16 v[222:223], v231 offset:1536
	ds_read_b64_tr_b16 v[224:225], v231 offset:3072
	ds_read_b64_tr_b16 v[226:227], v231 offset:3584
	v_exp_f32_e32 v32, v32
	v_exp_f32_e32 v33, v33
	v_exp_f32_e32 v34, v34
	v_exp_f32_e32 v35, v35
	s_waitcnt vmcnt(8)
	ds_write_b128 v247, v[156:159]
	ds_write_b128 v247, v[160:163] offset:1024
	ds_write_b128 v247, v[164:167] offset:2048
	ds_write_b128 v247, v[168:171] offset:3072
	ds_read_b128 v[156:159], v248
	ds_read_b128 v[160:163], v249
	ds_read_b128 v[164:167], v250
	ds_read_b128 v[168:171], v251
	ds_write_b128 v112, v[172:175]
	ds_write_b128 v112, v[176:179] offset:1024
	ds_write_b128 v112, v[180:183] offset:2048
	ds_write_b128 v112, v[184:187] offset:3072
	v_mfma_f32_32x32x16_bf16 v[0:15], v[64:67], v[204:207], v[0:15]
	v_mfma_f32_32x32x16_bf16 v[16:31], v[64:67], v[208:211], v[16:31]
	v_mfma_f32_32x32x16_bf16 v[0:15], v[68:71], v[212:215], v[0:15]
	v_mfma_f32_32x32x16_bf16 v[16:31], v[68:71], v[216:219], v[16:31]
	v_exp_f32_e32 v36, v36
	v_exp_f32_e32 v37, v37
	v_exp_f32_e32 v38, v38
	v_exp_f32_e32 v39, v39
	s_waitcnt lgkmcnt(4)
	v_mfma_f32_32x32x16_bf16 v[188:203], v[156:159], v[48:51], v[188:203]
	v_exp_f32_e32 v40, v40
	v_exp_f32_e32 v41, v41
	v_mfma_f32_32x32x16_bf16 v[188:203], v[160:163], v[52:55], v[188:203]
	v_exp_f32_e32 v42, v42
	v_exp_f32_e32 v43, v43
	v_mfma_f32_32x32x16_bf16 v[188:203], v[164:167], v[56:59], v[188:203]
	v_exp_f32_e32 v44, v44
	v_exp_f32_e32 v45, v45
	v_mfma_f32_32x32x16_bf16 v[188:203], v[168:171], v[60:63], v[188:203]
	v_exp_f32_e32 v46, v46
	v_exp_f32_e32 v47, v47
	s_add_i32 s90, s76, 256
	v_add_u32_e32 v84, s90, v107
	v_add_u32_e32 v85, 0, v84
	v_add_u32_e32 v86, 1, v84
	v_add_u32_e32 v87, 2, v84
	v_add_u32_e32 v88, 3, v84
	v_cmp_gt_u32_e64 s[30:31], s98, v85
	v_cmp_gt_u32_e64 s[36:37], s98, v86
	v_cmp_gt_u32_e64 s[78:79], s98, v87
	v_cmp_gt_u32_e64 s[50:51], s98, v88
	v_cndmask_b32_e64 v32, 0, v32, s[30:31]
	v_add_u32_e32 v85, 8, v84
	v_cmp_gt_u32_e64 s[30:31], s98, v85
	v_cndmask_b32_e64 v33, 0, v33, s[36:37]
	v_add_u32_e32 v86, 9, v84
	v_cmp_gt_u32_e64 s[36:37], s98, v86
	v_cndmask_b32_e64 v34, 0, v34, s[78:79]
	v_add_u32_e32 v87, 10, v84
	v_cmp_gt_u32_e64 s[78:79], s98, v87
	v_cndmask_b32_e64 v35, 0, v35, s[50:51]
	v_add_u32_e32 v88, 11, v84
	v_cmp_gt_u32_e64 s[50:51], s98, v88
	v_cndmask_b32_e64 v36, 0, v36, s[30:31]
	v_add_u32_e32 v85, 16, v84
	v_cmp_gt_u32_e64 s[30:31], s98, v85
	v_cndmask_b32_e64 v37, 0, v37, s[36:37]
	v_add_u32_e32 v86, 17, v84
	v_cmp_gt_u32_e64 s[36:37], s98, v86
	v_cndmask_b32_e64 v38, 0, v38, s[78:79]
	v_add_u32_e32 v87, 18, v84
	v_cmp_gt_u32_e64 s[78:79], s98, v87
	v_cndmask_b32_e64 v39, 0, v39, s[50:51]
	v_add_u32_e32 v88, 19, v84
	v_cmp_gt_u32_e64 s[50:51], s98, v88
	v_cndmask_b32_e64 v40, 0, v40, s[30:31]
	v_add_u32_e32 v85, 24, v84
	v_cmp_gt_u32_e64 s[30:31], s98, v85
	v_cndmask_b32_e64 v41, 0, v41, s[36:37]
	v_add_u32_e32 v86, 25, v84
	v_cmp_gt_u32_e64 s[36:37], s98, v86
	v_cndmask_b32_e64 v42, 0, v42, s[78:79]
	v_add_u32_e32 v87, 26, v84
	v_cmp_gt_u32_e64 s[78:79], s98, v87
	v_cndmask_b32_e64 v43, 0, v43, s[50:51]
	v_add_u32_e32 v88, 27, v84
	v_cmp_gt_u32_e64 s[50:51], s98, v88
	v_nop
	v_cndmask_b32_e64 v44, 0, v44, s[30:31]
	v_cndmask_b32_e64 v45, 0, v45, s[36:37]
	v_cndmask_b32_e64 v46, 0, v46, s[78:79]
	v_cndmask_b32_e64 v47, 0, v47, s[50:51]
	v_cvt_pk_bf16_f32 v64, v32, v33
	v_cvt_pk_bf16_f32 v65, v34, v35
	v_cvt_pk_bf16_f32 v66, v36, v37
	v_cvt_pk_bf16_f32 v67, v38, v39
	v_cvt_pk_bf16_f32 v68, v40, v41
	v_cvt_pk_bf16_f32 v69, v42, v43
	v_cvt_pk_bf16_f32 v70, v44, v45
	v_cvt_pk_bf16_f32 v71, v46, v47
	v_pk_add_f32 v[232:233], v[232:233], v[32:33]
	v_pk_add_f32 v[232:233], v[232:233], v[34:35]
	v_pk_add_f32 v[232:233], v[232:233], v[36:37]
	v_pk_add_f32 v[232:233], v[232:233], v[38:39]
	v_pk_add_f32 v[232:233], v[232:233], v[40:41]
	v_pk_add_f32 v[232:233], v[232:233], v[42:43]
	v_pk_add_f32 v[232:233], v[232:233], v[44:45]
	v_pk_add_f32 v[232:233], v[232:233], v[46:47]
	ds_read2_b32 v[32:33], v115 offset0:170 offset1:171
	ds_read2_b32 v[34:35], v115 offset0:172 offset1:173
	ds_read2_b32 v[36:37], v115 offset0:178 offset1:179
	ds_read2_b32 v[38:39], v115 offset0:180 offset1:181
	ds_read2_b32 v[40:41], v115 offset0:187 offset1:188
	ds_read2_b32 v[42:43], v115 offset0:189 offset1:190
	ds_read2_b32 v[44:45], v115 offset0:195 offset1:196
	ds_read2_b32 v[46:47], v115 offset0:197 offset1:198
	s_add_i32 s90, s76, 352
	v_add_u32_e32 v80, s90, v235
	v_add_u32_e32 v83, s90, v236
	v_add_u32_e32 v99, s90, v237
	v_add_u32_e32 v253, s90, v238
	v_add_u32_e32 v254, s90, v100
	v_add_u32_e32 v255, s90, v149
	v_med3_i32 v80, v80, 0, s99
	v_med3_i32 v83, v83, 0, s99
	v_med3_i32 v99, v99, 0, s99
	v_med3_i32 v253, v253, 0, s99
	v_med3_i32 v254, v254, 0, s99
	v_med3_i32 v255, v255, 0, s99
	v_mad_u32_u24 v80, v80, s100, v252
	v_mad_u32_u24 v83, v83, s100, v252
	v_mad_u32_u24 v99, v99, s100, v252
	v_mad_u32_u24 v253, v253, s100, v252
	v_mad_u32_u24 v254, v254, s100, v153
	v_mad_u32_u24 v255, v255, s100, v153
	global_load_dwordx4 v[156:159], v80, s[82:83]
	global_load_dwordx4 v[160:163], v83, s[82:83]
	global_load_dwordx4 v[164:167], v99, s[82:83]
	global_load_dwordx4 v[168:171], v253, s[82:83]
	global_load_dwordx4 v[172:175], v254, s[82:83] offset:768
	global_load_dwordx4 v[176:179], v255, s[82:83] offset:768
	global_load_dwordx4 v[180:183], v254, s[82:83] offset:832
	global_load_dwordx4 v[184:187], v255, s[82:83] offset:832
	ds_read_b64_tr_b16 v[204:205], v231
	ds_read_b64_tr_b16 v[206:207], v231 offset:512
	ds_read_b64_tr_b16 v[208:209], v231 offset:2048
	ds_read_b64_tr_b16 v[210:211], v231 offset:2560
	ds_read_b64_tr_b16 v[212:213], v231 offset:1024
	ds_read_b64_tr_b16 v[214:215], v231 offset:1536
	ds_read_b64_tr_b16 v[216:217], v231 offset:3072
	ds_read_b64_tr_b16 v[218:219], v231 offset:3584
	v_exp_f32_e32 v188, v188
	v_exp_f32_e32 v189, v189
	v_exp_f32_e32 v190, v190
	v_exp_f32_e32 v191, v191
	s_waitcnt vmcnt(8)
	ds_write_b128 v247, v[116:119]
	ds_write_b128 v247, v[120:123] offset:1024
	ds_write_b128 v247, v[124:127] offset:2048
	ds_write_b128 v247, v[128:131] offset:3072
	ds_read_b128 v[116:119], v248
	ds_read_b128 v[120:123], v249
	ds_read_b128 v[124:127], v250
	ds_read_b128 v[128:131], v251
	ds_write_b128 v112, v[132:135]
	ds_write_b128 v112, v[136:139] offset:1024
	ds_write_b128 v112, v[140:143] offset:2048
	ds_write_b128 v112, v[144:147] offset:3072
	v_mfma_f32_32x32x16_bf16 v[0:15], v[64:67], v[72:75], v[0:15]
	v_mfma_f32_32x32x16_bf16 v[16:31], v[64:67], v[76:79], v[16:31]
	v_mfma_f32_32x32x16_bf16 v[0:15], v[68:71], v[220:223], v[0:15]
	v_mfma_f32_32x32x16_bf16 v[16:31], v[68:71], v[224:227], v[16:31]
	v_exp_f32_e32 v192, v192
	v_exp_f32_e32 v193, v193
	v_exp_f32_e32 v194, v194
	v_exp_f32_e32 v195, v195
	s_waitcnt lgkmcnt(4)
	v_mfma_f32_32x32x16_bf16 v[32:47], v[116:119], v[48:51], v[32:47]
	v_exp_f32_e32 v196, v196
	v_exp_f32_e32 v197, v197
	v_mfma_f32_32x32x16_bf16 v[32:47], v[120:123], v[52:55], v[32:47]
	v_exp_f32_e32 v198, v198
	v_exp_f32_e32 v199, v199
	v_mfma_f32_32x32x16_bf16 v[32:47], v[124:127], v[56:59], v[32:47]
	v_exp_f32_e32 v200, v200
	v_exp_f32_e32 v201, v201
	v_mfma_f32_32x32x16_bf16 v[32:47], v[128:131], v[60:63], v[32:47]
	v_exp_f32_e32 v202, v202
	v_exp_f32_e32 v203, v203
	s_add_i32 s90, s76, 288
	v_add_u32_e32 v84, s90, v107
	v_add_u32_e32 v85, 0, v84
	v_add_u32_e32 v86, 1, v84
	v_add_u32_e32 v87, 2, v84
	v_add_u32_e32 v88, 3, v84
	v_cmp_gt_u32_e64 s[30:31], s98, v85
	v_cmp_gt_u32_e64 s[36:37], s98, v86
	v_cmp_gt_u32_e64 s[78:79], s98, v87
	v_cmp_gt_u32_e64 s[50:51], s98, v88
	v_cndmask_b32_e64 v188, 0, v188, s[30:31]
	v_add_u32_e32 v85, 8, v84
	v_cmp_gt_u32_e64 s[30:31], s98, v85
	v_cndmask_b32_e64 v189, 0, v189, s[36:37]
	v_add_u32_e32 v86, 9, v84
	v_cmp_gt_u32_e64 s[36:37], s98, v86
	v_cndmask_b32_e64 v190, 0, v190, s[78:79]
	v_add_u32_e32 v87, 10, v84
	v_cmp_gt_u32_e64 s[78:79], s98, v87
	v_cndmask_b32_e64 v191, 0, v191, s[50:51]
	v_add_u32_e32 v88, 11, v84
	v_cmp_gt_u32_e64 s[50:51], s98, v88
	v_cndmask_b32_e64 v192, 0, v192, s[30:31]
	v_add_u32_e32 v85, 16, v84
	v_cmp_gt_u32_e64 s[30:31], s98, v85
	v_cndmask_b32_e64 v193, 0, v193, s[36:37]
	v_add_u32_e32 v86, 17, v84
	v_cmp_gt_u32_e64 s[36:37], s98, v86
	v_cndmask_b32_e64 v194, 0, v194, s[78:79]
	v_add_u32_e32 v87, 18, v84
	v_cmp_gt_u32_e64 s[78:79], s98, v87
	v_cndmask_b32_e64 v195, 0, v195, s[50:51]
	v_add_u32_e32 v88, 19, v84
	v_cmp_gt_u32_e64 s[50:51], s98, v88
	v_cndmask_b32_e64 v196, 0, v196, s[30:31]
	v_add_u32_e32 v85, 24, v84
	v_cmp_gt_u32_e64 s[30:31], s98, v85
	v_cndmask_b32_e64 v197, 0, v197, s[36:37]
	v_add_u32_e32 v86, 25, v84
	v_cmp_gt_u32_e64 s[36:37], s98, v86
	v_cndmask_b32_e64 v198, 0, v198, s[78:79]
	v_add_u32_e32 v87, 26, v84
	v_cmp_gt_u32_e64 s[78:79], s98, v87
	v_cndmask_b32_e64 v199, 0, v199, s[50:51]
	v_add_u32_e32 v88, 27, v84
	v_cmp_gt_u32_e64 s[50:51], s98, v88
	v_nop
	v_cndmask_b32_e64 v200, 0, v200, s[30:31]
	v_cndmask_b32_e64 v201, 0, v201, s[36:37]
	v_cndmask_b32_e64 v202, 0, v202, s[78:79]
	v_cndmask_b32_e64 v203, 0, v203, s[50:51]
	v_cvt_pk_bf16_f32 v64, v188, v189
	v_cvt_pk_bf16_f32 v65, v190, v191
	v_cvt_pk_bf16_f32 v66, v192, v193
	v_cvt_pk_bf16_f32 v67, v194, v195
	v_cvt_pk_bf16_f32 v68, v196, v197
	v_cvt_pk_bf16_f32 v69, v198, v199
	v_cvt_pk_bf16_f32 v70, v200, v201
	v_cvt_pk_bf16_f32 v71, v202, v203
	v_pk_add_f32 v[232:233], v[232:233], v[188:189]
	v_pk_add_f32 v[232:233], v[232:233], v[190:191]
	v_pk_add_f32 v[232:233], v[232:233], v[192:193]
	v_pk_add_f32 v[232:233], v[232:233], v[194:195]
	v_pk_add_f32 v[232:233], v[232:233], v[196:197]
	v_pk_add_f32 v[232:233], v[232:233], v[198:199]
	v_pk_add_f32 v[232:233], v[232:233], v[200:201]
	v_pk_add_f32 v[232:233], v[232:233], v[202:203]
	ds_read2_b32 v[188:189], v115 offset0:204 offset1:205
	ds_read2_b32 v[190:191], v115 offset0:206 offset1:207
	ds_read2_b32 v[192:193], v115 offset0:212 offset1:213
	ds_read2_b32 v[194:195], v115 offset0:214 offset1:215
	ds_read2_b32 v[196:197], v115 offset0:221 offset1:222
	ds_read2_b32 v[198:199], v115 offset0:223 offset1:224
	ds_read2_b32 v[200:201], v115 offset0:229 offset1:230
	ds_read2_b32 v[202:203], v115 offset0:231 offset1:232
	s_add_i32 s90, s76, 384
	v_add_u32_e32 v80, s90, v235
	v_add_u32_e32 v83, s90, v236
	v_add_u32_e32 v99, s90, v237
	v_add_u32_e32 v253, s90, v238
	v_add_u32_e32 v254, s90, v100
	v_add_u32_e32 v255, s90, v149
	v_med3_i32 v80, v80, 0, s99
	v_med3_i32 v83, v83, 0, s99
	v_med3_i32 v99, v99, 0, s99
	v_med3_i32 v253, v253, 0, s99
	v_med3_i32 v254, v254, 0, s99
	v_med3_i32 v255, v255, 0, s99
	v_mad_u32_u24 v80, v80, s100, v252
	v_mad_u32_u24 v83, v83, s100, v252
	v_mad_u32_u24 v99, v99, s100, v252
	v_mad_u32_u24 v253, v253, s100, v252
	v_mad_u32_u24 v254, v254, s100, v153
	v_mad_u32_u24 v255, v255, s100, v153
	global_load_dwordx4 v[116:119], v80, s[82:83]
	global_load_dwordx4 v[120:123], v83, s[82:83]
	global_load_dwordx4 v[124:127], v99, s[82:83]
	global_load_dwordx4 v[128:131], v253, s[82:83]
	global_load_dwordx4 v[132:135], v254, s[82:83] offset:768
	global_load_dwordx4 v[136:139], v255, s[82:83] offset:768
	global_load_dwordx4 v[140:143], v254, s[82:83] offset:832
	global_load_dwordx4 v[144:147], v255, s[82:83] offset:832
	ds_read_b64_tr_b16 v[72:73], v231
	ds_read_b64_tr_b16 v[74:75], v231 offset:512
	ds_read_b64_tr_b16 v[76:77], v231 offset:2048
	ds_read_b64_tr_b16 v[78:79], v231 offset:2560
	ds_read_b64_tr_b16 v[220:221], v231 offset:1024
	ds_read_b64_tr_b16 v[222:223], v231 offset:1536
	ds_read_b64_tr_b16 v[224:225], v231 offset:3072
	ds_read_b64_tr_b16 v[226:227], v231 offset:3584
	v_exp_f32_e32 v32, v32
	v_exp_f32_e32 v33, v33
	v_exp_f32_e32 v34, v34
	v_exp_f32_e32 v35, v35
	s_waitcnt vmcnt(8)
	ds_write_b128 v247, v[156:159]
	ds_write_b128 v247, v[160:163] offset:1024
	ds_write_b128 v247, v[164:167] offset:2048
	ds_write_b128 v247, v[168:171] offset:3072
	ds_read_b128 v[156:159], v248
	ds_read_b128 v[160:163], v249
	ds_read_b128 v[164:167], v250
	ds_read_b128 v[168:171], v251
	ds_write_b128 v112, v[172:175]
	ds_write_b128 v112, v[176:179] offset:1024
	ds_write_b128 v112, v[180:183] offset:2048
	ds_write_b128 v112, v[184:187] offset:3072
	v_mfma_f32_32x32x16_bf16 v[0:15], v[64:67], v[204:207], v[0:15]
	v_mfma_f32_32x32x16_bf16 v[16:31], v[64:67], v[208:211], v[16:31]
	v_mfma_f32_32x32x16_bf16 v[0:15], v[68:71], v[212:215], v[0:15]
	v_mfma_f32_32x32x16_bf16 v[16:31], v[68:71], v[216:219], v[16:31]
	v_exp_f32_e32 v36, v36
	v_exp_f32_e32 v37, v37
	v_exp_f32_e32 v38, v38
	v_exp_f32_e32 v39, v39
	s_waitcnt lgkmcnt(4)
	v_mfma_f32_32x32x16_bf16 v[188:203], v[156:159], v[48:51], v[188:203]
	v_exp_f32_e32 v40, v40
	v_exp_f32_e32 v41, v41
	v_mfma_f32_32x32x16_bf16 v[188:203], v[160:163], v[52:55], v[188:203]
	v_exp_f32_e32 v42, v42
	v_exp_f32_e32 v43, v43
	v_mfma_f32_32x32x16_bf16 v[188:203], v[164:167], v[56:59], v[188:203]
	v_exp_f32_e32 v44, v44
	v_exp_f32_e32 v45, v45
	v_mfma_f32_32x32x16_bf16 v[188:203], v[168:171], v[60:63], v[188:203]
	v_exp_f32_e32 v46, v46
	v_exp_f32_e32 v47, v47
	s_add_i32 s90, s76, 320
	v_add_u32_e32 v84, s90, v107
	v_add_u32_e32 v85, 0, v84
	v_add_u32_e32 v86, 1, v84
	v_add_u32_e32 v87, 2, v84
	v_add_u32_e32 v88, 3, v84
	v_cmp_gt_u32_e64 s[30:31], s98, v85
	v_cmp_gt_u32_e64 s[36:37], s98, v86
	v_cmp_gt_u32_e64 s[78:79], s98, v87
	v_cmp_gt_u32_e64 s[50:51], s98, v88
	v_cndmask_b32_e64 v32, 0, v32, s[30:31]
	v_add_u32_e32 v85, 8, v84
	v_cmp_gt_u32_e64 s[30:31], s98, v85
	v_cndmask_b32_e64 v33, 0, v33, s[36:37]
	v_add_u32_e32 v86, 9, v84
	v_cmp_gt_u32_e64 s[36:37], s98, v86
	v_cndmask_b32_e64 v34, 0, v34, s[78:79]
	v_add_u32_e32 v87, 10, v84
	v_cmp_gt_u32_e64 s[78:79], s98, v87
	v_cndmask_b32_e64 v35, 0, v35, s[50:51]
	v_add_u32_e32 v88, 11, v84
	v_cmp_gt_u32_e64 s[50:51], s98, v88
	v_cndmask_b32_e64 v36, 0, v36, s[30:31]
	v_add_u32_e32 v85, 16, v84
	v_cmp_gt_u32_e64 s[30:31], s98, v85
	v_cndmask_b32_e64 v37, 0, v37, s[36:37]
	v_add_u32_e32 v86, 17, v84
	v_cmp_gt_u32_e64 s[36:37], s98, v86
	v_cndmask_b32_e64 v38, 0, v38, s[78:79]
	v_add_u32_e32 v87, 18, v84
	v_cmp_gt_u32_e64 s[78:79], s98, v87
	v_cndmask_b32_e64 v39, 0, v39, s[50:51]
	v_add_u32_e32 v88, 19, v84
	v_cmp_gt_u32_e64 s[50:51], s98, v88
	v_cndmask_b32_e64 v40, 0, v40, s[30:31]
	v_add_u32_e32 v85, 24, v84
	v_cmp_gt_u32_e64 s[30:31], s98, v85
	v_cndmask_b32_e64 v41, 0, v41, s[36:37]
	v_add_u32_e32 v86, 25, v84
	v_cmp_gt_u32_e64 s[36:37], s98, v86
	v_cndmask_b32_e64 v42, 0, v42, s[78:79]
	v_add_u32_e32 v87, 26, v84
	v_cmp_gt_u32_e64 s[78:79], s98, v87
	v_cndmask_b32_e64 v43, 0, v43, s[50:51]
	v_add_u32_e32 v88, 27, v84
	v_cmp_gt_u32_e64 s[50:51], s98, v88
	v_nop
	v_cndmask_b32_e64 v44, 0, v44, s[30:31]
	v_cndmask_b32_e64 v45, 0, v45, s[36:37]
	v_cndmask_b32_e64 v46, 0, v46, s[78:79]
	v_cndmask_b32_e64 v47, 0, v47, s[50:51]
	v_cvt_pk_bf16_f32 v64, v32, v33
	v_cvt_pk_bf16_f32 v65, v34, v35
	v_cvt_pk_bf16_f32 v66, v36, v37
	v_cvt_pk_bf16_f32 v67, v38, v39
	v_cvt_pk_bf16_f32 v68, v40, v41
	v_cvt_pk_bf16_f32 v69, v42, v43
	v_cvt_pk_bf16_f32 v70, v44, v45
	v_cvt_pk_bf16_f32 v71, v46, v47
	v_pk_add_f32 v[232:233], v[232:233], v[32:33]
	v_pk_add_f32 v[232:233], v[232:233], v[34:35]
	v_pk_add_f32 v[232:233], v[232:233], v[36:37]
	v_pk_add_f32 v[232:233], v[232:233], v[38:39]
	v_pk_add_f32 v[232:233], v[232:233], v[40:41]
	v_pk_add_f32 v[232:233], v[232:233], v[42:43]
	v_pk_add_f32 v[232:233], v[232:233], v[44:45]
	v_pk_add_f32 v[232:233], v[232:233], v[46:47]
	v_add_u32_e32 v115, 952, v115
	ds_read2_b32 v[32:33], v115 offset0:0 offset1:1
	ds_read2_b32 v[34:35], v115 offset0:2 offset1:3
	ds_read2_b32 v[36:37], v115 offset0:8 offset1:9
	ds_read2_b32 v[38:39], v115 offset0:10 offset1:11
	ds_read2_b32 v[40:41], v115 offset0:17 offset1:18
	ds_read2_b32 v[42:43], v115 offset0:19 offset1:20
	ds_read2_b32 v[44:45], v115 offset0:25 offset1:26
	ds_read2_b32 v[46:47], v115 offset0:27 offset1:28
	s_add_i32 s90, s76, 416
	v_add_u32_e32 v80, s90, v235
	v_add_u32_e32 v83, s90, v236
	v_add_u32_e32 v99, s90, v237
	v_add_u32_e32 v253, s90, v238
	v_add_u32_e32 v254, s90, v100
	v_add_u32_e32 v255, s90, v149
	v_med3_i32 v80, v80, 0, s99
	v_med3_i32 v83, v83, 0, s99
	v_med3_i32 v99, v99, 0, s99
	v_med3_i32 v253, v253, 0, s99
	v_med3_i32 v254, v254, 0, s99
	v_med3_i32 v255, v255, 0, s99
	v_mad_u32_u24 v80, v80, s100, v252
	v_mad_u32_u24 v83, v83, s100, v252
	v_mad_u32_u24 v99, v99, s100, v252
	v_mad_u32_u24 v253, v253, s100, v252
	v_mad_u32_u24 v254, v254, s100, v153
	v_mad_u32_u24 v255, v255, s100, v153
	global_load_dwordx4 v[156:159], v80, s[82:83]
	global_load_dwordx4 v[160:163], v83, s[82:83]
	global_load_dwordx4 v[164:167], v99, s[82:83]
	global_load_dwordx4 v[168:171], v253, s[82:83]
	global_load_dwordx4 v[172:175], v254, s[82:83] offset:768
	global_load_dwordx4 v[176:179], v255, s[82:83] offset:768
	global_load_dwordx4 v[180:183], v254, s[82:83] offset:832
	global_load_dwordx4 v[184:187], v255, s[82:83] offset:832
	ds_read_b64_tr_b16 v[204:205], v231
	ds_read_b64_tr_b16 v[206:207], v231 offset:512
	ds_read_b64_tr_b16 v[208:209], v231 offset:2048
	ds_read_b64_tr_b16 v[210:211], v231 offset:2560
	ds_read_b64_tr_b16 v[212:213], v231 offset:1024
	ds_read_b64_tr_b16 v[214:215], v231 offset:1536
	ds_read_b64_tr_b16 v[216:217], v231 offset:3072
	ds_read_b64_tr_b16 v[218:219], v231 offset:3584
	v_exp_f32_e32 v188, v188
	v_exp_f32_e32 v189, v189
	v_exp_f32_e32 v190, v190
	v_exp_f32_e32 v191, v191
	s_waitcnt vmcnt(8)
	ds_write_b128 v247, v[116:119]
	ds_write_b128 v247, v[120:123] offset:1024
	ds_write_b128 v247, v[124:127] offset:2048
	ds_write_b128 v247, v[128:131] offset:3072
	ds_read_b128 v[116:119], v248
	ds_read_b128 v[120:123], v249
	ds_read_b128 v[124:127], v250
	ds_read_b128 v[128:131], v251
	ds_write_b128 v112, v[132:135]
	ds_write_b128 v112, v[136:139] offset:1024
	ds_write_b128 v112, v[140:143] offset:2048
	ds_write_b128 v112, v[144:147] offset:3072
	v_mfma_f32_32x32x16_bf16 v[0:15], v[64:67], v[72:75], v[0:15]
	v_mfma_f32_32x32x16_bf16 v[16:31], v[64:67], v[76:79], v[16:31]
	v_mfma_f32_32x32x16_bf16 v[0:15], v[68:71], v[220:223], v[0:15]
	v_mfma_f32_32x32x16_bf16 v[16:31], v[68:71], v[224:227], v[16:31]
	v_exp_f32_e32 v192, v192
	v_exp_f32_e32 v193, v193
	v_exp_f32_e32 v194, v194
	v_exp_f32_e32 v195, v195
	s_waitcnt lgkmcnt(4)
	v_mfma_f32_32x32x16_bf16 v[32:47], v[116:119], v[48:51], v[32:47]
	v_exp_f32_e32 v196, v196
	v_exp_f32_e32 v197, v197
	v_mfma_f32_32x32x16_bf16 v[32:47], v[120:123], v[52:55], v[32:47]
	v_exp_f32_e32 v198, v198
	v_exp_f32_e32 v199, v199
	v_mfma_f32_32x32x16_bf16 v[32:47], v[124:127], v[56:59], v[32:47]
	v_exp_f32_e32 v200, v200
	v_exp_f32_e32 v201, v201
	v_mfma_f32_32x32x16_bf16 v[32:47], v[128:131], v[60:63], v[32:47]
	v_exp_f32_e32 v202, v202
	v_exp_f32_e32 v203, v203
	s_add_i32 s90, s76, 352
	v_add_u32_e32 v84, s90, v107
	v_add_u32_e32 v85, 0, v84
	v_add_u32_e32 v86, 1, v84
	v_add_u32_e32 v87, 2, v84
	v_add_u32_e32 v88, 3, v84
	v_cmp_gt_u32_e64 s[30:31], s98, v85
	v_cmp_gt_u32_e64 s[36:37], s98, v86
	v_cmp_gt_u32_e64 s[78:79], s98, v87
	v_cmp_gt_u32_e64 s[50:51], s98, v88
	v_cndmask_b32_e64 v188, 0, v188, s[30:31]
	v_add_u32_e32 v85, 8, v84
	v_cmp_gt_u32_e64 s[30:31], s98, v85
	v_cndmask_b32_e64 v189, 0, v189, s[36:37]
	v_add_u32_e32 v86, 9, v84
	v_cmp_gt_u32_e64 s[36:37], s98, v86
	v_cndmask_b32_e64 v190, 0, v190, s[78:79]
	v_add_u32_e32 v87, 10, v84
	v_cmp_gt_u32_e64 s[78:79], s98, v87
	v_cndmask_b32_e64 v191, 0, v191, s[50:51]
	v_add_u32_e32 v88, 11, v84
	v_cmp_gt_u32_e64 s[50:51], s98, v88
	v_cndmask_b32_e64 v192, 0, v192, s[30:31]
	v_add_u32_e32 v85, 16, v84
	v_cmp_gt_u32_e64 s[30:31], s98, v85
	v_cndmask_b32_e64 v193, 0, v193, s[36:37]
	v_add_u32_e32 v86, 17, v84
	v_cmp_gt_u32_e64 s[36:37], s98, v86
	v_cndmask_b32_e64 v194, 0, v194, s[78:79]
	v_add_u32_e32 v87, 18, v84
	v_cmp_gt_u32_e64 s[78:79], s98, v87
	v_cndmask_b32_e64 v195, 0, v195, s[50:51]
	v_add_u32_e32 v88, 19, v84
	v_cmp_gt_u32_e64 s[50:51], s98, v88
	v_cndmask_b32_e64 v196, 0, v196, s[30:31]
	v_add_u32_e32 v85, 24, v84
	v_cmp_gt_u32_e64 s[30:31], s98, v85
	v_cndmask_b32_e64 v197, 0, v197, s[36:37]
	v_add_u32_e32 v86, 25, v84
	v_cmp_gt_u32_e64 s[36:37], s98, v86
	v_cndmask_b32_e64 v198, 0, v198, s[78:79]
	v_add_u32_e32 v87, 26, v84
	v_cmp_gt_u32_e64 s[78:79], s98, v87
	v_cndmask_b32_e64 v199, 0, v199, s[50:51]
	v_add_u32_e32 v88, 27, v84
	v_cmp_gt_u32_e64 s[50:51], s98, v88
	v_nop
	v_cndmask_b32_e64 v200, 0, v200, s[30:31]
	v_cndmask_b32_e64 v201, 0, v201, s[36:37]
	v_cndmask_b32_e64 v202, 0, v202, s[78:79]
	v_cndmask_b32_e64 v203, 0, v203, s[50:51]
	v_cvt_pk_bf16_f32 v64, v188, v189
	v_cvt_pk_bf16_f32 v65, v190, v191
	v_cvt_pk_bf16_f32 v66, v192, v193
	v_cvt_pk_bf16_f32 v67, v194, v195
	v_cvt_pk_bf16_f32 v68, v196, v197
	v_cvt_pk_bf16_f32 v69, v198, v199
	v_cvt_pk_bf16_f32 v70, v200, v201
	v_cvt_pk_bf16_f32 v71, v202, v203
	v_pk_add_f32 v[232:233], v[232:233], v[188:189]
	v_pk_add_f32 v[232:233], v[232:233], v[190:191]
	v_pk_add_f32 v[232:233], v[232:233], v[192:193]
	v_pk_add_f32 v[232:233], v[232:233], v[194:195]
	v_pk_add_f32 v[232:233], v[232:233], v[196:197]
	v_pk_add_f32 v[232:233], v[232:233], v[198:199]
	v_pk_add_f32 v[232:233], v[232:233], v[200:201]
	v_pk_add_f32 v[232:233], v[232:233], v[202:203]
	ds_read2_b32 v[188:189], v115 offset0:34 offset1:35
	ds_read2_b32 v[190:191], v115 offset0:36 offset1:37
	ds_read2_b32 v[192:193], v115 offset0:42 offset1:43
	ds_read2_b32 v[194:195], v115 offset0:44 offset1:45
	ds_read2_b32 v[196:197], v115 offset0:51 offset1:52
	ds_read2_b32 v[198:199], v115 offset0:53 offset1:54
	ds_read2_b32 v[200:201], v115 offset0:59 offset1:60
	ds_read2_b32 v[202:203], v115 offset0:61 offset1:62
	s_add_i32 s90, s76, 448
	v_add_u32_e32 v80, s90, v235
	v_add_u32_e32 v83, s90, v236
	v_add_u32_e32 v99, s90, v237
	v_add_u32_e32 v253, s90, v238
	v_add_u32_e32 v254, s90, v100
	v_add_u32_e32 v255, s90, v149
	v_med3_i32 v80, v80, 0, s99
	v_med3_i32 v83, v83, 0, s99
	v_med3_i32 v99, v99, 0, s99
	v_med3_i32 v253, v253, 0, s99
	v_med3_i32 v254, v254, 0, s99
	v_med3_i32 v255, v255, 0, s99
	v_mad_u32_u24 v80, v80, s100, v252
	v_mad_u32_u24 v83, v83, s100, v252
	v_mad_u32_u24 v99, v99, s100, v252
	v_mad_u32_u24 v253, v253, s100, v252
	v_mad_u32_u24 v254, v254, s100, v153
	v_mad_u32_u24 v255, v255, s100, v153
	global_load_dwordx4 v[116:119], v80, s[82:83]
	global_load_dwordx4 v[120:123], v83, s[82:83]
	global_load_dwordx4 v[124:127], v99, s[82:83]
	global_load_dwordx4 v[128:131], v253, s[82:83]
	global_load_dwordx4 v[132:135], v254, s[82:83] offset:768
	global_load_dwordx4 v[136:139], v255, s[82:83] offset:768
	global_load_dwordx4 v[140:143], v254, s[82:83] offset:832
	global_load_dwordx4 v[144:147], v255, s[82:83] offset:832
	ds_read_b64_tr_b16 v[72:73], v231
	ds_read_b64_tr_b16 v[74:75], v231 offset:512
	ds_read_b64_tr_b16 v[76:77], v231 offset:2048
	ds_read_b64_tr_b16 v[78:79], v231 offset:2560
	ds_read_b64_tr_b16 v[220:221], v231 offset:1024
	ds_read_b64_tr_b16 v[222:223], v231 offset:1536
	ds_read_b64_tr_b16 v[224:225], v231 offset:3072
	ds_read_b64_tr_b16 v[226:227], v231 offset:3584
	v_exp_f32_e32 v32, v32
	v_exp_f32_e32 v33, v33
	v_exp_f32_e32 v34, v34
	v_exp_f32_e32 v35, v35
	s_waitcnt vmcnt(8)
	ds_write_b128 v247, v[156:159]
	ds_write_b128 v247, v[160:163] offset:1024
	ds_write_b128 v247, v[164:167] offset:2048
	ds_write_b128 v247, v[168:171] offset:3072
	ds_read_b128 v[156:159], v248
	ds_read_b128 v[160:163], v249
	ds_read_b128 v[164:167], v250
	ds_read_b128 v[168:171], v251
	ds_write_b128 v112, v[172:175]
	ds_write_b128 v112, v[176:179] offset:1024
	ds_write_b128 v112, v[180:183] offset:2048
	ds_write_b128 v112, v[184:187] offset:3072
	v_mfma_f32_32x32x16_bf16 v[0:15], v[64:67], v[204:207], v[0:15]
	v_mfma_f32_32x32x16_bf16 v[16:31], v[64:67], v[208:211], v[16:31]
	v_mfma_f32_32x32x16_bf16 v[0:15], v[68:71], v[212:215], v[0:15]
	v_mfma_f32_32x32x16_bf16 v[16:31], v[68:71], v[216:219], v[16:31]
	v_exp_f32_e32 v36, v36
	v_exp_f32_e32 v37, v37
	v_exp_f32_e32 v38, v38
	v_exp_f32_e32 v39, v39
	s_waitcnt lgkmcnt(4)
	v_mfma_f32_32x32x16_bf16 v[188:203], v[156:159], v[48:51], v[188:203]
	v_exp_f32_e32 v40, v40
	v_exp_f32_e32 v41, v41
	v_mfma_f32_32x32x16_bf16 v[188:203], v[160:163], v[52:55], v[188:203]
	v_exp_f32_e32 v42, v42
	v_exp_f32_e32 v43, v43
	v_mfma_f32_32x32x16_bf16 v[188:203], v[164:167], v[56:59], v[188:203]
	v_exp_f32_e32 v44, v44
	v_exp_f32_e32 v45, v45
	v_mfma_f32_32x32x16_bf16 v[188:203], v[168:171], v[60:63], v[188:203]
	v_exp_f32_e32 v46, v46
	v_exp_f32_e32 v47, v47
	s_add_i32 s90, s76, 384
	v_add_u32_e32 v84, s90, v107
	v_add_u32_e32 v85, 0, v84
	v_add_u32_e32 v86, 1, v84
	v_add_u32_e32 v87, 2, v84
	v_add_u32_e32 v88, 3, v84
	v_cmp_gt_u32_e64 s[30:31], s98, v85
	v_cmp_gt_u32_e64 s[36:37], s98, v86
	v_cmp_gt_u32_e64 s[78:79], s98, v87
	v_cmp_gt_u32_e64 s[50:51], s98, v88
	v_cndmask_b32_e64 v32, 0, v32, s[30:31]
	v_add_u32_e32 v85, 8, v84
	v_cmp_gt_u32_e64 s[30:31], s98, v85
	v_cndmask_b32_e64 v33, 0, v33, s[36:37]
	v_add_u32_e32 v86, 9, v84
	v_cmp_gt_u32_e64 s[36:37], s98, v86
	v_cndmask_b32_e64 v34, 0, v34, s[78:79]
	v_add_u32_e32 v87, 10, v84
	v_cmp_gt_u32_e64 s[78:79], s98, v87
	v_cndmask_b32_e64 v35, 0, v35, s[50:51]
	v_add_u32_e32 v88, 11, v84
	v_cmp_gt_u32_e64 s[50:51], s98, v88
	v_cndmask_b32_e64 v36, 0, v36, s[30:31]
	v_add_u32_e32 v85, 16, v84
	v_cmp_gt_u32_e64 s[30:31], s98, v85
	v_cndmask_b32_e64 v37, 0, v37, s[36:37]
	v_add_u32_e32 v86, 17, v84
	v_cmp_gt_u32_e64 s[36:37], s98, v86
	v_cndmask_b32_e64 v38, 0, v38, s[78:79]
	v_add_u32_e32 v87, 18, v84
	v_cmp_gt_u32_e64 s[78:79], s98, v87
	v_cndmask_b32_e64 v39, 0, v39, s[50:51]
	v_add_u32_e32 v88, 19, v84
	v_cmp_gt_u32_e64 s[50:51], s98, v88
	v_cndmask_b32_e64 v40, 0, v40, s[30:31]
	v_add_u32_e32 v85, 24, v84
	v_cmp_gt_u32_e64 s[30:31], s98, v85
	v_cndmask_b32_e64 v41, 0, v41, s[36:37]
	v_add_u32_e32 v86, 25, v84
	v_cmp_gt_u32_e64 s[36:37], s98, v86
	v_cndmask_b32_e64 v42, 0, v42, s[78:79]
	v_add_u32_e32 v87, 26, v84
	v_cmp_gt_u32_e64 s[78:79], s98, v87
	v_cndmask_b32_e64 v43, 0, v43, s[50:51]
	v_add_u32_e32 v88, 27, v84
	v_cmp_gt_u32_e64 s[50:51], s98, v88
	v_nop
	v_cndmask_b32_e64 v44, 0, v44, s[30:31]
	v_cndmask_b32_e64 v45, 0, v45, s[36:37]
	v_cndmask_b32_e64 v46, 0, v46, s[78:79]
	v_cndmask_b32_e64 v47, 0, v47, s[50:51]
	v_cvt_pk_bf16_f32 v64, v32, v33
	v_cvt_pk_bf16_f32 v65, v34, v35
	v_cvt_pk_bf16_f32 v66, v36, v37
	v_cvt_pk_bf16_f32 v67, v38, v39
	v_cvt_pk_bf16_f32 v68, v40, v41
	v_cvt_pk_bf16_f32 v69, v42, v43
	v_cvt_pk_bf16_f32 v70, v44, v45
	v_cvt_pk_bf16_f32 v71, v46, v47
	v_pk_add_f32 v[232:233], v[232:233], v[32:33]
	v_pk_add_f32 v[232:233], v[232:233], v[34:35]
	v_pk_add_f32 v[232:233], v[232:233], v[36:37]
	v_pk_add_f32 v[232:233], v[232:233], v[38:39]
	v_pk_add_f32 v[232:233], v[232:233], v[40:41]
	v_pk_add_f32 v[232:233], v[232:233], v[42:43]
	v_pk_add_f32 v[232:233], v[232:233], v[44:45]
	v_pk_add_f32 v[232:233], v[232:233], v[46:47]
	ds_read2_b32 v[32:33], v115 offset0:68 offset1:69
	ds_read2_b32 v[34:35], v115 offset0:70 offset1:71
	ds_read2_b32 v[36:37], v115 offset0:76 offset1:77
	ds_read2_b32 v[38:39], v115 offset0:78 offset1:79
	ds_read2_b32 v[40:41], v115 offset0:85 offset1:86
	ds_read2_b32 v[42:43], v115 offset0:87 offset1:88
	ds_read2_b32 v[44:45], v115 offset0:93 offset1:94
	ds_read2_b32 v[46:47], v115 offset0:95 offset1:96
	s_add_i32 s90, s76, 480
	v_add_u32_e32 v80, s90, v235
	v_add_u32_e32 v83, s90, v236
	v_add_u32_e32 v99, s90, v237
	v_add_u32_e32 v253, s90, v238
	v_add_u32_e32 v254, s90, v100
	v_add_u32_e32 v255, s90, v149
	v_med3_i32 v80, v80, 0, s99
	v_med3_i32 v83, v83, 0, s99
	v_med3_i32 v99, v99, 0, s99
	v_med3_i32 v253, v253, 0, s99
	v_med3_i32 v254, v254, 0, s99
	v_med3_i32 v255, v255, 0, s99
	v_mad_u32_u24 v80, v80, s100, v252
	v_mad_u32_u24 v83, v83, s100, v252
	v_mad_u32_u24 v99, v99, s100, v252
	v_mad_u32_u24 v253, v253, s100, v252
	v_mad_u32_u24 v254, v254, s100, v153
	v_mad_u32_u24 v255, v255, s100, v153
	global_load_dwordx4 v[156:159], v80, s[82:83]
	global_load_dwordx4 v[160:163], v83, s[82:83]
	global_load_dwordx4 v[164:167], v99, s[82:83]
	global_load_dwordx4 v[168:171], v253, s[82:83]
	global_load_dwordx4 v[172:175], v254, s[82:83] offset:768
	global_load_dwordx4 v[176:179], v255, s[82:83] offset:768
	global_load_dwordx4 v[180:183], v254, s[82:83] offset:832
	global_load_dwordx4 v[184:187], v255, s[82:83] offset:832
	ds_read_b64_tr_b16 v[204:205], v231
	ds_read_b64_tr_b16 v[206:207], v231 offset:512
	ds_read_b64_tr_b16 v[208:209], v231 offset:2048
	ds_read_b64_tr_b16 v[210:211], v231 offset:2560
	ds_read_b64_tr_b16 v[212:213], v231 offset:1024
	ds_read_b64_tr_b16 v[214:215], v231 offset:1536
	ds_read_b64_tr_b16 v[216:217], v231 offset:3072
	ds_read_b64_tr_b16 v[218:219], v231 offset:3584
	v_exp_f32_e32 v188, v188
	v_exp_f32_e32 v189, v189
	v_exp_f32_e32 v190, v190
	v_exp_f32_e32 v191, v191
	s_waitcnt vmcnt(8)
	ds_write_b128 v247, v[116:119]
	ds_write_b128 v247, v[120:123] offset:1024
	ds_write_b128 v247, v[124:127] offset:2048
	ds_write_b128 v247, v[128:131] offset:3072
	ds_read_b128 v[116:119], v248
	ds_read_b128 v[120:123], v249
	ds_read_b128 v[124:127], v250
	ds_read_b128 v[128:131], v251
	ds_write_b128 v112, v[132:135]
	ds_write_b128 v112, v[136:139] offset:1024
	ds_write_b128 v112, v[140:143] offset:2048
	ds_write_b128 v112, v[144:147] offset:3072
	v_mfma_f32_32x32x16_bf16 v[0:15], v[64:67], v[72:75], v[0:15]
	v_mfma_f32_32x32x16_bf16 v[16:31], v[64:67], v[76:79], v[16:31]
	v_mfma_f32_32x32x16_bf16 v[0:15], v[68:71], v[220:223], v[0:15]
	v_mfma_f32_32x32x16_bf16 v[16:31], v[68:71], v[224:227], v[16:31]
	v_exp_f32_e32 v192, v192
	v_exp_f32_e32 v193, v193
	v_exp_f32_e32 v194, v194
	v_exp_f32_e32 v195, v195
	s_waitcnt lgkmcnt(4)
	v_mfma_f32_32x32x16_bf16 v[32:47], v[116:119], v[48:51], v[32:47]
	v_exp_f32_e32 v196, v196
	v_exp_f32_e32 v197, v197
	v_mfma_f32_32x32x16_bf16 v[32:47], v[120:123], v[52:55], v[32:47]
	v_exp_f32_e32 v198, v198
	v_exp_f32_e32 v199, v199
	v_mfma_f32_32x32x16_bf16 v[32:47], v[124:127], v[56:59], v[32:47]
	v_exp_f32_e32 v200, v200
	v_exp_f32_e32 v201, v201
	v_mfma_f32_32x32x16_bf16 v[32:47], v[128:131], v[60:63], v[32:47]
	v_exp_f32_e32 v202, v202
	v_exp_f32_e32 v203, v203
	s_add_i32 s90, s76, 416
	v_add_u32_e32 v84, s90, v107
	v_add_u32_e32 v85, 0, v84
	v_add_u32_e32 v86, 1, v84
	v_add_u32_e32 v87, 2, v84
	v_add_u32_e32 v88, 3, v84
	v_cmp_gt_u32_e64 s[30:31], s98, v85
	v_cmp_gt_u32_e64 s[36:37], s98, v86
	v_cmp_gt_u32_e64 s[78:79], s98, v87
	v_cmp_gt_u32_e64 s[50:51], s98, v88
	v_cndmask_b32_e64 v188, 0, v188, s[30:31]
	v_add_u32_e32 v85, 8, v84
	v_cmp_gt_u32_e64 s[30:31], s98, v85
	v_cndmask_b32_e64 v189, 0, v189, s[36:37]
	v_add_u32_e32 v86, 9, v84
	v_cmp_gt_u32_e64 s[36:37], s98, v86
	v_cndmask_b32_e64 v190, 0, v190, s[78:79]
	v_add_u32_e32 v87, 10, v84
	v_cmp_gt_u32_e64 s[78:79], s98, v87
	v_cndmask_b32_e64 v191, 0, v191, s[50:51]
	v_add_u32_e32 v88, 11, v84
	v_cmp_gt_u32_e64 s[50:51], s98, v88
	v_cndmask_b32_e64 v192, 0, v192, s[30:31]
	v_add_u32_e32 v85, 16, v84
	v_cmp_gt_u32_e64 s[30:31], s98, v85
	v_cndmask_b32_e64 v193, 0, v193, s[36:37]
	v_add_u32_e32 v86, 17, v84
	v_cmp_gt_u32_e64 s[36:37], s98, v86
	v_cndmask_b32_e64 v194, 0, v194, s[78:79]
	v_add_u32_e32 v87, 18, v84
	v_cmp_gt_u32_e64 s[78:79], s98, v87
	v_cndmask_b32_e64 v195, 0, v195, s[50:51]
	v_add_u32_e32 v88, 19, v84
	v_cmp_gt_u32_e64 s[50:51], s98, v88
	v_cndmask_b32_e64 v196, 0, v196, s[30:31]
	v_add_u32_e32 v85, 24, v84
	v_cmp_gt_u32_e64 s[30:31], s98, v85
	v_cndmask_b32_e64 v197, 0, v197, s[36:37]
	v_add_u32_e32 v86, 25, v84
	v_cmp_gt_u32_e64 s[36:37], s98, v86
	v_cndmask_b32_e64 v198, 0, v198, s[78:79]
	v_add_u32_e32 v87, 26, v84
	v_cmp_gt_u32_e64 s[78:79], s98, v87
	v_cndmask_b32_e64 v199, 0, v199, s[50:51]
	v_add_u32_e32 v88, 27, v84
	v_cmp_gt_u32_e64 s[50:51], s98, v88
	v_nop
	v_cndmask_b32_e64 v200, 0, v200, s[30:31]
	v_cndmask_b32_e64 v201, 0, v201, s[36:37]
	v_cndmask_b32_e64 v202, 0, v202, s[78:79]
	v_cndmask_b32_e64 v203, 0, v203, s[50:51]
	v_cvt_pk_bf16_f32 v64, v188, v189
	v_cvt_pk_bf16_f32 v65, v190, v191
	v_cvt_pk_bf16_f32 v66, v192, v193
	v_cvt_pk_bf16_f32 v67, v194, v195
	v_cvt_pk_bf16_f32 v68, v196, v197
	v_cvt_pk_bf16_f32 v69, v198, v199
	v_cvt_pk_bf16_f32 v70, v200, v201
	v_cvt_pk_bf16_f32 v71, v202, v203
	v_pk_add_f32 v[232:233], v[232:233], v[188:189]
	v_pk_add_f32 v[232:233], v[232:233], v[190:191]
	v_pk_add_f32 v[232:233], v[232:233], v[192:193]
	v_pk_add_f32 v[232:233], v[232:233], v[194:195]
	v_pk_add_f32 v[232:233], v[232:233], v[196:197]
	v_pk_add_f32 v[232:233], v[232:233], v[198:199]
	v_pk_add_f32 v[232:233], v[232:233], v[200:201]
	v_pk_add_f32 v[232:233], v[232:233], v[202:203]
	ds_read2_b32 v[188:189], v115 offset0:102 offset1:103
	ds_read2_b32 v[190:191], v115 offset0:104 offset1:105
	ds_read2_b32 v[192:193], v115 offset0:110 offset1:111
	ds_read2_b32 v[194:195], v115 offset0:112 offset1:113
	ds_read2_b32 v[196:197], v115 offset0:119 offset1:120
	ds_read2_b32 v[198:199], v115 offset0:121 offset1:122
	ds_read2_b32 v[200:201], v115 offset0:127 offset1:128
	ds_read2_b32 v[202:203], v115 offset0:129 offset1:130
	s_add_i32 s90, s76, 512
	v_add_u32_e32 v80, s90, v235
	v_add_u32_e32 v83, s90, v236
	v_add_u32_e32 v99, s90, v237
	v_add_u32_e32 v253, s90, v238
	v_add_u32_e32 v254, s90, v100
	v_add_u32_e32 v255, s90, v149
	v_med3_i32 v80, v80, 0, s99
	v_med3_i32 v83, v83, 0, s99
	v_med3_i32 v99, v99, 0, s99
	v_med3_i32 v253, v253, 0, s99
	v_med3_i32 v254, v254, 0, s99
	v_med3_i32 v255, v255, 0, s99
	v_mad_u32_u24 v80, v80, s100, v252
	v_mad_u32_u24 v83, v83, s100, v252
	v_mad_u32_u24 v99, v99, s100, v252
	v_mad_u32_u24 v253, v253, s100, v252
	v_mad_u32_u24 v254, v254, s100, v153
	v_mad_u32_u24 v255, v255, s100, v153
	global_load_dwordx4 v[116:119], v80, s[82:83]
	global_load_dwordx4 v[120:123], v83, s[82:83]
	global_load_dwordx4 v[124:127], v99, s[82:83]
	global_load_dwordx4 v[128:131], v253, s[82:83]
	global_load_dwordx4 v[132:135], v254, s[82:83] offset:768
	global_load_dwordx4 v[136:139], v255, s[82:83] offset:768
	global_load_dwordx4 v[140:143], v254, s[82:83] offset:832
	global_load_dwordx4 v[144:147], v255, s[82:83] offset:832
	ds_read_b64_tr_b16 v[72:73], v231
	ds_read_b64_tr_b16 v[74:75], v231 offset:512
	ds_read_b64_tr_b16 v[76:77], v231 offset:2048
	ds_read_b64_tr_b16 v[78:79], v231 offset:2560
	ds_read_b64_tr_b16 v[220:221], v231 offset:1024
	ds_read_b64_tr_b16 v[222:223], v231 offset:1536
	ds_read_b64_tr_b16 v[224:225], v231 offset:3072
	ds_read_b64_tr_b16 v[226:227], v231 offset:3584
	v_exp_f32_e32 v32, v32
	v_exp_f32_e32 v33, v33
	v_exp_f32_e32 v34, v34
	v_exp_f32_e32 v35, v35
	s_waitcnt vmcnt(8)
	ds_write_b128 v247, v[156:159]
	ds_write_b128 v247, v[160:163] offset:1024
	ds_write_b128 v247, v[164:167] offset:2048
	ds_write_b128 v247, v[168:171] offset:3072
	ds_read_b128 v[156:159], v248
	ds_read_b128 v[160:163], v249
	ds_read_b128 v[164:167], v250
	ds_read_b128 v[168:171], v251
	ds_write_b128 v112, v[172:175]
	ds_write_b128 v112, v[176:179] offset:1024
	ds_write_b128 v112, v[180:183] offset:2048
	ds_write_b128 v112, v[184:187] offset:3072
	v_mfma_f32_32x32x16_bf16 v[0:15], v[64:67], v[204:207], v[0:15]
	v_mfma_f32_32x32x16_bf16 v[16:31], v[64:67], v[208:211], v[16:31]
	v_mfma_f32_32x32x16_bf16 v[0:15], v[68:71], v[212:215], v[0:15]
	v_mfma_f32_32x32x16_bf16 v[16:31], v[68:71], v[216:219], v[16:31]
	v_exp_f32_e32 v36, v36
	v_exp_f32_e32 v37, v37
	v_exp_f32_e32 v38, v38
	v_exp_f32_e32 v39, v39
	s_waitcnt lgkmcnt(4)
	v_mfma_f32_32x32x16_bf16 v[188:203], v[156:159], v[48:51], v[188:203]
	v_exp_f32_e32 v40, v40
	v_exp_f32_e32 v41, v41
	v_mfma_f32_32x32x16_bf16 v[188:203], v[160:163], v[52:55], v[188:203]
	v_exp_f32_e32 v42, v42
	v_exp_f32_e32 v43, v43
	v_mfma_f32_32x32x16_bf16 v[188:203], v[164:167], v[56:59], v[188:203]
	v_exp_f32_e32 v44, v44
	v_exp_f32_e32 v45, v45
	v_mfma_f32_32x32x16_bf16 v[188:203], v[168:171], v[60:63], v[188:203]
	v_exp_f32_e32 v46, v46
	v_exp_f32_e32 v47, v47
	s_add_i32 s90, s76, 448
	v_add_u32_e32 v84, s90, v107
	v_add_u32_e32 v85, 0, v84
	v_add_u32_e32 v86, 1, v84
	v_add_u32_e32 v87, 2, v84
	v_add_u32_e32 v88, 3, v84
	v_cmp_gt_u32_e64 s[30:31], s98, v85
	v_cmp_gt_u32_e64 s[36:37], s98, v86
	v_cmp_gt_u32_e64 s[78:79], s98, v87
	v_cmp_gt_u32_e64 s[50:51], s98, v88
	v_cndmask_b32_e64 v32, 0, v32, s[30:31]
	v_add_u32_e32 v85, 8, v84
	v_cmp_gt_u32_e64 s[30:31], s98, v85
	v_cndmask_b32_e64 v33, 0, v33, s[36:37]
	v_add_u32_e32 v86, 9, v84
	v_cmp_gt_u32_e64 s[36:37], s98, v86
	v_cndmask_b32_e64 v34, 0, v34, s[78:79]
	v_add_u32_e32 v87, 10, v84
	v_cmp_gt_u32_e64 s[78:79], s98, v87
	v_cndmask_b32_e64 v35, 0, v35, s[50:51]
	v_add_u32_e32 v88, 11, v84
	v_cmp_gt_u32_e64 s[50:51], s98, v88
	v_cndmask_b32_e64 v36, 0, v36, s[30:31]
	v_add_u32_e32 v85, 16, v84
	v_cmp_gt_u32_e64 s[30:31], s98, v85
	v_cndmask_b32_e64 v37, 0, v37, s[36:37]
	v_add_u32_e32 v86, 17, v84
	v_cmp_gt_u32_e64 s[36:37], s98, v86
	v_cndmask_b32_e64 v38, 0, v38, s[78:79]
	v_add_u32_e32 v87, 18, v84
	v_cmp_gt_u32_e64 s[78:79], s98, v87
	v_cndmask_b32_e64 v39, 0, v39, s[50:51]
	v_add_u32_e32 v88, 19, v84
	v_cmp_gt_u32_e64 s[50:51], s98, v88
	v_cndmask_b32_e64 v40, 0, v40, s[30:31]
	v_add_u32_e32 v85, 24, v84
	v_cmp_gt_u32_e64 s[30:31], s98, v85
	v_cndmask_b32_e64 v41, 0, v41, s[36:37]
	v_add_u32_e32 v86, 25, v84
	v_cmp_gt_u32_e64 s[36:37], s98, v86
	v_cndmask_b32_e64 v42, 0, v42, s[78:79]
	v_add_u32_e32 v87, 26, v84
	v_cmp_gt_u32_e64 s[78:79], s98, v87
	v_cndmask_b32_e64 v43, 0, v43, s[50:51]
	v_add_u32_e32 v88, 27, v84
	v_cmp_gt_u32_e64 s[50:51], s98, v88
	v_nop
	v_cndmask_b32_e64 v44, 0, v44, s[30:31]
	v_cndmask_b32_e64 v45, 0, v45, s[36:37]
	v_cndmask_b32_e64 v46, 0, v46, s[78:79]
	v_cndmask_b32_e64 v47, 0, v47, s[50:51]
	v_cvt_pk_bf16_f32 v64, v32, v33
	v_cvt_pk_bf16_f32 v65, v34, v35
	v_cvt_pk_bf16_f32 v66, v36, v37
	v_cvt_pk_bf16_f32 v67, v38, v39
	v_cvt_pk_bf16_f32 v68, v40, v41
	v_cvt_pk_bf16_f32 v69, v42, v43
	v_cvt_pk_bf16_f32 v70, v44, v45
	v_cvt_pk_bf16_f32 v71, v46, v47
	v_pk_add_f32 v[232:233], v[232:233], v[32:33]
	v_pk_add_f32 v[232:233], v[232:233], v[34:35]
	v_pk_add_f32 v[232:233], v[232:233], v[36:37]
	v_pk_add_f32 v[232:233], v[232:233], v[38:39]
	v_pk_add_f32 v[232:233], v[232:233], v[40:41]
	v_pk_add_f32 v[232:233], v[232:233], v[42:43]
	v_pk_add_f32 v[232:233], v[232:233], v[44:45]
	v_pk_add_f32 v[232:233], v[232:233], v[46:47]
	ds_read2_b32 v[32:33], v115 offset0:136 offset1:137
	ds_read2_b32 v[34:35], v115 offset0:138 offset1:139
	ds_read2_b32 v[36:37], v115 offset0:144 offset1:145
	ds_read2_b32 v[38:39], v115 offset0:146 offset1:147
	ds_read2_b32 v[40:41], v115 offset0:153 offset1:154
	ds_read2_b32 v[42:43], v115 offset0:155 offset1:156
	ds_read2_b32 v[44:45], v115 offset0:161 offset1:162
	ds_read2_b32 v[46:47], v115 offset0:163 offset1:164
	s_add_i32 s90, s76, 544
	v_add_u32_e32 v80, s90, v235
	v_add_u32_e32 v83, s90, v236
	v_add_u32_e32 v99, s90, v237
	v_add_u32_e32 v253, s90, v238
	v_add_u32_e32 v254, s90, v100
	v_add_u32_e32 v255, s90, v149
	v_med3_i32 v80, v80, 0, s99
	v_med3_i32 v83, v83, 0, s99
	v_med3_i32 v99, v99, 0, s99
	v_med3_i32 v253, v253, 0, s99
	v_med3_i32 v254, v254, 0, s99
	v_med3_i32 v255, v255, 0, s99
	v_mad_u32_u24 v80, v80, s100, v252
	v_mad_u32_u24 v83, v83, s100, v252
	v_mad_u32_u24 v99, v99, s100, v252
	v_mad_u32_u24 v253, v253, s100, v252
	v_mad_u32_u24 v254, v254, s100, v153
	v_mad_u32_u24 v255, v255, s100, v153
	global_load_dwordx4 v[156:159], v80, s[82:83]
	global_load_dwordx4 v[160:163], v83, s[82:83]
	global_load_dwordx4 v[164:167], v99, s[82:83]
	global_load_dwordx4 v[168:171], v253, s[82:83]
	global_load_dwordx4 v[172:175], v254, s[82:83] offset:768
	global_load_dwordx4 v[176:179], v255, s[82:83] offset:768
	global_load_dwordx4 v[180:183], v254, s[82:83] offset:832
	global_load_dwordx4 v[184:187], v255, s[82:83] offset:832
	ds_read_b64_tr_b16 v[204:205], v231
	ds_read_b64_tr_b16 v[206:207], v231 offset:512
	ds_read_b64_tr_b16 v[208:209], v231 offset:2048
	ds_read_b64_tr_b16 v[210:211], v231 offset:2560
	ds_read_b64_tr_b16 v[212:213], v231 offset:1024
	ds_read_b64_tr_b16 v[214:215], v231 offset:1536
	ds_read_b64_tr_b16 v[216:217], v231 offset:3072
	ds_read_b64_tr_b16 v[218:219], v231 offset:3584
	v_exp_f32_e32 v188, v188
	v_exp_f32_e32 v189, v189
	v_exp_f32_e32 v190, v190
	v_exp_f32_e32 v191, v191
	s_waitcnt vmcnt(8)
	ds_write_b128 v247, v[116:119]
	ds_write_b128 v247, v[120:123] offset:1024
	ds_write_b128 v247, v[124:127] offset:2048
	ds_write_b128 v247, v[128:131] offset:3072
	ds_read_b128 v[116:119], v248
	ds_read_b128 v[120:123], v249
	ds_read_b128 v[124:127], v250
	ds_read_b128 v[128:131], v251
	ds_write_b128 v112, v[132:135]
	ds_write_b128 v112, v[136:139] offset:1024
	ds_write_b128 v112, v[140:143] offset:2048
	ds_write_b128 v112, v[144:147] offset:3072
	v_mfma_f32_32x32x16_bf16 v[0:15], v[64:67], v[72:75], v[0:15]
	v_mfma_f32_32x32x16_bf16 v[16:31], v[64:67], v[76:79], v[16:31]
	v_mfma_f32_32x32x16_bf16 v[0:15], v[68:71], v[220:223], v[0:15]
	v_mfma_f32_32x32x16_bf16 v[16:31], v[68:71], v[224:227], v[16:31]
	v_exp_f32_e32 v192, v192
	v_exp_f32_e32 v193, v193
	v_exp_f32_e32 v194, v194
	v_exp_f32_e32 v195, v195
	s_waitcnt lgkmcnt(4)
	v_mfma_f32_32x32x16_bf16 v[32:47], v[116:119], v[48:51], v[32:47]
	v_exp_f32_e32 v196, v196
	v_exp_f32_e32 v197, v197
	v_mfma_f32_32x32x16_bf16 v[32:47], v[120:123], v[52:55], v[32:47]
	v_exp_f32_e32 v198, v198
	v_exp_f32_e32 v199, v199
	v_mfma_f32_32x32x16_bf16 v[32:47], v[124:127], v[56:59], v[32:47]
	v_exp_f32_e32 v200, v200
	v_exp_f32_e32 v201, v201
	v_mfma_f32_32x32x16_bf16 v[32:47], v[128:131], v[60:63], v[32:47]
	v_exp_f32_e32 v202, v202
	v_exp_f32_e32 v203, v203
	s_add_i32 s90, s76, 480
	v_add_u32_e32 v84, s90, v107
	v_add_u32_e32 v85, 0, v84
	v_add_u32_e32 v86, 1, v84
	v_add_u32_e32 v87, 2, v84
	v_add_u32_e32 v88, 3, v84
	v_cmp_gt_u32_e64 s[30:31], s98, v85
	v_cmp_gt_u32_e64 s[36:37], s98, v86
	v_cmp_gt_u32_e64 s[78:79], s98, v87
	v_cmp_gt_u32_e64 s[50:51], s98, v88
	v_cndmask_b32_e64 v188, 0, v188, s[30:31]
	v_add_u32_e32 v85, 8, v84
	v_cmp_gt_u32_e64 s[30:31], s98, v85
	v_cndmask_b32_e64 v189, 0, v189, s[36:37]
	v_add_u32_e32 v86, 9, v84
	v_cmp_gt_u32_e64 s[36:37], s98, v86
	v_cndmask_b32_e64 v190, 0, v190, s[78:79]
	v_add_u32_e32 v87, 10, v84
	v_cmp_gt_u32_e64 s[78:79], s98, v87
	v_cndmask_b32_e64 v191, 0, v191, s[50:51]
	v_add_u32_e32 v88, 11, v84
	v_cmp_gt_u32_e64 s[50:51], s98, v88
	v_cndmask_b32_e64 v192, 0, v192, s[30:31]
	v_add_u32_e32 v85, 16, v84
	v_cmp_gt_u32_e64 s[30:31], s98, v85
	v_cndmask_b32_e64 v193, 0, v193, s[36:37]
	v_add_u32_e32 v86, 17, v84
	v_cmp_gt_u32_e64 s[36:37], s98, v86
	v_cndmask_b32_e64 v194, 0, v194, s[78:79]
	v_add_u32_e32 v87, 18, v84
	v_cmp_gt_u32_e64 s[78:79], s98, v87
	v_cndmask_b32_e64 v195, 0, v195, s[50:51]
	v_add_u32_e32 v88, 19, v84
	v_cmp_gt_u32_e64 s[50:51], s98, v88
	v_cndmask_b32_e64 v196, 0, v196, s[30:31]
	v_add_u32_e32 v85, 24, v84
	v_cmp_gt_u32_e64 s[30:31], s98, v85
	v_cndmask_b32_e64 v197, 0, v197, s[36:37]
	v_add_u32_e32 v86, 25, v84
	v_cmp_gt_u32_e64 s[36:37], s98, v86
	v_cndmask_b32_e64 v198, 0, v198, s[78:79]
	v_add_u32_e32 v87, 26, v84
	v_cmp_gt_u32_e64 s[78:79], s98, v87
	v_cndmask_b32_e64 v199, 0, v199, s[50:51]
	v_add_u32_e32 v88, 27, v84
	v_cmp_gt_u32_e64 s[50:51], s98, v88
	v_nop
	v_cndmask_b32_e64 v200, 0, v200, s[30:31]
	v_cndmask_b32_e64 v201, 0, v201, s[36:37]
	v_cndmask_b32_e64 v202, 0, v202, s[78:79]
	v_cndmask_b32_e64 v203, 0, v203, s[50:51]
	v_cvt_pk_bf16_f32 v64, v188, v189
	v_cvt_pk_bf16_f32 v65, v190, v191
	v_cvt_pk_bf16_f32 v66, v192, v193
	v_cvt_pk_bf16_f32 v67, v194, v195
	v_cvt_pk_bf16_f32 v68, v196, v197
	v_cvt_pk_bf16_f32 v69, v198, v199
	v_cvt_pk_bf16_f32 v70, v200, v201
	v_cvt_pk_bf16_f32 v71, v202, v203
	v_pk_add_f32 v[232:233], v[232:233], v[188:189]
	v_pk_add_f32 v[232:233], v[232:233], v[190:191]
	v_pk_add_f32 v[232:233], v[232:233], v[192:193]
	v_pk_add_f32 v[232:233], v[232:233], v[194:195]
	v_pk_add_f32 v[232:233], v[232:233], v[196:197]
	v_pk_add_f32 v[232:233], v[232:233], v[198:199]
	v_pk_add_f32 v[232:233], v[232:233], v[200:201]
	v_pk_add_f32 v[232:233], v[232:233], v[202:203]
	ds_read2_b32 v[188:189], v115 offset0:170 offset1:171
	ds_read2_b32 v[190:191], v115 offset0:172 offset1:173
	ds_read2_b32 v[192:193], v115 offset0:178 offset1:179
	ds_read2_b32 v[194:195], v115 offset0:180 offset1:181
	ds_read2_b32 v[196:197], v115 offset0:187 offset1:188
	ds_read2_b32 v[198:199], v115 offset0:189 offset1:190
	ds_read2_b32 v[200:201], v115 offset0:195 offset1:196
	ds_read2_b32 v[202:203], v115 offset0:197 offset1:198
	s_add_i32 s90, s76, -256
	v_add_u32_e32 v80, s90, v239
	v_add_u32_e32 v83, s90, v240
	v_add_u32_e32 v99, s90, v241
	v_add_u32_e32 v253, s90, v242
	v_add_u32_e32 v254, s90, v101
	v_add_u32_e32 v255, s90, v150
	v_med3_i32 v80, v80, 0, s99
	v_med3_i32 v83, v83, 0, s99
	v_med3_i32 v99, v99, 0, s99
	v_med3_i32 v253, v253, 0, s99
	v_med3_i32 v254, v254, 0, s99
	v_med3_i32 v255, v255, 0, s99
	v_mad_u32_u24 v80, v80, s100, v252
	v_mad_u32_u24 v83, v83, s100, v252
	v_mad_u32_u24 v99, v99, s100, v252
	v_mad_u32_u24 v253, v253, s100, v252
	v_mad_u32_u24 v254, v254, s100, v153
	v_mad_u32_u24 v255, v255, s100, v153
	global_load_dwordx4 v[116:119], v80, s[82:83]
	global_load_dwordx4 v[120:123], v83, s[82:83]
	global_load_dwordx4 v[124:127], v99, s[82:83]
	global_load_dwordx4 v[128:131], v253, s[82:83]
	global_load_dwordx4 v[132:135], v254, s[82:83] offset:768
	global_load_dwordx4 v[136:139], v255, s[82:83] offset:768
	global_load_dwordx4 v[140:143], v254, s[82:83] offset:832
	global_load_dwordx4 v[144:147], v255, s[82:83] offset:832
	ds_read_b64_tr_b16 v[72:73], v231
	ds_read_b64_tr_b16 v[74:75], v231 offset:512
	ds_read_b64_tr_b16 v[76:77], v231 offset:2048
	ds_read_b64_tr_b16 v[78:79], v231 offset:2560
	ds_read_b64_tr_b16 v[220:221], v231 offset:1024
	ds_read_b64_tr_b16 v[222:223], v231 offset:1536
	ds_read_b64_tr_b16 v[224:225], v231 offset:3072
	ds_read_b64_tr_b16 v[226:227], v231 offset:3584
	v_exp_f32_e32 v32, v32
	v_exp_f32_e32 v33, v33
	v_exp_f32_e32 v34, v34
	v_exp_f32_e32 v35, v35
	s_waitcnt vmcnt(8)
	ds_write_b128 v247, v[156:159]
	ds_write_b128 v247, v[160:163] offset:1024
	ds_write_b128 v247, v[164:167] offset:2048
	ds_write_b128 v247, v[168:171] offset:3072
	ds_read_b128 v[156:159], v248
	ds_read_b128 v[160:163], v249
	ds_read_b128 v[164:167], v250
	ds_read_b128 v[168:171], v251
	ds_write_b128 v112, v[172:175]
	ds_write_b128 v112, v[176:179] offset:1024
	ds_write_b128 v112, v[180:183] offset:2048
	ds_write_b128 v112, v[184:187] offset:3072
	v_mfma_f32_32x32x16_bf16 v[0:15], v[64:67], v[204:207], v[0:15]
	v_mfma_f32_32x32x16_bf16 v[16:31], v[64:67], v[208:211], v[16:31]
	v_mfma_f32_32x32x16_bf16 v[0:15], v[68:71], v[212:215], v[0:15]
	v_mfma_f32_32x32x16_bf16 v[16:31], v[68:71], v[216:219], v[16:31]
	v_exp_f32_e32 v36, v36
	v_exp_f32_e32 v37, v37
	v_exp_f32_e32 v38, v38
	v_exp_f32_e32 v39, v39
	s_waitcnt lgkmcnt(4)
	v_mfma_f32_32x32x16_bf16 v[188:203], v[156:159], v[48:51], v[188:203]
	v_exp_f32_e32 v40, v40
	v_exp_f32_e32 v41, v41
	v_mfma_f32_32x32x16_bf16 v[188:203], v[160:163], v[52:55], v[188:203]
	v_exp_f32_e32 v42, v42
	v_exp_f32_e32 v43, v43
	v_mfma_f32_32x32x16_bf16 v[188:203], v[164:167], v[56:59], v[188:203]
	v_exp_f32_e32 v44, v44
	v_exp_f32_e32 v45, v45
	v_mfma_f32_32x32x16_bf16 v[188:203], v[168:171], v[60:63], v[188:203]
	v_exp_f32_e32 v46, v46
	v_exp_f32_e32 v47, v47
	s_add_i32 s90, s76, 512
	v_add_u32_e32 v84, s90, v107
	v_add_u32_e32 v85, 0, v84
	v_add_u32_e32 v86, 1, v84
	v_add_u32_e32 v87, 2, v84
	v_add_u32_e32 v88, 3, v84
	v_cmp_gt_u32_e64 s[30:31], s98, v85
	v_cmp_gt_u32_e64 s[36:37], s98, v86
	v_cmp_gt_u32_e64 s[78:79], s98, v87
	v_cmp_gt_u32_e64 s[50:51], s98, v88
	v_cndmask_b32_e64 v32, 0, v32, s[30:31]
	v_add_u32_e32 v85, 8, v84
	v_cmp_gt_u32_e64 s[30:31], s98, v85
	v_cndmask_b32_e64 v33, 0, v33, s[36:37]
	v_add_u32_e32 v86, 9, v84
	v_cmp_gt_u32_e64 s[36:37], s98, v86
	v_cndmask_b32_e64 v34, 0, v34, s[78:79]
	v_add_u32_e32 v87, 10, v84
	v_cmp_gt_u32_e64 s[78:79], s98, v87
	v_cndmask_b32_e64 v35, 0, v35, s[50:51]
	v_add_u32_e32 v88, 11, v84
	v_cmp_gt_u32_e64 s[50:51], s98, v88
	v_cndmask_b32_e64 v36, 0, v36, s[30:31]
	v_add_u32_e32 v85, 16, v84
	v_cmp_gt_u32_e64 s[30:31], s98, v85
	v_cndmask_b32_e64 v37, 0, v37, s[36:37]
	v_add_u32_e32 v86, 17, v84
	v_cmp_gt_u32_e64 s[36:37], s98, v86
	v_cndmask_b32_e64 v38, 0, v38, s[78:79]
	v_add_u32_e32 v87, 18, v84
	v_cmp_gt_u32_e64 s[78:79], s98, v87
	v_cndmask_b32_e64 v39, 0, v39, s[50:51]
	v_add_u32_e32 v88, 19, v84
	v_cmp_gt_u32_e64 s[50:51], s98, v88
	v_cndmask_b32_e64 v40, 0, v40, s[30:31]
	v_add_u32_e32 v85, 24, v84
	v_cmp_gt_u32_e64 s[30:31], s98, v85
	v_cndmask_b32_e64 v41, 0, v41, s[36:37]
	v_add_u32_e32 v86, 25, v84
	v_cmp_gt_u32_e64 s[36:37], s98, v86
	v_cndmask_b32_e64 v42, 0, v42, s[78:79]
	v_add_u32_e32 v87, 26, v84
	v_cmp_gt_u32_e64 s[78:79], s98, v87
	v_cndmask_b32_e64 v43, 0, v43, s[50:51]
	v_add_u32_e32 v88, 27, v84
	v_cmp_gt_u32_e64 s[50:51], s98, v88
	v_nop
	v_cndmask_b32_e64 v44, 0, v44, s[30:31]
	v_cndmask_b32_e64 v45, 0, v45, s[36:37]
	v_cndmask_b32_e64 v46, 0, v46, s[78:79]
	v_cndmask_b32_e64 v47, 0, v47, s[50:51]
	v_cvt_pk_bf16_f32 v64, v32, v33
	v_cvt_pk_bf16_f32 v65, v34, v35
	v_cvt_pk_bf16_f32 v66, v36, v37
	v_cvt_pk_bf16_f32 v67, v38, v39
	v_cvt_pk_bf16_f32 v68, v40, v41
	v_cvt_pk_bf16_f32 v69, v42, v43
	v_cvt_pk_bf16_f32 v70, v44, v45
	v_cvt_pk_bf16_f32 v71, v46, v47
	v_pk_add_f32 v[232:233], v[232:233], v[32:33]
	v_pk_add_f32 v[232:233], v[232:233], v[34:35]
	v_pk_add_f32 v[232:233], v[232:233], v[36:37]
	v_pk_add_f32 v[232:233], v[232:233], v[38:39]
	v_pk_add_f32 v[232:233], v[232:233], v[40:41]
	v_pk_add_f32 v[232:233], v[232:233], v[42:43]
	v_pk_add_f32 v[232:233], v[232:233], v[44:45]
	v_pk_add_f32 v[232:233], v[232:233], v[46:47]
	v_mov_b32_e32 v115, v229
	ds_read2_b32 v[32:33], v115 offset0:0 offset1:1
	ds_read2_b32 v[34:35], v115 offset0:2 offset1:3
	ds_read2_b32 v[36:37], v115 offset0:8 offset1:9
	ds_read2_b32 v[38:39], v115 offset0:10 offset1:11
	ds_read2_b32 v[40:41], v115 offset0:16 offset1:17
	ds_read2_b32 v[42:43], v115 offset0:18 offset1:19
	ds_read2_b32 v[44:45], v115 offset0:24 offset1:25
	ds_read2_b32 v[46:47], v115 offset0:26 offset1:27
	s_add_i32 s90, s76, -128
	v_add_u32_e32 v80, s90, v239
	v_add_u32_e32 v83, s90, v240
	v_add_u32_e32 v99, s90, v241
	v_add_u32_e32 v253, s90, v242
	v_add_u32_e32 v254, s90, v101
	v_add_u32_e32 v255, s90, v150
	v_med3_i32 v80, v80, 0, s99
	v_med3_i32 v83, v83, 0, s99
	v_med3_i32 v99, v99, 0, s99
	v_med3_i32 v253, v253, 0, s99
	v_med3_i32 v254, v254, 0, s99
	v_med3_i32 v255, v255, 0, s99
	v_mad_u32_u24 v80, v80, s100, v252
	v_mad_u32_u24 v83, v83, s100, v252
	v_mad_u32_u24 v99, v99, s100, v252
	v_mad_u32_u24 v253, v253, s100, v252
	v_mad_u32_u24 v254, v254, s100, v153
	v_mad_u32_u24 v255, v255, s100, v153
	global_load_dwordx4 v[156:159], v80, s[82:83]
	global_load_dwordx4 v[160:163], v83, s[82:83]
	global_load_dwordx4 v[164:167], v99, s[82:83]
	global_load_dwordx4 v[168:171], v253, s[82:83]
	global_load_dwordx4 v[172:175], v254, s[82:83] offset:768
	global_load_dwordx4 v[176:179], v255, s[82:83] offset:768
	global_load_dwordx4 v[180:183], v254, s[82:83] offset:832
	global_load_dwordx4 v[184:187], v255, s[82:83] offset:832
	ds_read_b64_tr_b16 v[204:205], v231
	ds_read_b64_tr_b16 v[206:207], v231 offset:512
	ds_read_b64_tr_b16 v[208:209], v231 offset:2048
	ds_read_b64_tr_b16 v[210:211], v231 offset:2560
	ds_read_b64_tr_b16 v[212:213], v231 offset:1024
	ds_read_b64_tr_b16 v[214:215], v231 offset:1536
	ds_read_b64_tr_b16 v[216:217], v231 offset:3072
	ds_read_b64_tr_b16 v[218:219], v231 offset:3584
	v_exp_f32_e32 v188, v188
	v_exp_f32_e32 v189, v189
	v_exp_f32_e32 v190, v190
	v_exp_f32_e32 v191, v191
	s_waitcnt vmcnt(8)
	ds_write_b128 v247, v[116:119]
	ds_write_b128 v247, v[120:123] offset:1024
	ds_write_b128 v247, v[124:127] offset:2048
	ds_write_b128 v247, v[128:131] offset:3072
	ds_read_b128 v[116:119], v248
	ds_read_b128 v[120:123], v249
	ds_read_b128 v[124:127], v250
	ds_read_b128 v[128:131], v251
	ds_write_b128 v112, v[132:135]
	ds_write_b128 v112, v[136:139] offset:1024
	ds_write_b128 v112, v[140:143] offset:2048
	ds_write_b128 v112, v[144:147] offset:3072
	v_mfma_f32_32x32x16_bf16 v[0:15], v[64:67], v[72:75], v[0:15]
	v_mfma_f32_32x32x16_bf16 v[16:31], v[64:67], v[76:79], v[16:31]
	v_mfma_f32_32x32x16_bf16 v[0:15], v[68:71], v[220:223], v[0:15]
	v_mfma_f32_32x32x16_bf16 v[16:31], v[68:71], v[224:227], v[16:31]
	v_exp_f32_e32 v192, v192
	v_exp_f32_e32 v193, v193
	v_exp_f32_e32 v194, v194
	v_exp_f32_e32 v195, v195
	s_waitcnt lgkmcnt(4)
	v_mfma_f32_32x32x16_bf16 v[32:47], v[116:119], v[48:51], v[32:47]
	v_exp_f32_e32 v196, v196
	v_exp_f32_e32 v197, v197
	v_mfma_f32_32x32x16_bf16 v[32:47], v[120:123], v[52:55], v[32:47]
	v_exp_f32_e32 v198, v198
	v_exp_f32_e32 v199, v199
	v_mfma_f32_32x32x16_bf16 v[32:47], v[124:127], v[56:59], v[32:47]
	v_exp_f32_e32 v200, v200
	v_exp_f32_e32 v201, v201
	v_mfma_f32_32x32x16_bf16 v[32:47], v[128:131], v[60:63], v[32:47]
	v_exp_f32_e32 v202, v202
	v_exp_f32_e32 v203, v203
	s_add_i32 s90, s76, 544
	v_add_u32_e32 v84, s90, v107
	v_add_u32_e32 v85, 0, v84
	v_add_u32_e32 v86, 1, v84
	v_add_u32_e32 v87, 2, v84
	v_add_u32_e32 v88, 3, v84
	v_cmp_gt_u32_e64 s[30:31], s98, v85
	v_cmp_gt_u32_e64 s[36:37], s98, v86
	v_cmp_gt_u32_e64 s[78:79], s98, v87
	v_cmp_gt_u32_e64 s[50:51], s98, v88
	v_cndmask_b32_e64 v188, 0, v188, s[30:31]
	v_add_u32_e32 v85, 8, v84
	v_cmp_gt_u32_e64 s[30:31], s98, v85
	v_cndmask_b32_e64 v189, 0, v189, s[36:37]
	v_add_u32_e32 v86, 9, v84
	v_cmp_gt_u32_e64 s[36:37], s98, v86
	v_cndmask_b32_e64 v190, 0, v190, s[78:79]
	v_add_u32_e32 v87, 10, v84
	v_cmp_gt_u32_e64 s[78:79], s98, v87
	v_cndmask_b32_e64 v191, 0, v191, s[50:51]
	v_add_u32_e32 v88, 11, v84
	v_cmp_gt_u32_e64 s[50:51], s98, v88
	v_cndmask_b32_e64 v192, 0, v192, s[30:31]
	v_add_u32_e32 v85, 16, v84
	v_cmp_gt_u32_e64 s[30:31], s98, v85
	v_cndmask_b32_e64 v193, 0, v193, s[36:37]
	v_add_u32_e32 v86, 17, v84
	v_cmp_gt_u32_e64 s[36:37], s98, v86
	v_cndmask_b32_e64 v194, 0, v194, s[78:79]
	v_add_u32_e32 v87, 18, v84
	v_cmp_gt_u32_e64 s[78:79], s98, v87
	v_cndmask_b32_e64 v195, 0, v195, s[50:51]
	v_add_u32_e32 v88, 19, v84
	v_cmp_gt_u32_e64 s[50:51], s98, v88
	v_cndmask_b32_e64 v196, 0, v196, s[30:31]
	v_add_u32_e32 v85, 24, v84
	v_cmp_gt_u32_e64 s[30:31], s98, v85
	v_cndmask_b32_e64 v197, 0, v197, s[36:37]
	v_add_u32_e32 v86, 25, v84
	v_cmp_gt_u32_e64 s[36:37], s98, v86
	v_cndmask_b32_e64 v198, 0, v198, s[78:79]
	v_add_u32_e32 v87, 26, v84
	v_cmp_gt_u32_e64 s[78:79], s98, v87
	v_cndmask_b32_e64 v199, 0, v199, s[50:51]
	v_add_u32_e32 v88, 27, v84
	v_cmp_gt_u32_e64 s[50:51], s98, v88
	v_nop
	v_cndmask_b32_e64 v200, 0, v200, s[30:31]
	v_cndmask_b32_e64 v201, 0, v201, s[36:37]
	v_cndmask_b32_e64 v202, 0, v202, s[78:79]
	v_cndmask_b32_e64 v203, 0, v203, s[50:51]
	v_cvt_pk_bf16_f32 v64, v188, v189
	v_cvt_pk_bf16_f32 v65, v190, v191
	v_cvt_pk_bf16_f32 v66, v192, v193
	v_cvt_pk_bf16_f32 v67, v194, v195
	v_cvt_pk_bf16_f32 v68, v196, v197
	v_cvt_pk_bf16_f32 v69, v198, v199
	v_cvt_pk_bf16_f32 v70, v200, v201
	v_cvt_pk_bf16_f32 v71, v202, v203
	v_pk_add_f32 v[232:233], v[232:233], v[188:189]
	v_pk_add_f32 v[232:233], v[232:233], v[190:191]
	v_pk_add_f32 v[232:233], v[232:233], v[192:193]
	v_pk_add_f32 v[232:233], v[232:233], v[194:195]
	v_pk_add_f32 v[232:233], v[232:233], v[196:197]
	v_pk_add_f32 v[232:233], v[232:233], v[198:199]
	v_pk_add_f32 v[232:233], v[232:233], v[200:201]
	v_pk_add_f32 v[232:233], v[232:233], v[202:203]
	ds_read2_b32 v[188:189], v115 offset0:32 offset1:33
	ds_read2_b32 v[190:191], v115 offset0:34 offset1:35
	ds_read2_b32 v[192:193], v115 offset0:40 offset1:41
	ds_read2_b32 v[194:195], v115 offset0:42 offset1:43
	ds_read2_b32 v[196:197], v115 offset0:48 offset1:49
	ds_read2_b32 v[198:199], v115 offset0:50 offset1:51
	ds_read2_b32 v[200:201], v115 offset0:56 offset1:57
	ds_read2_b32 v[202:203], v115 offset0:58 offset1:59
	s_add_i32 s90, s76, 0
	v_add_u32_e32 v80, s90, v239
	v_add_u32_e32 v83, s90, v240
	v_add_u32_e32 v99, s90, v241
	v_add_u32_e32 v253, s90, v242
	v_add_u32_e32 v254, s90, v101
	v_add_u32_e32 v255, s90, v150
	v_med3_i32 v80, v80, 0, s99
	v_med3_i32 v83, v83, 0, s99
	v_med3_i32 v99, v99, 0, s99
	v_med3_i32 v253, v253, 0, s99
	v_med3_i32 v254, v254, 0, s99
	v_med3_i32 v255, v255, 0, s99
	v_mad_u32_u24 v80, v80, s100, v252
	v_mad_u32_u24 v83, v83, s100, v252
	v_mad_u32_u24 v99, v99, s100, v252
	v_mad_u32_u24 v253, v253, s100, v252
	v_mad_u32_u24 v254, v254, s100, v153
	v_mad_u32_u24 v255, v255, s100, v153
	global_load_dwordx4 v[116:119], v80, s[82:83]
	global_load_dwordx4 v[120:123], v83, s[82:83]
	global_load_dwordx4 v[124:127], v99, s[82:83]
	global_load_dwordx4 v[128:131], v253, s[82:83]
	global_load_dwordx4 v[132:135], v254, s[82:83] offset:768
	global_load_dwordx4 v[136:139], v255, s[82:83] offset:768
	global_load_dwordx4 v[140:143], v254, s[82:83] offset:832
	global_load_dwordx4 v[144:147], v255, s[82:83] offset:832
	ds_read_b64_tr_b16 v[72:73], v231
	ds_read_b64_tr_b16 v[74:75], v231 offset:512
	ds_read_b64_tr_b16 v[76:77], v231 offset:2048
	ds_read_b64_tr_b16 v[78:79], v231 offset:2560
	ds_read_b64_tr_b16 v[220:221], v231 offset:1024
	ds_read_b64_tr_b16 v[222:223], v231 offset:1536
	ds_read_b64_tr_b16 v[224:225], v231 offset:3072
	ds_read_b64_tr_b16 v[226:227], v231 offset:3584
	v_exp_f32_e32 v32, v32
	v_exp_f32_e32 v33, v33
	v_exp_f32_e32 v34, v34
	v_exp_f32_e32 v35, v35
	s_waitcnt vmcnt(8)
	ds_write_b128 v247, v[156:159]
	ds_write_b128 v247, v[160:163] offset:1024
	ds_write_b128 v247, v[164:167] offset:2048
	ds_write_b128 v247, v[168:171] offset:3072
	ds_read_b128 v[156:159], v248
	ds_read_b128 v[160:163], v249
	ds_read_b128 v[164:167], v250
	ds_read_b128 v[168:171], v251
	ds_write_b128 v112, v[172:175]
	ds_write_b128 v112, v[176:179] offset:1024
	ds_write_b128 v112, v[180:183] offset:2048
	ds_write_b128 v112, v[184:187] offset:3072
	v_mfma_f32_32x32x16_bf16 v[0:15], v[64:67], v[204:207], v[0:15]
	v_mfma_f32_32x32x16_bf16 v[16:31], v[64:67], v[208:211], v[16:31]
	v_mfma_f32_32x32x16_bf16 v[0:15], v[68:71], v[212:215], v[0:15]
	v_mfma_f32_32x32x16_bf16 v[16:31], v[68:71], v[216:219], v[16:31]
	v_exp_f32_e32 v36, v36
	v_exp_f32_e32 v37, v37
	v_exp_f32_e32 v38, v38
	v_exp_f32_e32 v39, v39
	s_waitcnt lgkmcnt(4)
	v_mfma_f32_32x32x16_bf16 v[188:203], v[156:159], v[48:51], v[188:203]
	v_exp_f32_e32 v40, v40
	v_exp_f32_e32 v41, v41
	v_mfma_f32_32x32x16_bf16 v[188:203], v[160:163], v[52:55], v[188:203]
	v_exp_f32_e32 v42, v42
	v_exp_f32_e32 v43, v43
	v_mfma_f32_32x32x16_bf16 v[188:203], v[164:167], v[56:59], v[188:203]
	v_exp_f32_e32 v44, v44
	v_exp_f32_e32 v45, v45
	v_mfma_f32_32x32x16_bf16 v[188:203], v[168:171], v[60:63], v[188:203]
	v_exp_f32_e32 v46, v46
	v_exp_f32_e32 v47, v47
	s_add_i32 s90, s76, -256
	v_lshlrev_b32_e32 v84, 2, v107
	v_add_u32_e32 v84, s90, v84
	v_add_u32_e32 v85, 0, v84
	v_add_u32_e32 v86, 4, v84
	v_add_u32_e32 v87, 8, v84
	v_add_u32_e32 v88, 12, v84
	v_cmp_gt_u32_e64 s[30:31], s98, v85
	v_cmp_gt_u32_e64 s[36:37], s98, v86
	v_cmp_gt_u32_e64 s[78:79], s98, v87
	v_cmp_gt_u32_e64 s[50:51], s98, v88
	v_cndmask_b32_e64 v32, 0, v32, s[30:31]
	v_add_u32_e32 v85, 32, v84
	v_cmp_gt_u32_e64 s[30:31], s98, v85
	v_cndmask_b32_e64 v33, 0, v33, s[36:37]
	v_add_u32_e32 v86, 36, v84
	v_cmp_gt_u32_e64 s[36:37], s98, v86
	v_cndmask_b32_e64 v34, 0, v34, s[78:79]
	v_add_u32_e32 v87, 40, v84
	v_cmp_gt_u32_e64 s[78:79], s98, v87
	v_cndmask_b32_e64 v35, 0, v35, s[50:51]
	v_add_u32_e32 v88, 44, v84
	v_cmp_gt_u32_e64 s[50:51], s98, v88
	v_cndmask_b32_e64 v36, 0, v36, s[30:31]
	v_add_u32_e32 v85, 64, v84
	v_cmp_gt_u32_e64 s[30:31], s98, v85
	v_cndmask_b32_e64 v37, 0, v37, s[36:37]
	v_add_u32_e32 v86, 68, v84
	v_cmp_gt_u32_e64 s[36:37], s98, v86
	v_cndmask_b32_e64 v38, 0, v38, s[78:79]
	v_add_u32_e32 v87, 72, v84
	v_cmp_gt_u32_e64 s[78:79], s98, v87
	v_cndmask_b32_e64 v39, 0, v39, s[50:51]
	v_add_u32_e32 v88, 76, v84
	v_cmp_gt_u32_e64 s[50:51], s98, v88
	v_cndmask_b32_e64 v40, 0, v40, s[30:31]
	v_add_u32_e32 v85, 96, v84
	v_cmp_gt_u32_e64 s[30:31], s98, v85
	v_cndmask_b32_e64 v41, 0, v41, s[36:37]
	v_add_u32_e32 v86, 100, v84
	v_cmp_gt_u32_e64 s[36:37], s98, v86
	v_cndmask_b32_e64 v42, 0, v42, s[78:79]
	v_add_u32_e32 v87, 104, v84
	v_cmp_gt_u32_e64 s[78:79], s98, v87
	v_cndmask_b32_e64 v43, 0, v43, s[50:51]
	v_add_u32_e32 v88, 108, v84
	v_cmp_gt_u32_e64 s[50:51], s98, v88
	v_nop
	v_cndmask_b32_e64 v44, 0, v44, s[30:31]
	v_cndmask_b32_e64 v45, 0, v45, s[36:37]
	v_cndmask_b32_e64 v46, 0, v46, s[78:79]
	v_cndmask_b32_e64 v47, 0, v47, s[50:51]
	v_cvt_pk_bf16_f32 v64, v32, v33
	v_cvt_pk_bf16_f32 v65, v34, v35
	v_cvt_pk_bf16_f32 v66, v36, v37
	v_cvt_pk_bf16_f32 v67, v38, v39
	v_cvt_pk_bf16_f32 v68, v40, v41
	v_cvt_pk_bf16_f32 v69, v42, v43
	v_cvt_pk_bf16_f32 v70, v44, v45
	v_cvt_pk_bf16_f32 v71, v46, v47
	v_pk_add_f32 v[232:233], v[232:233], v[32:33]
	v_pk_add_f32 v[232:233], v[232:233], v[34:35]
	v_pk_add_f32 v[232:233], v[232:233], v[36:37]
	v_pk_add_f32 v[232:233], v[232:233], v[38:39]
	v_pk_add_f32 v[232:233], v[232:233], v[40:41]
	v_pk_add_f32 v[232:233], v[232:233], v[42:43]
	v_pk_add_f32 v[232:233], v[232:233], v[44:45]
	v_pk_add_f32 v[232:233], v[232:233], v[46:47]
	ds_read2_b32 v[32:33], v115 offset0:64 offset1:65
	ds_read2_b32 v[34:35], v115 offset0:66 offset1:67
	ds_read2_b32 v[36:37], v115 offset0:72 offset1:73
	ds_read2_b32 v[38:39], v115 offset0:74 offset1:75
	ds_read2_b32 v[40:41], v115 offset0:80 offset1:81
	ds_read2_b32 v[42:43], v115 offset0:82 offset1:83
	ds_read2_b32 v[44:45], v115 offset0:88 offset1:89
	ds_read2_b32 v[46:47], v115 offset0:90 offset1:91
	s_add_i32 s90, s76, 128
	v_add_u32_e32 v80, s90, v239
	v_add_u32_e32 v83, s90, v240
	v_add_u32_e32 v99, s90, v241
	v_add_u32_e32 v253, s90, v242
	v_add_u32_e32 v254, s90, v101
	v_add_u32_e32 v255, s90, v150
	v_med3_i32 v80, v80, 0, s99
	v_med3_i32 v83, v83, 0, s99
	v_med3_i32 v99, v99, 0, s99
	v_med3_i32 v253, v253, 0, s99
	v_med3_i32 v254, v254, 0, s99
	v_med3_i32 v255, v255, 0, s99
	v_mad_u32_u24 v80, v80, s100, v252
	v_mad_u32_u24 v83, v83, s100, v252
	v_mad_u32_u24 v99, v99, s100, v252
	v_mad_u32_u24 v253, v253, s100, v252
	v_mad_u32_u24 v254, v254, s100, v153
	v_mad_u32_u24 v255, v255, s100, v153
	global_load_dwordx4 v[156:159], v80, s[82:83]
	global_load_dwordx4 v[160:163], v83, s[82:83]
	global_load_dwordx4 v[164:167], v99, s[82:83]
	global_load_dwordx4 v[168:171], v253, s[82:83]
	global_load_dwordx4 v[172:175], v254, s[82:83] offset:768
	global_load_dwordx4 v[176:179], v255, s[82:83] offset:768
	global_load_dwordx4 v[180:183], v254, s[82:83] offset:832
	global_load_dwordx4 v[184:187], v255, s[82:83] offset:832
	ds_read_b64_tr_b16 v[204:205], v231
	ds_read_b64_tr_b16 v[206:207], v231 offset:512
	ds_read_b64_tr_b16 v[208:209], v231 offset:2048
	ds_read_b64_tr_b16 v[210:211], v231 offset:2560
	ds_read_b64_tr_b16 v[212:213], v231 offset:1024
	ds_read_b64_tr_b16 v[214:215], v231 offset:1536
	ds_read_b64_tr_b16 v[216:217], v231 offset:3072
	ds_read_b64_tr_b16 v[218:219], v231 offset:3584
	v_exp_f32_e32 v188, v188
	v_exp_f32_e32 v189, v189
	v_exp_f32_e32 v190, v190
	v_exp_f32_e32 v191, v191
	s_waitcnt vmcnt(8)
	ds_write_b128 v247, v[116:119]
	ds_write_b128 v247, v[120:123] offset:1024
	ds_write_b128 v247, v[124:127] offset:2048
	ds_write_b128 v247, v[128:131] offset:3072
	ds_read_b128 v[116:119], v248
	ds_read_b128 v[120:123], v249
	ds_read_b128 v[124:127], v250
	ds_read_b128 v[128:131], v251
	ds_write_b128 v112, v[132:135]
	ds_write_b128 v112, v[136:139] offset:1024
	ds_write_b128 v112, v[140:143] offset:2048
	ds_write_b128 v112, v[144:147] offset:3072
	v_mfma_f32_32x32x16_bf16 v[0:15], v[64:67], v[72:75], v[0:15]
	v_mfma_f32_32x32x16_bf16 v[16:31], v[64:67], v[76:79], v[16:31]
	v_mfma_f32_32x32x16_bf16 v[0:15], v[68:71], v[220:223], v[0:15]
	v_mfma_f32_32x32x16_bf16 v[16:31], v[68:71], v[224:227], v[16:31]
	v_exp_f32_e32 v192, v192
	v_exp_f32_e32 v193, v193
	v_exp_f32_e32 v194, v194
	v_exp_f32_e32 v195, v195
	s_waitcnt lgkmcnt(4)
	v_mfma_f32_32x32x16_bf16 v[32:47], v[116:119], v[48:51], v[32:47]
	v_exp_f32_e32 v196, v196
	v_exp_f32_e32 v197, v197
	v_mfma_f32_32x32x16_bf16 v[32:47], v[120:123], v[52:55], v[32:47]
	v_exp_f32_e32 v198, v198
	v_exp_f32_e32 v199, v199
	v_mfma_f32_32x32x16_bf16 v[32:47], v[124:127], v[56:59], v[32:47]
	v_exp_f32_e32 v200, v200
	v_exp_f32_e32 v201, v201
	v_mfma_f32_32x32x16_bf16 v[32:47], v[128:131], v[60:63], v[32:47]
	v_exp_f32_e32 v202, v202
	v_exp_f32_e32 v203, v203
	s_add_i32 s90, s76, -128
	v_lshlrev_b32_e32 v84, 2, v107
	v_add_u32_e32 v84, s90, v84
	v_add_u32_e32 v85, 0, v84
	v_add_u32_e32 v86, 4, v84
	v_add_u32_e32 v87, 8, v84
	v_add_u32_e32 v88, 12, v84
	v_cmp_gt_u32_e64 s[30:31], s98, v85
	v_cmp_gt_u32_e64 s[36:37], s98, v86
	v_cmp_gt_u32_e64 s[78:79], s98, v87
	v_cmp_gt_u32_e64 s[50:51], s98, v88
	v_cndmask_b32_e64 v188, 0, v188, s[30:31]
	v_add_u32_e32 v85, 32, v84
	v_cmp_gt_u32_e64 s[30:31], s98, v85
	v_cndmask_b32_e64 v189, 0, v189, s[36:37]
	v_add_u32_e32 v86, 36, v84
	v_cmp_gt_u32_e64 s[36:37], s98, v86
	v_cndmask_b32_e64 v190, 0, v190, s[78:79]
	v_add_u32_e32 v87, 40, v84
	v_cmp_gt_u32_e64 s[78:79], s98, v87
	v_cndmask_b32_e64 v191, 0, v191, s[50:51]
	v_add_u32_e32 v88, 44, v84
	v_cmp_gt_u32_e64 s[50:51], s98, v88
	v_cndmask_b32_e64 v192, 0, v192, s[30:31]
	v_add_u32_e32 v85, 64, v84
	v_cmp_gt_u32_e64 s[30:31], s98, v85
	v_cndmask_b32_e64 v193, 0, v193, s[36:37]
	v_add_u32_e32 v86, 68, v84
	v_cmp_gt_u32_e64 s[36:37], s98, v86
	v_cndmask_b32_e64 v194, 0, v194, s[78:79]
	v_add_u32_e32 v87, 72, v84
	v_cmp_gt_u32_e64 s[78:79], s98, v87
	v_cndmask_b32_e64 v195, 0, v195, s[50:51]
	v_add_u32_e32 v88, 76, v84
	v_cmp_gt_u32_e64 s[50:51], s98, v88
	v_cndmask_b32_e64 v196, 0, v196, s[30:31]
	v_add_u32_e32 v85, 96, v84
	v_cmp_gt_u32_e64 s[30:31], s98, v85
	v_cndmask_b32_e64 v197, 0, v197, s[36:37]
	v_add_u32_e32 v86, 100, v84
	v_cmp_gt_u32_e64 s[36:37], s98, v86
	v_cndmask_b32_e64 v198, 0, v198, s[78:79]
	v_add_u32_e32 v87, 104, v84
	v_cmp_gt_u32_e64 s[78:79], s98, v87
	v_cndmask_b32_e64 v199, 0, v199, s[50:51]
	v_add_u32_e32 v88, 108, v84
	v_cmp_gt_u32_e64 s[50:51], s98, v88
	v_nop
	v_cndmask_b32_e64 v200, 0, v200, s[30:31]
	v_cndmask_b32_e64 v201, 0, v201, s[36:37]
	v_cndmask_b32_e64 v202, 0, v202, s[78:79]
	v_cndmask_b32_e64 v203, 0, v203, s[50:51]
	v_cvt_pk_bf16_f32 v64, v188, v189
	v_cvt_pk_bf16_f32 v65, v190, v191
	v_cvt_pk_bf16_f32 v66, v192, v193
	v_cvt_pk_bf16_f32 v67, v194, v195
	v_cvt_pk_bf16_f32 v68, v196, v197
	v_cvt_pk_bf16_f32 v69, v198, v199
	v_cvt_pk_bf16_f32 v70, v200, v201
	v_cvt_pk_bf16_f32 v71, v202, v203
	v_pk_add_f32 v[232:233], v[232:233], v[188:189]
	v_pk_add_f32 v[232:233], v[232:233], v[190:191]
	v_pk_add_f32 v[232:233], v[232:233], v[192:193]
	v_pk_add_f32 v[232:233], v[232:233], v[194:195]
	v_pk_add_f32 v[232:233], v[232:233], v[196:197]
	v_pk_add_f32 v[232:233], v[232:233], v[198:199]
	v_pk_add_f32 v[232:233], v[232:233], v[200:201]
	v_pk_add_f32 v[232:233], v[232:233], v[202:203]
	ds_read2_b32 v[188:189], v115 offset0:96 offset1:97
	ds_read2_b32 v[190:191], v115 offset0:98 offset1:99
	ds_read2_b32 v[192:193], v115 offset0:104 offset1:105
	ds_read2_b32 v[194:195], v115 offset0:106 offset1:107
	ds_read2_b32 v[196:197], v115 offset0:112 offset1:113
	ds_read2_b32 v[198:199], v115 offset0:114 offset1:115
	ds_read2_b32 v[200:201], v115 offset0:120 offset1:121
	ds_read2_b32 v[202:203], v115 offset0:122 offset1:123
	s_add_i32 s90, s76, 256
	v_add_u32_e32 v80, s90, v239
	v_add_u32_e32 v83, s90, v240
	v_add_u32_e32 v99, s90, v241
	v_add_u32_e32 v253, s90, v242
	v_add_u32_e32 v254, s90, v101
	v_add_u32_e32 v255, s90, v150
	v_med3_i32 v80, v80, 0, s99
	v_med3_i32 v83, v83, 0, s99
	v_med3_i32 v99, v99, 0, s99
	v_med3_i32 v253, v253, 0, s99
	v_med3_i32 v254, v254, 0, s99
	v_med3_i32 v255, v255, 0, s99
	v_mad_u32_u24 v80, v80, s100, v252
	v_mad_u32_u24 v83, v83, s100, v252
	v_mad_u32_u24 v99, v99, s100, v252
	v_mad_u32_u24 v253, v253, s100, v252
	v_mad_u32_u24 v254, v254, s100, v153
	v_mad_u32_u24 v255, v255, s100, v153
	global_load_dwordx4 v[116:119], v80, s[82:83]
	global_load_dwordx4 v[120:123], v83, s[82:83]
	global_load_dwordx4 v[124:127], v99, s[82:83]
	global_load_dwordx4 v[128:131], v253, s[82:83]
	global_load_dwordx4 v[132:135], v254, s[82:83] offset:768
	global_load_dwordx4 v[136:139], v255, s[82:83] offset:768
	global_load_dwordx4 v[140:143], v254, s[82:83] offset:832
	global_load_dwordx4 v[144:147], v255, s[82:83] offset:832
	ds_read_b64_tr_b16 v[72:73], v231
	ds_read_b64_tr_b16 v[74:75], v231 offset:512
	ds_read_b64_tr_b16 v[76:77], v231 offset:2048
	ds_read_b64_tr_b16 v[78:79], v231 offset:2560
	ds_read_b64_tr_b16 v[220:221], v231 offset:1024
	ds_read_b64_tr_b16 v[222:223], v231 offset:1536
	ds_read_b64_tr_b16 v[224:225], v231 offset:3072
	ds_read_b64_tr_b16 v[226:227], v231 offset:3584
	v_exp_f32_e32 v32, v32
	v_exp_f32_e32 v33, v33
	v_exp_f32_e32 v34, v34
	v_exp_f32_e32 v35, v35
	s_waitcnt vmcnt(8)
	ds_write_b128 v247, v[156:159]
	ds_write_b128 v247, v[160:163] offset:1024
	ds_write_b128 v247, v[164:167] offset:2048
	ds_write_b128 v247, v[168:171] offset:3072
	ds_read_b128 v[156:159], v248
	ds_read_b128 v[160:163], v249
	ds_read_b128 v[164:167], v250
	ds_read_b128 v[168:171], v251
	ds_write_b128 v112, v[172:175]
	ds_write_b128 v112, v[176:179] offset:1024
	ds_write_b128 v112, v[180:183] offset:2048
	ds_write_b128 v112, v[184:187] offset:3072
	v_mfma_f32_32x32x16_bf16 v[0:15], v[64:67], v[204:207], v[0:15]
	v_mfma_f32_32x32x16_bf16 v[16:31], v[64:67], v[208:211], v[16:31]
	v_mfma_f32_32x32x16_bf16 v[0:15], v[68:71], v[212:215], v[0:15]
	v_mfma_f32_32x32x16_bf16 v[16:31], v[68:71], v[216:219], v[16:31]
	v_exp_f32_e32 v36, v36
	v_exp_f32_e32 v37, v37
	v_exp_f32_e32 v38, v38
	v_exp_f32_e32 v39, v39
	s_waitcnt lgkmcnt(4)
	v_mfma_f32_32x32x16_bf16 v[188:203], v[156:159], v[48:51], v[188:203]
	v_exp_f32_e32 v40, v40
	v_exp_f32_e32 v41, v41
	v_mfma_f32_32x32x16_bf16 v[188:203], v[160:163], v[52:55], v[188:203]
	v_exp_f32_e32 v42, v42
	v_exp_f32_e32 v43, v43
	v_mfma_f32_32x32x16_bf16 v[188:203], v[164:167], v[56:59], v[188:203]
	v_exp_f32_e32 v44, v44
	v_exp_f32_e32 v45, v45
	v_mfma_f32_32x32x16_bf16 v[188:203], v[168:171], v[60:63], v[188:203]
	v_exp_f32_e32 v46, v46
	v_exp_f32_e32 v47, v47
	s_add_i32 s90, s76, 0
	v_lshlrev_b32_e32 v84, 2, v107
	v_add_u32_e32 v84, s90, v84
	v_add_u32_e32 v85, 0, v84
	v_add_u32_e32 v86, 4, v84
	v_add_u32_e32 v87, 8, v84
	v_add_u32_e32 v88, 12, v84
	v_cmp_gt_u32_e64 s[30:31], s98, v85
	v_cmp_gt_u32_e64 s[36:37], s98, v86
	v_cmp_gt_u32_e64 s[78:79], s98, v87
	v_cmp_gt_u32_e64 s[50:51], s98, v88
	v_cndmask_b32_e64 v32, 0, v32, s[30:31]
	v_add_u32_e32 v85, 32, v84
	v_cmp_gt_u32_e64 s[30:31], s98, v85
	v_cndmask_b32_e64 v33, 0, v33, s[36:37]
	v_add_u32_e32 v86, 36, v84
	v_cmp_gt_u32_e64 s[36:37], s98, v86
	v_cndmask_b32_e64 v34, 0, v34, s[78:79]
	v_add_u32_e32 v87, 40, v84
	v_cmp_gt_u32_e64 s[78:79], s98, v87
	v_cndmask_b32_e64 v35, 0, v35, s[50:51]
	v_add_u32_e32 v88, 44, v84
	v_cmp_gt_u32_e64 s[50:51], s98, v88
	v_cndmask_b32_e64 v36, 0, v36, s[30:31]
	v_add_u32_e32 v85, 64, v84
	v_cmp_gt_u32_e64 s[30:31], s98, v85
	v_cndmask_b32_e64 v37, 0, v37, s[36:37]
	v_add_u32_e32 v86, 68, v84
	v_cmp_gt_u32_e64 s[36:37], s98, v86
	v_cndmask_b32_e64 v38, 0, v38, s[78:79]
	v_add_u32_e32 v87, 72, v84
	v_cmp_gt_u32_e64 s[78:79], s98, v87
	v_cndmask_b32_e64 v39, 0, v39, s[50:51]
	v_add_u32_e32 v88, 76, v84
	v_cmp_gt_u32_e64 s[50:51], s98, v88
	v_cndmask_b32_e64 v40, 0, v40, s[30:31]
	v_add_u32_e32 v85, 96, v84
	v_cmp_gt_u32_e64 s[30:31], s98, v85
	v_cndmask_b32_e64 v41, 0, v41, s[36:37]
	v_add_u32_e32 v86, 100, v84
	v_cmp_gt_u32_e64 s[36:37], s98, v86
	v_cndmask_b32_e64 v42, 0, v42, s[78:79]
	v_add_u32_e32 v87, 104, v84
	v_cmp_gt_u32_e64 s[78:79], s98, v87
	v_cndmask_b32_e64 v43, 0, v43, s[50:51]
	v_add_u32_e32 v88, 108, v84
	v_cmp_gt_u32_e64 s[50:51], s98, v88
	v_nop
	v_cndmask_b32_e64 v44, 0, v44, s[30:31]
	v_cndmask_b32_e64 v45, 0, v45, s[36:37]
	v_cndmask_b32_e64 v46, 0, v46, s[78:79]
	v_cndmask_b32_e64 v47, 0, v47, s[50:51]
	v_cvt_pk_bf16_f32 v64, v32, v33
	v_cvt_pk_bf16_f32 v65, v34, v35
	v_cvt_pk_bf16_f32 v66, v36, v37
	v_cvt_pk_bf16_f32 v67, v38, v39
	v_cvt_pk_bf16_f32 v68, v40, v41
	v_cvt_pk_bf16_f32 v69, v42, v43
	v_cvt_pk_bf16_f32 v70, v44, v45
	v_cvt_pk_bf16_f32 v71, v46, v47
	v_pk_add_f32 v[232:233], v[232:233], v[32:33]
	v_pk_add_f32 v[232:233], v[232:233], v[34:35]
	v_pk_add_f32 v[232:233], v[232:233], v[36:37]
	v_pk_add_f32 v[232:233], v[232:233], v[38:39]
	v_pk_add_f32 v[232:233], v[232:233], v[40:41]
	v_pk_add_f32 v[232:233], v[232:233], v[42:43]
	v_pk_add_f32 v[232:233], v[232:233], v[44:45]
	v_pk_add_f32 v[232:233], v[232:233], v[46:47]
	ds_read2_b32 v[32:33], v115 offset0:128 offset1:129
	ds_read2_b32 v[34:35], v115 offset0:130 offset1:131
	ds_read2_b32 v[36:37], v115 offset0:136 offset1:137
	ds_read2_b32 v[38:39], v115 offset0:138 offset1:139
	ds_read2_b32 v[40:41], v115 offset0:144 offset1:145
	ds_read2_b32 v[42:43], v115 offset0:146 offset1:147
	ds_read2_b32 v[44:45], v115 offset0:152 offset1:153
	ds_read2_b32 v[46:47], v115 offset0:154 offset1:155
	s_add_i32 s90, s76, 384
	v_add_u32_e32 v80, s90, v239
	v_add_u32_e32 v83, s90, v240
	v_add_u32_e32 v99, s90, v241
	v_add_u32_e32 v253, s90, v242
	v_add_u32_e32 v254, s90, v101
	v_add_u32_e32 v255, s90, v150
	v_med3_i32 v80, v80, 0, s99
	v_med3_i32 v83, v83, 0, s99
	v_med3_i32 v99, v99, 0, s99
	v_med3_i32 v253, v253, 0, s99
	v_med3_i32 v254, v254, 0, s99
	v_med3_i32 v255, v255, 0, s99
	v_mad_u32_u24 v80, v80, s100, v252
	v_mad_u32_u24 v83, v83, s100, v252
	v_mad_u32_u24 v99, v99, s100, v252
	v_mad_u32_u24 v253, v253, s100, v252
	v_mad_u32_u24 v254, v254, s100, v153
	v_mad_u32_u24 v255, v255, s100, v153
	global_load_dwordx4 v[156:159], v80, s[82:83]
	global_load_dwordx4 v[160:163], v83, s[82:83]
	global_load_dwordx4 v[164:167], v99, s[82:83]
	global_load_dwordx4 v[168:171], v253, s[82:83]
	global_load_dwordx4 v[172:175], v254, s[82:83] offset:768
	global_load_dwordx4 v[176:179], v255, s[82:83] offset:768
	global_load_dwordx4 v[180:183], v254, s[82:83] offset:832
	global_load_dwordx4 v[184:187], v255, s[82:83] offset:832
	ds_read_b64_tr_b16 v[204:205], v231
	ds_read_b64_tr_b16 v[206:207], v231 offset:512
	ds_read_b64_tr_b16 v[208:209], v231 offset:2048
	ds_read_b64_tr_b16 v[210:211], v231 offset:2560
	ds_read_b64_tr_b16 v[212:213], v231 offset:1024
	ds_read_b64_tr_b16 v[214:215], v231 offset:1536
	ds_read_b64_tr_b16 v[216:217], v231 offset:3072
	ds_read_b64_tr_b16 v[218:219], v231 offset:3584
	v_exp_f32_e32 v188, v188
	v_exp_f32_e32 v189, v189
	v_exp_f32_e32 v190, v190
	v_exp_f32_e32 v191, v191
	s_waitcnt vmcnt(8)
	ds_write_b128 v247, v[116:119]
	ds_write_b128 v247, v[120:123] offset:1024
	ds_write_b128 v247, v[124:127] offset:2048
	ds_write_b128 v247, v[128:131] offset:3072
	ds_read_b128 v[116:119], v248
	ds_read_b128 v[120:123], v249
	ds_read_b128 v[124:127], v250
	ds_read_b128 v[128:131], v251
	ds_write_b128 v112, v[132:135]
	ds_write_b128 v112, v[136:139] offset:1024
	ds_write_b128 v112, v[140:143] offset:2048
	ds_write_b128 v112, v[144:147] offset:3072
	v_mfma_f32_32x32x16_bf16 v[0:15], v[64:67], v[72:75], v[0:15]
	v_mfma_f32_32x32x16_bf16 v[16:31], v[64:67], v[76:79], v[16:31]
	v_mfma_f32_32x32x16_bf16 v[0:15], v[68:71], v[220:223], v[0:15]
	v_mfma_f32_32x32x16_bf16 v[16:31], v[68:71], v[224:227], v[16:31]
	v_exp_f32_e32 v192, v192
	v_exp_f32_e32 v193, v193
	v_exp_f32_e32 v194, v194
	v_exp_f32_e32 v195, v195
	s_waitcnt lgkmcnt(4)
	v_mfma_f32_32x32x16_bf16 v[32:47], v[116:119], v[48:51], v[32:47]
	v_exp_f32_e32 v196, v196
	v_exp_f32_e32 v197, v197
	v_mfma_f32_32x32x16_bf16 v[32:47], v[120:123], v[52:55], v[32:47]
	v_exp_f32_e32 v198, v198
	v_exp_f32_e32 v199, v199
	v_mfma_f32_32x32x16_bf16 v[32:47], v[124:127], v[56:59], v[32:47]
	v_exp_f32_e32 v200, v200
	v_exp_f32_e32 v201, v201
	v_mfma_f32_32x32x16_bf16 v[32:47], v[128:131], v[60:63], v[32:47]
	v_exp_f32_e32 v202, v202
	v_exp_f32_e32 v203, v203
	s_add_i32 s90, s76, 128
	v_lshlrev_b32_e32 v84, 2, v107
	v_add_u32_e32 v84, s90, v84
	v_add_u32_e32 v85, 0, v84
	v_add_u32_e32 v86, 4, v84
	v_add_u32_e32 v87, 8, v84
	v_add_u32_e32 v88, 12, v84
	v_cmp_gt_u32_e64 s[30:31], s98, v85
	v_cmp_gt_u32_e64 s[36:37], s98, v86
	v_cmp_gt_u32_e64 s[78:79], s98, v87
	v_cmp_gt_u32_e64 s[50:51], s98, v88
	v_cndmask_b32_e64 v188, 0, v188, s[30:31]
	v_add_u32_e32 v85, 32, v84
	v_cmp_gt_u32_e64 s[30:31], s98, v85
	v_cndmask_b32_e64 v189, 0, v189, s[36:37]
	v_add_u32_e32 v86, 36, v84
	v_cmp_gt_u32_e64 s[36:37], s98, v86
	v_cndmask_b32_e64 v190, 0, v190, s[78:79]
	v_add_u32_e32 v87, 40, v84
	v_cmp_gt_u32_e64 s[78:79], s98, v87
	v_cndmask_b32_e64 v191, 0, v191, s[50:51]
	v_add_u32_e32 v88, 44, v84
	v_cmp_gt_u32_e64 s[50:51], s98, v88
	v_cndmask_b32_e64 v192, 0, v192, s[30:31]
	v_add_u32_e32 v85, 64, v84
	v_cmp_gt_u32_e64 s[30:31], s98, v85
	v_cndmask_b32_e64 v193, 0, v193, s[36:37]
	v_add_u32_e32 v86, 68, v84
	v_cmp_gt_u32_e64 s[36:37], s98, v86
	v_cndmask_b32_e64 v194, 0, v194, s[78:79]
	v_add_u32_e32 v87, 72, v84
	v_cmp_gt_u32_e64 s[78:79], s98, v87
	v_cndmask_b32_e64 v195, 0, v195, s[50:51]
	v_add_u32_e32 v88, 76, v84
	v_cmp_gt_u32_e64 s[50:51], s98, v88
	v_cndmask_b32_e64 v196, 0, v196, s[30:31]
	v_add_u32_e32 v85, 96, v84
	v_cmp_gt_u32_e64 s[30:31], s98, v85
	v_cndmask_b32_e64 v197, 0, v197, s[36:37]
	v_add_u32_e32 v86, 100, v84
	v_cmp_gt_u32_e64 s[36:37], s98, v86
	v_cndmask_b32_e64 v198, 0, v198, s[78:79]
	v_add_u32_e32 v87, 104, v84
	v_cmp_gt_u32_e64 s[78:79], s98, v87
	v_cndmask_b32_e64 v199, 0, v199, s[50:51]
	v_add_u32_e32 v88, 108, v84
	v_cmp_gt_u32_e64 s[50:51], s98, v88
	v_nop
	v_cndmask_b32_e64 v200, 0, v200, s[30:31]
	v_cndmask_b32_e64 v201, 0, v201, s[36:37]
	v_cndmask_b32_e64 v202, 0, v202, s[78:79]
	v_cndmask_b32_e64 v203, 0, v203, s[50:51]
	v_cvt_pk_bf16_f32 v64, v188, v189
	v_cvt_pk_bf16_f32 v65, v190, v191
	v_cvt_pk_bf16_f32 v66, v192, v193
	v_cvt_pk_bf16_f32 v67, v194, v195
	v_cvt_pk_bf16_f32 v68, v196, v197
	v_cvt_pk_bf16_f32 v69, v198, v199
	v_cvt_pk_bf16_f32 v70, v200, v201
	v_cvt_pk_bf16_f32 v71, v202, v203
	v_pk_add_f32 v[232:233], v[232:233], v[188:189]
	v_pk_add_f32 v[232:233], v[232:233], v[190:191]
	v_pk_add_f32 v[232:233], v[232:233], v[192:193]
	v_pk_add_f32 v[232:233], v[232:233], v[194:195]
	v_pk_add_f32 v[232:233], v[232:233], v[196:197]
	v_pk_add_f32 v[232:233], v[232:233], v[198:199]
	v_pk_add_f32 v[232:233], v[232:233], v[200:201]
	v_pk_add_f32 v[232:233], v[232:233], v[202:203]
	ds_read2_b32 v[188:189], v115 offset0:160 offset1:161
	ds_read2_b32 v[190:191], v115 offset0:162 offset1:163
	ds_read2_b32 v[192:193], v115 offset0:168 offset1:169
	ds_read2_b32 v[194:195], v115 offset0:170 offset1:171
	ds_read2_b32 v[196:197], v115 offset0:176 offset1:177
	ds_read2_b32 v[198:199], v115 offset0:178 offset1:179
	ds_read2_b32 v[200:201], v115 offset0:184 offset1:185
	ds_read2_b32 v[202:203], v115 offset0:186 offset1:187
	s_add_i32 s90, s76, 512
	v_add_u32_e32 v80, s90, v239
	v_add_u32_e32 v83, s90, v240
	v_add_u32_e32 v99, s90, v241
	v_add_u32_e32 v253, s90, v242
	v_add_u32_e32 v254, s90, v101
	v_add_u32_e32 v255, s90, v150
	v_med3_i32 v80, v80, 0, s99
	v_med3_i32 v83, v83, 0, s99
	v_med3_i32 v99, v99, 0, s99
	v_med3_i32 v253, v253, 0, s99
	v_med3_i32 v254, v254, 0, s99
	v_med3_i32 v255, v255, 0, s99
	v_mad_u32_u24 v80, v80, s100, v252
	v_mad_u32_u24 v83, v83, s100, v252
	v_mad_u32_u24 v99, v99, s100, v252
	v_mad_u32_u24 v253, v253, s100, v252
	v_mad_u32_u24 v254, v254, s100, v153
	v_mad_u32_u24 v255, v255, s100, v153
	global_load_dwordx4 v[116:119], v80, s[82:83]
	global_load_dwordx4 v[120:123], v83, s[82:83]
	global_load_dwordx4 v[124:127], v99, s[82:83]
	global_load_dwordx4 v[128:131], v253, s[82:83]
	global_load_dwordx4 v[132:135], v254, s[82:83] offset:768
	global_load_dwordx4 v[136:139], v255, s[82:83] offset:768
	global_load_dwordx4 v[140:143], v254, s[82:83] offset:832
	global_load_dwordx4 v[144:147], v255, s[82:83] offset:832
	ds_read_b64_tr_b16 v[72:73], v231
	ds_read_b64_tr_b16 v[74:75], v231 offset:512
	ds_read_b64_tr_b16 v[76:77], v231 offset:2048
	ds_read_b64_tr_b16 v[78:79], v231 offset:2560
	ds_read_b64_tr_b16 v[220:221], v231 offset:1024
	ds_read_b64_tr_b16 v[222:223], v231 offset:1536
	ds_read_b64_tr_b16 v[224:225], v231 offset:3072
	ds_read_b64_tr_b16 v[226:227], v231 offset:3584
	v_exp_f32_e32 v32, v32
	v_exp_f32_e32 v33, v33
	v_exp_f32_e32 v34, v34
	v_exp_f32_e32 v35, v35
	s_waitcnt vmcnt(8)
	ds_write_b128 v247, v[156:159]
	ds_write_b128 v247, v[160:163] offset:1024
	ds_write_b128 v247, v[164:167] offset:2048
	ds_write_b128 v247, v[168:171] offset:3072
	ds_read_b128 v[156:159], v248
	ds_read_b128 v[160:163], v249
	ds_read_b128 v[164:167], v250
	ds_read_b128 v[168:171], v251
	ds_write_b128 v112, v[172:175]
	ds_write_b128 v112, v[176:179] offset:1024
	ds_write_b128 v112, v[180:183] offset:2048
	ds_write_b128 v112, v[184:187] offset:3072
	v_mfma_f32_32x32x16_bf16 v[0:15], v[64:67], v[204:207], v[0:15]
	v_mfma_f32_32x32x16_bf16 v[16:31], v[64:67], v[208:211], v[16:31]
	v_mfma_f32_32x32x16_bf16 v[0:15], v[68:71], v[212:215], v[0:15]
	v_mfma_f32_32x32x16_bf16 v[16:31], v[68:71], v[216:219], v[16:31]
	v_exp_f32_e32 v36, v36
	v_exp_f32_e32 v37, v37
	v_exp_f32_e32 v38, v38
	v_exp_f32_e32 v39, v39
	s_waitcnt lgkmcnt(4)
	v_mfma_f32_32x32x16_bf16 v[188:203], v[156:159], v[48:51], v[188:203]
	v_exp_f32_e32 v40, v40
	v_exp_f32_e32 v41, v41
	v_mfma_f32_32x32x16_bf16 v[188:203], v[160:163], v[52:55], v[188:203]
	v_exp_f32_e32 v42, v42
	v_exp_f32_e32 v43, v43
	v_mfma_f32_32x32x16_bf16 v[188:203], v[164:167], v[56:59], v[188:203]
	v_exp_f32_e32 v44, v44
	v_exp_f32_e32 v45, v45
	v_mfma_f32_32x32x16_bf16 v[188:203], v[168:171], v[60:63], v[188:203]
	v_exp_f32_e32 v46, v46
	v_exp_f32_e32 v47, v47
	s_add_i32 s90, s76, 256
	v_lshlrev_b32_e32 v84, 2, v107
	v_add_u32_e32 v84, s90, v84
	v_add_u32_e32 v85, 0, v84
	v_add_u32_e32 v86, 4, v84
	v_add_u32_e32 v87, 8, v84
	v_add_u32_e32 v88, 12, v84
	v_cmp_gt_u32_e64 s[30:31], s98, v85
	v_cmp_gt_u32_e64 s[36:37], s98, v86
	v_cmp_gt_u32_e64 s[78:79], s98, v87
	v_cmp_gt_u32_e64 s[50:51], s98, v88
	v_cndmask_b32_e64 v32, 0, v32, s[30:31]
	v_add_u32_e32 v85, 32, v84
	v_cmp_gt_u32_e64 s[30:31], s98, v85
	v_cndmask_b32_e64 v33, 0, v33, s[36:37]
	v_add_u32_e32 v86, 36, v84
	v_cmp_gt_u32_e64 s[36:37], s98, v86
	v_cndmask_b32_e64 v34, 0, v34, s[78:79]
	v_add_u32_e32 v87, 40, v84
	v_cmp_gt_u32_e64 s[78:79], s98, v87
	v_cndmask_b32_e64 v35, 0, v35, s[50:51]
	v_add_u32_e32 v88, 44, v84
	v_cmp_gt_u32_e64 s[50:51], s98, v88
	v_cndmask_b32_e64 v36, 0, v36, s[30:31]
	v_add_u32_e32 v85, 64, v84
	v_cmp_gt_u32_e64 s[30:31], s98, v85
	v_cndmask_b32_e64 v37, 0, v37, s[36:37]
	v_add_u32_e32 v86, 68, v84
	v_cmp_gt_u32_e64 s[36:37], s98, v86
	v_cndmask_b32_e64 v38, 0, v38, s[78:79]
	v_add_u32_e32 v87, 72, v84
	v_cmp_gt_u32_e64 s[78:79], s98, v87
	v_cndmask_b32_e64 v39, 0, v39, s[50:51]
	v_add_u32_e32 v88, 76, v84
	v_cmp_gt_u32_e64 s[50:51], s98, v88
	v_cndmask_b32_e64 v40, 0, v40, s[30:31]
	v_add_u32_e32 v85, 96, v84
	v_cmp_gt_u32_e64 s[30:31], s98, v85
	v_cndmask_b32_e64 v41, 0, v41, s[36:37]
	v_add_u32_e32 v86, 100, v84
	v_cmp_gt_u32_e64 s[36:37], s98, v86
	v_cndmask_b32_e64 v42, 0, v42, s[78:79]
	v_add_u32_e32 v87, 104, v84
	v_cmp_gt_u32_e64 s[78:79], s98, v87
	v_cndmask_b32_e64 v43, 0, v43, s[50:51]
	v_add_u32_e32 v88, 108, v84
	v_cmp_gt_u32_e64 s[50:51], s98, v88
	v_nop
	v_cndmask_b32_e64 v44, 0, v44, s[30:31]
	v_cndmask_b32_e64 v45, 0, v45, s[36:37]
	v_cndmask_b32_e64 v46, 0, v46, s[78:79]
	v_cndmask_b32_e64 v47, 0, v47, s[50:51]
	v_cvt_pk_bf16_f32 v64, v32, v33
	v_cvt_pk_bf16_f32 v65, v34, v35
	v_cvt_pk_bf16_f32 v66, v36, v37
	v_cvt_pk_bf16_f32 v67, v38, v39
	v_cvt_pk_bf16_f32 v68, v40, v41
	v_cvt_pk_bf16_f32 v69, v42, v43
	v_cvt_pk_bf16_f32 v70, v44, v45
	v_cvt_pk_bf16_f32 v71, v46, v47
	v_pk_add_f32 v[232:233], v[232:233], v[32:33]
	v_pk_add_f32 v[232:233], v[232:233], v[34:35]
	v_pk_add_f32 v[232:233], v[232:233], v[36:37]
	v_pk_add_f32 v[232:233], v[232:233], v[38:39]
	v_pk_add_f32 v[232:233], v[232:233], v[40:41]
	v_pk_add_f32 v[232:233], v[232:233], v[42:43]
	v_pk_add_f32 v[232:233], v[232:233], v[44:45]
	v_pk_add_f32 v[232:233], v[232:233], v[46:47]
	ds_read2_b32 v[32:33], v115 offset0:192 offset1:193
	ds_read2_b32 v[34:35], v115 offset0:194 offset1:195
	ds_read2_b32 v[36:37], v115 offset0:200 offset1:201
	ds_read2_b32 v[38:39], v115 offset0:202 offset1:203
	ds_read2_b32 v[40:41], v115 offset0:208 offset1:209
	ds_read2_b32 v[42:43], v115 offset0:210 offset1:211
	ds_read2_b32 v[44:45], v115 offset0:216 offset1:217
	ds_read2_b32 v[46:47], v115 offset0:218 offset1:219
	s_add_i32 s90, s76, 640
	v_add_u32_e32 v80, s90, v239
	v_add_u32_e32 v83, s90, v240
	v_add_u32_e32 v99, s90, v241
	v_add_u32_e32 v253, s90, v242
	v_add_u32_e32 v254, s90, v101
	v_add_u32_e32 v255, s90, v150
	v_med3_i32 v80, v80, 0, s99
	v_med3_i32 v83, v83, 0, s99
	v_med3_i32 v99, v99, 0, s99
	v_med3_i32 v253, v253, 0, s99
	v_med3_i32 v254, v254, 0, s99
	v_med3_i32 v255, v255, 0, s99
	v_mad_u32_u24 v80, v80, s100, v252
	v_mad_u32_u24 v83, v83, s100, v252
	v_mad_u32_u24 v99, v99, s100, v252
	v_mad_u32_u24 v253, v253, s100, v252
	v_mad_u32_u24 v254, v254, s100, v153
	v_mad_u32_u24 v255, v255, s100, v153
	global_load_dwordx4 v[156:159], v80, s[82:83]
	global_load_dwordx4 v[160:163], v83, s[82:83]
	global_load_dwordx4 v[164:167], v99, s[82:83]
	global_load_dwordx4 v[168:171], v253, s[82:83]
	global_load_dwordx4 v[172:175], v254, s[82:83] offset:768
	global_load_dwordx4 v[176:179], v255, s[82:83] offset:768
	global_load_dwordx4 v[180:183], v254, s[82:83] offset:832
	global_load_dwordx4 v[184:187], v255, s[82:83] offset:832
	ds_read_b64_tr_b16 v[204:205], v231
	ds_read_b64_tr_b16 v[206:207], v231 offset:512
	ds_read_b64_tr_b16 v[208:209], v231 offset:2048
	ds_read_b64_tr_b16 v[210:211], v231 offset:2560
	ds_read_b64_tr_b16 v[212:213], v231 offset:1024
	ds_read_b64_tr_b16 v[214:215], v231 offset:1536
	ds_read_b64_tr_b16 v[216:217], v231 offset:3072
	ds_read_b64_tr_b16 v[218:219], v231 offset:3584
	v_exp_f32_e32 v188, v188
	v_exp_f32_e32 v189, v189
	v_exp_f32_e32 v190, v190
	v_exp_f32_e32 v191, v191
	s_waitcnt vmcnt(8)
	ds_write_b128 v247, v[116:119]
	ds_write_b128 v247, v[120:123] offset:1024
	ds_write_b128 v247, v[124:127] offset:2048
	ds_write_b128 v247, v[128:131] offset:3072
	ds_read_b128 v[116:119], v248
	ds_read_b128 v[120:123], v249
	ds_read_b128 v[124:127], v250
	ds_read_b128 v[128:131], v251
	ds_write_b128 v112, v[132:135]
	ds_write_b128 v112, v[136:139] offset:1024
	ds_write_b128 v112, v[140:143] offset:2048
	ds_write_b128 v112, v[144:147] offset:3072
	v_mfma_f32_32x32x16_bf16 v[0:15], v[64:67], v[72:75], v[0:15]
	v_mfma_f32_32x32x16_bf16 v[16:31], v[64:67], v[76:79], v[16:31]
	v_mfma_f32_32x32x16_bf16 v[0:15], v[68:71], v[220:223], v[0:15]
	v_mfma_f32_32x32x16_bf16 v[16:31], v[68:71], v[224:227], v[16:31]
	v_exp_f32_e32 v192, v192
	v_exp_f32_e32 v193, v193
	v_exp_f32_e32 v194, v194
	v_exp_f32_e32 v195, v195
	s_waitcnt lgkmcnt(4)
	v_mfma_f32_32x32x16_bf16 v[32:47], v[116:119], v[48:51], v[32:47]
	v_exp_f32_e32 v196, v196
	v_exp_f32_e32 v197, v197
	v_mfma_f32_32x32x16_bf16 v[32:47], v[120:123], v[52:55], v[32:47]
	v_exp_f32_e32 v198, v198
	v_exp_f32_e32 v199, v199
	v_mfma_f32_32x32x16_bf16 v[32:47], v[124:127], v[56:59], v[32:47]
	v_exp_f32_e32 v200, v200
	v_exp_f32_e32 v201, v201
	v_mfma_f32_32x32x16_bf16 v[32:47], v[128:131], v[60:63], v[32:47]
	v_exp_f32_e32 v202, v202
	v_exp_f32_e32 v203, v203
	s_add_i32 s90, s76, 384
	v_lshlrev_b32_e32 v84, 2, v107
	v_add_u32_e32 v84, s90, v84
	v_add_u32_e32 v85, 0, v84
	v_add_u32_e32 v86, 4, v84
	v_add_u32_e32 v87, 8, v84
	v_add_u32_e32 v88, 12, v84
	v_cmp_gt_u32_e64 s[30:31], s98, v85
	v_cmp_gt_u32_e64 s[36:37], s98, v86
	v_cmp_gt_u32_e64 s[78:79], s98, v87
	v_cmp_gt_u32_e64 s[50:51], s98, v88
	v_cndmask_b32_e64 v188, 0, v188, s[30:31]
	v_add_u32_e32 v85, 32, v84
	v_cmp_gt_u32_e64 s[30:31], s98, v85
	v_cndmask_b32_e64 v189, 0, v189, s[36:37]
	v_add_u32_e32 v86, 36, v84
	v_cmp_gt_u32_e64 s[36:37], s98, v86
	v_cndmask_b32_e64 v190, 0, v190, s[78:79]
	v_add_u32_e32 v87, 40, v84
	v_cmp_gt_u32_e64 s[78:79], s98, v87
	v_cndmask_b32_e64 v191, 0, v191, s[50:51]
	v_add_u32_e32 v88, 44, v84
	v_cmp_gt_u32_e64 s[50:51], s98, v88
	v_cndmask_b32_e64 v192, 0, v192, s[30:31]
	v_add_u32_e32 v85, 64, v84
	v_cmp_gt_u32_e64 s[30:31], s98, v85
	v_cndmask_b32_e64 v193, 0, v193, s[36:37]
	v_add_u32_e32 v86, 68, v84
	v_cmp_gt_u32_e64 s[36:37], s98, v86
	v_cndmask_b32_e64 v194, 0, v194, s[78:79]
	v_add_u32_e32 v87, 72, v84
	v_cmp_gt_u32_e64 s[78:79], s98, v87
	v_cndmask_b32_e64 v195, 0, v195, s[50:51]
	v_add_u32_e32 v88, 76, v84
	v_cmp_gt_u32_e64 s[50:51], s98, v88
	v_cndmask_b32_e64 v196, 0, v196, s[30:31]
	v_add_u32_e32 v85, 96, v84
	v_cmp_gt_u32_e64 s[30:31], s98, v85
	v_cndmask_b32_e64 v197, 0, v197, s[36:37]
	v_add_u32_e32 v86, 100, v84
	v_cmp_gt_u32_e64 s[36:37], s98, v86
	v_cndmask_b32_e64 v198, 0, v198, s[78:79]
	v_add_u32_e32 v87, 104, v84
	v_cmp_gt_u32_e64 s[78:79], s98, v87
	v_cndmask_b32_e64 v199, 0, v199, s[50:51]
	v_add_u32_e32 v88, 108, v84
	v_cmp_gt_u32_e64 s[50:51], s98, v88
	v_nop
	v_cndmask_b32_e64 v200, 0, v200, s[30:31]
	v_cndmask_b32_e64 v201, 0, v201, s[36:37]
	v_cndmask_b32_e64 v202, 0, v202, s[78:79]
	v_cndmask_b32_e64 v203, 0, v203, s[50:51]
	v_cvt_pk_bf16_f32 v64, v188, v189
	v_cvt_pk_bf16_f32 v65, v190, v191
	v_cvt_pk_bf16_f32 v66, v192, v193
	v_cvt_pk_bf16_f32 v67, v194, v195
	v_cvt_pk_bf16_f32 v68, v196, v197
	v_cvt_pk_bf16_f32 v69, v198, v199
	v_cvt_pk_bf16_f32 v70, v200, v201
	v_cvt_pk_bf16_f32 v71, v202, v203
	v_pk_add_f32 v[232:233], v[232:233], v[188:189]
	v_pk_add_f32 v[232:233], v[232:233], v[190:191]
	v_pk_add_f32 v[232:233], v[232:233], v[192:193]
	v_pk_add_f32 v[232:233], v[232:233], v[194:195]
	v_pk_add_f32 v[232:233], v[232:233], v[196:197]
	v_pk_add_f32 v[232:233], v[232:233], v[198:199]
	v_pk_add_f32 v[232:233], v[232:233], v[200:201]
	v_pk_add_f32 v[232:233], v[232:233], v[202:203]
	ds_read2_b32 v[188:189], v115 offset0:224 offset1:225
	ds_read2_b32 v[190:191], v115 offset0:226 offset1:227
	ds_read2_b32 v[192:193], v115 offset0:232 offset1:233
	ds_read2_b32 v[194:195], v115 offset0:234 offset1:235
	ds_read2_b32 v[196:197], v115 offset0:240 offset1:241
	ds_read2_b32 v[198:199], v115 offset0:242 offset1:243
	ds_read2_b32 v[200:201], v115 offset0:248 offset1:249
	ds_read2_b32 v[202:203], v115 offset0:250 offset1:251
	s_add_i32 s90, s76, -1024
	v_add_u32_e32 v80, s90, v243
	v_add_u32_e32 v83, s90, v244
	v_add_u32_e32 v99, s90, v245
	v_add_u32_e32 v253, s90, v246
	v_add_u32_e32 v254, s90, v148
	v_add_u32_e32 v255, s90, v151
	v_med3_i32 v80, v80, 0, s99
	v_med3_i32 v83, v83, 0, s99
	v_med3_i32 v99, v99, 0, s99
	v_med3_i32 v253, v253, 0, s99
	v_med3_i32 v254, v254, 0, s99
	v_med3_i32 v255, v255, 0, s99
	v_mad_u32_u24 v80, v80, s100, v252
	v_mad_u32_u24 v83, v83, s100, v252
	v_mad_u32_u24 v99, v99, s100, v252
	v_mad_u32_u24 v253, v253, s100, v252
	v_mad_u32_u24 v254, v254, s100, v153
	v_mad_u32_u24 v255, v255, s100, v153
	global_load_dwordx4 v[116:119], v80, s[82:83]
	global_load_dwordx4 v[120:123], v83, s[82:83]
	global_load_dwordx4 v[124:127], v99, s[82:83]
	global_load_dwordx4 v[128:131], v253, s[82:83]
	global_load_dwordx4 v[132:135], v254, s[82:83] offset:768
	global_load_dwordx4 v[136:139], v255, s[82:83] offset:768
	global_load_dwordx4 v[140:143], v254, s[82:83] offset:832
	global_load_dwordx4 v[144:147], v255, s[82:83] offset:832
	ds_read_b64_tr_b16 v[72:73], v231
	ds_read_b64_tr_b16 v[74:75], v231 offset:512
	ds_read_b64_tr_b16 v[76:77], v231 offset:2048
	ds_read_b64_tr_b16 v[78:79], v231 offset:2560
	ds_read_b64_tr_b16 v[220:221], v231 offset:1024
	ds_read_b64_tr_b16 v[222:223], v231 offset:1536
	ds_read_b64_tr_b16 v[224:225], v231 offset:3072
	ds_read_b64_tr_b16 v[226:227], v231 offset:3584
	v_exp_f32_e32 v32, v32
	v_exp_f32_e32 v33, v33
	v_exp_f32_e32 v34, v34
	v_exp_f32_e32 v35, v35
	s_waitcnt vmcnt(8)
	ds_write_b128 v247, v[156:159]
	ds_write_b128 v247, v[160:163] offset:1024
	ds_write_b128 v247, v[164:167] offset:2048
	ds_write_b128 v247, v[168:171] offset:3072
	ds_read_b128 v[156:159], v248
	ds_read_b128 v[160:163], v249
	ds_read_b128 v[164:167], v250
	ds_read_b128 v[168:171], v251
	ds_write_b128 v112, v[172:175]
	ds_write_b128 v112, v[176:179] offset:1024
	ds_write_b128 v112, v[180:183] offset:2048
	ds_write_b128 v112, v[184:187] offset:3072
	v_mfma_f32_32x32x16_bf16 v[0:15], v[64:67], v[204:207], v[0:15]
	v_mfma_f32_32x32x16_bf16 v[16:31], v[64:67], v[208:211], v[16:31]
	v_mfma_f32_32x32x16_bf16 v[0:15], v[68:71], v[212:215], v[0:15]
	v_mfma_f32_32x32x16_bf16 v[16:31], v[68:71], v[216:219], v[16:31]
	v_exp_f32_e32 v36, v36
	v_exp_f32_e32 v37, v37
	v_exp_f32_e32 v38, v38
	v_exp_f32_e32 v39, v39
	s_waitcnt lgkmcnt(4)
	v_mfma_f32_32x32x16_bf16 v[188:203], v[156:159], v[48:51], v[188:203]
	v_exp_f32_e32 v40, v40
	v_exp_f32_e32 v41, v41
	v_mfma_f32_32x32x16_bf16 v[188:203], v[160:163], v[52:55], v[188:203]
	v_exp_f32_e32 v42, v42
	v_exp_f32_e32 v43, v43
	v_mfma_f32_32x32x16_bf16 v[188:203], v[164:167], v[56:59], v[188:203]
	v_exp_f32_e32 v44, v44
	v_exp_f32_e32 v45, v45
	v_mfma_f32_32x32x16_bf16 v[188:203], v[168:171], v[60:63], v[188:203]
	v_exp_f32_e32 v46, v46
	v_exp_f32_e32 v47, v47
	s_add_i32 s90, s76, 512
	v_lshlrev_b32_e32 v84, 2, v107
	v_add_u32_e32 v84, s90, v84
	v_add_u32_e32 v85, 0, v84
	v_add_u32_e32 v86, 4, v84
	v_add_u32_e32 v87, 8, v84
	v_add_u32_e32 v88, 12, v84
	v_cmp_gt_u32_e64 s[30:31], s98, v85
	v_cmp_gt_u32_e64 s[36:37], s98, v86
	v_cmp_gt_u32_e64 s[78:79], s98, v87
	v_cmp_gt_u32_e64 s[50:51], s98, v88
	v_cndmask_b32_e64 v32, 0, v32, s[30:31]
	v_add_u32_e32 v85, 32, v84
	v_cmp_gt_u32_e64 s[30:31], s98, v85
	v_cndmask_b32_e64 v33, 0, v33, s[36:37]
	v_add_u32_e32 v86, 36, v84
	v_cmp_gt_u32_e64 s[36:37], s98, v86
	v_cndmask_b32_e64 v34, 0, v34, s[78:79]
	v_add_u32_e32 v87, 40, v84
	v_cmp_gt_u32_e64 s[78:79], s98, v87
	v_cndmask_b32_e64 v35, 0, v35, s[50:51]
	v_add_u32_e32 v88, 44, v84
	v_cmp_gt_u32_e64 s[50:51], s98, v88
	v_cndmask_b32_e64 v36, 0, v36, s[30:31]
	v_add_u32_e32 v85, 64, v84
	v_cmp_gt_u32_e64 s[30:31], s98, v85
	v_cndmask_b32_e64 v37, 0, v37, s[36:37]
	v_add_u32_e32 v86, 68, v84
	v_cmp_gt_u32_e64 s[36:37], s98, v86
	v_cndmask_b32_e64 v38, 0, v38, s[78:79]
	v_add_u32_e32 v87, 72, v84
	v_cmp_gt_u32_e64 s[78:79], s98, v87
	v_cndmask_b32_e64 v39, 0, v39, s[50:51]
	v_add_u32_e32 v88, 76, v84
	v_cmp_gt_u32_e64 s[50:51], s98, v88
	v_cndmask_b32_e64 v40, 0, v40, s[30:31]
	v_add_u32_e32 v85, 96, v84
	v_cmp_gt_u32_e64 s[30:31], s98, v85
	v_cndmask_b32_e64 v41, 0, v41, s[36:37]
	v_add_u32_e32 v86, 100, v84
	v_cmp_gt_u32_e64 s[36:37], s98, v86
	v_cndmask_b32_e64 v42, 0, v42, s[78:79]
	v_add_u32_e32 v87, 104, v84
	v_cmp_gt_u32_e64 s[78:79], s98, v87
	v_cndmask_b32_e64 v43, 0, v43, s[50:51]
	v_add_u32_e32 v88, 108, v84
	v_cmp_gt_u32_e64 s[50:51], s98, v88
	v_nop
	v_cndmask_b32_e64 v44, 0, v44, s[30:31]
	v_cndmask_b32_e64 v45, 0, v45, s[36:37]
	v_cndmask_b32_e64 v46, 0, v46, s[78:79]
	v_cndmask_b32_e64 v47, 0, v47, s[50:51]
	v_cvt_pk_bf16_f32 v64, v32, v33
	v_cvt_pk_bf16_f32 v65, v34, v35
	v_cvt_pk_bf16_f32 v66, v36, v37
	v_cvt_pk_bf16_f32 v67, v38, v39
	v_cvt_pk_bf16_f32 v68, v40, v41
	v_cvt_pk_bf16_f32 v69, v42, v43
	v_cvt_pk_bf16_f32 v70, v44, v45
	v_cvt_pk_bf16_f32 v71, v46, v47
	v_pk_add_f32 v[232:233], v[232:233], v[32:33]
	v_pk_add_f32 v[232:233], v[232:233], v[34:35]
	v_pk_add_f32 v[232:233], v[232:233], v[36:37]
	v_pk_add_f32 v[232:233], v[232:233], v[38:39]
	v_pk_add_f32 v[232:233], v[232:233], v[40:41]
	v_pk_add_f32 v[232:233], v[232:233], v[42:43]
	v_pk_add_f32 v[232:233], v[232:233], v[44:45]
	v_pk_add_f32 v[232:233], v[232:233], v[46:47]
	v_mov_b32_e32 v115, v230
	ds_read2_b32 v[32:33], v115 offset0:0 offset1:1
	ds_read2_b32 v[34:35], v115 offset0:2 offset1:3
	ds_read2_b32 v[36:37], v115 offset0:8 offset1:9
	ds_read2_b32 v[38:39], v115 offset0:10 offset1:11
	ds_read2_b32 v[40:41], v115 offset0:16 offset1:17
	ds_read2_b32 v[42:43], v115 offset0:18 offset1:19
	ds_read2_b32 v[44:45], v115 offset0:24 offset1:25
	ds_read2_b32 v[46:47], v115 offset0:26 offset1:27
	s_add_i32 s90, s76, -512
	v_add_u32_e32 v80, s90, v243
	v_add_u32_e32 v83, s90, v244
	v_add_u32_e32 v99, s90, v245
	v_add_u32_e32 v253, s90, v246
	v_add_u32_e32 v254, s90, v148
	v_add_u32_e32 v255, s90, v151
	v_med3_i32 v80, v80, 0, s99
	v_med3_i32 v83, v83, 0, s99
	v_med3_i32 v99, v99, 0, s99
	v_med3_i32 v253, v253, 0, s99
	v_med3_i32 v254, v254, 0, s99
	v_med3_i32 v255, v255, 0, s99
	v_mad_u32_u24 v80, v80, s100, v252
	v_mad_u32_u24 v83, v83, s100, v252
	v_mad_u32_u24 v99, v99, s100, v252
	v_mad_u32_u24 v253, v253, s100, v252
	v_mad_u32_u24 v254, v254, s100, v153
	v_mad_u32_u24 v255, v255, s100, v153
	global_load_dwordx4 v[156:159], v80, s[82:83]
	global_load_dwordx4 v[160:163], v83, s[82:83]
	global_load_dwordx4 v[164:167], v99, s[82:83]
	global_load_dwordx4 v[168:171], v253, s[82:83]
	global_load_dwordx4 v[172:175], v254, s[82:83] offset:768
	global_load_dwordx4 v[176:179], v255, s[82:83] offset:768
	global_load_dwordx4 v[180:183], v254, s[82:83] offset:832
	global_load_dwordx4 v[184:187], v255, s[82:83] offset:832
	ds_read_b64_tr_b16 v[204:205], v231
	ds_read_b64_tr_b16 v[206:207], v231 offset:512
	ds_read_b64_tr_b16 v[208:209], v231 offset:2048
	ds_read_b64_tr_b16 v[210:211], v231 offset:2560
	ds_read_b64_tr_b16 v[212:213], v231 offset:1024
	ds_read_b64_tr_b16 v[214:215], v231 offset:1536
	ds_read_b64_tr_b16 v[216:217], v231 offset:3072
	ds_read_b64_tr_b16 v[218:219], v231 offset:3584
	v_exp_f32_e32 v188, v188
	v_exp_f32_e32 v189, v189
	v_exp_f32_e32 v190, v190
	v_exp_f32_e32 v191, v191
	s_waitcnt vmcnt(8)
	ds_write_b128 v247, v[116:119]
	ds_write_b128 v247, v[120:123] offset:1024
	ds_write_b128 v247, v[124:127] offset:2048
	ds_write_b128 v247, v[128:131] offset:3072
	ds_read_b128 v[116:119], v248
	ds_read_b128 v[120:123], v249
	ds_read_b128 v[124:127], v250
	ds_read_b128 v[128:131], v251
	ds_write_b128 v112, v[132:135]
	ds_write_b128 v112, v[136:139] offset:1024
	ds_write_b128 v112, v[140:143] offset:2048
	ds_write_b128 v112, v[144:147] offset:3072
	v_mfma_f32_32x32x16_bf16 v[0:15], v[64:67], v[72:75], v[0:15]
	v_mfma_f32_32x32x16_bf16 v[16:31], v[64:67], v[76:79], v[16:31]
	v_mfma_f32_32x32x16_bf16 v[0:15], v[68:71], v[220:223], v[0:15]
	v_mfma_f32_32x32x16_bf16 v[16:31], v[68:71], v[224:227], v[16:31]
	v_exp_f32_e32 v192, v192
	v_exp_f32_e32 v193, v193
	v_exp_f32_e32 v194, v194
	v_exp_f32_e32 v195, v195
	s_waitcnt lgkmcnt(4)
	v_mfma_f32_32x32x16_bf16 v[32:47], v[116:119], v[48:51], v[32:47]
	v_exp_f32_e32 v196, v196
	v_exp_f32_e32 v197, v197
	v_mfma_f32_32x32x16_bf16 v[32:47], v[120:123], v[52:55], v[32:47]
	v_exp_f32_e32 v198, v198
	v_exp_f32_e32 v199, v199
	v_mfma_f32_32x32x16_bf16 v[32:47], v[124:127], v[56:59], v[32:47]
	v_exp_f32_e32 v200, v200
	v_exp_f32_e32 v201, v201
	v_mfma_f32_32x32x16_bf16 v[32:47], v[128:131], v[60:63], v[32:47]
	v_exp_f32_e32 v202, v202
	v_exp_f32_e32 v203, v203
	s_add_i32 s90, s76, 640
	v_lshlrev_b32_e32 v84, 2, v107
	v_add_u32_e32 v84, s90, v84
	v_add_u32_e32 v85, 0, v84
	v_add_u32_e32 v86, 4, v84
	v_add_u32_e32 v87, 8, v84
	v_add_u32_e32 v88, 12, v84
	v_cmp_gt_u32_e64 s[30:31], s98, v85
	v_cmp_gt_u32_e64 s[36:37], s98, v86
	v_cmp_gt_u32_e64 s[78:79], s98, v87
	v_cmp_gt_u32_e64 s[50:51], s98, v88
	v_cndmask_b32_e64 v188, 0, v188, s[30:31]
	v_add_u32_e32 v85, 32, v84
	v_cmp_gt_u32_e64 s[30:31], s98, v85
	v_cndmask_b32_e64 v189, 0, v189, s[36:37]
	v_add_u32_e32 v86, 36, v84
	v_cmp_gt_u32_e64 s[36:37], s98, v86
	v_cndmask_b32_e64 v190, 0, v190, s[78:79]
	v_add_u32_e32 v87, 40, v84
	v_cmp_gt_u32_e64 s[78:79], s98, v87
	v_cndmask_b32_e64 v191, 0, v191, s[50:51]
	v_add_u32_e32 v88, 44, v84
	v_cmp_gt_u32_e64 s[50:51], s98, v88
	v_cndmask_b32_e64 v192, 0, v192, s[30:31]
	v_add_u32_e32 v85, 64, v84
	v_cmp_gt_u32_e64 s[30:31], s98, v85
	v_cndmask_b32_e64 v193, 0, v193, s[36:37]
	v_add_u32_e32 v86, 68, v84
	v_cmp_gt_u32_e64 s[36:37], s98, v86
	v_cndmask_b32_e64 v194, 0, v194, s[78:79]
	v_add_u32_e32 v87, 72, v84
	v_cmp_gt_u32_e64 s[78:79], s98, v87
	v_cndmask_b32_e64 v195, 0, v195, s[50:51]
	v_add_u32_e32 v88, 76, v84
	v_cmp_gt_u32_e64 s[50:51], s98, v88
	v_cndmask_b32_e64 v196, 0, v196, s[30:31]
	v_add_u32_e32 v85, 96, v84
	v_cmp_gt_u32_e64 s[30:31], s98, v85
	v_cndmask_b32_e64 v197, 0, v197, s[36:37]
	v_add_u32_e32 v86, 100, v84
	v_cmp_gt_u32_e64 s[36:37], s98, v86
	v_cndmask_b32_e64 v198, 0, v198, s[78:79]
	v_add_u32_e32 v87, 104, v84
	v_cmp_gt_u32_e64 s[78:79], s98, v87
	v_cndmask_b32_e64 v199, 0, v199, s[50:51]
	v_add_u32_e32 v88, 108, v84
	v_cmp_gt_u32_e64 s[50:51], s98, v88
	v_nop
	v_cndmask_b32_e64 v200, 0, v200, s[30:31]
	v_cndmask_b32_e64 v201, 0, v201, s[36:37]
	v_cndmask_b32_e64 v202, 0, v202, s[78:79]
	v_cndmask_b32_e64 v203, 0, v203, s[50:51]
	v_cvt_pk_bf16_f32 v64, v188, v189
	v_cvt_pk_bf16_f32 v65, v190, v191
	v_cvt_pk_bf16_f32 v66, v192, v193
	v_cvt_pk_bf16_f32 v67, v194, v195
	v_cvt_pk_bf16_f32 v68, v196, v197
	v_cvt_pk_bf16_f32 v69, v198, v199
	v_cvt_pk_bf16_f32 v70, v200, v201
	v_cvt_pk_bf16_f32 v71, v202, v203
	v_pk_add_f32 v[232:233], v[232:233], v[188:189]
	v_pk_add_f32 v[232:233], v[232:233], v[190:191]
	v_pk_add_f32 v[232:233], v[232:233], v[192:193]
	v_pk_add_f32 v[232:233], v[232:233], v[194:195]
	v_pk_add_f32 v[232:233], v[232:233], v[196:197]
	v_pk_add_f32 v[232:233], v[232:233], v[198:199]
	v_pk_add_f32 v[232:233], v[232:233], v[200:201]
	v_pk_add_f32 v[232:233], v[232:233], v[202:203]
	ds_read2_b32 v[188:189], v115 offset0:32 offset1:33
	ds_read2_b32 v[190:191], v115 offset0:34 offset1:35
	ds_read2_b32 v[192:193], v115 offset0:40 offset1:41
	ds_read2_b32 v[194:195], v115 offset0:42 offset1:43
	ds_read2_b32 v[196:197], v115 offset0:48 offset1:49
	ds_read2_b32 v[198:199], v115 offset0:50 offset1:51
	ds_read2_b32 v[200:201], v115 offset0:56 offset1:57
	ds_read2_b32 v[202:203], v115 offset0:58 offset1:59
	s_add_i32 s90, s76, 0
	v_add_u32_e32 v80, s90, v243
	v_add_u32_e32 v83, s90, v244
	v_add_u32_e32 v99, s90, v245
	v_add_u32_e32 v253, s90, v246
	v_add_u32_e32 v254, s90, v148
	v_add_u32_e32 v255, s90, v151
	v_med3_i32 v80, v80, 0, s99
	v_med3_i32 v83, v83, 0, s99
	v_med3_i32 v99, v99, 0, s99
	v_med3_i32 v253, v253, 0, s99
	v_med3_i32 v254, v254, 0, s99
	v_med3_i32 v255, v255, 0, s99
	v_mad_u32_u24 v80, v80, s100, v252
	v_mad_u32_u24 v83, v83, s100, v252
	v_mad_u32_u24 v99, v99, s100, v252
	v_mad_u32_u24 v253, v253, s100, v252
	v_mad_u32_u24 v254, v254, s100, v153
	v_mad_u32_u24 v255, v255, s100, v153
	global_load_dwordx4 v[116:119], v80, s[82:83]
	global_load_dwordx4 v[120:123], v83, s[82:83]
	global_load_dwordx4 v[124:127], v99, s[82:83]
	global_load_dwordx4 v[128:131], v253, s[82:83]
	global_load_dwordx4 v[132:135], v254, s[82:83] offset:768
	global_load_dwordx4 v[136:139], v255, s[82:83] offset:768
	global_load_dwordx4 v[140:143], v254, s[82:83] offset:832
	global_load_dwordx4 v[144:147], v255, s[82:83] offset:832
	ds_read_b64_tr_b16 v[72:73], v231
	ds_read_b64_tr_b16 v[74:75], v231 offset:512
	ds_read_b64_tr_b16 v[76:77], v231 offset:2048
	ds_read_b64_tr_b16 v[78:79], v231 offset:2560
	ds_read_b64_tr_b16 v[220:221], v231 offset:1024
	ds_read_b64_tr_b16 v[222:223], v231 offset:1536
	ds_read_b64_tr_b16 v[224:225], v231 offset:3072
	ds_read_b64_tr_b16 v[226:227], v231 offset:3584
	v_exp_f32_e32 v32, v32
	v_exp_f32_e32 v33, v33
	v_exp_f32_e32 v34, v34
	v_exp_f32_e32 v35, v35
	s_waitcnt vmcnt(8)
	ds_write_b128 v247, v[156:159]
	ds_write_b128 v247, v[160:163] offset:1024
	ds_write_b128 v247, v[164:167] offset:2048
	ds_write_b128 v247, v[168:171] offset:3072
	ds_read_b128 v[156:159], v248
	ds_read_b128 v[160:163], v249
	ds_read_b128 v[164:167], v250
	ds_read_b128 v[168:171], v251
	ds_write_b128 v112, v[172:175]
	ds_write_b128 v112, v[176:179] offset:1024
	ds_write_b128 v112, v[180:183] offset:2048
	ds_write_b128 v112, v[184:187] offset:3072
	v_mfma_f32_32x32x16_bf16 v[0:15], v[64:67], v[204:207], v[0:15]
	v_mfma_f32_32x32x16_bf16 v[16:31], v[64:67], v[208:211], v[16:31]
	v_mfma_f32_32x32x16_bf16 v[0:15], v[68:71], v[212:215], v[0:15]
	v_mfma_f32_32x32x16_bf16 v[16:31], v[68:71], v[216:219], v[16:31]
	v_exp_f32_e32 v36, v36
	v_exp_f32_e32 v37, v37
	v_exp_f32_e32 v38, v38
	v_exp_f32_e32 v39, v39
	s_waitcnt lgkmcnt(4)
	v_mfma_f32_32x32x16_bf16 v[188:203], v[156:159], v[48:51], v[188:203]
	v_exp_f32_e32 v40, v40
	v_exp_f32_e32 v41, v41
	v_mfma_f32_32x32x16_bf16 v[188:203], v[160:163], v[52:55], v[188:203]
	v_exp_f32_e32 v42, v42
	v_exp_f32_e32 v43, v43
	v_mfma_f32_32x32x16_bf16 v[188:203], v[164:167], v[56:59], v[188:203]
	v_exp_f32_e32 v44, v44
	v_exp_f32_e32 v45, v45
	v_mfma_f32_32x32x16_bf16 v[188:203], v[168:171], v[60:63], v[188:203]
	v_exp_f32_e32 v46, v46
	v_exp_f32_e32 v47, v47
	s_add_i32 s90, s76, -1024
	v_lshlrev_b32_e32 v84, 4, v107
	v_add_u32_e32 v84, s90, v84
	v_add_u32_e32 v85, 0, v84
	v_add_u32_e32 v86, 16, v84
	v_add_u32_e32 v87, 32, v84
	v_add_u32_e32 v88, 48, v84
	v_cmp_gt_u32_e64 s[30:31], s98, v85
	v_cmp_gt_u32_e64 s[36:37], s98, v86
	v_cmp_gt_u32_e64 s[78:79], s98, v87
	v_cmp_gt_u32_e64 s[50:51], s98, v88
	v_cndmask_b32_e64 v32, 0, v32, s[30:31]
	v_add_u32_e32 v85, 128, v84
	v_cmp_gt_u32_e64 s[30:31], s98, v85
	v_cndmask_b32_e64 v33, 0, v33, s[36:37]
	v_add_u32_e32 v86, 144, v84
	v_cmp_gt_u32_e64 s[36:37], s98, v86
	v_cndmask_b32_e64 v34, 0, v34, s[78:79]
	v_add_u32_e32 v87, 160, v84
	v_cmp_gt_u32_e64 s[78:79], s98, v87
	v_cndmask_b32_e64 v35, 0, v35, s[50:51]
	v_add_u32_e32 v88, 176, v84
	v_cmp_gt_u32_e64 s[50:51], s98, v88
	v_cndmask_b32_e64 v36, 0, v36, s[30:31]
	v_add_u32_e32 v85, 256, v84
	v_cmp_gt_u32_e64 s[30:31], s98, v85
	v_cndmask_b32_e64 v37, 0, v37, s[36:37]
	v_add_u32_e32 v86, 272, v84
	v_cmp_gt_u32_e64 s[36:37], s98, v86
	v_cndmask_b32_e64 v38, 0, v38, s[78:79]
	v_add_u32_e32 v87, 288, v84
	v_cmp_gt_u32_e64 s[78:79], s98, v87
	v_cndmask_b32_e64 v39, 0, v39, s[50:51]
	v_add_u32_e32 v88, 304, v84
	v_cmp_gt_u32_e64 s[50:51], s98, v88
	v_cndmask_b32_e64 v40, 0, v40, s[30:31]
	v_add_u32_e32 v85, 384, v84
	v_cmp_gt_u32_e64 s[30:31], s98, v85
	v_cndmask_b32_e64 v41, 0, v41, s[36:37]
	v_add_u32_e32 v86, 400, v84
	v_cmp_gt_u32_e64 s[36:37], s98, v86
	v_cndmask_b32_e64 v42, 0, v42, s[78:79]
	v_add_u32_e32 v87, 416, v84
	v_cmp_gt_u32_e64 s[78:79], s98, v87
	v_cndmask_b32_e64 v43, 0, v43, s[50:51]
	v_add_u32_e32 v88, 432, v84
	v_cmp_gt_u32_e64 s[50:51], s98, v88
	v_nop
	v_cndmask_b32_e64 v44, 0, v44, s[30:31]
	v_cndmask_b32_e64 v45, 0, v45, s[36:37]
	v_cndmask_b32_e64 v46, 0, v46, s[78:79]
	v_cndmask_b32_e64 v47, 0, v47, s[50:51]
	v_cvt_pk_bf16_f32 v64, v32, v33
	v_cvt_pk_bf16_f32 v65, v34, v35
	v_cvt_pk_bf16_f32 v66, v36, v37
	v_cvt_pk_bf16_f32 v67, v38, v39
	v_cvt_pk_bf16_f32 v68, v40, v41
	v_cvt_pk_bf16_f32 v69, v42, v43
	v_cvt_pk_bf16_f32 v70, v44, v45
	v_cvt_pk_bf16_f32 v71, v46, v47
	v_pk_add_f32 v[232:233], v[232:233], v[32:33]
	v_pk_add_f32 v[232:233], v[232:233], v[34:35]
	v_pk_add_f32 v[232:233], v[232:233], v[36:37]
	v_pk_add_f32 v[232:233], v[232:233], v[38:39]
	v_pk_add_f32 v[232:233], v[232:233], v[40:41]
	v_pk_add_f32 v[232:233], v[232:233], v[42:43]
	v_pk_add_f32 v[232:233], v[232:233], v[44:45]
	v_pk_add_f32 v[232:233], v[232:233], v[46:47]
	ds_read2_b32 v[32:33], v115 offset0:64 offset1:65
	ds_read2_b32 v[34:35], v115 offset0:66 offset1:67
	ds_read2_b32 v[36:37], v115 offset0:72 offset1:73
	ds_read2_b32 v[38:39], v115 offset0:74 offset1:75
	ds_read2_b32 v[40:41], v115 offset0:80 offset1:81
	ds_read2_b32 v[42:43], v115 offset0:82 offset1:83
	ds_read2_b32 v[44:45], v115 offset0:88 offset1:89
	ds_read2_b32 v[46:47], v115 offset0:90 offset1:91
	s_add_i32 s90, s76, 512
	v_add_u32_e32 v80, s90, v243
	v_add_u32_e32 v83, s90, v244
	v_add_u32_e32 v99, s90, v245
	v_add_u32_e32 v253, s90, v246
	v_add_u32_e32 v254, s90, v148
	v_add_u32_e32 v255, s90, v151
	v_med3_i32 v80, v80, 0, s99
	v_med3_i32 v83, v83, 0, s99
	v_med3_i32 v99, v99, 0, s99
	v_med3_i32 v253, v253, 0, s99
	v_med3_i32 v254, v254, 0, s99
	v_med3_i32 v255, v255, 0, s99
	v_mad_u32_u24 v80, v80, s100, v252
	v_mad_u32_u24 v83, v83, s100, v252
	v_mad_u32_u24 v99, v99, s100, v252
	v_mad_u32_u24 v253, v253, s100, v252
	v_mad_u32_u24 v254, v254, s100, v153
	v_mad_u32_u24 v255, v255, s100, v153
	global_load_dwordx4 v[156:159], v80, s[82:83]
	global_load_dwordx4 v[160:163], v83, s[82:83]
	global_load_dwordx4 v[164:167], v99, s[82:83]
	global_load_dwordx4 v[168:171], v253, s[82:83]
	global_load_dwordx4 v[172:175], v254, s[82:83] offset:768
	global_load_dwordx4 v[176:179], v255, s[82:83] offset:768
	global_load_dwordx4 v[180:183], v254, s[82:83] offset:832
	global_load_dwordx4 v[184:187], v255, s[82:83] offset:832
	ds_read_b64_tr_b16 v[204:205], v231
	ds_read_b64_tr_b16 v[206:207], v231 offset:512
	ds_read_b64_tr_b16 v[208:209], v231 offset:2048
	ds_read_b64_tr_b16 v[210:211], v231 offset:2560
	ds_read_b64_tr_b16 v[212:213], v231 offset:1024
	ds_read_b64_tr_b16 v[214:215], v231 offset:1536
	ds_read_b64_tr_b16 v[216:217], v231 offset:3072
	ds_read_b64_tr_b16 v[218:219], v231 offset:3584
	v_exp_f32_e32 v188, v188
	v_exp_f32_e32 v189, v189
	v_exp_f32_e32 v190, v190
	v_exp_f32_e32 v191, v191
	s_waitcnt vmcnt(8)
	ds_write_b128 v247, v[116:119]
	ds_write_b128 v247, v[120:123] offset:1024
	ds_write_b128 v247, v[124:127] offset:2048
	ds_write_b128 v247, v[128:131] offset:3072
	ds_read_b128 v[116:119], v248
	ds_read_b128 v[120:123], v249
	ds_read_b128 v[124:127], v250
	ds_read_b128 v[128:131], v251
	ds_write_b128 v112, v[132:135]
	ds_write_b128 v112, v[136:139] offset:1024
	ds_write_b128 v112, v[140:143] offset:2048
	ds_write_b128 v112, v[144:147] offset:3072
	v_mfma_f32_32x32x16_bf16 v[0:15], v[64:67], v[72:75], v[0:15]
	v_mfma_f32_32x32x16_bf16 v[16:31], v[64:67], v[76:79], v[16:31]
	v_mfma_f32_32x32x16_bf16 v[0:15], v[68:71], v[220:223], v[0:15]
	v_mfma_f32_32x32x16_bf16 v[16:31], v[68:71], v[224:227], v[16:31]
	v_exp_f32_e32 v192, v192
	v_exp_f32_e32 v193, v193
	v_exp_f32_e32 v194, v194
	v_exp_f32_e32 v195, v195
	s_waitcnt lgkmcnt(4)
	v_mfma_f32_32x32x16_bf16 v[32:47], v[116:119], v[48:51], v[32:47]
	v_exp_f32_e32 v196, v196
	v_exp_f32_e32 v197, v197
	v_mfma_f32_32x32x16_bf16 v[32:47], v[120:123], v[52:55], v[32:47]
	v_exp_f32_e32 v198, v198
	v_exp_f32_e32 v199, v199
	v_mfma_f32_32x32x16_bf16 v[32:47], v[124:127], v[56:59], v[32:47]
	v_exp_f32_e32 v200, v200
	v_exp_f32_e32 v201, v201
	v_mfma_f32_32x32x16_bf16 v[32:47], v[128:131], v[60:63], v[32:47]
	v_exp_f32_e32 v202, v202
	v_exp_f32_e32 v203, v203
	s_add_i32 s90, s76, -512
	v_lshlrev_b32_e32 v84, 4, v107
	v_add_u32_e32 v84, s90, v84
	v_add_u32_e32 v85, 0, v84
	v_add_u32_e32 v86, 16, v84
	v_add_u32_e32 v87, 32, v84
	v_add_u32_e32 v88, 48, v84
	v_cmp_gt_u32_e64 s[30:31], s98, v85
	v_cmp_gt_u32_e64 s[36:37], s98, v86
	v_cmp_gt_u32_e64 s[78:79], s98, v87
	v_cmp_gt_u32_e64 s[50:51], s98, v88
	v_cndmask_b32_e64 v188, 0, v188, s[30:31]
	v_add_u32_e32 v85, 128, v84
	v_cmp_gt_u32_e64 s[30:31], s98, v85
	v_cndmask_b32_e64 v189, 0, v189, s[36:37]
	v_add_u32_e32 v86, 144, v84
	v_cmp_gt_u32_e64 s[36:37], s98, v86
	v_cndmask_b32_e64 v190, 0, v190, s[78:79]
	v_add_u32_e32 v87, 160, v84
	v_cmp_gt_u32_e64 s[78:79], s98, v87
	v_cndmask_b32_e64 v191, 0, v191, s[50:51]
	v_add_u32_e32 v88, 176, v84
	v_cmp_gt_u32_e64 s[50:51], s98, v88
	v_cndmask_b32_e64 v192, 0, v192, s[30:31]
	v_add_u32_e32 v85, 256, v84
	v_cmp_gt_u32_e64 s[30:31], s98, v85
	v_cndmask_b32_e64 v193, 0, v193, s[36:37]
	v_add_u32_e32 v86, 272, v84
	v_cmp_gt_u32_e64 s[36:37], s98, v86
	v_cndmask_b32_e64 v194, 0, v194, s[78:79]
	v_add_u32_e32 v87, 288, v84
	v_cmp_gt_u32_e64 s[78:79], s98, v87
	v_cndmask_b32_e64 v195, 0, v195, s[50:51]
	v_add_u32_e32 v88, 304, v84
	v_cmp_gt_u32_e64 s[50:51], s98, v88
	v_cndmask_b32_e64 v196, 0, v196, s[30:31]
	v_add_u32_e32 v85, 384, v84
	v_cmp_gt_u32_e64 s[30:31], s98, v85
	v_cndmask_b32_e64 v197, 0, v197, s[36:37]
	v_add_u32_e32 v86, 400, v84
	v_cmp_gt_u32_e64 s[36:37], s98, v86
	v_cndmask_b32_e64 v198, 0, v198, s[78:79]
	v_add_u32_e32 v87, 416, v84
	v_cmp_gt_u32_e64 s[78:79], s98, v87
	v_cndmask_b32_e64 v199, 0, v199, s[50:51]
	v_add_u32_e32 v88, 432, v84
	v_cmp_gt_u32_e64 s[50:51], s98, v88
	v_nop
	v_cndmask_b32_e64 v200, 0, v200, s[30:31]
	v_cndmask_b32_e64 v201, 0, v201, s[36:37]
	v_cndmask_b32_e64 v202, 0, v202, s[78:79]
	v_cndmask_b32_e64 v203, 0, v203, s[50:51]
	v_cvt_pk_bf16_f32 v64, v188, v189
	v_cvt_pk_bf16_f32 v65, v190, v191
	v_cvt_pk_bf16_f32 v66, v192, v193
	v_cvt_pk_bf16_f32 v67, v194, v195
	v_cvt_pk_bf16_f32 v68, v196, v197
	v_cvt_pk_bf16_f32 v69, v198, v199
	v_cvt_pk_bf16_f32 v70, v200, v201
	v_cvt_pk_bf16_f32 v71, v202, v203
	v_pk_add_f32 v[232:233], v[232:233], v[188:189]
	v_pk_add_f32 v[232:233], v[232:233], v[190:191]
	v_pk_add_f32 v[232:233], v[232:233], v[192:193]
	v_pk_add_f32 v[232:233], v[232:233], v[194:195]
	v_pk_add_f32 v[232:233], v[232:233], v[196:197]
	v_pk_add_f32 v[232:233], v[232:233], v[198:199]
	v_pk_add_f32 v[232:233], v[232:233], v[200:201]
	v_pk_add_f32 v[232:233], v[232:233], v[202:203]
	ds_read2_b32 v[188:189], v115 offset0:96 offset1:97
	ds_read2_b32 v[190:191], v115 offset0:98 offset1:99
	ds_read2_b32 v[192:193], v115 offset0:104 offset1:105
	ds_read2_b32 v[194:195], v115 offset0:106 offset1:107
	ds_read2_b32 v[196:197], v115 offset0:112 offset1:113
	ds_read2_b32 v[198:199], v115 offset0:114 offset1:115
	ds_read2_b32 v[200:201], v115 offset0:120 offset1:121
	ds_read2_b32 v[202:203], v115 offset0:122 offset1:123
	s_add_i32 s90, s76, 1024
	v_add_u32_e32 v80, s90, v243
	v_add_u32_e32 v83, s90, v244
	v_add_u32_e32 v99, s90, v245
	v_add_u32_e32 v253, s90, v246
	v_add_u32_e32 v254, s90, v148
	v_add_u32_e32 v255, s90, v151
	v_med3_i32 v80, v80, 0, s99
	v_med3_i32 v83, v83, 0, s99
	v_med3_i32 v99, v99, 0, s99
	v_med3_i32 v253, v253, 0, s99
	v_med3_i32 v254, v254, 0, s99
	v_med3_i32 v255, v255, 0, s99
	v_mad_u32_u24 v80, v80, s100, v252
	v_mad_u32_u24 v83, v83, s100, v252
	v_mad_u32_u24 v99, v99, s100, v252
	v_mad_u32_u24 v253, v253, s100, v252
	v_mad_u32_u24 v254, v254, s100, v153
	v_mad_u32_u24 v255, v255, s100, v153
	global_load_dwordx4 v[116:119], v80, s[82:83]
	global_load_dwordx4 v[120:123], v83, s[82:83]
	global_load_dwordx4 v[124:127], v99, s[82:83]
	global_load_dwordx4 v[128:131], v253, s[82:83]
	global_load_dwordx4 v[132:135], v254, s[82:83] offset:768
	global_load_dwordx4 v[136:139], v255, s[82:83] offset:768
	global_load_dwordx4 v[140:143], v254, s[82:83] offset:832
	global_load_dwordx4 v[144:147], v255, s[82:83] offset:832
	ds_read_b64_tr_b16 v[72:73], v231
	ds_read_b64_tr_b16 v[74:75], v231 offset:512
	ds_read_b64_tr_b16 v[76:77], v231 offset:2048
	ds_read_b64_tr_b16 v[78:79], v231 offset:2560
	ds_read_b64_tr_b16 v[220:221], v231 offset:1024
	ds_read_b64_tr_b16 v[222:223], v231 offset:1536
	ds_read_b64_tr_b16 v[224:225], v231 offset:3072
	ds_read_b64_tr_b16 v[226:227], v231 offset:3584
	v_exp_f32_e32 v32, v32
	v_exp_f32_e32 v33, v33
	v_exp_f32_e32 v34, v34
	v_exp_f32_e32 v35, v35
	s_waitcnt vmcnt(8)
	ds_write_b128 v247, v[156:159]
	ds_write_b128 v247, v[160:163] offset:1024
	ds_write_b128 v247, v[164:167] offset:2048
	ds_write_b128 v247, v[168:171] offset:3072
	ds_read_b128 v[156:159], v248
	ds_read_b128 v[160:163], v249
	ds_read_b128 v[164:167], v250
	ds_read_b128 v[168:171], v251
	ds_write_b128 v112, v[172:175]
	ds_write_b128 v112, v[176:179] offset:1024
	ds_write_b128 v112, v[180:183] offset:2048
	ds_write_b128 v112, v[184:187] offset:3072
	v_mfma_f32_32x32x16_bf16 v[0:15], v[64:67], v[204:207], v[0:15]
	v_mfma_f32_32x32x16_bf16 v[16:31], v[64:67], v[208:211], v[16:31]
	v_mfma_f32_32x32x16_bf16 v[0:15], v[68:71], v[212:215], v[0:15]
	v_mfma_f32_32x32x16_bf16 v[16:31], v[68:71], v[216:219], v[16:31]
	v_exp_f32_e32 v36, v36
	v_exp_f32_e32 v37, v37
	v_exp_f32_e32 v38, v38
	v_exp_f32_e32 v39, v39
	s_waitcnt lgkmcnt(4)
	v_mfma_f32_32x32x16_bf16 v[188:203], v[156:159], v[48:51], v[188:203]
	v_exp_f32_e32 v40, v40
	v_exp_f32_e32 v41, v41
	v_mfma_f32_32x32x16_bf16 v[188:203], v[160:163], v[52:55], v[188:203]
	v_exp_f32_e32 v42, v42
	v_exp_f32_e32 v43, v43
	v_mfma_f32_32x32x16_bf16 v[188:203], v[164:167], v[56:59], v[188:203]
	v_exp_f32_e32 v44, v44
	v_exp_f32_e32 v45, v45
	v_mfma_f32_32x32x16_bf16 v[188:203], v[168:171], v[60:63], v[188:203]
	v_exp_f32_e32 v46, v46
	v_exp_f32_e32 v47, v47
	s_add_i32 s90, s76, 0
	v_lshlrev_b32_e32 v84, 4, v107
	v_add_u32_e32 v84, s90, v84
	v_add_u32_e32 v85, 0, v84
	v_add_u32_e32 v86, 16, v84
	v_add_u32_e32 v87, 32, v84
	v_add_u32_e32 v88, 48, v84
	v_cmp_gt_u32_e64 s[30:31], s98, v85
	v_cmp_gt_u32_e64 s[36:37], s98, v86
	v_cmp_gt_u32_e64 s[78:79], s98, v87
	v_cmp_gt_u32_e64 s[50:51], s98, v88
	v_cndmask_b32_e64 v32, 0, v32, s[30:31]
	v_add_u32_e32 v85, 128, v84
	v_cmp_gt_u32_e64 s[30:31], s98, v85
	v_cndmask_b32_e64 v33, 0, v33, s[36:37]
	v_add_u32_e32 v86, 144, v84
	v_cmp_gt_u32_e64 s[36:37], s98, v86
	v_cndmask_b32_e64 v34, 0, v34, s[78:79]
	v_add_u32_e32 v87, 160, v84
	v_cmp_gt_u32_e64 s[78:79], s98, v87
	v_cndmask_b32_e64 v35, 0, v35, s[50:51]
	v_add_u32_e32 v88, 176, v84
	v_cmp_gt_u32_e64 s[50:51], s98, v88
	v_cndmask_b32_e64 v36, 0, v36, s[30:31]
	v_add_u32_e32 v85, 256, v84
	v_cmp_gt_u32_e64 s[30:31], s98, v85
	v_cndmask_b32_e64 v37, 0, v37, s[36:37]
	v_add_u32_e32 v86, 272, v84
	v_cmp_gt_u32_e64 s[36:37], s98, v86
	v_cndmask_b32_e64 v38, 0, v38, s[78:79]
	v_add_u32_e32 v87, 288, v84
	v_cmp_gt_u32_e64 s[78:79], s98, v87
	v_cndmask_b32_e64 v39, 0, v39, s[50:51]
	v_add_u32_e32 v88, 304, v84
	v_cmp_gt_u32_e64 s[50:51], s98, v88
	v_cndmask_b32_e64 v40, 0, v40, s[30:31]
	v_add_u32_e32 v85, 384, v84
	v_cmp_gt_u32_e64 s[30:31], s98, v85
	v_cndmask_b32_e64 v41, 0, v41, s[36:37]
	v_add_u32_e32 v86, 400, v84
	v_cmp_gt_u32_e64 s[36:37], s98, v86
	v_cndmask_b32_e64 v42, 0, v42, s[78:79]
	v_add_u32_e32 v87, 416, v84
	v_cmp_gt_u32_e64 s[78:79], s98, v87
	v_cndmask_b32_e64 v43, 0, v43, s[50:51]
	v_add_u32_e32 v88, 432, v84
	v_cmp_gt_u32_e64 s[50:51], s98, v88
	v_nop
	v_cndmask_b32_e64 v44, 0, v44, s[30:31]
	v_cndmask_b32_e64 v45, 0, v45, s[36:37]
	v_cndmask_b32_e64 v46, 0, v46, s[78:79]
	v_cndmask_b32_e64 v47, 0, v47, s[50:51]
	v_cvt_pk_bf16_f32 v64, v32, v33
	v_cvt_pk_bf16_f32 v65, v34, v35
	v_cvt_pk_bf16_f32 v66, v36, v37
	v_cvt_pk_bf16_f32 v67, v38, v39
	v_cvt_pk_bf16_f32 v68, v40, v41
	v_cvt_pk_bf16_f32 v69, v42, v43
	v_cvt_pk_bf16_f32 v70, v44, v45
	v_cvt_pk_bf16_f32 v71, v46, v47
	v_pk_add_f32 v[232:233], v[232:233], v[32:33]
	v_pk_add_f32 v[232:233], v[232:233], v[34:35]
	v_pk_add_f32 v[232:233], v[232:233], v[36:37]
	v_pk_add_f32 v[232:233], v[232:233], v[38:39]
	v_pk_add_f32 v[232:233], v[232:233], v[40:41]
	v_pk_add_f32 v[232:233], v[232:233], v[42:43]
	v_pk_add_f32 v[232:233], v[232:233], v[44:45]
	v_pk_add_f32 v[232:233], v[232:233], v[46:47]
	ds_read2_b32 v[32:33], v115 offset0:128 offset1:129
	ds_read2_b32 v[34:35], v115 offset0:130 offset1:131
	ds_read2_b32 v[36:37], v115 offset0:136 offset1:137
	ds_read2_b32 v[38:39], v115 offset0:138 offset1:139
	ds_read2_b32 v[40:41], v115 offset0:144 offset1:145
	ds_read2_b32 v[42:43], v115 offset0:146 offset1:147
	ds_read2_b32 v[44:45], v115 offset0:152 offset1:153
	ds_read2_b32 v[46:47], v115 offset0:154 offset1:155
	ds_read_b64_tr_b16 v[204:205], v231
	ds_read_b64_tr_b16 v[206:207], v231 offset:512
	ds_read_b64_tr_b16 v[208:209], v231 offset:2048
	ds_read_b64_tr_b16 v[210:211], v231 offset:2560
	ds_read_b64_tr_b16 v[212:213], v231 offset:1024
	ds_read_b64_tr_b16 v[214:215], v231 offset:1536
	ds_read_b64_tr_b16 v[216:217], v231 offset:3072
	ds_read_b64_tr_b16 v[218:219], v231 offset:3584
	v_exp_f32_e32 v188, v188
	v_exp_f32_e32 v189, v189
	v_exp_f32_e32 v190, v190
	v_exp_f32_e32 v191, v191
	s_waitcnt vmcnt(0)
	ds_write_b128 v247, v[116:119]
	ds_write_b128 v247, v[120:123] offset:1024
	ds_write_b128 v247, v[124:127] offset:2048
	ds_write_b128 v247, v[128:131] offset:3072
	ds_read_b128 v[116:119], v248
	ds_read_b128 v[120:123], v249
	ds_read_b128 v[124:127], v250
	ds_read_b128 v[128:131], v251
	ds_write_b128 v112, v[132:135]
	ds_write_b128 v112, v[136:139] offset:1024
	ds_write_b128 v112, v[140:143] offset:2048
	ds_write_b128 v112, v[144:147] offset:3072
	v_mfma_f32_32x32x16_bf16 v[0:15], v[64:67], v[72:75], v[0:15]
	v_mfma_f32_32x32x16_bf16 v[16:31], v[64:67], v[76:79], v[16:31]
	v_mfma_f32_32x32x16_bf16 v[0:15], v[68:71], v[220:223], v[0:15]
	v_mfma_f32_32x32x16_bf16 v[16:31], v[68:71], v[224:227], v[16:31]
	v_exp_f32_e32 v192, v192
	v_exp_f32_e32 v193, v193
	v_exp_f32_e32 v194, v194
	v_exp_f32_e32 v195, v195
	s_waitcnt lgkmcnt(4)
	v_mfma_f32_32x32x16_bf16 v[32:47], v[116:119], v[48:51], v[32:47]
	v_exp_f32_e32 v196, v196
	v_exp_f32_e32 v197, v197
	v_mfma_f32_32x32x16_bf16 v[32:47], v[120:123], v[52:55], v[32:47]
	v_exp_f32_e32 v198, v198
	v_exp_f32_e32 v199, v199
	v_mfma_f32_32x32x16_bf16 v[32:47], v[124:127], v[56:59], v[32:47]
	v_exp_f32_e32 v200, v200
	v_exp_f32_e32 v201, v201
	v_mfma_f32_32x32x16_bf16 v[32:47], v[128:131], v[60:63], v[32:47]
	v_exp_f32_e32 v202, v202
	v_exp_f32_e32 v203, v203
	s_add_i32 s90, s76, 512
	v_lshlrev_b32_e32 v84, 4, v107
	v_add_u32_e32 v84, s90, v84
	v_add_u32_e32 v85, 0, v84
	v_add_u32_e32 v86, 16, v84
	v_add_u32_e32 v87, 32, v84
	v_add_u32_e32 v88, 48, v84
	v_cmp_gt_u32_e64 s[30:31], s98, v85
	v_cmp_gt_u32_e64 s[36:37], s98, v86
	v_cmp_gt_u32_e64 s[78:79], s98, v87
	v_cmp_gt_u32_e64 s[50:51], s98, v88
	v_cndmask_b32_e64 v188, 0, v188, s[30:31]
	v_add_u32_e32 v85, 128, v84
	v_cmp_gt_u32_e64 s[30:31], s98, v85
	v_cndmask_b32_e64 v189, 0, v189, s[36:37]
	v_add_u32_e32 v86, 144, v84
	v_cmp_gt_u32_e64 s[36:37], s98, v86
	v_cndmask_b32_e64 v190, 0, v190, s[78:79]
	v_add_u32_e32 v87, 160, v84
	v_cmp_gt_u32_e64 s[78:79], s98, v87
	v_cndmask_b32_e64 v191, 0, v191, s[50:51]
	v_add_u32_e32 v88, 176, v84
	v_cmp_gt_u32_e64 s[50:51], s98, v88
	v_cndmask_b32_e64 v192, 0, v192, s[30:31]
	v_add_u32_e32 v85, 256, v84
	v_cmp_gt_u32_e64 s[30:31], s98, v85
	v_cndmask_b32_e64 v193, 0, v193, s[36:37]
	v_add_u32_e32 v86, 272, v84
	v_cmp_gt_u32_e64 s[36:37], s98, v86
	v_cndmask_b32_e64 v194, 0, v194, s[78:79]
	v_add_u32_e32 v87, 288, v84
	v_cmp_gt_u32_e64 s[78:79], s98, v87
	v_cndmask_b32_e64 v195, 0, v195, s[50:51]
	v_add_u32_e32 v88, 304, v84
	v_cmp_gt_u32_e64 s[50:51], s98, v88
	v_cndmask_b32_e64 v196, 0, v196, s[30:31]
	v_add_u32_e32 v85, 384, v84
	v_cmp_gt_u32_e64 s[30:31], s98, v85
	v_cndmask_b32_e64 v197, 0, v197, s[36:37]
	v_add_u32_e32 v86, 400, v84
	v_cmp_gt_u32_e64 s[36:37], s98, v86
	v_cndmask_b32_e64 v198, 0, v198, s[78:79]
	v_add_u32_e32 v87, 416, v84
	v_cmp_gt_u32_e64 s[78:79], s98, v87
	v_cndmask_b32_e64 v199, 0, v199, s[50:51]
	v_add_u32_e32 v88, 432, v84
	v_cmp_gt_u32_e64 s[50:51], s98, v88
	v_nop
	v_cndmask_b32_e64 v200, 0, v200, s[30:31]
	v_cndmask_b32_e64 v201, 0, v201, s[36:37]
	v_cndmask_b32_e64 v202, 0, v202, s[78:79]
	v_cndmask_b32_e64 v203, 0, v203, s[50:51]
	v_cvt_pk_bf16_f32 v64, v188, v189
	v_cvt_pk_bf16_f32 v65, v190, v191
	v_cvt_pk_bf16_f32 v66, v192, v193
	v_cvt_pk_bf16_f32 v67, v194, v195
	v_cvt_pk_bf16_f32 v68, v196, v197
	v_cvt_pk_bf16_f32 v69, v198, v199
	v_cvt_pk_bf16_f32 v70, v200, v201
	v_cvt_pk_bf16_f32 v71, v202, v203
	v_pk_add_f32 v[232:233], v[232:233], v[188:189]
	v_pk_add_f32 v[232:233], v[232:233], v[190:191]
	v_pk_add_f32 v[232:233], v[232:233], v[192:193]
	v_pk_add_f32 v[232:233], v[232:233], v[194:195]
	v_pk_add_f32 v[232:233], v[232:233], v[196:197]
	v_pk_add_f32 v[232:233], v[232:233], v[198:199]
	v_pk_add_f32 v[232:233], v[232:233], v[200:201]
	v_pk_add_f32 v[232:233], v[232:233], v[202:203]
	ds_read_b64_tr_b16 v[72:73], v231
	ds_read_b64_tr_b16 v[74:75], v231 offset:512
	ds_read_b64_tr_b16 v[76:77], v231 offset:2048
	ds_read_b64_tr_b16 v[78:79], v231 offset:2560
	ds_read_b64_tr_b16 v[220:221], v231 offset:1024
	ds_read_b64_tr_b16 v[222:223], v231 offset:1536
	ds_read_b64_tr_b16 v[224:225], v231 offset:3072
	ds_read_b64_tr_b16 v[226:227], v231 offset:3584
	s_waitcnt lgkmcnt(0)
; #define LAS __attribute__((address_space(3)))
; __device__ __forceinline__ int crow(int r, int hi) { return (r & 3) + 8 * (r >> 2) + 4 * hi; }
; __device__ __forceinline__ void dil_unit(LAS unsigned char* lds, bf16_t* proj, int seq, int hd, int T0, int rho) {
;     ...
;     LAS bf16_t* stg = (LAS bf16_t*)wbuf;
;     l += __shfl_xor(l, 32);
; #pragma unroll
;     for (int rr = 0; rr < 16; ++rr) {
;         const int j = crow(rr, hi);
;         const float il = __builtin_amdgcn_rcpf(__shfl(l, j));
	v_mfma_f32_32x32x16_bf16 v[0:15], v[64:67], v[204:207], v[0:15]
	v_mfma_f32_32x32x16_bf16 v[16:31], v[64:67], v[208:211], v[16:31]
	v_mfma_f32_32x32x16_bf16 v[0:15], v[68:71], v[212:215], v[0:15]
	v_mfma_f32_32x32x16_bf16 v[16:31], v[68:71], v[216:219], v[16:31]
	v_exp_f32_e32 v32, v32
	v_exp_f32_e32 v33, v33
	v_exp_f32_e32 v34, v34
	v_exp_f32_e32 v35, v35
	v_exp_f32_e32 v36, v36
	v_exp_f32_e32 v37, v37
	v_exp_f32_e32 v38, v38
	v_exp_f32_e32 v39, v39
	v_exp_f32_e32 v40, v40
	v_exp_f32_e32 v41, v41
	v_exp_f32_e32 v42, v42
	v_exp_f32_e32 v43, v43
	v_exp_f32_e32 v44, v44
	v_exp_f32_e32 v45, v45
	v_exp_f32_e32 v46, v46
	v_exp_f32_e32 v47, v47
	s_add_i32 s90, s76, 1024
	v_lshlrev_b32_e32 v84, 4, v107
	v_add_u32_e32 v84, s90, v84
	v_add_u32_e32 v85, 0, v84
	v_add_u32_e32 v86, 16, v84
	v_add_u32_e32 v87, 32, v84
	v_add_u32_e32 v88, 48, v84
	v_cmp_gt_u32_e64 s[30:31], s98, v85
	v_cmp_gt_u32_e64 s[36:37], s98, v86
	v_cmp_gt_u32_e64 s[78:79], s98, v87
	v_cmp_gt_u32_e64 s[50:51], s98, v88
	v_cndmask_b32_e64 v32, 0, v32, s[30:31]
	v_add_u32_e32 v85, 128, v84
	v_cmp_gt_u32_e64 s[30:31], s98, v85
	v_cndmask_b32_e64 v33, 0, v33, s[36:37]
	v_add_u32_e32 v86, 144, v84
	v_cmp_gt_u32_e64 s[36:37], s98, v86
	v_cndmask_b32_e64 v34, 0, v34, s[78:79]
	v_add_u32_e32 v87, 160, v84
	v_cmp_gt_u32_e64 s[78:79], s98, v87
	v_cndmask_b32_e64 v35, 0, v35, s[50:51]
	v_add_u32_e32 v88, 176, v84
	v_cmp_gt_u32_e64 s[50:51], s98, v88
	v_cndmask_b32_e64 v36, 0, v36, s[30:31]
	v_add_u32_e32 v85, 256, v84
	v_cmp_gt_u32_e64 s[30:31], s98, v85
	v_cndmask_b32_e64 v37, 0, v37, s[36:37]
	v_add_u32_e32 v86, 272, v84
	v_cmp_gt_u32_e64 s[36:37], s98, v86
	v_cndmask_b32_e64 v38, 0, v38, s[78:79]
	v_add_u32_e32 v87, 288, v84
	v_cmp_gt_u32_e64 s[78:79], s98, v87
	v_cndmask_b32_e64 v39, 0, v39, s[50:51]
	v_add_u32_e32 v88, 304, v84
	v_cmp_gt_u32_e64 s[50:51], s98, v88
	v_cndmask_b32_e64 v40, 0, v40, s[30:31]
	v_add_u32_e32 v85, 384, v84
	v_cmp_gt_u32_e64 s[30:31], s98, v85
	v_cndmask_b32_e64 v41, 0, v41, s[36:37]
	v_add_u32_e32 v86, 400, v84
	v_cmp_gt_u32_e64 s[36:37], s98, v86
	v_cndmask_b32_e64 v42, 0, v42, s[78:79]
	v_add_u32_e32 v87, 416, v84
	v_cmp_gt_u32_e64 s[78:79], s98, v87
	v_cndmask_b32_e64 v43, 0, v43, s[50:51]
	v_add_u32_e32 v88, 432, v84
	v_cmp_gt_u32_e64 s[50:51], s98, v88
	v_nop
	v_cndmask_b32_e64 v44, 0, v44, s[30:31]
	v_cndmask_b32_e64 v45, 0, v45, s[36:37]
	v_cndmask_b32_e64 v46, 0, v46, s[78:79]
	v_cndmask_b32_e64 v47, 0, v47, s[50:51]
	v_cvt_pk_bf16_f32 v64, v32, v33
	v_cvt_pk_bf16_f32 v65, v34, v35
	v_cvt_pk_bf16_f32 v66, v36, v37
	v_cvt_pk_bf16_f32 v67, v38, v39
	v_cvt_pk_bf16_f32 v68, v40, v41
	v_cvt_pk_bf16_f32 v69, v42, v43
	v_cvt_pk_bf16_f32 v70, v44, v45
	v_cvt_pk_bf16_f32 v71, v46, v47
	v_pk_add_f32 v[232:233], v[232:233], v[32:33]
	v_pk_add_f32 v[232:233], v[232:233], v[34:35]
	v_pk_add_f32 v[232:233], v[232:233], v[36:37]
	v_pk_add_f32 v[232:233], v[232:233], v[38:39]
	v_pk_add_f32 v[232:233], v[232:233], v[40:41]
	v_pk_add_f32 v[232:233], v[232:233], v[42:43]
	v_pk_add_f32 v[232:233], v[232:233], v[44:45]
	v_pk_add_f32 v[232:233], v[232:233], v[46:47]
	v_mfma_f32_32x32x16_bf16 v[0:15], v[64:67], v[72:75], v[0:15]
	v_mfma_f32_32x32x16_bf16 v[16:31], v[64:67], v[76:79], v[16:31]
	v_mfma_f32_32x32x16_bf16 v[0:15], v[68:71], v[220:223], v[0:15]
	v_mfma_f32_32x32x16_bf16 v[16:31], v[68:71], v[224:227], v[16:31]
	v_add_f32_e32 v113, v232, v233
	v_or_b32_e32 v114, 1, v107
	v_or_b32_e32 v97, 2, v107
	v_or_b32_e32 v96, 3, v107
	v_or_b32_e32 v95, 8, v107
	v_or_b32_e32 v94, 9, v107
	v_or_b32_e32 v93, 10, v107
	v_or_b32_e32 v92, 11, v107
	v_or_b32_e32 v91, 16, v107
	v_or_b32_e32 v90, 17, v107
	v_or_b32_e32 v89, 18, v107
	v_or_b32_e32 v88, 19, v107
	v_or_b32_e32 v87, 24, v107
	v_or_b32_e32 v86, 25, v107
	v_or_b32_e32 v85, 26, v107
	v_or_b32_e32 v84, 27, v107
	s_nop 11
	s_branch .LBB0_553

; #define LAS __attribute__((address_space(3)))
; #define GAS __attribute__((address_space(1)))
; __device__ __forceinline__ void dil_unit(LAS unsigned char* lds, bf16_t* proj, int seq, int hd, int T0, int rho) {
;     ...
;     const int tid = tid_, lane = tid & 63, r32 = lane & 31, hi = lane >> 5, wid = __builtin_amdgcn_readfirstlane(tid >> 6);
;     bf16_t* base = proj + (size_t)seq * SEQ * NIN;
;     LAS unsigned char* wbuf = lds + wid * 4096;
;     const LAS unsigned char* vp = wbuf + ((lane >> 4) & 1) * 32 + (lane & 3) * 8 + (4 * hi + ((lane & 15) >> 2)) * 64;
;     const int P0 = T0 + rho;
;     bf16x8 qr[4];
; #pragma unroll
;     for (int ks = 0; ks < 4; ++ks) qr[ks] = *(const GAS bf16x8*)(base + (size_t)(P0 + 16 * r32) * NIN + PC_LQ + hd * 64 + 16 * ks + 8 * hi);
;     f32x16 o0 = {}, o1 = {}; float l = 0.f;
;     const bool bound = (T0 < 1024) || (T0 >= 15360);
; __device__ __forceinline__ void attn_phase(unsigned char* ws, int l, LAS unsigned char* lds, int G) {
;     ...
;         const int sh = bu >> 6, rem = bu & 63, T0 = (rem >> 1) * 512, rho = (rem & 1) * 8 + wid;
;         dil_unit(lds, proj, sh / 6, sh % 6, T0, rho);
.LBB0_1266:
	s_lshr_b32 s82, s60, 8
	s_mul_i32 s82, s82, 13
	s_add_i32 s82, s82, s60
	s_ashr_i32 s4, s60, 6
	s_mul_hi_i32 s9, s4, 0x2aaaaaab
	s_lshl_b32 s5, s82, 8
	s_lshr_b32 s10, s9, 31
	s_and_b32 s8, s5, 0x3e00
	s_lshl_b32 s5, s82, 3
	s_add_i32 s9, s9, s10
	s_and_b32 s5, s5, 8
	s_mul_i32 s10, s9, 6
	s_add_i32 s5, s5, s61
	s_sub_i32 s10, s4, s10
	s_mul_hi_i32 s4, s9, 0x6000000
	s_mul_i32 s9, s9, 0x6000000
	v_mov_b32_e32 v2, v154
	s_add_u32 s52, s44, s9
	s_addc_u32 s53, s45, s4
	v_and_b32_e32 v105, 31, v2
	s_add_i32 s67, s5, s8
	v_lshl_add_u32 v3, v105, 4, s67
	v_mov_b64_e32 v[0:1], s[52:53]
	s_lshl_b32 s54, s10, 6
	v_bfe_u32 v106, v2, 5, 1
	v_mad_u64_u32 v[0:1], s[4:5], v3, s62, v[0:1]
	s_ashr_i32 s55, s54, 31
	v_lshl_add_u64 v[0:1], s[54:55], 1, v[0:1]
	v_lshlrev_b32_e32 v80, 4, v106
	v_lshl_add_u64 v[0:1], v[0:1], 0, v[80:81]
	global_load_dwordx4 v[48:51], v[0:1], off offset:1280
	global_load_dwordx4 v[52:55], v[0:1], off offset:1312
	global_load_dwordx4 v[56:59], v[0:1], off offset:1344
	global_load_dwordx4 v[60:63], v[0:1], off offset:1376
	v_readfirstlane_b32 s4, v2
	s_lshl_b32 s4, s4, 6
	s_and_b32 s4, s4, 0xfffff000
	v_lshlrev_b32_e32 v0, 1, v2
	v_lshlrev_b32_e32 v104, 3, v2
	v_lshlrev_b32_e32 v107, 2, v106
	v_lshrrev_b32_e32 v1, 2, v2
	v_and_b32_e32 v103, 63, v2
	v_and_b32_e32 v0, 32, v0
	v_and_b32_e32 v98, 24, v104
	v_and_or_b32 v1, v1, 3, v107
	s_add_i32 s69, s4, 0
	v_lshlrev_b32_e32 v108, 6, v1
	v_lshlrev_b32_e32 v1, 3, v106
	v_add3_u32 v109, s69, v0, v98
	s_addk_i32 s8, 0xc400
	v_lshrrev_b32_e32 v110, 2, v103
	v_lshlrev_b32_e32 v0, 4, v103
	s_mov_b64 s[4:5], -1
	s_cmp_gt_u32 s8, 0xffffc7ff
	v_lshlrev_b32_e32 v100, 1, v98
	s_mul_i32 s8, s10, 0x1c00
	v_lshlrev_b32_e32 v82, 1, v1
	v_or_b32_e32 v111, 16, v110
	v_add_u32_e32 v112, s69, v0
	s_cbranch_scc0 .LBB0_1270
	s_movk_i32 s100, 0x1800
	s_add_i32 s101, s8, 0x15c00
	s_lshl_b32 s90, s54, 1
	s_add_u32 s82, s52, s90
	s_addc_u32 s83, s53, 0
	s_add_u32 s82, s82, 0x1200
	s_addc_u32 s83, s83, 0
	s_sub_i32 s90, s67, 64
	s_mul_i32 s90, s90, 0x1800
	s_add_u32 s84, s82, s90
	s_addc_u32 s85, s83, 0
	s_sub_i32 s90, s67, 256
	s_mul_i32 s90, s90, 0x1800
	s_add_u32 s86, s82, s90
	s_addc_u32 s87, s83, 0
	s_sub_i32 s90, s67, 1024
	s_mul_i32 s90, s90, 0x1800
	s_add_u32 s88, s82, s90
	s_addc_u32 s89, s83, 0
	v_lshlrev_b32_e32 v153, 1, v98
	v_mad_u32_u24 v80, v105, s100, v82
	v_mad_u32_u24 v100, v110, s100, v153
	v_add_u32_e32 v149, 0x18000, v100
	v_lshlrev_b32_e32 v83, 2, v105
	v_mad_u32_u24 v83, v83, s100, v82
	v_lshlrev_b32_e32 v101, 2, v110
	v_mad_u32_u24 v101, v101, s100, v153
	v_add_u32_e32 v150, 0x60000, v101
	v_lshlrev_b32_e32 v99, 4, v105
	v_mad_u32_u24 v99, v99, s100, v82
	v_lshlrev_b32_e32 v148, 4, v110
	v_mad_u32_u24 v148, v148, s100, v153
	v_add_u32_e32 v151, 0x180000, v148
	v_lshrrev_b32_e32 v249, 3, v103
	v_and_b32_e32 v250, 7, v103
	v_lshlrev_b32_e32 v250, 4, v250
	v_add_u32_e32 v235, 0, v249
	v_mad_u32_u24 v235, v235, s100, v250
	v_add_u32_e32 v236, 8, v249
	v_mad_u32_u24 v236, v236, s100, v250
	v_add_u32_e32 v237, 16, v249
	v_mad_u32_u24 v237, v237, s100, v250
	v_add_u32_e32 v238, 24, v249
	v_mad_u32_u24 v238, v238, s100, v250
	v_add_u32_e32 v239, 0, v249
	v_lshlrev_b32_e32 v239, 2, v239
	v_mad_u32_u24 v239, v239, s100, v250
	v_add_u32_e32 v240, 8, v249
	v_lshlrev_b32_e32 v240, 2, v240
	v_mad_u32_u24 v240, v240, s100, v250
	v_add_u32_e32 v241, 16, v249
	v_lshlrev_b32_e32 v241, 2, v241
	v_mad_u32_u24 v241, v241, s100, v250
	v_add_u32_e32 v242, 24, v249
	v_lshlrev_b32_e32 v242, 2, v242
	v_mad_u32_u24 v242, v242, s100, v250
	v_add_u32_e32 v243, 0, v249
	v_lshlrev_b32_e32 v243, 4, v243
	v_mad_u32_u24 v243, v243, s100, v250
	v_add_u32_e32 v244, 8, v249
	v_lshlrev_b32_e32 v244, 4, v244
	v_mad_u32_u24 v244, v244, s100, v250
	v_add_u32_e32 v245, 16, v249
	v_lshlrev_b32_e32 v245, 4, v245
	v_mad_u32_u24 v245, v245, s100, v250
	v_add_u32_e32 v246, 24, v249
	v_lshlrev_b32_e32 v246, 4, v246
	v_mad_u32_u24 v246, v246, s100, v250
	v_and_b32_e32 v247, 7, v249
	v_lshlrev_b32_e32 v247, 4, v247
	v_xor_b32_e32 v247, v247, v112
	v_and_b32_e32 v153, 7, v105
	v_or_b32_e32 v248, 0, v106
	v_xor_b32_e32 v248, v248, v153
	v_lshlrev_b32_e32 v248, 4, v248
	v_lshl_add_u32 v248, v105, 7, v248
	v_add_u32_e32 v248, s69, v248
	v_or_b32_e32 v249, 2, v106
	v_xor_b32_e32 v249, v249, v153
	v_lshlrev_b32_e32 v249, 4, v249
	v_lshl_add_u32 v249, v105, 7, v249
	v_add_u32_e32 v249, s69, v249
	v_or_b32_e32 v250, 4, v106
	v_xor_b32_e32 v250, v250, v153
	v_lshlrev_b32_e32 v250, 4, v250
	v_lshl_add_u32 v250, v105, 7, v250
	v_add_u32_e32 v250, s69, v250
	v_or_b32_e32 v251, 6, v106
	v_xor_b32_e32 v251, v251, v153
	v_lshlrev_b32_e32 v251, 4, v251
	v_lshl_add_u32 v251, v105, 7, v251
	v_add_u32_e32 v251, s69, v251
	v_lshlrev_b32_e32 v153, 1, v98
	v_mul_u32_u24_e32 v228, 17, v105
	v_sub_u32_e32 v228, v107, v228
	s_mul_i32 s90, s54, 153
	s_lshr_b32 s90, s90, 1
	s_add_i32 s90, s90, 34876
	v_lshl_add_u32 v228, v228, 2, s90
	v_lshlrev_b32_e32 v229, 2, v105
	v_sub_u32_e32 v229, v107, v229
	s_add_i32 s90, s101, 5104
	v_lshl_add_u32 v229, v229, 2, s90
	v_sub_u32_e32 v230, v107, v105
	s_add_i32 s90, s101, 6364
	v_lshl_add_u32 v230, v230, 2, s90
	v_add_u32_e32 v231, v109, v108
	v_mov_b64_e32 v[232:233], 0
	v_mov_b64_e32 v[0:1], 0
	v_mov_b64_e32 v[2:3], 0
	v_mov_b64_e32 v[4:5], 0
	v_mov_b64_e32 v[6:7], 0
	v_mov_b64_e32 v[8:9], 0
	v_mov_b64_e32 v[10:11], 0
	v_mov_b64_e32 v[12:13], 0
	v_mov_b64_e32 v[14:15], 0
	v_mov_b64_e32 v[16:17], 0
	v_mov_b64_e32 v[18:19], 0
	v_mov_b64_e32 v[20:21], 0
	v_mov_b64_e32 v[22:23], 0
	v_mov_b64_e32 v[24:25], 0
	v_mov_b64_e32 v[26:27], 0
	v_mov_b64_e32 v[28:29], 0
	v_mov_b64_e32 v[30:31], 0
	global_load_dwordx4 v[116:119], v235, s[84:85]
	global_load_dwordx4 v[120:123], v236, s[84:85]
	global_load_dwordx4 v[124:127], v237, s[84:85]
	global_load_dwordx4 v[128:131], v238, s[84:85]
	global_load_dwordx4 v[132:135], v100, s[84:85] offset:768
	global_load_dwordx4 v[136:139], v149, s[84:85] offset:768
	global_load_dwordx4 v[140:143], v100, s[84:85] offset:832
	global_load_dwordx4 v[144:147], v149, s[84:85] offset:832
	s_add_u32 s84, s84, 0x30000
	s_addc_u32 s85, s85, 0
	global_load_dwordx4 v[156:159], v235, s[84:85]
	global_load_dwordx4 v[160:163], v236, s[84:85]
	global_load_dwordx4 v[164:167], v237, s[84:85]
	global_load_dwordx4 v[168:171], v238, s[84:85]
	global_load_dwordx4 v[172:175], v100, s[84:85] offset:768
	global_load_dwordx4 v[176:179], v149, s[84:85] offset:768
	global_load_dwordx4 v[180:183], v100, s[84:85] offset:832
	global_load_dwordx4 v[184:187], v149, s[84:85] offset:832
	s_add_u32 s84, s84, 0x30000
	s_addc_u32 s85, s85, 0
	v_mov_b32_e32 v115, v228
	ds_read2_b32 v[32:33], v115 offset0:0 offset1:1
	ds_read2_b32 v[34:35], v115 offset0:2 offset1:3
	ds_read2_b32 v[36:37], v115 offset0:8 offset1:9
	ds_read2_b32 v[38:39], v115 offset0:10 offset1:11
	ds_read2_b32 v[40:41], v115 offset0:17 offset1:18
	ds_read2_b32 v[42:43], v115 offset0:19 offset1:20
	ds_read2_b32 v[44:45], v115 offset0:25 offset1:26
	ds_read2_b32 v[46:47], v115 offset0:27 offset1:28
	s_waitcnt vmcnt(8)
	ds_write_b128 v247, v[116:119]
	ds_write_b128 v247, v[120:123] offset:1024
	ds_write_b128 v247, v[124:127] offset:2048
	ds_write_b128 v247, v[128:131] offset:3072
	ds_read_b128 v[116:119], v248
	ds_read_b128 v[120:123], v249
	ds_read_b128 v[124:127], v250
	ds_read_b128 v[128:131], v251
	ds_write_b128 v112, v[132:135]
	ds_write_b128 v112, v[136:139] offset:1024
	ds_write_b128 v112, v[140:143] offset:2048
	ds_write_b128 v112, v[144:147] offset:3072
	s_waitcnt lgkmcnt(4)
	v_mfma_f32_32x32x16_bf16 v[32:47], v[116:119], v[48:51], v[32:47]
	v_mfma_f32_32x32x16_bf16 v[32:47], v[120:123], v[52:55], v[32:47]
	v_mfma_f32_32x32x16_bf16 v[32:47], v[124:127], v[56:59], v[32:47]
	v_mfma_f32_32x32x16_bf16 v[32:47], v[128:131], v[60:63], v[32:47]
	ds_read2_b32 v[188:189], v115 offset0:34 offset1:35
	ds_read2_b32 v[190:191], v115 offset0:36 offset1:37
	ds_read2_b32 v[192:193], v115 offset0:42 offset1:43
	ds_read2_b32 v[194:195], v115 offset0:44 offset1:45
	ds_read2_b32 v[196:197], v115 offset0:51 offset1:52
	ds_read2_b32 v[198:199], v115 offset0:53 offset1:54
	ds_read2_b32 v[200:201], v115 offset0:59 offset1:60
	ds_read2_b32 v[202:203], v115 offset0:61 offset1:62
	global_load_dwordx4 v[116:119], v235, s[84:85]
	global_load_dwordx4 v[120:123], v236, s[84:85]
	global_load_dwordx4 v[124:127], v237, s[84:85]
	global_load_dwordx4 v[128:131], v238, s[84:85]
	global_load_dwordx4 v[132:135], v100, s[84:85] offset:768
	global_load_dwordx4 v[136:139], v149, s[84:85] offset:768
	global_load_dwordx4 v[140:143], v100, s[84:85] offset:832
	global_load_dwordx4 v[144:147], v149, s[84:85] offset:832
	s_add_u32 s84, s84, 0x30000
	s_addc_u32 s85, s85, 0
	ds_read_b64_tr_b16 v[72:73], v231
	ds_read_b64_tr_b16 v[74:75], v231 offset:512
	ds_read_b64_tr_b16 v[76:77], v231 offset:2048
	ds_read_b64_tr_b16 v[78:79], v231 offset:2560
	ds_read_b64_tr_b16 v[220:221], v231 offset:1024
	ds_read_b64_tr_b16 v[222:223], v231 offset:1536
	ds_read_b64_tr_b16 v[224:225], v231 offset:3072
	ds_read_b64_tr_b16 v[226:227], v231 offset:3584
	v_exp_f32_e32 v32, v32
	v_exp_f32_e32 v33, v33
	v_exp_f32_e32 v34, v34
	v_exp_f32_e32 v35, v35
	s_waitcnt vmcnt(8)
	ds_write_b128 v247, v[156:159]
	ds_write_b128 v247, v[160:163] offset:1024
	ds_write_b128 v247, v[164:167] offset:2048
	ds_write_b128 v247, v[168:171] offset:3072
	ds_read_b128 v[156:159], v248
	ds_read_b128 v[160:163], v249
	ds_read_b128 v[164:167], v250
	ds_read_b128 v[168:171], v251
	ds_write_b128 v112, v[172:175]
	ds_write_b128 v112, v[176:179] offset:1024
	ds_write_b128 v112, v[180:183] offset:2048
	ds_write_b128 v112, v[184:187] offset:3072
	v_exp_f32_e32 v36, v36
	v_exp_f32_e32 v37, v37
	v_exp_f32_e32 v38, v38
	v_exp_f32_e32 v39, v39
	s_waitcnt lgkmcnt(4)
	v_mfma_f32_32x32x16_bf16 v[188:203], v[156:159], v[48:51], v[188:203]
	v_exp_f32_e32 v40, v40
	v_exp_f32_e32 v41, v41
	v_mfma_f32_32x32x16_bf16 v[188:203], v[160:163], v[52:55], v[188:203]
	v_exp_f32_e32 v42, v42
	v_exp_f32_e32 v43, v43
	v_mfma_f32_32x32x16_bf16 v[188:203], v[164:167], v[56:59], v[188:203]
	v_exp_f32_e32 v44, v44
	v_exp_f32_e32 v45, v45
	v_mfma_f32_32x32x16_bf16 v[188:203], v[168:171], v[60:63], v[188:203]
	v_exp_f32_e32 v46, v46
	v_exp_f32_e32 v47, v47
	v_cvt_pk_bf16_f32 v64, v32, v33
	v_cvt_pk_bf16_f32 v65, v34, v35
	v_cvt_pk_bf16_f32 v66, v36, v37
	v_cvt_pk_bf16_f32 v67, v38, v39
	v_cvt_pk_bf16_f32 v68, v40, v41
	v_cvt_pk_bf16_f32 v69, v42, v43
	v_cvt_pk_bf16_f32 v70, v44, v45
	v_cvt_pk_bf16_f32 v71, v46, v47
	v_pk_add_f32 v[232:233], v[232:233], v[32:33]
	v_pk_add_f32 v[232:233], v[232:233], v[34:35]
	v_pk_add_f32 v[232:233], v[232:233], v[36:37]
	v_pk_add_f32 v[232:233], v[232:233], v[38:39]
	v_pk_add_f32 v[232:233], v[232:233], v[40:41]
	v_pk_add_f32 v[232:233], v[232:233], v[42:43]
	v_pk_add_f32 v[232:233], v[232:233], v[44:45]
	v_pk_add_f32 v[232:233], v[232:233], v[46:47]
	ds_read2_b32 v[32:33], v115 offset0:68 offset1:69
	ds_read2_b32 v[34:35], v115 offset0:70 offset1:71
	ds_read2_b32 v[36:37], v115 offset0:76 offset1:77
	ds_read2_b32 v[38:39], v115 offset0:78 offset1:79
	ds_read2_b32 v[40:41], v115 offset0:85 offset1:86
	ds_read2_b32 v[42:43], v115 offset0:87 offset1:88
	ds_read2_b32 v[44:45], v115 offset0:93 offset1:94
	ds_read2_b32 v[46:47], v115 offset0:95 offset1:96
	global_load_dwordx4 v[156:159], v235, s[84:85]
	global_load_dwordx4 v[160:163], v236, s[84:85]
	global_load_dwordx4 v[164:167], v237, s[84:85]
	global_load_dwordx4 v[168:171], v238, s[84:85]
	global_load_dwordx4 v[172:175], v100, s[84:85] offset:768
	global_load_dwordx4 v[176:179], v149, s[84:85] offset:768
	global_load_dwordx4 v[180:183], v100, s[84:85] offset:832
	global_load_dwordx4 v[184:187], v149, s[84:85] offset:832
	s_add_u32 s84, s84, 0x30000
	s_addc_u32 s85, s85, 0
	ds_read_b64_tr_b16 v[204:205], v231
	ds_read_b64_tr_b16 v[206:207], v231 offset:512
	ds_read_b64_tr_b16 v[208:209], v231 offset:2048
	ds_read_b64_tr_b16 v[210:211], v231 offset:2560
	ds_read_b64_tr_b16 v[212:213], v231 offset:1024
	ds_read_b64_tr_b16 v[214:215], v231 offset:1536
	ds_read_b64_tr_b16 v[216:217], v231 offset:3072
	ds_read_b64_tr_b16 v[218:219], v231 offset:3584
	v_exp_f32_e32 v188, v188
	v_exp_f32_e32 v189, v189
	v_exp_f32_e32 v190, v190
	v_exp_f32_e32 v191, v191
	s_waitcnt vmcnt(8)
	ds_write_b128 v247, v[116:119]
	ds_write_b128 v247, v[120:123] offset:1024
	ds_write_b128 v247, v[124:127] offset:2048
	ds_write_b128 v247, v[128:131] offset:3072
	ds_read_b128 v[116:119], v248
	ds_read_b128 v[120:123], v249
	ds_read_b128 v[124:127], v250
	ds_read_b128 v[128:131], v251
	ds_write_b128 v112, v[132:135]
	ds_write_b128 v112, v[136:139] offset:1024
	ds_write_b128 v112, v[140:143] offset:2048
	ds_write_b128 v112, v[144:147] offset:3072
	v_mfma_f32_32x32x16_bf16 v[0:15], v[64:67], v[72:75], v[0:15]
	v_mfma_f32_32x32x16_bf16 v[16:31], v[64:67], v[76:79], v[16:31]
	v_mfma_f32_32x32x16_bf16 v[0:15], v[68:71], v[220:223], v[0:15]
	v_mfma_f32_32x32x16_bf16 v[16:31], v[68:71], v[224:227], v[16:31]
	v_exp_f32_e32 v192, v192
	v_exp_f32_e32 v193, v193
	v_exp_f32_e32 v194, v194
	v_exp_f32_e32 v195, v195
	s_waitcnt lgkmcnt(4)
	v_mfma_f32_32x32x16_bf16 v[32:47], v[116:119], v[48:51], v[32:47]
	v_exp_f32_e32 v196, v196
	v_exp_f32_e32 v197, v197
	v_mfma_f32_32x32x16_bf16 v[32:47], v[120:123], v[52:55], v[32:47]
	v_exp_f32_e32 v198, v198
	v_exp_f32_e32 v199, v199
	v_mfma_f32_32x32x16_bf16 v[32:47], v[124:127], v[56:59], v[32:47]
	v_exp_f32_e32 v200, v200
	v_exp_f32_e32 v201, v201
	v_mfma_f32_32x32x16_bf16 v[32:47], v[128:131], v[60:63], v[32:47]
	v_exp_f32_e32 v202, v202
	v_exp_f32_e32 v203, v203
	v_cvt_pk_bf16_f32 v64, v188, v189
	v_cvt_pk_bf16_f32 v65, v190, v191
	v_cvt_pk_bf16_f32 v66, v192, v193
	v_cvt_pk_bf16_f32 v67, v194, v195
	v_cvt_pk_bf16_f32 v68, v196, v197
	v_cvt_pk_bf16_f32 v69, v198, v199
	v_cvt_pk_bf16_f32 v70, v200, v201
	v_cvt_pk_bf16_f32 v71, v202, v203
	v_pk_add_f32 v[232:233], v[232:233], v[188:189]
	v_pk_add_f32 v[232:233], v[232:233], v[190:191]
	v_pk_add_f32 v[232:233], v[232:233], v[192:193]
	v_pk_add_f32 v[232:233], v[232:233], v[194:195]
	v_pk_add_f32 v[232:233], v[232:233], v[196:197]
	v_pk_add_f32 v[232:233], v[232:233], v[198:199]
	v_pk_add_f32 v[232:233], v[232:233], v[200:201]
	v_pk_add_f32 v[232:233], v[232:233], v[202:203]
	ds_read2_b32 v[188:189], v115 offset0:102 offset1:103
	ds_read2_b32 v[190:191], v115 offset0:104 offset1:105
	ds_read2_b32 v[192:193], v115 offset0:110 offset1:111
	ds_read2_b32 v[194:195], v115 offset0:112 offset1:113
	ds_read2_b32 v[196:197], v115 offset0:119 offset1:120
	ds_read2_b32 v[198:199], v115 offset0:121 offset1:122
	ds_read2_b32 v[200:201], v115 offset0:127 offset1:128
	ds_read2_b32 v[202:203], v115 offset0:129 offset1:130
	global_load_dwordx4 v[116:119], v235, s[84:85]
	global_load_dwordx4 v[120:123], v236, s[84:85]
	global_load_dwordx4 v[124:127], v237, s[84:85]
	global_load_dwordx4 v[128:131], v238, s[84:85]
	global_load_dwordx4 v[132:135], v100, s[84:85] offset:768
	global_load_dwordx4 v[136:139], v149, s[84:85] offset:768
	global_load_dwordx4 v[140:143], v100, s[84:85] offset:832
	global_load_dwordx4 v[144:147], v149, s[84:85] offset:832
	s_add_u32 s84, s84, 0x30000
	s_addc_u32 s85, s85, 0
	ds_read_b64_tr_b16 v[72:73], v231
	ds_read_b64_tr_b16 v[74:75], v231 offset:512
	ds_read_b64_tr_b16 v[76:77], v231 offset:2048
	ds_read_b64_tr_b16 v[78:79], v231 offset:2560
	ds_read_b64_tr_b16 v[220:221], v231 offset:1024
	ds_read_b64_tr_b16 v[222:223], v231 offset:1536
	ds_read_b64_tr_b16 v[224:225], v231 offset:3072
	ds_read_b64_tr_b16 v[226:227], v231 offset:3584
	v_exp_f32_e32 v32, v32
	v_exp_f32_e32 v33, v33
	v_exp_f32_e32 v34, v34
	v_exp_f32_e32 v35, v35
	s_waitcnt vmcnt(8)
	ds_write_b128 v247, v[156:159]
	ds_write_b128 v247, v[160:163] offset:1024
	ds_write_b128 v247, v[164:167] offset:2048
	ds_write_b128 v247, v[168:171] offset:3072
	ds_read_b128 v[156:159], v248
	ds_read_b128 v[160:163], v249
	ds_read_b128 v[164:167], v250
	ds_read_b128 v[168:171], v251
	ds_write_b128 v112, v[172:175]
	ds_write_b128 v112, v[176:179] offset:1024
	ds_write_b128 v112, v[180:183] offset:2048
	ds_write_b128 v112, v[184:187] offset:3072
	v_mfma_f32_32x32x16_bf16 v[0:15], v[64:67], v[204:207], v[0:15]
	v_mfma_f32_32x32x16_bf16 v[16:31], v[64:67], v[208:211], v[16:31]
	v_mfma_f32_32x32x16_bf16 v[0:15], v[68:71], v[212:215], v[0:15]
	v_mfma_f32_32x32x16_bf16 v[16:31], v[68:71], v[216:219], v[16:31]
	v_exp_f32_e32 v36, v36
	v_exp_f32_e32 v37, v37
	v_exp_f32_e32 v38, v38
	v_exp_f32_e32 v39, v39
	s_waitcnt lgkmcnt(4)
	v_mfma_f32_32x32x16_bf16 v[188:203], v[156:159], v[48:51], v[188:203]
	v_exp_f32_e32 v40, v40
	v_exp_f32_e32 v41, v41
	v_mfma_f32_32x32x16_bf16 v[188:203], v[160:163], v[52:55], v[188:203]
	v_exp_f32_e32 v42, v42
	v_exp_f32_e32 v43, v43
	v_mfma_f32_32x32x16_bf16 v[188:203], v[164:167], v[56:59], v[188:203]
	v_exp_f32_e32 v44, v44
	v_exp_f32_e32 v45, v45
	v_mfma_f32_32x32x16_bf16 v[188:203], v[168:171], v[60:63], v[188:203]
	v_exp_f32_e32 v46, v46
	v_exp_f32_e32 v47, v47
	v_cvt_pk_bf16_f32 v64, v32, v33
	v_cvt_pk_bf16_f32 v65, v34, v35
	v_cvt_pk_bf16_f32 v66, v36, v37
	v_cvt_pk_bf16_f32 v67, v38, v39
	v_cvt_pk_bf16_f32 v68, v40, v41
	v_cvt_pk_bf16_f32 v69, v42, v43
	v_cvt_pk_bf16_f32 v70, v44, v45
	v_cvt_pk_bf16_f32 v71, v46, v47
	v_pk_add_f32 v[232:233], v[232:233], v[32:33]
	v_pk_add_f32 v[232:233], v[232:233], v[34:35]
	v_pk_add_f32 v[232:233], v[232:233], v[36:37]
	v_pk_add_f32 v[232:233], v[232:233], v[38:39]
	v_pk_add_f32 v[232:233], v[232:233], v[40:41]
	v_pk_add_f32 v[232:233], v[232:233], v[42:43]
	v_pk_add_f32 v[232:233], v[232:233], v[44:45]
	v_pk_add_f32 v[232:233], v[232:233], v[46:47]
	ds_read2_b32 v[32:33], v115 offset0:136 offset1:137
	ds_read2_b32 v[34:35], v115 offset0:138 offset1:139
	ds_read2_b32 v[36:37], v115 offset0:144 offset1:145
	ds_read2_b32 v[38:39], v115 offset0:146 offset1:147
	ds_read2_b32 v[40:41], v115 offset0:153 offset1:154
	ds_read2_b32 v[42:43], v115 offset0:155 offset1:156
	ds_read2_b32 v[44:45], v115 offset0:161 offset1:162
	ds_read2_b32 v[46:47], v115 offset0:163 offset1:164
	global_load_dwordx4 v[156:159], v235, s[84:85]
	global_load_dwordx4 v[160:163], v236, s[84:85]
	global_load_dwordx4 v[164:167], v237, s[84:85]
	global_load_dwordx4 v[168:171], v238, s[84:85]
	global_load_dwordx4 v[172:175], v100, s[84:85] offset:768
	global_load_dwordx4 v[176:179], v149, s[84:85] offset:768
	global_load_dwordx4 v[180:183], v100, s[84:85] offset:832
	global_load_dwordx4 v[184:187], v149, s[84:85] offset:832
	s_add_u32 s84, s84, 0x30000
	s_addc_u32 s85, s85, 0
	ds_read_b64_tr_b16 v[204:205], v231
	ds_read_b64_tr_b16 v[206:207], v231 offset:512
	ds_read_b64_tr_b16 v[208:209], v231 offset:2048
	ds_read_b64_tr_b16 v[210:211], v231 offset:2560
	ds_read_b64_tr_b16 v[212:213], v231 offset:1024
	ds_read_b64_tr_b16 v[214:215], v231 offset:1536
	ds_read_b64_tr_b16 v[216:217], v231 offset:3072
	ds_read_b64_tr_b16 v[218:219], v231 offset:3584
	v_exp_f32_e32 v188, v188
	v_exp_f32_e32 v189, v189
	v_exp_f32_e32 v190, v190
	v_exp_f32_e32 v191, v191
	s_waitcnt vmcnt(8)
	ds_write_b128 v247, v[116:119]
	ds_write_b128 v247, v[120:123] offset:1024
	ds_write_b128 v247, v[124:127] offset:2048
	ds_write_b128 v247, v[128:131] offset:3072
	ds_read_b128 v[116:119], v248
	ds_read_b128 v[120:123], v249
	ds_read_b128 v[124:127], v250
	ds_read_b128 v[128:131], v251
	ds_write_b128 v112, v[132:135]
	ds_write_b128 v112, v[136:139] offset:1024
	ds_write_b128 v112, v[140:143] offset:2048
	ds_write_b128 v112, v[144:147] offset:3072
	v_mfma_f32_32x32x16_bf16 v[0:15], v[64:67], v[72:75], v[0:15]
	v_mfma_f32_32x32x16_bf16 v[16:31], v[64:67], v[76:79], v[16:31]
	v_mfma_f32_32x32x16_bf16 v[0:15], v[68:71], v[220:223], v[0:15]
	v_mfma_f32_32x32x16_bf16 v[16:31], v[68:71], v[224:227], v[16:31]
	v_exp_f32_e32 v192, v192
	v_exp_f32_e32 v193, v193
	v_exp_f32_e32 v194, v194
	v_exp_f32_e32 v195, v195
	s_waitcnt lgkmcnt(4)
	v_mfma_f32_32x32x16_bf16 v[32:47], v[116:119], v[48:51], v[32:47]
	v_exp_f32_e32 v196, v196
	v_exp_f32_e32 v197, v197
	v_mfma_f32_32x32x16_bf16 v[32:47], v[120:123], v[52:55], v[32:47]
	v_exp_f32_e32 v198, v198
	v_exp_f32_e32 v199, v199
	v_mfma_f32_32x32x16_bf16 v[32:47], v[124:127], v[56:59], v[32:47]
	v_exp_f32_e32 v200, v200
	v_exp_f32_e32 v201, v201
	v_mfma_f32_32x32x16_bf16 v[32:47], v[128:131], v[60:63], v[32:47]
	v_exp_f32_e32 v202, v202
	v_exp_f32_e32 v203, v203
	v_cvt_pk_bf16_f32 v64, v188, v189
	v_cvt_pk_bf16_f32 v65, v190, v191
	v_cvt_pk_bf16_f32 v66, v192, v193
	v_cvt_pk_bf16_f32 v67, v194, v195
	v_cvt_pk_bf16_f32 v68, v196, v197
	v_cvt_pk_bf16_f32 v69, v198, v199
	v_cvt_pk_bf16_f32 v70, v200, v201
	v_cvt_pk_bf16_f32 v71, v202, v203
	v_pk_add_f32 v[232:233], v[232:233], v[188:189]
	v_pk_add_f32 v[232:233], v[232:233], v[190:191]
	v_pk_add_f32 v[232:233], v[232:233], v[192:193]
	v_pk_add_f32 v[232:233], v[232:233], v[194:195]
	v_pk_add_f32 v[232:233], v[232:233], v[196:197]
	v_pk_add_f32 v[232:233], v[232:233], v[198:199]
	v_pk_add_f32 v[232:233], v[232:233], v[200:201]
	v_pk_add_f32 v[232:233], v[232:233], v[202:203]
	ds_read2_b32 v[188:189], v115 offset0:170 offset1:171
	ds_read2_b32 v[190:191], v115 offset0:172 offset1:173
	ds_read2_b32 v[192:193], v115 offset0:178 offset1:179
	ds_read2_b32 v[194:195], v115 offset0:180 offset1:181
	ds_read2_b32 v[196:197], v115 offset0:187 offset1:188
	ds_read2_b32 v[198:199], v115 offset0:189 offset1:190
	ds_read2_b32 v[200:201], v115 offset0:195 offset1:196
	ds_read2_b32 v[202:203], v115 offset0:197 offset1:198
	global_load_dwordx4 v[116:119], v235, s[84:85]
	global_load_dwordx4 v[120:123], v236, s[84:85]
	global_load_dwordx4 v[124:127], v237, s[84:85]
	global_load_dwordx4 v[128:131], v238, s[84:85]
	global_load_dwordx4 v[132:135], v100, s[84:85] offset:768
	global_load_dwordx4 v[136:139], v149, s[84:85] offset:768
	global_load_dwordx4 v[140:143], v100, s[84:85] offset:832
	global_load_dwordx4 v[144:147], v149, s[84:85] offset:832
	s_add_u32 s84, s84, 0x30000
	s_addc_u32 s85, s85, 0
	ds_read_b64_tr_b16 v[72:73], v231
	ds_read_b64_tr_b16 v[74:75], v231 offset:512
	ds_read_b64_tr_b16 v[76:77], v231 offset:2048
	ds_read_b64_tr_b16 v[78:79], v231 offset:2560
	ds_read_b64_tr_b16 v[220:221], v231 offset:1024
	ds_read_b64_tr_b16 v[222:223], v231 offset:1536
	ds_read_b64_tr_b16 v[224:225], v231 offset:3072
	ds_read_b64_tr_b16 v[226:227], v231 offset:3584
	v_exp_f32_e32 v32, v32
	v_exp_f32_e32 v33, v33
	v_exp_f32_e32 v34, v34
	v_exp_f32_e32 v35, v35
	s_waitcnt vmcnt(8)
	ds_write_b128 v247, v[156:159]
	ds_write_b128 v247, v[160:163] offset:1024
	ds_write_b128 v247, v[164:167] offset:2048
	ds_write_b128 v247, v[168:171] offset:3072
	ds_read_b128 v[156:159], v248
	ds_read_b128 v[160:163], v249
	ds_read_b128 v[164:167], v250
	ds_read_b128 v[168:171], v251
	ds_write_b128 v112, v[172:175]
	ds_write_b128 v112, v[176:179] offset:1024
	ds_write_b128 v112, v[180:183] offset:2048
	ds_write_b128 v112, v[184:187] offset:3072
	v_mfma_f32_32x32x16_bf16 v[0:15], v[64:67], v[204:207], v[0:15]
	v_mfma_f32_32x32x16_bf16 v[16:31], v[64:67], v[208:211], v[16:31]
	v_mfma_f32_32x32x16_bf16 v[0:15], v[68:71], v[212:215], v[0:15]
	v_mfma_f32_32x32x16_bf16 v[16:31], v[68:71], v[216:219], v[16:31]
	v_exp_f32_e32 v36, v36
	v_exp_f32_e32 v37, v37
	v_exp_f32_e32 v38, v38
	v_exp_f32_e32 v39, v39
	s_waitcnt lgkmcnt(4)
	v_mfma_f32_32x32x16_bf16 v[188:203], v[156:159], v[48:51], v[188:203]
	v_exp_f32_e32 v40, v40
	v_exp_f32_e32 v41, v41
	v_mfma_f32_32x32x16_bf16 v[188:203], v[160:163], v[52:55], v[188:203]
	v_exp_f32_e32 v42, v42
	v_exp_f32_e32 v43, v43
	v_mfma_f32_32x32x16_bf16 v[188:203], v[164:167], v[56:59], v[188:203]
	v_exp_f32_e32 v44, v44
	v_exp_f32_e32 v45, v45
	v_mfma_f32_32x32x16_bf16 v[188:203], v[168:171], v[60:63], v[188:203]
	v_exp_f32_e32 v46, v46
	v_exp_f32_e32 v47, v47
	v_cvt_pk_bf16_f32 v64, v32, v33
	v_cvt_pk_bf16_f32 v65, v34, v35
	v_cvt_pk_bf16_f32 v66, v36, v37
	v_cvt_pk_bf16_f32 v67, v38, v39
	v_cvt_pk_bf16_f32 v68, v40, v41
	v_cvt_pk_bf16_f32 v69, v42, v43
	v_cvt_pk_bf16_f32 v70, v44, v45
	v_cvt_pk_bf16_f32 v71, v46, v47
	v_pk_add_f32 v[232:233], v[232:233], v[32:33]
	v_pk_add_f32 v[232:233], v[232:233], v[34:35]
	v_pk_add_f32 v[232:233], v[232:233], v[36:37]
	v_pk_add_f32 v[232:233], v[232:233], v[38:39]
	v_pk_add_f32 v[232:233], v[232:233], v[40:41]
	v_pk_add_f32 v[232:233], v[232:233], v[42:43]
	v_pk_add_f32 v[232:233], v[232:233], v[44:45]
	v_pk_add_f32 v[232:233], v[232:233], v[46:47]
	ds_read2_b32 v[32:33], v115 offset0:204 offset1:205
	ds_read2_b32 v[34:35], v115 offset0:206 offset1:207
	ds_read2_b32 v[36:37], v115 offset0:212 offset1:213
	ds_read2_b32 v[38:39], v115 offset0:214 offset1:215
	ds_read2_b32 v[40:41], v115 offset0:221 offset1:222
	ds_read2_b32 v[42:43], v115 offset0:223 offset1:224
	ds_read2_b32 v[44:45], v115 offset0:229 offset1:230
	ds_read2_b32 v[46:47], v115 offset0:231 offset1:232
	global_load_dwordx4 v[156:159], v235, s[84:85]
	global_load_dwordx4 v[160:163], v236, s[84:85]
	global_load_dwordx4 v[164:167], v237, s[84:85]
	global_load_dwordx4 v[168:171], v238, s[84:85]
	global_load_dwordx4 v[172:175], v100, s[84:85] offset:768
	global_load_dwordx4 v[176:179], v149, s[84:85] offset:768
	global_load_dwordx4 v[180:183], v100, s[84:85] offset:832
	global_load_dwordx4 v[184:187], v149, s[84:85] offset:832
	s_add_u32 s84, s84, 0x30000
	s_addc_u32 s85, s85, 0
	ds_read_b64_tr_b16 v[204:205], v231
	ds_read_b64_tr_b16 v[206:207], v231 offset:512
	ds_read_b64_tr_b16 v[208:209], v231 offset:2048
	ds_read_b64_tr_b16 v[210:211], v231 offset:2560
	ds_read_b64_tr_b16 v[212:213], v231 offset:1024
	ds_read_b64_tr_b16 v[214:215], v231 offset:1536
	ds_read_b64_tr_b16 v[216:217], v231 offset:3072
	ds_read_b64_tr_b16 v[218:219], v231 offset:3584
	v_exp_f32_e32 v188, v188
	v_exp_f32_e32 v189, v189
	v_exp_f32_e32 v190, v190
	v_exp_f32_e32 v191, v191
	s_waitcnt vmcnt(8)
	ds_write_b128 v247, v[116:119]
	ds_write_b128 v247, v[120:123] offset:1024
	ds_write_b128 v247, v[124:127] offset:2048
	ds_write_b128 v247, v[128:131] offset:3072
	ds_read_b128 v[116:119], v248
	ds_read_b128 v[120:123], v249
	ds_read_b128 v[124:127], v250
	ds_read_b128 v[128:131], v251
	ds_write_b128 v112, v[132:135]
	ds_write_b128 v112, v[136:139] offset:1024
	ds_write_b128 v112, v[140:143] offset:2048
	ds_write_b128 v112, v[144:147] offset:3072
	v_mfma_f32_32x32x16_bf16 v[0:15], v[64:67], v[72:75], v[0:15]
	v_mfma_f32_32x32x16_bf16 v[16:31], v[64:67], v[76:79], v[16:31]
	v_mfma_f32_32x32x16_bf16 v[0:15], v[68:71], v[220:223], v[0:15]
	v_mfma_f32_32x32x16_bf16 v[16:31], v[68:71], v[224:227], v[16:31]
	v_exp_f32_e32 v192, v192
	v_exp_f32_e32 v193, v193
	v_exp_f32_e32 v194, v194
	v_exp_f32_e32 v195, v195
	s_waitcnt lgkmcnt(4)
	v_mfma_f32_32x32x16_bf16 v[32:47], v[116:119], v[48:51], v[32:47]
	v_exp_f32_e32 v196, v196
	v_exp_f32_e32 v197, v197
	v_mfma_f32_32x32x16_bf16 v[32:47], v[120:123], v[52:55], v[32:47]
	v_exp_f32_e32 v198, v198
	v_exp_f32_e32 v199, v199
	v_mfma_f32_32x32x16_bf16 v[32:47], v[124:127], v[56:59], v[32:47]
	v_exp_f32_e32 v200, v200
	v_exp_f32_e32 v201, v201
	v_mfma_f32_32x32x16_bf16 v[32:47], v[128:131], v[60:63], v[32:47]
	v_exp_f32_e32 v202, v202
	v_exp_f32_e32 v203, v203
	v_cvt_pk_bf16_f32 v64, v188, v189
	v_cvt_pk_bf16_f32 v65, v190, v191
	v_cvt_pk_bf16_f32 v66, v192, v193
	v_cvt_pk_bf16_f32 v67, v194, v195
	v_cvt_pk_bf16_f32 v68, v196, v197
	v_cvt_pk_bf16_f32 v69, v198, v199
	v_cvt_pk_bf16_f32 v70, v200, v201
	v_cvt_pk_bf16_f32 v71, v202, v203
	v_pk_add_f32 v[232:233], v[232:233], v[188:189]
	v_pk_add_f32 v[232:233], v[232:233], v[190:191]
	v_pk_add_f32 v[232:233], v[232:233], v[192:193]
	v_pk_add_f32 v[232:233], v[232:233], v[194:195]
	v_pk_add_f32 v[232:233], v[232:233], v[196:197]
	v_pk_add_f32 v[232:233], v[232:233], v[198:199]
	v_pk_add_f32 v[232:233], v[232:233], v[200:201]
	v_pk_add_f32 v[232:233], v[232:233], v[202:203]
	v_add_u32_e32 v115, 952, v115
	ds_read2_b32 v[188:189], v115 offset0:0 offset1:1
	ds_read2_b32 v[190:191], v115 offset0:2 offset1:3
	ds_read2_b32 v[192:193], v115 offset0:8 offset1:9
	ds_read2_b32 v[194:195], v115 offset0:10 offset1:11
	ds_read2_b32 v[196:197], v115 offset0:17 offset1:18
	ds_read2_b32 v[198:199], v115 offset0:19 offset1:20
	ds_read2_b32 v[200:201], v115 offset0:25 offset1:26
	ds_read2_b32 v[202:203], v115 offset0:27 offset1:28
	global_load_dwordx4 v[116:119], v235, s[84:85]
	global_load_dwordx4 v[120:123], v236, s[84:85]
	global_load_dwordx4 v[124:127], v237, s[84:85]
	global_load_dwordx4 v[128:131], v238, s[84:85]
	global_load_dwordx4 v[132:135], v100, s[84:85] offset:768
	global_load_dwordx4 v[136:139], v149, s[84:85] offset:768
	global_load_dwordx4 v[140:143], v100, s[84:85] offset:832
	global_load_dwordx4 v[144:147], v149, s[84:85] offset:832
	s_add_u32 s84, s84, 0x30000
	s_addc_u32 s85, s85, 0
	ds_read_b64_tr_b16 v[72:73], v231
	ds_read_b64_tr_b16 v[74:75], v231 offset:512
	ds_read_b64_tr_b16 v[76:77], v231 offset:2048
	ds_read_b64_tr_b16 v[78:79], v231 offset:2560
	ds_read_b64_tr_b16 v[220:221], v231 offset:1024
	ds_read_b64_tr_b16 v[222:223], v231 offset:1536
	ds_read_b64_tr_b16 v[224:225], v231 offset:3072
	ds_read_b64_tr_b16 v[226:227], v231 offset:3584
	v_exp_f32_e32 v32, v32
	v_exp_f32_e32 v33, v33
	v_exp_f32_e32 v34, v34
	v_exp_f32_e32 v35, v35
	s_waitcnt vmcnt(8)
	ds_write_b128 v247, v[156:159]
	ds_write_b128 v247, v[160:163] offset:1024
	ds_write_b128 v247, v[164:167] offset:2048
	ds_write_b128 v247, v[168:171] offset:3072
	ds_read_b128 v[156:159], v248
	ds_read_b128 v[160:163], v249
	ds_read_b128 v[164:167], v250
	ds_read_b128 v[168:171], v251
	ds_write_b128 v112, v[172:175]
	ds_write_b128 v112, v[176:179] offset:1024
	ds_write_b128 v112, v[180:183] offset:2048
	ds_write_b128 v112, v[184:187] offset:3072
	v_mfma_f32_32x32x16_bf16 v[0:15], v[64:67], v[204:207], v[0:15]
	v_mfma_f32_32x32x16_bf16 v[16:31], v[64:67], v[208:211], v[16:31]
	v_mfma_f32_32x32x16_bf16 v[0:15], v[68:71], v[212:215], v[0:15]
	v_mfma_f32_32x32x16_bf16 v[16:31], v[68:71], v[216:219], v[16:31]
	v_exp_f32_e32 v36, v36
	v_exp_f32_e32 v37, v37
	v_exp_f32_e32 v38, v38
	v_exp_f32_e32 v39, v39
	s_waitcnt lgkmcnt(4)
	v_mfma_f32_32x32x16_bf16 v[188:203], v[156:159], v[48:51], v[188:203]
	v_exp_f32_e32 v40, v40
	v_exp_f32_e32 v41, v41
	v_mfma_f32_32x32x16_bf16 v[188:203], v[160:163], v[52:55], v[188:203]
	v_exp_f32_e32 v42, v42
	v_exp_f32_e32 v43, v43
	v_mfma_f32_32x32x16_bf16 v[188:203], v[164:167], v[56:59], v[188:203]
	v_exp_f32_e32 v44, v44
	v_exp_f32_e32 v45, v45
	v_mfma_f32_32x32x16_bf16 v[188:203], v[168:171], v[60:63], v[188:203]
	v_exp_f32_e32 v46, v46
	v_exp_f32_e32 v47, v47
	v_cvt_pk_bf16_f32 v64, v32, v33
	v_cvt_pk_bf16_f32 v65, v34, v35
	v_cvt_pk_bf16_f32 v66, v36, v37
	v_cvt_pk_bf16_f32 v67, v38, v39
	v_cvt_pk_bf16_f32 v68, v40, v41
	v_cvt_pk_bf16_f32 v69, v42, v43
	v_cvt_pk_bf16_f32 v70, v44, v45
	v_cvt_pk_bf16_f32 v71, v46, v47
	v_pk_add_f32 v[232:233], v[232:233], v[32:33]
	v_pk_add_f32 v[232:233], v[232:233], v[34:35]
	v_pk_add_f32 v[232:233], v[232:233], v[36:37]
	v_pk_add_f32 v[232:233], v[232:233], v[38:39]
	v_pk_add_f32 v[232:233], v[232:233], v[40:41]
	v_pk_add_f32 v[232:233], v[232:233], v[42:43]
	v_pk_add_f32 v[232:233], v[232:233], v[44:45]
	v_pk_add_f32 v[232:233], v[232:233], v[46:47]
	ds_read2_b32 v[32:33], v115 offset0:34 offset1:35
	ds_read2_b32 v[34:35], v115 offset0:36 offset1:37
	ds_read2_b32 v[36:37], v115 offset0:42 offset1:43
	ds_read2_b32 v[38:39], v115 offset0:44 offset1:45
	ds_read2_b32 v[40:41], v115 offset0:51 offset1:52
	ds_read2_b32 v[42:43], v115 offset0:53 offset1:54
	ds_read2_b32 v[44:45], v115 offset0:59 offset1:60
	ds_read2_b32 v[46:47], v115 offset0:61 offset1:62
	global_load_dwordx4 v[156:159], v235, s[84:85]
	global_load_dwordx4 v[160:163], v236, s[84:85]
	global_load_dwordx4 v[164:167], v237, s[84:85]
	global_load_dwordx4 v[168:171], v238, s[84:85]
	global_load_dwordx4 v[172:175], v100, s[84:85] offset:768
	global_load_dwordx4 v[176:179], v149, s[84:85] offset:768
	global_load_dwordx4 v[180:183], v100, s[84:85] offset:832
	global_load_dwordx4 v[184:187], v149, s[84:85] offset:832
	s_add_u32 s84, s84, 0x30000
	s_addc_u32 s85, s85, 0
	ds_read_b64_tr_b16 v[204:205], v231
	ds_read_b64_tr_b16 v[206:207], v231 offset:512
	ds_read_b64_tr_b16 v[208:209], v231 offset:2048
	ds_read_b64_tr_b16 v[210:211], v231 offset:2560
	ds_read_b64_tr_b16 v[212:213], v231 offset:1024
	ds_read_b64_tr_b16 v[214:215], v231 offset:1536
	ds_read_b64_tr_b16 v[216:217], v231 offset:3072
	ds_read_b64_tr_b16 v[218:219], v231 offset:3584
	v_exp_f32_e32 v188, v188
	v_exp_f32_e32 v189, v189
	v_exp_f32_e32 v190, v190
	v_exp_f32_e32 v191, v191
	s_waitcnt vmcnt(8)
	ds_write_b128 v247, v[116:119]
	ds_write_b128 v247, v[120:123] offset:1024
	ds_write_b128 v247, v[124:127] offset:2048
	ds_write_b128 v247, v[128:131] offset:3072
	ds_read_b128 v[116:119], v248
	ds_read_b128 v[120:123], v249
	ds_read_b128 v[124:127], v250
	ds_read_b128 v[128:131], v251
	ds_write_b128 v112, v[132:135]
	ds_write_b128 v112, v[136:139] offset:1024
	ds_write_b128 v112, v[140:143] offset:2048
	ds_write_b128 v112, v[144:147] offset:3072
	v_mfma_f32_32x32x16_bf16 v[0:15], v[64:67], v[72:75], v[0:15]
	v_mfma_f32_32x32x16_bf16 v[16:31], v[64:67], v[76:79], v[16:31]
	v_mfma_f32_32x32x16_bf16 v[0:15], v[68:71], v[220:223], v[0:15]
	v_mfma_f32_32x32x16_bf16 v[16:31], v[68:71], v[224:227], v[16:31]
	v_exp_f32_e32 v192, v192
	v_exp_f32_e32 v193, v193
	v_exp_f32_e32 v194, v194
	v_exp_f32_e32 v195, v195
	s_waitcnt lgkmcnt(4)
	v_mfma_f32_32x32x16_bf16 v[32:47], v[116:119], v[48:51], v[32:47]
	v_exp_f32_e32 v196, v196
	v_exp_f32_e32 v197, v197
	v_mfma_f32_32x32x16_bf16 v[32:47], v[120:123], v[52:55], v[32:47]
	v_exp_f32_e32 v198, v198
	v_exp_f32_e32 v199, v199
	v_mfma_f32_32x32x16_bf16 v[32:47], v[124:127], v[56:59], v[32:47]
	v_exp_f32_e32 v200, v200
	v_exp_f32_e32 v201, v201
	v_mfma_f32_32x32x16_bf16 v[32:47], v[128:131], v[60:63], v[32:47]
	v_exp_f32_e32 v202, v202
	v_exp_f32_e32 v203, v203
	v_cvt_pk_bf16_f32 v64, v188, v189
	v_cvt_pk_bf16_f32 v65, v190, v191
	v_cvt_pk_bf16_f32 v66, v192, v193
	v_cvt_pk_bf16_f32 v67, v194, v195
	v_cvt_pk_bf16_f32 v68, v196, v197
	v_cvt_pk_bf16_f32 v69, v198, v199
	v_cvt_pk_bf16_f32 v70, v200, v201
	v_cvt_pk_bf16_f32 v71, v202, v203
	v_pk_add_f32 v[232:233], v[232:233], v[188:189]
	v_pk_add_f32 v[232:233], v[232:233], v[190:191]
	v_pk_add_f32 v[232:233], v[232:233], v[192:193]
	v_pk_add_f32 v[232:233], v[232:233], v[194:195]
	v_pk_add_f32 v[232:233], v[232:233], v[196:197]
	v_pk_add_f32 v[232:233], v[232:233], v[198:199]
	v_pk_add_f32 v[232:233], v[232:233], v[200:201]
	v_pk_add_f32 v[232:233], v[232:233], v[202:203]
	ds_read2_b32 v[188:189], v115 offset0:68 offset1:69
	ds_read2_b32 v[190:191], v115 offset0:70 offset1:71
	ds_read2_b32 v[192:193], v115 offset0:76 offset1:77
	ds_read2_b32 v[194:195], v115 offset0:78 offset1:79
	ds_read2_b32 v[196:197], v115 offset0:85 offset1:86
	ds_read2_b32 v[198:199], v115 offset0:87 offset1:88
	ds_read2_b32 v[200:201], v115 offset0:93 offset1:94
	ds_read2_b32 v[202:203], v115 offset0:95 offset1:96
	global_load_dwordx4 v[116:119], v235, s[84:85]
	global_load_dwordx4 v[120:123], v236, s[84:85]
	global_load_dwordx4 v[124:127], v237, s[84:85]
	global_load_dwordx4 v[128:131], v238, s[84:85]
	global_load_dwordx4 v[132:135], v100, s[84:85] offset:768
	global_load_dwordx4 v[136:139], v149, s[84:85] offset:768
	global_load_dwordx4 v[140:143], v100, s[84:85] offset:832
	global_load_dwordx4 v[144:147], v149, s[84:85] offset:832
	s_add_u32 s84, s84, 0x30000
	s_addc_u32 s85, s85, 0
	ds_read_b64_tr_b16 v[72:73], v231
	ds_read_b64_tr_b16 v[74:75], v231 offset:512
	ds_read_b64_tr_b16 v[76:77], v231 offset:2048
	ds_read_b64_tr_b16 v[78:79], v231 offset:2560
	ds_read_b64_tr_b16 v[220:221], v231 offset:1024
	ds_read_b64_tr_b16 v[222:223], v231 offset:1536
	ds_read_b64_tr_b16 v[224:225], v231 offset:3072
	ds_read_b64_tr_b16 v[226:227], v231 offset:3584
	v_exp_f32_e32 v32, v32
	v_exp_f32_e32 v33, v33
	v_exp_f32_e32 v34, v34
	v_exp_f32_e32 v35, v35
	s_waitcnt vmcnt(8)
	ds_write_b128 v247, v[156:159]
	ds_write_b128 v247, v[160:163] offset:1024
	ds_write_b128 v247, v[164:167] offset:2048
	ds_write_b128 v247, v[168:171] offset:3072
	ds_read_b128 v[156:159], v248
	ds_read_b128 v[160:163], v249
	ds_read_b128 v[164:167], v250
	ds_read_b128 v[168:171], v251
	ds_write_b128 v112, v[172:175]
	ds_write_b128 v112, v[176:179] offset:1024
	ds_write_b128 v112, v[180:183] offset:2048
	ds_write_b128 v112, v[184:187] offset:3072
	v_mfma_f32_32x32x16_bf16 v[0:15], v[64:67], v[204:207], v[0:15]
	v_mfma_f32_32x32x16_bf16 v[16:31], v[64:67], v[208:211], v[16:31]
	v_mfma_f32_32x32x16_bf16 v[0:15], v[68:71], v[212:215], v[0:15]
	v_mfma_f32_32x32x16_bf16 v[16:31], v[68:71], v[216:219], v[16:31]
	v_exp_f32_e32 v36, v36
	v_exp_f32_e32 v37, v37
	v_exp_f32_e32 v38, v38
	v_exp_f32_e32 v39, v39
	s_waitcnt lgkmcnt(4)
	v_mfma_f32_32x32x16_bf16 v[188:203], v[156:159], v[48:51], v[188:203]
	v_exp_f32_e32 v40, v40
	v_exp_f32_e32 v41, v41
	v_mfma_f32_32x32x16_bf16 v[188:203], v[160:163], v[52:55], v[188:203]
	v_exp_f32_e32 v42, v42
	v_exp_f32_e32 v43, v43
	v_mfma_f32_32x32x16_bf16 v[188:203], v[164:167], v[56:59], v[188:203]
	v_exp_f32_e32 v44, v44
	v_exp_f32_e32 v45, v45
	v_mfma_f32_32x32x16_bf16 v[188:203], v[168:171], v[60:63], v[188:203]
	v_exp_f32_e32 v46, v46
	v_exp_f32_e32 v47, v47
	v_cvt_pk_bf16_f32 v64, v32, v33
	v_cvt_pk_bf16_f32 v65, v34, v35
	v_cvt_pk_bf16_f32 v66, v36, v37
	v_cvt_pk_bf16_f32 v67, v38, v39
	v_cvt_pk_bf16_f32 v68, v40, v41
	v_cvt_pk_bf16_f32 v69, v42, v43
	v_cvt_pk_bf16_f32 v70, v44, v45
	v_cvt_pk_bf16_f32 v71, v46, v47
	v_pk_add_f32 v[232:233], v[232:233], v[32:33]
	v_pk_add_f32 v[232:233], v[232:233], v[34:35]
	v_pk_add_f32 v[232:233], v[232:233], v[36:37]
	v_pk_add_f32 v[232:233], v[232:233], v[38:39]
	v_pk_add_f32 v[232:233], v[232:233], v[40:41]
	v_pk_add_f32 v[232:233], v[232:233], v[42:43]
	v_pk_add_f32 v[232:233], v[232:233], v[44:45]
	v_pk_add_f32 v[232:233], v[232:233], v[46:47]
	ds_read2_b32 v[32:33], v115 offset0:102 offset1:103
	ds_read2_b32 v[34:35], v115 offset0:104 offset1:105
	ds_read2_b32 v[36:37], v115 offset0:110 offset1:111
	ds_read2_b32 v[38:39], v115 offset0:112 offset1:113
	ds_read2_b32 v[40:41], v115 offset0:119 offset1:120
	ds_read2_b32 v[42:43], v115 offset0:121 offset1:122
	ds_read2_b32 v[44:45], v115 offset0:127 offset1:128
	ds_read2_b32 v[46:47], v115 offset0:129 offset1:130
	global_load_dwordx4 v[156:159], v235, s[84:85]
	global_load_dwordx4 v[160:163], v236, s[84:85]
	global_load_dwordx4 v[164:167], v237, s[84:85]
	global_load_dwordx4 v[168:171], v238, s[84:85]
	global_load_dwordx4 v[172:175], v100, s[84:85] offset:768
	global_load_dwordx4 v[176:179], v149, s[84:85] offset:768
	global_load_dwordx4 v[180:183], v100, s[84:85] offset:832
	global_load_dwordx4 v[184:187], v149, s[84:85] offset:832
	s_add_u32 s84, s84, 0x30000
	s_addc_u32 s85, s85, 0
	ds_read_b64_tr_b16 v[204:205], v231
	ds_read_b64_tr_b16 v[206:207], v231 offset:512
	ds_read_b64_tr_b16 v[208:209], v231 offset:2048
	ds_read_b64_tr_b16 v[210:211], v231 offset:2560
	ds_read_b64_tr_b16 v[212:213], v231 offset:1024
	ds_read_b64_tr_b16 v[214:215], v231 offset:1536
	ds_read_b64_tr_b16 v[216:217], v231 offset:3072
	ds_read_b64_tr_b16 v[218:219], v231 offset:3584
	v_exp_f32_e32 v188, v188
	v_exp_f32_e32 v189, v189
	v_exp_f32_e32 v190, v190
	v_exp_f32_e32 v191, v191
	s_waitcnt vmcnt(8)
	ds_write_b128 v247, v[116:119]
	ds_write_b128 v247, v[120:123] offset:1024
	ds_write_b128 v247, v[124:127] offset:2048
	ds_write_b128 v247, v[128:131] offset:3072
	ds_read_b128 v[116:119], v248
	ds_read_b128 v[120:123], v249
	ds_read_b128 v[124:127], v250
	ds_read_b128 v[128:131], v251
	ds_write_b128 v112, v[132:135]
	ds_write_b128 v112, v[136:139] offset:1024
	ds_write_b128 v112, v[140:143] offset:2048
	ds_write_b128 v112, v[144:147] offset:3072
	v_mfma_f32_32x32x16_bf16 v[0:15], v[64:67], v[72:75], v[0:15]
	v_mfma_f32_32x32x16_bf16 v[16:31], v[64:67], v[76:79], v[16:31]
	v_mfma_f32_32x32x16_bf16 v[0:15], v[68:71], v[220:223], v[0:15]
	v_mfma_f32_32x32x16_bf16 v[16:31], v[68:71], v[224:227], v[16:31]
	v_exp_f32_e32 v192, v192
	v_exp_f32_e32 v193, v193
	v_exp_f32_e32 v194, v194
	v_exp_f32_e32 v195, v195
	s_waitcnt lgkmcnt(4)
	v_mfma_f32_32x32x16_bf16 v[32:47], v[116:119], v[48:51], v[32:47]
	v_exp_f32_e32 v196, v196
	v_exp_f32_e32 v197, v197
	v_mfma_f32_32x32x16_bf16 v[32:47], v[120:123], v[52:55], v[32:47]
	v_exp_f32_e32 v198, v198
	v_exp_f32_e32 v199, v199
	v_mfma_f32_32x32x16_bf16 v[32:47], v[124:127], v[56:59], v[32:47]
	v_exp_f32_e32 v200, v200
	v_exp_f32_e32 v201, v201
	v_mfma_f32_32x32x16_bf16 v[32:47], v[128:131], v[60:63], v[32:47]
	v_exp_f32_e32 v202, v202
	v_exp_f32_e32 v203, v203
	v_cvt_pk_bf16_f32 v64, v188, v189
	v_cvt_pk_bf16_f32 v65, v190, v191
	v_cvt_pk_bf16_f32 v66, v192, v193
	v_cvt_pk_bf16_f32 v67, v194, v195
	v_cvt_pk_bf16_f32 v68, v196, v197
	v_cvt_pk_bf16_f32 v69, v198, v199
	v_cvt_pk_bf16_f32 v70, v200, v201
	v_cvt_pk_bf16_f32 v71, v202, v203
	v_pk_add_f32 v[232:233], v[232:233], v[188:189]
	v_pk_add_f32 v[232:233], v[232:233], v[190:191]
	v_pk_add_f32 v[232:233], v[232:233], v[192:193]
	v_pk_add_f32 v[232:233], v[232:233], v[194:195]
	v_pk_add_f32 v[232:233], v[232:233], v[196:197]
	v_pk_add_f32 v[232:233], v[232:233], v[198:199]
	v_pk_add_f32 v[232:233], v[232:233], v[200:201]
	v_pk_add_f32 v[232:233], v[232:233], v[202:203]
	ds_read2_b32 v[188:189], v115 offset0:136 offset1:137
	ds_read2_b32 v[190:191], v115 offset0:138 offset1:139
	ds_read2_b32 v[192:193], v115 offset0:144 offset1:145
	ds_read2_b32 v[194:195], v115 offset0:146 offset1:147
	ds_read2_b32 v[196:197], v115 offset0:153 offset1:154
	ds_read2_b32 v[198:199], v115 offset0:155 offset1:156
	ds_read2_b32 v[200:201], v115 offset0:161 offset1:162
	ds_read2_b32 v[202:203], v115 offset0:163 offset1:164
	global_load_dwordx4 v[116:119], v235, s[84:85]
	global_load_dwordx4 v[120:123], v236, s[84:85]
	global_load_dwordx4 v[124:127], v237, s[84:85]
	global_load_dwordx4 v[128:131], v238, s[84:85]
	global_load_dwordx4 v[132:135], v100, s[84:85] offset:768
	global_load_dwordx4 v[136:139], v149, s[84:85] offset:768
	global_load_dwordx4 v[140:143], v100, s[84:85] offset:832
	global_load_dwordx4 v[144:147], v149, s[84:85] offset:832
	s_add_u32 s84, s84, 0x30000
	s_addc_u32 s85, s85, 0
	ds_read_b64_tr_b16 v[72:73], v231
	ds_read_b64_tr_b16 v[74:75], v231 offset:512
	ds_read_b64_tr_b16 v[76:77], v231 offset:2048
	ds_read_b64_tr_b16 v[78:79], v231 offset:2560
	ds_read_b64_tr_b16 v[220:221], v231 offset:1024
	ds_read_b64_tr_b16 v[222:223], v231 offset:1536
	ds_read_b64_tr_b16 v[224:225], v231 offset:3072
	ds_read_b64_tr_b16 v[226:227], v231 offset:3584
	v_exp_f32_e32 v32, v32
	v_exp_f32_e32 v33, v33
	v_exp_f32_e32 v34, v34
	v_exp_f32_e32 v35, v35
	s_waitcnt vmcnt(8)
	ds_write_b128 v247, v[156:159]
	ds_write_b128 v247, v[160:163] offset:1024
	ds_write_b128 v247, v[164:167] offset:2048
	ds_write_b128 v247, v[168:171] offset:3072
	ds_read_b128 v[156:159], v248
	ds_read_b128 v[160:163], v249
	ds_read_b128 v[164:167], v250
	ds_read_b128 v[168:171], v251
	ds_write_b128 v112, v[172:175]
	ds_write_b128 v112, v[176:179] offset:1024
	ds_write_b128 v112, v[180:183] offset:2048
	ds_write_b128 v112, v[184:187] offset:3072
	v_mfma_f32_32x32x16_bf16 v[0:15], v[64:67], v[204:207], v[0:15]
	v_mfma_f32_32x32x16_bf16 v[16:31], v[64:67], v[208:211], v[16:31]
	v_mfma_f32_32x32x16_bf16 v[0:15], v[68:71], v[212:215], v[0:15]
	v_mfma_f32_32x32x16_bf16 v[16:31], v[68:71], v[216:219], v[16:31]
	v_exp_f32_e32 v36, v36
	v_exp_f32_e32 v37, v37
	v_exp_f32_e32 v38, v38
	v_exp_f32_e32 v39, v39
	s_waitcnt lgkmcnt(4)
	v_mfma_f32_32x32x16_bf16 v[188:203], v[156:159], v[48:51], v[188:203]
	v_exp_f32_e32 v40, v40
	v_exp_f32_e32 v41, v41
	v_mfma_f32_32x32x16_bf16 v[188:203], v[160:163], v[52:55], v[188:203]
	v_exp_f32_e32 v42, v42
	v_exp_f32_e32 v43, v43
	v_mfma_f32_32x32x16_bf16 v[188:203], v[164:167], v[56:59], v[188:203]
	v_exp_f32_e32 v44, v44
	v_exp_f32_e32 v45, v45
	v_mfma_f32_32x32x16_bf16 v[188:203], v[168:171], v[60:63], v[188:203]
	v_exp_f32_e32 v46, v46
	v_exp_f32_e32 v47, v47
	v_cvt_pk_bf16_f32 v64, v32, v33
	v_cvt_pk_bf16_f32 v65, v34, v35
	v_cvt_pk_bf16_f32 v66, v36, v37
	v_cvt_pk_bf16_f32 v67, v38, v39
	v_cvt_pk_bf16_f32 v68, v40, v41
	v_cvt_pk_bf16_f32 v69, v42, v43
	v_cvt_pk_bf16_f32 v70, v44, v45
	v_cvt_pk_bf16_f32 v71, v46, v47
	v_pk_add_f32 v[232:233], v[232:233], v[32:33]
	v_pk_add_f32 v[232:233], v[232:233], v[34:35]
	v_pk_add_f32 v[232:233], v[232:233], v[36:37]
	v_pk_add_f32 v[232:233], v[232:233], v[38:39]
	v_pk_add_f32 v[232:233], v[232:233], v[40:41]
	v_pk_add_f32 v[232:233], v[232:233], v[42:43]
	v_pk_add_f32 v[232:233], v[232:233], v[44:45]
	v_pk_add_f32 v[232:233], v[232:233], v[46:47]
	ds_read2_b32 v[32:33], v115 offset0:170 offset1:171
	ds_read2_b32 v[34:35], v115 offset0:172 offset1:173
	ds_read2_b32 v[36:37], v115 offset0:178 offset1:179
	ds_read2_b32 v[38:39], v115 offset0:180 offset1:181
	ds_read2_b32 v[40:41], v115 offset0:187 offset1:188
	ds_read2_b32 v[42:43], v115 offset0:189 offset1:190
	ds_read2_b32 v[44:45], v115 offset0:195 offset1:196
	ds_read2_b32 v[46:47], v115 offset0:197 offset1:198
	global_load_dwordx4 v[156:159], v235, s[84:85]
	global_load_dwordx4 v[160:163], v236, s[84:85]
	global_load_dwordx4 v[164:167], v237, s[84:85]
	global_load_dwordx4 v[168:171], v238, s[84:85]
	global_load_dwordx4 v[172:175], v100, s[84:85] offset:768
	global_load_dwordx4 v[176:179], v149, s[84:85] offset:768
	global_load_dwordx4 v[180:183], v100, s[84:85] offset:832
	global_load_dwordx4 v[184:187], v149, s[84:85] offset:832
	s_add_u32 s84, s84, 0x30000
	s_addc_u32 s85, s85, 0
	ds_read_b64_tr_b16 v[204:205], v231
	ds_read_b64_tr_b16 v[206:207], v231 offset:512
	ds_read_b64_tr_b16 v[208:209], v231 offset:2048
	ds_read_b64_tr_b16 v[210:211], v231 offset:2560
	ds_read_b64_tr_b16 v[212:213], v231 offset:1024
	ds_read_b64_tr_b16 v[214:215], v231 offset:1536
	ds_read_b64_tr_b16 v[216:217], v231 offset:3072
	ds_read_b64_tr_b16 v[218:219], v231 offset:3584
	v_exp_f32_e32 v188, v188
	v_exp_f32_e32 v189, v189
	v_exp_f32_e32 v190, v190
	v_exp_f32_e32 v191, v191
	s_waitcnt vmcnt(8)
	ds_write_b128 v247, v[116:119]
	ds_write_b128 v247, v[120:123] offset:1024
	ds_write_b128 v247, v[124:127] offset:2048
	ds_write_b128 v247, v[128:131] offset:3072
	ds_read_b128 v[116:119], v248
	ds_read_b128 v[120:123], v249
	ds_read_b128 v[124:127], v250
	ds_read_b128 v[128:131], v251
	ds_write_b128 v112, v[132:135]
	ds_write_b128 v112, v[136:139] offset:1024
	ds_write_b128 v112, v[140:143] offset:2048
	ds_write_b128 v112, v[144:147] offset:3072
	v_mfma_f32_32x32x16_bf16 v[0:15], v[64:67], v[72:75], v[0:15]
	v_mfma_f32_32x32x16_bf16 v[16:31], v[64:67], v[76:79], v[16:31]
	v_mfma_f32_32x32x16_bf16 v[0:15], v[68:71], v[220:223], v[0:15]
	v_mfma_f32_32x32x16_bf16 v[16:31], v[68:71], v[224:227], v[16:31]
	v_exp_f32_e32 v192, v192
	v_exp_f32_e32 v193, v193
	v_exp_f32_e32 v194, v194
	v_exp_f32_e32 v195, v195
	s_waitcnt lgkmcnt(4)
	v_mfma_f32_32x32x16_bf16 v[32:47], v[116:119], v[48:51], v[32:47]
	v_exp_f32_e32 v196, v196
	v_exp_f32_e32 v197, v197
	v_mfma_f32_32x32x16_bf16 v[32:47], v[120:123], v[52:55], v[32:47]
	v_exp_f32_e32 v198, v198
	v_exp_f32_e32 v199, v199
	v_mfma_f32_32x32x16_bf16 v[32:47], v[124:127], v[56:59], v[32:47]
	v_exp_f32_e32 v200, v200
	v_exp_f32_e32 v201, v201
	v_mfma_f32_32x32x16_bf16 v[32:47], v[128:131], v[60:63], v[32:47]
	v_exp_f32_e32 v202, v202
	v_exp_f32_e32 v203, v203
	v_cvt_pk_bf16_f32 v64, v188, v189
	v_cvt_pk_bf16_f32 v65, v190, v191
	v_cvt_pk_bf16_f32 v66, v192, v193
	v_cvt_pk_bf16_f32 v67, v194, v195
	v_cvt_pk_bf16_f32 v68, v196, v197
	v_cvt_pk_bf16_f32 v69, v198, v199
	v_cvt_pk_bf16_f32 v70, v200, v201
	v_cvt_pk_bf16_f32 v71, v202, v203
	v_pk_add_f32 v[232:233], v[232:233], v[188:189]
	v_pk_add_f32 v[232:233], v[232:233], v[190:191]
	v_pk_add_f32 v[232:233], v[232:233], v[192:193]
	v_pk_add_f32 v[232:233], v[232:233], v[194:195]
	v_pk_add_f32 v[232:233], v[232:233], v[196:197]
	v_pk_add_f32 v[232:233], v[232:233], v[198:199]
	v_pk_add_f32 v[232:233], v[232:233], v[200:201]
	v_pk_add_f32 v[232:233], v[232:233], v[202:203]
	ds_read2_b32 v[188:189], v115 offset0:204 offset1:205
	ds_read2_b32 v[190:191], v115 offset0:206 offset1:207
	ds_read2_b32 v[192:193], v115 offset0:212 offset1:213
	ds_read2_b32 v[194:195], v115 offset0:214 offset1:215
	ds_read2_b32 v[196:197], v115 offset0:221 offset1:222
	ds_read2_b32 v[198:199], v115 offset0:223 offset1:224
	ds_read2_b32 v[200:201], v115 offset0:229 offset1:230
	ds_read2_b32 v[202:203], v115 offset0:231 offset1:232
	global_load_dwordx4 v[116:119], v235, s[84:85]
	global_load_dwordx4 v[120:123], v236, s[84:85]
	global_load_dwordx4 v[124:127], v237, s[84:85]
	global_load_dwordx4 v[128:131], v238, s[84:85]
	global_load_dwordx4 v[132:135], v100, s[84:85] offset:768
	global_load_dwordx4 v[136:139], v149, s[84:85] offset:768
	global_load_dwordx4 v[140:143], v100, s[84:85] offset:832
	global_load_dwordx4 v[144:147], v149, s[84:85] offset:832
	s_add_u32 s84, s84, 0x30000
	s_addc_u32 s85, s85, 0
	ds_read_b64_tr_b16 v[72:73], v231
	ds_read_b64_tr_b16 v[74:75], v231 offset:512
	ds_read_b64_tr_b16 v[76:77], v231 offset:2048
	ds_read_b64_tr_b16 v[78:79], v231 offset:2560
	ds_read_b64_tr_b16 v[220:221], v231 offset:1024
	ds_read_b64_tr_b16 v[222:223], v231 offset:1536
	ds_read_b64_tr_b16 v[224:225], v231 offset:3072
	ds_read_b64_tr_b16 v[226:227], v231 offset:3584
	v_exp_f32_e32 v32, v32
	v_exp_f32_e32 v33, v33
	v_exp_f32_e32 v34, v34
	v_exp_f32_e32 v35, v35
	s_waitcnt vmcnt(8)
	ds_write_b128 v247, v[156:159]
	ds_write_b128 v247, v[160:163] offset:1024
	ds_write_b128 v247, v[164:167] offset:2048
	ds_write_b128 v247, v[168:171] offset:3072
	ds_read_b128 v[156:159], v248
	ds_read_b128 v[160:163], v249
	ds_read_b128 v[164:167], v250
	ds_read_b128 v[168:171], v251
	ds_write_b128 v112, v[172:175]
	ds_write_b128 v112, v[176:179] offset:1024
	ds_write_b128 v112, v[180:183] offset:2048
	ds_write_b128 v112, v[184:187] offset:3072
	v_mfma_f32_32x32x16_bf16 v[0:15], v[64:67], v[204:207], v[0:15]
	v_mfma_f32_32x32x16_bf16 v[16:31], v[64:67], v[208:211], v[16:31]
	v_mfma_f32_32x32x16_bf16 v[0:15], v[68:71], v[212:215], v[0:15]
	v_mfma_f32_32x32x16_bf16 v[16:31], v[68:71], v[216:219], v[16:31]
	v_exp_f32_e32 v36, v36
	v_exp_f32_e32 v37, v37
	v_exp_f32_e32 v38, v38
	v_exp_f32_e32 v39, v39
	s_waitcnt lgkmcnt(4)
	v_mfma_f32_32x32x16_bf16 v[188:203], v[156:159], v[48:51], v[188:203]
	v_exp_f32_e32 v40, v40
	v_exp_f32_e32 v41, v41
	v_mfma_f32_32x32x16_bf16 v[188:203], v[160:163], v[52:55], v[188:203]
	v_exp_f32_e32 v42, v42
	v_exp_f32_e32 v43, v43
	v_mfma_f32_32x32x16_bf16 v[188:203], v[164:167], v[56:59], v[188:203]
	v_exp_f32_e32 v44, v44
	v_exp_f32_e32 v45, v45
	v_mfma_f32_32x32x16_bf16 v[188:203], v[168:171], v[60:63], v[188:203]
	v_exp_f32_e32 v46, v46
	v_exp_f32_e32 v47, v47
	v_cvt_pk_bf16_f32 v64, v32, v33
	v_cvt_pk_bf16_f32 v65, v34, v35
	v_cvt_pk_bf16_f32 v66, v36, v37
	v_cvt_pk_bf16_f32 v67, v38, v39
	v_cvt_pk_bf16_f32 v68, v40, v41
	v_cvt_pk_bf16_f32 v69, v42, v43
	v_cvt_pk_bf16_f32 v70, v44, v45
	v_cvt_pk_bf16_f32 v71, v46, v47
	v_pk_add_f32 v[232:233], v[232:233], v[32:33]
	v_pk_add_f32 v[232:233], v[232:233], v[34:35]
	v_pk_add_f32 v[232:233], v[232:233], v[36:37]
	v_pk_add_f32 v[232:233], v[232:233], v[38:39]
	v_pk_add_f32 v[232:233], v[232:233], v[40:41]
	v_pk_add_f32 v[232:233], v[232:233], v[42:43]
	v_pk_add_f32 v[232:233], v[232:233], v[44:45]
	v_pk_add_f32 v[232:233], v[232:233], v[46:47]
	v_add_u32_e32 v115, 952, v115
	ds_read2_b32 v[32:33], v115 offset0:0 offset1:1
	ds_read2_b32 v[34:35], v115 offset0:2 offset1:3
	ds_read2_b32 v[36:37], v115 offset0:8 offset1:9
	ds_read2_b32 v[38:39], v115 offset0:10 offset1:11
	ds_read2_b32 v[40:41], v115 offset0:17 offset1:18
	ds_read2_b32 v[42:43], v115 offset0:19 offset1:20
	ds_read2_b32 v[44:45], v115 offset0:25 offset1:26
	ds_read2_b32 v[46:47], v115 offset0:27 offset1:28
	global_load_dwordx4 v[156:159], v235, s[84:85]
	global_load_dwordx4 v[160:163], v236, s[84:85]
	global_load_dwordx4 v[164:167], v237, s[84:85]
	global_load_dwordx4 v[168:171], v238, s[84:85]
	global_load_dwordx4 v[172:175], v100, s[84:85] offset:768
	global_load_dwordx4 v[176:179], v149, s[84:85] offset:768
	global_load_dwordx4 v[180:183], v100, s[84:85] offset:832
	global_load_dwordx4 v[184:187], v149, s[84:85] offset:832
	s_add_u32 s84, s84, 0x30000
	s_addc_u32 s85, s85, 0
	ds_read_b64_tr_b16 v[204:205], v231
	ds_read_b64_tr_b16 v[206:207], v231 offset:512
	ds_read_b64_tr_b16 v[208:209], v231 offset:2048
	ds_read_b64_tr_b16 v[210:211], v231 offset:2560
	ds_read_b64_tr_b16 v[212:213], v231 offset:1024
	ds_read_b64_tr_b16 v[214:215], v231 offset:1536
	ds_read_b64_tr_b16 v[216:217], v231 offset:3072
	ds_read_b64_tr_b16 v[218:219], v231 offset:3584
	v_exp_f32_e32 v188, v188
	v_exp_f32_e32 v189, v189
	v_exp_f32_e32 v190, v190
	v_exp_f32_e32 v191, v191
	s_waitcnt vmcnt(8)
	ds_write_b128 v247, v[116:119]
	ds_write_b128 v247, v[120:123] offset:1024
	ds_write_b128 v247, v[124:127] offset:2048
	ds_write_b128 v247, v[128:131] offset:3072
	ds_read_b128 v[116:119], v248
	ds_read_b128 v[120:123], v249
	ds_read_b128 v[124:127], v250
	ds_read_b128 v[128:131], v251
	ds_write_b128 v112, v[132:135]
	ds_write_b128 v112, v[136:139] offset:1024
	ds_write_b128 v112, v[140:143] offset:2048
	ds_write_b128 v112, v[144:147] offset:3072
	v_mfma_f32_32x32x16_bf16 v[0:15], v[64:67], v[72:75], v[0:15]
	v_mfma_f32_32x32x16_bf16 v[16:31], v[64:67], v[76:79], v[16:31]
	v_mfma_f32_32x32x16_bf16 v[0:15], v[68:71], v[220:223], v[0:15]
	v_mfma_f32_32x32x16_bf16 v[16:31], v[68:71], v[224:227], v[16:31]
	v_exp_f32_e32 v192, v192
	v_exp_f32_e32 v193, v193
	v_exp_f32_e32 v194, v194
	v_exp_f32_e32 v195, v195
	s_waitcnt lgkmcnt(4)
	v_mfma_f32_32x32x16_bf16 v[32:47], v[116:119], v[48:51], v[32:47]
	v_exp_f32_e32 v196, v196
	v_exp_f32_e32 v197, v197
	v_mfma_f32_32x32x16_bf16 v[32:47], v[120:123], v[52:55], v[32:47]
	v_exp_f32_e32 v198, v198
	v_exp_f32_e32 v199, v199
	v_mfma_f32_32x32x16_bf16 v[32:47], v[124:127], v[56:59], v[32:47]
	v_exp_f32_e32 v200, v200
	v_exp_f32_e32 v201, v201
	v_mfma_f32_32x32x16_bf16 v[32:47], v[128:131], v[60:63], v[32:47]
	v_exp_f32_e32 v202, v202
	v_exp_f32_e32 v203, v203
	v_cvt_pk_bf16_f32 v64, v188, v189
	v_cvt_pk_bf16_f32 v65, v190, v191
	v_cvt_pk_bf16_f32 v66, v192, v193
	v_cvt_pk_bf16_f32 v67, v194, v195
	v_cvt_pk_bf16_f32 v68, v196, v197
	v_cvt_pk_bf16_f32 v69, v198, v199
	v_cvt_pk_bf16_f32 v70, v200, v201
	v_cvt_pk_bf16_f32 v71, v202, v203
	v_pk_add_f32 v[232:233], v[232:233], v[188:189]
	v_pk_add_f32 v[232:233], v[232:233], v[190:191]
	v_pk_add_f32 v[232:233], v[232:233], v[192:193]
	v_pk_add_f32 v[232:233], v[232:233], v[194:195]
	v_pk_add_f32 v[232:233], v[232:233], v[196:197]
	v_pk_add_f32 v[232:233], v[232:233], v[198:199]
	v_pk_add_f32 v[232:233], v[232:233], v[200:201]
	v_pk_add_f32 v[232:233], v[232:233], v[202:203]
	ds_read2_b32 v[188:189], v115 offset0:34 offset1:35
	ds_read2_b32 v[190:191], v115 offset0:36 offset1:37
	ds_read2_b32 v[192:193], v115 offset0:42 offset1:43
	ds_read2_b32 v[194:195], v115 offset0:44 offset1:45
	ds_read2_b32 v[196:197], v115 offset0:51 offset1:52
	ds_read2_b32 v[198:199], v115 offset0:53 offset1:54
	ds_read2_b32 v[200:201], v115 offset0:59 offset1:60
	ds_read2_b32 v[202:203], v115 offset0:61 offset1:62
	global_load_dwordx4 v[116:119], v235, s[84:85]
	global_load_dwordx4 v[120:123], v236, s[84:85]
	global_load_dwordx4 v[124:127], v237, s[84:85]
	global_load_dwordx4 v[128:131], v238, s[84:85]
	global_load_dwordx4 v[132:135], v100, s[84:85] offset:768
	global_load_dwordx4 v[136:139], v149, s[84:85] offset:768
	global_load_dwordx4 v[140:143], v100, s[84:85] offset:832
	global_load_dwordx4 v[144:147], v149, s[84:85] offset:832
	s_add_u32 s84, s84, 0x30000
	s_addc_u32 s85, s85, 0
	ds_read_b64_tr_b16 v[72:73], v231
	ds_read_b64_tr_b16 v[74:75], v231 offset:512
	ds_read_b64_tr_b16 v[76:77], v231 offset:2048
	ds_read_b64_tr_b16 v[78:79], v231 offset:2560
	ds_read_b64_tr_b16 v[220:221], v231 offset:1024
	ds_read_b64_tr_b16 v[222:223], v231 offset:1536
	ds_read_b64_tr_b16 v[224:225], v231 offset:3072
	ds_read_b64_tr_b16 v[226:227], v231 offset:3584
	v_exp_f32_e32 v32, v32
	v_exp_f32_e32 v33, v33
	v_exp_f32_e32 v34, v34
	v_exp_f32_e32 v35, v35
	s_waitcnt vmcnt(8)
	ds_write_b128 v247, v[156:159]
	ds_write_b128 v247, v[160:163] offset:1024
	ds_write_b128 v247, v[164:167] offset:2048
	ds_write_b128 v247, v[168:171] offset:3072
	ds_read_b128 v[156:159], v248
	ds_read_b128 v[160:163], v249
	ds_read_b128 v[164:167], v250
	ds_read_b128 v[168:171], v251
	ds_write_b128 v112, v[172:175]
	ds_write_b128 v112, v[176:179] offset:1024
	ds_write_b128 v112, v[180:183] offset:2048
	ds_write_b128 v112, v[184:187] offset:3072
	v_mfma_f32_32x32x16_bf16 v[0:15], v[64:67], v[204:207], v[0:15]
	v_mfma_f32_32x32x16_bf16 v[16:31], v[64:67], v[208:211], v[16:31]
	v_mfma_f32_32x32x16_bf16 v[0:15], v[68:71], v[212:215], v[0:15]
	v_mfma_f32_32x32x16_bf16 v[16:31], v[68:71], v[216:219], v[16:31]
	v_exp_f32_e32 v36, v36
	v_exp_f32_e32 v37, v37
	v_exp_f32_e32 v38, v38
	v_exp_f32_e32 v39, v39
	s_waitcnt lgkmcnt(4)
	v_mfma_f32_32x32x16_bf16 v[188:203], v[156:159], v[48:51], v[188:203]
	v_exp_f32_e32 v40, v40
	v_exp_f32_e32 v41, v41
	v_mfma_f32_32x32x16_bf16 v[188:203], v[160:163], v[52:55], v[188:203]
	v_exp_f32_e32 v42, v42
	v_exp_f32_e32 v43, v43
	v_mfma_f32_32x32x16_bf16 v[188:203], v[164:167], v[56:59], v[188:203]
	v_exp_f32_e32 v44, v44
	v_exp_f32_e32 v45, v45
	v_mfma_f32_32x32x16_bf16 v[188:203], v[168:171], v[60:63], v[188:203]
	v_exp_f32_e32 v46, v46
	v_exp_f32_e32 v47, v47
	v_cvt_pk_bf16_f32 v64, v32, v33
	v_cvt_pk_bf16_f32 v65, v34, v35
	v_cvt_pk_bf16_f32 v66, v36, v37
	v_cvt_pk_bf16_f32 v67, v38, v39
	v_cvt_pk_bf16_f32 v68, v40, v41
	v_cvt_pk_bf16_f32 v69, v42, v43
	v_cvt_pk_bf16_f32 v70, v44, v45
	v_cvt_pk_bf16_f32 v71, v46, v47
	v_pk_add_f32 v[232:233], v[232:233], v[32:33]
	v_pk_add_f32 v[232:233], v[232:233], v[34:35]
	v_pk_add_f32 v[232:233], v[232:233], v[36:37]
	v_pk_add_f32 v[232:233], v[232:233], v[38:39]
	v_pk_add_f32 v[232:233], v[232:233], v[40:41]
	v_pk_add_f32 v[232:233], v[232:233], v[42:43]
	v_pk_add_f32 v[232:233], v[232:233], v[44:45]
	v_pk_add_f32 v[232:233], v[232:233], v[46:47]
	ds_read2_b32 v[32:33], v115 offset0:68 offset1:69
	ds_read2_b32 v[34:35], v115 offset0:70 offset1:71
	ds_read2_b32 v[36:37], v115 offset0:76 offset1:77
	ds_read2_b32 v[38:39], v115 offset0:78 offset1:79
	ds_read2_b32 v[40:41], v115 offset0:85 offset1:86
	ds_read2_b32 v[42:43], v115 offset0:87 offset1:88
	ds_read2_b32 v[44:45], v115 offset0:93 offset1:94
	ds_read2_b32 v[46:47], v115 offset0:95 offset1:96
	global_load_dwordx4 v[156:159], v235, s[84:85]
	global_load_dwordx4 v[160:163], v236, s[84:85]
	global_load_dwordx4 v[164:167], v237, s[84:85]
	global_load_dwordx4 v[168:171], v238, s[84:85]
	global_load_dwordx4 v[172:175], v100, s[84:85] offset:768
	global_load_dwordx4 v[176:179], v149, s[84:85] offset:768
	global_load_dwordx4 v[180:183], v100, s[84:85] offset:832
	global_load_dwordx4 v[184:187], v149, s[84:85] offset:832
	s_add_u32 s84, s84, 0x30000
	s_addc_u32 s85, s85, 0
	ds_read_b64_tr_b16 v[204:205], v231
	ds_read_b64_tr_b16 v[206:207], v231 offset:512
	ds_read_b64_tr_b16 v[208:209], v231 offset:2048
	ds_read_b64_tr_b16 v[210:211], v231 offset:2560
	ds_read_b64_tr_b16 v[212:213], v231 offset:1024
	ds_read_b64_tr_b16 v[214:215], v231 offset:1536
	ds_read_b64_tr_b16 v[216:217], v231 offset:3072
	ds_read_b64_tr_b16 v[218:219], v231 offset:3584
	v_exp_f32_e32 v188, v188
	v_exp_f32_e32 v189, v189
	v_exp_f32_e32 v190, v190
	v_exp_f32_e32 v191, v191
	s_waitcnt vmcnt(8)
	ds_write_b128 v247, v[116:119]
	ds_write_b128 v247, v[120:123] offset:1024
	ds_write_b128 v247, v[124:127] offset:2048
	ds_write_b128 v247, v[128:131] offset:3072
	ds_read_b128 v[116:119], v248
	ds_read_b128 v[120:123], v249
	ds_read_b128 v[124:127], v250
	ds_read_b128 v[128:131], v251
	ds_write_b128 v112, v[132:135]
	ds_write_b128 v112, v[136:139] offset:1024
	ds_write_b128 v112, v[140:143] offset:2048
	ds_write_b128 v112, v[144:147] offset:3072
	v_mfma_f32_32x32x16_bf16 v[0:15], v[64:67], v[72:75], v[0:15]
	v_mfma_f32_32x32x16_bf16 v[16:31], v[64:67], v[76:79], v[16:31]
	v_mfma_f32_32x32x16_bf16 v[0:15], v[68:71], v[220:223], v[0:15]
	v_mfma_f32_32x32x16_bf16 v[16:31], v[68:71], v[224:227], v[16:31]
	v_exp_f32_e32 v192, v192
	v_exp_f32_e32 v193, v193
	v_exp_f32_e32 v194, v194
	v_exp_f32_e32 v195, v195
	s_waitcnt lgkmcnt(4)
	v_mfma_f32_32x32x16_bf16 v[32:47], v[116:119], v[48:51], v[32:47]
	v_exp_f32_e32 v196, v196
	v_exp_f32_e32 v197, v197
	v_mfma_f32_32x32x16_bf16 v[32:47], v[120:123], v[52:55], v[32:47]
	v_exp_f32_e32 v198, v198
	v_exp_f32_e32 v199, v199
	v_mfma_f32_32x32x16_bf16 v[32:47], v[124:127], v[56:59], v[32:47]
	v_exp_f32_e32 v200, v200
	v_exp_f32_e32 v201, v201
	v_mfma_f32_32x32x16_bf16 v[32:47], v[128:131], v[60:63], v[32:47]
	v_exp_f32_e32 v202, v202
	v_exp_f32_e32 v203, v203
	v_cvt_pk_bf16_f32 v64, v188, v189
	v_cvt_pk_bf16_f32 v65, v190, v191
	v_cvt_pk_bf16_f32 v66, v192, v193
	v_cvt_pk_bf16_f32 v67, v194, v195
	v_cvt_pk_bf16_f32 v68, v196, v197
	v_cvt_pk_bf16_f32 v69, v198, v199
	v_cvt_pk_bf16_f32 v70, v200, v201
	v_cvt_pk_bf16_f32 v71, v202, v203
	v_pk_add_f32 v[232:233], v[232:233], v[188:189]
	v_pk_add_f32 v[232:233], v[232:233], v[190:191]
	v_pk_add_f32 v[232:233], v[232:233], v[192:193]
	v_pk_add_f32 v[232:233], v[232:233], v[194:195]
	v_pk_add_f32 v[232:233], v[232:233], v[196:197]
	v_pk_add_f32 v[232:233], v[232:233], v[198:199]
	v_pk_add_f32 v[232:233], v[232:233], v[200:201]
	v_pk_add_f32 v[232:233], v[232:233], v[202:203]
	ds_read2_b32 v[188:189], v115 offset0:102 offset1:103
	ds_read2_b32 v[190:191], v115 offset0:104 offset1:105
	ds_read2_b32 v[192:193], v115 offset0:110 offset1:111
	ds_read2_b32 v[194:195], v115 offset0:112 offset1:113
	ds_read2_b32 v[196:197], v115 offset0:119 offset1:120
	ds_read2_b32 v[198:199], v115 offset0:121 offset1:122
	ds_read2_b32 v[200:201], v115 offset0:127 offset1:128
	ds_read2_b32 v[202:203], v115 offset0:129 offset1:130
	global_load_dwordx4 v[116:119], v235, s[84:85]
	global_load_dwordx4 v[120:123], v236, s[84:85]
	global_load_dwordx4 v[124:127], v237, s[84:85]
	global_load_dwordx4 v[128:131], v238, s[84:85]
	global_load_dwordx4 v[132:135], v100, s[84:85] offset:768
	global_load_dwordx4 v[136:139], v149, s[84:85] offset:768
	global_load_dwordx4 v[140:143], v100, s[84:85] offset:832
	global_load_dwordx4 v[144:147], v149, s[84:85] offset:832
	s_add_u32 s84, s84, 0x30000
	s_addc_u32 s85, s85, 0
	ds_read_b64_tr_b16 v[72:73], v231
	ds_read_b64_tr_b16 v[74:75], v231 offset:512
	ds_read_b64_tr_b16 v[76:77], v231 offset:2048
	ds_read_b64_tr_b16 v[78:79], v231 offset:2560
	ds_read_b64_tr_b16 v[220:221], v231 offset:1024
	ds_read_b64_tr_b16 v[222:223], v231 offset:1536
	ds_read_b64_tr_b16 v[224:225], v231 offset:3072
	ds_read_b64_tr_b16 v[226:227], v231 offset:3584
	v_exp_f32_e32 v32, v32
	v_exp_f32_e32 v33, v33
	v_exp_f32_e32 v34, v34
	v_exp_f32_e32 v35, v35
	s_waitcnt vmcnt(8)
	ds_write_b128 v247, v[156:159]
	ds_write_b128 v247, v[160:163] offset:1024
	ds_write_b128 v247, v[164:167] offset:2048
	ds_write_b128 v247, v[168:171] offset:3072
	ds_read_b128 v[156:159], v248
	ds_read_b128 v[160:163], v249
	ds_read_b128 v[164:167], v250
	ds_read_b128 v[168:171], v251
	ds_write_b128 v112, v[172:175]
	ds_write_b128 v112, v[176:179] offset:1024
	ds_write_b128 v112, v[180:183] offset:2048
	ds_write_b128 v112, v[184:187] offset:3072
	v_mfma_f32_32x32x16_bf16 v[0:15], v[64:67], v[204:207], v[0:15]
	v_mfma_f32_32x32x16_bf16 v[16:31], v[64:67], v[208:211], v[16:31]
	v_mfma_f32_32x32x16_bf16 v[0:15], v[68:71], v[212:215], v[0:15]
	v_mfma_f32_32x32x16_bf16 v[16:31], v[68:71], v[216:219], v[16:31]
	v_exp_f32_e32 v36, v36
	v_exp_f32_e32 v37, v37
	v_exp_f32_e32 v38, v38
	v_exp_f32_e32 v39, v39
	s_waitcnt lgkmcnt(4)
	v_mfma_f32_32x32x16_bf16 v[188:203], v[156:159], v[48:51], v[188:203]
	v_exp_f32_e32 v40, v40
	v_exp_f32_e32 v41, v41
	v_mfma_f32_32x32x16_bf16 v[188:203], v[160:163], v[52:55], v[188:203]
	v_exp_f32_e32 v42, v42
	v_exp_f32_e32 v43, v43
	v_mfma_f32_32x32x16_bf16 v[188:203], v[164:167], v[56:59], v[188:203]
	v_exp_f32_e32 v44, v44
	v_exp_f32_e32 v45, v45
	v_mfma_f32_32x32x16_bf16 v[188:203], v[168:171], v[60:63], v[188:203]
	v_exp_f32_e32 v46, v46
	v_exp_f32_e32 v47, v47
	v_cvt_pk_bf16_f32 v64, v32, v33
	v_cvt_pk_bf16_f32 v65, v34, v35
	v_cvt_pk_bf16_f32 v66, v36, v37
	v_cvt_pk_bf16_f32 v67, v38, v39
	v_cvt_pk_bf16_f32 v68, v40, v41
	v_cvt_pk_bf16_f32 v69, v42, v43
	v_cvt_pk_bf16_f32 v70, v44, v45
	v_cvt_pk_bf16_f32 v71, v46, v47
	v_pk_add_f32 v[232:233], v[232:233], v[32:33]
	v_pk_add_f32 v[232:233], v[232:233], v[34:35]
	v_pk_add_f32 v[232:233], v[232:233], v[36:37]
	v_pk_add_f32 v[232:233], v[232:233], v[38:39]
	v_pk_add_f32 v[232:233], v[232:233], v[40:41]
	v_pk_add_f32 v[232:233], v[232:233], v[42:43]
	v_pk_add_f32 v[232:233], v[232:233], v[44:45]
	v_pk_add_f32 v[232:233], v[232:233], v[46:47]
	ds_read2_b32 v[32:33], v115 offset0:136 offset1:137
	ds_read2_b32 v[34:35], v115 offset0:138 offset1:139
	ds_read2_b32 v[36:37], v115 offset0:144 offset1:145
	ds_read2_b32 v[38:39], v115 offset0:146 offset1:147
	ds_read2_b32 v[40:41], v115 offset0:153 offset1:154
	ds_read2_b32 v[42:43], v115 offset0:155 offset1:156
	ds_read2_b32 v[44:45], v115 offset0:161 offset1:162
	ds_read2_b32 v[46:47], v115 offset0:163 offset1:164
	global_load_dwordx4 v[156:159], v235, s[84:85]
	global_load_dwordx4 v[160:163], v236, s[84:85]
	global_load_dwordx4 v[164:167], v237, s[84:85]
	global_load_dwordx4 v[168:171], v238, s[84:85]
	global_load_dwordx4 v[172:175], v100, s[84:85] offset:768
	global_load_dwordx4 v[176:179], v149, s[84:85] offset:768
	global_load_dwordx4 v[180:183], v100, s[84:85] offset:832
	global_load_dwordx4 v[184:187], v149, s[84:85] offset:832
	ds_read_b64_tr_b16 v[204:205], v231
	ds_read_b64_tr_b16 v[206:207], v231 offset:512
	ds_read_b64_tr_b16 v[208:209], v231 offset:2048
	ds_read_b64_tr_b16 v[210:211], v231 offset:2560
	ds_read_b64_tr_b16 v[212:213], v231 offset:1024
	ds_read_b64_tr_b16 v[214:215], v231 offset:1536
	ds_read_b64_tr_b16 v[216:217], v231 offset:3072
	ds_read_b64_tr_b16 v[218:219], v231 offset:3584
	v_exp_f32_e32 v188, v188
	v_exp_f32_e32 v189, v189
	v_exp_f32_e32 v190, v190
	v_exp_f32_e32 v191, v191
	s_waitcnt vmcnt(8)
	ds_write_b128 v247, v[116:119]
	ds_write_b128 v247, v[120:123] offset:1024
	ds_write_b128 v247, v[124:127] offset:2048
	ds_write_b128 v247, v[128:131] offset:3072
	ds_read_b128 v[116:119], v248
	ds_read_b128 v[120:123], v249
	ds_read_b128 v[124:127], v250
	ds_read_b128 v[128:131], v251
	ds_write_b128 v112, v[132:135]
	ds_write_b128 v112, v[136:139] offset:1024
	ds_write_b128 v112, v[140:143] offset:2048
	ds_write_b128 v112, v[144:147] offset:3072
	v_mfma_f32_32x32x16_bf16 v[0:15], v[64:67], v[72:75], v[0:15]
	v_mfma_f32_32x32x16_bf16 v[16:31], v[64:67], v[76:79], v[16:31]
	v_mfma_f32_32x32x16_bf16 v[0:15], v[68:71], v[220:223], v[0:15]
	v_mfma_f32_32x32x16_bf16 v[16:31], v[68:71], v[224:227], v[16:31]
	v_exp_f32_e32 v192, v192
	v_exp_f32_e32 v193, v193
	v_exp_f32_e32 v194, v194
	v_exp_f32_e32 v195, v195
	s_waitcnt lgkmcnt(4)
	v_mfma_f32_32x32x16_bf16 v[32:47], v[116:119], v[48:51], v[32:47]
	v_exp_f32_e32 v196, v196
	v_exp_f32_e32 v197, v197
	v_mfma_f32_32x32x16_bf16 v[32:47], v[120:123], v[52:55], v[32:47]
	v_exp_f32_e32 v198, v198
	v_exp_f32_e32 v199, v199
	v_mfma_f32_32x32x16_bf16 v[32:47], v[124:127], v[56:59], v[32:47]
	v_exp_f32_e32 v200, v200
	v_exp_f32_e32 v201, v201
	v_mfma_f32_32x32x16_bf16 v[32:47], v[128:131], v[60:63], v[32:47]
	v_exp_f32_e32 v202, v202
	v_exp_f32_e32 v203, v203
	v_cvt_pk_bf16_f32 v64, v188, v189
	v_cvt_pk_bf16_f32 v65, v190, v191
	v_cvt_pk_bf16_f32 v66, v192, v193
	v_cvt_pk_bf16_f32 v67, v194, v195
	v_cvt_pk_bf16_f32 v68, v196, v197
	v_cvt_pk_bf16_f32 v69, v198, v199
	v_cvt_pk_bf16_f32 v70, v200, v201
	v_cvt_pk_bf16_f32 v71, v202, v203
	v_pk_add_f32 v[232:233], v[232:233], v[188:189]
	v_pk_add_f32 v[232:233], v[232:233], v[190:191]
	v_pk_add_f32 v[232:233], v[232:233], v[192:193]
	v_pk_add_f32 v[232:233], v[232:233], v[194:195]
	v_pk_add_f32 v[232:233], v[232:233], v[196:197]
	v_pk_add_f32 v[232:233], v[232:233], v[198:199]
	v_pk_add_f32 v[232:233], v[232:233], v[200:201]
	v_pk_add_f32 v[232:233], v[232:233], v[202:203]
	ds_read2_b32 v[188:189], v115 offset0:170 offset1:171
	ds_read2_b32 v[190:191], v115 offset0:172 offset1:173
	ds_read2_b32 v[192:193], v115 offset0:178 offset1:179
	ds_read2_b32 v[194:195], v115 offset0:180 offset1:181
	ds_read2_b32 v[196:197], v115 offset0:187 offset1:188
	ds_read2_b32 v[198:199], v115 offset0:189 offset1:190
	ds_read2_b32 v[200:201], v115 offset0:195 offset1:196
	ds_read2_b32 v[202:203], v115 offset0:197 offset1:198
	global_load_dwordx4 v[116:119], v239, s[86:87]
	global_load_dwordx4 v[120:123], v240, s[86:87]
	global_load_dwordx4 v[124:127], v241, s[86:87]
	global_load_dwordx4 v[128:131], v242, s[86:87]
	global_load_dwordx4 v[132:135], v101, s[86:87] offset:768
	global_load_dwordx4 v[136:139], v150, s[86:87] offset:768
	global_load_dwordx4 v[140:143], v101, s[86:87] offset:832
	global_load_dwordx4 v[144:147], v150, s[86:87] offset:832
	s_add_u32 s86, s86, 0xc0000
	s_addc_u32 s87, s87, 0
	ds_read_b64_tr_b16 v[72:73], v231
	ds_read_b64_tr_b16 v[74:75], v231 offset:512
	ds_read_b64_tr_b16 v[76:77], v231 offset:2048
	ds_read_b64_tr_b16 v[78:79], v231 offset:2560
	ds_read_b64_tr_b16 v[220:221], v231 offset:1024
	ds_read_b64_tr_b16 v[222:223], v231 offset:1536
	ds_read_b64_tr_b16 v[224:225], v231 offset:3072
	ds_read_b64_tr_b16 v[226:227], v231 offset:3584
	v_exp_f32_e32 v32, v32
	v_exp_f32_e32 v33, v33
	v_exp_f32_e32 v34, v34
	v_exp_f32_e32 v35, v35
	s_waitcnt vmcnt(8)
	ds_write_b128 v247, v[156:159]
	ds_write_b128 v247, v[160:163] offset:1024
	ds_write_b128 v247, v[164:167] offset:2048
	ds_write_b128 v247, v[168:171] offset:3072
	ds_read_b128 v[156:159], v248
	ds_read_b128 v[160:163], v249
	ds_read_b128 v[164:167], v250
	ds_read_b128 v[168:171], v251
	ds_write_b128 v112, v[172:175]
	ds_write_b128 v112, v[176:179] offset:1024
	ds_write_b128 v112, v[180:183] offset:2048
	ds_write_b128 v112, v[184:187] offset:3072
	v_mfma_f32_32x32x16_bf16 v[0:15], v[64:67], v[204:207], v[0:15]
	v_mfma_f32_32x32x16_bf16 v[16:31], v[64:67], v[208:211], v[16:31]
	v_mfma_f32_32x32x16_bf16 v[0:15], v[68:71], v[212:215], v[0:15]
	v_mfma_f32_32x32x16_bf16 v[16:31], v[68:71], v[216:219], v[16:31]
	v_exp_f32_e32 v36, v36
	v_exp_f32_e32 v37, v37
	v_exp_f32_e32 v38, v38
	v_exp_f32_e32 v39, v39
	s_waitcnt lgkmcnt(4)
	v_mfma_f32_32x32x16_bf16 v[188:203], v[156:159], v[48:51], v[188:203]
	v_exp_f32_e32 v40, v40
	v_exp_f32_e32 v41, v41
	v_mfma_f32_32x32x16_bf16 v[188:203], v[160:163], v[52:55], v[188:203]
	v_exp_f32_e32 v42, v42
	v_exp_f32_e32 v43, v43
	v_mfma_f32_32x32x16_bf16 v[188:203], v[164:167], v[56:59], v[188:203]
	v_exp_f32_e32 v44, v44
	v_exp_f32_e32 v45, v45
	v_mfma_f32_32x32x16_bf16 v[188:203], v[168:171], v[60:63], v[188:203]
	v_exp_f32_e32 v46, v46
	v_exp_f32_e32 v47, v47
	v_cvt_pk_bf16_f32 v64, v32, v33
	v_cvt_pk_bf16_f32 v65, v34, v35
	v_cvt_pk_bf16_f32 v66, v36, v37
	v_cvt_pk_bf16_f32 v67, v38, v39
	v_cvt_pk_bf16_f32 v68, v40, v41
	v_cvt_pk_bf16_f32 v69, v42, v43
	v_cvt_pk_bf16_f32 v70, v44, v45
	v_cvt_pk_bf16_f32 v71, v46, v47
	v_pk_add_f32 v[232:233], v[232:233], v[32:33]
	v_pk_add_f32 v[232:233], v[232:233], v[34:35]
	v_pk_add_f32 v[232:233], v[232:233], v[36:37]
	v_pk_add_f32 v[232:233], v[232:233], v[38:39]
	v_pk_add_f32 v[232:233], v[232:233], v[40:41]
	v_pk_add_f32 v[232:233], v[232:233], v[42:43]
	v_pk_add_f32 v[232:233], v[232:233], v[44:45]
	v_pk_add_f32 v[232:233], v[232:233], v[46:47]
	v_mov_b32_e32 v115, v229
	ds_read2_b32 v[32:33], v115 offset0:0 offset1:1
	ds_read2_b32 v[34:35], v115 offset0:2 offset1:3
	ds_read2_b32 v[36:37], v115 offset0:8 offset1:9
	ds_read2_b32 v[38:39], v115 offset0:10 offset1:11
	ds_read2_b32 v[40:41], v115 offset0:16 offset1:17
	ds_read2_b32 v[42:43], v115 offset0:18 offset1:19
	ds_read2_b32 v[44:45], v115 offset0:24 offset1:25
	ds_read2_b32 v[46:47], v115 offset0:26 offset1:27
	global_load_dwordx4 v[156:159], v239, s[86:87]
	global_load_dwordx4 v[160:163], v240, s[86:87]
	global_load_dwordx4 v[164:167], v241, s[86:87]
	global_load_dwordx4 v[168:171], v242, s[86:87]
	global_load_dwordx4 v[172:175], v101, s[86:87] offset:768
	global_load_dwordx4 v[176:179], v150, s[86:87] offset:768
	global_load_dwordx4 v[180:183], v101, s[86:87] offset:832
	global_load_dwordx4 v[184:187], v150, s[86:87] offset:832
	s_add_u32 s86, s86, 0xc0000
	s_addc_u32 s87, s87, 0
	ds_read_b64_tr_b16 v[204:205], v231
	ds_read_b64_tr_b16 v[206:207], v231 offset:512
	ds_read_b64_tr_b16 v[208:209], v231 offset:2048
	ds_read_b64_tr_b16 v[210:211], v231 offset:2560
	ds_read_b64_tr_b16 v[212:213], v231 offset:1024
	ds_read_b64_tr_b16 v[214:215], v231 offset:1536
	ds_read_b64_tr_b16 v[216:217], v231 offset:3072
	ds_read_b64_tr_b16 v[218:219], v231 offset:3584
	v_exp_f32_e32 v188, v188
	v_exp_f32_e32 v189, v189
	v_exp_f32_e32 v190, v190
	v_exp_f32_e32 v191, v191
	s_waitcnt vmcnt(8)
	ds_write_b128 v247, v[116:119]
	ds_write_b128 v247, v[120:123] offset:1024
	ds_write_b128 v247, v[124:127] offset:2048
	ds_write_b128 v247, v[128:131] offset:3072
	ds_read_b128 v[116:119], v248
	ds_read_b128 v[120:123], v249
	ds_read_b128 v[124:127], v250
	ds_read_b128 v[128:131], v251
	ds_write_b128 v112, v[132:135]
	ds_write_b128 v112, v[136:139] offset:1024
	ds_write_b128 v112, v[140:143] offset:2048
	ds_write_b128 v112, v[144:147] offset:3072
	v_mfma_f32_32x32x16_bf16 v[0:15], v[64:67], v[72:75], v[0:15]
	v_mfma_f32_32x32x16_bf16 v[16:31], v[64:67], v[76:79], v[16:31]
	v_mfma_f32_32x32x16_bf16 v[0:15], v[68:71], v[220:223], v[0:15]
	v_mfma_f32_32x32x16_bf16 v[16:31], v[68:71], v[224:227], v[16:31]
	v_exp_f32_e32 v192, v192
	v_exp_f32_e32 v193, v193
	v_exp_f32_e32 v194, v194
	v_exp_f32_e32 v195, v195
	s_waitcnt lgkmcnt(4)
	v_mfma_f32_32x32x16_bf16 v[32:47], v[116:119], v[48:51], v[32:47]
	v_exp_f32_e32 v196, v196
	v_exp_f32_e32 v197, v197
	v_mfma_f32_32x32x16_bf16 v[32:47], v[120:123], v[52:55], v[32:47]
	v_exp_f32_e32 v198, v198
	v_exp_f32_e32 v199, v199
	v_mfma_f32_32x32x16_bf16 v[32:47], v[124:127], v[56:59], v[32:47]
	v_exp_f32_e32 v200, v200
	v_exp_f32_e32 v201, v201
	v_mfma_f32_32x32x16_bf16 v[32:47], v[128:131], v[60:63], v[32:47]
	v_exp_f32_e32 v202, v202
	v_exp_f32_e32 v203, v203
	v_cvt_pk_bf16_f32 v64, v188, v189
	v_cvt_pk_bf16_f32 v65, v190, v191
	v_cvt_pk_bf16_f32 v66, v192, v193
	v_cvt_pk_bf16_f32 v67, v194, v195
	v_cvt_pk_bf16_f32 v68, v196, v197
	v_cvt_pk_bf16_f32 v69, v198, v199
	v_cvt_pk_bf16_f32 v70, v200, v201
	v_cvt_pk_bf16_f32 v71, v202, v203
	v_pk_add_f32 v[232:233], v[232:233], v[188:189]
	v_pk_add_f32 v[232:233], v[232:233], v[190:191]
	v_pk_add_f32 v[232:233], v[232:233], v[192:193]
	v_pk_add_f32 v[232:233], v[232:233], v[194:195]
	v_pk_add_f32 v[232:233], v[232:233], v[196:197]
	v_pk_add_f32 v[232:233], v[232:233], v[198:199]
	v_pk_add_f32 v[232:233], v[232:233], v[200:201]
	v_pk_add_f32 v[232:233], v[232:233], v[202:203]
	ds_read2_b32 v[188:189], v115 offset0:32 offset1:33
	ds_read2_b32 v[190:191], v115 offset0:34 offset1:35
	ds_read2_b32 v[192:193], v115 offset0:40 offset1:41
	ds_read2_b32 v[194:195], v115 offset0:42 offset1:43
	ds_read2_b32 v[196:197], v115 offset0:48 offset1:49
	ds_read2_b32 v[198:199], v115 offset0:50 offset1:51
	ds_read2_b32 v[200:201], v115 offset0:56 offset1:57
	ds_read2_b32 v[202:203], v115 offset0:58 offset1:59
	global_load_dwordx4 v[116:119], v239, s[86:87]
	global_load_dwordx4 v[120:123], v240, s[86:87]
	global_load_dwordx4 v[124:127], v241, s[86:87]
	global_load_dwordx4 v[128:131], v242, s[86:87]
	global_load_dwordx4 v[132:135], v101, s[86:87] offset:768
	global_load_dwordx4 v[136:139], v150, s[86:87] offset:768
	global_load_dwordx4 v[140:143], v101, s[86:87] offset:832
	global_load_dwordx4 v[144:147], v150, s[86:87] offset:832
	s_add_u32 s86, s86, 0xc0000
	s_addc_u32 s87, s87, 0
	ds_read_b64_tr_b16 v[72:73], v231
	ds_read_b64_tr_b16 v[74:75], v231 offset:512
	ds_read_b64_tr_b16 v[76:77], v231 offset:2048
	ds_read_b64_tr_b16 v[78:79], v231 offset:2560
	ds_read_b64_tr_b16 v[220:221], v231 offset:1024
	ds_read_b64_tr_b16 v[222:223], v231 offset:1536
	ds_read_b64_tr_b16 v[224:225], v231 offset:3072
	ds_read_b64_tr_b16 v[226:227], v231 offset:3584
	v_exp_f32_e32 v32, v32
	v_exp_f32_e32 v33, v33
	v_exp_f32_e32 v34, v34
	v_exp_f32_e32 v35, v35
	s_waitcnt vmcnt(8)
	ds_write_b128 v247, v[156:159]
	ds_write_b128 v247, v[160:163] offset:1024
	ds_write_b128 v247, v[164:167] offset:2048
	ds_write_b128 v247, v[168:171] offset:3072
	ds_read_b128 v[156:159], v248
	ds_read_b128 v[160:163], v249
	ds_read_b128 v[164:167], v250
	ds_read_b128 v[168:171], v251
	ds_write_b128 v112, v[172:175]
	ds_write_b128 v112, v[176:179] offset:1024
	ds_write_b128 v112, v[180:183] offset:2048
	ds_write_b128 v112, v[184:187] offset:3072
	v_mfma_f32_32x32x16_bf16 v[0:15], v[64:67], v[204:207], v[0:15]
	v_mfma_f32_32x32x16_bf16 v[16:31], v[64:67], v[208:211], v[16:31]
	v_mfma_f32_32x32x16_bf16 v[0:15], v[68:71], v[212:215], v[0:15]
	v_mfma_f32_32x32x16_bf16 v[16:31], v[68:71], v[216:219], v[16:31]
	v_exp_f32_e32 v36, v36
	v_exp_f32_e32 v37, v37
	v_exp_f32_e32 v38, v38
	v_exp_f32_e32 v39, v39
	s_waitcnt lgkmcnt(4)
	v_mfma_f32_32x32x16_bf16 v[188:203], v[156:159], v[48:51], v[188:203]
	v_exp_f32_e32 v40, v40
	v_exp_f32_e32 v41, v41
	v_mfma_f32_32x32x16_bf16 v[188:203], v[160:163], v[52:55], v[188:203]
	v_exp_f32_e32 v42, v42
	v_exp_f32_e32 v43, v43
	v_mfma_f32_32x32x16_bf16 v[188:203], v[164:167], v[56:59], v[188:203]
	v_exp_f32_e32 v44, v44
	v_exp_f32_e32 v45, v45
	v_mfma_f32_32x32x16_bf16 v[188:203], v[168:171], v[60:63], v[188:203]
	v_exp_f32_e32 v46, v46
	v_exp_f32_e32 v47, v47
	v_cvt_pk_bf16_f32 v64, v32, v33
	v_cvt_pk_bf16_f32 v65, v34, v35
	v_cvt_pk_bf16_f32 v66, v36, v37
	v_cvt_pk_bf16_f32 v67, v38, v39
	v_cvt_pk_bf16_f32 v68, v40, v41
	v_cvt_pk_bf16_f32 v69, v42, v43
	v_cvt_pk_bf16_f32 v70, v44, v45
	v_cvt_pk_bf16_f32 v71, v46, v47
	v_pk_add_f32 v[232:233], v[232:233], v[32:33]
	v_pk_add_f32 v[232:233], v[232:233], v[34:35]
	v_pk_add_f32 v[232:233], v[232:233], v[36:37]
	v_pk_add_f32 v[232:233], v[232:233], v[38:39]
	v_pk_add_f32 v[232:233], v[232:233], v[40:41]
	v_pk_add_f32 v[232:233], v[232:233], v[42:43]
	v_pk_add_f32 v[232:233], v[232:233], v[44:45]
	v_pk_add_f32 v[232:233], v[232:233], v[46:47]
	ds_read2_b32 v[32:33], v115 offset0:64 offset1:65
	ds_read2_b32 v[34:35], v115 offset0:66 offset1:67
	ds_read2_b32 v[36:37], v115 offset0:72 offset1:73
	ds_read2_b32 v[38:39], v115 offset0:74 offset1:75
	ds_read2_b32 v[40:41], v115 offset0:80 offset1:81
	ds_read2_b32 v[42:43], v115 offset0:82 offset1:83
	ds_read2_b32 v[44:45], v115 offset0:88 offset1:89
	ds_read2_b32 v[46:47], v115 offset0:90 offset1:91
	global_load_dwordx4 v[156:159], v239, s[86:87]
	global_load_dwordx4 v[160:163], v240, s[86:87]
	global_load_dwordx4 v[164:167], v241, s[86:87]
	global_load_dwordx4 v[168:171], v242, s[86:87]
	global_load_dwordx4 v[172:175], v101, s[86:87] offset:768
	global_load_dwordx4 v[176:179], v150, s[86:87] offset:768
	global_load_dwordx4 v[180:183], v101, s[86:87] offset:832
	global_load_dwordx4 v[184:187], v150, s[86:87] offset:832
	s_add_u32 s86, s86, 0xc0000
	s_addc_u32 s87, s87, 0
	ds_read_b64_tr_b16 v[204:205], v231
	ds_read_b64_tr_b16 v[206:207], v231 offset:512
	ds_read_b64_tr_b16 v[208:209], v231 offset:2048
	ds_read_b64_tr_b16 v[210:211], v231 offset:2560
	ds_read_b64_tr_b16 v[212:213], v231 offset:1024
	ds_read_b64_tr_b16 v[214:215], v231 offset:1536
	ds_read_b64_tr_b16 v[216:217], v231 offset:3072
	ds_read_b64_tr_b16 v[218:219], v231 offset:3584
	v_exp_f32_e32 v188, v188
	v_exp_f32_e32 v189, v189
	v_exp_f32_e32 v190, v190
	v_exp_f32_e32 v191, v191
	s_waitcnt vmcnt(8)
	ds_write_b128 v247, v[116:119]
	ds_write_b128 v247, v[120:123] offset:1024
	ds_write_b128 v247, v[124:127] offset:2048
	ds_write_b128 v247, v[128:131] offset:3072
	ds_read_b128 v[116:119], v248
	ds_read_b128 v[120:123], v249
	ds_read_b128 v[124:127], v250
	ds_read_b128 v[128:131], v251
	ds_write_b128 v112, v[132:135]
	ds_write_b128 v112, v[136:139] offset:1024
	ds_write_b128 v112, v[140:143] offset:2048
	ds_write_b128 v112, v[144:147] offset:3072
	v_mfma_f32_32x32x16_bf16 v[0:15], v[64:67], v[72:75], v[0:15]
	v_mfma_f32_32x32x16_bf16 v[16:31], v[64:67], v[76:79], v[16:31]
	v_mfma_f32_32x32x16_bf16 v[0:15], v[68:71], v[220:223], v[0:15]
	v_mfma_f32_32x32x16_bf16 v[16:31], v[68:71], v[224:227], v[16:31]
	v_exp_f32_e32 v192, v192
	v_exp_f32_e32 v193, v193
	v_exp_f32_e32 v194, v194
	v_exp_f32_e32 v195, v195
	s_waitcnt lgkmcnt(4)
	v_mfma_f32_32x32x16_bf16 v[32:47], v[116:119], v[48:51], v[32:47]
	v_exp_f32_e32 v196, v196
	v_exp_f32_e32 v197, v197
	v_mfma_f32_32x32x16_bf16 v[32:47], v[120:123], v[52:55], v[32:47]
	v_exp_f32_e32 v198, v198
	v_exp_f32_e32 v199, v199
	v_mfma_f32_32x32x16_bf16 v[32:47], v[124:127], v[56:59], v[32:47]
	v_exp_f32_e32 v200, v200
	v_exp_f32_e32 v201, v201
	v_mfma_f32_32x32x16_bf16 v[32:47], v[128:131], v[60:63], v[32:47]
	v_exp_f32_e32 v202, v202
	v_exp_f32_e32 v203, v203
	v_cvt_pk_bf16_f32 v64, v188, v189
	v_cvt_pk_bf16_f32 v65, v190, v191
	v_cvt_pk_bf16_f32 v66, v192, v193
	v_cvt_pk_bf16_f32 v67, v194, v195
	v_cvt_pk_bf16_f32 v68, v196, v197
	v_cvt_pk_bf16_f32 v69, v198, v199
	v_cvt_pk_bf16_f32 v70, v200, v201
	v_cvt_pk_bf16_f32 v71, v202, v203
	v_pk_add_f32 v[232:233], v[232:233], v[188:189]
	v_pk_add_f32 v[232:233], v[232:233], v[190:191]
	v_pk_add_f32 v[232:233], v[232:233], v[192:193]
	v_pk_add_f32 v[232:233], v[232:233], v[194:195]
	v_pk_add_f32 v[232:233], v[232:233], v[196:197]
	v_pk_add_f32 v[232:233], v[232:233], v[198:199]
	v_pk_add_f32 v[232:233], v[232:233], v[200:201]
	v_pk_add_f32 v[232:233], v[232:233], v[202:203]
	ds_read2_b32 v[188:189], v115 offset0:96 offset1:97
	ds_read2_b32 v[190:191], v115 offset0:98 offset1:99
	ds_read2_b32 v[192:193], v115 offset0:104 offset1:105
	ds_read2_b32 v[194:195], v115 offset0:106 offset1:107
	ds_read2_b32 v[196:197], v115 offset0:112 offset1:113
	ds_read2_b32 v[198:199], v115 offset0:114 offset1:115
	ds_read2_b32 v[200:201], v115 offset0:120 offset1:121
	ds_read2_b32 v[202:203], v115 offset0:122 offset1:123
	global_load_dwordx4 v[116:119], v239, s[86:87]
	global_load_dwordx4 v[120:123], v240, s[86:87]
	global_load_dwordx4 v[124:127], v241, s[86:87]
	global_load_dwordx4 v[128:131], v242, s[86:87]
	global_load_dwordx4 v[132:135], v101, s[86:87] offset:768
	global_load_dwordx4 v[136:139], v150, s[86:87] offset:768
	global_load_dwordx4 v[140:143], v101, s[86:87] offset:832
	global_load_dwordx4 v[144:147], v150, s[86:87] offset:832
	s_add_u32 s86, s86, 0xc0000
	s_addc_u32 s87, s87, 0
	ds_read_b64_tr_b16 v[72:73], v231
	ds_read_b64_tr_b16 v[74:75], v231 offset:512
	ds_read_b64_tr_b16 v[76:77], v231 offset:2048
	ds_read_b64_tr_b16 v[78:79], v231 offset:2560
	ds_read_b64_tr_b16 v[220:221], v231 offset:1024
	ds_read_b64_tr_b16 v[222:223], v231 offset:1536
	ds_read_b64_tr_b16 v[224:225], v231 offset:3072
	ds_read_b64_tr_b16 v[226:227], v231 offset:3584
	v_exp_f32_e32 v32, v32
	v_exp_f32_e32 v33, v33
	v_exp_f32_e32 v34, v34
	v_exp_f32_e32 v35, v35
	s_waitcnt vmcnt(8)
	ds_write_b128 v247, v[156:159]
	ds_write_b128 v247, v[160:163] offset:1024
	ds_write_b128 v247, v[164:167] offset:2048
	ds_write_b128 v247, v[168:171] offset:3072
	ds_read_b128 v[156:159], v248
	ds_read_b128 v[160:163], v249
	ds_read_b128 v[164:167], v250
	ds_read_b128 v[168:171], v251
	ds_write_b128 v112, v[172:175]
	ds_write_b128 v112, v[176:179] offset:1024
	ds_write_b128 v112, v[180:183] offset:2048
	ds_write_b128 v112, v[184:187] offset:3072
	v_mfma_f32_32x32x16_bf16 v[0:15], v[64:67], v[204:207], v[0:15]
	v_mfma_f32_32x32x16_bf16 v[16:31], v[64:67], v[208:211], v[16:31]
	v_mfma_f32_32x32x16_bf16 v[0:15], v[68:71], v[212:215], v[0:15]
	v_mfma_f32_32x32x16_bf16 v[16:31], v[68:71], v[216:219], v[16:31]
	v_exp_f32_e32 v36, v36
	v_exp_f32_e32 v37, v37
	v_exp_f32_e32 v38, v38
	v_exp_f32_e32 v39, v39
	s_waitcnt lgkmcnt(4)
	v_mfma_f32_32x32x16_bf16 v[188:203], v[156:159], v[48:51], v[188:203]
	v_exp_f32_e32 v40, v40
	v_exp_f32_e32 v41, v41
	v_mfma_f32_32x32x16_bf16 v[188:203], v[160:163], v[52:55], v[188:203]
	v_exp_f32_e32 v42, v42
	v_exp_f32_e32 v43, v43
	v_mfma_f32_32x32x16_bf16 v[188:203], v[164:167], v[56:59], v[188:203]
	v_exp_f32_e32 v44, v44
	v_exp_f32_e32 v45, v45
	v_mfma_f32_32x32x16_bf16 v[188:203], v[168:171], v[60:63], v[188:203]
	v_exp_f32_e32 v46, v46
	v_exp_f32_e32 v47, v47
	v_cvt_pk_bf16_f32 v64, v32, v33
	v_cvt_pk_bf16_f32 v65, v34, v35
	v_cvt_pk_bf16_f32 v66, v36, v37
	v_cvt_pk_bf16_f32 v67, v38, v39
	v_cvt_pk_bf16_f32 v68, v40, v41
	v_cvt_pk_bf16_f32 v69, v42, v43
	v_cvt_pk_bf16_f32 v70, v44, v45
	v_cvt_pk_bf16_f32 v71, v46, v47
	v_pk_add_f32 v[232:233], v[232:233], v[32:33]
	v_pk_add_f32 v[232:233], v[232:233], v[34:35]
	v_pk_add_f32 v[232:233], v[232:233], v[36:37]
	v_pk_add_f32 v[232:233], v[232:233], v[38:39]
	v_pk_add_f32 v[232:233], v[232:233], v[40:41]
	v_pk_add_f32 v[232:233], v[232:233], v[42:43]
	v_pk_add_f32 v[232:233], v[232:233], v[44:45]
	v_pk_add_f32 v[232:233], v[232:233], v[46:47]
	ds_read2_b32 v[32:33], v115 offset0:128 offset1:129
	ds_read2_b32 v[34:35], v115 offset0:130 offset1:131
	ds_read2_b32 v[36:37], v115 offset0:136 offset1:137
	ds_read2_b32 v[38:39], v115 offset0:138 offset1:139
	ds_read2_b32 v[40:41], v115 offset0:144 offset1:145
	ds_read2_b32 v[42:43], v115 offset0:146 offset1:147
	ds_read2_b32 v[44:45], v115 offset0:152 offset1:153
	ds_read2_b32 v[46:47], v115 offset0:154 offset1:155
	global_load_dwordx4 v[156:159], v239, s[86:87]
	global_load_dwordx4 v[160:163], v240, s[86:87]
	global_load_dwordx4 v[164:167], v241, s[86:87]
	global_load_dwordx4 v[168:171], v242, s[86:87]
	global_load_dwordx4 v[172:175], v101, s[86:87] offset:768
	global_load_dwordx4 v[176:179], v150, s[86:87] offset:768
	global_load_dwordx4 v[180:183], v101, s[86:87] offset:832
	global_load_dwordx4 v[184:187], v150, s[86:87] offset:832
	s_add_u32 s86, s86, 0xc0000
	s_addc_u32 s87, s87, 0
	ds_read_b64_tr_b16 v[204:205], v231
	ds_read_b64_tr_b16 v[206:207], v231 offset:512
	ds_read_b64_tr_b16 v[208:209], v231 offset:2048
	ds_read_b64_tr_b16 v[210:211], v231 offset:2560
	ds_read_b64_tr_b16 v[212:213], v231 offset:1024
	ds_read_b64_tr_b16 v[214:215], v231 offset:1536
	ds_read_b64_tr_b16 v[216:217], v231 offset:3072
	ds_read_b64_tr_b16 v[218:219], v231 offset:3584
	v_exp_f32_e32 v188, v188
	v_exp_f32_e32 v189, v189
	v_exp_f32_e32 v190, v190
	v_exp_f32_e32 v191, v191
	s_waitcnt vmcnt(8)
	ds_write_b128 v247, v[116:119]
	ds_write_b128 v247, v[120:123] offset:1024
	ds_write_b128 v247, v[124:127] offset:2048
	ds_write_b128 v247, v[128:131] offset:3072
	ds_read_b128 v[116:119], v248
	ds_read_b128 v[120:123], v249
	ds_read_b128 v[124:127], v250
	ds_read_b128 v[128:131], v251
	ds_write_b128 v112, v[132:135]
	ds_write_b128 v112, v[136:139] offset:1024
	ds_write_b128 v112, v[140:143] offset:2048
	ds_write_b128 v112, v[144:147] offset:3072
	v_mfma_f32_32x32x16_bf16 v[0:15], v[64:67], v[72:75], v[0:15]
	v_mfma_f32_32x32x16_bf16 v[16:31], v[64:67], v[76:79], v[16:31]
	v_mfma_f32_32x32x16_bf16 v[0:15], v[68:71], v[220:223], v[0:15]
	v_mfma_f32_32x32x16_bf16 v[16:31], v[68:71], v[224:227], v[16:31]
	v_exp_f32_e32 v192, v192
	v_exp_f32_e32 v193, v193
	v_exp_f32_e32 v194, v194
	v_exp_f32_e32 v195, v195
	s_waitcnt lgkmcnt(4)
	v_mfma_f32_32x32x16_bf16 v[32:47], v[116:119], v[48:51], v[32:47]
	v_exp_f32_e32 v196, v196
	v_exp_f32_e32 v197, v197
	v_mfma_f32_32x32x16_bf16 v[32:47], v[120:123], v[52:55], v[32:47]
	v_exp_f32_e32 v198, v198
	v_exp_f32_e32 v199, v199
	v_mfma_f32_32x32x16_bf16 v[32:47], v[124:127], v[56:59], v[32:47]
	v_exp_f32_e32 v200, v200
	v_exp_f32_e32 v201, v201
	v_mfma_f32_32x32x16_bf16 v[32:47], v[128:131], v[60:63], v[32:47]
	v_exp_f32_e32 v202, v202
	v_exp_f32_e32 v203, v203
	v_cvt_pk_bf16_f32 v64, v188, v189
	v_cvt_pk_bf16_f32 v65, v190, v191
	v_cvt_pk_bf16_f32 v66, v192, v193
	v_cvt_pk_bf16_f32 v67, v194, v195
	v_cvt_pk_bf16_f32 v68, v196, v197
	v_cvt_pk_bf16_f32 v69, v198, v199
	v_cvt_pk_bf16_f32 v70, v200, v201
	v_cvt_pk_bf16_f32 v71, v202, v203
	v_pk_add_f32 v[232:233], v[232:233], v[188:189]
	v_pk_add_f32 v[232:233], v[232:233], v[190:191]
	v_pk_add_f32 v[232:233], v[232:233], v[192:193]
	v_pk_add_f32 v[232:233], v[232:233], v[194:195]
	v_pk_add_f32 v[232:233], v[232:233], v[196:197]
	v_pk_add_f32 v[232:233], v[232:233], v[198:199]
	v_pk_add_f32 v[232:233], v[232:233], v[200:201]
	v_pk_add_f32 v[232:233], v[232:233], v[202:203]
	ds_read2_b32 v[188:189], v115 offset0:160 offset1:161
	ds_read2_b32 v[190:191], v115 offset0:162 offset1:163
	ds_read2_b32 v[192:193], v115 offset0:168 offset1:169
	ds_read2_b32 v[194:195], v115 offset0:170 offset1:171
	ds_read2_b32 v[196:197], v115 offset0:176 offset1:177
	ds_read2_b32 v[198:199], v115 offset0:178 offset1:179
	ds_read2_b32 v[200:201], v115 offset0:184 offset1:185
	ds_read2_b32 v[202:203], v115 offset0:186 offset1:187
	global_load_dwordx4 v[116:119], v239, s[86:87]
	global_load_dwordx4 v[120:123], v240, s[86:87]
	global_load_dwordx4 v[124:127], v241, s[86:87]
	global_load_dwordx4 v[128:131], v242, s[86:87]
	global_load_dwordx4 v[132:135], v101, s[86:87] offset:768
	global_load_dwordx4 v[136:139], v150, s[86:87] offset:768
	global_load_dwordx4 v[140:143], v101, s[86:87] offset:832
	global_load_dwordx4 v[144:147], v150, s[86:87] offset:832
	s_add_u32 s86, s86, 0xc0000
	s_addc_u32 s87, s87, 0
	ds_read_b64_tr_b16 v[72:73], v231
	ds_read_b64_tr_b16 v[74:75], v231 offset:512
	ds_read_b64_tr_b16 v[76:77], v231 offset:2048
	ds_read_b64_tr_b16 v[78:79], v231 offset:2560
	ds_read_b64_tr_b16 v[220:221], v231 offset:1024
	ds_read_b64_tr_b16 v[222:223], v231 offset:1536
	ds_read_b64_tr_b16 v[224:225], v231 offset:3072
	ds_read_b64_tr_b16 v[226:227], v231 offset:3584
	v_exp_f32_e32 v32, v32
	v_exp_f32_e32 v33, v33
	v_exp_f32_e32 v34, v34
	v_exp_f32_e32 v35, v35
	s_waitcnt vmcnt(8)
	ds_write_b128 v247, v[156:159]
	ds_write_b128 v247, v[160:163] offset:1024
	ds_write_b128 v247, v[164:167] offset:2048
	ds_write_b128 v247, v[168:171] offset:3072
	ds_read_b128 v[156:159], v248
	ds_read_b128 v[160:163], v249
	ds_read_b128 v[164:167], v250
	ds_read_b128 v[168:171], v251
	ds_write_b128 v112, v[172:175]
	ds_write_b128 v112, v[176:179] offset:1024
	ds_write_b128 v112, v[180:183] offset:2048
	ds_write_b128 v112, v[184:187] offset:3072
	v_mfma_f32_32x32x16_bf16 v[0:15], v[64:67], v[204:207], v[0:15]
	v_mfma_f32_32x32x16_bf16 v[16:31], v[64:67], v[208:211], v[16:31]
	v_mfma_f32_32x32x16_bf16 v[0:15], v[68:71], v[212:215], v[0:15]
	v_mfma_f32_32x32x16_bf16 v[16:31], v[68:71], v[216:219], v[16:31]
	v_exp_f32_e32 v36, v36
	v_exp_f32_e32 v37, v37
	v_exp_f32_e32 v38, v38
	v_exp_f32_e32 v39, v39
	s_waitcnt lgkmcnt(4)
	v_mfma_f32_32x32x16_bf16 v[188:203], v[156:159], v[48:51], v[188:203]
	v_exp_f32_e32 v40, v40
	v_exp_f32_e32 v41, v41
	v_mfma_f32_32x32x16_bf16 v[188:203], v[160:163], v[52:55], v[188:203]
	v_exp_f32_e32 v42, v42
	v_exp_f32_e32 v43, v43
	v_mfma_f32_32x32x16_bf16 v[188:203], v[164:167], v[56:59], v[188:203]
	v_exp_f32_e32 v44, v44
	v_exp_f32_e32 v45, v45
	v_mfma_f32_32x32x16_bf16 v[188:203], v[168:171], v[60:63], v[188:203]
	v_exp_f32_e32 v46, v46
	v_exp_f32_e32 v47, v47
	v_cvt_pk_bf16_f32 v64, v32, v33
	v_cvt_pk_bf16_f32 v65, v34, v35
	v_cvt_pk_bf16_f32 v66, v36, v37
	v_cvt_pk_bf16_f32 v67, v38, v39
	v_cvt_pk_bf16_f32 v68, v40, v41
	v_cvt_pk_bf16_f32 v69, v42, v43
	v_cvt_pk_bf16_f32 v70, v44, v45
	v_cvt_pk_bf16_f32 v71, v46, v47
	v_pk_add_f32 v[232:233], v[232:233], v[32:33]
	v_pk_add_f32 v[232:233], v[232:233], v[34:35]
	v_pk_add_f32 v[232:233], v[232:233], v[36:37]
	v_pk_add_f32 v[232:233], v[232:233], v[38:39]
	v_pk_add_f32 v[232:233], v[232:233], v[40:41]
	v_pk_add_f32 v[232:233], v[232:233], v[42:43]
	v_pk_add_f32 v[232:233], v[232:233], v[44:45]
	v_pk_add_f32 v[232:233], v[232:233], v[46:47]
	ds_read2_b32 v[32:33], v115 offset0:192 offset1:193
	ds_read2_b32 v[34:35], v115 offset0:194 offset1:195
	ds_read2_b32 v[36:37], v115 offset0:200 offset1:201
	ds_read2_b32 v[38:39], v115 offset0:202 offset1:203
	ds_read2_b32 v[40:41], v115 offset0:208 offset1:209
	ds_read2_b32 v[42:43], v115 offset0:210 offset1:211
	ds_read2_b32 v[44:45], v115 offset0:216 offset1:217
	ds_read2_b32 v[46:47], v115 offset0:218 offset1:219
	global_load_dwordx4 v[156:159], v239, s[86:87]
	global_load_dwordx4 v[160:163], v240, s[86:87]
	global_load_dwordx4 v[164:167], v241, s[86:87]
	global_load_dwordx4 v[168:171], v242, s[86:87]
	global_load_dwordx4 v[172:175], v101, s[86:87] offset:768
	global_load_dwordx4 v[176:179], v150, s[86:87] offset:768
	global_load_dwordx4 v[180:183], v101, s[86:87] offset:832
	global_load_dwordx4 v[184:187], v150, s[86:87] offset:832
	ds_read_b64_tr_b16 v[204:205], v231
	ds_read_b64_tr_b16 v[206:207], v231 offset:512
	ds_read_b64_tr_b16 v[208:209], v231 offset:2048
	ds_read_b64_tr_b16 v[210:211], v231 offset:2560
	ds_read_b64_tr_b16 v[212:213], v231 offset:1024
	ds_read_b64_tr_b16 v[214:215], v231 offset:1536
	ds_read_b64_tr_b16 v[216:217], v231 offset:3072
	ds_read_b64_tr_b16 v[218:219], v231 offset:3584
	v_exp_f32_e32 v188, v188
	v_exp_f32_e32 v189, v189
	v_exp_f32_e32 v190, v190
	v_exp_f32_e32 v191, v191
	s_waitcnt vmcnt(8)
	ds_write_b128 v247, v[116:119]
	ds_write_b128 v247, v[120:123] offset:1024
	ds_write_b128 v247, v[124:127] offset:2048
	ds_write_b128 v247, v[128:131] offset:3072
	ds_read_b128 v[116:119], v248
	ds_read_b128 v[120:123], v249
	ds_read_b128 v[124:127], v250
	ds_read_b128 v[128:131], v251
	ds_write_b128 v112, v[132:135]
	ds_write_b128 v112, v[136:139] offset:1024
	ds_write_b128 v112, v[140:143] offset:2048
	ds_write_b128 v112, v[144:147] offset:3072
	v_mfma_f32_32x32x16_bf16 v[0:15], v[64:67], v[72:75], v[0:15]
	v_mfma_f32_32x32x16_bf16 v[16:31], v[64:67], v[76:79], v[16:31]
	v_mfma_f32_32x32x16_bf16 v[0:15], v[68:71], v[220:223], v[0:15]
	v_mfma_f32_32x32x16_bf16 v[16:31], v[68:71], v[224:227], v[16:31]
	v_exp_f32_e32 v192, v192
	v_exp_f32_e32 v193, v193
	v_exp_f32_e32 v194, v194
	v_exp_f32_e32 v195, v195
	s_waitcnt lgkmcnt(4)
	v_mfma_f32_32x32x16_bf16 v[32:47], v[116:119], v[48:51], v[32:47]
	v_exp_f32_e32 v196, v196
	v_exp_f32_e32 v197, v197
	v_mfma_f32_32x32x16_bf16 v[32:47], v[120:123], v[52:55], v[32:47]
	v_exp_f32_e32 v198, v198
	v_exp_f32_e32 v199, v199
	v_mfma_f32_32x32x16_bf16 v[32:47], v[124:127], v[56:59], v[32:47]
	v_exp_f32_e32 v200, v200
	v_exp_f32_e32 v201, v201
	v_mfma_f32_32x32x16_bf16 v[32:47], v[128:131], v[60:63], v[32:47]
	v_exp_f32_e32 v202, v202
	v_exp_f32_e32 v203, v203
	v_cvt_pk_bf16_f32 v64, v188, v189
	v_cvt_pk_bf16_f32 v65, v190, v191
	v_cvt_pk_bf16_f32 v66, v192, v193
	v_cvt_pk_bf16_f32 v67, v194, v195
	v_cvt_pk_bf16_f32 v68, v196, v197
	v_cvt_pk_bf16_f32 v69, v198, v199
	v_cvt_pk_bf16_f32 v70, v200, v201
	v_cvt_pk_bf16_f32 v71, v202, v203
	v_pk_add_f32 v[232:233], v[232:233], v[188:189]
	v_pk_add_f32 v[232:233], v[232:233], v[190:191]
	v_pk_add_f32 v[232:233], v[232:233], v[192:193]
	v_pk_add_f32 v[232:233], v[232:233], v[194:195]
	v_pk_add_f32 v[232:233], v[232:233], v[196:197]
	v_pk_add_f32 v[232:233], v[232:233], v[198:199]
	v_pk_add_f32 v[232:233], v[232:233], v[200:201]
	v_pk_add_f32 v[232:233], v[232:233], v[202:203]
	ds_read2_b32 v[188:189], v115 offset0:224 offset1:225
	ds_read2_b32 v[190:191], v115 offset0:226 offset1:227
	ds_read2_b32 v[192:193], v115 offset0:232 offset1:233
	ds_read2_b32 v[194:195], v115 offset0:234 offset1:235
	ds_read2_b32 v[196:197], v115 offset0:240 offset1:241
	ds_read2_b32 v[198:199], v115 offset0:242 offset1:243
	ds_read2_b32 v[200:201], v115 offset0:248 offset1:249
	ds_read2_b32 v[202:203], v115 offset0:250 offset1:251
	global_load_dwordx4 v[116:119], v243, s[88:89]
	global_load_dwordx4 v[120:123], v244, s[88:89]
	global_load_dwordx4 v[124:127], v245, s[88:89]
	global_load_dwordx4 v[128:131], v246, s[88:89]
	global_load_dwordx4 v[132:135], v148, s[88:89] offset:768
	global_load_dwordx4 v[136:139], v151, s[88:89] offset:768
	global_load_dwordx4 v[140:143], v148, s[88:89] offset:832
	global_load_dwordx4 v[144:147], v151, s[88:89] offset:832
	s_add_u32 s88, s88, 0x300000
	s_addc_u32 s89, s89, 0
	ds_read_b64_tr_b16 v[72:73], v231
	ds_read_b64_tr_b16 v[74:75], v231 offset:512
	ds_read_b64_tr_b16 v[76:77], v231 offset:2048
	ds_read_b64_tr_b16 v[78:79], v231 offset:2560
	ds_read_b64_tr_b16 v[220:221], v231 offset:1024
	ds_read_b64_tr_b16 v[222:223], v231 offset:1536
	ds_read_b64_tr_b16 v[224:225], v231 offset:3072
	ds_read_b64_tr_b16 v[226:227], v231 offset:3584
	v_exp_f32_e32 v32, v32
	v_exp_f32_e32 v33, v33
	v_exp_f32_e32 v34, v34
	v_exp_f32_e32 v35, v35
	s_waitcnt vmcnt(8)
	ds_write_b128 v247, v[156:159]
	ds_write_b128 v247, v[160:163] offset:1024
	ds_write_b128 v247, v[164:167] offset:2048
	ds_write_b128 v247, v[168:171] offset:3072
	ds_read_b128 v[156:159], v248
	ds_read_b128 v[160:163], v249
	ds_read_b128 v[164:167], v250
	ds_read_b128 v[168:171], v251
	ds_write_b128 v112, v[172:175]
	ds_write_b128 v112, v[176:179] offset:1024
	ds_write_b128 v112, v[180:183] offset:2048
	ds_write_b128 v112, v[184:187] offset:3072
	v_mfma_f32_32x32x16_bf16 v[0:15], v[64:67], v[204:207], v[0:15]
	v_mfma_f32_32x32x16_bf16 v[16:31], v[64:67], v[208:211], v[16:31]
	v_mfma_f32_32x32x16_bf16 v[0:15], v[68:71], v[212:215], v[0:15]
	v_mfma_f32_32x32x16_bf16 v[16:31], v[68:71], v[216:219], v[16:31]
	v_exp_f32_e32 v36, v36
	v_exp_f32_e32 v37, v37
	v_exp_f32_e32 v38, v38
	v_exp_f32_e32 v39, v39
	s_waitcnt lgkmcnt(4)
	v_mfma_f32_32x32x16_bf16 v[188:203], v[156:159], v[48:51], v[188:203]
	v_exp_f32_e32 v40, v40
	v_exp_f32_e32 v41, v41
	v_mfma_f32_32x32x16_bf16 v[188:203], v[160:163], v[52:55], v[188:203]
	v_exp_f32_e32 v42, v42
	v_exp_f32_e32 v43, v43
	v_mfma_f32_32x32x16_bf16 v[188:203], v[164:167], v[56:59], v[188:203]
	v_exp_f32_e32 v44, v44
	v_exp_f32_e32 v45, v45
	v_mfma_f32_32x32x16_bf16 v[188:203], v[168:171], v[60:63], v[188:203]
	v_exp_f32_e32 v46, v46
	v_exp_f32_e32 v47, v47
	v_cvt_pk_bf16_f32 v64, v32, v33
	v_cvt_pk_bf16_f32 v65, v34, v35
	v_cvt_pk_bf16_f32 v66, v36, v37
	v_cvt_pk_bf16_f32 v67, v38, v39
	v_cvt_pk_bf16_f32 v68, v40, v41
	v_cvt_pk_bf16_f32 v69, v42, v43
	v_cvt_pk_bf16_f32 v70, v44, v45
	v_cvt_pk_bf16_f32 v71, v46, v47
	v_pk_add_f32 v[232:233], v[232:233], v[32:33]
	v_pk_add_f32 v[232:233], v[232:233], v[34:35]
	v_pk_add_f32 v[232:233], v[232:233], v[36:37]
	v_pk_add_f32 v[232:233], v[232:233], v[38:39]
	v_pk_add_f32 v[232:233], v[232:233], v[40:41]
	v_pk_add_f32 v[232:233], v[232:233], v[42:43]
	v_pk_add_f32 v[232:233], v[232:233], v[44:45]
	v_pk_add_f32 v[232:233], v[232:233], v[46:47]
	v_mov_b32_e32 v115, v230
	ds_read2_b32 v[32:33], v115 offset0:0 offset1:1
	ds_read2_b32 v[34:35], v115 offset0:2 offset1:3
	ds_read2_b32 v[36:37], v115 offset0:8 offset1:9
	ds_read2_b32 v[38:39], v115 offset0:10 offset1:11
	ds_read2_b32 v[40:41], v115 offset0:16 offset1:17
	ds_read2_b32 v[42:43], v115 offset0:18 offset1:19
	ds_read2_b32 v[44:45], v115 offset0:24 offset1:25
	ds_read2_b32 v[46:47], v115 offset0:26 offset1:27
	global_load_dwordx4 v[156:159], v243, s[88:89]
	global_load_dwordx4 v[160:163], v244, s[88:89]
	global_load_dwordx4 v[164:167], v245, s[88:89]
	global_load_dwordx4 v[168:171], v246, s[88:89]
	global_load_dwordx4 v[172:175], v148, s[88:89] offset:768
	global_load_dwordx4 v[176:179], v151, s[88:89] offset:768
	global_load_dwordx4 v[180:183], v148, s[88:89] offset:832
	global_load_dwordx4 v[184:187], v151, s[88:89] offset:832
	s_add_u32 s88, s88, 0x300000
	s_addc_u32 s89, s89, 0
	ds_read_b64_tr_b16 v[204:205], v231
	ds_read_b64_tr_b16 v[206:207], v231 offset:512
	ds_read_b64_tr_b16 v[208:209], v231 offset:2048
	ds_read_b64_tr_b16 v[210:211], v231 offset:2560
	ds_read_b64_tr_b16 v[212:213], v231 offset:1024
	ds_read_b64_tr_b16 v[214:215], v231 offset:1536
	ds_read_b64_tr_b16 v[216:217], v231 offset:3072
	ds_read_b64_tr_b16 v[218:219], v231 offset:3584
	v_exp_f32_e32 v188, v188
	v_exp_f32_e32 v189, v189
	v_exp_f32_e32 v190, v190
	v_exp_f32_e32 v191, v191
	s_waitcnt vmcnt(8)
	ds_write_b128 v247, v[116:119]
	ds_write_b128 v247, v[120:123] offset:1024
	ds_write_b128 v247, v[124:127] offset:2048
	ds_write_b128 v247, v[128:131] offset:3072
	ds_read_b128 v[116:119], v248
	ds_read_b128 v[120:123], v249
	ds_read_b128 v[124:127], v250
	ds_read_b128 v[128:131], v251
	ds_write_b128 v112, v[132:135]
	ds_write_b128 v112, v[136:139] offset:1024
	ds_write_b128 v112, v[140:143] offset:2048
	ds_write_b128 v112, v[144:147] offset:3072
	v_mfma_f32_32x32x16_bf16 v[0:15], v[64:67], v[72:75], v[0:15]
	v_mfma_f32_32x32x16_bf16 v[16:31], v[64:67], v[76:79], v[16:31]
	v_mfma_f32_32x32x16_bf16 v[0:15], v[68:71], v[220:223], v[0:15]
	v_mfma_f32_32x32x16_bf16 v[16:31], v[68:71], v[224:227], v[16:31]
	v_exp_f32_e32 v192, v192
	v_exp_f32_e32 v193, v193
	v_exp_f32_e32 v194, v194
	v_exp_f32_e32 v195, v195
	s_waitcnt lgkmcnt(4)
	v_mfma_f32_32x32x16_bf16 v[32:47], v[116:119], v[48:51], v[32:47]
	v_exp_f32_e32 v196, v196
	v_exp_f32_e32 v197, v197
	v_mfma_f32_32x32x16_bf16 v[32:47], v[120:123], v[52:55], v[32:47]
	v_exp_f32_e32 v198, v198
	v_exp_f32_e32 v199, v199
	v_mfma_f32_32x32x16_bf16 v[32:47], v[124:127], v[56:59], v[32:47]
	v_exp_f32_e32 v200, v200
	v_exp_f32_e32 v201, v201
	v_mfma_f32_32x32x16_bf16 v[32:47], v[128:131], v[60:63], v[32:47]
	v_exp_f32_e32 v202, v202
	v_exp_f32_e32 v203, v203
	v_cvt_pk_bf16_f32 v64, v188, v189
	v_cvt_pk_bf16_f32 v65, v190, v191
	v_cvt_pk_bf16_f32 v66, v192, v193
	v_cvt_pk_bf16_f32 v67, v194, v195
	v_cvt_pk_bf16_f32 v68, v196, v197
	v_cvt_pk_bf16_f32 v69, v198, v199
	v_cvt_pk_bf16_f32 v70, v200, v201
	v_cvt_pk_bf16_f32 v71, v202, v203
	v_pk_add_f32 v[232:233], v[232:233], v[188:189]
	v_pk_add_f32 v[232:233], v[232:233], v[190:191]
	v_pk_add_f32 v[232:233], v[232:233], v[192:193]
	v_pk_add_f32 v[232:233], v[232:233], v[194:195]
	v_pk_add_f32 v[232:233], v[232:233], v[196:197]
	v_pk_add_f32 v[232:233], v[232:233], v[198:199]
	v_pk_add_f32 v[232:233], v[232:233], v[200:201]
	v_pk_add_f32 v[232:233], v[232:233], v[202:203]
	ds_read2_b32 v[188:189], v115 offset0:32 offset1:33
	ds_read2_b32 v[190:191], v115 offset0:34 offset1:35
	ds_read2_b32 v[192:193], v115 offset0:40 offset1:41
	ds_read2_b32 v[194:195], v115 offset0:42 offset1:43
	ds_read2_b32 v[196:197], v115 offset0:48 offset1:49
	ds_read2_b32 v[198:199], v115 offset0:50 offset1:51
	ds_read2_b32 v[200:201], v115 offset0:56 offset1:57
	ds_read2_b32 v[202:203], v115 offset0:58 offset1:59
	global_load_dwordx4 v[116:119], v243, s[88:89]
	global_load_dwordx4 v[120:123], v244, s[88:89]
	global_load_dwordx4 v[124:127], v245, s[88:89]
	global_load_dwordx4 v[128:131], v246, s[88:89]
	global_load_dwordx4 v[132:135], v148, s[88:89] offset:768
	global_load_dwordx4 v[136:139], v151, s[88:89] offset:768
	global_load_dwordx4 v[140:143], v148, s[88:89] offset:832
	global_load_dwordx4 v[144:147], v151, s[88:89] offset:832
	s_add_u32 s88, s88, 0x300000
	s_addc_u32 s89, s89, 0
	ds_read_b64_tr_b16 v[72:73], v231
	ds_read_b64_tr_b16 v[74:75], v231 offset:512
	ds_read_b64_tr_b16 v[76:77], v231 offset:2048
	ds_read_b64_tr_b16 v[78:79], v231 offset:2560
	ds_read_b64_tr_b16 v[220:221], v231 offset:1024
	ds_read_b64_tr_b16 v[222:223], v231 offset:1536
	ds_read_b64_tr_b16 v[224:225], v231 offset:3072
	ds_read_b64_tr_b16 v[226:227], v231 offset:3584
	v_exp_f32_e32 v32, v32
	v_exp_f32_e32 v33, v33
	v_exp_f32_e32 v34, v34
	v_exp_f32_e32 v35, v35
	s_waitcnt vmcnt(8)
	ds_write_b128 v247, v[156:159]
	ds_write_b128 v247, v[160:163] offset:1024
	ds_write_b128 v247, v[164:167] offset:2048
	ds_write_b128 v247, v[168:171] offset:3072
	ds_read_b128 v[156:159], v248
	ds_read_b128 v[160:163], v249
	ds_read_b128 v[164:167], v250
	ds_read_b128 v[168:171], v251
	ds_write_b128 v112, v[172:175]
	ds_write_b128 v112, v[176:179] offset:1024
	ds_write_b128 v112, v[180:183] offset:2048
	ds_write_b128 v112, v[184:187] offset:3072
	v_mfma_f32_32x32x16_bf16 v[0:15], v[64:67], v[204:207], v[0:15]
	v_mfma_f32_32x32x16_bf16 v[16:31], v[64:67], v[208:211], v[16:31]
	v_mfma_f32_32x32x16_bf16 v[0:15], v[68:71], v[212:215], v[0:15]
	v_mfma_f32_32x32x16_bf16 v[16:31], v[68:71], v[216:219], v[16:31]
	v_exp_f32_e32 v36, v36
	v_exp_f32_e32 v37, v37
	v_exp_f32_e32 v38, v38
	v_exp_f32_e32 v39, v39
	s_waitcnt lgkmcnt(4)
	v_mfma_f32_32x32x16_bf16 v[188:203], v[156:159], v[48:51], v[188:203]
	v_exp_f32_e32 v40, v40
	v_exp_f32_e32 v41, v41
	v_mfma_f32_32x32x16_bf16 v[188:203], v[160:163], v[52:55], v[188:203]
	v_exp_f32_e32 v42, v42
	v_exp_f32_e32 v43, v43
	v_mfma_f32_32x32x16_bf16 v[188:203], v[164:167], v[56:59], v[188:203]
	v_exp_f32_e32 v44, v44
	v_exp_f32_e32 v45, v45
	v_mfma_f32_32x32x16_bf16 v[188:203], v[168:171], v[60:63], v[188:203]
	v_exp_f32_e32 v46, v46
	v_exp_f32_e32 v47, v47
	v_cvt_pk_bf16_f32 v64, v32, v33
	v_cvt_pk_bf16_f32 v65, v34, v35
	v_cvt_pk_bf16_f32 v66, v36, v37
	v_cvt_pk_bf16_f32 v67, v38, v39
	v_cvt_pk_bf16_f32 v68, v40, v41
	v_cvt_pk_bf16_f32 v69, v42, v43
	v_cvt_pk_bf16_f32 v70, v44, v45
	v_cvt_pk_bf16_f32 v71, v46, v47
	v_pk_add_f32 v[232:233], v[232:233], v[32:33]
	v_pk_add_f32 v[232:233], v[232:233], v[34:35]
	v_pk_add_f32 v[232:233], v[232:233], v[36:37]
	v_pk_add_f32 v[232:233], v[232:233], v[38:39]
	v_pk_add_f32 v[232:233], v[232:233], v[40:41]
	v_pk_add_f32 v[232:233], v[232:233], v[42:43]
	v_pk_add_f32 v[232:233], v[232:233], v[44:45]
	v_pk_add_f32 v[232:233], v[232:233], v[46:47]
	ds_read2_b32 v[32:33], v115 offset0:64 offset1:65
	ds_read2_b32 v[34:35], v115 offset0:66 offset1:67
	ds_read2_b32 v[36:37], v115 offset0:72 offset1:73
	ds_read2_b32 v[38:39], v115 offset0:74 offset1:75
	ds_read2_b32 v[40:41], v115 offset0:80 offset1:81
	ds_read2_b32 v[42:43], v115 offset0:82 offset1:83
	ds_read2_b32 v[44:45], v115 offset0:88 offset1:89
	ds_read2_b32 v[46:47], v115 offset0:90 offset1:91
	global_load_dwordx4 v[156:159], v243, s[88:89]
	global_load_dwordx4 v[160:163], v244, s[88:89]
	global_load_dwordx4 v[164:167], v245, s[88:89]
	global_load_dwordx4 v[168:171], v246, s[88:89]
	global_load_dwordx4 v[172:175], v148, s[88:89] offset:768
	global_load_dwordx4 v[176:179], v151, s[88:89] offset:768
	global_load_dwordx4 v[180:183], v148, s[88:89] offset:832
	global_load_dwordx4 v[184:187], v151, s[88:89] offset:832
	s_add_u32 s88, s88, 0x300000
	s_addc_u32 s89, s89, 0
	ds_read_b64_tr_b16 v[204:205], v231
	ds_read_b64_tr_b16 v[206:207], v231 offset:512
	ds_read_b64_tr_b16 v[208:209], v231 offset:2048
	ds_read_b64_tr_b16 v[210:211], v231 offset:2560
	ds_read_b64_tr_b16 v[212:213], v231 offset:1024
	ds_read_b64_tr_b16 v[214:215], v231 offset:1536
	ds_read_b64_tr_b16 v[216:217], v231 offset:3072
	ds_read_b64_tr_b16 v[218:219], v231 offset:3584
	v_exp_f32_e32 v188, v188
	v_exp_f32_e32 v189, v189
	v_exp_f32_e32 v190, v190
	v_exp_f32_e32 v191, v191
	s_waitcnt vmcnt(8)
	ds_write_b128 v247, v[116:119]
	ds_write_b128 v247, v[120:123] offset:1024
	ds_write_b128 v247, v[124:127] offset:2048
	ds_write_b128 v247, v[128:131] offset:3072
	ds_read_b128 v[116:119], v248
	ds_read_b128 v[120:123], v249
	ds_read_b128 v[124:127], v250
	ds_read_b128 v[128:131], v251
	ds_write_b128 v112, v[132:135]
	ds_write_b128 v112, v[136:139] offset:1024
	ds_write_b128 v112, v[140:143] offset:2048
	ds_write_b128 v112, v[144:147] offset:3072
	v_mfma_f32_32x32x16_bf16 v[0:15], v[64:67], v[72:75], v[0:15]
	v_mfma_f32_32x32x16_bf16 v[16:31], v[64:67], v[76:79], v[16:31]
	v_mfma_f32_32x32x16_bf16 v[0:15], v[68:71], v[220:223], v[0:15]
	v_mfma_f32_32x32x16_bf16 v[16:31], v[68:71], v[224:227], v[16:31]
	v_exp_f32_e32 v192, v192
	v_exp_f32_e32 v193, v193
	v_exp_f32_e32 v194, v194
	v_exp_f32_e32 v195, v195
	s_waitcnt lgkmcnt(4)
	v_mfma_f32_32x32x16_bf16 v[32:47], v[116:119], v[48:51], v[32:47]
	v_exp_f32_e32 v196, v196
	v_exp_f32_e32 v197, v197
	v_mfma_f32_32x32x16_bf16 v[32:47], v[120:123], v[52:55], v[32:47]
	v_exp_f32_e32 v198, v198
	v_exp_f32_e32 v199, v199
	v_mfma_f32_32x32x16_bf16 v[32:47], v[124:127], v[56:59], v[32:47]
	v_exp_f32_e32 v200, v200
	v_exp_f32_e32 v201, v201
	v_mfma_f32_32x32x16_bf16 v[32:47], v[128:131], v[60:63], v[32:47]
	v_exp_f32_e32 v202, v202
	v_exp_f32_e32 v203, v203
	v_cvt_pk_bf16_f32 v64, v188, v189
	v_cvt_pk_bf16_f32 v65, v190, v191
	v_cvt_pk_bf16_f32 v66, v192, v193
	v_cvt_pk_bf16_f32 v67, v194, v195
	v_cvt_pk_bf16_f32 v68, v196, v197
	v_cvt_pk_bf16_f32 v69, v198, v199
	v_cvt_pk_bf16_f32 v70, v200, v201
	v_cvt_pk_bf16_f32 v71, v202, v203
	v_pk_add_f32 v[232:233], v[232:233], v[188:189]
	v_pk_add_f32 v[232:233], v[232:233], v[190:191]
	v_pk_add_f32 v[232:233], v[232:233], v[192:193]
	v_pk_add_f32 v[232:233], v[232:233], v[194:195]
	v_pk_add_f32 v[232:233], v[232:233], v[196:197]
	v_pk_add_f32 v[232:233], v[232:233], v[198:199]
	v_pk_add_f32 v[232:233], v[232:233], v[200:201]
	v_pk_add_f32 v[232:233], v[232:233], v[202:203]
	ds_read2_b32 v[188:189], v115 offset0:96 offset1:97
	ds_read2_b32 v[190:191], v115 offset0:98 offset1:99
	ds_read2_b32 v[192:193], v115 offset0:104 offset1:105
	ds_read2_b32 v[194:195], v115 offset0:106 offset1:107
	ds_read2_b32 v[196:197], v115 offset0:112 offset1:113
	ds_read2_b32 v[198:199], v115 offset0:114 offset1:115
	ds_read2_b32 v[200:201], v115 offset0:120 offset1:121
	ds_read2_b32 v[202:203], v115 offset0:122 offset1:123
	global_load_dwordx4 v[116:119], v243, s[88:89]
	global_load_dwordx4 v[120:123], v244, s[88:89]
	global_load_dwordx4 v[124:127], v245, s[88:89]
	global_load_dwordx4 v[128:131], v246, s[88:89]
	global_load_dwordx4 v[132:135], v148, s[88:89] offset:768
	global_load_dwordx4 v[136:139], v151, s[88:89] offset:768
	global_load_dwordx4 v[140:143], v148, s[88:89] offset:832
	global_load_dwordx4 v[144:147], v151, s[88:89] offset:832
	ds_read_b64_tr_b16 v[72:73], v231
	ds_read_b64_tr_b16 v[74:75], v231 offset:512
	ds_read_b64_tr_b16 v[76:77], v231 offset:2048
	ds_read_b64_tr_b16 v[78:79], v231 offset:2560
	ds_read_b64_tr_b16 v[220:221], v231 offset:1024
	ds_read_b64_tr_b16 v[222:223], v231 offset:1536
	ds_read_b64_tr_b16 v[224:225], v231 offset:3072
	ds_read_b64_tr_b16 v[226:227], v231 offset:3584
	v_exp_f32_e32 v32, v32
	v_exp_f32_e32 v33, v33
	v_exp_f32_e32 v34, v34
	v_exp_f32_e32 v35, v35
	s_waitcnt vmcnt(8)
	ds_write_b128 v247, v[156:159]
	ds_write_b128 v247, v[160:163] offset:1024
	ds_write_b128 v247, v[164:167] offset:2048
	ds_write_b128 v247, v[168:171] offset:3072
	ds_read_b128 v[156:159], v248
	ds_read_b128 v[160:163], v249
	ds_read_b128 v[164:167], v250
	ds_read_b128 v[168:171], v251
	ds_write_b128 v112, v[172:175]
	ds_write_b128 v112, v[176:179] offset:1024
	ds_write_b128 v112, v[180:183] offset:2048
	ds_write_b128 v112, v[184:187] offset:3072
	v_mfma_f32_32x32x16_bf16 v[0:15], v[64:67], v[204:207], v[0:15]
	v_mfma_f32_32x32x16_bf16 v[16:31], v[64:67], v[208:211], v[16:31]
	v_mfma_f32_32x32x16_bf16 v[0:15], v[68:71], v[212:215], v[0:15]
	v_mfma_f32_32x32x16_bf16 v[16:31], v[68:71], v[216:219], v[16:31]
	v_exp_f32_e32 v36, v36
	v_exp_f32_e32 v37, v37
	v_exp_f32_e32 v38, v38
	v_exp_f32_e32 v39, v39
	s_waitcnt lgkmcnt(4)
	v_mfma_f32_32x32x16_bf16 v[188:203], v[156:159], v[48:51], v[188:203]
	v_exp_f32_e32 v40, v40
	v_exp_f32_e32 v41, v41
	v_mfma_f32_32x32x16_bf16 v[188:203], v[160:163], v[52:55], v[188:203]
	v_exp_f32_e32 v42, v42
	v_exp_f32_e32 v43, v43
	v_mfma_f32_32x32x16_bf16 v[188:203], v[164:167], v[56:59], v[188:203]
	v_exp_f32_e32 v44, v44
	v_exp_f32_e32 v45, v45
	v_mfma_f32_32x32x16_bf16 v[188:203], v[168:171], v[60:63], v[188:203]
	v_exp_f32_e32 v46, v46
	v_exp_f32_e32 v47, v47
	v_cvt_pk_bf16_f32 v64, v32, v33
	v_cvt_pk_bf16_f32 v65, v34, v35
	v_cvt_pk_bf16_f32 v66, v36, v37
	v_cvt_pk_bf16_f32 v67, v38, v39
	v_cvt_pk_bf16_f32 v68, v40, v41
	v_cvt_pk_bf16_f32 v69, v42, v43
	v_cvt_pk_bf16_f32 v70, v44, v45
	v_cvt_pk_bf16_f32 v71, v46, v47
	v_pk_add_f32 v[232:233], v[232:233], v[32:33]
	v_pk_add_f32 v[232:233], v[232:233], v[34:35]
	v_pk_add_f32 v[232:233], v[232:233], v[36:37]
	v_pk_add_f32 v[232:233], v[232:233], v[38:39]
	v_pk_add_f32 v[232:233], v[232:233], v[40:41]
	v_pk_add_f32 v[232:233], v[232:233], v[42:43]
	v_pk_add_f32 v[232:233], v[232:233], v[44:45]
	v_pk_add_f32 v[232:233], v[232:233], v[46:47]
	ds_read2_b32 v[32:33], v115 offset0:128 offset1:129
	ds_read2_b32 v[34:35], v115 offset0:130 offset1:131
	ds_read2_b32 v[36:37], v115 offset0:136 offset1:137
	ds_read2_b32 v[38:39], v115 offset0:138 offset1:139
	ds_read2_b32 v[40:41], v115 offset0:144 offset1:145
	ds_read2_b32 v[42:43], v115 offset0:146 offset1:147
	ds_read2_b32 v[44:45], v115 offset0:152 offset1:153
	ds_read2_b32 v[46:47], v115 offset0:154 offset1:155
	ds_read_b64_tr_b16 v[204:205], v231
	ds_read_b64_tr_b16 v[206:207], v231 offset:512
	ds_read_b64_tr_b16 v[208:209], v231 offset:2048
	ds_read_b64_tr_b16 v[210:211], v231 offset:2560
	ds_read_b64_tr_b16 v[212:213], v231 offset:1024
	ds_read_b64_tr_b16 v[214:215], v231 offset:1536
	ds_read_b64_tr_b16 v[216:217], v231 offset:3072
	ds_read_b64_tr_b16 v[218:219], v231 offset:3584
	v_exp_f32_e32 v188, v188
	v_exp_f32_e32 v189, v189
	v_exp_f32_e32 v190, v190
	v_exp_f32_e32 v191, v191
	s_waitcnt vmcnt(0)
; __device__ __forceinline__ int crow(int r, int hi) { return (r & 3) + 8 * (r >> 2) + 4 * hi; }
; __device__ __forceinline__ void dil_unit(LAS unsigned char* lds, bf16_t* proj, int seq, int hd, int T0, int rho) {
;     ...
;     l += __shfl_xor(l, 32);
; #pragma unroll
;     for (int rr = 0; rr < 16; ++rr) {
;         const int j = crow(rr, hi);
;         const float il = __builtin_amdgcn_rcpf(__shfl(l, j));
	ds_write_b128 v247, v[116:119]
	ds_write_b128 v247, v[120:123] offset:1024
	ds_write_b128 v247, v[124:127] offset:2048
	ds_write_b128 v247, v[128:131] offset:3072
	ds_read_b128 v[116:119], v248
	ds_read_b128 v[120:123], v249
	ds_read_b128 v[124:127], v250
	ds_read_b128 v[128:131], v251
	ds_write_b128 v112, v[132:135]
	ds_write_b128 v112, v[136:139] offset:1024
	ds_write_b128 v112, v[140:143] offset:2048
	ds_write_b128 v112, v[144:147] offset:3072
	v_mfma_f32_32x32x16_bf16 v[0:15], v[64:67], v[72:75], v[0:15]
	v_mfma_f32_32x32x16_bf16 v[16:31], v[64:67], v[76:79], v[16:31]
	v_mfma_f32_32x32x16_bf16 v[0:15], v[68:71], v[220:223], v[0:15]
	v_mfma_f32_32x32x16_bf16 v[16:31], v[68:71], v[224:227], v[16:31]
	v_exp_f32_e32 v192, v192
	v_exp_f32_e32 v193, v193
	v_exp_f32_e32 v194, v194
	v_exp_f32_e32 v195, v195
	s_waitcnt lgkmcnt(4)
	v_mfma_f32_32x32x16_bf16 v[32:47], v[116:119], v[48:51], v[32:47]
	v_exp_f32_e32 v196, v196
	v_exp_f32_e32 v197, v197
	v_mfma_f32_32x32x16_bf16 v[32:47], v[120:123], v[52:55], v[32:47]
	v_exp_f32_e32 v198, v198
	v_exp_f32_e32 v199, v199
	v_mfma_f32_32x32x16_bf16 v[32:47], v[124:127], v[56:59], v[32:47]
	v_exp_f32_e32 v200, v200
	v_exp_f32_e32 v201, v201
	v_mfma_f32_32x32x16_bf16 v[32:47], v[128:131], v[60:63], v[32:47]
	v_exp_f32_e32 v202, v202
	v_exp_f32_e32 v203, v203
	v_cvt_pk_bf16_f32 v64, v188, v189
	v_cvt_pk_bf16_f32 v65, v190, v191
	v_cvt_pk_bf16_f32 v66, v192, v193
	v_cvt_pk_bf16_f32 v67, v194, v195
	v_cvt_pk_bf16_f32 v68, v196, v197
	v_cvt_pk_bf16_f32 v69, v198, v199
	v_cvt_pk_bf16_f32 v70, v200, v201
	v_cvt_pk_bf16_f32 v71, v202, v203
	v_pk_add_f32 v[232:233], v[232:233], v[188:189]
	v_pk_add_f32 v[232:233], v[232:233], v[190:191]
	v_pk_add_f32 v[232:233], v[232:233], v[192:193]
	v_pk_add_f32 v[232:233], v[232:233], v[194:195]
	v_pk_add_f32 v[232:233], v[232:233], v[196:197]
	v_pk_add_f32 v[232:233], v[232:233], v[198:199]
	v_pk_add_f32 v[232:233], v[232:233], v[200:201]
	v_pk_add_f32 v[232:233], v[232:233], v[202:203]
	ds_read_b64_tr_b16 v[72:73], v231
	ds_read_b64_tr_b16 v[74:75], v231 offset:512
	ds_read_b64_tr_b16 v[76:77], v231 offset:2048
	ds_read_b64_tr_b16 v[78:79], v231 offset:2560
	ds_read_b64_tr_b16 v[220:221], v231 offset:1024
	ds_read_b64_tr_b16 v[222:223], v231 offset:1536
	ds_read_b64_tr_b16 v[224:225], v231 offset:3072
	ds_read_b64_tr_b16 v[226:227], v231 offset:3584
	s_waitcnt lgkmcnt(0)
	v_mfma_f32_32x32x16_bf16 v[0:15], v[64:67], v[204:207], v[0:15]
	v_mfma_f32_32x32x16_bf16 v[16:31], v[64:67], v[208:211], v[16:31]
	v_mfma_f32_32x32x16_bf16 v[0:15], v[68:71], v[212:215], v[0:15]
	v_mfma_f32_32x32x16_bf16 v[16:31], v[68:71], v[216:219], v[16:31]
	v_exp_f32_e32 v32, v32
	v_exp_f32_e32 v33, v33
	v_exp_f32_e32 v34, v34
	v_exp_f32_e32 v35, v35
	v_exp_f32_e32 v36, v36
	v_exp_f32_e32 v37, v37
	v_exp_f32_e32 v38, v38
	v_exp_f32_e32 v39, v39
	v_exp_f32_e32 v40, v40
	v_exp_f32_e32 v41, v41
	v_exp_f32_e32 v42, v42
	v_exp_f32_e32 v43, v43
	v_exp_f32_e32 v44, v44
	v_exp_f32_e32 v45, v45
	v_exp_f32_e32 v46, v46
	v_exp_f32_e32 v47, v47
	v_cvt_pk_bf16_f32 v64, v32, v33
	v_cvt_pk_bf16_f32 v65, v34, v35
	v_cvt_pk_bf16_f32 v66, v36, v37
	v_cvt_pk_bf16_f32 v67, v38, v39
	v_cvt_pk_bf16_f32 v68, v40, v41
	v_cvt_pk_bf16_f32 v69, v42, v43
	v_cvt_pk_bf16_f32 v70, v44, v45
	v_cvt_pk_bf16_f32 v71, v46, v47
	v_pk_add_f32 v[232:233], v[232:233], v[32:33]
	v_pk_add_f32 v[232:233], v[232:233], v[34:35]
	v_pk_add_f32 v[232:233], v[232:233], v[36:37]
	v_pk_add_f32 v[232:233], v[232:233], v[38:39]
	v_pk_add_f32 v[232:233], v[232:233], v[40:41]
	v_pk_add_f32 v[232:233], v[232:233], v[42:43]
	v_pk_add_f32 v[232:233], v[232:233], v[44:45]
	v_pk_add_f32 v[232:233], v[232:233], v[46:47]
	v_mfma_f32_32x32x16_bf16 v[0:15], v[64:67], v[72:75], v[0:15]
	v_mfma_f32_32x32x16_bf16 v[16:31], v[64:67], v[76:79], v[16:31]
	v_mfma_f32_32x32x16_bf16 v[0:15], v[68:71], v[220:223], v[0:15]
	v_mfma_f32_32x32x16_bf16 v[16:31], v[68:71], v[224:227], v[16:31]
	v_add_f32_e32 v113, v232, v233
	v_or_b32_e32 v114, 1, v107
	v_or_b32_e32 v97, 2, v107
	v_or_b32_e32 v96, 3, v107
	v_or_b32_e32 v95, 8, v107
	v_or_b32_e32 v94, 9, v107
	v_or_b32_e32 v93, 10, v107
	v_or_b32_e32 v92, 11, v107
	v_or_b32_e32 v91, 16, v107
	v_or_b32_e32 v90, 17, v107
	v_or_b32_e32 v89, 18, v107
	v_or_b32_e32 v88, 19, v107
	v_or_b32_e32 v87, 24, v107
	v_or_b32_e32 v86, 25, v107
	v_or_b32_e32 v85, 26, v107
	v_or_b32_e32 v84, 27, v107
	s_nop 11
	s_branch .LBB0_1265
; #define LAS __attribute__((address_space(3)))
; #define GAS __attribute__((address_space(1)))
; __device__ __forceinline__ void dil_unit(LAS unsigned char* lds, bf16_t* proj, int seq, int hd, int T0, int rho) {
;     ...
;     const int tid = tid_, lane = tid & 63, r32 = lane & 31, hi = lane >> 5, wid = __builtin_amdgcn_readfirstlane(tid >> 6);
;     bf16_t* base = proj + (size_t)seq * SEQ * NIN;
;     LAS unsigned char* wbuf = lds + wid * 4096;
;     const LAS unsigned char* vp = wbuf + ((lane >> 4) & 1) * 32 + (lane & 3) * 8 + (4 * hi + ((lane & 15) >> 2)) * 64;
;     const int P0 = T0 + rho;
;     bf16x8 qr[4];
; #pragma unroll
;     for (int ks = 0; ks < 4; ++ks) qr[ks] = *(const GAS bf16x8*)(base + (size_t)(P0 + 16 * r32) * NIN + PC_LQ + hd * 64 + 16 * ks + 8 * hi);
;     f32x16 o0 = {}, o1 = {}; float l = 0.f;
;     const bool bound = (T0 < 1024) || (T0 >= 15360);
.LBB0_1270:
	s_movk_i32 s100, 0x1800
	s_add_i32 s101, s8, 0x15c00
	s_lshl_b32 s90, s54, 1
	s_add_u32 s82, s52, s90
	s_addc_u32 s83, s53, 0
	s_add_u32 s82, s82, 0x1200
	s_addc_u32 s83, s83, 0
	s_sub_i32 s90, s67, 64
	s_mul_i32 s90, s90, 0x1800
	s_add_u32 s84, s82, s90
	s_addc_u32 s85, s83, 0
	s_sub_i32 s90, s67, 256
	s_mul_i32 s90, s90, 0x1800
	s_add_u32 s86, s82, s90
	s_addc_u32 s87, s83, 0
	s_sub_i32 s90, s67, 1024
	s_mul_i32 s90, s90, 0x1800
	s_add_u32 s88, s82, s90
	s_addc_u32 s89, s83, 0
	v_lshlrev_b32_e32 v153, 1, v98
	v_mad_u32_u24 v80, v105, s100, v82
	v_mad_u32_u24 v100, v110, s100, v153
	v_add_u32_e32 v149, 0x18000, v100
	v_lshlrev_b32_e32 v83, 2, v105
	v_mad_u32_u24 v83, v83, s100, v82
	v_lshlrev_b32_e32 v101, 2, v110
	v_mad_u32_u24 v101, v101, s100, v153
	v_add_u32_e32 v150, 0x60000, v101
	v_lshlrev_b32_e32 v99, 4, v105
	v_mad_u32_u24 v99, v99, s100, v82
	v_lshlrev_b32_e32 v148, 4, v110
	v_mad_u32_u24 v148, v148, s100, v153
	v_add_u32_e32 v151, 0x180000, v148
	v_lshrrev_b32_e32 v249, 3, v103
	v_and_b32_e32 v250, 7, v103
	v_lshlrev_b32_e32 v250, 4, v250
	v_add_u32_e32 v235, 0, v249
	v_add_u32_e32 v236, 8, v249
	v_add_u32_e32 v237, 16, v249
	v_add_u32_e32 v238, 24, v249
	v_add_u32_e32 v239, 0, v249
	v_lshlrev_b32_e32 v239, 2, v239
	v_add_u32_e32 v240, 8, v249
	v_lshlrev_b32_e32 v240, 2, v240
	v_add_u32_e32 v241, 16, v249
	v_lshlrev_b32_e32 v241, 2, v241
	v_add_u32_e32 v242, 24, v249
	v_lshlrev_b32_e32 v242, 2, v242
	v_add_u32_e32 v243, 0, v249
	v_lshlrev_b32_e32 v243, 4, v243
	v_add_u32_e32 v244, 8, v249
	v_lshlrev_b32_e32 v244, 4, v244
	v_add_u32_e32 v245, 16, v249
	v_lshlrev_b32_e32 v245, 4, v245
	v_add_u32_e32 v246, 24, v249
	v_lshlrev_b32_e32 v246, 4, v246
	v_mov_b32_e32 v252, v250
	v_mov_b32_e32 v100, v110
	v_add_u32_e32 v149, 16, v100
	v_lshlrev_b32_e32 v101, 2, v110
	v_add_u32_e32 v150, 64, v101
	v_lshlrev_b32_e32 v148, 4, v110
	v_add_u32_e32 v151, 256, v148
	s_mov_b32 s98, 0x4000
	s_mov_b32 s99, 0x3fff
	v_and_b32_e32 v247, 7, v249
	v_lshlrev_b32_e32 v247, 4, v247
	v_xor_b32_e32 v247, v247, v112
	v_and_b32_e32 v153, 7, v105
	v_or_b32_e32 v248, 0, v106
	v_xor_b32_e32 v248, v248, v153
	v_lshlrev_b32_e32 v248, 4, v248
	v_lshl_add_u32 v248, v105, 7, v248
	v_add_u32_e32 v248, s69, v248
	v_or_b32_e32 v249, 2, v106
	v_xor_b32_e32 v249, v249, v153
	v_lshlrev_b32_e32 v249, 4, v249
	v_lshl_add_u32 v249, v105, 7, v249
	v_add_u32_e32 v249, s69, v249
	v_or_b32_e32 v250, 4, v106
	v_xor_b32_e32 v250, v250, v153
	v_lshlrev_b32_e32 v250, 4, v250
	v_lshl_add_u32 v250, v105, 7, v250
	v_add_u32_e32 v250, s69, v250
	v_or_b32_e32 v251, 6, v106
	v_xor_b32_e32 v251, v251, v153
	v_lshlrev_b32_e32 v251, 4, v251
	v_lshl_add_u32 v251, v105, 7, v251
	v_add_u32_e32 v251, s69, v251
	v_lshlrev_b32_e32 v153, 1, v98
	v_mul_u32_u24_e32 v228, 17, v105
	v_sub_u32_e32 v228, v107, v228
	s_mul_i32 s90, s54, 153
	s_lshr_b32 s90, s90, 1
	s_add_i32 s90, s90, 34876
	v_lshl_add_u32 v228, v228, 2, s90
	v_lshlrev_b32_e32 v229, 2, v105
	v_sub_u32_e32 v229, v107, v229
	s_add_i32 s90, s101, 5104
	v_lshl_add_u32 v229, v229, 2, s90
	v_sub_u32_e32 v230, v107, v105
	s_add_i32 s90, s101, 6364
	v_lshl_add_u32 v230, v230, 2, s90
	v_add_u32_e32 v231, v109, v108
	v_mov_b64_e32 v[232:233], 0
	v_mov_b64_e32 v[0:1], 0
	v_mov_b64_e32 v[2:3], 0
	v_mov_b64_e32 v[4:5], 0
	v_mov_b64_e32 v[6:7], 0
	v_mov_b64_e32 v[8:9], 0
	v_mov_b64_e32 v[10:11], 0
	v_mov_b64_e32 v[12:13], 0
	v_mov_b64_e32 v[14:15], 0
	v_mov_b64_e32 v[16:17], 0
	v_mov_b64_e32 v[18:19], 0
	v_mov_b64_e32 v[20:21], 0
	v_mov_b64_e32 v[22:23], 0
	v_mov_b64_e32 v[24:25], 0
	v_mov_b64_e32 v[26:27], 0
	v_mov_b64_e32 v[28:29], 0
	v_mov_b64_e32 v[30:31], 0
	s_add_i32 s90, s67, -64
	v_add_u32_e32 v80, s90, v235
	v_add_u32_e32 v83, s90, v236
	v_add_u32_e32 v99, s90, v237
	v_add_u32_e32 v253, s90, v238
	v_add_u32_e32 v254, s90, v100
	v_add_u32_e32 v255, s90, v149
	v_med3_i32 v80, v80, 0, s99
	v_med3_i32 v83, v83, 0, s99
	v_med3_i32 v99, v99, 0, s99
	v_med3_i32 v253, v253, 0, s99
	v_med3_i32 v254, v254, 0, s99
	v_med3_i32 v255, v255, 0, s99
	v_mad_u32_u24 v80, v80, s100, v252
	v_mad_u32_u24 v83, v83, s100, v252
	v_mad_u32_u24 v99, v99, s100, v252
	v_mad_u32_u24 v253, v253, s100, v252
	v_mad_u32_u24 v254, v254, s100, v153
	v_mad_u32_u24 v255, v255, s100, v153
	global_load_dwordx4 v[116:119], v80, s[82:83]
	global_load_dwordx4 v[120:123], v83, s[82:83]
	global_load_dwordx4 v[124:127], v99, s[82:83]
	global_load_dwordx4 v[128:131], v253, s[82:83]
	global_load_dwordx4 v[132:135], v254, s[82:83] offset:768
	global_load_dwordx4 v[136:139], v255, s[82:83] offset:768
	global_load_dwordx4 v[140:143], v254, s[82:83] offset:832
	global_load_dwordx4 v[144:147], v255, s[82:83] offset:832
	s_add_i32 s90, s67, -32
	v_add_u32_e32 v80, s90, v235
	v_add_u32_e32 v83, s90, v236
	v_add_u32_e32 v99, s90, v237
	v_add_u32_e32 v253, s90, v238
	v_add_u32_e32 v254, s90, v100
	v_add_u32_e32 v255, s90, v149
	v_med3_i32 v80, v80, 0, s99
	v_med3_i32 v83, v83, 0, s99
	v_med3_i32 v99, v99, 0, s99
	v_med3_i32 v253, v253, 0, s99
	v_med3_i32 v254, v254, 0, s99
	v_med3_i32 v255, v255, 0, s99
	v_mad_u32_u24 v80, v80, s100, v252
	v_mad_u32_u24 v83, v83, s100, v252
	v_mad_u32_u24 v99, v99, s100, v252
	v_mad_u32_u24 v253, v253, s100, v252
	v_mad_u32_u24 v254, v254, s100, v153
	v_mad_u32_u24 v255, v255, s100, v153
	global_load_dwordx4 v[156:159], v80, s[82:83]
	global_load_dwordx4 v[160:163], v83, s[82:83]
	global_load_dwordx4 v[164:167], v99, s[82:83]
	global_load_dwordx4 v[168:171], v253, s[82:83]
	global_load_dwordx4 v[172:175], v254, s[82:83] offset:768
	global_load_dwordx4 v[176:179], v255, s[82:83] offset:768
	global_load_dwordx4 v[180:183], v254, s[82:83] offset:832
	global_load_dwordx4 v[184:187], v255, s[82:83] offset:832
	v_mov_b32_e32 v115, v228
	ds_read2_b32 v[32:33], v115 offset0:0 offset1:1
	ds_read2_b32 v[34:35], v115 offset0:2 offset1:3
	ds_read2_b32 v[36:37], v115 offset0:8 offset1:9
	ds_read2_b32 v[38:39], v115 offset0:10 offset1:11
	ds_read2_b32 v[40:41], v115 offset0:17 offset1:18
	ds_read2_b32 v[42:43], v115 offset0:19 offset1:20
	ds_read2_b32 v[44:45], v115 offset0:25 offset1:26
	ds_read2_b32 v[46:47], v115 offset0:27 offset1:28
	s_waitcnt vmcnt(8)
	ds_write_b128 v247, v[116:119]
	ds_write_b128 v247, v[120:123] offset:1024
	ds_write_b128 v247, v[124:127] offset:2048
	ds_write_b128 v247, v[128:131] offset:3072
	ds_read_b128 v[116:119], v248
	ds_read_b128 v[120:123], v249
	ds_read_b128 v[124:127], v250
	ds_read_b128 v[128:131], v251
	ds_write_b128 v112, v[132:135]
	ds_write_b128 v112, v[136:139] offset:1024
	ds_write_b128 v112, v[140:143] offset:2048
	ds_write_b128 v112, v[144:147] offset:3072
	s_waitcnt lgkmcnt(4)
	v_mfma_f32_32x32x16_bf16 v[32:47], v[116:119], v[48:51], v[32:47]
	v_mfma_f32_32x32x16_bf16 v[32:47], v[120:123], v[52:55], v[32:47]
	v_mfma_f32_32x32x16_bf16 v[32:47], v[124:127], v[56:59], v[32:47]
	v_mfma_f32_32x32x16_bf16 v[32:47], v[128:131], v[60:63], v[32:47]
	ds_read2_b32 v[188:189], v115 offset0:34 offset1:35
	ds_read2_b32 v[190:191], v115 offset0:36 offset1:37
	ds_read2_b32 v[192:193], v115 offset0:42 offset1:43
	ds_read2_b32 v[194:195], v115 offset0:44 offset1:45
	ds_read2_b32 v[196:197], v115 offset0:51 offset1:52
	ds_read2_b32 v[198:199], v115 offset0:53 offset1:54
	ds_read2_b32 v[200:201], v115 offset0:59 offset1:60
	ds_read2_b32 v[202:203], v115 offset0:61 offset1:62
	s_add_i32 s90, s67, 0
	v_add_u32_e32 v80, s90, v235
	v_add_u32_e32 v83, s90, v236
	v_add_u32_e32 v99, s90, v237
	v_add_u32_e32 v253, s90, v238
	v_add_u32_e32 v254, s90, v100
	v_add_u32_e32 v255, s90, v149
	v_med3_i32 v80, v80, 0, s99
	v_med3_i32 v83, v83, 0, s99
	v_med3_i32 v99, v99, 0, s99
	v_med3_i32 v253, v253, 0, s99
	v_med3_i32 v254, v254, 0, s99
	v_med3_i32 v255, v255, 0, s99
	v_mad_u32_u24 v80, v80, s100, v252
	v_mad_u32_u24 v83, v83, s100, v252
	v_mad_u32_u24 v99, v99, s100, v252
	v_mad_u32_u24 v253, v253, s100, v252
	v_mad_u32_u24 v254, v254, s100, v153
	v_mad_u32_u24 v255, v255, s100, v153
	global_load_dwordx4 v[116:119], v80, s[82:83]
	global_load_dwordx4 v[120:123], v83, s[82:83]
	global_load_dwordx4 v[124:127], v99, s[82:83]
	global_load_dwordx4 v[128:131], v253, s[82:83]
	global_load_dwordx4 v[132:135], v254, s[82:83] offset:768
	global_load_dwordx4 v[136:139], v255, s[82:83] offset:768
	global_load_dwordx4 v[140:143], v254, s[82:83] offset:832
	global_load_dwordx4 v[144:147], v255, s[82:83] offset:832
	ds_read_b64_tr_b16 v[72:73], v231
	ds_read_b64_tr_b16 v[74:75], v231 offset:512
	ds_read_b64_tr_b16 v[76:77], v231 offset:2048
	ds_read_b64_tr_b16 v[78:79], v231 offset:2560
	ds_read_b64_tr_b16 v[220:221], v231 offset:1024
	ds_read_b64_tr_b16 v[222:223], v231 offset:1536
	ds_read_b64_tr_b16 v[224:225], v231 offset:3072
	ds_read_b64_tr_b16 v[226:227], v231 offset:3584
	v_exp_f32_e32 v32, v32
	v_exp_f32_e32 v33, v33
	v_exp_f32_e32 v34, v34
	v_exp_f32_e32 v35, v35
	s_waitcnt vmcnt(8)
	ds_write_b128 v247, v[156:159]
	ds_write_b128 v247, v[160:163] offset:1024
	ds_write_b128 v247, v[164:167] offset:2048
	ds_write_b128 v247, v[168:171] offset:3072
	ds_read_b128 v[156:159], v248
	ds_read_b128 v[160:163], v249
	ds_read_b128 v[164:167], v250
	ds_read_b128 v[168:171], v251
	ds_write_b128 v112, v[172:175]
	ds_write_b128 v112, v[176:179] offset:1024
	ds_write_b128 v112, v[180:183] offset:2048
	ds_write_b128 v112, v[184:187] offset:3072
	v_exp_f32_e32 v36, v36
	v_exp_f32_e32 v37, v37
	v_exp_f32_e32 v38, v38
	v_exp_f32_e32 v39, v39
	s_waitcnt lgkmcnt(4)
	v_mfma_f32_32x32x16_bf16 v[188:203], v[156:159], v[48:51], v[188:203]
	v_exp_f32_e32 v40, v40
	v_exp_f32_e32 v41, v41
	v_mfma_f32_32x32x16_bf16 v[188:203], v[160:163], v[52:55], v[188:203]
	v_exp_f32_e32 v42, v42
	v_exp_f32_e32 v43, v43
	v_mfma_f32_32x32x16_bf16 v[188:203], v[164:167], v[56:59], v[188:203]
	v_exp_f32_e32 v44, v44
	v_exp_f32_e32 v45, v45
	v_mfma_f32_32x32x16_bf16 v[188:203], v[168:171], v[60:63], v[188:203]
	v_exp_f32_e32 v46, v46
	v_exp_f32_e32 v47, v47
	s_add_i32 s90, s67, -64
	v_add_u32_e32 v84, s90, v107
	v_add_u32_e32 v85, 0, v84
	v_add_u32_e32 v86, 1, v84
	v_add_u32_e32 v87, 2, v84
	v_add_u32_e32 v88, 3, v84
	v_cmp_gt_u32_e64 s[30:31], s98, v85
	v_cmp_gt_u32_e64 s[36:37], s98, v86
	v_cmp_gt_u32_e64 s[78:79], s98, v87
	v_cmp_gt_u32_e64 s[50:51], s98, v88
	v_cndmask_b32_e64 v32, 0, v32, s[30:31]
	v_add_u32_e32 v85, 8, v84
	v_cmp_gt_u32_e64 s[30:31], s98, v85
	v_cndmask_b32_e64 v33, 0, v33, s[36:37]
	v_add_u32_e32 v86, 9, v84
	v_cmp_gt_u32_e64 s[36:37], s98, v86
	v_cndmask_b32_e64 v34, 0, v34, s[78:79]
	v_add_u32_e32 v87, 10, v84
	v_cmp_gt_u32_e64 s[78:79], s98, v87
	v_cndmask_b32_e64 v35, 0, v35, s[50:51]
	v_add_u32_e32 v88, 11, v84
	v_cmp_gt_u32_e64 s[50:51], s98, v88
	v_cndmask_b32_e64 v36, 0, v36, s[30:31]
	v_add_u32_e32 v85, 16, v84
	v_cmp_gt_u32_e64 s[30:31], s98, v85
	v_cndmask_b32_e64 v37, 0, v37, s[36:37]
	v_add_u32_e32 v86, 17, v84
	v_cmp_gt_u32_e64 s[36:37], s98, v86
	v_cndmask_b32_e64 v38, 0, v38, s[78:79]
	v_add_u32_e32 v87, 18, v84
	v_cmp_gt_u32_e64 s[78:79], s98, v87
	v_cndmask_b32_e64 v39, 0, v39, s[50:51]
	v_add_u32_e32 v88, 19, v84
	v_cmp_gt_u32_e64 s[50:51], s98, v88
	v_cndmask_b32_e64 v40, 0, v40, s[30:31]
	v_add_u32_e32 v85, 24, v84
	v_cmp_gt_u32_e64 s[30:31], s98, v85
	v_cndmask_b32_e64 v41, 0, v41, s[36:37]
	v_add_u32_e32 v86, 25, v84
	v_cmp_gt_u32_e64 s[36:37], s98, v86
	v_cndmask_b32_e64 v42, 0, v42, s[78:79]
	v_add_u32_e32 v87, 26, v84
	v_cmp_gt_u32_e64 s[78:79], s98, v87
	v_cndmask_b32_e64 v43, 0, v43, s[50:51]
	v_add_u32_e32 v88, 27, v84
	v_cmp_gt_u32_e64 s[50:51], s98, v88
	v_nop
	v_cndmask_b32_e64 v44, 0, v44, s[30:31]
	v_cndmask_b32_e64 v45, 0, v45, s[36:37]
	v_cndmask_b32_e64 v46, 0, v46, s[78:79]
	v_cndmask_b32_e64 v47, 0, v47, s[50:51]
	v_cvt_pk_bf16_f32 v64, v32, v33
	v_cvt_pk_bf16_f32 v65, v34, v35
	v_cvt_pk_bf16_f32 v66, v36, v37
	v_cvt_pk_bf16_f32 v67, v38, v39
	v_cvt_pk_bf16_f32 v68, v40, v41
	v_cvt_pk_bf16_f32 v69, v42, v43
	v_cvt_pk_bf16_f32 v70, v44, v45
	v_cvt_pk_bf16_f32 v71, v46, v47
	v_pk_add_f32 v[232:233], v[232:233], v[32:33]
	v_pk_add_f32 v[232:233], v[232:233], v[34:35]
	v_pk_add_f32 v[232:233], v[232:233], v[36:37]
	v_pk_add_f32 v[232:233], v[232:233], v[38:39]
	v_pk_add_f32 v[232:233], v[232:233], v[40:41]
	v_pk_add_f32 v[232:233], v[232:233], v[42:43]
	v_pk_add_f32 v[232:233], v[232:233], v[44:45]
	v_pk_add_f32 v[232:233], v[232:233], v[46:47]
	ds_read2_b32 v[32:33], v115 offset0:68 offset1:69
	ds_read2_b32 v[34:35], v115 offset0:70 offset1:71
	ds_read2_b32 v[36:37], v115 offset0:76 offset1:77
	ds_read2_b32 v[38:39], v115 offset0:78 offset1:79
	ds_read2_b32 v[40:41], v115 offset0:85 offset1:86
	ds_read2_b32 v[42:43], v115 offset0:87 offset1:88
	ds_read2_b32 v[44:45], v115 offset0:93 offset1:94
	ds_read2_b32 v[46:47], v115 offset0:95 offset1:96
	s_add_i32 s90, s67, 32
	v_add_u32_e32 v80, s90, v235
	v_add_u32_e32 v83, s90, v236
	v_add_u32_e32 v99, s90, v237
	v_add_u32_e32 v253, s90, v238
	v_add_u32_e32 v254, s90, v100
	v_add_u32_e32 v255, s90, v149
	v_med3_i32 v80, v80, 0, s99
	v_med3_i32 v83, v83, 0, s99
	v_med3_i32 v99, v99, 0, s99
	v_med3_i32 v253, v253, 0, s99
	v_med3_i32 v254, v254, 0, s99
	v_med3_i32 v255, v255, 0, s99
	v_mad_u32_u24 v80, v80, s100, v252
	v_mad_u32_u24 v83, v83, s100, v252
	v_mad_u32_u24 v99, v99, s100, v252
	v_mad_u32_u24 v253, v253, s100, v252
	v_mad_u32_u24 v254, v254, s100, v153
	v_mad_u32_u24 v255, v255, s100, v153
	global_load_dwordx4 v[156:159], v80, s[82:83]
	global_load_dwordx4 v[160:163], v83, s[82:83]
	global_load_dwordx4 v[164:167], v99, s[82:83]
	global_load_dwordx4 v[168:171], v253, s[82:83]
	global_load_dwordx4 v[172:175], v254, s[82:83] offset:768
	global_load_dwordx4 v[176:179], v255, s[82:83] offset:768
	global_load_dwordx4 v[180:183], v254, s[82:83] offset:832
	global_load_dwordx4 v[184:187], v255, s[82:83] offset:832
	ds_read_b64_tr_b16 v[204:205], v231
	ds_read_b64_tr_b16 v[206:207], v231 offset:512
	ds_read_b64_tr_b16 v[208:209], v231 offset:2048
	ds_read_b64_tr_b16 v[210:211], v231 offset:2560
	ds_read_b64_tr_b16 v[212:213], v231 offset:1024
	ds_read_b64_tr_b16 v[214:215], v231 offset:1536
	ds_read_b64_tr_b16 v[216:217], v231 offset:3072
	ds_read_b64_tr_b16 v[218:219], v231 offset:3584
	v_exp_f32_e32 v188, v188
	v_exp_f32_e32 v189, v189
	v_exp_f32_e32 v190, v190
	v_exp_f32_e32 v191, v191
	s_waitcnt vmcnt(8)
	ds_write_b128 v247, v[116:119]
	ds_write_b128 v247, v[120:123] offset:1024
	ds_write_b128 v247, v[124:127] offset:2048
	ds_write_b128 v247, v[128:131] offset:3072
	ds_read_b128 v[116:119], v248
	ds_read_b128 v[120:123], v249
	ds_read_b128 v[124:127], v250
	ds_read_b128 v[128:131], v251
	ds_write_b128 v112, v[132:135]
	ds_write_b128 v112, v[136:139] offset:1024
	ds_write_b128 v112, v[140:143] offset:2048
	ds_write_b128 v112, v[144:147] offset:3072
	v_mfma_f32_32x32x16_bf16 v[0:15], v[64:67], v[72:75], v[0:15]
	v_mfma_f32_32x32x16_bf16 v[16:31], v[64:67], v[76:79], v[16:31]
	v_mfma_f32_32x32x16_bf16 v[0:15], v[68:71], v[220:223], v[0:15]
	v_mfma_f32_32x32x16_bf16 v[16:31], v[68:71], v[224:227], v[16:31]
	v_exp_f32_e32 v192, v192
	v_exp_f32_e32 v193, v193
	v_exp_f32_e32 v194, v194
	v_exp_f32_e32 v195, v195
	s_waitcnt lgkmcnt(4)
	v_mfma_f32_32x32x16_bf16 v[32:47], v[116:119], v[48:51], v[32:47]
	v_exp_f32_e32 v196, v196
	v_exp_f32_e32 v197, v197
	v_mfma_f32_32x32x16_bf16 v[32:47], v[120:123], v[52:55], v[32:47]
	v_exp_f32_e32 v198, v198
	v_exp_f32_e32 v199, v199
	v_mfma_f32_32x32x16_bf16 v[32:47], v[124:127], v[56:59], v[32:47]
	v_exp_f32_e32 v200, v200
	v_exp_f32_e32 v201, v201
	v_mfma_f32_32x32x16_bf16 v[32:47], v[128:131], v[60:63], v[32:47]
	v_exp_f32_e32 v202, v202
	v_exp_f32_e32 v203, v203
	s_add_i32 s90, s67, -32
	v_add_u32_e32 v84, s90, v107
	v_add_u32_e32 v85, 0, v84
	v_add_u32_e32 v86, 1, v84
	v_add_u32_e32 v87, 2, v84
	v_add_u32_e32 v88, 3, v84
	v_cmp_gt_u32_e64 s[30:31], s98, v85
	v_cmp_gt_u32_e64 s[36:37], s98, v86
	v_cmp_gt_u32_e64 s[78:79], s98, v87
	v_cmp_gt_u32_e64 s[50:51], s98, v88
	v_cndmask_b32_e64 v188, 0, v188, s[30:31]
	v_add_u32_e32 v85, 8, v84
	v_cmp_gt_u32_e64 s[30:31], s98, v85
	v_cndmask_b32_e64 v189, 0, v189, s[36:37]
	v_add_u32_e32 v86, 9, v84
	v_cmp_gt_u32_e64 s[36:37], s98, v86
	v_cndmask_b32_e64 v190, 0, v190, s[78:79]
	v_add_u32_e32 v87, 10, v84
	v_cmp_gt_u32_e64 s[78:79], s98, v87
	v_cndmask_b32_e64 v191, 0, v191, s[50:51]
	v_add_u32_e32 v88, 11, v84
	v_cmp_gt_u32_e64 s[50:51], s98, v88
	v_cndmask_b32_e64 v192, 0, v192, s[30:31]
	v_add_u32_e32 v85, 16, v84
	v_cmp_gt_u32_e64 s[30:31], s98, v85
	v_cndmask_b32_e64 v193, 0, v193, s[36:37]
	v_add_u32_e32 v86, 17, v84
	v_cmp_gt_u32_e64 s[36:37], s98, v86
	v_cndmask_b32_e64 v194, 0, v194, s[78:79]
	v_add_u32_e32 v87, 18, v84
	v_cmp_gt_u32_e64 s[78:79], s98, v87
	v_cndmask_b32_e64 v195, 0, v195, s[50:51]
	v_add_u32_e32 v88, 19, v84
	v_cmp_gt_u32_e64 s[50:51], s98, v88
	v_cndmask_b32_e64 v196, 0, v196, s[30:31]
	v_add_u32_e32 v85, 24, v84
	v_cmp_gt_u32_e64 s[30:31], s98, v85
	v_cndmask_b32_e64 v197, 0, v197, s[36:37]
	v_add_u32_e32 v86, 25, v84
	v_cmp_gt_u32_e64 s[36:37], s98, v86
	v_cndmask_b32_e64 v198, 0, v198, s[78:79]
	v_add_u32_e32 v87, 26, v84
	v_cmp_gt_u32_e64 s[78:79], s98, v87
	v_cndmask_b32_e64 v199, 0, v199, s[50:51]
	v_add_u32_e32 v88, 27, v84
	v_cmp_gt_u32_e64 s[50:51], s98, v88
	v_nop
	v_cndmask_b32_e64 v200, 0, v200, s[30:31]
	v_cndmask_b32_e64 v201, 0, v201, s[36:37]
	v_cndmask_b32_e64 v202, 0, v202, s[78:79]
	v_cndmask_b32_e64 v203, 0, v203, s[50:51]
	v_cvt_pk_bf16_f32 v64, v188, v189
	v_cvt_pk_bf16_f32 v65, v190, v191
	v_cvt_pk_bf16_f32 v66, v192, v193
	v_cvt_pk_bf16_f32 v67, v194, v195
	v_cvt_pk_bf16_f32 v68, v196, v197
	v_cvt_pk_bf16_f32 v69, v198, v199
	v_cvt_pk_bf16_f32 v70, v200, v201
	v_cvt_pk_bf16_f32 v71, v202, v203
	v_pk_add_f32 v[232:233], v[232:233], v[188:189]
	v_pk_add_f32 v[232:233], v[232:233], v[190:191]
	v_pk_add_f32 v[232:233], v[232:233], v[192:193]
	v_pk_add_f32 v[232:233], v[232:233], v[194:195]
	v_pk_add_f32 v[232:233], v[232:233], v[196:197]
	v_pk_add_f32 v[232:233], v[232:233], v[198:199]
	v_pk_add_f32 v[232:233], v[232:233], v[200:201]
	v_pk_add_f32 v[232:233], v[232:233], v[202:203]
	ds_read2_b32 v[188:189], v115 offset0:102 offset1:103
	ds_read2_b32 v[190:191], v115 offset0:104 offset1:105
	ds_read2_b32 v[192:193], v115 offset0:110 offset1:111
	ds_read2_b32 v[194:195], v115 offset0:112 offset1:113
	ds_read2_b32 v[196:197], v115 offset0:119 offset1:120
	ds_read2_b32 v[198:199], v115 offset0:121 offset1:122
	ds_read2_b32 v[200:201], v115 offset0:127 offset1:128
	ds_read2_b32 v[202:203], v115 offset0:129 offset1:130
	s_add_i32 s90, s67, 64
	v_add_u32_e32 v80, s90, v235
	v_add_u32_e32 v83, s90, v236
	v_add_u32_e32 v99, s90, v237
	v_add_u32_e32 v253, s90, v238
	v_add_u32_e32 v254, s90, v100
	v_add_u32_e32 v255, s90, v149
	v_med3_i32 v80, v80, 0, s99
	v_med3_i32 v83, v83, 0, s99
	v_med3_i32 v99, v99, 0, s99
	v_med3_i32 v253, v253, 0, s99
	v_med3_i32 v254, v254, 0, s99
	v_med3_i32 v255, v255, 0, s99
	v_mad_u32_u24 v80, v80, s100, v252
	v_mad_u32_u24 v83, v83, s100, v252
	v_mad_u32_u24 v99, v99, s100, v252
	v_mad_u32_u24 v253, v253, s100, v252
	v_mad_u32_u24 v254, v254, s100, v153
	v_mad_u32_u24 v255, v255, s100, v153
	global_load_dwordx4 v[116:119], v80, s[82:83]
	global_load_dwordx4 v[120:123], v83, s[82:83]
	global_load_dwordx4 v[124:127], v99, s[82:83]
	global_load_dwordx4 v[128:131], v253, s[82:83]
	global_load_dwordx4 v[132:135], v254, s[82:83] offset:768
	global_load_dwordx4 v[136:139], v255, s[82:83] offset:768
	global_load_dwordx4 v[140:143], v254, s[82:83] offset:832
	global_load_dwordx4 v[144:147], v255, s[82:83] offset:832
	ds_read_b64_tr_b16 v[72:73], v231
	ds_read_b64_tr_b16 v[74:75], v231 offset:512
	ds_read_b64_tr_b16 v[76:77], v231 offset:2048
	ds_read_b64_tr_b16 v[78:79], v231 offset:2560
	ds_read_b64_tr_b16 v[220:221], v231 offset:1024
	ds_read_b64_tr_b16 v[222:223], v231 offset:1536
	ds_read_b64_tr_b16 v[224:225], v231 offset:3072
	ds_read_b64_tr_b16 v[226:227], v231 offset:3584
	v_exp_f32_e32 v32, v32
	v_exp_f32_e32 v33, v33
	v_exp_f32_e32 v34, v34
	v_exp_f32_e32 v35, v35
	s_waitcnt vmcnt(8)
	ds_write_b128 v247, v[156:159]
	ds_write_b128 v247, v[160:163] offset:1024
	ds_write_b128 v247, v[164:167] offset:2048
	ds_write_b128 v247, v[168:171] offset:3072
	ds_read_b128 v[156:159], v248
	ds_read_b128 v[160:163], v249
	ds_read_b128 v[164:167], v250
	ds_read_b128 v[168:171], v251
	ds_write_b128 v112, v[172:175]
	ds_write_b128 v112, v[176:179] offset:1024
	ds_write_b128 v112, v[180:183] offset:2048
	ds_write_b128 v112, v[184:187] offset:3072
	v_mfma_f32_32x32x16_bf16 v[0:15], v[64:67], v[204:207], v[0:15]
	v_mfma_f32_32x32x16_bf16 v[16:31], v[64:67], v[208:211], v[16:31]
	v_mfma_f32_32x32x16_bf16 v[0:15], v[68:71], v[212:215], v[0:15]
	v_mfma_f32_32x32x16_bf16 v[16:31], v[68:71], v[216:219], v[16:31]
	v_exp_f32_e32 v36, v36
	v_exp_f32_e32 v37, v37
	v_exp_f32_e32 v38, v38
	v_exp_f32_e32 v39, v39
	s_waitcnt lgkmcnt(4)
	v_mfma_f32_32x32x16_bf16 v[188:203], v[156:159], v[48:51], v[188:203]
	v_exp_f32_e32 v40, v40
	v_exp_f32_e32 v41, v41
	v_mfma_f32_32x32x16_bf16 v[188:203], v[160:163], v[52:55], v[188:203]
	v_exp_f32_e32 v42, v42
	v_exp_f32_e32 v43, v43
	v_mfma_f32_32x32x16_bf16 v[188:203], v[164:167], v[56:59], v[188:203]
	v_exp_f32_e32 v44, v44
	v_exp_f32_e32 v45, v45
	v_mfma_f32_32x32x16_bf16 v[188:203], v[168:171], v[60:63], v[188:203]
	v_exp_f32_e32 v46, v46
	v_exp_f32_e32 v47, v47
	s_add_i32 s90, s67, 0
	v_add_u32_e32 v84, s90, v107
	v_add_u32_e32 v85, 0, v84
	v_add_u32_e32 v86, 1, v84
	v_add_u32_e32 v87, 2, v84
	v_add_u32_e32 v88, 3, v84
	v_cmp_gt_u32_e64 s[30:31], s98, v85
	v_cmp_gt_u32_e64 s[36:37], s98, v86
	v_cmp_gt_u32_e64 s[78:79], s98, v87
	v_cmp_gt_u32_e64 s[50:51], s98, v88
	v_cndmask_b32_e64 v32, 0, v32, s[30:31]
	v_add_u32_e32 v85, 8, v84
	v_cmp_gt_u32_e64 s[30:31], s98, v85
	v_cndmask_b32_e64 v33, 0, v33, s[36:37]
	v_add_u32_e32 v86, 9, v84
	v_cmp_gt_u32_e64 s[36:37], s98, v86
	v_cndmask_b32_e64 v34, 0, v34, s[78:79]
	v_add_u32_e32 v87, 10, v84
	v_cmp_gt_u32_e64 s[78:79], s98, v87
	v_cndmask_b32_e64 v35, 0, v35, s[50:51]
	v_add_u32_e32 v88, 11, v84
	v_cmp_gt_u32_e64 s[50:51], s98, v88
	v_cndmask_b32_e64 v36, 0, v36, s[30:31]
	v_add_u32_e32 v85, 16, v84
	v_cmp_gt_u32_e64 s[30:31], s98, v85
	v_cndmask_b32_e64 v37, 0, v37, s[36:37]
	v_add_u32_e32 v86, 17, v84
	v_cmp_gt_u32_e64 s[36:37], s98, v86
	v_cndmask_b32_e64 v38, 0, v38, s[78:79]
	v_add_u32_e32 v87, 18, v84
	v_cmp_gt_u32_e64 s[78:79], s98, v87
	v_cndmask_b32_e64 v39, 0, v39, s[50:51]
	v_add_u32_e32 v88, 19, v84
	v_cmp_gt_u32_e64 s[50:51], s98, v88
	v_cndmask_b32_e64 v40, 0, v40, s[30:31]
	v_add_u32_e32 v85, 24, v84
	v_cmp_gt_u32_e64 s[30:31], s98, v85
	v_cndmask_b32_e64 v41, 0, v41, s[36:37]
	v_add_u32_e32 v86, 25, v84
	v_cmp_gt_u32_e64 s[36:37], s98, v86
	v_cndmask_b32_e64 v42, 0, v42, s[78:79]
	v_add_u32_e32 v87, 26, v84
	v_cmp_gt_u32_e64 s[78:79], s98, v87
	v_cndmask_b32_e64 v43, 0, v43, s[50:51]
	v_add_u32_e32 v88, 27, v84
	v_cmp_gt_u32_e64 s[50:51], s98, v88
	v_nop
	v_cndmask_b32_e64 v44, 0, v44, s[30:31]
	v_cndmask_b32_e64 v45, 0, v45, s[36:37]
	v_cndmask_b32_e64 v46, 0, v46, s[78:79]
	v_cndmask_b32_e64 v47, 0, v47, s[50:51]
	v_cvt_pk_bf16_f32 v64, v32, v33
	v_cvt_pk_bf16_f32 v65, v34, v35
	v_cvt_pk_bf16_f32 v66, v36, v37
	v_cvt_pk_bf16_f32 v67, v38, v39
	v_cvt_pk_bf16_f32 v68, v40, v41
	v_cvt_pk_bf16_f32 v69, v42, v43
	v_cvt_pk_bf16_f32 v70, v44, v45
	v_cvt_pk_bf16_f32 v71, v46, v47
	v_pk_add_f32 v[232:233], v[232:233], v[32:33]
	v_pk_add_f32 v[232:233], v[232:233], v[34:35]
	v_pk_add_f32 v[232:233], v[232:233], v[36:37]
	v_pk_add_f32 v[232:233], v[232:233], v[38:39]
	v_pk_add_f32 v[232:233], v[232:233], v[40:41]
	v_pk_add_f32 v[232:233], v[232:233], v[42:43]
	v_pk_add_f32 v[232:233], v[232:233], v[44:45]
	v_pk_add_f32 v[232:233], v[232:233], v[46:47]
	ds_read2_b32 v[32:33], v115 offset0:136 offset1:137
	ds_read2_b32 v[34:35], v115 offset0:138 offset1:139
	ds_read2_b32 v[36:37], v115 offset0:144 offset1:145
	ds_read2_b32 v[38:39], v115 offset0:146 offset1:147
	ds_read2_b32 v[40:41], v115 offset0:153 offset1:154
	ds_read2_b32 v[42:43], v115 offset0:155 offset1:156
	ds_read2_b32 v[44:45], v115 offset0:161 offset1:162
	ds_read2_b32 v[46:47], v115 offset0:163 offset1:164
	s_add_i32 s90, s67, 96
	v_add_u32_e32 v80, s90, v235
	v_add_u32_e32 v83, s90, v236
	v_add_u32_e32 v99, s90, v237
	v_add_u32_e32 v253, s90, v238
	v_add_u32_e32 v254, s90, v100
	v_add_u32_e32 v255, s90, v149
	v_med3_i32 v80, v80, 0, s99
	v_med3_i32 v83, v83, 0, s99
	v_med3_i32 v99, v99, 0, s99
	v_med3_i32 v253, v253, 0, s99
	v_med3_i32 v254, v254, 0, s99
	v_med3_i32 v255, v255, 0, s99
	v_mad_u32_u24 v80, v80, s100, v252
	v_mad_u32_u24 v83, v83, s100, v252
	v_mad_u32_u24 v99, v99, s100, v252
	v_mad_u32_u24 v253, v253, s100, v252
	v_mad_u32_u24 v254, v254, s100, v153
	v_mad_u32_u24 v255, v255, s100, v153
	global_load_dwordx4 v[156:159], v80, s[82:83]
	global_load_dwordx4 v[160:163], v83, s[82:83]
	global_load_dwordx4 v[164:167], v99, s[82:83]
	global_load_dwordx4 v[168:171], v253, s[82:83]
	global_load_dwordx4 v[172:175], v254, s[82:83] offset:768
	global_load_dwordx4 v[176:179], v255, s[82:83] offset:768
	global_load_dwordx4 v[180:183], v254, s[82:83] offset:832
	global_load_dwordx4 v[184:187], v255, s[82:83] offset:832
	ds_read_b64_tr_b16 v[204:205], v231
	ds_read_b64_tr_b16 v[206:207], v231 offset:512
	ds_read_b64_tr_b16 v[208:209], v231 offset:2048
	ds_read_b64_tr_b16 v[210:211], v231 offset:2560
	ds_read_b64_tr_b16 v[212:213], v231 offset:1024
	ds_read_b64_tr_b16 v[214:215], v231 offset:1536
	ds_read_b64_tr_b16 v[216:217], v231 offset:3072
	ds_read_b64_tr_b16 v[218:219], v231 offset:3584
	v_exp_f32_e32 v188, v188
	v_exp_f32_e32 v189, v189
	v_exp_f32_e32 v190, v190
	v_exp_f32_e32 v191, v191
	s_waitcnt vmcnt(8)
	ds_write_b128 v247, v[116:119]
	ds_write_b128 v247, v[120:123] offset:1024
	ds_write_b128 v247, v[124:127] offset:2048
	ds_write_b128 v247, v[128:131] offset:3072
	ds_read_b128 v[116:119], v248
	ds_read_b128 v[120:123], v249
	ds_read_b128 v[124:127], v250
	ds_read_b128 v[128:131], v251
	ds_write_b128 v112, v[132:135]
	ds_write_b128 v112, v[136:139] offset:1024
	ds_write_b128 v112, v[140:143] offset:2048
	ds_write_b128 v112, v[144:147] offset:3072
	v_mfma_f32_32x32x16_bf16 v[0:15], v[64:67], v[72:75], v[0:15]
	v_mfma_f32_32x32x16_bf16 v[16:31], v[64:67], v[76:79], v[16:31]
	v_mfma_f32_32x32x16_bf16 v[0:15], v[68:71], v[220:223], v[0:15]
	v_mfma_f32_32x32x16_bf16 v[16:31], v[68:71], v[224:227], v[16:31]
	v_exp_f32_e32 v192, v192
	v_exp_f32_e32 v193, v193
	v_exp_f32_e32 v194, v194
	v_exp_f32_e32 v195, v195
	s_waitcnt lgkmcnt(4)
	v_mfma_f32_32x32x16_bf16 v[32:47], v[116:119], v[48:51], v[32:47]
	v_exp_f32_e32 v196, v196
	v_exp_f32_e32 v197, v197
	v_mfma_f32_32x32x16_bf16 v[32:47], v[120:123], v[52:55], v[32:47]
	v_exp_f32_e32 v198, v198
	v_exp_f32_e32 v199, v199
	v_mfma_f32_32x32x16_bf16 v[32:47], v[124:127], v[56:59], v[32:47]
	v_exp_f32_e32 v200, v200
	v_exp_f32_e32 v201, v201
	v_mfma_f32_32x32x16_bf16 v[32:47], v[128:131], v[60:63], v[32:47]
	v_exp_f32_e32 v202, v202
	v_exp_f32_e32 v203, v203
	s_add_i32 s90, s67, 32
	v_add_u32_e32 v84, s90, v107
	v_add_u32_e32 v85, 0, v84
	v_add_u32_e32 v86, 1, v84
	v_add_u32_e32 v87, 2, v84
	v_add_u32_e32 v88, 3, v84
	v_cmp_gt_u32_e64 s[30:31], s98, v85
	v_cmp_gt_u32_e64 s[36:37], s98, v86
	v_cmp_gt_u32_e64 s[78:79], s98, v87
	v_cmp_gt_u32_e64 s[50:51], s98, v88
	v_cndmask_b32_e64 v188, 0, v188, s[30:31]
	v_add_u32_e32 v85, 8, v84
	v_cmp_gt_u32_e64 s[30:31], s98, v85
	v_cndmask_b32_e64 v189, 0, v189, s[36:37]
	v_add_u32_e32 v86, 9, v84
	v_cmp_gt_u32_e64 s[36:37], s98, v86
	v_cndmask_b32_e64 v190, 0, v190, s[78:79]
	v_add_u32_e32 v87, 10, v84
	v_cmp_gt_u32_e64 s[78:79], s98, v87
	v_cndmask_b32_e64 v191, 0, v191, s[50:51]
	v_add_u32_e32 v88, 11, v84
	v_cmp_gt_u32_e64 s[50:51], s98, v88
	v_cndmask_b32_e64 v192, 0, v192, s[30:31]
	v_add_u32_e32 v85, 16, v84
	v_cmp_gt_u32_e64 s[30:31], s98, v85
	v_cndmask_b32_e64 v193, 0, v193, s[36:37]
	v_add_u32_e32 v86, 17, v84
	v_cmp_gt_u32_e64 s[36:37], s98, v86
	v_cndmask_b32_e64 v194, 0, v194, s[78:79]
	v_add_u32_e32 v87, 18, v84
	v_cmp_gt_u32_e64 s[78:79], s98, v87
	v_cndmask_b32_e64 v195, 0, v195, s[50:51]
	v_add_u32_e32 v88, 19, v84
	v_cmp_gt_u32_e64 s[50:51], s98, v88
	v_cndmask_b32_e64 v196, 0, v196, s[30:31]
	v_add_u32_e32 v85, 24, v84
	v_cmp_gt_u32_e64 s[30:31], s98, v85
	v_cndmask_b32_e64 v197, 0, v197, s[36:37]
	v_add_u32_e32 v86, 25, v84
	v_cmp_gt_u32_e64 s[36:37], s98, v86
	v_cndmask_b32_e64 v198, 0, v198, s[78:79]
	v_add_u32_e32 v87, 26, v84
	v_cmp_gt_u32_e64 s[78:79], s98, v87
	v_cndmask_b32_e64 v199, 0, v199, s[50:51]
	v_add_u32_e32 v88, 27, v84
	v_cmp_gt_u32_e64 s[50:51], s98, v88
	v_nop
	v_cndmask_b32_e64 v200, 0, v200, s[30:31]
	v_cndmask_b32_e64 v201, 0, v201, s[36:37]
	v_cndmask_b32_e64 v202, 0, v202, s[78:79]
	v_cndmask_b32_e64 v203, 0, v203, s[50:51]
	v_cvt_pk_bf16_f32 v64, v188, v189
	v_cvt_pk_bf16_f32 v65, v190, v191
	v_cvt_pk_bf16_f32 v66, v192, v193
	v_cvt_pk_bf16_f32 v67, v194, v195
	v_cvt_pk_bf16_f32 v68, v196, v197
	v_cvt_pk_bf16_f32 v69, v198, v199
	v_cvt_pk_bf16_f32 v70, v200, v201
	v_cvt_pk_bf16_f32 v71, v202, v203
	v_pk_add_f32 v[232:233], v[232:233], v[188:189]
	v_pk_add_f32 v[232:233], v[232:233], v[190:191]
	v_pk_add_f32 v[232:233], v[232:233], v[192:193]
	v_pk_add_f32 v[232:233], v[232:233], v[194:195]
	v_pk_add_f32 v[232:233], v[232:233], v[196:197]
	v_pk_add_f32 v[232:233], v[232:233], v[198:199]
	v_pk_add_f32 v[232:233], v[232:233], v[200:201]
	v_pk_add_f32 v[232:233], v[232:233], v[202:203]
	ds_read2_b32 v[188:189], v115 offset0:170 offset1:171
	ds_read2_b32 v[190:191], v115 offset0:172 offset1:173
	ds_read2_b32 v[192:193], v115 offset0:178 offset1:179
	ds_read2_b32 v[194:195], v115 offset0:180 offset1:181
	ds_read2_b32 v[196:197], v115 offset0:187 offset1:188
	ds_read2_b32 v[198:199], v115 offset0:189 offset1:190
	ds_read2_b32 v[200:201], v115 offset0:195 offset1:196
	ds_read2_b32 v[202:203], v115 offset0:197 offset1:198
	s_add_i32 s90, s67, 128
	v_add_u32_e32 v80, s90, v235
	v_add_u32_e32 v83, s90, v236
	v_add_u32_e32 v99, s90, v237
	v_add_u32_e32 v253, s90, v238
	v_add_u32_e32 v254, s90, v100
	v_add_u32_e32 v255, s90, v149
	v_med3_i32 v80, v80, 0, s99
	v_med3_i32 v83, v83, 0, s99
	v_med3_i32 v99, v99, 0, s99
	v_med3_i32 v253, v253, 0, s99
	v_med3_i32 v254, v254, 0, s99
	v_med3_i32 v255, v255, 0, s99
	v_mad_u32_u24 v80, v80, s100, v252
	v_mad_u32_u24 v83, v83, s100, v252
	v_mad_u32_u24 v99, v99, s100, v252
	v_mad_u32_u24 v253, v253, s100, v252
	v_mad_u32_u24 v254, v254, s100, v153
	v_mad_u32_u24 v255, v255, s100, v153
	global_load_dwordx4 v[116:119], v80, s[82:83]
	global_load_dwordx4 v[120:123], v83, s[82:83]
	global_load_dwordx4 v[124:127], v99, s[82:83]
	global_load_dwordx4 v[128:131], v253, s[82:83]
	global_load_dwordx4 v[132:135], v254, s[82:83] offset:768
	global_load_dwordx4 v[136:139], v255, s[82:83] offset:768
	global_load_dwordx4 v[140:143], v254, s[82:83] offset:832
	global_load_dwordx4 v[144:147], v255, s[82:83] offset:832
	ds_read_b64_tr_b16 v[72:73], v231
	ds_read_b64_tr_b16 v[74:75], v231 offset:512
	ds_read_b64_tr_b16 v[76:77], v231 offset:2048
	ds_read_b64_tr_b16 v[78:79], v231 offset:2560
	ds_read_b64_tr_b16 v[220:221], v231 offset:1024
	ds_read_b64_tr_b16 v[222:223], v231 offset:1536
	ds_read_b64_tr_b16 v[224:225], v231 offset:3072
	ds_read_b64_tr_b16 v[226:227], v231 offset:3584
	v_exp_f32_e32 v32, v32
	v_exp_f32_e32 v33, v33
	v_exp_f32_e32 v34, v34
	v_exp_f32_e32 v35, v35
	s_waitcnt vmcnt(8)
	ds_write_b128 v247, v[156:159]
	ds_write_b128 v247, v[160:163] offset:1024
	ds_write_b128 v247, v[164:167] offset:2048
	ds_write_b128 v247, v[168:171] offset:3072
	ds_read_b128 v[156:159], v248
	ds_read_b128 v[160:163], v249
	ds_read_b128 v[164:167], v250
	ds_read_b128 v[168:171], v251
	ds_write_b128 v112, v[172:175]
	ds_write_b128 v112, v[176:179] offset:1024
	ds_write_b128 v112, v[180:183] offset:2048
	ds_write_b128 v112, v[184:187] offset:3072
	v_mfma_f32_32x32x16_bf16 v[0:15], v[64:67], v[204:207], v[0:15]
	v_mfma_f32_32x32x16_bf16 v[16:31], v[64:67], v[208:211], v[16:31]
	v_mfma_f32_32x32x16_bf16 v[0:15], v[68:71], v[212:215], v[0:15]
	v_mfma_f32_32x32x16_bf16 v[16:31], v[68:71], v[216:219], v[16:31]
	v_exp_f32_e32 v36, v36
	v_exp_f32_e32 v37, v37
	v_exp_f32_e32 v38, v38
	v_exp_f32_e32 v39, v39
	s_waitcnt lgkmcnt(4)
	v_mfma_f32_32x32x16_bf16 v[188:203], v[156:159], v[48:51], v[188:203]
	v_exp_f32_e32 v40, v40
	v_exp_f32_e32 v41, v41
	v_mfma_f32_32x32x16_bf16 v[188:203], v[160:163], v[52:55], v[188:203]
	v_exp_f32_e32 v42, v42
	v_exp_f32_e32 v43, v43
	v_mfma_f32_32x32x16_bf16 v[188:203], v[164:167], v[56:59], v[188:203]
	v_exp_f32_e32 v44, v44
	v_exp_f32_e32 v45, v45
	v_mfma_f32_32x32x16_bf16 v[188:203], v[168:171], v[60:63], v[188:203]
	v_exp_f32_e32 v46, v46
	v_exp_f32_e32 v47, v47
	s_add_i32 s90, s67, 64
	v_add_u32_e32 v84, s90, v107
	v_add_u32_e32 v85, 0, v84
	v_add_u32_e32 v86, 1, v84
	v_add_u32_e32 v87, 2, v84
	v_add_u32_e32 v88, 3, v84
	v_cmp_gt_u32_e64 s[30:31], s98, v85
	v_cmp_gt_u32_e64 s[36:37], s98, v86
	v_cmp_gt_u32_e64 s[78:79], s98, v87
	v_cmp_gt_u32_e64 s[50:51], s98, v88
	v_cndmask_b32_e64 v32, 0, v32, s[30:31]
	v_add_u32_e32 v85, 8, v84
	v_cmp_gt_u32_e64 s[30:31], s98, v85
	v_cndmask_b32_e64 v33, 0, v33, s[36:37]
	v_add_u32_e32 v86, 9, v84
	v_cmp_gt_u32_e64 s[36:37], s98, v86
	v_cndmask_b32_e64 v34, 0, v34, s[78:79]
	v_add_u32_e32 v87, 10, v84
	v_cmp_gt_u32_e64 s[78:79], s98, v87
	v_cndmask_b32_e64 v35, 0, v35, s[50:51]
	v_add_u32_e32 v88, 11, v84
	v_cmp_gt_u32_e64 s[50:51], s98, v88
	v_cndmask_b32_e64 v36, 0, v36, s[30:31]
	v_add_u32_e32 v85, 16, v84
	v_cmp_gt_u32_e64 s[30:31], s98, v85
	v_cndmask_b32_e64 v37, 0, v37, s[36:37]
	v_add_u32_e32 v86, 17, v84
	v_cmp_gt_u32_e64 s[36:37], s98, v86
	v_cndmask_b32_e64 v38, 0, v38, s[78:79]
	v_add_u32_e32 v87, 18, v84
	v_cmp_gt_u32_e64 s[78:79], s98, v87
	v_cndmask_b32_e64 v39, 0, v39, s[50:51]
	v_add_u32_e32 v88, 19, v84
	v_cmp_gt_u32_e64 s[50:51], s98, v88
	v_cndmask_b32_e64 v40, 0, v40, s[30:31]
	v_add_u32_e32 v85, 24, v84
	v_cmp_gt_u32_e64 s[30:31], s98, v85
	v_cndmask_b32_e64 v41, 0, v41, s[36:37]
	v_add_u32_e32 v86, 25, v84
	v_cmp_gt_u32_e64 s[36:37], s98, v86
	v_cndmask_b32_e64 v42, 0, v42, s[78:79]
	v_add_u32_e32 v87, 26, v84
	v_cmp_gt_u32_e64 s[78:79], s98, v87
	v_cndmask_b32_e64 v43, 0, v43, s[50:51]
	v_add_u32_e32 v88, 27, v84
	v_cmp_gt_u32_e64 s[50:51], s98, v88
	v_nop
	v_cndmask_b32_e64 v44, 0, v44, s[30:31]
	v_cndmask_b32_e64 v45, 0, v45, s[36:37]
	v_cndmask_b32_e64 v46, 0, v46, s[78:79]
	v_cndmask_b32_e64 v47, 0, v47, s[50:51]
	v_cvt_pk_bf16_f32 v64, v32, v33
	v_cvt_pk_bf16_f32 v65, v34, v35
	v_cvt_pk_bf16_f32 v66, v36, v37
	v_cvt_pk_bf16_f32 v67, v38, v39
	v_cvt_pk_bf16_f32 v68, v40, v41
	v_cvt_pk_bf16_f32 v69, v42, v43
	v_cvt_pk_bf16_f32 v70, v44, v45
	v_cvt_pk_bf16_f32 v71, v46, v47
	v_pk_add_f32 v[232:233], v[232:233], v[32:33]
	v_pk_add_f32 v[232:233], v[232:233], v[34:35]
	v_pk_add_f32 v[232:233], v[232:233], v[36:37]
	v_pk_add_f32 v[232:233], v[232:233], v[38:39]
	v_pk_add_f32 v[232:233], v[232:233], v[40:41]
	v_pk_add_f32 v[232:233], v[232:233], v[42:43]
	v_pk_add_f32 v[232:233], v[232:233], v[44:45]
	v_pk_add_f32 v[232:233], v[232:233], v[46:47]
	ds_read2_b32 v[32:33], v115 offset0:204 offset1:205
	ds_read2_b32 v[34:35], v115 offset0:206 offset1:207
	ds_read2_b32 v[36:37], v115 offset0:212 offset1:213
	ds_read2_b32 v[38:39], v115 offset0:214 offset1:215
	ds_read2_b32 v[40:41], v115 offset0:221 offset1:222
	ds_read2_b32 v[42:43], v115 offset0:223 offset1:224
	ds_read2_b32 v[44:45], v115 offset0:229 offset1:230
	ds_read2_b32 v[46:47], v115 offset0:231 offset1:232
	s_add_i32 s90, s67, 160
	v_add_u32_e32 v80, s90, v235
	v_add_u32_e32 v83, s90, v236
	v_add_u32_e32 v99, s90, v237
	v_add_u32_e32 v253, s90, v238
	v_add_u32_e32 v254, s90, v100
	v_add_u32_e32 v255, s90, v149
	v_med3_i32 v80, v80, 0, s99
	v_med3_i32 v83, v83, 0, s99
	v_med3_i32 v99, v99, 0, s99
	v_med3_i32 v253, v253, 0, s99
	v_med3_i32 v254, v254, 0, s99
	v_med3_i32 v255, v255, 0, s99
	v_mad_u32_u24 v80, v80, s100, v252
	v_mad_u32_u24 v83, v83, s100, v252
	v_mad_u32_u24 v99, v99, s100, v252
	v_mad_u32_u24 v253, v253, s100, v252
	v_mad_u32_u24 v254, v254, s100, v153
	v_mad_u32_u24 v255, v255, s100, v153
	global_load_dwordx4 v[156:159], v80, s[82:83]
	global_load_dwordx4 v[160:163], v83, s[82:83]
	global_load_dwordx4 v[164:167], v99, s[82:83]
	global_load_dwordx4 v[168:171], v253, s[82:83]
	global_load_dwordx4 v[172:175], v254, s[82:83] offset:768
	global_load_dwordx4 v[176:179], v255, s[82:83] offset:768
	global_load_dwordx4 v[180:183], v254, s[82:83] offset:832
	global_load_dwordx4 v[184:187], v255, s[82:83] offset:832
	ds_read_b64_tr_b16 v[204:205], v231
	ds_read_b64_tr_b16 v[206:207], v231 offset:512
	ds_read_b64_tr_b16 v[208:209], v231 offset:2048
	ds_read_b64_tr_b16 v[210:211], v231 offset:2560
	ds_read_b64_tr_b16 v[212:213], v231 offset:1024
	ds_read_b64_tr_b16 v[214:215], v231 offset:1536
	ds_read_b64_tr_b16 v[216:217], v231 offset:3072
	ds_read_b64_tr_b16 v[218:219], v231 offset:3584
	v_exp_f32_e32 v188, v188
	v_exp_f32_e32 v189, v189
	v_exp_f32_e32 v190, v190
	v_exp_f32_e32 v191, v191
	s_waitcnt vmcnt(8)
	ds_write_b128 v247, v[116:119]
	ds_write_b128 v247, v[120:123] offset:1024
	ds_write_b128 v247, v[124:127] offset:2048
	ds_write_b128 v247, v[128:131] offset:3072
	ds_read_b128 v[116:119], v248
	ds_read_b128 v[120:123], v249
	ds_read_b128 v[124:127], v250
	ds_read_b128 v[128:131], v251
	ds_write_b128 v112, v[132:135]
	ds_write_b128 v112, v[136:139] offset:1024
	ds_write_b128 v112, v[140:143] offset:2048
	ds_write_b128 v112, v[144:147] offset:3072
	v_mfma_f32_32x32x16_bf16 v[0:15], v[64:67], v[72:75], v[0:15]
	v_mfma_f32_32x32x16_bf16 v[16:31], v[64:67], v[76:79], v[16:31]
	v_mfma_f32_32x32x16_bf16 v[0:15], v[68:71], v[220:223], v[0:15]
	v_mfma_f32_32x32x16_bf16 v[16:31], v[68:71], v[224:227], v[16:31]
	v_exp_f32_e32 v192, v192
	v_exp_f32_e32 v193, v193
	v_exp_f32_e32 v194, v194
	v_exp_f32_e32 v195, v195
	s_waitcnt lgkmcnt(4)
	v_mfma_f32_32x32x16_bf16 v[32:47], v[116:119], v[48:51], v[32:47]
	v_exp_f32_e32 v196, v196
	v_exp_f32_e32 v197, v197
	v_mfma_f32_32x32x16_bf16 v[32:47], v[120:123], v[52:55], v[32:47]
	v_exp_f32_e32 v198, v198
	v_exp_f32_e32 v199, v199
	v_mfma_f32_32x32x16_bf16 v[32:47], v[124:127], v[56:59], v[32:47]
	v_exp_f32_e32 v200, v200
	v_exp_f32_e32 v201, v201
	v_mfma_f32_32x32x16_bf16 v[32:47], v[128:131], v[60:63], v[32:47]
	v_exp_f32_e32 v202, v202
	v_exp_f32_e32 v203, v203
	s_add_i32 s90, s67, 96
	v_add_u32_e32 v84, s90, v107
	v_add_u32_e32 v85, 0, v84
	v_add_u32_e32 v86, 1, v84
	v_add_u32_e32 v87, 2, v84
	v_add_u32_e32 v88, 3, v84
	v_cmp_gt_u32_e64 s[30:31], s98, v85
	v_cmp_gt_u32_e64 s[36:37], s98, v86
	v_cmp_gt_u32_e64 s[78:79], s98, v87
	v_cmp_gt_u32_e64 s[50:51], s98, v88
	v_cndmask_b32_e64 v188, 0, v188, s[30:31]
	v_add_u32_e32 v85, 8, v84
	v_cmp_gt_u32_e64 s[30:31], s98, v85
	v_cndmask_b32_e64 v189, 0, v189, s[36:37]
	v_add_u32_e32 v86, 9, v84
	v_cmp_gt_u32_e64 s[36:37], s98, v86
	v_cndmask_b32_e64 v190, 0, v190, s[78:79]
	v_add_u32_e32 v87, 10, v84
	v_cmp_gt_u32_e64 s[78:79], s98, v87
	v_cndmask_b32_e64 v191, 0, v191, s[50:51]
	v_add_u32_e32 v88, 11, v84
	v_cmp_gt_u32_e64 s[50:51], s98, v88
	v_cndmask_b32_e64 v192, 0, v192, s[30:31]
	v_add_u32_e32 v85, 16, v84
	v_cmp_gt_u32_e64 s[30:31], s98, v85
	v_cndmask_b32_e64 v193, 0, v193, s[36:37]
	v_add_u32_e32 v86, 17, v84
	v_cmp_gt_u32_e64 s[36:37], s98, v86
	v_cndmask_b32_e64 v194, 0, v194, s[78:79]
	v_add_u32_e32 v87, 18, v84
	v_cmp_gt_u32_e64 s[78:79], s98, v87
	v_cndmask_b32_e64 v195, 0, v195, s[50:51]
	v_add_u32_e32 v88, 19, v84
	v_cmp_gt_u32_e64 s[50:51], s98, v88
	v_cndmask_b32_e64 v196, 0, v196, s[30:31]
	v_add_u32_e32 v85, 24, v84
	v_cmp_gt_u32_e64 s[30:31], s98, v85
	v_cndmask_b32_e64 v197, 0, v197, s[36:37]
	v_add_u32_e32 v86, 25, v84
	v_cmp_gt_u32_e64 s[36:37], s98, v86
	v_cndmask_b32_e64 v198, 0, v198, s[78:79]
	v_add_u32_e32 v87, 26, v84
	v_cmp_gt_u32_e64 s[78:79], s98, v87
	v_cndmask_b32_e64 v199, 0, v199, s[50:51]
	v_add_u32_e32 v88, 27, v84
	v_cmp_gt_u32_e64 s[50:51], s98, v88
	v_nop
	v_cndmask_b32_e64 v200, 0, v200, s[30:31]
	v_cndmask_b32_e64 v201, 0, v201, s[36:37]
	v_cndmask_b32_e64 v202, 0, v202, s[78:79]
	v_cndmask_b32_e64 v203, 0, v203, s[50:51]
	v_cvt_pk_bf16_f32 v64, v188, v189
	v_cvt_pk_bf16_f32 v65, v190, v191
	v_cvt_pk_bf16_f32 v66, v192, v193
	v_cvt_pk_bf16_f32 v67, v194, v195
	v_cvt_pk_bf16_f32 v68, v196, v197
	v_cvt_pk_bf16_f32 v69, v198, v199
	v_cvt_pk_bf16_f32 v70, v200, v201
	v_cvt_pk_bf16_f32 v71, v202, v203
	v_pk_add_f32 v[232:233], v[232:233], v[188:189]
	v_pk_add_f32 v[232:233], v[232:233], v[190:191]
	v_pk_add_f32 v[232:233], v[232:233], v[192:193]
	v_pk_add_f32 v[232:233], v[232:233], v[194:195]
	v_pk_add_f32 v[232:233], v[232:233], v[196:197]
	v_pk_add_f32 v[232:233], v[232:233], v[198:199]
	v_pk_add_f32 v[232:233], v[232:233], v[200:201]
	v_pk_add_f32 v[232:233], v[232:233], v[202:203]
	v_add_u32_e32 v115, 952, v115
	ds_read2_b32 v[188:189], v115 offset0:0 offset1:1
	ds_read2_b32 v[190:191], v115 offset0:2 offset1:3
	ds_read2_b32 v[192:193], v115 offset0:8 offset1:9
	ds_read2_b32 v[194:195], v115 offset0:10 offset1:11
	ds_read2_b32 v[196:197], v115 offset0:17 offset1:18
	ds_read2_b32 v[198:199], v115 offset0:19 offset1:20
	ds_read2_b32 v[200:201], v115 offset0:25 offset1:26
	ds_read2_b32 v[202:203], v115 offset0:27 offset1:28
	s_add_i32 s90, s67, 192
	v_add_u32_e32 v80, s90, v235
	v_add_u32_e32 v83, s90, v236
	v_add_u32_e32 v99, s90, v237
	v_add_u32_e32 v253, s90, v238
	v_add_u32_e32 v254, s90, v100
	v_add_u32_e32 v255, s90, v149
	v_med3_i32 v80, v80, 0, s99
	v_med3_i32 v83, v83, 0, s99
	v_med3_i32 v99, v99, 0, s99
	v_med3_i32 v253, v253, 0, s99
	v_med3_i32 v254, v254, 0, s99
	v_med3_i32 v255, v255, 0, s99
	v_mad_u32_u24 v80, v80, s100, v252
	v_mad_u32_u24 v83, v83, s100, v252
	v_mad_u32_u24 v99, v99, s100, v252
	v_mad_u32_u24 v253, v253, s100, v252
	v_mad_u32_u24 v254, v254, s100, v153
	v_mad_u32_u24 v255, v255, s100, v153
	global_load_dwordx4 v[116:119], v80, s[82:83]
	global_load_dwordx4 v[120:123], v83, s[82:83]
	global_load_dwordx4 v[124:127], v99, s[82:83]
	global_load_dwordx4 v[128:131], v253, s[82:83]
	global_load_dwordx4 v[132:135], v254, s[82:83] offset:768
	global_load_dwordx4 v[136:139], v255, s[82:83] offset:768
	global_load_dwordx4 v[140:143], v254, s[82:83] offset:832
	global_load_dwordx4 v[144:147], v255, s[82:83] offset:832
	ds_read_b64_tr_b16 v[72:73], v231
	ds_read_b64_tr_b16 v[74:75], v231 offset:512
	ds_read_b64_tr_b16 v[76:77], v231 offset:2048
	ds_read_b64_tr_b16 v[78:79], v231 offset:2560
	ds_read_b64_tr_b16 v[220:221], v231 offset:1024
	ds_read_b64_tr_b16 v[222:223], v231 offset:1536
	ds_read_b64_tr_b16 v[224:225], v231 offset:3072
	ds_read_b64_tr_b16 v[226:227], v231 offset:3584
	v_exp_f32_e32 v32, v32
	v_exp_f32_e32 v33, v33
	v_exp_f32_e32 v34, v34
	v_exp_f32_e32 v35, v35
	s_waitcnt vmcnt(8)
	ds_write_b128 v247, v[156:159]
	ds_write_b128 v247, v[160:163] offset:1024
	ds_write_b128 v247, v[164:167] offset:2048
	ds_write_b128 v247, v[168:171] offset:3072
	ds_read_b128 v[156:159], v248
	ds_read_b128 v[160:163], v249
	ds_read_b128 v[164:167], v250
	ds_read_b128 v[168:171], v251
	ds_write_b128 v112, v[172:175]
	ds_write_b128 v112, v[176:179] offset:1024
	ds_write_b128 v112, v[180:183] offset:2048
	ds_write_b128 v112, v[184:187] offset:3072
	v_mfma_f32_32x32x16_bf16 v[0:15], v[64:67], v[204:207], v[0:15]
	v_mfma_f32_32x32x16_bf16 v[16:31], v[64:67], v[208:211], v[16:31]
	v_mfma_f32_32x32x16_bf16 v[0:15], v[68:71], v[212:215], v[0:15]
	v_mfma_f32_32x32x16_bf16 v[16:31], v[68:71], v[216:219], v[16:31]
	v_exp_f32_e32 v36, v36
	v_exp_f32_e32 v37, v37
	v_exp_f32_e32 v38, v38
	v_exp_f32_e32 v39, v39
	s_waitcnt lgkmcnt(4)
	v_mfma_f32_32x32x16_bf16 v[188:203], v[156:159], v[48:51], v[188:203]
	v_exp_f32_e32 v40, v40
	v_exp_f32_e32 v41, v41
	v_mfma_f32_32x32x16_bf16 v[188:203], v[160:163], v[52:55], v[188:203]
	v_exp_f32_e32 v42, v42
	v_exp_f32_e32 v43, v43
	v_mfma_f32_32x32x16_bf16 v[188:203], v[164:167], v[56:59], v[188:203]
	v_exp_f32_e32 v44, v44
	v_exp_f32_e32 v45, v45
	v_mfma_f32_32x32x16_bf16 v[188:203], v[168:171], v[60:63], v[188:203]
	v_exp_f32_e32 v46, v46
	v_exp_f32_e32 v47, v47
	s_add_i32 s90, s67, 128
	v_add_u32_e32 v84, s90, v107
	v_add_u32_e32 v85, 0, v84
	v_add_u32_e32 v86, 1, v84
	v_add_u32_e32 v87, 2, v84
	v_add_u32_e32 v88, 3, v84
	v_cmp_gt_u32_e64 s[30:31], s98, v85
	v_cmp_gt_u32_e64 s[36:37], s98, v86
	v_cmp_gt_u32_e64 s[78:79], s98, v87
	v_cmp_gt_u32_e64 s[50:51], s98, v88
	v_cndmask_b32_e64 v32, 0, v32, s[30:31]
	v_add_u32_e32 v85, 8, v84
	v_cmp_gt_u32_e64 s[30:31], s98, v85
	v_cndmask_b32_e64 v33, 0, v33, s[36:37]
	v_add_u32_e32 v86, 9, v84
	v_cmp_gt_u32_e64 s[36:37], s98, v86
	v_cndmask_b32_e64 v34, 0, v34, s[78:79]
	v_add_u32_e32 v87, 10, v84
	v_cmp_gt_u32_e64 s[78:79], s98, v87
	v_cndmask_b32_e64 v35, 0, v35, s[50:51]
	v_add_u32_e32 v88, 11, v84
	v_cmp_gt_u32_e64 s[50:51], s98, v88
	v_cndmask_b32_e64 v36, 0, v36, s[30:31]
	v_add_u32_e32 v85, 16, v84
	v_cmp_gt_u32_e64 s[30:31], s98, v85
	v_cndmask_b32_e64 v37, 0, v37, s[36:37]
	v_add_u32_e32 v86, 17, v84
	v_cmp_gt_u32_e64 s[36:37], s98, v86
	v_cndmask_b32_e64 v38, 0, v38, s[78:79]
	v_add_u32_e32 v87, 18, v84
	v_cmp_gt_u32_e64 s[78:79], s98, v87
	v_cndmask_b32_e64 v39, 0, v39, s[50:51]
	v_add_u32_e32 v88, 19, v84
	v_cmp_gt_u32_e64 s[50:51], s98, v88
	v_cndmask_b32_e64 v40, 0, v40, s[30:31]
	v_add_u32_e32 v85, 24, v84
	v_cmp_gt_u32_e64 s[30:31], s98, v85
	v_cndmask_b32_e64 v41, 0, v41, s[36:37]
	v_add_u32_e32 v86, 25, v84
	v_cmp_gt_u32_e64 s[36:37], s98, v86
	v_cndmask_b32_e64 v42, 0, v42, s[78:79]
	v_add_u32_e32 v87, 26, v84
	v_cmp_gt_u32_e64 s[78:79], s98, v87
	v_cndmask_b32_e64 v43, 0, v43, s[50:51]
	v_add_u32_e32 v88, 27, v84
	v_cmp_gt_u32_e64 s[50:51], s98, v88
	v_nop
	v_cndmask_b32_e64 v44, 0, v44, s[30:31]
	v_cndmask_b32_e64 v45, 0, v45, s[36:37]
	v_cndmask_b32_e64 v46, 0, v46, s[78:79]
	v_cndmask_b32_e64 v47, 0, v47, s[50:51]
	v_cvt_pk_bf16_f32 v64, v32, v33
	v_cvt_pk_bf16_f32 v65, v34, v35
	v_cvt_pk_bf16_f32 v66, v36, v37
	v_cvt_pk_bf16_f32 v67, v38, v39
	v_cvt_pk_bf16_f32 v68, v40, v41
	v_cvt_pk_bf16_f32 v69, v42, v43
	v_cvt_pk_bf16_f32 v70, v44, v45
	v_cvt_pk_bf16_f32 v71, v46, v47
	v_pk_add_f32 v[232:233], v[232:233], v[32:33]
	v_pk_add_f32 v[232:233], v[232:233], v[34:35]
	v_pk_add_f32 v[232:233], v[232:233], v[36:37]
	v_pk_add_f32 v[232:233], v[232:233], v[38:39]
	v_pk_add_f32 v[232:233], v[232:233], v[40:41]
	v_pk_add_f32 v[232:233], v[232:233], v[42:43]
	v_pk_add_f32 v[232:233], v[232:233], v[44:45]
	v_pk_add_f32 v[232:233], v[232:233], v[46:47]
	ds_read2_b32 v[32:33], v115 offset0:34 offset1:35
	ds_read2_b32 v[34:35], v115 offset0:36 offset1:37
	ds_read2_b32 v[36:37], v115 offset0:42 offset1:43
	ds_read2_b32 v[38:39], v115 offset0:44 offset1:45
	ds_read2_b32 v[40:41], v115 offset0:51 offset1:52
	ds_read2_b32 v[42:43], v115 offset0:53 offset1:54
	ds_read2_b32 v[44:45], v115 offset0:59 offset1:60
	ds_read2_b32 v[46:47], v115 offset0:61 offset1:62
	s_add_i32 s90, s67, 224
	v_add_u32_e32 v80, s90, v235
	v_add_u32_e32 v83, s90, v236
	v_add_u32_e32 v99, s90, v237
	v_add_u32_e32 v253, s90, v238
	v_add_u32_e32 v254, s90, v100
	v_add_u32_e32 v255, s90, v149
	v_med3_i32 v80, v80, 0, s99
	v_med3_i32 v83, v83, 0, s99
	v_med3_i32 v99, v99, 0, s99
	v_med3_i32 v253, v253, 0, s99
	v_med3_i32 v254, v254, 0, s99
	v_med3_i32 v255, v255, 0, s99
	v_mad_u32_u24 v80, v80, s100, v252
	v_mad_u32_u24 v83, v83, s100, v252
	v_mad_u32_u24 v99, v99, s100, v252
	v_mad_u32_u24 v253, v253, s100, v252
	v_mad_u32_u24 v254, v254, s100, v153
	v_mad_u32_u24 v255, v255, s100, v153
	global_load_dwordx4 v[156:159], v80, s[82:83]
	global_load_dwordx4 v[160:163], v83, s[82:83]
	global_load_dwordx4 v[164:167], v99, s[82:83]
	global_load_dwordx4 v[168:171], v253, s[82:83]
	global_load_dwordx4 v[172:175], v254, s[82:83] offset:768
	global_load_dwordx4 v[176:179], v255, s[82:83] offset:768
	global_load_dwordx4 v[180:183], v254, s[82:83] offset:832
	global_load_dwordx4 v[184:187], v255, s[82:83] offset:832
	ds_read_b64_tr_b16 v[204:205], v231
	ds_read_b64_tr_b16 v[206:207], v231 offset:512
	ds_read_b64_tr_b16 v[208:209], v231 offset:2048
	ds_read_b64_tr_b16 v[210:211], v231 offset:2560
	ds_read_b64_tr_b16 v[212:213], v231 offset:1024
	ds_read_b64_tr_b16 v[214:215], v231 offset:1536
	ds_read_b64_tr_b16 v[216:217], v231 offset:3072
	ds_read_b64_tr_b16 v[218:219], v231 offset:3584
	v_exp_f32_e32 v188, v188
	v_exp_f32_e32 v189, v189
	v_exp_f32_e32 v190, v190
	v_exp_f32_e32 v191, v191
	s_waitcnt vmcnt(8)
	ds_write_b128 v247, v[116:119]
	ds_write_b128 v247, v[120:123] offset:1024
	ds_write_b128 v247, v[124:127] offset:2048
	ds_write_b128 v247, v[128:131] offset:3072
	ds_read_b128 v[116:119], v248
	ds_read_b128 v[120:123], v249
	ds_read_b128 v[124:127], v250
	ds_read_b128 v[128:131], v251
	ds_write_b128 v112, v[132:135]
	ds_write_b128 v112, v[136:139] offset:1024
	ds_write_b128 v112, v[140:143] offset:2048
	ds_write_b128 v112, v[144:147] offset:3072
	v_mfma_f32_32x32x16_bf16 v[0:15], v[64:67], v[72:75], v[0:15]
	v_mfma_f32_32x32x16_bf16 v[16:31], v[64:67], v[76:79], v[16:31]
	v_mfma_f32_32x32x16_bf16 v[0:15], v[68:71], v[220:223], v[0:15]
	v_mfma_f32_32x32x16_bf16 v[16:31], v[68:71], v[224:227], v[16:31]
	v_exp_f32_e32 v192, v192
	v_exp_f32_e32 v193, v193
	v_exp_f32_e32 v194, v194
	v_exp_f32_e32 v195, v195
	s_waitcnt lgkmcnt(4)
	v_mfma_f32_32x32x16_bf16 v[32:47], v[116:119], v[48:51], v[32:47]
	v_exp_f32_e32 v196, v196
	v_exp_f32_e32 v197, v197
	v_mfma_f32_32x32x16_bf16 v[32:47], v[120:123], v[52:55], v[32:47]
	v_exp_f32_e32 v198, v198
	v_exp_f32_e32 v199, v199
	v_mfma_f32_32x32x16_bf16 v[32:47], v[124:127], v[56:59], v[32:47]
	v_exp_f32_e32 v200, v200
	v_exp_f32_e32 v201, v201
	v_mfma_f32_32x32x16_bf16 v[32:47], v[128:131], v[60:63], v[32:47]
	v_exp_f32_e32 v202, v202
	v_exp_f32_e32 v203, v203
	s_add_i32 s90, s67, 160
	v_add_u32_e32 v84, s90, v107
	v_add_u32_e32 v85, 0, v84
	v_add_u32_e32 v86, 1, v84
	v_add_u32_e32 v87, 2, v84
	v_add_u32_e32 v88, 3, v84
	v_cmp_gt_u32_e64 s[30:31], s98, v85
	v_cmp_gt_u32_e64 s[36:37], s98, v86
	v_cmp_gt_u32_e64 s[78:79], s98, v87
	v_cmp_gt_u32_e64 s[50:51], s98, v88
	v_cndmask_b32_e64 v188, 0, v188, s[30:31]
	v_add_u32_e32 v85, 8, v84
	v_cmp_gt_u32_e64 s[30:31], s98, v85
	v_cndmask_b32_e64 v189, 0, v189, s[36:37]
	v_add_u32_e32 v86, 9, v84
	v_cmp_gt_u32_e64 s[36:37], s98, v86
	v_cndmask_b32_e64 v190, 0, v190, s[78:79]
	v_add_u32_e32 v87, 10, v84
	v_cmp_gt_u32_e64 s[78:79], s98, v87
	v_cndmask_b32_e64 v191, 0, v191, s[50:51]
	v_add_u32_e32 v88, 11, v84
	v_cmp_gt_u32_e64 s[50:51], s98, v88
	v_cndmask_b32_e64 v192, 0, v192, s[30:31]
	v_add_u32_e32 v85, 16, v84
	v_cmp_gt_u32_e64 s[30:31], s98, v85
	v_cndmask_b32_e64 v193, 0, v193, s[36:37]
	v_add_u32_e32 v86, 17, v84
	v_cmp_gt_u32_e64 s[36:37], s98, v86
	v_cndmask_b32_e64 v194, 0, v194, s[78:79]
	v_add_u32_e32 v87, 18, v84
	v_cmp_gt_u32_e64 s[78:79], s98, v87
	v_cndmask_b32_e64 v195, 0, v195, s[50:51]
	v_add_u32_e32 v88, 19, v84
	v_cmp_gt_u32_e64 s[50:51], s98, v88
	v_cndmask_b32_e64 v196, 0, v196, s[30:31]
	v_add_u32_e32 v85, 24, v84
	v_cmp_gt_u32_e64 s[30:31], s98, v85
	v_cndmask_b32_e64 v197, 0, v197, s[36:37]
	v_add_u32_e32 v86, 25, v84
	v_cmp_gt_u32_e64 s[36:37], s98, v86
	v_cndmask_b32_e64 v198, 0, v198, s[78:79]
	v_add_u32_e32 v87, 26, v84
	v_cmp_gt_u32_e64 s[78:79], s98, v87
	v_cndmask_b32_e64 v199, 0, v199, s[50:51]
	v_add_u32_e32 v88, 27, v84
	v_cmp_gt_u32_e64 s[50:51], s98, v88
	v_nop
	v_cndmask_b32_e64 v200, 0, v200, s[30:31]
	v_cndmask_b32_e64 v201, 0, v201, s[36:37]
	v_cndmask_b32_e64 v202, 0, v202, s[78:79]
	v_cndmask_b32_e64 v203, 0, v203, s[50:51]
	v_cvt_pk_bf16_f32 v64, v188, v189
	v_cvt_pk_bf16_f32 v65, v190, v191
	v_cvt_pk_bf16_f32 v66, v192, v193
	v_cvt_pk_bf16_f32 v67, v194, v195
	v_cvt_pk_bf16_f32 v68, v196, v197
	v_cvt_pk_bf16_f32 v69, v198, v199
	v_cvt_pk_bf16_f32 v70, v200, v201
	v_cvt_pk_bf16_f32 v71, v202, v203
	v_pk_add_f32 v[232:233], v[232:233], v[188:189]
	v_pk_add_f32 v[232:233], v[232:233], v[190:191]
	v_pk_add_f32 v[232:233], v[232:233], v[192:193]
	v_pk_add_f32 v[232:233], v[232:233], v[194:195]
	v_pk_add_f32 v[232:233], v[232:233], v[196:197]
	v_pk_add_f32 v[232:233], v[232:233], v[198:199]
	v_pk_add_f32 v[232:233], v[232:233], v[200:201]
	v_pk_add_f32 v[232:233], v[232:233], v[202:203]
	ds_read2_b32 v[188:189], v115 offset0:68 offset1:69
	ds_read2_b32 v[190:191], v115 offset0:70 offset1:71
	ds_read2_b32 v[192:193], v115 offset0:76 offset1:77
	ds_read2_b32 v[194:195], v115 offset0:78 offset1:79
	ds_read2_b32 v[196:197], v115 offset0:85 offset1:86
	ds_read2_b32 v[198:199], v115 offset0:87 offset1:88
	ds_read2_b32 v[200:201], v115 offset0:93 offset1:94
	ds_read2_b32 v[202:203], v115 offset0:95 offset1:96
	s_add_i32 s90, s67, 256
	v_add_u32_e32 v80, s90, v235
	v_add_u32_e32 v83, s90, v236
	v_add_u32_e32 v99, s90, v237
	v_add_u32_e32 v253, s90, v238
	v_add_u32_e32 v254, s90, v100
	v_add_u32_e32 v255, s90, v149
	v_med3_i32 v80, v80, 0, s99
	v_med3_i32 v83, v83, 0, s99
	v_med3_i32 v99, v99, 0, s99
	v_med3_i32 v253, v253, 0, s99
	v_med3_i32 v254, v254, 0, s99
	v_med3_i32 v255, v255, 0, s99
	v_mad_u32_u24 v80, v80, s100, v252
	v_mad_u32_u24 v83, v83, s100, v252
	v_mad_u32_u24 v99, v99, s100, v252
	v_mad_u32_u24 v253, v253, s100, v252
	v_mad_u32_u24 v254, v254, s100, v153
	v_mad_u32_u24 v255, v255, s100, v153
	global_load_dwordx4 v[116:119], v80, s[82:83]
	global_load_dwordx4 v[120:123], v83, s[82:83]
	global_load_dwordx4 v[124:127], v99, s[82:83]
	global_load_dwordx4 v[128:131], v253, s[82:83]
	global_load_dwordx4 v[132:135], v254, s[82:83] offset:768
	global_load_dwordx4 v[136:139], v255, s[82:83] offset:768
	global_load_dwordx4 v[140:143], v254, s[82:83] offset:832
	global_load_dwordx4 v[144:147], v255, s[82:83] offset:832
	ds_read_b64_tr_b16 v[72:73], v231
	ds_read_b64_tr_b16 v[74:75], v231 offset:512
	ds_read_b64_tr_b16 v[76:77], v231 offset:2048
	ds_read_b64_tr_b16 v[78:79], v231 offset:2560
	ds_read_b64_tr_b16 v[220:221], v231 offset:1024
	ds_read_b64_tr_b16 v[222:223], v231 offset:1536
	ds_read_b64_tr_b16 v[224:225], v231 offset:3072
	ds_read_b64_tr_b16 v[226:227], v231 offset:3584
	v_exp_f32_e32 v32, v32
	v_exp_f32_e32 v33, v33
	v_exp_f32_e32 v34, v34
	v_exp_f32_e32 v35, v35
	s_waitcnt vmcnt(8)
	ds_write_b128 v247, v[156:159]
	ds_write_b128 v247, v[160:163] offset:1024
	ds_write_b128 v247, v[164:167] offset:2048
	ds_write_b128 v247, v[168:171] offset:3072
	ds_read_b128 v[156:159], v248
	ds_read_b128 v[160:163], v249
	ds_read_b128 v[164:167], v250
	ds_read_b128 v[168:171], v251
	ds_write_b128 v112, v[172:175]
	ds_write_b128 v112, v[176:179] offset:1024
	ds_write_b128 v112, v[180:183] offset:2048
	ds_write_b128 v112, v[184:187] offset:3072
	v_mfma_f32_32x32x16_bf16 v[0:15], v[64:67], v[204:207], v[0:15]
	v_mfma_f32_32x32x16_bf16 v[16:31], v[64:67], v[208:211], v[16:31]
	v_mfma_f32_32x32x16_bf16 v[0:15], v[68:71], v[212:215], v[0:15]
	v_mfma_f32_32x32x16_bf16 v[16:31], v[68:71], v[216:219], v[16:31]
	v_exp_f32_e32 v36, v36
	v_exp_f32_e32 v37, v37
	v_exp_f32_e32 v38, v38
	v_exp_f32_e32 v39, v39
	s_waitcnt lgkmcnt(4)
	v_mfma_f32_32x32x16_bf16 v[188:203], v[156:159], v[48:51], v[188:203]
	v_exp_f32_e32 v40, v40
	v_exp_f32_e32 v41, v41
	v_mfma_f32_32x32x16_bf16 v[188:203], v[160:163], v[52:55], v[188:203]
	v_exp_f32_e32 v42, v42
	v_exp_f32_e32 v43, v43
	v_mfma_f32_32x32x16_bf16 v[188:203], v[164:167], v[56:59], v[188:203]
	v_exp_f32_e32 v44, v44
	v_exp_f32_e32 v45, v45
	v_mfma_f32_32x32x16_bf16 v[188:203], v[168:171], v[60:63], v[188:203]
	v_exp_f32_e32 v46, v46
	v_exp_f32_e32 v47, v47
	s_add_i32 s90, s67, 192
	v_add_u32_e32 v84, s90, v107
	v_add_u32_e32 v85, 0, v84
	v_add_u32_e32 v86, 1, v84
	v_add_u32_e32 v87, 2, v84
	v_add_u32_e32 v88, 3, v84
	v_cmp_gt_u32_e64 s[30:31], s98, v85
	v_cmp_gt_u32_e64 s[36:37], s98, v86
	v_cmp_gt_u32_e64 s[78:79], s98, v87
	v_cmp_gt_u32_e64 s[50:51], s98, v88
	v_cndmask_b32_e64 v32, 0, v32, s[30:31]
	v_add_u32_e32 v85, 8, v84
	v_cmp_gt_u32_e64 s[30:31], s98, v85
	v_cndmask_b32_e64 v33, 0, v33, s[36:37]
	v_add_u32_e32 v86, 9, v84
	v_cmp_gt_u32_e64 s[36:37], s98, v86
	v_cndmask_b32_e64 v34, 0, v34, s[78:79]
	v_add_u32_e32 v87, 10, v84
	v_cmp_gt_u32_e64 s[78:79], s98, v87
	v_cndmask_b32_e64 v35, 0, v35, s[50:51]
	v_add_u32_e32 v88, 11, v84
	v_cmp_gt_u32_e64 s[50:51], s98, v88
	v_cndmask_b32_e64 v36, 0, v36, s[30:31]
	v_add_u32_e32 v85, 16, v84
	v_cmp_gt_u32_e64 s[30:31], s98, v85
	v_cndmask_b32_e64 v37, 0, v37, s[36:37]
	v_add_u32_e32 v86, 17, v84
	v_cmp_gt_u32_e64 s[36:37], s98, v86
	v_cndmask_b32_e64 v38, 0, v38, s[78:79]
	v_add_u32_e32 v87, 18, v84
	v_cmp_gt_u32_e64 s[78:79], s98, v87
	v_cndmask_b32_e64 v39, 0, v39, s[50:51]
	v_add_u32_e32 v88, 19, v84
	v_cmp_gt_u32_e64 s[50:51], s98, v88
	v_cndmask_b32_e64 v40, 0, v40, s[30:31]
	v_add_u32_e32 v85, 24, v84
	v_cmp_gt_u32_e64 s[30:31], s98, v85
	v_cndmask_b32_e64 v41, 0, v41, s[36:37]
	v_add_u32_e32 v86, 25, v84
	v_cmp_gt_u32_e64 s[36:37], s98, v86
	v_cndmask_b32_e64 v42, 0, v42, s[78:79]
	v_add_u32_e32 v87, 26, v84
	v_cmp_gt_u32_e64 s[78:79], s98, v87
	v_cndmask_b32_e64 v43, 0, v43, s[50:51]
	v_add_u32_e32 v88, 27, v84
	v_cmp_gt_u32_e64 s[50:51], s98, v88
	v_nop
	v_cndmask_b32_e64 v44, 0, v44, s[30:31]
	v_cndmask_b32_e64 v45, 0, v45, s[36:37]
	v_cndmask_b32_e64 v46, 0, v46, s[78:79]
	v_cndmask_b32_e64 v47, 0, v47, s[50:51]
	v_cvt_pk_bf16_f32 v64, v32, v33
	v_cvt_pk_bf16_f32 v65, v34, v35
	v_cvt_pk_bf16_f32 v66, v36, v37
	v_cvt_pk_bf16_f32 v67, v38, v39
	v_cvt_pk_bf16_f32 v68, v40, v41
	v_cvt_pk_bf16_f32 v69, v42, v43
	v_cvt_pk_bf16_f32 v70, v44, v45
	v_cvt_pk_bf16_f32 v71, v46, v47
	v_pk_add_f32 v[232:233], v[232:233], v[32:33]
	v_pk_add_f32 v[232:233], v[232:233], v[34:35]
	v_pk_add_f32 v[232:233], v[232:233], v[36:37]
	v_pk_add_f32 v[232:233], v[232:233], v[38:39]
	v_pk_add_f32 v[232:233], v[232:233], v[40:41]
	v_pk_add_f32 v[232:233], v[232:233], v[42:43]
	v_pk_add_f32 v[232:233], v[232:233], v[44:45]
	v_pk_add_f32 v[232:233], v[232:233], v[46:47]
	ds_read2_b32 v[32:33], v115 offset0:102 offset1:103
	ds_read2_b32 v[34:35], v115 offset0:104 offset1:105
	ds_read2_b32 v[36:37], v115 offset0:110 offset1:111
	ds_read2_b32 v[38:39], v115 offset0:112 offset1:113
	ds_read2_b32 v[40:41], v115 offset0:119 offset1:120
	ds_read2_b32 v[42:43], v115 offset0:121 offset1:122
	ds_read2_b32 v[44:45], v115 offset0:127 offset1:128
	ds_read2_b32 v[46:47], v115 offset0:129 offset1:130
	s_add_i32 s90, s67, 288
	v_add_u32_e32 v80, s90, v235
	v_add_u32_e32 v83, s90, v236
	v_add_u32_e32 v99, s90, v237
	v_add_u32_e32 v253, s90, v238
	v_add_u32_e32 v254, s90, v100
	v_add_u32_e32 v255, s90, v149
	v_med3_i32 v80, v80, 0, s99
	v_med3_i32 v83, v83, 0, s99
	v_med3_i32 v99, v99, 0, s99
	v_med3_i32 v253, v253, 0, s99
	v_med3_i32 v254, v254, 0, s99
	v_med3_i32 v255, v255, 0, s99
	v_mad_u32_u24 v80, v80, s100, v252
	v_mad_u32_u24 v83, v83, s100, v252
	v_mad_u32_u24 v99, v99, s100, v252
	v_mad_u32_u24 v253, v253, s100, v252
	v_mad_u32_u24 v254, v254, s100, v153
	v_mad_u32_u24 v255, v255, s100, v153
	global_load_dwordx4 v[156:159], v80, s[82:83]
	global_load_dwordx4 v[160:163], v83, s[82:83]
	global_load_dwordx4 v[164:167], v99, s[82:83]
	global_load_dwordx4 v[168:171], v253, s[82:83]
	global_load_dwordx4 v[172:175], v254, s[82:83] offset:768
	global_load_dwordx4 v[176:179], v255, s[82:83] offset:768
	global_load_dwordx4 v[180:183], v254, s[82:83] offset:832
	global_load_dwordx4 v[184:187], v255, s[82:83] offset:832
	ds_read_b64_tr_b16 v[204:205], v231
	ds_read_b64_tr_b16 v[206:207], v231 offset:512
	ds_read_b64_tr_b16 v[208:209], v231 offset:2048
	ds_read_b64_tr_b16 v[210:211], v231 offset:2560
	ds_read_b64_tr_b16 v[212:213], v231 offset:1024
	ds_read_b64_tr_b16 v[214:215], v231 offset:1536
	ds_read_b64_tr_b16 v[216:217], v231 offset:3072
	ds_read_b64_tr_b16 v[218:219], v231 offset:3584
	v_exp_f32_e32 v188, v188
	v_exp_f32_e32 v189, v189
	v_exp_f32_e32 v190, v190
	v_exp_f32_e32 v191, v191
	s_waitcnt vmcnt(8)
	ds_write_b128 v247, v[116:119]
	ds_write_b128 v247, v[120:123] offset:1024
	ds_write_b128 v247, v[124:127] offset:2048
	ds_write_b128 v247, v[128:131] offset:3072
	ds_read_b128 v[116:119], v248
	ds_read_b128 v[120:123], v249
	ds_read_b128 v[124:127], v250
	ds_read_b128 v[128:131], v251
	ds_write_b128 v112, v[132:135]
	ds_write_b128 v112, v[136:139] offset:1024
	ds_write_b128 v112, v[140:143] offset:2048
	ds_write_b128 v112, v[144:147] offset:3072
	v_mfma_f32_32x32x16_bf16 v[0:15], v[64:67], v[72:75], v[0:15]
	v_mfma_f32_32x32x16_bf16 v[16:31], v[64:67], v[76:79], v[16:31]
	v_mfma_f32_32x32x16_bf16 v[0:15], v[68:71], v[220:223], v[0:15]
	v_mfma_f32_32x32x16_bf16 v[16:31], v[68:71], v[224:227], v[16:31]
	v_exp_f32_e32 v192, v192
	v_exp_f32_e32 v193, v193
	v_exp_f32_e32 v194, v194
	v_exp_f32_e32 v195, v195
	s_waitcnt lgkmcnt(4)
	v_mfma_f32_32x32x16_bf16 v[32:47], v[116:119], v[48:51], v[32:47]
	v_exp_f32_e32 v196, v196
	v_exp_f32_e32 v197, v197
	v_mfma_f32_32x32x16_bf16 v[32:47], v[120:123], v[52:55], v[32:47]
	v_exp_f32_e32 v198, v198
	v_exp_f32_e32 v199, v199
	v_mfma_f32_32x32x16_bf16 v[32:47], v[124:127], v[56:59], v[32:47]
	v_exp_f32_e32 v200, v200
	v_exp_f32_e32 v201, v201
	v_mfma_f32_32x32x16_bf16 v[32:47], v[128:131], v[60:63], v[32:47]
	v_exp_f32_e32 v202, v202
	v_exp_f32_e32 v203, v203
	s_add_i32 s90, s67, 224
	v_add_u32_e32 v84, s90, v107
	v_add_u32_e32 v85, 0, v84
	v_add_u32_e32 v86, 1, v84
	v_add_u32_e32 v87, 2, v84
	v_add_u32_e32 v88, 3, v84
	v_cmp_gt_u32_e64 s[30:31], s98, v85
	v_cmp_gt_u32_e64 s[36:37], s98, v86
	v_cmp_gt_u32_e64 s[78:79], s98, v87
	v_cmp_gt_u32_e64 s[50:51], s98, v88
	v_cndmask_b32_e64 v188, 0, v188, s[30:31]
	v_add_u32_e32 v85, 8, v84
	v_cmp_gt_u32_e64 s[30:31], s98, v85
	v_cndmask_b32_e64 v189, 0, v189, s[36:37]
	v_add_u32_e32 v86, 9, v84
	v_cmp_gt_u32_e64 s[36:37], s98, v86
	v_cndmask_b32_e64 v190, 0, v190, s[78:79]
	v_add_u32_e32 v87, 10, v84
	v_cmp_gt_u32_e64 s[78:79], s98, v87
	v_cndmask_b32_e64 v191, 0, v191, s[50:51]
	v_add_u32_e32 v88, 11, v84
	v_cmp_gt_u32_e64 s[50:51], s98, v88
	v_cndmask_b32_e64 v192, 0, v192, s[30:31]
	v_add_u32_e32 v85, 16, v84
	v_cmp_gt_u32_e64 s[30:31], s98, v85
	v_cndmask_b32_e64 v193, 0, v193, s[36:37]
	v_add_u32_e32 v86, 17, v84
	v_cmp_gt_u32_e64 s[36:37], s98, v86
	v_cndmask_b32_e64 v194, 0, v194, s[78:79]
	v_add_u32_e32 v87, 18, v84
	v_cmp_gt_u32_e64 s[78:79], s98, v87
	v_cndmask_b32_e64 v195, 0, v195, s[50:51]
	v_add_u32_e32 v88, 19, v84
	v_cmp_gt_u32_e64 s[50:51], s98, v88
	v_cndmask_b32_e64 v196, 0, v196, s[30:31]
	v_add_u32_e32 v85, 24, v84
	v_cmp_gt_u32_e64 s[30:31], s98, v85
	v_cndmask_b32_e64 v197, 0, v197, s[36:37]
	v_add_u32_e32 v86, 25, v84
	v_cmp_gt_u32_e64 s[36:37], s98, v86
	v_cndmask_b32_e64 v198, 0, v198, s[78:79]
	v_add_u32_e32 v87, 26, v84
	v_cmp_gt_u32_e64 s[78:79], s98, v87
	v_cndmask_b32_e64 v199, 0, v199, s[50:51]
	v_add_u32_e32 v88, 27, v84
	v_cmp_gt_u32_e64 s[50:51], s98, v88
	v_nop
	v_cndmask_b32_e64 v200, 0, v200, s[30:31]
	v_cndmask_b32_e64 v201, 0, v201, s[36:37]
	v_cndmask_b32_e64 v202, 0, v202, s[78:79]
	v_cndmask_b32_e64 v203, 0, v203, s[50:51]
	v_cvt_pk_bf16_f32 v64, v188, v189
	v_cvt_pk_bf16_f32 v65, v190, v191
	v_cvt_pk_bf16_f32 v66, v192, v193
	v_cvt_pk_bf16_f32 v67, v194, v195
	v_cvt_pk_bf16_f32 v68, v196, v197
	v_cvt_pk_bf16_f32 v69, v198, v199
	v_cvt_pk_bf16_f32 v70, v200, v201
	v_cvt_pk_bf16_f32 v71, v202, v203
	v_pk_add_f32 v[232:233], v[232:233], v[188:189]
	v_pk_add_f32 v[232:233], v[232:233], v[190:191]
	v_pk_add_f32 v[232:233], v[232:233], v[192:193]
	v_pk_add_f32 v[232:233], v[232:233], v[194:195]
	v_pk_add_f32 v[232:233], v[232:233], v[196:197]
	v_pk_add_f32 v[232:233], v[232:233], v[198:199]
	v_pk_add_f32 v[232:233], v[232:233], v[200:201]
	v_pk_add_f32 v[232:233], v[232:233], v[202:203]
	ds_read2_b32 v[188:189], v115 offset0:136 offset1:137
	ds_read2_b32 v[190:191], v115 offset0:138 offset1:139
	ds_read2_b32 v[192:193], v115 offset0:144 offset1:145
	ds_read2_b32 v[194:195], v115 offset0:146 offset1:147
	ds_read2_b32 v[196:197], v115 offset0:153 offset1:154
	ds_read2_b32 v[198:199], v115 offset0:155 offset1:156
	ds_read2_b32 v[200:201], v115 offset0:161 offset1:162
	ds_read2_b32 v[202:203], v115 offset0:163 offset1:164
	s_add_i32 s90, s67, 320
	v_add_u32_e32 v80, s90, v235
	v_add_u32_e32 v83, s90, v236
	v_add_u32_e32 v99, s90, v237
	v_add_u32_e32 v253, s90, v238
	v_add_u32_e32 v254, s90, v100
	v_add_u32_e32 v255, s90, v149
	v_med3_i32 v80, v80, 0, s99
	v_med3_i32 v83, v83, 0, s99
	v_med3_i32 v99, v99, 0, s99
	v_med3_i32 v253, v253, 0, s99
	v_med3_i32 v254, v254, 0, s99
	v_med3_i32 v255, v255, 0, s99
	v_mad_u32_u24 v80, v80, s100, v252
	v_mad_u32_u24 v83, v83, s100, v252
	v_mad_u32_u24 v99, v99, s100, v252
	v_mad_u32_u24 v253, v253, s100, v252
	v_mad_u32_u24 v254, v254, s100, v153
	v_mad_u32_u24 v255, v255, s100, v153
	global_load_dwordx4 v[116:119], v80, s[82:83]
	global_load_dwordx4 v[120:123], v83, s[82:83]
	global_load_dwordx4 v[124:127], v99, s[82:83]
	global_load_dwordx4 v[128:131], v253, s[82:83]
	global_load_dwordx4 v[132:135], v254, s[82:83] offset:768
	global_load_dwordx4 v[136:139], v255, s[82:83] offset:768
	global_load_dwordx4 v[140:143], v254, s[82:83] offset:832
	global_load_dwordx4 v[144:147], v255, s[82:83] offset:832
	ds_read_b64_tr_b16 v[72:73], v231
	ds_read_b64_tr_b16 v[74:75], v231 offset:512
	ds_read_b64_tr_b16 v[76:77], v231 offset:2048
	ds_read_b64_tr_b16 v[78:79], v231 offset:2560
	ds_read_b64_tr_b16 v[220:221], v231 offset:1024
	ds_read_b64_tr_b16 v[222:223], v231 offset:1536
	ds_read_b64_tr_b16 v[224:225], v231 offset:3072
	ds_read_b64_tr_b16 v[226:227], v231 offset:3584
	v_exp_f32_e32 v32, v32
	v_exp_f32_e32 v33, v33
	v_exp_f32_e32 v34, v34
	v_exp_f32_e32 v35, v35
	s_waitcnt vmcnt(8)
	ds_write_b128 v247, v[156:159]
	ds_write_b128 v247, v[160:163] offset:1024
	ds_write_b128 v247, v[164:167] offset:2048
	ds_write_b128 v247, v[168:171] offset:3072
	ds_read_b128 v[156:159], v248
	ds_read_b128 v[160:163], v249
	ds_read_b128 v[164:167], v250
	ds_read_b128 v[168:171], v251
	ds_write_b128 v112, v[172:175]
	ds_write_b128 v112, v[176:179] offset:1024
	ds_write_b128 v112, v[180:183] offset:2048
	ds_write_b128 v112, v[184:187] offset:3072
	v_mfma_f32_32x32x16_bf16 v[0:15], v[64:67], v[204:207], v[0:15]
	v_mfma_f32_32x32x16_bf16 v[16:31], v[64:67], v[208:211], v[16:31]
	v_mfma_f32_32x32x16_bf16 v[0:15], v[68:71], v[212:215], v[0:15]
	v_mfma_f32_32x32x16_bf16 v[16:31], v[68:71], v[216:219], v[16:31]
	v_exp_f32_e32 v36, v36
	v_exp_f32_e32 v37, v37
	v_exp_f32_e32 v38, v38
	v_exp_f32_e32 v39, v39
	s_waitcnt lgkmcnt(4)
	v_mfma_f32_32x32x16_bf16 v[188:203], v[156:159], v[48:51], v[188:203]
	v_exp_f32_e32 v40, v40
	v_exp_f32_e32 v41, v41
	v_mfma_f32_32x32x16_bf16 v[188:203], v[160:163], v[52:55], v[188:203]
	v_exp_f32_e32 v42, v42
	v_exp_f32_e32 v43, v43
	v_mfma_f32_32x32x16_bf16 v[188:203], v[164:167], v[56:59], v[188:203]
	v_exp_f32_e32 v44, v44
	v_exp_f32_e32 v45, v45
	v_mfma_f32_32x32x16_bf16 v[188:203], v[168:171], v[60:63], v[188:203]
	v_exp_f32_e32 v46, v46
	v_exp_f32_e32 v47, v47
	s_add_i32 s90, s67, 256
	v_add_u32_e32 v84, s90, v107
	v_add_u32_e32 v85, 0, v84
	v_add_u32_e32 v86, 1, v84
	v_add_u32_e32 v87, 2, v84
	v_add_u32_e32 v88, 3, v84
	v_cmp_gt_u32_e64 s[30:31], s98, v85
	v_cmp_gt_u32_e64 s[36:37], s98, v86
	v_cmp_gt_u32_e64 s[78:79], s98, v87
	v_cmp_gt_u32_e64 s[50:51], s98, v88
	v_cndmask_b32_e64 v32, 0, v32, s[30:31]
	v_add_u32_e32 v85, 8, v84
	v_cmp_gt_u32_e64 s[30:31], s98, v85
	v_cndmask_b32_e64 v33, 0, v33, s[36:37]
	v_add_u32_e32 v86, 9, v84
	v_cmp_gt_u32_e64 s[36:37], s98, v86
	v_cndmask_b32_e64 v34, 0, v34, s[78:79]
	v_add_u32_e32 v87, 10, v84
	v_cmp_gt_u32_e64 s[78:79], s98, v87
	v_cndmask_b32_e64 v35, 0, v35, s[50:51]
	v_add_u32_e32 v88, 11, v84
	v_cmp_gt_u32_e64 s[50:51], s98, v88
	v_cndmask_b32_e64 v36, 0, v36, s[30:31]
	v_add_u32_e32 v85, 16, v84
	v_cmp_gt_u32_e64 s[30:31], s98, v85
	v_cndmask_b32_e64 v37, 0, v37, s[36:37]
	v_add_u32_e32 v86, 17, v84
	v_cmp_gt_u32_e64 s[36:37], s98, v86
	v_cndmask_b32_e64 v38, 0, v38, s[78:79]
	v_add_u32_e32 v87, 18, v84
	v_cmp_gt_u32_e64 s[78:79], s98, v87
	v_cndmask_b32_e64 v39, 0, v39, s[50:51]
	v_add_u32_e32 v88, 19, v84
	v_cmp_gt_u32_e64 s[50:51], s98, v88
	v_cndmask_b32_e64 v40, 0, v40, s[30:31]
	v_add_u32_e32 v85, 24, v84
	v_cmp_gt_u32_e64 s[30:31], s98, v85
	v_cndmask_b32_e64 v41, 0, v41, s[36:37]
	v_add_u32_e32 v86, 25, v84
	v_cmp_gt_u32_e64 s[36:37], s98, v86
	v_cndmask_b32_e64 v42, 0, v42, s[78:79]
	v_add_u32_e32 v87, 26, v84
	v_cmp_gt_u32_e64 s[78:79], s98, v87
	v_cndmask_b32_e64 v43, 0, v43, s[50:51]
	v_add_u32_e32 v88, 27, v84
	v_cmp_gt_u32_e64 s[50:51], s98, v88
	v_nop
	v_cndmask_b32_e64 v44, 0, v44, s[30:31]
	v_cndmask_b32_e64 v45, 0, v45, s[36:37]
	v_cndmask_b32_e64 v46, 0, v46, s[78:79]
	v_cndmask_b32_e64 v47, 0, v47, s[50:51]
	v_cvt_pk_bf16_f32 v64, v32, v33
	v_cvt_pk_bf16_f32 v65, v34, v35
	v_cvt_pk_bf16_f32 v66, v36, v37
	v_cvt_pk_bf16_f32 v67, v38, v39
	v_cvt_pk_bf16_f32 v68, v40, v41
	v_cvt_pk_bf16_f32 v69, v42, v43
	v_cvt_pk_bf16_f32 v70, v44, v45
	v_cvt_pk_bf16_f32 v71, v46, v47
	v_pk_add_f32 v[232:233], v[232:233], v[32:33]
	v_pk_add_f32 v[232:233], v[232:233], v[34:35]
	v_pk_add_f32 v[232:233], v[232:233], v[36:37]
	v_pk_add_f32 v[232:233], v[232:233], v[38:39]
	v_pk_add_f32 v[232:233], v[232:233], v[40:41]
	v_pk_add_f32 v[232:233], v[232:233], v[42:43]
	v_pk_add_f32 v[232:233], v[232:233], v[44:45]
	v_pk_add_f32 v[232:233], v[232:233], v[46:47]
	ds_read2_b32 v[32:33], v115 offset0:170 offset1:171
	ds_read2_b32 v[34:35], v115 offset0:172 offset1:173
	ds_read2_b32 v[36:37], v115 offset0:178 offset1:179
	ds_read2_b32 v[38:39], v115 offset0:180 offset1:181
	ds_read2_b32 v[40:41], v115 offset0:187 offset1:188
	ds_read2_b32 v[42:43], v115 offset0:189 offset1:190
	ds_read2_b32 v[44:45], v115 offset0:195 offset1:196
	ds_read2_b32 v[46:47], v115 offset0:197 offset1:198
	s_add_i32 s90, s67, 352
	v_add_u32_e32 v80, s90, v235
	v_add_u32_e32 v83, s90, v236
	v_add_u32_e32 v99, s90, v237
	v_add_u32_e32 v253, s90, v238
	v_add_u32_e32 v254, s90, v100
	v_add_u32_e32 v255, s90, v149
	v_med3_i32 v80, v80, 0, s99
	v_med3_i32 v83, v83, 0, s99
	v_med3_i32 v99, v99, 0, s99
	v_med3_i32 v253, v253, 0, s99
	v_med3_i32 v254, v254, 0, s99
	v_med3_i32 v255, v255, 0, s99
	v_mad_u32_u24 v80, v80, s100, v252
	v_mad_u32_u24 v83, v83, s100, v252
	v_mad_u32_u24 v99, v99, s100, v252
	v_mad_u32_u24 v253, v253, s100, v252
	v_mad_u32_u24 v254, v254, s100, v153
	v_mad_u32_u24 v255, v255, s100, v153
	global_load_dwordx4 v[156:159], v80, s[82:83]
	global_load_dwordx4 v[160:163], v83, s[82:83]
	global_load_dwordx4 v[164:167], v99, s[82:83]
	global_load_dwordx4 v[168:171], v253, s[82:83]
	global_load_dwordx4 v[172:175], v254, s[82:83] offset:768
	global_load_dwordx4 v[176:179], v255, s[82:83] offset:768
	global_load_dwordx4 v[180:183], v254, s[82:83] offset:832
	global_load_dwordx4 v[184:187], v255, s[82:83] offset:832
	ds_read_b64_tr_b16 v[204:205], v231
	ds_read_b64_tr_b16 v[206:207], v231 offset:512
	ds_read_b64_tr_b16 v[208:209], v231 offset:2048
	ds_read_b64_tr_b16 v[210:211], v231 offset:2560
	ds_read_b64_tr_b16 v[212:213], v231 offset:1024
	ds_read_b64_tr_b16 v[214:215], v231 offset:1536
	ds_read_b64_tr_b16 v[216:217], v231 offset:3072
	ds_read_b64_tr_b16 v[218:219], v231 offset:3584
	v_exp_f32_e32 v188, v188
	v_exp_f32_e32 v189, v189
	v_exp_f32_e32 v190, v190
	v_exp_f32_e32 v191, v191
	s_waitcnt vmcnt(8)
	ds_write_b128 v247, v[116:119]
	ds_write_b128 v247, v[120:123] offset:1024
	ds_write_b128 v247, v[124:127] offset:2048
	ds_write_b128 v247, v[128:131] offset:3072
	ds_read_b128 v[116:119], v248
	ds_read_b128 v[120:123], v249
	ds_read_b128 v[124:127], v250
	ds_read_b128 v[128:131], v251
	ds_write_b128 v112, v[132:135]
	ds_write_b128 v112, v[136:139] offset:1024
	ds_write_b128 v112, v[140:143] offset:2048
	ds_write_b128 v112, v[144:147] offset:3072
	v_mfma_f32_32x32x16_bf16 v[0:15], v[64:67], v[72:75], v[0:15]
	v_mfma_f32_32x32x16_bf16 v[16:31], v[64:67], v[76:79], v[16:31]
	v_mfma_f32_32x32x16_bf16 v[0:15], v[68:71], v[220:223], v[0:15]
	v_mfma_f32_32x32x16_bf16 v[16:31], v[68:71], v[224:227], v[16:31]
	v_exp_f32_e32 v192, v192
	v_exp_f32_e32 v193, v193
	v_exp_f32_e32 v194, v194
	v_exp_f32_e32 v195, v195
	s_waitcnt lgkmcnt(4)
	v_mfma_f32_32x32x16_bf16 v[32:47], v[116:119], v[48:51], v[32:47]
	v_exp_f32_e32 v196, v196
	v_exp_f32_e32 v197, v197
	v_mfma_f32_32x32x16_bf16 v[32:47], v[120:123], v[52:55], v[32:47]
	v_exp_f32_e32 v198, v198
	v_exp_f32_e32 v199, v199
	v_mfma_f32_32x32x16_bf16 v[32:47], v[124:127], v[56:59], v[32:47]
	v_exp_f32_e32 v200, v200
	v_exp_f32_e32 v201, v201
	v_mfma_f32_32x32x16_bf16 v[32:47], v[128:131], v[60:63], v[32:47]
	v_exp_f32_e32 v202, v202
	v_exp_f32_e32 v203, v203
	s_add_i32 s90, s67, 288
	v_add_u32_e32 v84, s90, v107
	v_add_u32_e32 v85, 0, v84
	v_add_u32_e32 v86, 1, v84
	v_add_u32_e32 v87, 2, v84
	v_add_u32_e32 v88, 3, v84
	v_cmp_gt_u32_e64 s[30:31], s98, v85
	v_cmp_gt_u32_e64 s[36:37], s98, v86
	v_cmp_gt_u32_e64 s[78:79], s98, v87
	v_cmp_gt_u32_e64 s[50:51], s98, v88
	v_cndmask_b32_e64 v188, 0, v188, s[30:31]
	v_add_u32_e32 v85, 8, v84
	v_cmp_gt_u32_e64 s[30:31], s98, v85
	v_cndmask_b32_e64 v189, 0, v189, s[36:37]
	v_add_u32_e32 v86, 9, v84
	v_cmp_gt_u32_e64 s[36:37], s98, v86
	v_cndmask_b32_e64 v190, 0, v190, s[78:79]
	v_add_u32_e32 v87, 10, v84
	v_cmp_gt_u32_e64 s[78:79], s98, v87
	v_cndmask_b32_e64 v191, 0, v191, s[50:51]
	v_add_u32_e32 v88, 11, v84
	v_cmp_gt_u32_e64 s[50:51], s98, v88
	v_cndmask_b32_e64 v192, 0, v192, s[30:31]
	v_add_u32_e32 v85, 16, v84
	v_cmp_gt_u32_e64 s[30:31], s98, v85
	v_cndmask_b32_e64 v193, 0, v193, s[36:37]
	v_add_u32_e32 v86, 17, v84
	v_cmp_gt_u32_e64 s[36:37], s98, v86
	v_cndmask_b32_e64 v194, 0, v194, s[78:79]
	v_add_u32_e32 v87, 18, v84
	v_cmp_gt_u32_e64 s[78:79], s98, v87
	v_cndmask_b32_e64 v195, 0, v195, s[50:51]
	v_add_u32_e32 v88, 19, v84
	v_cmp_gt_u32_e64 s[50:51], s98, v88
	v_cndmask_b32_e64 v196, 0, v196, s[30:31]
	v_add_u32_e32 v85, 24, v84
	v_cmp_gt_u32_e64 s[30:31], s98, v85
	v_cndmask_b32_e64 v197, 0, v197, s[36:37]
	v_add_u32_e32 v86, 25, v84
	v_cmp_gt_u32_e64 s[36:37], s98, v86
	v_cndmask_b32_e64 v198, 0, v198, s[78:79]
	v_add_u32_e32 v87, 26, v84
	v_cmp_gt_u32_e64 s[78:79], s98, v87
	v_cndmask_b32_e64 v199, 0, v199, s[50:51]
	v_add_u32_e32 v88, 27, v84
	v_cmp_gt_u32_e64 s[50:51], s98, v88
	v_nop
	v_cndmask_b32_e64 v200, 0, v200, s[30:31]
	v_cndmask_b32_e64 v201, 0, v201, s[36:37]
	v_cndmask_b32_e64 v202, 0, v202, s[78:79]
	v_cndmask_b32_e64 v203, 0, v203, s[50:51]
	v_cvt_pk_bf16_f32 v64, v188, v189
	v_cvt_pk_bf16_f32 v65, v190, v191
	v_cvt_pk_bf16_f32 v66, v192, v193
	v_cvt_pk_bf16_f32 v67, v194, v195
	v_cvt_pk_bf16_f32 v68, v196, v197
	v_cvt_pk_bf16_f32 v69, v198, v199
	v_cvt_pk_bf16_f32 v70, v200, v201
	v_cvt_pk_bf16_f32 v71, v202, v203
	v_pk_add_f32 v[232:233], v[232:233], v[188:189]
	v_pk_add_f32 v[232:233], v[232:233], v[190:191]
	v_pk_add_f32 v[232:233], v[232:233], v[192:193]
	v_pk_add_f32 v[232:233], v[232:233], v[194:195]
	v_pk_add_f32 v[232:233], v[232:233], v[196:197]
	v_pk_add_f32 v[232:233], v[232:233], v[198:199]
	v_pk_add_f32 v[232:233], v[232:233], v[200:201]
	v_pk_add_f32 v[232:233], v[232:233], v[202:203]
	ds_read2_b32 v[188:189], v115 offset0:204 offset1:205
	ds_read2_b32 v[190:191], v115 offset0:206 offset1:207
	ds_read2_b32 v[192:193], v115 offset0:212 offset1:213
	ds_read2_b32 v[194:195], v115 offset0:214 offset1:215
	ds_read2_b32 v[196:197], v115 offset0:221 offset1:222
	ds_read2_b32 v[198:199], v115 offset0:223 offset1:224
	ds_read2_b32 v[200:201], v115 offset0:229 offset1:230
	ds_read2_b32 v[202:203], v115 offset0:231 offset1:232
	s_add_i32 s90, s67, 384
	v_add_u32_e32 v80, s90, v235
	v_add_u32_e32 v83, s90, v236
	v_add_u32_e32 v99, s90, v237
	v_add_u32_e32 v253, s90, v238
	v_add_u32_e32 v254, s90, v100
	v_add_u32_e32 v255, s90, v149
	v_med3_i32 v80, v80, 0, s99
	v_med3_i32 v83, v83, 0, s99
	v_med3_i32 v99, v99, 0, s99
	v_med3_i32 v253, v253, 0, s99
	v_med3_i32 v254, v254, 0, s99
	v_med3_i32 v255, v255, 0, s99
	v_mad_u32_u24 v80, v80, s100, v252
	v_mad_u32_u24 v83, v83, s100, v252
	v_mad_u32_u24 v99, v99, s100, v252
	v_mad_u32_u24 v253, v253, s100, v252
	v_mad_u32_u24 v254, v254, s100, v153
	v_mad_u32_u24 v255, v255, s100, v153
	global_load_dwordx4 v[116:119], v80, s[82:83]
	global_load_dwordx4 v[120:123], v83, s[82:83]
	global_load_dwordx4 v[124:127], v99, s[82:83]
	global_load_dwordx4 v[128:131], v253, s[82:83]
	global_load_dwordx4 v[132:135], v254, s[82:83] offset:768
	global_load_dwordx4 v[136:139], v255, s[82:83] offset:768
	global_load_dwordx4 v[140:143], v254, s[82:83] offset:832
	global_load_dwordx4 v[144:147], v255, s[82:83] offset:832
	ds_read_b64_tr_b16 v[72:73], v231
	ds_read_b64_tr_b16 v[74:75], v231 offset:512
	ds_read_b64_tr_b16 v[76:77], v231 offset:2048
	ds_read_b64_tr_b16 v[78:79], v231 offset:2560
	ds_read_b64_tr_b16 v[220:221], v231 offset:1024
	ds_read_b64_tr_b16 v[222:223], v231 offset:1536
	ds_read_b64_tr_b16 v[224:225], v231 offset:3072
	ds_read_b64_tr_b16 v[226:227], v231 offset:3584
	v_exp_f32_e32 v32, v32
	v_exp_f32_e32 v33, v33
	v_exp_f32_e32 v34, v34
	v_exp_f32_e32 v35, v35
	s_waitcnt vmcnt(8)
	ds_write_b128 v247, v[156:159]
	ds_write_b128 v247, v[160:163] offset:1024
	ds_write_b128 v247, v[164:167] offset:2048
	ds_write_b128 v247, v[168:171] offset:3072
	ds_read_b128 v[156:159], v248
	ds_read_b128 v[160:163], v249
	ds_read_b128 v[164:167], v250
	ds_read_b128 v[168:171], v251
	ds_write_b128 v112, v[172:175]
	ds_write_b128 v112, v[176:179] offset:1024
	ds_write_b128 v112, v[180:183] offset:2048
	ds_write_b128 v112, v[184:187] offset:3072
	v_mfma_f32_32x32x16_bf16 v[0:15], v[64:67], v[204:207], v[0:15]
	v_mfma_f32_32x32x16_bf16 v[16:31], v[64:67], v[208:211], v[16:31]
	v_mfma_f32_32x32x16_bf16 v[0:15], v[68:71], v[212:215], v[0:15]
	v_mfma_f32_32x32x16_bf16 v[16:31], v[68:71], v[216:219], v[16:31]
	v_exp_f32_e32 v36, v36
	v_exp_f32_e32 v37, v37
	v_exp_f32_e32 v38, v38
	v_exp_f32_e32 v39, v39
	s_waitcnt lgkmcnt(4)
	v_mfma_f32_32x32x16_bf16 v[188:203], v[156:159], v[48:51], v[188:203]
	v_exp_f32_e32 v40, v40
	v_exp_f32_e32 v41, v41
	v_mfma_f32_32x32x16_bf16 v[188:203], v[160:163], v[52:55], v[188:203]
	v_exp_f32_e32 v42, v42
	v_exp_f32_e32 v43, v43
	v_mfma_f32_32x32x16_bf16 v[188:203], v[164:167], v[56:59], v[188:203]
	v_exp_f32_e32 v44, v44
	v_exp_f32_e32 v45, v45
	v_mfma_f32_32x32x16_bf16 v[188:203], v[168:171], v[60:63], v[188:203]
	v_exp_f32_e32 v46, v46
	v_exp_f32_e32 v47, v47
	s_add_i32 s90, s67, 320
	v_add_u32_e32 v84, s90, v107
	v_add_u32_e32 v85, 0, v84
	v_add_u32_e32 v86, 1, v84
	v_add_u32_e32 v87, 2, v84
	v_add_u32_e32 v88, 3, v84
	v_cmp_gt_u32_e64 s[30:31], s98, v85
	v_cmp_gt_u32_e64 s[36:37], s98, v86
	v_cmp_gt_u32_e64 s[78:79], s98, v87
	v_cmp_gt_u32_e64 s[50:51], s98, v88
	v_cndmask_b32_e64 v32, 0, v32, s[30:31]
	v_add_u32_e32 v85, 8, v84
	v_cmp_gt_u32_e64 s[30:31], s98, v85
	v_cndmask_b32_e64 v33, 0, v33, s[36:37]
	v_add_u32_e32 v86, 9, v84
	v_cmp_gt_u32_e64 s[36:37], s98, v86
	v_cndmask_b32_e64 v34, 0, v34, s[78:79]
	v_add_u32_e32 v87, 10, v84
	v_cmp_gt_u32_e64 s[78:79], s98, v87
	v_cndmask_b32_e64 v35, 0, v35, s[50:51]
	v_add_u32_e32 v88, 11, v84
	v_cmp_gt_u32_e64 s[50:51], s98, v88
	v_cndmask_b32_e64 v36, 0, v36, s[30:31]
	v_add_u32_e32 v85, 16, v84
	v_cmp_gt_u32_e64 s[30:31], s98, v85
	v_cndmask_b32_e64 v37, 0, v37, s[36:37]
	v_add_u32_e32 v86, 17, v84
	v_cmp_gt_u32_e64 s[36:37], s98, v86
	v_cndmask_b32_e64 v38, 0, v38, s[78:79]
	v_add_u32_e32 v87, 18, v84
	v_cmp_gt_u32_e64 s[78:79], s98, v87
	v_cndmask_b32_e64 v39, 0, v39, s[50:51]
	v_add_u32_e32 v88, 19, v84
	v_cmp_gt_u32_e64 s[50:51], s98, v88
	v_cndmask_b32_e64 v40, 0, v40, s[30:31]
	v_add_u32_e32 v85, 24, v84
	v_cmp_gt_u32_e64 s[30:31], s98, v85
	v_cndmask_b32_e64 v41, 0, v41, s[36:37]
	v_add_u32_e32 v86, 25, v84
	v_cmp_gt_u32_e64 s[36:37], s98, v86
	v_cndmask_b32_e64 v42, 0, v42, s[78:79]
	v_add_u32_e32 v87, 26, v84
	v_cmp_gt_u32_e64 s[78:79], s98, v87
	v_cndmask_b32_e64 v43, 0, v43, s[50:51]
	v_add_u32_e32 v88, 27, v84
	v_cmp_gt_u32_e64 s[50:51], s98, v88
	v_nop
	v_cndmask_b32_e64 v44, 0, v44, s[30:31]
	v_cndmask_b32_e64 v45, 0, v45, s[36:37]
	v_cndmask_b32_e64 v46, 0, v46, s[78:79]
	v_cndmask_b32_e64 v47, 0, v47, s[50:51]
	v_cvt_pk_bf16_f32 v64, v32, v33
	v_cvt_pk_bf16_f32 v65, v34, v35
	v_cvt_pk_bf16_f32 v66, v36, v37
	v_cvt_pk_bf16_f32 v67, v38, v39
	v_cvt_pk_bf16_f32 v68, v40, v41
	v_cvt_pk_bf16_f32 v69, v42, v43
	v_cvt_pk_bf16_f32 v70, v44, v45
	v_cvt_pk_bf16_f32 v71, v46, v47
	v_pk_add_f32 v[232:233], v[232:233], v[32:33]
	v_pk_add_f32 v[232:233], v[232:233], v[34:35]
	v_pk_add_f32 v[232:233], v[232:233], v[36:37]
	v_pk_add_f32 v[232:233], v[232:233], v[38:39]
	v_pk_add_f32 v[232:233], v[232:233], v[40:41]
	v_pk_add_f32 v[232:233], v[232:233], v[42:43]
	v_pk_add_f32 v[232:233], v[232:233], v[44:45]
	v_pk_add_f32 v[232:233], v[232:233], v[46:47]
	v_add_u32_e32 v115, 952, v115
	ds_read2_b32 v[32:33], v115 offset0:0 offset1:1
	ds_read2_b32 v[34:35], v115 offset0:2 offset1:3
	ds_read2_b32 v[36:37], v115 offset0:8 offset1:9
	ds_read2_b32 v[38:39], v115 offset0:10 offset1:11
	ds_read2_b32 v[40:41], v115 offset0:17 offset1:18
	ds_read2_b32 v[42:43], v115 offset0:19 offset1:20
	ds_read2_b32 v[44:45], v115 offset0:25 offset1:26
	ds_read2_b32 v[46:47], v115 offset0:27 offset1:28
	s_add_i32 s90, s67, 416
	v_add_u32_e32 v80, s90, v235
	v_add_u32_e32 v83, s90, v236
	v_add_u32_e32 v99, s90, v237
	v_add_u32_e32 v253, s90, v238
	v_add_u32_e32 v254, s90, v100
	v_add_u32_e32 v255, s90, v149
	v_med3_i32 v80, v80, 0, s99
	v_med3_i32 v83, v83, 0, s99
	v_med3_i32 v99, v99, 0, s99
	v_med3_i32 v253, v253, 0, s99
	v_med3_i32 v254, v254, 0, s99
	v_med3_i32 v255, v255, 0, s99
	v_mad_u32_u24 v80, v80, s100, v252
	v_mad_u32_u24 v83, v83, s100, v252
	v_mad_u32_u24 v99, v99, s100, v252
	v_mad_u32_u24 v253, v253, s100, v252
	v_mad_u32_u24 v254, v254, s100, v153
	v_mad_u32_u24 v255, v255, s100, v153
	global_load_dwordx4 v[156:159], v80, s[82:83]
	global_load_dwordx4 v[160:163], v83, s[82:83]
	global_load_dwordx4 v[164:167], v99, s[82:83]
	global_load_dwordx4 v[168:171], v253, s[82:83]
	global_load_dwordx4 v[172:175], v254, s[82:83] offset:768
	global_load_dwordx4 v[176:179], v255, s[82:83] offset:768
	global_load_dwordx4 v[180:183], v254, s[82:83] offset:832
	global_load_dwordx4 v[184:187], v255, s[82:83] offset:832
	ds_read_b64_tr_b16 v[204:205], v231
	ds_read_b64_tr_b16 v[206:207], v231 offset:512
	ds_read_b64_tr_b16 v[208:209], v231 offset:2048
	ds_read_b64_tr_b16 v[210:211], v231 offset:2560
	ds_read_b64_tr_b16 v[212:213], v231 offset:1024
	ds_read_b64_tr_b16 v[214:215], v231 offset:1536
	ds_read_b64_tr_b16 v[216:217], v231 offset:3072
	ds_read_b64_tr_b16 v[218:219], v231 offset:3584
	v_exp_f32_e32 v188, v188
	v_exp_f32_e32 v189, v189
	v_exp_f32_e32 v190, v190
	v_exp_f32_e32 v191, v191
	s_waitcnt vmcnt(8)
	ds_write_b128 v247, v[116:119]
	ds_write_b128 v247, v[120:123] offset:1024
	ds_write_b128 v247, v[124:127] offset:2048
	ds_write_b128 v247, v[128:131] offset:3072
	ds_read_b128 v[116:119], v248
	ds_read_b128 v[120:123], v249
	ds_read_b128 v[124:127], v250
	ds_read_b128 v[128:131], v251
	ds_write_b128 v112, v[132:135]
	ds_write_b128 v112, v[136:139] offset:1024
	ds_write_b128 v112, v[140:143] offset:2048
	ds_write_b128 v112, v[144:147] offset:3072
	v_mfma_f32_32x32x16_bf16 v[0:15], v[64:67], v[72:75], v[0:15]
	v_mfma_f32_32x32x16_bf16 v[16:31], v[64:67], v[76:79], v[16:31]
	v_mfma_f32_32x32x16_bf16 v[0:15], v[68:71], v[220:223], v[0:15]
	v_mfma_f32_32x32x16_bf16 v[16:31], v[68:71], v[224:227], v[16:31]
	v_exp_f32_e32 v192, v192
	v_exp_f32_e32 v193, v193
	v_exp_f32_e32 v194, v194
	v_exp_f32_e32 v195, v195
	s_waitcnt lgkmcnt(4)
	v_mfma_f32_32x32x16_bf16 v[32:47], v[116:119], v[48:51], v[32:47]
	v_exp_f32_e32 v196, v196
	v_exp_f32_e32 v197, v197
	v_mfma_f32_32x32x16_bf16 v[32:47], v[120:123], v[52:55], v[32:47]
	v_exp_f32_e32 v198, v198
	v_exp_f32_e32 v199, v199
	v_mfma_f32_32x32x16_bf16 v[32:47], v[124:127], v[56:59], v[32:47]
	v_exp_f32_e32 v200, v200
	v_exp_f32_e32 v201, v201
	v_mfma_f32_32x32x16_bf16 v[32:47], v[128:131], v[60:63], v[32:47]
	v_exp_f32_e32 v202, v202
	v_exp_f32_e32 v203, v203
	s_add_i32 s90, s67, 352
	v_add_u32_e32 v84, s90, v107
	v_add_u32_e32 v85, 0, v84
	v_add_u32_e32 v86, 1, v84
	v_add_u32_e32 v87, 2, v84
	v_add_u32_e32 v88, 3, v84
	v_cmp_gt_u32_e64 s[30:31], s98, v85
	v_cmp_gt_u32_e64 s[36:37], s98, v86
	v_cmp_gt_u32_e64 s[78:79], s98, v87
	v_cmp_gt_u32_e64 s[50:51], s98, v88
	v_cndmask_b32_e64 v188, 0, v188, s[30:31]
	v_add_u32_e32 v85, 8, v84
	v_cmp_gt_u32_e64 s[30:31], s98, v85
	v_cndmask_b32_e64 v189, 0, v189, s[36:37]
	v_add_u32_e32 v86, 9, v84
	v_cmp_gt_u32_e64 s[36:37], s98, v86
	v_cndmask_b32_e64 v190, 0, v190, s[78:79]
	v_add_u32_e32 v87, 10, v84
	v_cmp_gt_u32_e64 s[78:79], s98, v87
	v_cndmask_b32_e64 v191, 0, v191, s[50:51]
	v_add_u32_e32 v88, 11, v84
	v_cmp_gt_u32_e64 s[50:51], s98, v88
	v_cndmask_b32_e64 v192, 0, v192, s[30:31]
	v_add_u32_e32 v85, 16, v84
	v_cmp_gt_u32_e64 s[30:31], s98, v85
	v_cndmask_b32_e64 v193, 0, v193, s[36:37]
	v_add_u32_e32 v86, 17, v84
	v_cmp_gt_u32_e64 s[36:37], s98, v86
	v_cndmask_b32_e64 v194, 0, v194, s[78:79]
	v_add_u32_e32 v87, 18, v84
	v_cmp_gt_u32_e64 s[78:79], s98, v87
	v_cndmask_b32_e64 v195, 0, v195, s[50:51]
	v_add_u32_e32 v88, 19, v84
	v_cmp_gt_u32_e64 s[50:51], s98, v88
	v_cndmask_b32_e64 v196, 0, v196, s[30:31]
	v_add_u32_e32 v85, 24, v84
	v_cmp_gt_u32_e64 s[30:31], s98, v85
	v_cndmask_b32_e64 v197, 0, v197, s[36:37]
	v_add_u32_e32 v86, 25, v84
	v_cmp_gt_u32_e64 s[36:37], s98, v86
	v_cndmask_b32_e64 v198, 0, v198, s[78:79]
	v_add_u32_e32 v87, 26, v84
	v_cmp_gt_u32_e64 s[78:79], s98, v87
	v_cndmask_b32_e64 v199, 0, v199, s[50:51]
	v_add_u32_e32 v88, 27, v84
	v_cmp_gt_u32_e64 s[50:51], s98, v88
	v_nop
	v_cndmask_b32_e64 v200, 0, v200, s[30:31]
	v_cndmask_b32_e64 v201, 0, v201, s[36:37]
	v_cndmask_b32_e64 v202, 0, v202, s[78:79]
	v_cndmask_b32_e64 v203, 0, v203, s[50:51]
	v_cvt_pk_bf16_f32 v64, v188, v189
	v_cvt_pk_bf16_f32 v65, v190, v191
	v_cvt_pk_bf16_f32 v66, v192, v193
	v_cvt_pk_bf16_f32 v67, v194, v195
	v_cvt_pk_bf16_f32 v68, v196, v197
	v_cvt_pk_bf16_f32 v69, v198, v199
	v_cvt_pk_bf16_f32 v70, v200, v201
	v_cvt_pk_bf16_f32 v71, v202, v203
	v_pk_add_f32 v[232:233], v[232:233], v[188:189]
	v_pk_add_f32 v[232:233], v[232:233], v[190:191]
	v_pk_add_f32 v[232:233], v[232:233], v[192:193]
	v_pk_add_f32 v[232:233], v[232:233], v[194:195]
	v_pk_add_f32 v[232:233], v[232:233], v[196:197]
	v_pk_add_f32 v[232:233], v[232:233], v[198:199]
	v_pk_add_f32 v[232:233], v[232:233], v[200:201]
	v_pk_add_f32 v[232:233], v[232:233], v[202:203]
	ds_read2_b32 v[188:189], v115 offset0:34 offset1:35
	ds_read2_b32 v[190:191], v115 offset0:36 offset1:37
	ds_read2_b32 v[192:193], v115 offset0:42 offset1:43
	ds_read2_b32 v[194:195], v115 offset0:44 offset1:45
	ds_read2_b32 v[196:197], v115 offset0:51 offset1:52
	ds_read2_b32 v[198:199], v115 offset0:53 offset1:54
	ds_read2_b32 v[200:201], v115 offset0:59 offset1:60
	ds_read2_b32 v[202:203], v115 offset0:61 offset1:62
	s_add_i32 s90, s67, 448
	v_add_u32_e32 v80, s90, v235
	v_add_u32_e32 v83, s90, v236
	v_add_u32_e32 v99, s90, v237
	v_add_u32_e32 v253, s90, v238
	v_add_u32_e32 v254, s90, v100
	v_add_u32_e32 v255, s90, v149
	v_med3_i32 v80, v80, 0, s99
	v_med3_i32 v83, v83, 0, s99
	v_med3_i32 v99, v99, 0, s99
	v_med3_i32 v253, v253, 0, s99
	v_med3_i32 v254, v254, 0, s99
	v_med3_i32 v255, v255, 0, s99
	v_mad_u32_u24 v80, v80, s100, v252
	v_mad_u32_u24 v83, v83, s100, v252
	v_mad_u32_u24 v99, v99, s100, v252
	v_mad_u32_u24 v253, v253, s100, v252
	v_mad_u32_u24 v254, v254, s100, v153
	v_mad_u32_u24 v255, v255, s100, v153
	global_load_dwordx4 v[116:119], v80, s[82:83]
	global_load_dwordx4 v[120:123], v83, s[82:83]
	global_load_dwordx4 v[124:127], v99, s[82:83]
	global_load_dwordx4 v[128:131], v253, s[82:83]
	global_load_dwordx4 v[132:135], v254, s[82:83] offset:768
	global_load_dwordx4 v[136:139], v255, s[82:83] offset:768
	global_load_dwordx4 v[140:143], v254, s[82:83] offset:832
	global_load_dwordx4 v[144:147], v255, s[82:83] offset:832
	ds_read_b64_tr_b16 v[72:73], v231
	ds_read_b64_tr_b16 v[74:75], v231 offset:512
	ds_read_b64_tr_b16 v[76:77], v231 offset:2048
	ds_read_b64_tr_b16 v[78:79], v231 offset:2560
	ds_read_b64_tr_b16 v[220:221], v231 offset:1024
	ds_read_b64_tr_b16 v[222:223], v231 offset:1536
	ds_read_b64_tr_b16 v[224:225], v231 offset:3072
	ds_read_b64_tr_b16 v[226:227], v231 offset:3584
	v_exp_f32_e32 v32, v32
	v_exp_f32_e32 v33, v33
	v_exp_f32_e32 v34, v34
	v_exp_f32_e32 v35, v35
	s_waitcnt vmcnt(8)
	ds_write_b128 v247, v[156:159]
	ds_write_b128 v247, v[160:163] offset:1024
	ds_write_b128 v247, v[164:167] offset:2048
	ds_write_b128 v247, v[168:171] offset:3072
	ds_read_b128 v[156:159], v248
	ds_read_b128 v[160:163], v249
	ds_read_b128 v[164:167], v250
	ds_read_b128 v[168:171], v251
	ds_write_b128 v112, v[172:175]
	ds_write_b128 v112, v[176:179] offset:1024
	ds_write_b128 v112, v[180:183] offset:2048
	ds_write_b128 v112, v[184:187] offset:3072
	v_mfma_f32_32x32x16_bf16 v[0:15], v[64:67], v[204:207], v[0:15]
	v_mfma_f32_32x32x16_bf16 v[16:31], v[64:67], v[208:211], v[16:31]
	v_mfma_f32_32x32x16_bf16 v[0:15], v[68:71], v[212:215], v[0:15]
	v_mfma_f32_32x32x16_bf16 v[16:31], v[68:71], v[216:219], v[16:31]
	v_exp_f32_e32 v36, v36
	v_exp_f32_e32 v37, v37
	v_exp_f32_e32 v38, v38
	v_exp_f32_e32 v39, v39
	s_waitcnt lgkmcnt(4)
	v_mfma_f32_32x32x16_bf16 v[188:203], v[156:159], v[48:51], v[188:203]
	v_exp_f32_e32 v40, v40
	v_exp_f32_e32 v41, v41
	v_mfma_f32_32x32x16_bf16 v[188:203], v[160:163], v[52:55], v[188:203]
	v_exp_f32_e32 v42, v42
	v_exp_f32_e32 v43, v43
	v_mfma_f32_32x32x16_bf16 v[188:203], v[164:167], v[56:59], v[188:203]
	v_exp_f32_e32 v44, v44
	v_exp_f32_e32 v45, v45
	v_mfma_f32_32x32x16_bf16 v[188:203], v[168:171], v[60:63], v[188:203]
	v_exp_f32_e32 v46, v46
	v_exp_f32_e32 v47, v47
	s_add_i32 s90, s67, 384
	v_add_u32_e32 v84, s90, v107
	v_add_u32_e32 v85, 0, v84
	v_add_u32_e32 v86, 1, v84
	v_add_u32_e32 v87, 2, v84
	v_add_u32_e32 v88, 3, v84
	v_cmp_gt_u32_e64 s[30:31], s98, v85
	v_cmp_gt_u32_e64 s[36:37], s98, v86
	v_cmp_gt_u32_e64 s[78:79], s98, v87
	v_cmp_gt_u32_e64 s[50:51], s98, v88
	v_cndmask_b32_e64 v32, 0, v32, s[30:31]
	v_add_u32_e32 v85, 8, v84
	v_cmp_gt_u32_e64 s[30:31], s98, v85
	v_cndmask_b32_e64 v33, 0, v33, s[36:37]
	v_add_u32_e32 v86, 9, v84
	v_cmp_gt_u32_e64 s[36:37], s98, v86
	v_cndmask_b32_e64 v34, 0, v34, s[78:79]
	v_add_u32_e32 v87, 10, v84
	v_cmp_gt_u32_e64 s[78:79], s98, v87
	v_cndmask_b32_e64 v35, 0, v35, s[50:51]
	v_add_u32_e32 v88, 11, v84
	v_cmp_gt_u32_e64 s[50:51], s98, v88
	v_cndmask_b32_e64 v36, 0, v36, s[30:31]
	v_add_u32_e32 v85, 16, v84
	v_cmp_gt_u32_e64 s[30:31], s98, v85
	v_cndmask_b32_e64 v37, 0, v37, s[36:37]
	v_add_u32_e32 v86, 17, v84
	v_cmp_gt_u32_e64 s[36:37], s98, v86
	v_cndmask_b32_e64 v38, 0, v38, s[78:79]
	v_add_u32_e32 v87, 18, v84
	v_cmp_gt_u32_e64 s[78:79], s98, v87
	v_cndmask_b32_e64 v39, 0, v39, s[50:51]
	v_add_u32_e32 v88, 19, v84
	v_cmp_gt_u32_e64 s[50:51], s98, v88
	v_cndmask_b32_e64 v40, 0, v40, s[30:31]
	v_add_u32_e32 v85, 24, v84
	v_cmp_gt_u32_e64 s[30:31], s98, v85
	v_cndmask_b32_e64 v41, 0, v41, s[36:37]
	v_add_u32_e32 v86, 25, v84
	v_cmp_gt_u32_e64 s[36:37], s98, v86
	v_cndmask_b32_e64 v42, 0, v42, s[78:79]
	v_add_u32_e32 v87, 26, v84
	v_cmp_gt_u32_e64 s[78:79], s98, v87
	v_cndmask_b32_e64 v43, 0, v43, s[50:51]
	v_add_u32_e32 v88, 27, v84
	v_cmp_gt_u32_e64 s[50:51], s98, v88
	v_nop
	v_cndmask_b32_e64 v44, 0, v44, s[30:31]
	v_cndmask_b32_e64 v45, 0, v45, s[36:37]
	v_cndmask_b32_e64 v46, 0, v46, s[78:79]
	v_cndmask_b32_e64 v47, 0, v47, s[50:51]
	v_cvt_pk_bf16_f32 v64, v32, v33
	v_cvt_pk_bf16_f32 v65, v34, v35
	v_cvt_pk_bf16_f32 v66, v36, v37
	v_cvt_pk_bf16_f32 v67, v38, v39
	v_cvt_pk_bf16_f32 v68, v40, v41
	v_cvt_pk_bf16_f32 v69, v42, v43
	v_cvt_pk_bf16_f32 v70, v44, v45
	v_cvt_pk_bf16_f32 v71, v46, v47
	v_pk_add_f32 v[232:233], v[232:233], v[32:33]
	v_pk_add_f32 v[232:233], v[232:233], v[34:35]
	v_pk_add_f32 v[232:233], v[232:233], v[36:37]
	v_pk_add_f32 v[232:233], v[232:233], v[38:39]
	v_pk_add_f32 v[232:233], v[232:233], v[40:41]
	v_pk_add_f32 v[232:233], v[232:233], v[42:43]
	v_pk_add_f32 v[232:233], v[232:233], v[44:45]
	v_pk_add_f32 v[232:233], v[232:233], v[46:47]
	ds_read2_b32 v[32:33], v115 offset0:68 offset1:69
	ds_read2_b32 v[34:35], v115 offset0:70 offset1:71
	ds_read2_b32 v[36:37], v115 offset0:76 offset1:77
	ds_read2_b32 v[38:39], v115 offset0:78 offset1:79
	ds_read2_b32 v[40:41], v115 offset0:85 offset1:86
	ds_read2_b32 v[42:43], v115 offset0:87 offset1:88
	ds_read2_b32 v[44:45], v115 offset0:93 offset1:94
	ds_read2_b32 v[46:47], v115 offset0:95 offset1:96
	s_add_i32 s90, s67, 480
	v_add_u32_e32 v80, s90, v235
	v_add_u32_e32 v83, s90, v236
	v_add_u32_e32 v99, s90, v237
	v_add_u32_e32 v253, s90, v238
	v_add_u32_e32 v254, s90, v100
	v_add_u32_e32 v255, s90, v149
	v_med3_i32 v80, v80, 0, s99
	v_med3_i32 v83, v83, 0, s99
	v_med3_i32 v99, v99, 0, s99
	v_med3_i32 v253, v253, 0, s99
	v_med3_i32 v254, v254, 0, s99
	v_med3_i32 v255, v255, 0, s99
	v_mad_u32_u24 v80, v80, s100, v252
	v_mad_u32_u24 v83, v83, s100, v252
	v_mad_u32_u24 v99, v99, s100, v252
	v_mad_u32_u24 v253, v253, s100, v252
	v_mad_u32_u24 v254, v254, s100, v153
	v_mad_u32_u24 v255, v255, s100, v153
	global_load_dwordx4 v[156:159], v80, s[82:83]
	global_load_dwordx4 v[160:163], v83, s[82:83]
	global_load_dwordx4 v[164:167], v99, s[82:83]
	global_load_dwordx4 v[168:171], v253, s[82:83]
	global_load_dwordx4 v[172:175], v254, s[82:83] offset:768
	global_load_dwordx4 v[176:179], v255, s[82:83] offset:768
	global_load_dwordx4 v[180:183], v254, s[82:83] offset:832
	global_load_dwordx4 v[184:187], v255, s[82:83] offset:832
	ds_read_b64_tr_b16 v[204:205], v231
	ds_read_b64_tr_b16 v[206:207], v231 offset:512
	ds_read_b64_tr_b16 v[208:209], v231 offset:2048
	ds_read_b64_tr_b16 v[210:211], v231 offset:2560
	ds_read_b64_tr_b16 v[212:213], v231 offset:1024
	ds_read_b64_tr_b16 v[214:215], v231 offset:1536
	ds_read_b64_tr_b16 v[216:217], v231 offset:3072
	ds_read_b64_tr_b16 v[218:219], v231 offset:3584
	v_exp_f32_e32 v188, v188
	v_exp_f32_e32 v189, v189
	v_exp_f32_e32 v190, v190
	v_exp_f32_e32 v191, v191
	s_waitcnt vmcnt(8)
	ds_write_b128 v247, v[116:119]
	ds_write_b128 v247, v[120:123] offset:1024
	ds_write_b128 v247, v[124:127] offset:2048
	ds_write_b128 v247, v[128:131] offset:3072
	ds_read_b128 v[116:119], v248
	ds_read_b128 v[120:123], v249
	ds_read_b128 v[124:127], v250
	ds_read_b128 v[128:131], v251
	ds_write_b128 v112, v[132:135]
	ds_write_b128 v112, v[136:139] offset:1024
	ds_write_b128 v112, v[140:143] offset:2048
	ds_write_b128 v112, v[144:147] offset:3072
	v_mfma_f32_32x32x16_bf16 v[0:15], v[64:67], v[72:75], v[0:15]
	v_mfma_f32_32x32x16_bf16 v[16:31], v[64:67], v[76:79], v[16:31]
	v_mfma_f32_32x32x16_bf16 v[0:15], v[68:71], v[220:223], v[0:15]
	v_mfma_f32_32x32x16_bf16 v[16:31], v[68:71], v[224:227], v[16:31]
	v_exp_f32_e32 v192, v192
	v_exp_f32_e32 v193, v193
	v_exp_f32_e32 v194, v194
	v_exp_f32_e32 v195, v195
	s_waitcnt lgkmcnt(4)
	v_mfma_f32_32x32x16_bf16 v[32:47], v[116:119], v[48:51], v[32:47]
	v_exp_f32_e32 v196, v196
	v_exp_f32_e32 v197, v197
	v_mfma_f32_32x32x16_bf16 v[32:47], v[120:123], v[52:55], v[32:47]
	v_exp_f32_e32 v198, v198
	v_exp_f32_e32 v199, v199
	v_mfma_f32_32x32x16_bf16 v[32:47], v[124:127], v[56:59], v[32:47]
	v_exp_f32_e32 v200, v200
	v_exp_f32_e32 v201, v201
	v_mfma_f32_32x32x16_bf16 v[32:47], v[128:131], v[60:63], v[32:47]
	v_exp_f32_e32 v202, v202
	v_exp_f32_e32 v203, v203
	s_add_i32 s90, s67, 416
	v_add_u32_e32 v84, s90, v107
	v_add_u32_e32 v85, 0, v84
	v_add_u32_e32 v86, 1, v84
	v_add_u32_e32 v87, 2, v84
	v_add_u32_e32 v88, 3, v84
	v_cmp_gt_u32_e64 s[30:31], s98, v85
	v_cmp_gt_u32_e64 s[36:37], s98, v86
	v_cmp_gt_u32_e64 s[78:79], s98, v87
	v_cmp_gt_u32_e64 s[50:51], s98, v88
	v_cndmask_b32_e64 v188, 0, v188, s[30:31]
	v_add_u32_e32 v85, 8, v84
	v_cmp_gt_u32_e64 s[30:31], s98, v85
	v_cndmask_b32_e64 v189, 0, v189, s[36:37]
	v_add_u32_e32 v86, 9, v84
	v_cmp_gt_u32_e64 s[36:37], s98, v86
	v_cndmask_b32_e64 v190, 0, v190, s[78:79]
	v_add_u32_e32 v87, 10, v84
	v_cmp_gt_u32_e64 s[78:79], s98, v87
	v_cndmask_b32_e64 v191, 0, v191, s[50:51]
	v_add_u32_e32 v88, 11, v84
	v_cmp_gt_u32_e64 s[50:51], s98, v88
	v_cndmask_b32_e64 v192, 0, v192, s[30:31]
	v_add_u32_e32 v85, 16, v84
	v_cmp_gt_u32_e64 s[30:31], s98, v85
	v_cndmask_b32_e64 v193, 0, v193, s[36:37]
	v_add_u32_e32 v86, 17, v84
	v_cmp_gt_u32_e64 s[36:37], s98, v86
	v_cndmask_b32_e64 v194, 0, v194, s[78:79]
	v_add_u32_e32 v87, 18, v84
	v_cmp_gt_u32_e64 s[78:79], s98, v87
	v_cndmask_b32_e64 v195, 0, v195, s[50:51]
	v_add_u32_e32 v88, 19, v84
	v_cmp_gt_u32_e64 s[50:51], s98, v88
	v_cndmask_b32_e64 v196, 0, v196, s[30:31]
	v_add_u32_e32 v85, 24, v84
	v_cmp_gt_u32_e64 s[30:31], s98, v85
	v_cndmask_b32_e64 v197, 0, v197, s[36:37]
	v_add_u32_e32 v86, 25, v84
	v_cmp_gt_u32_e64 s[36:37], s98, v86
	v_cndmask_b32_e64 v198, 0, v198, s[78:79]
	v_add_u32_e32 v87, 26, v84
	v_cmp_gt_u32_e64 s[78:79], s98, v87
	v_cndmask_b32_e64 v199, 0, v199, s[50:51]
	v_add_u32_e32 v88, 27, v84
	v_cmp_gt_u32_e64 s[50:51], s98, v88
	v_nop
	v_cndmask_b32_e64 v200, 0, v200, s[30:31]
	v_cndmask_b32_e64 v201, 0, v201, s[36:37]
	v_cndmask_b32_e64 v202, 0, v202, s[78:79]
	v_cndmask_b32_e64 v203, 0, v203, s[50:51]
	v_cvt_pk_bf16_f32 v64, v188, v189
	v_cvt_pk_bf16_f32 v65, v190, v191
	v_cvt_pk_bf16_f32 v66, v192, v193
	v_cvt_pk_bf16_f32 v67, v194, v195
	v_cvt_pk_bf16_f32 v68, v196, v197
	v_cvt_pk_bf16_f32 v69, v198, v199
	v_cvt_pk_bf16_f32 v70, v200, v201
	v_cvt_pk_bf16_f32 v71, v202, v203
	v_pk_add_f32 v[232:233], v[232:233], v[188:189]
	v_pk_add_f32 v[232:233], v[232:233], v[190:191]
	v_pk_add_f32 v[232:233], v[232:233], v[192:193]
	v_pk_add_f32 v[232:233], v[232:233], v[194:195]
	v_pk_add_f32 v[232:233], v[232:233], v[196:197]
	v_pk_add_f32 v[232:233], v[232:233], v[198:199]
	v_pk_add_f32 v[232:233], v[232:233], v[200:201]
	v_pk_add_f32 v[232:233], v[232:233], v[202:203]
	ds_read2_b32 v[188:189], v115 offset0:102 offset1:103
	ds_read2_b32 v[190:191], v115 offset0:104 offset1:105
	ds_read2_b32 v[192:193], v115 offset0:110 offset1:111
	ds_read2_b32 v[194:195], v115 offset0:112 offset1:113
	ds_read2_b32 v[196:197], v115 offset0:119 offset1:120
	ds_read2_b32 v[198:199], v115 offset0:121 offset1:122
	ds_read2_b32 v[200:201], v115 offset0:127 offset1:128
	ds_read2_b32 v[202:203], v115 offset0:129 offset1:130
	s_add_i32 s90, s67, 512
	v_add_u32_e32 v80, s90, v235
	v_add_u32_e32 v83, s90, v236
	v_add_u32_e32 v99, s90, v237
	v_add_u32_e32 v253, s90, v238
	v_add_u32_e32 v254, s90, v100
	v_add_u32_e32 v255, s90, v149
	v_med3_i32 v80, v80, 0, s99
	v_med3_i32 v83, v83, 0, s99
	v_med3_i32 v99, v99, 0, s99
	v_med3_i32 v253, v253, 0, s99
	v_med3_i32 v254, v254, 0, s99
	v_med3_i32 v255, v255, 0, s99
	v_mad_u32_u24 v80, v80, s100, v252
	v_mad_u32_u24 v83, v83, s100, v252
	v_mad_u32_u24 v99, v99, s100, v252
	v_mad_u32_u24 v253, v253, s100, v252
	v_mad_u32_u24 v254, v254, s100, v153
	v_mad_u32_u24 v255, v255, s100, v153
	global_load_dwordx4 v[116:119], v80, s[82:83]
	global_load_dwordx4 v[120:123], v83, s[82:83]
	global_load_dwordx4 v[124:127], v99, s[82:83]
	global_load_dwordx4 v[128:131], v253, s[82:83]
	global_load_dwordx4 v[132:135], v254, s[82:83] offset:768
	global_load_dwordx4 v[136:139], v255, s[82:83] offset:768
	global_load_dwordx4 v[140:143], v254, s[82:83] offset:832
	global_load_dwordx4 v[144:147], v255, s[82:83] offset:832
	ds_read_b64_tr_b16 v[72:73], v231
	ds_read_b64_tr_b16 v[74:75], v231 offset:512
	ds_read_b64_tr_b16 v[76:77], v231 offset:2048
	ds_read_b64_tr_b16 v[78:79], v231 offset:2560
	ds_read_b64_tr_b16 v[220:221], v231 offset:1024
	ds_read_b64_tr_b16 v[222:223], v231 offset:1536
	ds_read_b64_tr_b16 v[224:225], v231 offset:3072
	ds_read_b64_tr_b16 v[226:227], v231 offset:3584
	v_exp_f32_e32 v32, v32
	v_exp_f32_e32 v33, v33
	v_exp_f32_e32 v34, v34
	v_exp_f32_e32 v35, v35
	s_waitcnt vmcnt(8)
	ds_write_b128 v247, v[156:159]
	ds_write_b128 v247, v[160:163] offset:1024
	ds_write_b128 v247, v[164:167] offset:2048
	ds_write_b128 v247, v[168:171] offset:3072
	ds_read_b128 v[156:159], v248
	ds_read_b128 v[160:163], v249
	ds_read_b128 v[164:167], v250
	ds_read_b128 v[168:171], v251
	ds_write_b128 v112, v[172:175]
	ds_write_b128 v112, v[176:179] offset:1024
	ds_write_b128 v112, v[180:183] offset:2048
	ds_write_b128 v112, v[184:187] offset:3072
	v_mfma_f32_32x32x16_bf16 v[0:15], v[64:67], v[204:207], v[0:15]
	v_mfma_f32_32x32x16_bf16 v[16:31], v[64:67], v[208:211], v[16:31]
	v_mfma_f32_32x32x16_bf16 v[0:15], v[68:71], v[212:215], v[0:15]
	v_mfma_f32_32x32x16_bf16 v[16:31], v[68:71], v[216:219], v[16:31]
	v_exp_f32_e32 v36, v36
	v_exp_f32_e32 v37, v37
	v_exp_f32_e32 v38, v38
	v_exp_f32_e32 v39, v39
	s_waitcnt lgkmcnt(4)
	v_mfma_f32_32x32x16_bf16 v[188:203], v[156:159], v[48:51], v[188:203]
	v_exp_f32_e32 v40, v40
	v_exp_f32_e32 v41, v41
	v_mfma_f32_32x32x16_bf16 v[188:203], v[160:163], v[52:55], v[188:203]
	v_exp_f32_e32 v42, v42
	v_exp_f32_e32 v43, v43
	v_mfma_f32_32x32x16_bf16 v[188:203], v[164:167], v[56:59], v[188:203]
	v_exp_f32_e32 v44, v44
	v_exp_f32_e32 v45, v45
	v_mfma_f32_32x32x16_bf16 v[188:203], v[168:171], v[60:63], v[188:203]
	v_exp_f32_e32 v46, v46
	v_exp_f32_e32 v47, v47
	s_add_i32 s90, s67, 448
	v_add_u32_e32 v84, s90, v107
	v_add_u32_e32 v85, 0, v84
	v_add_u32_e32 v86, 1, v84
	v_add_u32_e32 v87, 2, v84
	v_add_u32_e32 v88, 3, v84
	v_cmp_gt_u32_e64 s[30:31], s98, v85
	v_cmp_gt_u32_e64 s[36:37], s98, v86
	v_cmp_gt_u32_e64 s[78:79], s98, v87
	v_cmp_gt_u32_e64 s[50:51], s98, v88
	v_cndmask_b32_e64 v32, 0, v32, s[30:31]
	v_add_u32_e32 v85, 8, v84
	v_cmp_gt_u32_e64 s[30:31], s98, v85
	v_cndmask_b32_e64 v33, 0, v33, s[36:37]
	v_add_u32_e32 v86, 9, v84
	v_cmp_gt_u32_e64 s[36:37], s98, v86
	v_cndmask_b32_e64 v34, 0, v34, s[78:79]
	v_add_u32_e32 v87, 10, v84
	v_cmp_gt_u32_e64 s[78:79], s98, v87
	v_cndmask_b32_e64 v35, 0, v35, s[50:51]
	v_add_u32_e32 v88, 11, v84
	v_cmp_gt_u32_e64 s[50:51], s98, v88
	v_cndmask_b32_e64 v36, 0, v36, s[30:31]
	v_add_u32_e32 v85, 16, v84
	v_cmp_gt_u32_e64 s[30:31], s98, v85
	v_cndmask_b32_e64 v37, 0, v37, s[36:37]
	v_add_u32_e32 v86, 17, v84
	v_cmp_gt_u32_e64 s[36:37], s98, v86
	v_cndmask_b32_e64 v38, 0, v38, s[78:79]
	v_add_u32_e32 v87, 18, v84
	v_cmp_gt_u32_e64 s[78:79], s98, v87
	v_cndmask_b32_e64 v39, 0, v39, s[50:51]
	v_add_u32_e32 v88, 19, v84
	v_cmp_gt_u32_e64 s[50:51], s98, v88
	v_cndmask_b32_e64 v40, 0, v40, s[30:31]
	v_add_u32_e32 v85, 24, v84
	v_cmp_gt_u32_e64 s[30:31], s98, v85
	v_cndmask_b32_e64 v41, 0, v41, s[36:37]
	v_add_u32_e32 v86, 25, v84
	v_cmp_gt_u32_e64 s[36:37], s98, v86
	v_cndmask_b32_e64 v42, 0, v42, s[78:79]
	v_add_u32_e32 v87, 26, v84
	v_cmp_gt_u32_e64 s[78:79], s98, v87
	v_cndmask_b32_e64 v43, 0, v43, s[50:51]
	v_add_u32_e32 v88, 27, v84
	v_cmp_gt_u32_e64 s[50:51], s98, v88
	v_nop
	v_cndmask_b32_e64 v44, 0, v44, s[30:31]
	v_cndmask_b32_e64 v45, 0, v45, s[36:37]
	v_cndmask_b32_e64 v46, 0, v46, s[78:79]
	v_cndmask_b32_e64 v47, 0, v47, s[50:51]
	v_cvt_pk_bf16_f32 v64, v32, v33
	v_cvt_pk_bf16_f32 v65, v34, v35
	v_cvt_pk_bf16_f32 v66, v36, v37
	v_cvt_pk_bf16_f32 v67, v38, v39
	v_cvt_pk_bf16_f32 v68, v40, v41
	v_cvt_pk_bf16_f32 v69, v42, v43
	v_cvt_pk_bf16_f32 v70, v44, v45
	v_cvt_pk_bf16_f32 v71, v46, v47
	v_pk_add_f32 v[232:233], v[232:233], v[32:33]
	v_pk_add_f32 v[232:233], v[232:233], v[34:35]
	v_pk_add_f32 v[232:233], v[232:233], v[36:37]
	v_pk_add_f32 v[232:233], v[232:233], v[38:39]
	v_pk_add_f32 v[232:233], v[232:233], v[40:41]
	v_pk_add_f32 v[232:233], v[232:233], v[42:43]
	v_pk_add_f32 v[232:233], v[232:233], v[44:45]
	v_pk_add_f32 v[232:233], v[232:233], v[46:47]
	ds_read2_b32 v[32:33], v115 offset0:136 offset1:137
	ds_read2_b32 v[34:35], v115 offset0:138 offset1:139
	ds_read2_b32 v[36:37], v115 offset0:144 offset1:145
	ds_read2_b32 v[38:39], v115 offset0:146 offset1:147
	ds_read2_b32 v[40:41], v115 offset0:153 offset1:154
	ds_read2_b32 v[42:43], v115 offset0:155 offset1:156
	ds_read2_b32 v[44:45], v115 offset0:161 offset1:162
	ds_read2_b32 v[46:47], v115 offset0:163 offset1:164
	s_add_i32 s90, s67, 544
	v_add_u32_e32 v80, s90, v235
	v_add_u32_e32 v83, s90, v236
	v_add_u32_e32 v99, s90, v237
	v_add_u32_e32 v253, s90, v238
	v_add_u32_e32 v254, s90, v100
	v_add_u32_e32 v255, s90, v149
	v_med3_i32 v80, v80, 0, s99
	v_med3_i32 v83, v83, 0, s99
	v_med3_i32 v99, v99, 0, s99
	v_med3_i32 v253, v253, 0, s99
	v_med3_i32 v254, v254, 0, s99
	v_med3_i32 v255, v255, 0, s99
	v_mad_u32_u24 v80, v80, s100, v252
	v_mad_u32_u24 v83, v83, s100, v252
	v_mad_u32_u24 v99, v99, s100, v252
	v_mad_u32_u24 v253, v253, s100, v252
	v_mad_u32_u24 v254, v254, s100, v153
	v_mad_u32_u24 v255, v255, s100, v153
	global_load_dwordx4 v[156:159], v80, s[82:83]
	global_load_dwordx4 v[160:163], v83, s[82:83]
	global_load_dwordx4 v[164:167], v99, s[82:83]
	global_load_dwordx4 v[168:171], v253, s[82:83]
	global_load_dwordx4 v[172:175], v254, s[82:83] offset:768
	global_load_dwordx4 v[176:179], v255, s[82:83] offset:768
	global_load_dwordx4 v[180:183], v254, s[82:83] offset:832
	global_load_dwordx4 v[184:187], v255, s[82:83] offset:832
	ds_read_b64_tr_b16 v[204:205], v231
	ds_read_b64_tr_b16 v[206:207], v231 offset:512
	ds_read_b64_tr_b16 v[208:209], v231 offset:2048
	ds_read_b64_tr_b16 v[210:211], v231 offset:2560
	ds_read_b64_tr_b16 v[212:213], v231 offset:1024
	ds_read_b64_tr_b16 v[214:215], v231 offset:1536
	ds_read_b64_tr_b16 v[216:217], v231 offset:3072
	ds_read_b64_tr_b16 v[218:219], v231 offset:3584
	v_exp_f32_e32 v188, v188
	v_exp_f32_e32 v189, v189
	v_exp_f32_e32 v190, v190
	v_exp_f32_e32 v191, v191
	s_waitcnt vmcnt(8)
	ds_write_b128 v247, v[116:119]
	ds_write_b128 v247, v[120:123] offset:1024
	ds_write_b128 v247, v[124:127] offset:2048
	ds_write_b128 v247, v[128:131] offset:3072
	ds_read_b128 v[116:119], v248
	ds_read_b128 v[120:123], v249
	ds_read_b128 v[124:127], v250
	ds_read_b128 v[128:131], v251
	ds_write_b128 v112, v[132:135]
	ds_write_b128 v112, v[136:139] offset:1024
	ds_write_b128 v112, v[140:143] offset:2048
	ds_write_b128 v112, v[144:147] offset:3072
	v_mfma_f32_32x32x16_bf16 v[0:15], v[64:67], v[72:75], v[0:15]
	v_mfma_f32_32x32x16_bf16 v[16:31], v[64:67], v[76:79], v[16:31]
	v_mfma_f32_32x32x16_bf16 v[0:15], v[68:71], v[220:223], v[0:15]
	v_mfma_f32_32x32x16_bf16 v[16:31], v[68:71], v[224:227], v[16:31]
	v_exp_f32_e32 v192, v192
	v_exp_f32_e32 v193, v193
	v_exp_f32_e32 v194, v194
	v_exp_f32_e32 v195, v195
	s_waitcnt lgkmcnt(4)
	v_mfma_f32_32x32x16_bf16 v[32:47], v[116:119], v[48:51], v[32:47]
	v_exp_f32_e32 v196, v196
	v_exp_f32_e32 v197, v197
	v_mfma_f32_32x32x16_bf16 v[32:47], v[120:123], v[52:55], v[32:47]
	v_exp_f32_e32 v198, v198
	v_exp_f32_e32 v199, v199
	v_mfma_f32_32x32x16_bf16 v[32:47], v[124:127], v[56:59], v[32:47]
	v_exp_f32_e32 v200, v200
	v_exp_f32_e32 v201, v201
	v_mfma_f32_32x32x16_bf16 v[32:47], v[128:131], v[60:63], v[32:47]
	v_exp_f32_e32 v202, v202
	v_exp_f32_e32 v203, v203
	s_add_i32 s90, s67, 480
	v_add_u32_e32 v84, s90, v107
	v_add_u32_e32 v85, 0, v84
	v_add_u32_e32 v86, 1, v84
	v_add_u32_e32 v87, 2, v84
	v_add_u32_e32 v88, 3, v84
	v_cmp_gt_u32_e64 s[30:31], s98, v85
	v_cmp_gt_u32_e64 s[36:37], s98, v86
	v_cmp_gt_u32_e64 s[78:79], s98, v87
	v_cmp_gt_u32_e64 s[50:51], s98, v88
	v_cndmask_b32_e64 v188, 0, v188, s[30:31]
	v_add_u32_e32 v85, 8, v84
	v_cmp_gt_u32_e64 s[30:31], s98, v85
	v_cndmask_b32_e64 v189, 0, v189, s[36:37]
	v_add_u32_e32 v86, 9, v84
	v_cmp_gt_u32_e64 s[36:37], s98, v86
	v_cndmask_b32_e64 v190, 0, v190, s[78:79]
	v_add_u32_e32 v87, 10, v84
	v_cmp_gt_u32_e64 s[78:79], s98, v87
	v_cndmask_b32_e64 v191, 0, v191, s[50:51]
	v_add_u32_e32 v88, 11, v84
	v_cmp_gt_u32_e64 s[50:51], s98, v88
	v_cndmask_b32_e64 v192, 0, v192, s[30:31]
	v_add_u32_e32 v85, 16, v84
	v_cmp_gt_u32_e64 s[30:31], s98, v85
	v_cndmask_b32_e64 v193, 0, v193, s[36:37]
	v_add_u32_e32 v86, 17, v84
	v_cmp_gt_u32_e64 s[36:37], s98, v86
	v_cndmask_b32_e64 v194, 0, v194, s[78:79]
	v_add_u32_e32 v87, 18, v84
	v_cmp_gt_u32_e64 s[78:79], s98, v87
	v_cndmask_b32_e64 v195, 0, v195, s[50:51]
	v_add_u32_e32 v88, 19, v84
	v_cmp_gt_u32_e64 s[50:51], s98, v88
	v_cndmask_b32_e64 v196, 0, v196, s[30:31]
	v_add_u32_e32 v85, 24, v84
	v_cmp_gt_u32_e64 s[30:31], s98, v85
	v_cndmask_b32_e64 v197, 0, v197, s[36:37]
	v_add_u32_e32 v86, 25, v84
	v_cmp_gt_u32_e64 s[36:37], s98, v86
	v_cndmask_b32_e64 v198, 0, v198, s[78:79]
	v_add_u32_e32 v87, 26, v84
	v_cmp_gt_u32_e64 s[78:79], s98, v87
	v_cndmask_b32_e64 v199, 0, v199, s[50:51]
	v_add_u32_e32 v88, 27, v84
	v_cmp_gt_u32_e64 s[50:51], s98, v88
	v_nop
	v_cndmask_b32_e64 v200, 0, v200, s[30:31]
	v_cndmask_b32_e64 v201, 0, v201, s[36:37]
	v_cndmask_b32_e64 v202, 0, v202, s[78:79]
	v_cndmask_b32_e64 v203, 0, v203, s[50:51]
	v_cvt_pk_bf16_f32 v64, v188, v189
	v_cvt_pk_bf16_f32 v65, v190, v191
	v_cvt_pk_bf16_f32 v66, v192, v193
	v_cvt_pk_bf16_f32 v67, v194, v195
	v_cvt_pk_bf16_f32 v68, v196, v197
	v_cvt_pk_bf16_f32 v69, v198, v199
	v_cvt_pk_bf16_f32 v70, v200, v201
	v_cvt_pk_bf16_f32 v71, v202, v203
	v_pk_add_f32 v[232:233], v[232:233], v[188:189]
	v_pk_add_f32 v[232:233], v[232:233], v[190:191]
	v_pk_add_f32 v[232:233], v[232:233], v[192:193]
	v_pk_add_f32 v[232:233], v[232:233], v[194:195]
	v_pk_add_f32 v[232:233], v[232:233], v[196:197]
	v_pk_add_f32 v[232:233], v[232:233], v[198:199]
	v_pk_add_f32 v[232:233], v[232:233], v[200:201]
	v_pk_add_f32 v[232:233], v[232:233], v[202:203]
	ds_read2_b32 v[188:189], v115 offset0:170 offset1:171
	ds_read2_b32 v[190:191], v115 offset0:172 offset1:173
	ds_read2_b32 v[192:193], v115 offset0:178 offset1:179
	ds_read2_b32 v[194:195], v115 offset0:180 offset1:181
	ds_read2_b32 v[196:197], v115 offset0:187 offset1:188
	ds_read2_b32 v[198:199], v115 offset0:189 offset1:190
	ds_read2_b32 v[200:201], v115 offset0:195 offset1:196
	ds_read2_b32 v[202:203], v115 offset0:197 offset1:198
	s_add_i32 s90, s67, -256
	v_add_u32_e32 v80, s90, v239
	v_add_u32_e32 v83, s90, v240
	v_add_u32_e32 v99, s90, v241
	v_add_u32_e32 v253, s90, v242
	v_add_u32_e32 v254, s90, v101
	v_add_u32_e32 v255, s90, v150
	v_med3_i32 v80, v80, 0, s99
	v_med3_i32 v83, v83, 0, s99
	v_med3_i32 v99, v99, 0, s99
	v_med3_i32 v253, v253, 0, s99
	v_med3_i32 v254, v254, 0, s99
	v_med3_i32 v255, v255, 0, s99
	v_mad_u32_u24 v80, v80, s100, v252
	v_mad_u32_u24 v83, v83, s100, v252
	v_mad_u32_u24 v99, v99, s100, v252
	v_mad_u32_u24 v253, v253, s100, v252
	v_mad_u32_u24 v254, v254, s100, v153
	v_mad_u32_u24 v255, v255, s100, v153
	global_load_dwordx4 v[116:119], v80, s[82:83]
	global_load_dwordx4 v[120:123], v83, s[82:83]
	global_load_dwordx4 v[124:127], v99, s[82:83]
	global_load_dwordx4 v[128:131], v253, s[82:83]
	global_load_dwordx4 v[132:135], v254, s[82:83] offset:768
	global_load_dwordx4 v[136:139], v255, s[82:83] offset:768
	global_load_dwordx4 v[140:143], v254, s[82:83] offset:832
	global_load_dwordx4 v[144:147], v255, s[82:83] offset:832
	ds_read_b64_tr_b16 v[72:73], v231
	ds_read_b64_tr_b16 v[74:75], v231 offset:512
	ds_read_b64_tr_b16 v[76:77], v231 offset:2048
	ds_read_b64_tr_b16 v[78:79], v231 offset:2560
	ds_read_b64_tr_b16 v[220:221], v231 offset:1024
	ds_read_b64_tr_b16 v[222:223], v231 offset:1536
	ds_read_b64_tr_b16 v[224:225], v231 offset:3072
	ds_read_b64_tr_b16 v[226:227], v231 offset:3584
	v_exp_f32_e32 v32, v32
	v_exp_f32_e32 v33, v33
	v_exp_f32_e32 v34, v34
	v_exp_f32_e32 v35, v35
	s_waitcnt vmcnt(8)
	ds_write_b128 v247, v[156:159]
	ds_write_b128 v247, v[160:163] offset:1024
	ds_write_b128 v247, v[164:167] offset:2048
	ds_write_b128 v247, v[168:171] offset:3072
	ds_read_b128 v[156:159], v248
	ds_read_b128 v[160:163], v249
	ds_read_b128 v[164:167], v250
	ds_read_b128 v[168:171], v251
	ds_write_b128 v112, v[172:175]
	ds_write_b128 v112, v[176:179] offset:1024
	ds_write_b128 v112, v[180:183] offset:2048
	ds_write_b128 v112, v[184:187] offset:3072
	v_mfma_f32_32x32x16_bf16 v[0:15], v[64:67], v[204:207], v[0:15]
	v_mfma_f32_32x32x16_bf16 v[16:31], v[64:67], v[208:211], v[16:31]
	v_mfma_f32_32x32x16_bf16 v[0:15], v[68:71], v[212:215], v[0:15]
	v_mfma_f32_32x32x16_bf16 v[16:31], v[68:71], v[216:219], v[16:31]
	v_exp_f32_e32 v36, v36
	v_exp_f32_e32 v37, v37
	v_exp_f32_e32 v38, v38
	v_exp_f32_e32 v39, v39
	s_waitcnt lgkmcnt(4)
	v_mfma_f32_32x32x16_bf16 v[188:203], v[156:159], v[48:51], v[188:203]
	v_exp_f32_e32 v40, v40
	v_exp_f32_e32 v41, v41
	v_mfma_f32_32x32x16_bf16 v[188:203], v[160:163], v[52:55], v[188:203]
	v_exp_f32_e32 v42, v42
	v_exp_f32_e32 v43, v43
	v_mfma_f32_32x32x16_bf16 v[188:203], v[164:167], v[56:59], v[188:203]
	v_exp_f32_e32 v44, v44
	v_exp_f32_e32 v45, v45
	v_mfma_f32_32x32x16_bf16 v[188:203], v[168:171], v[60:63], v[188:203]
	v_exp_f32_e32 v46, v46
	v_exp_f32_e32 v47, v47
	s_add_i32 s90, s67, 512
	v_add_u32_e32 v84, s90, v107
	v_add_u32_e32 v85, 0, v84
	v_add_u32_e32 v86, 1, v84
	v_add_u32_e32 v87, 2, v84
	v_add_u32_e32 v88, 3, v84
	v_cmp_gt_u32_e64 s[30:31], s98, v85
	v_cmp_gt_u32_e64 s[36:37], s98, v86
	v_cmp_gt_u32_e64 s[78:79], s98, v87
	v_cmp_gt_u32_e64 s[50:51], s98, v88
	v_cndmask_b32_e64 v32, 0, v32, s[30:31]
	v_add_u32_e32 v85, 8, v84
	v_cmp_gt_u32_e64 s[30:31], s98, v85
	v_cndmask_b32_e64 v33, 0, v33, s[36:37]
	v_add_u32_e32 v86, 9, v84
	v_cmp_gt_u32_e64 s[36:37], s98, v86
	v_cndmask_b32_e64 v34, 0, v34, s[78:79]
	v_add_u32_e32 v87, 10, v84
	v_cmp_gt_u32_e64 s[78:79], s98, v87
	v_cndmask_b32_e64 v35, 0, v35, s[50:51]
	v_add_u32_e32 v88, 11, v84
	v_cmp_gt_u32_e64 s[50:51], s98, v88
	v_cndmask_b32_e64 v36, 0, v36, s[30:31]
	v_add_u32_e32 v85, 16, v84
	v_cmp_gt_u32_e64 s[30:31], s98, v85
	v_cndmask_b32_e64 v37, 0, v37, s[36:37]
	v_add_u32_e32 v86, 17, v84
	v_cmp_gt_u32_e64 s[36:37], s98, v86
	v_cndmask_b32_e64 v38, 0, v38, s[78:79]
	v_add_u32_e32 v87, 18, v84
	v_cmp_gt_u32_e64 s[78:79], s98, v87
	v_cndmask_b32_e64 v39, 0, v39, s[50:51]
	v_add_u32_e32 v88, 19, v84
	v_cmp_gt_u32_e64 s[50:51], s98, v88
	v_cndmask_b32_e64 v40, 0, v40, s[30:31]
	v_add_u32_e32 v85, 24, v84
	v_cmp_gt_u32_e64 s[30:31], s98, v85
	v_cndmask_b32_e64 v41, 0, v41, s[36:37]
	v_add_u32_e32 v86, 25, v84
	v_cmp_gt_u32_e64 s[36:37], s98, v86
	v_cndmask_b32_e64 v42, 0, v42, s[78:79]
	v_add_u32_e32 v87, 26, v84
	v_cmp_gt_u32_e64 s[78:79], s98, v87
	v_cndmask_b32_e64 v43, 0, v43, s[50:51]
	v_add_u32_e32 v88, 27, v84
	v_cmp_gt_u32_e64 s[50:51], s98, v88
	v_nop
	v_cndmask_b32_e64 v44, 0, v44, s[30:31]
	v_cndmask_b32_e64 v45, 0, v45, s[36:37]
	v_cndmask_b32_e64 v46, 0, v46, s[78:79]
	v_cndmask_b32_e64 v47, 0, v47, s[50:51]
	v_cvt_pk_bf16_f32 v64, v32, v33
	v_cvt_pk_bf16_f32 v65, v34, v35
	v_cvt_pk_bf16_f32 v66, v36, v37
	v_cvt_pk_bf16_f32 v67, v38, v39
	v_cvt_pk_bf16_f32 v68, v40, v41
	v_cvt_pk_bf16_f32 v69, v42, v43
	v_cvt_pk_bf16_f32 v70, v44, v45
	v_cvt_pk_bf16_f32 v71, v46, v47
	v_pk_add_f32 v[232:233], v[232:233], v[32:33]
	v_pk_add_f32 v[232:233], v[232:233], v[34:35]
	v_pk_add_f32 v[232:233], v[232:233], v[36:37]
	v_pk_add_f32 v[232:233], v[232:233], v[38:39]
	v_pk_add_f32 v[232:233], v[232:233], v[40:41]
	v_pk_add_f32 v[232:233], v[232:233], v[42:43]
	v_pk_add_f32 v[232:233], v[232:233], v[44:45]
	v_pk_add_f32 v[232:233], v[232:233], v[46:47]
	v_mov_b32_e32 v115, v229
	ds_read2_b32 v[32:33], v115 offset0:0 offset1:1
	ds_read2_b32 v[34:35], v115 offset0:2 offset1:3
	ds_read2_b32 v[36:37], v115 offset0:8 offset1:9
	ds_read2_b32 v[38:39], v115 offset0:10 offset1:11
	ds_read2_b32 v[40:41], v115 offset0:16 offset1:17
	ds_read2_b32 v[42:43], v115 offset0:18 offset1:19
	ds_read2_b32 v[44:45], v115 offset0:24 offset1:25
	ds_read2_b32 v[46:47], v115 offset0:26 offset1:27
	s_add_i32 s90, s67, -128
	v_add_u32_e32 v80, s90, v239
	v_add_u32_e32 v83, s90, v240
	v_add_u32_e32 v99, s90, v241
	v_add_u32_e32 v253, s90, v242
	v_add_u32_e32 v254, s90, v101
	v_add_u32_e32 v255, s90, v150
	v_med3_i32 v80, v80, 0, s99
	v_med3_i32 v83, v83, 0, s99
	v_med3_i32 v99, v99, 0, s99
	v_med3_i32 v253, v253, 0, s99
	v_med3_i32 v254, v254, 0, s99
	v_med3_i32 v255, v255, 0, s99
	v_mad_u32_u24 v80, v80, s100, v252
	v_mad_u32_u24 v83, v83, s100, v252
	v_mad_u32_u24 v99, v99, s100, v252
	v_mad_u32_u24 v253, v253, s100, v252
	v_mad_u32_u24 v254, v254, s100, v153
	v_mad_u32_u24 v255, v255, s100, v153
	global_load_dwordx4 v[156:159], v80, s[82:83]
	global_load_dwordx4 v[160:163], v83, s[82:83]
	global_load_dwordx4 v[164:167], v99, s[82:83]
	global_load_dwordx4 v[168:171], v253, s[82:83]
	global_load_dwordx4 v[172:175], v254, s[82:83] offset:768
	global_load_dwordx4 v[176:179], v255, s[82:83] offset:768
	global_load_dwordx4 v[180:183], v254, s[82:83] offset:832
	global_load_dwordx4 v[184:187], v255, s[82:83] offset:832
	ds_read_b64_tr_b16 v[204:205], v231
	ds_read_b64_tr_b16 v[206:207], v231 offset:512
	ds_read_b64_tr_b16 v[208:209], v231 offset:2048
	ds_read_b64_tr_b16 v[210:211], v231 offset:2560
	ds_read_b64_tr_b16 v[212:213], v231 offset:1024
	ds_read_b64_tr_b16 v[214:215], v231 offset:1536
	ds_read_b64_tr_b16 v[216:217], v231 offset:3072
	ds_read_b64_tr_b16 v[218:219], v231 offset:3584
	v_exp_f32_e32 v188, v188
	v_exp_f32_e32 v189, v189
	v_exp_f32_e32 v190, v190
	v_exp_f32_e32 v191, v191
	s_waitcnt vmcnt(8)
	ds_write_b128 v247, v[116:119]
	ds_write_b128 v247, v[120:123] offset:1024
	ds_write_b128 v247, v[124:127] offset:2048
	ds_write_b128 v247, v[128:131] offset:3072
	ds_read_b128 v[116:119], v248
	ds_read_b128 v[120:123], v249
	ds_read_b128 v[124:127], v250
	ds_read_b128 v[128:131], v251
	ds_write_b128 v112, v[132:135]
	ds_write_b128 v112, v[136:139] offset:1024
	ds_write_b128 v112, v[140:143] offset:2048
	ds_write_b128 v112, v[144:147] offset:3072
	v_mfma_f32_32x32x16_bf16 v[0:15], v[64:67], v[72:75], v[0:15]
	v_mfma_f32_32x32x16_bf16 v[16:31], v[64:67], v[76:79], v[16:31]
	v_mfma_f32_32x32x16_bf16 v[0:15], v[68:71], v[220:223], v[0:15]
	v_mfma_f32_32x32x16_bf16 v[16:31], v[68:71], v[224:227], v[16:31]
	v_exp_f32_e32 v192, v192
	v_exp_f32_e32 v193, v193
	v_exp_f32_e32 v194, v194
	v_exp_f32_e32 v195, v195
	s_waitcnt lgkmcnt(4)
	v_mfma_f32_32x32x16_bf16 v[32:47], v[116:119], v[48:51], v[32:47]
	v_exp_f32_e32 v196, v196
	v_exp_f32_e32 v197, v197
	v_mfma_f32_32x32x16_bf16 v[32:47], v[120:123], v[52:55], v[32:47]
	v_exp_f32_e32 v198, v198
	v_exp_f32_e32 v199, v199
	v_mfma_f32_32x32x16_bf16 v[32:47], v[124:127], v[56:59], v[32:47]
	v_exp_f32_e32 v200, v200
	v_exp_f32_e32 v201, v201
	v_mfma_f32_32x32x16_bf16 v[32:47], v[128:131], v[60:63], v[32:47]
	v_exp_f32_e32 v202, v202
	v_exp_f32_e32 v203, v203
	s_add_i32 s90, s67, 544
	v_add_u32_e32 v84, s90, v107
	v_add_u32_e32 v85, 0, v84
	v_add_u32_e32 v86, 1, v84
	v_add_u32_e32 v87, 2, v84
	v_add_u32_e32 v88, 3, v84
	v_cmp_gt_u32_e64 s[30:31], s98, v85
	v_cmp_gt_u32_e64 s[36:37], s98, v86
	v_cmp_gt_u32_e64 s[78:79], s98, v87
	v_cmp_gt_u32_e64 s[50:51], s98, v88
	v_cndmask_b32_e64 v188, 0, v188, s[30:31]
	v_add_u32_e32 v85, 8, v84
	v_cmp_gt_u32_e64 s[30:31], s98, v85
	v_cndmask_b32_e64 v189, 0, v189, s[36:37]
	v_add_u32_e32 v86, 9, v84
	v_cmp_gt_u32_e64 s[36:37], s98, v86
	v_cndmask_b32_e64 v190, 0, v190, s[78:79]
	v_add_u32_e32 v87, 10, v84
	v_cmp_gt_u32_e64 s[78:79], s98, v87
	v_cndmask_b32_e64 v191, 0, v191, s[50:51]
	v_add_u32_e32 v88, 11, v84
	v_cmp_gt_u32_e64 s[50:51], s98, v88
	v_cndmask_b32_e64 v192, 0, v192, s[30:31]
	v_add_u32_e32 v85, 16, v84
	v_cmp_gt_u32_e64 s[30:31], s98, v85
	v_cndmask_b32_e64 v193, 0, v193, s[36:37]
	v_add_u32_e32 v86, 17, v84
	v_cmp_gt_u32_e64 s[36:37], s98, v86
	v_cndmask_b32_e64 v194, 0, v194, s[78:79]
	v_add_u32_e32 v87, 18, v84
	v_cmp_gt_u32_e64 s[78:79], s98, v87
	v_cndmask_b32_e64 v195, 0, v195, s[50:51]
	v_add_u32_e32 v88, 19, v84
	v_cmp_gt_u32_e64 s[50:51], s98, v88
	v_cndmask_b32_e64 v196, 0, v196, s[30:31]
	v_add_u32_e32 v85, 24, v84
	v_cmp_gt_u32_e64 s[30:31], s98, v85
	v_cndmask_b32_e64 v197, 0, v197, s[36:37]
	v_add_u32_e32 v86, 25, v84
	v_cmp_gt_u32_e64 s[36:37], s98, v86
	v_cndmask_b32_e64 v198, 0, v198, s[78:79]
	v_add_u32_e32 v87, 26, v84
	v_cmp_gt_u32_e64 s[78:79], s98, v87
	v_cndmask_b32_e64 v199, 0, v199, s[50:51]
	v_add_u32_e32 v88, 27, v84
	v_cmp_gt_u32_e64 s[50:51], s98, v88
	v_nop
	v_cndmask_b32_e64 v200, 0, v200, s[30:31]
	v_cndmask_b32_e64 v201, 0, v201, s[36:37]
	v_cndmask_b32_e64 v202, 0, v202, s[78:79]
	v_cndmask_b32_e64 v203, 0, v203, s[50:51]
	v_cvt_pk_bf16_f32 v64, v188, v189
	v_cvt_pk_bf16_f32 v65, v190, v191
	v_cvt_pk_bf16_f32 v66, v192, v193
	v_cvt_pk_bf16_f32 v67, v194, v195
	v_cvt_pk_bf16_f32 v68, v196, v197
	v_cvt_pk_bf16_f32 v69, v198, v199
	v_cvt_pk_bf16_f32 v70, v200, v201
	v_cvt_pk_bf16_f32 v71, v202, v203
	v_pk_add_f32 v[232:233], v[232:233], v[188:189]
	v_pk_add_f32 v[232:233], v[232:233], v[190:191]
	v_pk_add_f32 v[232:233], v[232:233], v[192:193]
	v_pk_add_f32 v[232:233], v[232:233], v[194:195]
	v_pk_add_f32 v[232:233], v[232:233], v[196:197]
	v_pk_add_f32 v[232:233], v[232:233], v[198:199]
	v_pk_add_f32 v[232:233], v[232:233], v[200:201]
	v_pk_add_f32 v[232:233], v[232:233], v[202:203]
	ds_read2_b32 v[188:189], v115 offset0:32 offset1:33
	ds_read2_b32 v[190:191], v115 offset0:34 offset1:35
	ds_read2_b32 v[192:193], v115 offset0:40 offset1:41
	ds_read2_b32 v[194:195], v115 offset0:42 offset1:43
	ds_read2_b32 v[196:197], v115 offset0:48 offset1:49
	ds_read2_b32 v[198:199], v115 offset0:50 offset1:51
	ds_read2_b32 v[200:201], v115 offset0:56 offset1:57
	ds_read2_b32 v[202:203], v115 offset0:58 offset1:59
	s_add_i32 s90, s67, 0
	v_add_u32_e32 v80, s90, v239
	v_add_u32_e32 v83, s90, v240
	v_add_u32_e32 v99, s90, v241
	v_add_u32_e32 v253, s90, v242
	v_add_u32_e32 v254, s90, v101
	v_add_u32_e32 v255, s90, v150
	v_med3_i32 v80, v80, 0, s99
	v_med3_i32 v83, v83, 0, s99
	v_med3_i32 v99, v99, 0, s99
	v_med3_i32 v253, v253, 0, s99
	v_med3_i32 v254, v254, 0, s99
	v_med3_i32 v255, v255, 0, s99
	v_mad_u32_u24 v80, v80, s100, v252
	v_mad_u32_u24 v83, v83, s100, v252
	v_mad_u32_u24 v99, v99, s100, v252
	v_mad_u32_u24 v253, v253, s100, v252
	v_mad_u32_u24 v254, v254, s100, v153
	v_mad_u32_u24 v255, v255, s100, v153
	global_load_dwordx4 v[116:119], v80, s[82:83]
	global_load_dwordx4 v[120:123], v83, s[82:83]
	global_load_dwordx4 v[124:127], v99, s[82:83]
	global_load_dwordx4 v[128:131], v253, s[82:83]
	global_load_dwordx4 v[132:135], v254, s[82:83] offset:768
	global_load_dwordx4 v[136:139], v255, s[82:83] offset:768
	global_load_dwordx4 v[140:143], v254, s[82:83] offset:832
	global_load_dwordx4 v[144:147], v255, s[82:83] offset:832
	ds_read_b64_tr_b16 v[72:73], v231
	ds_read_b64_tr_b16 v[74:75], v231 offset:512
	ds_read_b64_tr_b16 v[76:77], v231 offset:2048
	ds_read_b64_tr_b16 v[78:79], v231 offset:2560
	ds_read_b64_tr_b16 v[220:221], v231 offset:1024
	ds_read_b64_tr_b16 v[222:223], v231 offset:1536
	ds_read_b64_tr_b16 v[224:225], v231 offset:3072
	ds_read_b64_tr_b16 v[226:227], v231 offset:3584
	v_exp_f32_e32 v32, v32
	v_exp_f32_e32 v33, v33
	v_exp_f32_e32 v34, v34
	v_exp_f32_e32 v35, v35
	s_waitcnt vmcnt(8)
	ds_write_b128 v247, v[156:159]
	ds_write_b128 v247, v[160:163] offset:1024
	ds_write_b128 v247, v[164:167] offset:2048
	ds_write_b128 v247, v[168:171] offset:3072
	ds_read_b128 v[156:159], v248
	ds_read_b128 v[160:163], v249
	ds_read_b128 v[164:167], v250
	ds_read_b128 v[168:171], v251
	ds_write_b128 v112, v[172:175]
	ds_write_b128 v112, v[176:179] offset:1024
	ds_write_b128 v112, v[180:183] offset:2048
	ds_write_b128 v112, v[184:187] offset:3072
	v_mfma_f32_32x32x16_bf16 v[0:15], v[64:67], v[204:207], v[0:15]
	v_mfma_f32_32x32x16_bf16 v[16:31], v[64:67], v[208:211], v[16:31]
	v_mfma_f32_32x32x16_bf16 v[0:15], v[68:71], v[212:215], v[0:15]
	v_mfma_f32_32x32x16_bf16 v[16:31], v[68:71], v[216:219], v[16:31]
	v_exp_f32_e32 v36, v36
	v_exp_f32_e32 v37, v37
	v_exp_f32_e32 v38, v38
	v_exp_f32_e32 v39, v39
	s_waitcnt lgkmcnt(4)
	v_mfma_f32_32x32x16_bf16 v[188:203], v[156:159], v[48:51], v[188:203]
	v_exp_f32_e32 v40, v40
	v_exp_f32_e32 v41, v41
	v_mfma_f32_32x32x16_bf16 v[188:203], v[160:163], v[52:55], v[188:203]
	v_exp_f32_e32 v42, v42
	v_exp_f32_e32 v43, v43
	v_mfma_f32_32x32x16_bf16 v[188:203], v[164:167], v[56:59], v[188:203]
	v_exp_f32_e32 v44, v44
	v_exp_f32_e32 v45, v45
	v_mfma_f32_32x32x16_bf16 v[188:203], v[168:171], v[60:63], v[188:203]
	v_exp_f32_e32 v46, v46
	v_exp_f32_e32 v47, v47
	s_add_i32 s90, s67, -256
	v_lshlrev_b32_e32 v84, 2, v107
	v_add_u32_e32 v84, s90, v84
	v_add_u32_e32 v85, 0, v84
	v_add_u32_e32 v86, 4, v84
	v_add_u32_e32 v87, 8, v84
	v_add_u32_e32 v88, 12, v84
	v_cmp_gt_u32_e64 s[30:31], s98, v85
	v_cmp_gt_u32_e64 s[36:37], s98, v86
	v_cmp_gt_u32_e64 s[78:79], s98, v87
	v_cmp_gt_u32_e64 s[50:51], s98, v88
	v_cndmask_b32_e64 v32, 0, v32, s[30:31]
	v_add_u32_e32 v85, 32, v84
	v_cmp_gt_u32_e64 s[30:31], s98, v85
	v_cndmask_b32_e64 v33, 0, v33, s[36:37]
	v_add_u32_e32 v86, 36, v84
	v_cmp_gt_u32_e64 s[36:37], s98, v86
	v_cndmask_b32_e64 v34, 0, v34, s[78:79]
	v_add_u32_e32 v87, 40, v84
	v_cmp_gt_u32_e64 s[78:79], s98, v87
	v_cndmask_b32_e64 v35, 0, v35, s[50:51]
	v_add_u32_e32 v88, 44, v84
	v_cmp_gt_u32_e64 s[50:51], s98, v88
	v_cndmask_b32_e64 v36, 0, v36, s[30:31]
	v_add_u32_e32 v85, 64, v84
	v_cmp_gt_u32_e64 s[30:31], s98, v85
	v_cndmask_b32_e64 v37, 0, v37, s[36:37]
	v_add_u32_e32 v86, 68, v84
	v_cmp_gt_u32_e64 s[36:37], s98, v86
	v_cndmask_b32_e64 v38, 0, v38, s[78:79]
	v_add_u32_e32 v87, 72, v84
	v_cmp_gt_u32_e64 s[78:79], s98, v87
	v_cndmask_b32_e64 v39, 0, v39, s[50:51]
	v_add_u32_e32 v88, 76, v84
	v_cmp_gt_u32_e64 s[50:51], s98, v88
	v_cndmask_b32_e64 v40, 0, v40, s[30:31]
	v_add_u32_e32 v85, 96, v84
	v_cmp_gt_u32_e64 s[30:31], s98, v85
	v_cndmask_b32_e64 v41, 0, v41, s[36:37]
	v_add_u32_e32 v86, 100, v84
	v_cmp_gt_u32_e64 s[36:37], s98, v86
	v_cndmask_b32_e64 v42, 0, v42, s[78:79]
	v_add_u32_e32 v87, 104, v84
	v_cmp_gt_u32_e64 s[78:79], s98, v87
	v_cndmask_b32_e64 v43, 0, v43, s[50:51]
	v_add_u32_e32 v88, 108, v84
	v_cmp_gt_u32_e64 s[50:51], s98, v88
	v_nop
	v_cndmask_b32_e64 v44, 0, v44, s[30:31]
	v_cndmask_b32_e64 v45, 0, v45, s[36:37]
	v_cndmask_b32_e64 v46, 0, v46, s[78:79]
	v_cndmask_b32_e64 v47, 0, v47, s[50:51]
	v_cvt_pk_bf16_f32 v64, v32, v33
	v_cvt_pk_bf16_f32 v65, v34, v35
	v_cvt_pk_bf16_f32 v66, v36, v37
	v_cvt_pk_bf16_f32 v67, v38, v39
	v_cvt_pk_bf16_f32 v68, v40, v41
	v_cvt_pk_bf16_f32 v69, v42, v43
	v_cvt_pk_bf16_f32 v70, v44, v45
	v_cvt_pk_bf16_f32 v71, v46, v47
	v_pk_add_f32 v[232:233], v[232:233], v[32:33]
	v_pk_add_f32 v[232:233], v[232:233], v[34:35]
	v_pk_add_f32 v[232:233], v[232:233], v[36:37]
	v_pk_add_f32 v[232:233], v[232:233], v[38:39]
	v_pk_add_f32 v[232:233], v[232:233], v[40:41]
	v_pk_add_f32 v[232:233], v[232:233], v[42:43]
	v_pk_add_f32 v[232:233], v[232:233], v[44:45]
	v_pk_add_f32 v[232:233], v[232:233], v[46:47]
	ds_read2_b32 v[32:33], v115 offset0:64 offset1:65
	ds_read2_b32 v[34:35], v115 offset0:66 offset1:67
	ds_read2_b32 v[36:37], v115 offset0:72 offset1:73
	ds_read2_b32 v[38:39], v115 offset0:74 offset1:75
	ds_read2_b32 v[40:41], v115 offset0:80 offset1:81
	ds_read2_b32 v[42:43], v115 offset0:82 offset1:83
	ds_read2_b32 v[44:45], v115 offset0:88 offset1:89
	ds_read2_b32 v[46:47], v115 offset0:90 offset1:91
	s_add_i32 s90, s67, 128
	v_add_u32_e32 v80, s90, v239
	v_add_u32_e32 v83, s90, v240
	v_add_u32_e32 v99, s90, v241
	v_add_u32_e32 v253, s90, v242
	v_add_u32_e32 v254, s90, v101
	v_add_u32_e32 v255, s90, v150
	v_med3_i32 v80, v80, 0, s99
	v_med3_i32 v83, v83, 0, s99
	v_med3_i32 v99, v99, 0, s99
	v_med3_i32 v253, v253, 0, s99
	v_med3_i32 v254, v254, 0, s99
	v_med3_i32 v255, v255, 0, s99
	v_mad_u32_u24 v80, v80, s100, v252
	v_mad_u32_u24 v83, v83, s100, v252
	v_mad_u32_u24 v99, v99, s100, v252
	v_mad_u32_u24 v253, v253, s100, v252
	v_mad_u32_u24 v254, v254, s100, v153
	v_mad_u32_u24 v255, v255, s100, v153
	global_load_dwordx4 v[156:159], v80, s[82:83]
	global_load_dwordx4 v[160:163], v83, s[82:83]
	global_load_dwordx4 v[164:167], v99, s[82:83]
	global_load_dwordx4 v[168:171], v253, s[82:83]
	global_load_dwordx4 v[172:175], v254, s[82:83] offset:768
	global_load_dwordx4 v[176:179], v255, s[82:83] offset:768
	global_load_dwordx4 v[180:183], v254, s[82:83] offset:832
	global_load_dwordx4 v[184:187], v255, s[82:83] offset:832
	ds_read_b64_tr_b16 v[204:205], v231
	ds_read_b64_tr_b16 v[206:207], v231 offset:512
	ds_read_b64_tr_b16 v[208:209], v231 offset:2048
	ds_read_b64_tr_b16 v[210:211], v231 offset:2560
	ds_read_b64_tr_b16 v[212:213], v231 offset:1024
	ds_read_b64_tr_b16 v[214:215], v231 offset:1536
	ds_read_b64_tr_b16 v[216:217], v231 offset:3072
	ds_read_b64_tr_b16 v[218:219], v231 offset:3584
	v_exp_f32_e32 v188, v188
	v_exp_f32_e32 v189, v189
	v_exp_f32_e32 v190, v190
	v_exp_f32_e32 v191, v191
	s_waitcnt vmcnt(8)
	ds_write_b128 v247, v[116:119]
	ds_write_b128 v247, v[120:123] offset:1024
	ds_write_b128 v247, v[124:127] offset:2048
	ds_write_b128 v247, v[128:131] offset:3072
	ds_read_b128 v[116:119], v248
	ds_read_b128 v[120:123], v249
	ds_read_b128 v[124:127], v250
	ds_read_b128 v[128:131], v251
	ds_write_b128 v112, v[132:135]
	ds_write_b128 v112, v[136:139] offset:1024
	ds_write_b128 v112, v[140:143] offset:2048
	ds_write_b128 v112, v[144:147] offset:3072
	v_mfma_f32_32x32x16_bf16 v[0:15], v[64:67], v[72:75], v[0:15]
	v_mfma_f32_32x32x16_bf16 v[16:31], v[64:67], v[76:79], v[16:31]
	v_mfma_f32_32x32x16_bf16 v[0:15], v[68:71], v[220:223], v[0:15]
	v_mfma_f32_32x32x16_bf16 v[16:31], v[68:71], v[224:227], v[16:31]
	v_exp_f32_e32 v192, v192
	v_exp_f32_e32 v193, v193
	v_exp_f32_e32 v194, v194
	v_exp_f32_e32 v195, v195
	s_waitcnt lgkmcnt(4)
	v_mfma_f32_32x32x16_bf16 v[32:47], v[116:119], v[48:51], v[32:47]
	v_exp_f32_e32 v196, v196
	v_exp_f32_e32 v197, v197
	v_mfma_f32_32x32x16_bf16 v[32:47], v[120:123], v[52:55], v[32:47]
	v_exp_f32_e32 v198, v198
	v_exp_f32_e32 v199, v199
	v_mfma_f32_32x32x16_bf16 v[32:47], v[124:127], v[56:59], v[32:47]
	v_exp_f32_e32 v200, v200
	v_exp_f32_e32 v201, v201
	v_mfma_f32_32x32x16_bf16 v[32:47], v[128:131], v[60:63], v[32:47]
	v_exp_f32_e32 v202, v202
	v_exp_f32_e32 v203, v203
	s_add_i32 s90, s67, -128
	v_lshlrev_b32_e32 v84, 2, v107
	v_add_u32_e32 v84, s90, v84
	v_add_u32_e32 v85, 0, v84
	v_add_u32_e32 v86, 4, v84
	v_add_u32_e32 v87, 8, v84
	v_add_u32_e32 v88, 12, v84
	v_cmp_gt_u32_e64 s[30:31], s98, v85
	v_cmp_gt_u32_e64 s[36:37], s98, v86
	v_cmp_gt_u32_e64 s[78:79], s98, v87
	v_cmp_gt_u32_e64 s[50:51], s98, v88
	v_cndmask_b32_e64 v188, 0, v188, s[30:31]
	v_add_u32_e32 v85, 32, v84
	v_cmp_gt_u32_e64 s[30:31], s98, v85
	v_cndmask_b32_e64 v189, 0, v189, s[36:37]
	v_add_u32_e32 v86, 36, v84
	v_cmp_gt_u32_e64 s[36:37], s98, v86
	v_cndmask_b32_e64 v190, 0, v190, s[78:79]
	v_add_u32_e32 v87, 40, v84
	v_cmp_gt_u32_e64 s[78:79], s98, v87
	v_cndmask_b32_e64 v191, 0, v191, s[50:51]
	v_add_u32_e32 v88, 44, v84
	v_cmp_gt_u32_e64 s[50:51], s98, v88
	v_cndmask_b32_e64 v192, 0, v192, s[30:31]
	v_add_u32_e32 v85, 64, v84
	v_cmp_gt_u32_e64 s[30:31], s98, v85
	v_cndmask_b32_e64 v193, 0, v193, s[36:37]
	v_add_u32_e32 v86, 68, v84
	v_cmp_gt_u32_e64 s[36:37], s98, v86
	v_cndmask_b32_e64 v194, 0, v194, s[78:79]
	v_add_u32_e32 v87, 72, v84
	v_cmp_gt_u32_e64 s[78:79], s98, v87
	v_cndmask_b32_e64 v195, 0, v195, s[50:51]
	v_add_u32_e32 v88, 76, v84
	v_cmp_gt_u32_e64 s[50:51], s98, v88
	v_cndmask_b32_e64 v196, 0, v196, s[30:31]
	v_add_u32_e32 v85, 96, v84
	v_cmp_gt_u32_e64 s[30:31], s98, v85
	v_cndmask_b32_e64 v197, 0, v197, s[36:37]
	v_add_u32_e32 v86, 100, v84
	v_cmp_gt_u32_e64 s[36:37], s98, v86
	v_cndmask_b32_e64 v198, 0, v198, s[78:79]
	v_add_u32_e32 v87, 104, v84
	v_cmp_gt_u32_e64 s[78:79], s98, v87
	v_cndmask_b32_e64 v199, 0, v199, s[50:51]
	v_add_u32_e32 v88, 108, v84
	v_cmp_gt_u32_e64 s[50:51], s98, v88
	v_nop
	v_cndmask_b32_e64 v200, 0, v200, s[30:31]
	v_cndmask_b32_e64 v201, 0, v201, s[36:37]
	v_cndmask_b32_e64 v202, 0, v202, s[78:79]
	v_cndmask_b32_e64 v203, 0, v203, s[50:51]
	v_cvt_pk_bf16_f32 v64, v188, v189
	v_cvt_pk_bf16_f32 v65, v190, v191
	v_cvt_pk_bf16_f32 v66, v192, v193
	v_cvt_pk_bf16_f32 v67, v194, v195
	v_cvt_pk_bf16_f32 v68, v196, v197
	v_cvt_pk_bf16_f32 v69, v198, v199
	v_cvt_pk_bf16_f32 v70, v200, v201
	v_cvt_pk_bf16_f32 v71, v202, v203
	v_pk_add_f32 v[232:233], v[232:233], v[188:189]
	v_pk_add_f32 v[232:233], v[232:233], v[190:191]
	v_pk_add_f32 v[232:233], v[232:233], v[192:193]
	v_pk_add_f32 v[232:233], v[232:233], v[194:195]
	v_pk_add_f32 v[232:233], v[232:233], v[196:197]
	v_pk_add_f32 v[232:233], v[232:233], v[198:199]
	v_pk_add_f32 v[232:233], v[232:233], v[200:201]
	v_pk_add_f32 v[232:233], v[232:233], v[202:203]
	ds_read2_b32 v[188:189], v115 offset0:96 offset1:97
	ds_read2_b32 v[190:191], v115 offset0:98 offset1:99
	ds_read2_b32 v[192:193], v115 offset0:104 offset1:105
	ds_read2_b32 v[194:195], v115 offset0:106 offset1:107
	ds_read2_b32 v[196:197], v115 offset0:112 offset1:113
	ds_read2_b32 v[198:199], v115 offset0:114 offset1:115
	ds_read2_b32 v[200:201], v115 offset0:120 offset1:121
	ds_read2_b32 v[202:203], v115 offset0:122 offset1:123
	s_add_i32 s90, s67, 256
	v_add_u32_e32 v80, s90, v239
	v_add_u32_e32 v83, s90, v240
	v_add_u32_e32 v99, s90, v241
	v_add_u32_e32 v253, s90, v242
	v_add_u32_e32 v254, s90, v101
	v_add_u32_e32 v255, s90, v150
	v_med3_i32 v80, v80, 0, s99
	v_med3_i32 v83, v83, 0, s99
	v_med3_i32 v99, v99, 0, s99
	v_med3_i32 v253, v253, 0, s99
	v_med3_i32 v254, v254, 0, s99
	v_med3_i32 v255, v255, 0, s99
	v_mad_u32_u24 v80, v80, s100, v252
	v_mad_u32_u24 v83, v83, s100, v252
	v_mad_u32_u24 v99, v99, s100, v252
	v_mad_u32_u24 v253, v253, s100, v252
	v_mad_u32_u24 v254, v254, s100, v153
	v_mad_u32_u24 v255, v255, s100, v153
	global_load_dwordx4 v[116:119], v80, s[82:83]
	global_load_dwordx4 v[120:123], v83, s[82:83]
	global_load_dwordx4 v[124:127], v99, s[82:83]
	global_load_dwordx4 v[128:131], v253, s[82:83]
	global_load_dwordx4 v[132:135], v254, s[82:83] offset:768
	global_load_dwordx4 v[136:139], v255, s[82:83] offset:768
	global_load_dwordx4 v[140:143], v254, s[82:83] offset:832
	global_load_dwordx4 v[144:147], v255, s[82:83] offset:832
	ds_read_b64_tr_b16 v[72:73], v231
	ds_read_b64_tr_b16 v[74:75], v231 offset:512
	ds_read_b64_tr_b16 v[76:77], v231 offset:2048
	ds_read_b64_tr_b16 v[78:79], v231 offset:2560
	ds_read_b64_tr_b16 v[220:221], v231 offset:1024
	ds_read_b64_tr_b16 v[222:223], v231 offset:1536
	ds_read_b64_tr_b16 v[224:225], v231 offset:3072
	ds_read_b64_tr_b16 v[226:227], v231 offset:3584
	v_exp_f32_e32 v32, v32
	v_exp_f32_e32 v33, v33
	v_exp_f32_e32 v34, v34
	v_exp_f32_e32 v35, v35
	s_waitcnt vmcnt(8)
	ds_write_b128 v247, v[156:159]
	ds_write_b128 v247, v[160:163] offset:1024
	ds_write_b128 v247, v[164:167] offset:2048
	ds_write_b128 v247, v[168:171] offset:3072
	ds_read_b128 v[156:159], v248
	ds_read_b128 v[160:163], v249
	ds_read_b128 v[164:167], v250
	ds_read_b128 v[168:171], v251
	ds_write_b128 v112, v[172:175]
	ds_write_b128 v112, v[176:179] offset:1024
	ds_write_b128 v112, v[180:183] offset:2048
	ds_write_b128 v112, v[184:187] offset:3072
	v_mfma_f32_32x32x16_bf16 v[0:15], v[64:67], v[204:207], v[0:15]
	v_mfma_f32_32x32x16_bf16 v[16:31], v[64:67], v[208:211], v[16:31]
	v_mfma_f32_32x32x16_bf16 v[0:15], v[68:71], v[212:215], v[0:15]
	v_mfma_f32_32x32x16_bf16 v[16:31], v[68:71], v[216:219], v[16:31]
	v_exp_f32_e32 v36, v36
	v_exp_f32_e32 v37, v37
	v_exp_f32_e32 v38, v38
	v_exp_f32_e32 v39, v39
	s_waitcnt lgkmcnt(4)
	v_mfma_f32_32x32x16_bf16 v[188:203], v[156:159], v[48:51], v[188:203]
	v_exp_f32_e32 v40, v40
	v_exp_f32_e32 v41, v41
	v_mfma_f32_32x32x16_bf16 v[188:203], v[160:163], v[52:55], v[188:203]
	v_exp_f32_e32 v42, v42
	v_exp_f32_e32 v43, v43
	v_mfma_f32_32x32x16_bf16 v[188:203], v[164:167], v[56:59], v[188:203]
	v_exp_f32_e32 v44, v44
	v_exp_f32_e32 v45, v45
	v_mfma_f32_32x32x16_bf16 v[188:203], v[168:171], v[60:63], v[188:203]
	v_exp_f32_e32 v46, v46
	v_exp_f32_e32 v47, v47
	s_add_i32 s90, s67, 0
	v_lshlrev_b32_e32 v84, 2, v107
	v_add_u32_e32 v84, s90, v84
	v_add_u32_e32 v85, 0, v84
	v_add_u32_e32 v86, 4, v84
	v_add_u32_e32 v87, 8, v84
	v_add_u32_e32 v88, 12, v84
	v_cmp_gt_u32_e64 s[30:31], s98, v85
	v_cmp_gt_u32_e64 s[36:37], s98, v86
	v_cmp_gt_u32_e64 s[78:79], s98, v87
	v_cmp_gt_u32_e64 s[50:51], s98, v88
	v_cndmask_b32_e64 v32, 0, v32, s[30:31]
	v_add_u32_e32 v85, 32, v84
	v_cmp_gt_u32_e64 s[30:31], s98, v85
	v_cndmask_b32_e64 v33, 0, v33, s[36:37]
	v_add_u32_e32 v86, 36, v84
	v_cmp_gt_u32_e64 s[36:37], s98, v86
	v_cndmask_b32_e64 v34, 0, v34, s[78:79]
	v_add_u32_e32 v87, 40, v84
	v_cmp_gt_u32_e64 s[78:79], s98, v87
	v_cndmask_b32_e64 v35, 0, v35, s[50:51]
	v_add_u32_e32 v88, 44, v84
	v_cmp_gt_u32_e64 s[50:51], s98, v88
	v_cndmask_b32_e64 v36, 0, v36, s[30:31]
	v_add_u32_e32 v85, 64, v84
	v_cmp_gt_u32_e64 s[30:31], s98, v85
	v_cndmask_b32_e64 v37, 0, v37, s[36:37]
	v_add_u32_e32 v86, 68, v84
	v_cmp_gt_u32_e64 s[36:37], s98, v86
	v_cndmask_b32_e64 v38, 0, v38, s[78:79]
	v_add_u32_e32 v87, 72, v84
	v_cmp_gt_u32_e64 s[78:79], s98, v87
	v_cndmask_b32_e64 v39, 0, v39, s[50:51]
	v_add_u32_e32 v88, 76, v84
	v_cmp_gt_u32_e64 s[50:51], s98, v88
	v_cndmask_b32_e64 v40, 0, v40, s[30:31]
	v_add_u32_e32 v85, 96, v84
	v_cmp_gt_u32_e64 s[30:31], s98, v85
	v_cndmask_b32_e64 v41, 0, v41, s[36:37]
	v_add_u32_e32 v86, 100, v84
	v_cmp_gt_u32_e64 s[36:37], s98, v86
	v_cndmask_b32_e64 v42, 0, v42, s[78:79]
	v_add_u32_e32 v87, 104, v84
	v_cmp_gt_u32_e64 s[78:79], s98, v87
	v_cndmask_b32_e64 v43, 0, v43, s[50:51]
	v_add_u32_e32 v88, 108, v84
	v_cmp_gt_u32_e64 s[50:51], s98, v88
	v_nop
	v_cndmask_b32_e64 v44, 0, v44, s[30:31]
	v_cndmask_b32_e64 v45, 0, v45, s[36:37]
	v_cndmask_b32_e64 v46, 0, v46, s[78:79]
	v_cndmask_b32_e64 v47, 0, v47, s[50:51]
	v_cvt_pk_bf16_f32 v64, v32, v33
	v_cvt_pk_bf16_f32 v65, v34, v35
	v_cvt_pk_bf16_f32 v66, v36, v37
	v_cvt_pk_bf16_f32 v67, v38, v39
	v_cvt_pk_bf16_f32 v68, v40, v41
	v_cvt_pk_bf16_f32 v69, v42, v43
	v_cvt_pk_bf16_f32 v70, v44, v45
	v_cvt_pk_bf16_f32 v71, v46, v47
	v_pk_add_f32 v[232:233], v[232:233], v[32:33]
	v_pk_add_f32 v[232:233], v[232:233], v[34:35]
	v_pk_add_f32 v[232:233], v[232:233], v[36:37]
	v_pk_add_f32 v[232:233], v[232:233], v[38:39]
	v_pk_add_f32 v[232:233], v[232:233], v[40:41]
	v_pk_add_f32 v[232:233], v[232:233], v[42:43]
	v_pk_add_f32 v[232:233], v[232:233], v[44:45]
	v_pk_add_f32 v[232:233], v[232:233], v[46:47]
	ds_read2_b32 v[32:33], v115 offset0:128 offset1:129
	ds_read2_b32 v[34:35], v115 offset0:130 offset1:131
	ds_read2_b32 v[36:37], v115 offset0:136 offset1:137
	ds_read2_b32 v[38:39], v115 offset0:138 offset1:139
	ds_read2_b32 v[40:41], v115 offset0:144 offset1:145
	ds_read2_b32 v[42:43], v115 offset0:146 offset1:147
	ds_read2_b32 v[44:45], v115 offset0:152 offset1:153
	ds_read2_b32 v[46:47], v115 offset0:154 offset1:155
	s_add_i32 s90, s67, 384
	v_add_u32_e32 v80, s90, v239
	v_add_u32_e32 v83, s90, v240
	v_add_u32_e32 v99, s90, v241
	v_add_u32_e32 v253, s90, v242
	v_add_u32_e32 v254, s90, v101
	v_add_u32_e32 v255, s90, v150
	v_med3_i32 v80, v80, 0, s99
	v_med3_i32 v83, v83, 0, s99
	v_med3_i32 v99, v99, 0, s99
	v_med3_i32 v253, v253, 0, s99
	v_med3_i32 v254, v254, 0, s99
	v_med3_i32 v255, v255, 0, s99
	v_mad_u32_u24 v80, v80, s100, v252
	v_mad_u32_u24 v83, v83, s100, v252
	v_mad_u32_u24 v99, v99, s100, v252
	v_mad_u32_u24 v253, v253, s100, v252
	v_mad_u32_u24 v254, v254, s100, v153
	v_mad_u32_u24 v255, v255, s100, v153
	global_load_dwordx4 v[156:159], v80, s[82:83]
	global_load_dwordx4 v[160:163], v83, s[82:83]
	global_load_dwordx4 v[164:167], v99, s[82:83]
	global_load_dwordx4 v[168:171], v253, s[82:83]
	global_load_dwordx4 v[172:175], v254, s[82:83] offset:768
	global_load_dwordx4 v[176:179], v255, s[82:83] offset:768
	global_load_dwordx4 v[180:183], v254, s[82:83] offset:832
	global_load_dwordx4 v[184:187], v255, s[82:83] offset:832
	ds_read_b64_tr_b16 v[204:205], v231
	ds_read_b64_tr_b16 v[206:207], v231 offset:512
	ds_read_b64_tr_b16 v[208:209], v231 offset:2048
	ds_read_b64_tr_b16 v[210:211], v231 offset:2560
	ds_read_b64_tr_b16 v[212:213], v231 offset:1024
	ds_read_b64_tr_b16 v[214:215], v231 offset:1536
	ds_read_b64_tr_b16 v[216:217], v231 offset:3072
	ds_read_b64_tr_b16 v[218:219], v231 offset:3584
	v_exp_f32_e32 v188, v188
	v_exp_f32_e32 v189, v189
	v_exp_f32_e32 v190, v190
	v_exp_f32_e32 v191, v191
	s_waitcnt vmcnt(8)
	ds_write_b128 v247, v[116:119]
	ds_write_b128 v247, v[120:123] offset:1024
	ds_write_b128 v247, v[124:127] offset:2048
	ds_write_b128 v247, v[128:131] offset:3072
	ds_read_b128 v[116:119], v248
	ds_read_b128 v[120:123], v249
	ds_read_b128 v[124:127], v250
	ds_read_b128 v[128:131], v251
	ds_write_b128 v112, v[132:135]
	ds_write_b128 v112, v[136:139] offset:1024
	ds_write_b128 v112, v[140:143] offset:2048
	ds_write_b128 v112, v[144:147] offset:3072
	v_mfma_f32_32x32x16_bf16 v[0:15], v[64:67], v[72:75], v[0:15]
	v_mfma_f32_32x32x16_bf16 v[16:31], v[64:67], v[76:79], v[16:31]
	v_mfma_f32_32x32x16_bf16 v[0:15], v[68:71], v[220:223], v[0:15]
	v_mfma_f32_32x32x16_bf16 v[16:31], v[68:71], v[224:227], v[16:31]
	v_exp_f32_e32 v192, v192
	v_exp_f32_e32 v193, v193
	v_exp_f32_e32 v194, v194
	v_exp_f32_e32 v195, v195
	s_waitcnt lgkmcnt(4)
	v_mfma_f32_32x32x16_bf16 v[32:47], v[116:119], v[48:51], v[32:47]
	v_exp_f32_e32 v196, v196
	v_exp_f32_e32 v197, v197
	v_mfma_f32_32x32x16_bf16 v[32:47], v[120:123], v[52:55], v[32:47]
	v_exp_f32_e32 v198, v198
	v_exp_f32_e32 v199, v199
	v_mfma_f32_32x32x16_bf16 v[32:47], v[124:127], v[56:59], v[32:47]
	v_exp_f32_e32 v200, v200
	v_exp_f32_e32 v201, v201
	v_mfma_f32_32x32x16_bf16 v[32:47], v[128:131], v[60:63], v[32:47]
	v_exp_f32_e32 v202, v202
	v_exp_f32_e32 v203, v203
	s_add_i32 s90, s67, 128
	v_lshlrev_b32_e32 v84, 2, v107
	v_add_u32_e32 v84, s90, v84
	v_add_u32_e32 v85, 0, v84
	v_add_u32_e32 v86, 4, v84
	v_add_u32_e32 v87, 8, v84
	v_add_u32_e32 v88, 12, v84
	v_cmp_gt_u32_e64 s[30:31], s98, v85
	v_cmp_gt_u32_e64 s[36:37], s98, v86
	v_cmp_gt_u32_e64 s[78:79], s98, v87
	v_cmp_gt_u32_e64 s[50:51], s98, v88
	v_cndmask_b32_e64 v188, 0, v188, s[30:31]
	v_add_u32_e32 v85, 32, v84
	v_cmp_gt_u32_e64 s[30:31], s98, v85
	v_cndmask_b32_e64 v189, 0, v189, s[36:37]
	v_add_u32_e32 v86, 36, v84
	v_cmp_gt_u32_e64 s[36:37], s98, v86
	v_cndmask_b32_e64 v190, 0, v190, s[78:79]
	v_add_u32_e32 v87, 40, v84
	v_cmp_gt_u32_e64 s[78:79], s98, v87
	v_cndmask_b32_e64 v191, 0, v191, s[50:51]
	v_add_u32_e32 v88, 44, v84
	v_cmp_gt_u32_e64 s[50:51], s98, v88
	v_cndmask_b32_e64 v192, 0, v192, s[30:31]
	v_add_u32_e32 v85, 64, v84
	v_cmp_gt_u32_e64 s[30:31], s98, v85
	v_cndmask_b32_e64 v193, 0, v193, s[36:37]
	v_add_u32_e32 v86, 68, v84
	v_cmp_gt_u32_e64 s[36:37], s98, v86
	v_cndmask_b32_e64 v194, 0, v194, s[78:79]
	v_add_u32_e32 v87, 72, v84
	v_cmp_gt_u32_e64 s[78:79], s98, v87
	v_cndmask_b32_e64 v195, 0, v195, s[50:51]
	v_add_u32_e32 v88, 76, v84
	v_cmp_gt_u32_e64 s[50:51], s98, v88
	v_cndmask_b32_e64 v196, 0, v196, s[30:31]
	v_add_u32_e32 v85, 96, v84
	v_cmp_gt_u32_e64 s[30:31], s98, v85
	v_cndmask_b32_e64 v197, 0, v197, s[36:37]
	v_add_u32_e32 v86, 100, v84
	v_cmp_gt_u32_e64 s[36:37], s98, v86
	v_cndmask_b32_e64 v198, 0, v198, s[78:79]
	v_add_u32_e32 v87, 104, v84
	v_cmp_gt_u32_e64 s[78:79], s98, v87
	v_cndmask_b32_e64 v199, 0, v199, s[50:51]
	v_add_u32_e32 v88, 108, v84
	v_cmp_gt_u32_e64 s[50:51], s98, v88
	v_nop
	v_cndmask_b32_e64 v200, 0, v200, s[30:31]
	v_cndmask_b32_e64 v201, 0, v201, s[36:37]
	v_cndmask_b32_e64 v202, 0, v202, s[78:79]
	v_cndmask_b32_e64 v203, 0, v203, s[50:51]
	v_cvt_pk_bf16_f32 v64, v188, v189
	v_cvt_pk_bf16_f32 v65, v190, v191
	v_cvt_pk_bf16_f32 v66, v192, v193
	v_cvt_pk_bf16_f32 v67, v194, v195
	v_cvt_pk_bf16_f32 v68, v196, v197
	v_cvt_pk_bf16_f32 v69, v198, v199
	v_cvt_pk_bf16_f32 v70, v200, v201
	v_cvt_pk_bf16_f32 v71, v202, v203
	v_pk_add_f32 v[232:233], v[232:233], v[188:189]
	v_pk_add_f32 v[232:233], v[232:233], v[190:191]
	v_pk_add_f32 v[232:233], v[232:233], v[192:193]
	v_pk_add_f32 v[232:233], v[232:233], v[194:195]
	v_pk_add_f32 v[232:233], v[232:233], v[196:197]
	v_pk_add_f32 v[232:233], v[232:233], v[198:199]
	v_pk_add_f32 v[232:233], v[232:233], v[200:201]
	v_pk_add_f32 v[232:233], v[232:233], v[202:203]
	ds_read2_b32 v[188:189], v115 offset0:160 offset1:161
	ds_read2_b32 v[190:191], v115 offset0:162 offset1:163
	ds_read2_b32 v[192:193], v115 offset0:168 offset1:169
	ds_read2_b32 v[194:195], v115 offset0:170 offset1:171
	ds_read2_b32 v[196:197], v115 offset0:176 offset1:177
	ds_read2_b32 v[198:199], v115 offset0:178 offset1:179
	ds_read2_b32 v[200:201], v115 offset0:184 offset1:185
	ds_read2_b32 v[202:203], v115 offset0:186 offset1:187
	s_add_i32 s90, s67, 512
	v_add_u32_e32 v80, s90, v239
	v_add_u32_e32 v83, s90, v240
	v_add_u32_e32 v99, s90, v241
	v_add_u32_e32 v253, s90, v242
	v_add_u32_e32 v254, s90, v101
	v_add_u32_e32 v255, s90, v150
	v_med3_i32 v80, v80, 0, s99
	v_med3_i32 v83, v83, 0, s99
	v_med3_i32 v99, v99, 0, s99
	v_med3_i32 v253, v253, 0, s99
	v_med3_i32 v254, v254, 0, s99
	v_med3_i32 v255, v255, 0, s99
	v_mad_u32_u24 v80, v80, s100, v252
	v_mad_u32_u24 v83, v83, s100, v252
	v_mad_u32_u24 v99, v99, s100, v252
	v_mad_u32_u24 v253, v253, s100, v252
	v_mad_u32_u24 v254, v254, s100, v153
	v_mad_u32_u24 v255, v255, s100, v153
	global_load_dwordx4 v[116:119], v80, s[82:83]
	global_load_dwordx4 v[120:123], v83, s[82:83]
	global_load_dwordx4 v[124:127], v99, s[82:83]
	global_load_dwordx4 v[128:131], v253, s[82:83]
	global_load_dwordx4 v[132:135], v254, s[82:83] offset:768
	global_load_dwordx4 v[136:139], v255, s[82:83] offset:768
	global_load_dwordx4 v[140:143], v254, s[82:83] offset:832
	global_load_dwordx4 v[144:147], v255, s[82:83] offset:832
	ds_read_b64_tr_b16 v[72:73], v231
	ds_read_b64_tr_b16 v[74:75], v231 offset:512
	ds_read_b64_tr_b16 v[76:77], v231 offset:2048
	ds_read_b64_tr_b16 v[78:79], v231 offset:2560
	ds_read_b64_tr_b16 v[220:221], v231 offset:1024
	ds_read_b64_tr_b16 v[222:223], v231 offset:1536
	ds_read_b64_tr_b16 v[224:225], v231 offset:3072
	ds_read_b64_tr_b16 v[226:227], v231 offset:3584
	v_exp_f32_e32 v32, v32
	v_exp_f32_e32 v33, v33
	v_exp_f32_e32 v34, v34
	v_exp_f32_e32 v35, v35
	s_waitcnt vmcnt(8)
	ds_write_b128 v247, v[156:159]
	ds_write_b128 v247, v[160:163] offset:1024
	ds_write_b128 v247, v[164:167] offset:2048
	ds_write_b128 v247, v[168:171] offset:3072
	ds_read_b128 v[156:159], v248
	ds_read_b128 v[160:163], v249
	ds_read_b128 v[164:167], v250
	ds_read_b128 v[168:171], v251
	ds_write_b128 v112, v[172:175]
	ds_write_b128 v112, v[176:179] offset:1024
	ds_write_b128 v112, v[180:183] offset:2048
	ds_write_b128 v112, v[184:187] offset:3072
	v_mfma_f32_32x32x16_bf16 v[0:15], v[64:67], v[204:207], v[0:15]
	v_mfma_f32_32x32x16_bf16 v[16:31], v[64:67], v[208:211], v[16:31]
	v_mfma_f32_32x32x16_bf16 v[0:15], v[68:71], v[212:215], v[0:15]
	v_mfma_f32_32x32x16_bf16 v[16:31], v[68:71], v[216:219], v[16:31]
	v_exp_f32_e32 v36, v36
	v_exp_f32_e32 v37, v37
	v_exp_f32_e32 v38, v38
	v_exp_f32_e32 v39, v39
	s_waitcnt lgkmcnt(4)
	v_mfma_f32_32x32x16_bf16 v[188:203], v[156:159], v[48:51], v[188:203]
	v_exp_f32_e32 v40, v40
	v_exp_f32_e32 v41, v41
	v_mfma_f32_32x32x16_bf16 v[188:203], v[160:163], v[52:55], v[188:203]
	v_exp_f32_e32 v42, v42
	v_exp_f32_e32 v43, v43
	v_mfma_f32_32x32x16_bf16 v[188:203], v[164:167], v[56:59], v[188:203]
	v_exp_f32_e32 v44, v44
	v_exp_f32_e32 v45, v45
	v_mfma_f32_32x32x16_bf16 v[188:203], v[168:171], v[60:63], v[188:203]
	v_exp_f32_e32 v46, v46
	v_exp_f32_e32 v47, v47
	s_add_i32 s90, s67, 256
	v_lshlrev_b32_e32 v84, 2, v107
	v_add_u32_e32 v84, s90, v84
	v_add_u32_e32 v85, 0, v84
	v_add_u32_e32 v86, 4, v84
	v_add_u32_e32 v87, 8, v84
	v_add_u32_e32 v88, 12, v84
	v_cmp_gt_u32_e64 s[30:31], s98, v85
	v_cmp_gt_u32_e64 s[36:37], s98, v86
	v_cmp_gt_u32_e64 s[78:79], s98, v87
	v_cmp_gt_u32_e64 s[50:51], s98, v88
	v_cndmask_b32_e64 v32, 0, v32, s[30:31]
	v_add_u32_e32 v85, 32, v84
	v_cmp_gt_u32_e64 s[30:31], s98, v85
	v_cndmask_b32_e64 v33, 0, v33, s[36:37]
	v_add_u32_e32 v86, 36, v84
	v_cmp_gt_u32_e64 s[36:37], s98, v86
	v_cndmask_b32_e64 v34, 0, v34, s[78:79]
	v_add_u32_e32 v87, 40, v84
	v_cmp_gt_u32_e64 s[78:79], s98, v87
	v_cndmask_b32_e64 v35, 0, v35, s[50:51]
	v_add_u32_e32 v88, 44, v84
	v_cmp_gt_u32_e64 s[50:51], s98, v88
	v_cndmask_b32_e64 v36, 0, v36, s[30:31]
	v_add_u32_e32 v85, 64, v84
	v_cmp_gt_u32_e64 s[30:31], s98, v85
	v_cndmask_b32_e64 v37, 0, v37, s[36:37]
	v_add_u32_e32 v86, 68, v84
	v_cmp_gt_u32_e64 s[36:37], s98, v86
	v_cndmask_b32_e64 v38, 0, v38, s[78:79]
	v_add_u32_e32 v87, 72, v84
	v_cmp_gt_u32_e64 s[78:79], s98, v87
	v_cndmask_b32_e64 v39, 0, v39, s[50:51]
	v_add_u32_e32 v88, 76, v84
	v_cmp_gt_u32_e64 s[50:51], s98, v88
	v_cndmask_b32_e64 v40, 0, v40, s[30:31]
	v_add_u32_e32 v85, 96, v84
	v_cmp_gt_u32_e64 s[30:31], s98, v85
	v_cndmask_b32_e64 v41, 0, v41, s[36:37]
	v_add_u32_e32 v86, 100, v84
	v_cmp_gt_u32_e64 s[36:37], s98, v86
	v_cndmask_b32_e64 v42, 0, v42, s[78:79]
	v_add_u32_e32 v87, 104, v84
	v_cmp_gt_u32_e64 s[78:79], s98, v87
	v_cndmask_b32_e64 v43, 0, v43, s[50:51]
	v_add_u32_e32 v88, 108, v84
	v_cmp_gt_u32_e64 s[50:51], s98, v88
	v_nop
	v_cndmask_b32_e64 v44, 0, v44, s[30:31]
	v_cndmask_b32_e64 v45, 0, v45, s[36:37]
	v_cndmask_b32_e64 v46, 0, v46, s[78:79]
	v_cndmask_b32_e64 v47, 0, v47, s[50:51]
	v_cvt_pk_bf16_f32 v64, v32, v33
	v_cvt_pk_bf16_f32 v65, v34, v35
	v_cvt_pk_bf16_f32 v66, v36, v37
	v_cvt_pk_bf16_f32 v67, v38, v39
	v_cvt_pk_bf16_f32 v68, v40, v41
	v_cvt_pk_bf16_f32 v69, v42, v43
	v_cvt_pk_bf16_f32 v70, v44, v45
	v_cvt_pk_bf16_f32 v71, v46, v47
	v_pk_add_f32 v[232:233], v[232:233], v[32:33]
	v_pk_add_f32 v[232:233], v[232:233], v[34:35]
	v_pk_add_f32 v[232:233], v[232:233], v[36:37]
	v_pk_add_f32 v[232:233], v[232:233], v[38:39]
	v_pk_add_f32 v[232:233], v[232:233], v[40:41]
	v_pk_add_f32 v[232:233], v[232:233], v[42:43]
	v_pk_add_f32 v[232:233], v[232:233], v[44:45]
	v_pk_add_f32 v[232:233], v[232:233], v[46:47]
	ds_read2_b32 v[32:33], v115 offset0:192 offset1:193
	ds_read2_b32 v[34:35], v115 offset0:194 offset1:195
	ds_read2_b32 v[36:37], v115 offset0:200 offset1:201
	ds_read2_b32 v[38:39], v115 offset0:202 offset1:203
	ds_read2_b32 v[40:41], v115 offset0:208 offset1:209
	ds_read2_b32 v[42:43], v115 offset0:210 offset1:211
	ds_read2_b32 v[44:45], v115 offset0:216 offset1:217
	ds_read2_b32 v[46:47], v115 offset0:218 offset1:219
	s_add_i32 s90, s67, 640
	v_add_u32_e32 v80, s90, v239
	v_add_u32_e32 v83, s90, v240
	v_add_u32_e32 v99, s90, v241
	v_add_u32_e32 v253, s90, v242
	v_add_u32_e32 v254, s90, v101
	v_add_u32_e32 v255, s90, v150
	v_med3_i32 v80, v80, 0, s99
	v_med3_i32 v83, v83, 0, s99
	v_med3_i32 v99, v99, 0, s99
	v_med3_i32 v253, v253, 0, s99
	v_med3_i32 v254, v254, 0, s99
	v_med3_i32 v255, v255, 0, s99
	v_mad_u32_u24 v80, v80, s100, v252
	v_mad_u32_u24 v83, v83, s100, v252
	v_mad_u32_u24 v99, v99, s100, v252
	v_mad_u32_u24 v253, v253, s100, v252
	v_mad_u32_u24 v254, v254, s100, v153
	v_mad_u32_u24 v255, v255, s100, v153
	global_load_dwordx4 v[156:159], v80, s[82:83]
	global_load_dwordx4 v[160:163], v83, s[82:83]
	global_load_dwordx4 v[164:167], v99, s[82:83]
	global_load_dwordx4 v[168:171], v253, s[82:83]
	global_load_dwordx4 v[172:175], v254, s[82:83] offset:768
	global_load_dwordx4 v[176:179], v255, s[82:83] offset:768
	global_load_dwordx4 v[180:183], v254, s[82:83] offset:832
	global_load_dwordx4 v[184:187], v255, s[82:83] offset:832
	ds_read_b64_tr_b16 v[204:205], v231
	ds_read_b64_tr_b16 v[206:207], v231 offset:512
	ds_read_b64_tr_b16 v[208:209], v231 offset:2048
	ds_read_b64_tr_b16 v[210:211], v231 offset:2560
	ds_read_b64_tr_b16 v[212:213], v231 offset:1024
	ds_read_b64_tr_b16 v[214:215], v231 offset:1536
	ds_read_b64_tr_b16 v[216:217], v231 offset:3072
	ds_read_b64_tr_b16 v[218:219], v231 offset:3584
	v_exp_f32_e32 v188, v188
	v_exp_f32_e32 v189, v189
	v_exp_f32_e32 v190, v190
	v_exp_f32_e32 v191, v191
	s_waitcnt vmcnt(8)
	ds_write_b128 v247, v[116:119]
	ds_write_b128 v247, v[120:123] offset:1024
	ds_write_b128 v247, v[124:127] offset:2048
	ds_write_b128 v247, v[128:131] offset:3072
	ds_read_b128 v[116:119], v248
	ds_read_b128 v[120:123], v249
	ds_read_b128 v[124:127], v250
	ds_read_b128 v[128:131], v251
	ds_write_b128 v112, v[132:135]
	ds_write_b128 v112, v[136:139] offset:1024
	ds_write_b128 v112, v[140:143] offset:2048
	ds_write_b128 v112, v[144:147] offset:3072
	v_mfma_f32_32x32x16_bf16 v[0:15], v[64:67], v[72:75], v[0:15]
	v_mfma_f32_32x32x16_bf16 v[16:31], v[64:67], v[76:79], v[16:31]
	v_mfma_f32_32x32x16_bf16 v[0:15], v[68:71], v[220:223], v[0:15]
	v_mfma_f32_32x32x16_bf16 v[16:31], v[68:71], v[224:227], v[16:31]
	v_exp_f32_e32 v192, v192
	v_exp_f32_e32 v193, v193
	v_exp_f32_e32 v194, v194
	v_exp_f32_e32 v195, v195
	s_waitcnt lgkmcnt(4)
	v_mfma_f32_32x32x16_bf16 v[32:47], v[116:119], v[48:51], v[32:47]
	v_exp_f32_e32 v196, v196
	v_exp_f32_e32 v197, v197
	v_mfma_f32_32x32x16_bf16 v[32:47], v[120:123], v[52:55], v[32:47]
	v_exp_f32_e32 v198, v198
	v_exp_f32_e32 v199, v199
	v_mfma_f32_32x32x16_bf16 v[32:47], v[124:127], v[56:59], v[32:47]
	v_exp_f32_e32 v200, v200
	v_exp_f32_e32 v201, v201
	v_mfma_f32_32x32x16_bf16 v[32:47], v[128:131], v[60:63], v[32:47]
	v_exp_f32_e32 v202, v202
	v_exp_f32_e32 v203, v203
	s_add_i32 s90, s67, 384
	v_lshlrev_b32_e32 v84, 2, v107
	v_add_u32_e32 v84, s90, v84
	v_add_u32_e32 v85, 0, v84
	v_add_u32_e32 v86, 4, v84
	v_add_u32_e32 v87, 8, v84
	v_add_u32_e32 v88, 12, v84
	v_cmp_gt_u32_e64 s[30:31], s98, v85
	v_cmp_gt_u32_e64 s[36:37], s98, v86
	v_cmp_gt_u32_e64 s[78:79], s98, v87
	v_cmp_gt_u32_e64 s[50:51], s98, v88
	v_cndmask_b32_e64 v188, 0, v188, s[30:31]
	v_add_u32_e32 v85, 32, v84
	v_cmp_gt_u32_e64 s[30:31], s98, v85
	v_cndmask_b32_e64 v189, 0, v189, s[36:37]
	v_add_u32_e32 v86, 36, v84
	v_cmp_gt_u32_e64 s[36:37], s98, v86
	v_cndmask_b32_e64 v190, 0, v190, s[78:79]
	v_add_u32_e32 v87, 40, v84
	v_cmp_gt_u32_e64 s[78:79], s98, v87
	v_cndmask_b32_e64 v191, 0, v191, s[50:51]
	v_add_u32_e32 v88, 44, v84
	v_cmp_gt_u32_e64 s[50:51], s98, v88
	v_cndmask_b32_e64 v192, 0, v192, s[30:31]
	v_add_u32_e32 v85, 64, v84
	v_cmp_gt_u32_e64 s[30:31], s98, v85
	v_cndmask_b32_e64 v193, 0, v193, s[36:37]
	v_add_u32_e32 v86, 68, v84
	v_cmp_gt_u32_e64 s[36:37], s98, v86
	v_cndmask_b32_e64 v194, 0, v194, s[78:79]
	v_add_u32_e32 v87, 72, v84
	v_cmp_gt_u32_e64 s[78:79], s98, v87
	v_cndmask_b32_e64 v195, 0, v195, s[50:51]
	v_add_u32_e32 v88, 76, v84
	v_cmp_gt_u32_e64 s[50:51], s98, v88
	v_cndmask_b32_e64 v196, 0, v196, s[30:31]
	v_add_u32_e32 v85, 96, v84
	v_cmp_gt_u32_e64 s[30:31], s98, v85
	v_cndmask_b32_e64 v197, 0, v197, s[36:37]
	v_add_u32_e32 v86, 100, v84
	v_cmp_gt_u32_e64 s[36:37], s98, v86
	v_cndmask_b32_e64 v198, 0, v198, s[78:79]
	v_add_u32_e32 v87, 104, v84
	v_cmp_gt_u32_e64 s[78:79], s98, v87
	v_cndmask_b32_e64 v199, 0, v199, s[50:51]
	v_add_u32_e32 v88, 108, v84
	v_cmp_gt_u32_e64 s[50:51], s98, v88
	v_nop
	v_cndmask_b32_e64 v200, 0, v200, s[30:31]
	v_cndmask_b32_e64 v201, 0, v201, s[36:37]
	v_cndmask_b32_e64 v202, 0, v202, s[78:79]
	v_cndmask_b32_e64 v203, 0, v203, s[50:51]
	v_cvt_pk_bf16_f32 v64, v188, v189
	v_cvt_pk_bf16_f32 v65, v190, v191
	v_cvt_pk_bf16_f32 v66, v192, v193
	v_cvt_pk_bf16_f32 v67, v194, v195
	v_cvt_pk_bf16_f32 v68, v196, v197
	v_cvt_pk_bf16_f32 v69, v198, v199
	v_cvt_pk_bf16_f32 v70, v200, v201
	v_cvt_pk_bf16_f32 v71, v202, v203
	v_pk_add_f32 v[232:233], v[232:233], v[188:189]
	v_pk_add_f32 v[232:233], v[232:233], v[190:191]
	v_pk_add_f32 v[232:233], v[232:233], v[192:193]
	v_pk_add_f32 v[232:233], v[232:233], v[194:195]
	v_pk_add_f32 v[232:233], v[232:233], v[196:197]
	v_pk_add_f32 v[232:233], v[232:233], v[198:199]
	v_pk_add_f32 v[232:233], v[232:233], v[200:201]
	v_pk_add_f32 v[232:233], v[232:233], v[202:203]
	ds_read2_b32 v[188:189], v115 offset0:224 offset1:225
	ds_read2_b32 v[190:191], v115 offset0:226 offset1:227
	ds_read2_b32 v[192:193], v115 offset0:232 offset1:233
	ds_read2_b32 v[194:195], v115 offset0:234 offset1:235
	ds_read2_b32 v[196:197], v115 offset0:240 offset1:241
	ds_read2_b32 v[198:199], v115 offset0:242 offset1:243
	ds_read2_b32 v[200:201], v115 offset0:248 offset1:249
	ds_read2_b32 v[202:203], v115 offset0:250 offset1:251
	s_add_i32 s90, s67, -1024
	v_add_u32_e32 v80, s90, v243
	v_add_u32_e32 v83, s90, v244
	v_add_u32_e32 v99, s90, v245
	v_add_u32_e32 v253, s90, v246
	v_add_u32_e32 v254, s90, v148
	v_add_u32_e32 v255, s90, v151
	v_med3_i32 v80, v80, 0, s99
	v_med3_i32 v83, v83, 0, s99
	v_med3_i32 v99, v99, 0, s99
	v_med3_i32 v253, v253, 0, s99
	v_med3_i32 v254, v254, 0, s99
	v_med3_i32 v255, v255, 0, s99
	v_mad_u32_u24 v80, v80, s100, v252
	v_mad_u32_u24 v83, v83, s100, v252
	v_mad_u32_u24 v99, v99, s100, v252
	v_mad_u32_u24 v253, v253, s100, v252
	v_mad_u32_u24 v254, v254, s100, v153
	v_mad_u32_u24 v255, v255, s100, v153
	global_load_dwordx4 v[116:119], v80, s[82:83]
	global_load_dwordx4 v[120:123], v83, s[82:83]
	global_load_dwordx4 v[124:127], v99, s[82:83]
	global_load_dwordx4 v[128:131], v253, s[82:83]
	global_load_dwordx4 v[132:135], v254, s[82:83] offset:768
	global_load_dwordx4 v[136:139], v255, s[82:83] offset:768
	global_load_dwordx4 v[140:143], v254, s[82:83] offset:832
	global_load_dwordx4 v[144:147], v255, s[82:83] offset:832
	ds_read_b64_tr_b16 v[72:73], v231
	ds_read_b64_tr_b16 v[74:75], v231 offset:512
	ds_read_b64_tr_b16 v[76:77], v231 offset:2048
	ds_read_b64_tr_b16 v[78:79], v231 offset:2560
	ds_read_b64_tr_b16 v[220:221], v231 offset:1024
	ds_read_b64_tr_b16 v[222:223], v231 offset:1536
	ds_read_b64_tr_b16 v[224:225], v231 offset:3072
	ds_read_b64_tr_b16 v[226:227], v231 offset:3584
	v_exp_f32_e32 v32, v32
	v_exp_f32_e32 v33, v33
	v_exp_f32_e32 v34, v34
	v_exp_f32_e32 v35, v35
	s_waitcnt vmcnt(8)
	ds_write_b128 v247, v[156:159]
	ds_write_b128 v247, v[160:163] offset:1024
	ds_write_b128 v247, v[164:167] offset:2048
	ds_write_b128 v247, v[168:171] offset:3072
	ds_read_b128 v[156:159], v248
	ds_read_b128 v[160:163], v249
	ds_read_b128 v[164:167], v250
	ds_read_b128 v[168:171], v251
	ds_write_b128 v112, v[172:175]
	ds_write_b128 v112, v[176:179] offset:1024
	ds_write_b128 v112, v[180:183] offset:2048
	ds_write_b128 v112, v[184:187] offset:3072
	v_mfma_f32_32x32x16_bf16 v[0:15], v[64:67], v[204:207], v[0:15]
	v_mfma_f32_32x32x16_bf16 v[16:31], v[64:67], v[208:211], v[16:31]
	v_mfma_f32_32x32x16_bf16 v[0:15], v[68:71], v[212:215], v[0:15]
	v_mfma_f32_32x32x16_bf16 v[16:31], v[68:71], v[216:219], v[16:31]
	v_exp_f32_e32 v36, v36
	v_exp_f32_e32 v37, v37
	v_exp_f32_e32 v38, v38
	v_exp_f32_e32 v39, v39
	s_waitcnt lgkmcnt(4)
	v_mfma_f32_32x32x16_bf16 v[188:203], v[156:159], v[48:51], v[188:203]
	v_exp_f32_e32 v40, v40
	v_exp_f32_e32 v41, v41
	v_mfma_f32_32x32x16_bf16 v[188:203], v[160:163], v[52:55], v[188:203]
	v_exp_f32_e32 v42, v42
	v_exp_f32_e32 v43, v43
	v_mfma_f32_32x32x16_bf16 v[188:203], v[164:167], v[56:59], v[188:203]
	v_exp_f32_e32 v44, v44
	v_exp_f32_e32 v45, v45
	v_mfma_f32_32x32x16_bf16 v[188:203], v[168:171], v[60:63], v[188:203]
	v_exp_f32_e32 v46, v46
	v_exp_f32_e32 v47, v47
	s_add_i32 s90, s67, 512
	v_lshlrev_b32_e32 v84, 2, v107
	v_add_u32_e32 v84, s90, v84
	v_add_u32_e32 v85, 0, v84
	v_add_u32_e32 v86, 4, v84
	v_add_u32_e32 v87, 8, v84
	v_add_u32_e32 v88, 12, v84
	v_cmp_gt_u32_e64 s[30:31], s98, v85
	v_cmp_gt_u32_e64 s[36:37], s98, v86
	v_cmp_gt_u32_e64 s[78:79], s98, v87
	v_cmp_gt_u32_e64 s[50:51], s98, v88
	v_cndmask_b32_e64 v32, 0, v32, s[30:31]
	v_add_u32_e32 v85, 32, v84
	v_cmp_gt_u32_e64 s[30:31], s98, v85
	v_cndmask_b32_e64 v33, 0, v33, s[36:37]
	v_add_u32_e32 v86, 36, v84
	v_cmp_gt_u32_e64 s[36:37], s98, v86
	v_cndmask_b32_e64 v34, 0, v34, s[78:79]
	v_add_u32_e32 v87, 40, v84
	v_cmp_gt_u32_e64 s[78:79], s98, v87
	v_cndmask_b32_e64 v35, 0, v35, s[50:51]
	v_add_u32_e32 v88, 44, v84
	v_cmp_gt_u32_e64 s[50:51], s98, v88
	v_cndmask_b32_e64 v36, 0, v36, s[30:31]
	v_add_u32_e32 v85, 64, v84
	v_cmp_gt_u32_e64 s[30:31], s98, v85
	v_cndmask_b32_e64 v37, 0, v37, s[36:37]
	v_add_u32_e32 v86, 68, v84
	v_cmp_gt_u32_e64 s[36:37], s98, v86
	v_cndmask_b32_e64 v38, 0, v38, s[78:79]
	v_add_u32_e32 v87, 72, v84
	v_cmp_gt_u32_e64 s[78:79], s98, v87
	v_cndmask_b32_e64 v39, 0, v39, s[50:51]
	v_add_u32_e32 v88, 76, v84
	v_cmp_gt_u32_e64 s[50:51], s98, v88
	v_cndmask_b32_e64 v40, 0, v40, s[30:31]
	v_add_u32_e32 v85, 96, v84
	v_cmp_gt_u32_e64 s[30:31], s98, v85
	v_cndmask_b32_e64 v41, 0, v41, s[36:37]
	v_add_u32_e32 v86, 100, v84
	v_cmp_gt_u32_e64 s[36:37], s98, v86
	v_cndmask_b32_e64 v42, 0, v42, s[78:79]
	v_add_u32_e32 v87, 104, v84
	v_cmp_gt_u32_e64 s[78:79], s98, v87
	v_cndmask_b32_e64 v43, 0, v43, s[50:51]
	v_add_u32_e32 v88, 108, v84
	v_cmp_gt_u32_e64 s[50:51], s98, v88
	v_nop
	v_cndmask_b32_e64 v44, 0, v44, s[30:31]
	v_cndmask_b32_e64 v45, 0, v45, s[36:37]
	v_cndmask_b32_e64 v46, 0, v46, s[78:79]
	v_cndmask_b32_e64 v47, 0, v47, s[50:51]
	v_cvt_pk_bf16_f32 v64, v32, v33
	v_cvt_pk_bf16_f32 v65, v34, v35
	v_cvt_pk_bf16_f32 v66, v36, v37
	v_cvt_pk_bf16_f32 v67, v38, v39
	v_cvt_pk_bf16_f32 v68, v40, v41
	v_cvt_pk_bf16_f32 v69, v42, v43
	v_cvt_pk_bf16_f32 v70, v44, v45
	v_cvt_pk_bf16_f32 v71, v46, v47
	v_pk_add_f32 v[232:233], v[232:233], v[32:33]
	v_pk_add_f32 v[232:233], v[232:233], v[34:35]
	v_pk_add_f32 v[232:233], v[232:233], v[36:37]
	v_pk_add_f32 v[232:233], v[232:233], v[38:39]
	v_pk_add_f32 v[232:233], v[232:233], v[40:41]
	v_pk_add_f32 v[232:233], v[232:233], v[42:43]
	v_pk_add_f32 v[232:233], v[232:233], v[44:45]
	v_pk_add_f32 v[232:233], v[232:233], v[46:47]
	v_mov_b32_e32 v115, v230
	ds_read2_b32 v[32:33], v115 offset0:0 offset1:1
	ds_read2_b32 v[34:35], v115 offset0:2 offset1:3
	ds_read2_b32 v[36:37], v115 offset0:8 offset1:9
	ds_read2_b32 v[38:39], v115 offset0:10 offset1:11
	ds_read2_b32 v[40:41], v115 offset0:16 offset1:17
	ds_read2_b32 v[42:43], v115 offset0:18 offset1:19
	ds_read2_b32 v[44:45], v115 offset0:24 offset1:25
	ds_read2_b32 v[46:47], v115 offset0:26 offset1:27
	s_add_i32 s90, s67, -512
	v_add_u32_e32 v80, s90, v243
	v_add_u32_e32 v83, s90, v244
	v_add_u32_e32 v99, s90, v245
	v_add_u32_e32 v253, s90, v246
	v_add_u32_e32 v254, s90, v148
	v_add_u32_e32 v255, s90, v151
	v_med3_i32 v80, v80, 0, s99
	v_med3_i32 v83, v83, 0, s99
	v_med3_i32 v99, v99, 0, s99
	v_med3_i32 v253, v253, 0, s99
	v_med3_i32 v254, v254, 0, s99
	v_med3_i32 v255, v255, 0, s99
	v_mad_u32_u24 v80, v80, s100, v252
	v_mad_u32_u24 v83, v83, s100, v252
	v_mad_u32_u24 v99, v99, s100, v252
	v_mad_u32_u24 v253, v253, s100, v252
	v_mad_u32_u24 v254, v254, s100, v153
	v_mad_u32_u24 v255, v255, s100, v153
	global_load_dwordx4 v[156:159], v80, s[82:83]
	global_load_dwordx4 v[160:163], v83, s[82:83]
	global_load_dwordx4 v[164:167], v99, s[82:83]
	global_load_dwordx4 v[168:171], v253, s[82:83]
	global_load_dwordx4 v[172:175], v254, s[82:83] offset:768
	global_load_dwordx4 v[176:179], v255, s[82:83] offset:768
	global_load_dwordx4 v[180:183], v254, s[82:83] offset:832
	global_load_dwordx4 v[184:187], v255, s[82:83] offset:832
	ds_read_b64_tr_b16 v[204:205], v231
	ds_read_b64_tr_b16 v[206:207], v231 offset:512
	ds_read_b64_tr_b16 v[208:209], v231 offset:2048
	ds_read_b64_tr_b16 v[210:211], v231 offset:2560
	ds_read_b64_tr_b16 v[212:213], v231 offset:1024
	ds_read_b64_tr_b16 v[214:215], v231 offset:1536
	ds_read_b64_tr_b16 v[216:217], v231 offset:3072
	ds_read_b64_tr_b16 v[218:219], v231 offset:3584
	v_exp_f32_e32 v188, v188
	v_exp_f32_e32 v189, v189
	v_exp_f32_e32 v190, v190
	v_exp_f32_e32 v191, v191
	s_waitcnt vmcnt(8)
	ds_write_b128 v247, v[116:119]
	ds_write_b128 v247, v[120:123] offset:1024
	ds_write_b128 v247, v[124:127] offset:2048
	ds_write_b128 v247, v[128:131] offset:3072
	ds_read_b128 v[116:119], v248
	ds_read_b128 v[120:123], v249
	ds_read_b128 v[124:127], v250
	ds_read_b128 v[128:131], v251
	ds_write_b128 v112, v[132:135]
	ds_write_b128 v112, v[136:139] offset:1024
	ds_write_b128 v112, v[140:143] offset:2048
	ds_write_b128 v112, v[144:147] offset:3072
	v_mfma_f32_32x32x16_bf16 v[0:15], v[64:67], v[72:75], v[0:15]
	v_mfma_f32_32x32x16_bf16 v[16:31], v[64:67], v[76:79], v[16:31]
	v_mfma_f32_32x32x16_bf16 v[0:15], v[68:71], v[220:223], v[0:15]
	v_mfma_f32_32x32x16_bf16 v[16:31], v[68:71], v[224:227], v[16:31]
	v_exp_f32_e32 v192, v192
	v_exp_f32_e32 v193, v193
	v_exp_f32_e32 v194, v194
	v_exp_f32_e32 v195, v195
	s_waitcnt lgkmcnt(4)
	v_mfma_f32_32x32x16_bf16 v[32:47], v[116:119], v[48:51], v[32:47]
	v_exp_f32_e32 v196, v196
	v_exp_f32_e32 v197, v197
	v_mfma_f32_32x32x16_bf16 v[32:47], v[120:123], v[52:55], v[32:47]
	v_exp_f32_e32 v198, v198
	v_exp_f32_e32 v199, v199
	v_mfma_f32_32x32x16_bf16 v[32:47], v[124:127], v[56:59], v[32:47]
	v_exp_f32_e32 v200, v200
	v_exp_f32_e32 v201, v201
	v_mfma_f32_32x32x16_bf16 v[32:47], v[128:131], v[60:63], v[32:47]
	v_exp_f32_e32 v202, v202
	v_exp_f32_e32 v203, v203
	s_add_i32 s90, s67, 640
	v_lshlrev_b32_e32 v84, 2, v107
	v_add_u32_e32 v84, s90, v84
	v_add_u32_e32 v85, 0, v84
	v_add_u32_e32 v86, 4, v84
	v_add_u32_e32 v87, 8, v84
	v_add_u32_e32 v88, 12, v84
	v_cmp_gt_u32_e64 s[30:31], s98, v85
	v_cmp_gt_u32_e64 s[36:37], s98, v86
	v_cmp_gt_u32_e64 s[78:79], s98, v87
	v_cmp_gt_u32_e64 s[50:51], s98, v88
	v_cndmask_b32_e64 v188, 0, v188, s[30:31]
	v_add_u32_e32 v85, 32, v84
	v_cmp_gt_u32_e64 s[30:31], s98, v85
	v_cndmask_b32_e64 v189, 0, v189, s[36:37]
	v_add_u32_e32 v86, 36, v84
	v_cmp_gt_u32_e64 s[36:37], s98, v86
	v_cndmask_b32_e64 v190, 0, v190, s[78:79]
	v_add_u32_e32 v87, 40, v84
	v_cmp_gt_u32_e64 s[78:79], s98, v87
	v_cndmask_b32_e64 v191, 0, v191, s[50:51]
	v_add_u32_e32 v88, 44, v84
	v_cmp_gt_u32_e64 s[50:51], s98, v88
	v_cndmask_b32_e64 v192, 0, v192, s[30:31]
	v_add_u32_e32 v85, 64, v84
	v_cmp_gt_u32_e64 s[30:31], s98, v85
	v_cndmask_b32_e64 v193, 0, v193, s[36:37]
	v_add_u32_e32 v86, 68, v84
	v_cmp_gt_u32_e64 s[36:37], s98, v86
	v_cndmask_b32_e64 v194, 0, v194, s[78:79]
	v_add_u32_e32 v87, 72, v84
	v_cmp_gt_u32_e64 s[78:79], s98, v87
	v_cndmask_b32_e64 v195, 0, v195, s[50:51]
	v_add_u32_e32 v88, 76, v84
	v_cmp_gt_u32_e64 s[50:51], s98, v88
	v_cndmask_b32_e64 v196, 0, v196, s[30:31]
	v_add_u32_e32 v85, 96, v84
	v_cmp_gt_u32_e64 s[30:31], s98, v85
	v_cndmask_b32_e64 v197, 0, v197, s[36:37]
	v_add_u32_e32 v86, 100, v84
	v_cmp_gt_u32_e64 s[36:37], s98, v86
	v_cndmask_b32_e64 v198, 0, v198, s[78:79]
	v_add_u32_e32 v87, 104, v84
	v_cmp_gt_u32_e64 s[78:79], s98, v87
	v_cndmask_b32_e64 v199, 0, v199, s[50:51]
	v_add_u32_e32 v88, 108, v84
	v_cmp_gt_u32_e64 s[50:51], s98, v88
	v_nop
	v_cndmask_b32_e64 v200, 0, v200, s[30:31]
	v_cndmask_b32_e64 v201, 0, v201, s[36:37]
	v_cndmask_b32_e64 v202, 0, v202, s[78:79]
	v_cndmask_b32_e64 v203, 0, v203, s[50:51]
	v_cvt_pk_bf16_f32 v64, v188, v189
	v_cvt_pk_bf16_f32 v65, v190, v191
	v_cvt_pk_bf16_f32 v66, v192, v193
	v_cvt_pk_bf16_f32 v67, v194, v195
	v_cvt_pk_bf16_f32 v68, v196, v197
	v_cvt_pk_bf16_f32 v69, v198, v199
	v_cvt_pk_bf16_f32 v70, v200, v201
	v_cvt_pk_bf16_f32 v71, v202, v203
	v_pk_add_f32 v[232:233], v[232:233], v[188:189]
	v_pk_add_f32 v[232:233], v[232:233], v[190:191]
	v_pk_add_f32 v[232:233], v[232:233], v[192:193]
	v_pk_add_f32 v[232:233], v[232:233], v[194:195]
	v_pk_add_f32 v[232:233], v[232:233], v[196:197]
	v_pk_add_f32 v[232:233], v[232:233], v[198:199]
	v_pk_add_f32 v[232:233], v[232:233], v[200:201]
	v_pk_add_f32 v[232:233], v[232:233], v[202:203]
	ds_read2_b32 v[188:189], v115 offset0:32 offset1:33
	ds_read2_b32 v[190:191], v115 offset0:34 offset1:35
	ds_read2_b32 v[192:193], v115 offset0:40 offset1:41
	ds_read2_b32 v[194:195], v115 offset0:42 offset1:43
	ds_read2_b32 v[196:197], v115 offset0:48 offset1:49
	ds_read2_b32 v[198:199], v115 offset0:50 offset1:51
	ds_read2_b32 v[200:201], v115 offset0:56 offset1:57
	ds_read2_b32 v[202:203], v115 offset0:58 offset1:59
	s_add_i32 s90, s67, 0
	v_add_u32_e32 v80, s90, v243
	v_add_u32_e32 v83, s90, v244
	v_add_u32_e32 v99, s90, v245
	v_add_u32_e32 v253, s90, v246
	v_add_u32_e32 v254, s90, v148
	v_add_u32_e32 v255, s90, v151
	v_med3_i32 v80, v80, 0, s99
	v_med3_i32 v83, v83, 0, s99
	v_med3_i32 v99, v99, 0, s99
	v_med3_i32 v253, v253, 0, s99
	v_med3_i32 v254, v254, 0, s99
	v_med3_i32 v255, v255, 0, s99
	v_mad_u32_u24 v80, v80, s100, v252
	v_mad_u32_u24 v83, v83, s100, v252
	v_mad_u32_u24 v99, v99, s100, v252
	v_mad_u32_u24 v253, v253, s100, v252
	v_mad_u32_u24 v254, v254, s100, v153
	v_mad_u32_u24 v255, v255, s100, v153
	global_load_dwordx4 v[116:119], v80, s[82:83]
	global_load_dwordx4 v[120:123], v83, s[82:83]
	global_load_dwordx4 v[124:127], v99, s[82:83]
	global_load_dwordx4 v[128:131], v253, s[82:83]
	global_load_dwordx4 v[132:135], v254, s[82:83] offset:768
	global_load_dwordx4 v[136:139], v255, s[82:83] offset:768
	global_load_dwordx4 v[140:143], v254, s[82:83] offset:832
	global_load_dwordx4 v[144:147], v255, s[82:83] offset:832
	ds_read_b64_tr_b16 v[72:73], v231
	ds_read_b64_tr_b16 v[74:75], v231 offset:512
	ds_read_b64_tr_b16 v[76:77], v231 offset:2048
	ds_read_b64_tr_b16 v[78:79], v231 offset:2560
	ds_read_b64_tr_b16 v[220:221], v231 offset:1024
	ds_read_b64_tr_b16 v[222:223], v231 offset:1536
	ds_read_b64_tr_b16 v[224:225], v231 offset:3072
	ds_read_b64_tr_b16 v[226:227], v231 offset:3584
	v_exp_f32_e32 v32, v32
	v_exp_f32_e32 v33, v33
	v_exp_f32_e32 v34, v34
	v_exp_f32_e32 v35, v35
	s_waitcnt vmcnt(8)
	ds_write_b128 v247, v[156:159]
	ds_write_b128 v247, v[160:163] offset:1024
	ds_write_b128 v247, v[164:167] offset:2048
	ds_write_b128 v247, v[168:171] offset:3072
	ds_read_b128 v[156:159], v248
	ds_read_b128 v[160:163], v249
	ds_read_b128 v[164:167], v250
	ds_read_b128 v[168:171], v251
	ds_write_b128 v112, v[172:175]
	ds_write_b128 v112, v[176:179] offset:1024
	ds_write_b128 v112, v[180:183] offset:2048
	ds_write_b128 v112, v[184:187] offset:3072
	v_mfma_f32_32x32x16_bf16 v[0:15], v[64:67], v[204:207], v[0:15]
	v_mfma_f32_32x32x16_bf16 v[16:31], v[64:67], v[208:211], v[16:31]
	v_mfma_f32_32x32x16_bf16 v[0:15], v[68:71], v[212:215], v[0:15]
	v_mfma_f32_32x32x16_bf16 v[16:31], v[68:71], v[216:219], v[16:31]
	v_exp_f32_e32 v36, v36
	v_exp_f32_e32 v37, v37
	v_exp_f32_e32 v38, v38
	v_exp_f32_e32 v39, v39
	s_waitcnt lgkmcnt(4)
	v_mfma_f32_32x32x16_bf16 v[188:203], v[156:159], v[48:51], v[188:203]
	v_exp_f32_e32 v40, v40
	v_exp_f32_e32 v41, v41
	v_mfma_f32_32x32x16_bf16 v[188:203], v[160:163], v[52:55], v[188:203]
	v_exp_f32_e32 v42, v42
	v_exp_f32_e32 v43, v43
	v_mfma_f32_32x32x16_bf16 v[188:203], v[164:167], v[56:59], v[188:203]
	v_exp_f32_e32 v44, v44
	v_exp_f32_e32 v45, v45
	v_mfma_f32_32x32x16_bf16 v[188:203], v[168:171], v[60:63], v[188:203]
	v_exp_f32_e32 v46, v46
	v_exp_f32_e32 v47, v47
	s_add_i32 s90, s67, -1024
	v_lshlrev_b32_e32 v84, 4, v107
	v_add_u32_e32 v84, s90, v84
	v_add_u32_e32 v85, 0, v84
	v_add_u32_e32 v86, 16, v84
	v_add_u32_e32 v87, 32, v84
	v_add_u32_e32 v88, 48, v84
	v_cmp_gt_u32_e64 s[30:31], s98, v85
	v_cmp_gt_u32_e64 s[36:37], s98, v86
	v_cmp_gt_u32_e64 s[78:79], s98, v87
	v_cmp_gt_u32_e64 s[50:51], s98, v88
	v_cndmask_b32_e64 v32, 0, v32, s[30:31]
	v_add_u32_e32 v85, 128, v84
	v_cmp_gt_u32_e64 s[30:31], s98, v85
	v_cndmask_b32_e64 v33, 0, v33, s[36:37]
	v_add_u32_e32 v86, 144, v84
	v_cmp_gt_u32_e64 s[36:37], s98, v86
	v_cndmask_b32_e64 v34, 0, v34, s[78:79]
	v_add_u32_e32 v87, 160, v84
	v_cmp_gt_u32_e64 s[78:79], s98, v87
	v_cndmask_b32_e64 v35, 0, v35, s[50:51]
	v_add_u32_e32 v88, 176, v84
	v_cmp_gt_u32_e64 s[50:51], s98, v88
	v_cndmask_b32_e64 v36, 0, v36, s[30:31]
	v_add_u32_e32 v85, 256, v84
	v_cmp_gt_u32_e64 s[30:31], s98, v85
	v_cndmask_b32_e64 v37, 0, v37, s[36:37]
	v_add_u32_e32 v86, 272, v84
	v_cmp_gt_u32_e64 s[36:37], s98, v86
	v_cndmask_b32_e64 v38, 0, v38, s[78:79]
	v_add_u32_e32 v87, 288, v84
	v_cmp_gt_u32_e64 s[78:79], s98, v87
	v_cndmask_b32_e64 v39, 0, v39, s[50:51]
	v_add_u32_e32 v88, 304, v84
	v_cmp_gt_u32_e64 s[50:51], s98, v88
	v_cndmask_b32_e64 v40, 0, v40, s[30:31]
	v_add_u32_e32 v85, 384, v84
	v_cmp_gt_u32_e64 s[30:31], s98, v85
	v_cndmask_b32_e64 v41, 0, v41, s[36:37]
	v_add_u32_e32 v86, 400, v84
	v_cmp_gt_u32_e64 s[36:37], s98, v86
	v_cndmask_b32_e64 v42, 0, v42, s[78:79]
	v_add_u32_e32 v87, 416, v84
	v_cmp_gt_u32_e64 s[78:79], s98, v87
	v_cndmask_b32_e64 v43, 0, v43, s[50:51]
	v_add_u32_e32 v88, 432, v84
	v_cmp_gt_u32_e64 s[50:51], s98, v88
	v_nop
	v_cndmask_b32_e64 v44, 0, v44, s[30:31]
	v_cndmask_b32_e64 v45, 0, v45, s[36:37]
	v_cndmask_b32_e64 v46, 0, v46, s[78:79]
	v_cndmask_b32_e64 v47, 0, v47, s[50:51]
	v_cvt_pk_bf16_f32 v64, v32, v33
	v_cvt_pk_bf16_f32 v65, v34, v35
	v_cvt_pk_bf16_f32 v66, v36, v37
	v_cvt_pk_bf16_f32 v67, v38, v39
	v_cvt_pk_bf16_f32 v68, v40, v41
	v_cvt_pk_bf16_f32 v69, v42, v43
	v_cvt_pk_bf16_f32 v70, v44, v45
	v_cvt_pk_bf16_f32 v71, v46, v47
	v_pk_add_f32 v[232:233], v[232:233], v[32:33]
	v_pk_add_f32 v[232:233], v[232:233], v[34:35]
	v_pk_add_f32 v[232:233], v[232:233], v[36:37]
	v_pk_add_f32 v[232:233], v[232:233], v[38:39]
	v_pk_add_f32 v[232:233], v[232:233], v[40:41]
	v_pk_add_f32 v[232:233], v[232:233], v[42:43]
	v_pk_add_f32 v[232:233], v[232:233], v[44:45]
	v_pk_add_f32 v[232:233], v[232:233], v[46:47]
	ds_read2_b32 v[32:33], v115 offset0:64 offset1:65
	ds_read2_b32 v[34:35], v115 offset0:66 offset1:67
	ds_read2_b32 v[36:37], v115 offset0:72 offset1:73
	ds_read2_b32 v[38:39], v115 offset0:74 offset1:75
	ds_read2_b32 v[40:41], v115 offset0:80 offset1:81
	ds_read2_b32 v[42:43], v115 offset0:82 offset1:83
	ds_read2_b32 v[44:45], v115 offset0:88 offset1:89
	ds_read2_b32 v[46:47], v115 offset0:90 offset1:91
	s_add_i32 s90, s67, 512
	v_add_u32_e32 v80, s90, v243
	v_add_u32_e32 v83, s90, v244
	v_add_u32_e32 v99, s90, v245
	v_add_u32_e32 v253, s90, v246
	v_add_u32_e32 v254, s90, v148
	v_add_u32_e32 v255, s90, v151
	v_med3_i32 v80, v80, 0, s99
	v_med3_i32 v83, v83, 0, s99
	v_med3_i32 v99, v99, 0, s99
	v_med3_i32 v253, v253, 0, s99
	v_med3_i32 v254, v254, 0, s99
	v_med3_i32 v255, v255, 0, s99
	v_mad_u32_u24 v80, v80, s100, v252
	v_mad_u32_u24 v83, v83, s100, v252
	v_mad_u32_u24 v99, v99, s100, v252
	v_mad_u32_u24 v253, v253, s100, v252
	v_mad_u32_u24 v254, v254, s100, v153
	v_mad_u32_u24 v255, v255, s100, v153
	global_load_dwordx4 v[156:159], v80, s[82:83]
	global_load_dwordx4 v[160:163], v83, s[82:83]
	global_load_dwordx4 v[164:167], v99, s[82:83]
	global_load_dwordx4 v[168:171], v253, s[82:83]
	global_load_dwordx4 v[172:175], v254, s[82:83] offset:768
	global_load_dwordx4 v[176:179], v255, s[82:83] offset:768
	global_load_dwordx4 v[180:183], v254, s[82:83] offset:832
	global_load_dwordx4 v[184:187], v255, s[82:83] offset:832
	ds_read_b64_tr_b16 v[204:205], v231
	ds_read_b64_tr_b16 v[206:207], v231 offset:512
	ds_read_b64_tr_b16 v[208:209], v231 offset:2048
	ds_read_b64_tr_b16 v[210:211], v231 offset:2560
	ds_read_b64_tr_b16 v[212:213], v231 offset:1024
	ds_read_b64_tr_b16 v[214:215], v231 offset:1536
	ds_read_b64_tr_b16 v[216:217], v231 offset:3072
	ds_read_b64_tr_b16 v[218:219], v231 offset:3584
	v_exp_f32_e32 v188, v188
	v_exp_f32_e32 v189, v189
	v_exp_f32_e32 v190, v190
	v_exp_f32_e32 v191, v191
	s_waitcnt vmcnt(8)
	ds_write_b128 v247, v[116:119]
	ds_write_b128 v247, v[120:123] offset:1024
	ds_write_b128 v247, v[124:127] offset:2048
	ds_write_b128 v247, v[128:131] offset:3072
	ds_read_b128 v[116:119], v248
	ds_read_b128 v[120:123], v249
	ds_read_b128 v[124:127], v250
	ds_read_b128 v[128:131], v251
	ds_write_b128 v112, v[132:135]
	ds_write_b128 v112, v[136:139] offset:1024
	ds_write_b128 v112, v[140:143] offset:2048
	ds_write_b128 v112, v[144:147] offset:3072
	v_mfma_f32_32x32x16_bf16 v[0:15], v[64:67], v[72:75], v[0:15]
	v_mfma_f32_32x32x16_bf16 v[16:31], v[64:67], v[76:79], v[16:31]
	v_mfma_f32_32x32x16_bf16 v[0:15], v[68:71], v[220:223], v[0:15]
	v_mfma_f32_32x32x16_bf16 v[16:31], v[68:71], v[224:227], v[16:31]
	v_exp_f32_e32 v192, v192
	v_exp_f32_e32 v193, v193
	v_exp_f32_e32 v194, v194
	v_exp_f32_e32 v195, v195
	s_waitcnt lgkmcnt(4)
	v_mfma_f32_32x32x16_bf16 v[32:47], v[116:119], v[48:51], v[32:47]
	v_exp_f32_e32 v196, v196
	v_exp_f32_e32 v197, v197
	v_mfma_f32_32x32x16_bf16 v[32:47], v[120:123], v[52:55], v[32:47]
	v_exp_f32_e32 v198, v198
	v_exp_f32_e32 v199, v199
	v_mfma_f32_32x32x16_bf16 v[32:47], v[124:127], v[56:59], v[32:47]
	v_exp_f32_e32 v200, v200
	v_exp_f32_e32 v201, v201
	v_mfma_f32_32x32x16_bf16 v[32:47], v[128:131], v[60:63], v[32:47]
	v_exp_f32_e32 v202, v202
	v_exp_f32_e32 v203, v203
	s_add_i32 s90, s67, -512
	v_lshlrev_b32_e32 v84, 4, v107
	v_add_u32_e32 v84, s90, v84
	v_add_u32_e32 v85, 0, v84
	v_add_u32_e32 v86, 16, v84
	v_add_u32_e32 v87, 32, v84
	v_add_u32_e32 v88, 48, v84
	v_cmp_gt_u32_e64 s[30:31], s98, v85
	v_cmp_gt_u32_e64 s[36:37], s98, v86
	v_cmp_gt_u32_e64 s[78:79], s98, v87
	v_cmp_gt_u32_e64 s[50:51], s98, v88
	v_cndmask_b32_e64 v188, 0, v188, s[30:31]
	v_add_u32_e32 v85, 128, v84
	v_cmp_gt_u32_e64 s[30:31], s98, v85
	v_cndmask_b32_e64 v189, 0, v189, s[36:37]
	v_add_u32_e32 v86, 144, v84
	v_cmp_gt_u32_e64 s[36:37], s98, v86
	v_cndmask_b32_e64 v190, 0, v190, s[78:79]
	v_add_u32_e32 v87, 160, v84
	v_cmp_gt_u32_e64 s[78:79], s98, v87
	v_cndmask_b32_e64 v191, 0, v191, s[50:51]
	v_add_u32_e32 v88, 176, v84
	v_cmp_gt_u32_e64 s[50:51], s98, v88
	v_cndmask_b32_e64 v192, 0, v192, s[30:31]
	v_add_u32_e32 v85, 256, v84
	v_cmp_gt_u32_e64 s[30:31], s98, v85
	v_cndmask_b32_e64 v193, 0, v193, s[36:37]
	v_add_u32_e32 v86, 272, v84
	v_cmp_gt_u32_e64 s[36:37], s98, v86
	v_cndmask_b32_e64 v194, 0, v194, s[78:79]
	v_add_u32_e32 v87, 288, v84
	v_cmp_gt_u32_e64 s[78:79], s98, v87
	v_cndmask_b32_e64 v195, 0, v195, s[50:51]
	v_add_u32_e32 v88, 304, v84
	v_cmp_gt_u32_e64 s[50:51], s98, v88
	v_cndmask_b32_e64 v196, 0, v196, s[30:31]
	v_add_u32_e32 v85, 384, v84
	v_cmp_gt_u32_e64 s[30:31], s98, v85
	v_cndmask_b32_e64 v197, 0, v197, s[36:37]
	v_add_u32_e32 v86, 400, v84
	v_cmp_gt_u32_e64 s[36:37], s98, v86
	v_cndmask_b32_e64 v198, 0, v198, s[78:79]
	v_add_u32_e32 v87, 416, v84
	v_cmp_gt_u32_e64 s[78:79], s98, v87
	v_cndmask_b32_e64 v199, 0, v199, s[50:51]
	v_add_u32_e32 v88, 432, v84
	v_cmp_gt_u32_e64 s[50:51], s98, v88
	v_nop
	v_cndmask_b32_e64 v200, 0, v200, s[30:31]
	v_cndmask_b32_e64 v201, 0, v201, s[36:37]
	v_cndmask_b32_e64 v202, 0, v202, s[78:79]
	v_cndmask_b32_e64 v203, 0, v203, s[50:51]
	v_cvt_pk_bf16_f32 v64, v188, v189
	v_cvt_pk_bf16_f32 v65, v190, v191
	v_cvt_pk_bf16_f32 v66, v192, v193
	v_cvt_pk_bf16_f32 v67, v194, v195
	v_cvt_pk_bf16_f32 v68, v196, v197
	v_cvt_pk_bf16_f32 v69, v198, v199
	v_cvt_pk_bf16_f32 v70, v200, v201
	v_cvt_pk_bf16_f32 v71, v202, v203
	v_pk_add_f32 v[232:233], v[232:233], v[188:189]
	v_pk_add_f32 v[232:233], v[232:233], v[190:191]
	v_pk_add_f32 v[232:233], v[232:233], v[192:193]
	v_pk_add_f32 v[232:233], v[232:233], v[194:195]
	v_pk_add_f32 v[232:233], v[232:233], v[196:197]
	v_pk_add_f32 v[232:233], v[232:233], v[198:199]
	v_pk_add_f32 v[232:233], v[232:233], v[200:201]
	v_pk_add_f32 v[232:233], v[232:233], v[202:203]
	ds_read2_b32 v[188:189], v115 offset0:96 offset1:97
	ds_read2_b32 v[190:191], v115 offset0:98 offset1:99
	ds_read2_b32 v[192:193], v115 offset0:104 offset1:105
	ds_read2_b32 v[194:195], v115 offset0:106 offset1:107
	ds_read2_b32 v[196:197], v115 offset0:112 offset1:113
	ds_read2_b32 v[198:199], v115 offset0:114 offset1:115
	ds_read2_b32 v[200:201], v115 offset0:120 offset1:121
	ds_read2_b32 v[202:203], v115 offset0:122 offset1:123
	s_add_i32 s90, s67, 1024
	v_add_u32_e32 v80, s90, v243
	v_add_u32_e32 v83, s90, v244
	v_add_u32_e32 v99, s90, v245
	v_add_u32_e32 v253, s90, v246
	v_add_u32_e32 v254, s90, v148
	v_add_u32_e32 v255, s90, v151
	v_med3_i32 v80, v80, 0, s99
	v_med3_i32 v83, v83, 0, s99
	v_med3_i32 v99, v99, 0, s99
	v_med3_i32 v253, v253, 0, s99
	v_med3_i32 v254, v254, 0, s99
	v_med3_i32 v255, v255, 0, s99
	v_mad_u32_u24 v80, v80, s100, v252
	v_mad_u32_u24 v83, v83, s100, v252
	v_mad_u32_u24 v99, v99, s100, v252
	v_mad_u32_u24 v253, v253, s100, v252
	v_mad_u32_u24 v254, v254, s100, v153
	v_mad_u32_u24 v255, v255, s100, v153
	global_load_dwordx4 v[116:119], v80, s[82:83]
	global_load_dwordx4 v[120:123], v83, s[82:83]
	global_load_dwordx4 v[124:127], v99, s[82:83]
	global_load_dwordx4 v[128:131], v253, s[82:83]
	global_load_dwordx4 v[132:135], v254, s[82:83] offset:768
	global_load_dwordx4 v[136:139], v255, s[82:83] offset:768
	global_load_dwordx4 v[140:143], v254, s[82:83] offset:832
	global_load_dwordx4 v[144:147], v255, s[82:83] offset:832
	ds_read_b64_tr_b16 v[72:73], v231
	ds_read_b64_tr_b16 v[74:75], v231 offset:512
	ds_read_b64_tr_b16 v[76:77], v231 offset:2048
	ds_read_b64_tr_b16 v[78:79], v231 offset:2560
	ds_read_b64_tr_b16 v[220:221], v231 offset:1024
	ds_read_b64_tr_b16 v[222:223], v231 offset:1536
	ds_read_b64_tr_b16 v[224:225], v231 offset:3072
	ds_read_b64_tr_b16 v[226:227], v231 offset:3584
	v_exp_f32_e32 v32, v32
	v_exp_f32_e32 v33, v33
	v_exp_f32_e32 v34, v34
	v_exp_f32_e32 v35, v35
	s_waitcnt vmcnt(8)
	ds_write_b128 v247, v[156:159]
	ds_write_b128 v247, v[160:163] offset:1024
	ds_write_b128 v247, v[164:167] offset:2048
	ds_write_b128 v247, v[168:171] offset:3072
	ds_read_b128 v[156:159], v248
	ds_read_b128 v[160:163], v249
	ds_read_b128 v[164:167], v250
	ds_read_b128 v[168:171], v251
	ds_write_b128 v112, v[172:175]
	ds_write_b128 v112, v[176:179] offset:1024
	ds_write_b128 v112, v[180:183] offset:2048
	ds_write_b128 v112, v[184:187] offset:3072
	v_mfma_f32_32x32x16_bf16 v[0:15], v[64:67], v[204:207], v[0:15]
	v_mfma_f32_32x32x16_bf16 v[16:31], v[64:67], v[208:211], v[16:31]
	v_mfma_f32_32x32x16_bf16 v[0:15], v[68:71], v[212:215], v[0:15]
	v_mfma_f32_32x32x16_bf16 v[16:31], v[68:71], v[216:219], v[16:31]
	v_exp_f32_e32 v36, v36
	v_exp_f32_e32 v37, v37
	v_exp_f32_e32 v38, v38
	v_exp_f32_e32 v39, v39
	s_waitcnt lgkmcnt(4)
	v_mfma_f32_32x32x16_bf16 v[188:203], v[156:159], v[48:51], v[188:203]
	v_exp_f32_e32 v40, v40
	v_exp_f32_e32 v41, v41
	v_mfma_f32_32x32x16_bf16 v[188:203], v[160:163], v[52:55], v[188:203]
	v_exp_f32_e32 v42, v42
	v_exp_f32_e32 v43, v43
	v_mfma_f32_32x32x16_bf16 v[188:203], v[164:167], v[56:59], v[188:203]
	v_exp_f32_e32 v44, v44
	v_exp_f32_e32 v45, v45
	v_mfma_f32_32x32x16_bf16 v[188:203], v[168:171], v[60:63], v[188:203]
	v_exp_f32_e32 v46, v46
	v_exp_f32_e32 v47, v47
	s_add_i32 s90, s67, 0
	v_lshlrev_b32_e32 v84, 4, v107
	v_add_u32_e32 v84, s90, v84
	v_add_u32_e32 v85, 0, v84
	v_add_u32_e32 v86, 16, v84
	v_add_u32_e32 v87, 32, v84
	v_add_u32_e32 v88, 48, v84
	v_cmp_gt_u32_e64 s[30:31], s98, v85
	v_cmp_gt_u32_e64 s[36:37], s98, v86
	v_cmp_gt_u32_e64 s[78:79], s98, v87
	v_cmp_gt_u32_e64 s[50:51], s98, v88
	v_cndmask_b32_e64 v32, 0, v32, s[30:31]
	v_add_u32_e32 v85, 128, v84
	v_cmp_gt_u32_e64 s[30:31], s98, v85
	v_cndmask_b32_e64 v33, 0, v33, s[36:37]
	v_add_u32_e32 v86, 144, v84
	v_cmp_gt_u32_e64 s[36:37], s98, v86
	v_cndmask_b32_e64 v34, 0, v34, s[78:79]
	v_add_u32_e32 v87, 160, v84
	v_cmp_gt_u32_e64 s[78:79], s98, v87
	v_cndmask_b32_e64 v35, 0, v35, s[50:51]
	v_add_u32_e32 v88, 176, v84
	v_cmp_gt_u32_e64 s[50:51], s98, v88
	v_cndmask_b32_e64 v36, 0, v36, s[30:31]
	v_add_u32_e32 v85, 256, v84
	v_cmp_gt_u32_e64 s[30:31], s98, v85
	v_cndmask_b32_e64 v37, 0, v37, s[36:37]
	v_add_u32_e32 v86, 272, v84
	v_cmp_gt_u32_e64 s[36:37], s98, v86
	v_cndmask_b32_e64 v38, 0, v38, s[78:79]
	v_add_u32_e32 v87, 288, v84
	v_cmp_gt_u32_e64 s[78:79], s98, v87
	v_cndmask_b32_e64 v39, 0, v39, s[50:51]
	v_add_u32_e32 v88, 304, v84
	v_cmp_gt_u32_e64 s[50:51], s98, v88
	v_cndmask_b32_e64 v40, 0, v40, s[30:31]
	v_add_u32_e32 v85, 384, v84
	v_cmp_gt_u32_e64 s[30:31], s98, v85
	v_cndmask_b32_e64 v41, 0, v41, s[36:37]
	v_add_u32_e32 v86, 400, v84
	v_cmp_gt_u32_e64 s[36:37], s98, v86
	v_cndmask_b32_e64 v42, 0, v42, s[78:79]
	v_add_u32_e32 v87, 416, v84
	v_cmp_gt_u32_e64 s[78:79], s98, v87
	v_cndmask_b32_e64 v43, 0, v43, s[50:51]
	v_add_u32_e32 v88, 432, v84
	v_cmp_gt_u32_e64 s[50:51], s98, v88
	v_nop
	v_cndmask_b32_e64 v44, 0, v44, s[30:31]
	v_cndmask_b32_e64 v45, 0, v45, s[36:37]
	v_cndmask_b32_e64 v46, 0, v46, s[78:79]
	v_cndmask_b32_e64 v47, 0, v47, s[50:51]
	v_cvt_pk_bf16_f32 v64, v32, v33
	v_cvt_pk_bf16_f32 v65, v34, v35
	v_cvt_pk_bf16_f32 v66, v36, v37
	v_cvt_pk_bf16_f32 v67, v38, v39
	v_cvt_pk_bf16_f32 v68, v40, v41
	v_cvt_pk_bf16_f32 v69, v42, v43
	v_cvt_pk_bf16_f32 v70, v44, v45
	v_cvt_pk_bf16_f32 v71, v46, v47
	v_pk_add_f32 v[232:233], v[232:233], v[32:33]
	v_pk_add_f32 v[232:233], v[232:233], v[34:35]
	v_pk_add_f32 v[232:233], v[232:233], v[36:37]
	v_pk_add_f32 v[232:233], v[232:233], v[38:39]
	v_pk_add_f32 v[232:233], v[232:233], v[40:41]
	v_pk_add_f32 v[232:233], v[232:233], v[42:43]
	v_pk_add_f32 v[232:233], v[232:233], v[44:45]
	v_pk_add_f32 v[232:233], v[232:233], v[46:47]
	ds_read2_b32 v[32:33], v115 offset0:128 offset1:129
	ds_read2_b32 v[34:35], v115 offset0:130 offset1:131
	ds_read2_b32 v[36:37], v115 offset0:136 offset1:137
	ds_read2_b32 v[38:39], v115 offset0:138 offset1:139
	ds_read2_b32 v[40:41], v115 offset0:144 offset1:145
	ds_read2_b32 v[42:43], v115 offset0:146 offset1:147
	ds_read2_b32 v[44:45], v115 offset0:152 offset1:153
	ds_read2_b32 v[46:47], v115 offset0:154 offset1:155
	ds_read_b64_tr_b16 v[204:205], v231
	ds_read_b64_tr_b16 v[206:207], v231 offset:512
	ds_read_b64_tr_b16 v[208:209], v231 offset:2048
	ds_read_b64_tr_b16 v[210:211], v231 offset:2560
	ds_read_b64_tr_b16 v[212:213], v231 offset:1024
	ds_read_b64_tr_b16 v[214:215], v231 offset:1536
	ds_read_b64_tr_b16 v[216:217], v231 offset:3072
	ds_read_b64_tr_b16 v[218:219], v231 offset:3584
	v_exp_f32_e32 v188, v188
	v_exp_f32_e32 v189, v189
	v_exp_f32_e32 v190, v190
	v_exp_f32_e32 v191, v191
	s_waitcnt vmcnt(0)
	ds_write_b128 v247, v[116:119]
	ds_write_b128 v247, v[120:123] offset:1024
	ds_write_b128 v247, v[124:127] offset:2048
	ds_write_b128 v247, v[128:131] offset:3072
	ds_read_b128 v[116:119], v248
	ds_read_b128 v[120:123], v249
	ds_read_b128 v[124:127], v250
	ds_read_b128 v[128:131], v251
	ds_write_b128 v112, v[132:135]
	ds_write_b128 v112, v[136:139] offset:1024
	ds_write_b128 v112, v[140:143] offset:2048
	ds_write_b128 v112, v[144:147] offset:3072
	v_mfma_f32_32x32x16_bf16 v[0:15], v[64:67], v[72:75], v[0:15]
	v_mfma_f32_32x32x16_bf16 v[16:31], v[64:67], v[76:79], v[16:31]
	v_mfma_f32_32x32x16_bf16 v[0:15], v[68:71], v[220:223], v[0:15]
	v_mfma_f32_32x32x16_bf16 v[16:31], v[68:71], v[224:227], v[16:31]
	v_exp_f32_e32 v192, v192
	v_exp_f32_e32 v193, v193
	v_exp_f32_e32 v194, v194
	v_exp_f32_e32 v195, v195
	s_waitcnt lgkmcnt(4)
	v_mfma_f32_32x32x16_bf16 v[32:47], v[116:119], v[48:51], v[32:47]
	v_exp_f32_e32 v196, v196
	v_exp_f32_e32 v197, v197
	v_mfma_f32_32x32x16_bf16 v[32:47], v[120:123], v[52:55], v[32:47]
	v_exp_f32_e32 v198, v198
	v_exp_f32_e32 v199, v199
	v_mfma_f32_32x32x16_bf16 v[32:47], v[124:127], v[56:59], v[32:47]
	v_exp_f32_e32 v200, v200
	v_exp_f32_e32 v201, v201
	v_mfma_f32_32x32x16_bf16 v[32:47], v[128:131], v[60:63], v[32:47]
	v_exp_f32_e32 v202, v202
	v_exp_f32_e32 v203, v203
	s_add_i32 s90, s67, 512
	v_lshlrev_b32_e32 v84, 4, v107
	v_add_u32_e32 v84, s90, v84
	v_add_u32_e32 v85, 0, v84
	v_add_u32_e32 v86, 16, v84
	v_add_u32_e32 v87, 32, v84
	v_add_u32_e32 v88, 48, v84
	v_cmp_gt_u32_e64 s[30:31], s98, v85
	v_cmp_gt_u32_e64 s[36:37], s98, v86
	v_cmp_gt_u32_e64 s[78:79], s98, v87
	v_cmp_gt_u32_e64 s[50:51], s98, v88
	v_cndmask_b32_e64 v188, 0, v188, s[30:31]
	v_add_u32_e32 v85, 128, v84
	v_cmp_gt_u32_e64 s[30:31], s98, v85
	v_cndmask_b32_e64 v189, 0, v189, s[36:37]
	v_add_u32_e32 v86, 144, v84
	v_cmp_gt_u32_e64 s[36:37], s98, v86
	v_cndmask_b32_e64 v190, 0, v190, s[78:79]
	v_add_u32_e32 v87, 160, v84
	v_cmp_gt_u32_e64 s[78:79], s98, v87
	v_cndmask_b32_e64 v191, 0, v191, s[50:51]
	v_add_u32_e32 v88, 176, v84
	v_cmp_gt_u32_e64 s[50:51], s98, v88
	v_cndmask_b32_e64 v192, 0, v192, s[30:31]
	v_add_u32_e32 v85, 256, v84
	v_cmp_gt_u32_e64 s[30:31], s98, v85
	v_cndmask_b32_e64 v193, 0, v193, s[36:37]
	v_add_u32_e32 v86, 272, v84
	v_cmp_gt_u32_e64 s[36:37], s98, v86
	v_cndmask_b32_e64 v194, 0, v194, s[78:79]
	v_add_u32_e32 v87, 288, v84
	v_cmp_gt_u32_e64 s[78:79], s98, v87
	v_cndmask_b32_e64 v195, 0, v195, s[50:51]
	v_add_u32_e32 v88, 304, v84
	v_cmp_gt_u32_e64 s[50:51], s98, v88
	v_cndmask_b32_e64 v196, 0, v196, s[30:31]
	v_add_u32_e32 v85, 384, v84
	v_cmp_gt_u32_e64 s[30:31], s98, v85
	v_cndmask_b32_e64 v197, 0, v197, s[36:37]
	v_add_u32_e32 v86, 400, v84
	v_cmp_gt_u32_e64 s[36:37], s98, v86
	v_cndmask_b32_e64 v198, 0, v198, s[78:79]
	v_add_u32_e32 v87, 416, v84
	v_cmp_gt_u32_e64 s[78:79], s98, v87
	v_cndmask_b32_e64 v199, 0, v199, s[50:51]
	v_add_u32_e32 v88, 432, v84
	v_cmp_gt_u32_e64 s[50:51], s98, v88
	v_nop
	v_cndmask_b32_e64 v200, 0, v200, s[30:31]
	v_cndmask_b32_e64 v201, 0, v201, s[36:37]
	v_cndmask_b32_e64 v202, 0, v202, s[78:79]
	v_cndmask_b32_e64 v203, 0, v203, s[50:51]
	v_cvt_pk_bf16_f32 v64, v188, v189
	v_cvt_pk_bf16_f32 v65, v190, v191
	v_cvt_pk_bf16_f32 v66, v192, v193
	v_cvt_pk_bf16_f32 v67, v194, v195
	v_cvt_pk_bf16_f32 v68, v196, v197
	v_cvt_pk_bf16_f32 v69, v198, v199
	v_cvt_pk_bf16_f32 v70, v200, v201
	v_cvt_pk_bf16_f32 v71, v202, v203
	v_pk_add_f32 v[232:233], v[232:233], v[188:189]
	v_pk_add_f32 v[232:233], v[232:233], v[190:191]
	v_pk_add_f32 v[232:233], v[232:233], v[192:193]
	v_pk_add_f32 v[232:233], v[232:233], v[194:195]
	v_pk_add_f32 v[232:233], v[232:233], v[196:197]
	v_pk_add_f32 v[232:233], v[232:233], v[198:199]
	v_pk_add_f32 v[232:233], v[232:233], v[200:201]
	v_pk_add_f32 v[232:233], v[232:233], v[202:203]
	ds_read_b64_tr_b16 v[72:73], v231
	ds_read_b64_tr_b16 v[74:75], v231 offset:512
	ds_read_b64_tr_b16 v[76:77], v231 offset:2048
	ds_read_b64_tr_b16 v[78:79], v231 offset:2560
	ds_read_b64_tr_b16 v[220:221], v231 offset:1024
	ds_read_b64_tr_b16 v[222:223], v231 offset:1536
	ds_read_b64_tr_b16 v[224:225], v231 offset:3072
	ds_read_b64_tr_b16 v[226:227], v231 offset:3584
	s_waitcnt lgkmcnt(0)
; __device__ __forceinline__ int crow(int r, int hi) { return (r & 3) + 8 * (r >> 2) + 4 * hi; }
; __device__ __forceinline__ void dil_unit(LAS unsigned char* lds, bf16_t* proj, int seq, int hd, int T0, int rho) {
;     ...
;     l += __shfl_xor(l, 32);
; #pragma unroll
;     for (int rr = 0; rr < 16; ++rr) {
;         const int j = crow(rr, hi);
	v_mfma_f32_32x32x16_bf16 v[0:15], v[64:67], v[204:207], v[0:15]
	v_mfma_f32_32x32x16_bf16 v[16:31], v[64:67], v[208:211], v[16:31]
	v_mfma_f32_32x32x16_bf16 v[0:15], v[68:71], v[212:215], v[0:15]
	v_mfma_f32_32x32x16_bf16 v[16:31], v[68:71], v[216:219], v[16:31]
	v_exp_f32_e32 v32, v32
	v_exp_f32_e32 v33, v33
	v_exp_f32_e32 v34, v34
	v_exp_f32_e32 v35, v35
	v_exp_f32_e32 v36, v36
	v_exp_f32_e32 v37, v37
	v_exp_f32_e32 v38, v38
	v_exp_f32_e32 v39, v39
	v_exp_f32_e32 v40, v40
	v_exp_f32_e32 v41, v41
	v_exp_f32_e32 v42, v42
	v_exp_f32_e32 v43, v43
	v_exp_f32_e32 v44, v44
	v_exp_f32_e32 v45, v45
	v_exp_f32_e32 v46, v46
	v_exp_f32_e32 v47, v47
	s_add_i32 s90, s67, 1024
	v_lshlrev_b32_e32 v84, 4, v107
	v_add_u32_e32 v84, s90, v84
	v_add_u32_e32 v85, 0, v84
	v_add_u32_e32 v86, 16, v84
	v_add_u32_e32 v87, 32, v84
	v_add_u32_e32 v88, 48, v84
	v_cmp_gt_u32_e64 s[30:31], s98, v85
	v_cmp_gt_u32_e64 s[36:37], s98, v86
	v_cmp_gt_u32_e64 s[78:79], s98, v87
	v_cmp_gt_u32_e64 s[50:51], s98, v88
	v_cndmask_b32_e64 v32, 0, v32, s[30:31]
	v_add_u32_e32 v85, 128, v84
	v_cmp_gt_u32_e64 s[30:31], s98, v85
	v_cndmask_b32_e64 v33, 0, v33, s[36:37]
	v_add_u32_e32 v86, 144, v84
	v_cmp_gt_u32_e64 s[36:37], s98, v86
	v_cndmask_b32_e64 v34, 0, v34, s[78:79]
	v_add_u32_e32 v87, 160, v84
	v_cmp_gt_u32_e64 s[78:79], s98, v87
	v_cndmask_b32_e64 v35, 0, v35, s[50:51]
	v_add_u32_e32 v88, 176, v84
	v_cmp_gt_u32_e64 s[50:51], s98, v88
	v_cndmask_b32_e64 v36, 0, v36, s[30:31]
	v_add_u32_e32 v85, 256, v84
	v_cmp_gt_u32_e64 s[30:31], s98, v85
	v_cndmask_b32_e64 v37, 0, v37, s[36:37]
	v_add_u32_e32 v86, 272, v84
	v_cmp_gt_u32_e64 s[36:37], s98, v86
	v_cndmask_b32_e64 v38, 0, v38, s[78:79]
	v_add_u32_e32 v87, 288, v84
	v_cmp_gt_u32_e64 s[78:79], s98, v87
	v_cndmask_b32_e64 v39, 0, v39, s[50:51]
	v_add_u32_e32 v88, 304, v84
	v_cmp_gt_u32_e64 s[50:51], s98, v88
	v_cndmask_b32_e64 v40, 0, v40, s[30:31]
	v_add_u32_e32 v85, 384, v84
	v_cmp_gt_u32_e64 s[30:31], s98, v85
	v_cndmask_b32_e64 v41, 0, v41, s[36:37]
	v_add_u32_e32 v86, 400, v84
	v_cmp_gt_u32_e64 s[36:37], s98, v86
	v_cndmask_b32_e64 v42, 0, v42, s[78:79]
	v_add_u32_e32 v87, 416, v84
	v_cmp_gt_u32_e64 s[78:79], s98, v87
	v_cndmask_b32_e64 v43, 0, v43, s[50:51]
	v_add_u32_e32 v88, 432, v84
	v_cmp_gt_u32_e64 s[50:51], s98, v88
	v_nop
	v_cndmask_b32_e64 v44, 0, v44, s[30:31]
	v_cndmask_b32_e64 v45, 0, v45, s[36:37]
	v_cndmask_b32_e64 v46, 0, v46, s[78:79]
	v_cndmask_b32_e64 v47, 0, v47, s[50:51]
	v_cvt_pk_bf16_f32 v64, v32, v33
	v_cvt_pk_bf16_f32 v65, v34, v35
	v_cvt_pk_bf16_f32 v66, v36, v37
	v_cvt_pk_bf16_f32 v67, v38, v39
	v_cvt_pk_bf16_f32 v68, v40, v41
	v_cvt_pk_bf16_f32 v69, v42, v43
	v_cvt_pk_bf16_f32 v70, v44, v45
	v_cvt_pk_bf16_f32 v71, v46, v47
	v_pk_add_f32 v[232:233], v[232:233], v[32:33]
	v_pk_add_f32 v[232:233], v[232:233], v[34:35]
	v_pk_add_f32 v[232:233], v[232:233], v[36:37]
	v_pk_add_f32 v[232:233], v[232:233], v[38:39]
	v_pk_add_f32 v[232:233], v[232:233], v[40:41]
	v_pk_add_f32 v[232:233], v[232:233], v[42:43]
	v_pk_add_f32 v[232:233], v[232:233], v[44:45]
	v_pk_add_f32 v[232:233], v[232:233], v[46:47]
	v_mfma_f32_32x32x16_bf16 v[0:15], v[64:67], v[72:75], v[0:15]
	v_mfma_f32_32x32x16_bf16 v[16:31], v[64:67], v[76:79], v[16:31]
	v_mfma_f32_32x32x16_bf16 v[0:15], v[68:71], v[220:223], v[0:15]
	v_mfma_f32_32x32x16_bf16 v[16:31], v[68:71], v[224:227], v[16:31]
	v_add_f32_e32 v113, v232, v233
	v_or_b32_e32 v114, 1, v107
	v_or_b32_e32 v97, 2, v107
	v_or_b32_e32 v96, 3, v107
	v_or_b32_e32 v95, 8, v107
	v_or_b32_e32 v94, 9, v107
	v_or_b32_e32 v93, 10, v107
	v_or_b32_e32 v92, 11, v107
	v_or_b32_e32 v91, 16, v107
	v_or_b32_e32 v90, 17, v107
	v_or_b32_e32 v89, 18, v107
	v_or_b32_e32 v88, 19, v107
	v_or_b32_e32 v87, 24, v107
	v_or_b32_e32 v86, 25, v107
	v_or_b32_e32 v85, 26, v107
	v_or_b32_e32 v84, 27, v107
	s_nop 11
	s_branch .LBB0_1265
